# all packed f32 ops (v_pk_add/mul/fma_f32) split into their two single f32 ops (bit-identical)
# speedup vs baseline: 1.0204x; 1.0204x over previous
; #define GAS __attribute__((address_space(1)))
; __device__ __forceinline__ float lx_get(float v, int src) { return __int_as_float(__builtin_amdgcn_readlane(__float_as_int(v), src)); }
; __device__ __forceinline__ void p_final(Frame& F) {
;     ...
;     for (int grp = gw; grp < MLAT / 16; grp += NGW) { const int rowb = grp * 16;
;         f32x4 qs = *(const GAS f32x4*)(RQ + (size_t)(F.lane >> 2) * MROWS + rowb + 4 * (F.lane & 3));
; #pragma unroll
;         for (int c = 0; c < 4; ++c) { float v = qs[c];
;             v += __int_as_float(__builtin_amdgcn_update_dpp(0, __float_as_int(v), 0x124, 0xF, 0xF, false)); v += __int_as_float(__builtin_amdgcn_update_dpp(0, __float_as_int(v), 0x128, 0xF, 0xF, false));
;             { auto r = __builtin_amdgcn_permlane16_swap(__float_as_uint(v), __float_as_uint(v), false, false); v = __uint_as_float(r[0]) + __uint_as_float(r[1]); }
;             { auto r = __builtin_amdgcn_permlane32_swap(__float_as_uint(v), __float_as_uint(v), false, false); v = __uint_as_float(r[0]) + __uint_as_float(r[1]); }
;             qs[c] = __builtin_amdgcn_rsqf(v * (1.f / 1024.f) + EPS); }
; #pragma unroll
;         for (int trip = 0; trip < 4; ++trip) {
;             h16x4 xv[4][4];
; #pragma unroll
;             for (int t = 0; t < 4; ++t)
; #pragma unroll
;                 for (int j = 0; j < 4; ++j) xv[t][j] = *(const GAS h16x4*)(X16 + (size_t)(rowb + 4 * trip + t) * D + j * 256 + F.lane * 4);
; #pragma unroll
;             for (int t = 0; t < 4; ++t) { const float rs = lx_get(qs[t], trip); float* orow = p.out + (size_t)(rowb + 4 * trip + t) * D;
; #pragma unroll
;                 for (int j = 0; j < 4; ++j) { const h16x4 v = xv[t][j];
;                     *(GAS f32x4*)(orow + j * 256 + F.lane * 4) = (f32x4){(float)v[0], (float)v[1], (float)v[2], (float)v[3]} * rs * gf[j]; } } }
.LBB0_19:
	s_add_i32 s4, s2, -15
	s_ashr_i32 s5, s4, 31
	v_lshl_add_u64 v[24:25], s[4:5], 2, v[18:19]
	global_load_dwordx4 v[24:27], v[24:25], off
	s_lshl_b64 s[6:7], s[4:5], 11
	s_add_i32 s10, s2, -14
	s_ashr_i32 s11, s10, 31
	s_add_i32 s8, s2, -13
	s_ashr_i32 s9, s8, 31
	s_lshl_b64 s[4:5], s[4:5], 12
	v_lshl_add_u64 v[64:65], v[22:23], 0, s[4:5]
	s_ashr_i32 s3, s2, 31
	s_add_i32 s12, s12, s78
	s_waitcnt vmcnt(0)
	v_add_f32_dpp v0, v24, v24 row_ror:4 row_mask:0xf bank_mask:0xf bound_ctrl:1
	s_nop 1
	v_add_f32_dpp v0, v0, v0 row_ror:8 row_mask:0xf bank_mask:0xf bound_ctrl:1
	v_mov_b32_e32 v24, v0
	s_nop 1
	v_permlane16_swap_b32_e32 v0, v24
	v_add_f32_e32 v0, v0, v24
	v_mov_b32_e32 v24, v0
	s_nop 1
	v_permlane32_swap_b32_e32 v0, v24
	v_add_f32_e32 v0, v0, v24
	v_fmamk_f32 v0, v0, 0x3a800000, v229
	v_rsq_f32_e32 v34, v0
	s_nop 0
	v_add_f32_dpp v0, v25, v25 row_ror:4 row_mask:0xf bank_mask:0xf bound_ctrl:1
	s_nop 1
	v_add_f32_dpp v0, v0, v0 row_ror:8 row_mask:0xf bank_mask:0xf bound_ctrl:1
	v_mov_b32_e32 v24, v0
	s_nop 1
	v_permlane16_swap_b32_e32 v0, v24
	v_add_f32_e32 v0, v0, v24
	v_mov_b32_e32 v24, v0
	s_nop 1
	v_permlane32_swap_b32_e32 v0, v24
	v_add_f32_e32 v0, v0, v24
	v_fmamk_f32 v0, v0, 0x3a800000, v229
	v_rsq_f32_e32 v33, v0
	s_nop 0
	v_add_f32_dpp v0, v26, v26 row_ror:4 row_mask:0xf bank_mask:0xf bound_ctrl:1
	v_readlane_b32 s4, v33, 0
	s_nop 0
	v_add_f32_dpp v0, v0, v0 row_ror:8 row_mask:0xf bank_mask:0xf bound_ctrl:1
	v_mov_b32_e32 v24, v0
	s_nop 1
	v_permlane16_swap_b32_e32 v0, v24
	v_add_f32_e32 v0, v0, v24
	v_mov_b32_e32 v24, v0
	s_nop 1
	v_permlane32_swap_b32_e32 v0, v24
	v_add_f32_e32 v0, v0, v24
	v_fmamk_f32 v0, v0, 0x3a800000, v229
	v_rsq_f32_e32 v32, v0
	s_nop 0
	v_add_f32_dpp v0, v27, v27 row_ror:4 row_mask:0xf bank_mask:0xf bound_ctrl:1
	s_nop 1
	v_add_f32_dpp v0, v0, v0 row_ror:8 row_mask:0xf bank_mask:0xf bound_ctrl:1
	v_mov_b32_e32 v24, v0
	s_nop 1
	v_permlane16_swap_b32_e32 v0, v24
	v_add_f32_e32 v0, v0, v24
	v_mov_b32_e32 v24, v0
	s_nop 1
	v_permlane32_swap_b32_e32 v0, v24
	v_add_f32_e32 v0, v0, v24
	v_lshl_add_u64 v[24:25], v[20:21], 0, s[6:7]
	global_load_dwordx2 v[30:31], v[24:25], off
	global_load_dwordx2 v[28:29], v[24:25], off offset:512
	global_load_dwordx2 v[26:27], v[24:25], off offset:1024
	s_nop 0
	global_load_dwordx2 v[24:25], v[24:25], off offset:1536
	s_lshl_b64 s[6:7], s[10:11], 11
	v_lshl_add_u64 v[36:37], v[20:21], 0, s[6:7]
	global_load_dwordx2 v[40:41], v[36:37], off
	global_load_dwordx2 v[42:43], v[36:37], off offset:512
	global_load_dwordx2 v[44:45], v[36:37], off offset:1024
	global_load_dwordx2 v[46:47], v[36:37], off offset:1536
	s_lshl_b64 s[6:7], s[8:9], 11
	v_lshl_add_u64 v[36:37], v[20:21], 0, s[6:7]
	global_load_dwordx2 v[48:49], v[36:37], off
	global_load_dwordx2 v[50:51], v[36:37], off offset:512
	global_load_dwordx2 v[52:53], v[36:37], off offset:1024
	global_load_dwordx2 v[54:55], v[36:37], off offset:1536
	s_add_i32 s6, s2, -12
	s_ashr_i32 s7, s6, 31
	s_lshl_b64 s[14:15], s[6:7], 11
	v_lshl_add_u64 v[36:37], v[20:21], 0, s[14:15]
	global_load_dwordx2 v[56:57], v[36:37], off
	global_load_dwordx2 v[58:59], v[36:37], off offset:512
	global_load_dwordx2 v[60:61], v[36:37], off offset:1024
	global_load_dwordx2 v[62:63], v[36:37], off offset:1536
	v_readlane_b32 s14, v34, 0
	s_lshl_b64 s[10:11], s[10:11], 12
	s_lshl_b64 s[8:9], s[8:9], 12
	v_fmamk_f32 v0, v0, 0x3a800000, v229
	v_rsq_f32_e32 v0, v0
	s_lshl_b64 s[6:7], s[6:7], 12
	s_waitcnt vmcnt(15)
	v_cvt_f32_f16_e32 v36, v30
	v_cvt_f32_f16_sdwa v37, v30 dst_sel:DWORD dst_unused:UNUSED_PAD src0_sel:WORD_1
	v_cvt_f32_f16_e32 v30, v31
	v_cvt_f32_f16_sdwa v31, v31 dst_sel:DWORD dst_unused:UNUSED_PAD src0_sel:WORD_1
	v_mul_f32_e32 v36, s14, v36
	v_mul_f32_e32 v37, s14, v37
	s_nop 0
	v_mul_f32_e32 v36, v2, v36
	v_mul_f32_e32 v37, v3, v37
	v_mul_f32_e32 v30, s14, v30
	v_mul_f32_e32 v31, s14, v31
	s_nop 0
	v_mul_f32_e32 v38, v4, v30
	v_mul_f32_e32 v39, v5, v31
	s_waitcnt vmcnt(14)
	v_cvt_f32_f16_e32 v30, v28
	v_cvt_f32_f16_sdwa v31, v28 dst_sel:DWORD dst_unused:UNUSED_PAD src0_sel:WORD_1
	v_cvt_f32_f16_e32 v28, v29
	v_cvt_f32_f16_sdwa v29, v29 dst_sel:DWORD dst_unused:UNUSED_PAD src0_sel:WORD_1
	global_store_dwordx4 v[64:65], v[36:39], off sc1
	v_mul_f32_e32 v28, s14, v28
	v_mul_f32_e32 v29, s14, v29
	s_nop 0
	v_mul_f32_e32 v36, s14, v30
	v_mul_f32_e32 v37, s14, v31
	v_mul_f32_e32 v30, v8, v28
	v_mul_f32_e32 v31, v9, v29
	v_mul_f32_e32 v28, v6, v36
	v_mul_f32_e32 v29, v7, v37
	global_store_dwordx4 v[64:65], v[28:31], off offset:1024 sc1
	s_waitcnt vmcnt(15)
	s_nop 0
	v_cvt_f32_f16_e32 v28, v26
	v_cvt_f32_f16_sdwa v29, v26 dst_sel:DWORD dst_unused:UNUSED_PAD src0_sel:WORD_1
	v_cvt_f32_f16_e32 v26, v27
	v_cvt_f32_f16_sdwa v27, v27 dst_sel:DWORD dst_unused:UNUSED_PAD src0_sel:WORD_1
	v_mul_f32_e32 v30, s14, v28
	v_mul_f32_e32 v31, s14, v29
	v_mul_f32_e32 v26, s14, v26
	v_mul_f32_e32 v27, s14, v27
	s_nop 0
	v_mul_f32_e32 v28, v12, v26
	v_mul_f32_e32 v29, v13, v27
	v_mul_f32_e32 v26, v10, v30
	v_mul_f32_e32 v27, v11, v31
	global_store_dwordx4 v[64:65], v[26:29], off offset:2048 sc1
	s_waitcnt vmcnt(15)
	s_nop 0
	v_cvt_f32_f16_e32 v26, v24
	v_cvt_f32_f16_sdwa v27, v24 dst_sel:DWORD dst_unused:UNUSED_PAD src0_sel:WORD_1
	v_cvt_f32_f16_e32 v24, v25
	v_cvt_f32_f16_sdwa v25, v25 dst_sel:DWORD dst_unused:UNUSED_PAD src0_sel:WORD_1
	v_mul_f32_e32 v28, s14, v26
	v_mul_f32_e32 v29, s14, v27
	v_mul_f32_e32 v24, s14, v24
	v_mul_f32_e32 v25, s14, v25
	s_nop 0
	v_mul_f32_e32 v26, v16, v24
	v_mul_f32_e32 v27, v17, v25
	v_mul_f32_e32 v24, v14, v28
	v_mul_f32_e32 v25, v15, v29
	global_store_dwordx4 v[64:65], v[24:27], off offset:3072 sc1
	v_lshl_add_u64 v[28:29], v[22:23], 0, s[10:11]
	s_add_i32 s10, s2, -11
	s_waitcnt vmcnt(15)
; #define GAS __attribute__((address_space(1)))
; __device__ __forceinline__ float lx_get(float v, int src) { return __int_as_float(__builtin_amdgcn_readlane(__float_as_int(v), src)); }
; __device__ __forceinline__ void p_final(Frame& F) {
;     ...
;         for (int trip = 0; trip < 4; ++trip) {
;             h16x4 xv[4][4];
; #pragma unroll
;             for (int t = 0; t < 4; ++t)
; #pragma unroll
;                 for (int j = 0; j < 4; ++j) xv[t][j] = *(const GAS h16x4*)(X16 + (size_t)(rowb + 4 * trip + t) * D + j * 256 + F.lane * 4);
; #pragma unroll
;             for (int t = 0; t < 4; ++t) { const float rs = lx_get(qs[t], trip); float* orow = p.out + (size_t)(rowb + 4 * trip + t) * D;
; #pragma unroll
;                 for (int j = 0; j < 4; ++j) { const h16x4 v = xv[t][j];
;                     *(GAS f32x4*)(orow + j * 256 + F.lane * 4) = (f32x4){(float)v[0], (float)v[1], (float)v[2], (float)v[3]} * rs * gf[j]; } } }
	v_cvt_f32_f16_e32 v24, v40
	v_cvt_f32_f16_sdwa v25, v40 dst_sel:DWORD dst_unused:UNUSED_PAD src0_sel:WORD_1
	v_cvt_f32_f16_e32 v26, v41
	v_cvt_f32_f16_sdwa v27, v41 dst_sel:DWORD dst_unused:UNUSED_PAD src0_sel:WORD_1
	s_ashr_i32 s11, s10, 31
	v_mul_f32_e32 v24, s4, v24
	v_mul_f32_e32 v25, s4, v25
	v_mul_f32_e32 v26, s4, v26
	v_mul_f32_e32 v27, s4, v27
	s_nop 0
	v_mul_f32_e32 v26, v4, v26
	v_mul_f32_e32 v27, v5, v27
	v_mul_f32_e32 v24, v2, v24
	v_mul_f32_e32 v25, v3, v25
	global_store_dwordx4 v[28:29], v[24:27], off sc1
	s_waitcnt vmcnt(15)
	s_nop 0
	v_cvt_f32_f16_e32 v24, v42
	v_cvt_f32_f16_sdwa v25, v42 dst_sel:DWORD dst_unused:UNUSED_PAD src0_sel:WORD_1
	v_cvt_f32_f16_e32 v26, v43
	v_cvt_f32_f16_sdwa v27, v43 dst_sel:DWORD dst_unused:UNUSED_PAD src0_sel:WORD_1
	v_mul_f32_e32 v24, s4, v24
	v_mul_f32_e32 v25, s4, v25
	s_nop 0
	v_mul_f32_e32 v24, v6, v24
	v_mul_f32_e32 v25, v7, v25
	v_mul_f32_e32 v26, s4, v26
	v_mul_f32_e32 v27, s4, v27
	s_nop 0
	v_mul_f32_e32 v26, v8, v26
	v_mul_f32_e32 v27, v9, v27
	global_store_dwordx4 v[28:29], v[24:27], off offset:1024 sc1
	s_waitcnt vmcnt(15)
	s_nop 0
	v_cvt_f32_f16_e32 v24, v44
	v_cvt_f32_f16_sdwa v25, v44 dst_sel:DWORD dst_unused:UNUSED_PAD src0_sel:WORD_1
	v_cvt_f32_f16_e32 v26, v45
	v_cvt_f32_f16_sdwa v27, v45 dst_sel:DWORD dst_unused:UNUSED_PAD src0_sel:WORD_1
	v_mul_f32_e32 v24, s4, v24
	v_mul_f32_e32 v25, s4, v25
	s_nop 0
	v_mul_f32_e32 v24, v10, v24
	v_mul_f32_e32 v25, v11, v25
	v_mul_f32_e32 v26, s4, v26
	v_mul_f32_e32 v27, s4, v27
	s_nop 0
	v_mul_f32_e32 v26, v12, v26
	v_mul_f32_e32 v27, v13, v27
	global_store_dwordx4 v[28:29], v[24:27], off offset:2048 sc1
	s_waitcnt vmcnt(15)
	s_nop 0
	v_cvt_f32_f16_e32 v24, v46
	v_cvt_f32_f16_sdwa v25, v46 dst_sel:DWORD dst_unused:UNUSED_PAD src0_sel:WORD_1
	v_cvt_f32_f16_e32 v26, v47
	v_cvt_f32_f16_sdwa v27, v47 dst_sel:DWORD dst_unused:UNUSED_PAD src0_sel:WORD_1
	v_mul_f32_e32 v24, s4, v24
	v_mul_f32_e32 v25, s4, v25
	s_nop 0
	v_mul_f32_e32 v24, v14, v24
	v_mul_f32_e32 v25, v15, v25
	v_mul_f32_e32 v26, s4, v26
	v_mul_f32_e32 v27, s4, v27
	v_readlane_b32 s4, v32, 0
	v_mul_f32_e32 v26, v16, v26
	v_mul_f32_e32 v27, v17, v27
	global_store_dwordx4 v[28:29], v[24:27], off offset:3072 sc1
	v_lshl_add_u64 v[28:29], v[22:23], 0, s[8:9]
	s_add_i32 s8, s2, -10
	s_waitcnt vmcnt(15)
	v_cvt_f32_f16_e32 v24, v48
	v_cvt_f32_f16_sdwa v25, v48 dst_sel:DWORD dst_unused:UNUSED_PAD src0_sel:WORD_1
	v_cvt_f32_f16_e32 v26, v49
	v_cvt_f32_f16_sdwa v27, v49 dst_sel:DWORD dst_unused:UNUSED_PAD src0_sel:WORD_1
	s_ashr_i32 s9, s8, 31
	v_mul_f32_e32 v24, s4, v24
	v_mul_f32_e32 v25, s4, v25
	v_mul_f32_e32 v26, s4, v26
	v_mul_f32_e32 v27, s4, v27
	s_nop 0
	v_mul_f32_e32 v26, v4, v26
	v_mul_f32_e32 v27, v5, v27
	v_mul_f32_e32 v24, v2, v24
	v_mul_f32_e32 v25, v3, v25
	global_store_dwordx4 v[28:29], v[24:27], off sc1
	s_waitcnt vmcnt(15)
	s_nop 0
	v_cvt_f32_f16_e32 v24, v50
	v_cvt_f32_f16_sdwa v25, v50 dst_sel:DWORD dst_unused:UNUSED_PAD src0_sel:WORD_1
	v_cvt_f32_f16_e32 v26, v51
	v_cvt_f32_f16_sdwa v27, v51 dst_sel:DWORD dst_unused:UNUSED_PAD src0_sel:WORD_1
	v_mul_f32_e32 v24, s4, v24
	v_mul_f32_e32 v25, s4, v25
	s_nop 0
	v_mul_f32_e32 v24, v6, v24
	v_mul_f32_e32 v25, v7, v25
	v_mul_f32_e32 v26, s4, v26
	v_mul_f32_e32 v27, s4, v27
	s_nop 0
	v_mul_f32_e32 v26, v8, v26
	v_mul_f32_e32 v27, v9, v27
	global_store_dwordx4 v[28:29], v[24:27], off offset:1024 sc1
	s_waitcnt vmcnt(15)
	s_nop 0
	v_cvt_f32_f16_e32 v24, v52
	v_cvt_f32_f16_sdwa v25, v52 dst_sel:DWORD dst_unused:UNUSED_PAD src0_sel:WORD_1
	v_cvt_f32_f16_e32 v26, v53
	v_cvt_f32_f16_sdwa v27, v53 dst_sel:DWORD dst_unused:UNUSED_PAD src0_sel:WORD_1
	v_mul_f32_e32 v24, s4, v24
	v_mul_f32_e32 v25, s4, v25
	s_nop 0
	v_mul_f32_e32 v24, v10, v24
	v_mul_f32_e32 v25, v11, v25
	v_mul_f32_e32 v26, s4, v26
	v_mul_f32_e32 v27, s4, v27
	s_nop 0
	v_mul_f32_e32 v26, v12, v26
	v_mul_f32_e32 v27, v13, v27
	global_store_dwordx4 v[28:29], v[24:27], off offset:2048 sc1
	s_waitcnt vmcnt(15)
	s_nop 0
	v_cvt_f32_f16_e32 v24, v54
	v_cvt_f32_f16_sdwa v25, v54 dst_sel:DWORD dst_unused:UNUSED_PAD src0_sel:WORD_1
	v_cvt_f32_f16_e32 v26, v55
	v_cvt_f32_f16_sdwa v27, v55 dst_sel:DWORD dst_unused:UNUSED_PAD src0_sel:WORD_1
	v_mul_f32_e32 v24, s4, v24
	v_mul_f32_e32 v25, s4, v25
	s_nop 0
	v_mul_f32_e32 v24, v14, v24
	v_mul_f32_e32 v25, v15, v25
	v_mul_f32_e32 v26, s4, v26
	v_mul_f32_e32 v27, s4, v27
	v_readlane_b32 s4, v0, 0
	v_mul_f32_e32 v26, v16, v26
	v_mul_f32_e32 v27, v17, v27
	global_store_dwordx4 v[28:29], v[24:27], off offset:3072 sc1
	v_lshl_add_u64 v[28:29], v[22:23], 0, s[6:7]
	s_add_i32 s6, s2, -9
	s_waitcnt vmcnt(15)
	v_cvt_f32_f16_e32 v24, v56
	v_cvt_f32_f16_sdwa v25, v56 dst_sel:DWORD dst_unused:UNUSED_PAD src0_sel:WORD_1
	v_cvt_f32_f16_e32 v26, v57
	v_cvt_f32_f16_sdwa v27, v57 dst_sel:DWORD dst_unused:UNUSED_PAD src0_sel:WORD_1
	s_ashr_i32 s7, s6, 31
	v_mul_f32_e32 v24, s4, v24
	v_mul_f32_e32 v25, s4, v25
	v_mul_f32_e32 v26, s4, v26
	v_mul_f32_e32 v27, s4, v27
	s_nop 0
	v_mul_f32_e32 v26, v4, v26
	v_mul_f32_e32 v27, v5, v27
	v_mul_f32_e32 v24, v2, v24
	v_mul_f32_e32 v25, v3, v25
	global_store_dwordx4 v[28:29], v[24:27], off sc1
	s_waitcnt vmcnt(15)
	s_nop 0
	v_cvt_f32_f16_e32 v24, v58
	v_cvt_f32_f16_sdwa v25, v58 dst_sel:DWORD dst_unused:UNUSED_PAD src0_sel:WORD_1
	v_cvt_f32_f16_e32 v26, v59
	v_cvt_f32_f16_sdwa v27, v59 dst_sel:DWORD dst_unused:UNUSED_PAD src0_sel:WORD_1
	v_mul_f32_e32 v24, s4, v24
	v_mul_f32_e32 v25, s4, v25
	s_nop 0
	v_mul_f32_e32 v24, v6, v24
	v_mul_f32_e32 v25, v7, v25
	v_mul_f32_e32 v26, s4, v26
	v_mul_f32_e32 v27, s4, v27
	s_nop 0
	v_mul_f32_e32 v26, v8, v26
	v_mul_f32_e32 v27, v9, v27
	global_store_dwordx4 v[28:29], v[24:27], off offset:1024 sc1
	s_waitcnt vmcnt(15)
; #define GAS __attribute__((address_space(1)))
; __device__ __forceinline__ float lx_get(float v, int src) { return __int_as_float(__builtin_amdgcn_readlane(__float_as_int(v), src)); }
; __device__ __forceinline__ void p_final(Frame& F) {
;     ...
;         for (int trip = 0; trip < 4; ++trip) {
;             h16x4 xv[4][4];
; #pragma unroll
;             for (int t = 0; t < 4; ++t)
; #pragma unroll
;                 for (int j = 0; j < 4; ++j) xv[t][j] = *(const GAS h16x4*)(X16 + (size_t)(rowb + 4 * trip + t) * D + j * 256 + F.lane * 4);
; #pragma unroll
;             for (int t = 0; t < 4; ++t) { const float rs = lx_get(qs[t], trip); float* orow = p.out + (size_t)(rowb + 4 * trip + t) * D;
; #pragma unroll
;                 for (int j = 0; j < 4; ++j) { const h16x4 v = xv[t][j];
;                     *(GAS f32x4*)(orow + j * 256 + F.lane * 4) = (f32x4){(float)v[0], (float)v[1], (float)v[2], (float)v[3]} * rs * gf[j]; } } }
	s_nop 0
	v_cvt_f32_f16_e32 v24, v60
	v_cvt_f32_f16_sdwa v25, v60 dst_sel:DWORD dst_unused:UNUSED_PAD src0_sel:WORD_1
	v_cvt_f32_f16_e32 v26, v61
	v_cvt_f32_f16_sdwa v27, v61 dst_sel:DWORD dst_unused:UNUSED_PAD src0_sel:WORD_1
	v_mul_f32_e32 v24, s4, v24
	v_mul_f32_e32 v25, s4, v25
	s_nop 0
	v_mul_f32_e32 v24, v10, v24
	v_mul_f32_e32 v25, v11, v25
	v_mul_f32_e32 v26, s4, v26
	v_mul_f32_e32 v27, s4, v27
	s_nop 0
	v_mul_f32_e32 v26, v12, v26
	v_mul_f32_e32 v27, v13, v27
	global_store_dwordx4 v[28:29], v[24:27], off offset:2048 sc1
	s_waitcnt vmcnt(15)
	s_nop 0
	v_cvt_f32_f16_e32 v24, v62
	v_cvt_f32_f16_sdwa v25, v62 dst_sel:DWORD dst_unused:UNUSED_PAD src0_sel:WORD_1
	v_cvt_f32_f16_e32 v26, v63
	v_cvt_f32_f16_sdwa v27, v63 dst_sel:DWORD dst_unused:UNUSED_PAD src0_sel:WORD_1
	v_mul_f32_e32 v24, s4, v24
	v_mul_f32_e32 v25, s4, v25
	s_nop 0
	v_mul_f32_e32 v24, v14, v24
	v_mul_f32_e32 v25, v15, v25
	v_mul_f32_e32 v26, s4, v26
	v_mul_f32_e32 v27, s4, v27
	s_lshl_b64 s[4:5], s[10:11], 11
	v_mul_f32_e32 v26, v16, v26
	v_mul_f32_e32 v27, v17, v27
	global_store_dwordx4 v[28:29], v[24:27], off offset:3072 sc1
	s_lshl_b64 s[10:11], s[10:11], 12
	v_lshl_add_u64 v[62:63], v[22:23], 0, s[10:11]
	v_lshl_add_u64 v[24:25], v[20:21], 0, s[4:5]
	global_load_dwordx2 v[26:27], v[24:25], off
	global_load_dwordx2 v[28:29], v[24:25], off offset:512
	global_load_dwordx2 v[30:31], v[24:25], off offset:1024
	global_load_dwordx2 v[36:37], v[24:25], off offset:1536
	s_lshl_b64 s[4:5], s[8:9], 11
	v_lshl_add_u64 v[24:25], v[20:21], 0, s[4:5]
	global_load_dwordx2 v[38:39], v[24:25], off
	global_load_dwordx2 v[40:41], v[24:25], off offset:512
	global_load_dwordx2 v[42:43], v[24:25], off offset:1024
	global_load_dwordx2 v[44:45], v[24:25], off offset:1536
	s_lshl_b64 s[4:5], s[6:7], 11
	v_lshl_add_u64 v[24:25], v[20:21], 0, s[4:5]
	global_load_dwordx2 v[46:47], v[24:25], off
	global_load_dwordx2 v[48:49], v[24:25], off offset:512
	global_load_dwordx2 v[50:51], v[24:25], off offset:1024
	global_load_dwordx2 v[52:53], v[24:25], off offset:1536
	s_add_i32 s4, s2, -8
	s_ashr_i32 s5, s4, 31
	s_lshl_b64 s[14:15], s[4:5], 11
	v_lshl_add_u64 v[24:25], v[20:21], 0, s[14:15]
	global_load_dwordx2 v[54:55], v[24:25], off
	global_load_dwordx2 v[56:57], v[24:25], off offset:512
	global_load_dwordx2 v[58:59], v[24:25], off offset:1024
	global_load_dwordx2 v[60:61], v[24:25], off offset:1536
	v_readlane_b32 s14, v34, 1
	v_readlane_b32 s10, v33, 1
	s_lshl_b64 s[8:9], s[8:9], 12
	s_lshl_b64 s[6:7], s[6:7], 12
	s_lshl_b64 s[4:5], s[4:5], 12
	s_waitcnt vmcnt(15)
	v_cvt_f32_f16_e32 v24, v26
	v_cvt_f32_f16_sdwa v25, v26 dst_sel:DWORD dst_unused:UNUSED_PAD src0_sel:WORD_1
	v_cvt_f32_f16_e32 v26, v27
	v_cvt_f32_f16_sdwa v27, v27 dst_sel:DWORD dst_unused:UNUSED_PAD src0_sel:WORD_1
	v_mul_f32_e32 v24, s14, v24
	v_mul_f32_e32 v25, s14, v25
	s_nop 0
	v_mul_f32_e32 v24, v2, v24
	v_mul_f32_e32 v25, v3, v25
	v_mul_f32_e32 v26, s14, v26
	v_mul_f32_e32 v27, s14, v27
	s_nop 0
	v_mul_f32_e32 v26, v4, v26
	v_mul_f32_e32 v27, v5, v27
	global_store_dwordx4 v[62:63], v[24:27], off sc1
	s_waitcnt vmcnt(15)
	s_nop 0
	v_cvt_f32_f16_e32 v24, v28
	v_cvt_f32_f16_sdwa v25, v28 dst_sel:DWORD dst_unused:UNUSED_PAD src0_sel:WORD_1
	v_cvt_f32_f16_e32 v26, v29
	v_cvt_f32_f16_sdwa v27, v29 dst_sel:DWORD dst_unused:UNUSED_PAD src0_sel:WORD_1
	v_lshl_add_u64 v[28:29], v[22:23], 0, s[8:9]
	v_mul_f32_e32 v24, s14, v24
	v_mul_f32_e32 v25, s14, v25
	v_readlane_b32 s8, v32, 1
	v_mul_f32_e32 v26, s14, v26
	v_mul_f32_e32 v27, s14, v27
	v_mul_f32_e32 v24, v6, v24
	v_mul_f32_e32 v25, v7, v25
	v_mul_f32_e32 v26, v8, v26
	v_mul_f32_e32 v27, v9, v27
	global_store_dwordx4 v[62:63], v[24:27], off offset:1024 sc1
	s_waitcnt vmcnt(15)
	s_nop 0
	v_cvt_f32_f16_e32 v24, v30
	v_cvt_f32_f16_sdwa v25, v30 dst_sel:DWORD dst_unused:UNUSED_PAD src0_sel:WORD_1
	v_cvt_f32_f16_e32 v26, v31
	v_cvt_f32_f16_sdwa v27, v31 dst_sel:DWORD dst_unused:UNUSED_PAD src0_sel:WORD_1
	v_mul_f32_e32 v24, s14, v24
	v_mul_f32_e32 v25, s14, v25
	s_nop 0
	v_mul_f32_e32 v24, v10, v24
	v_mul_f32_e32 v25, v11, v25
	v_mul_f32_e32 v26, s14, v26
	v_mul_f32_e32 v27, s14, v27
	s_nop 0
	v_mul_f32_e32 v26, v12, v26
	v_mul_f32_e32 v27, v13, v27
	global_store_dwordx4 v[62:63], v[24:27], off offset:2048 sc1
	s_waitcnt vmcnt(15)
	s_nop 0
	v_cvt_f32_f16_e32 v24, v36
	v_cvt_f32_f16_sdwa v25, v36 dst_sel:DWORD dst_unused:UNUSED_PAD src0_sel:WORD_1
	v_cvt_f32_f16_e32 v26, v37
	v_cvt_f32_f16_sdwa v27, v37 dst_sel:DWORD dst_unused:UNUSED_PAD src0_sel:WORD_1
	v_mul_f32_e32 v24, s14, v24
	v_mul_f32_e32 v25, s14, v25
	s_nop 0
	v_mul_f32_e32 v24, v14, v24
	v_mul_f32_e32 v25, v15, v25
	v_mul_f32_e32 v26, s14, v26
	v_mul_f32_e32 v27, s14, v27
	s_nop 0
	v_mul_f32_e32 v26, v16, v26
	v_mul_f32_e32 v27, v17, v27
	global_store_dwordx4 v[62:63], v[24:27], off offset:3072 sc1
	s_waitcnt vmcnt(15)
	s_nop 0
	v_cvt_f32_f16_e32 v24, v38
	v_cvt_f32_f16_sdwa v25, v38 dst_sel:DWORD dst_unused:UNUSED_PAD src0_sel:WORD_1
	v_cvt_f32_f16_e32 v26, v39
	v_cvt_f32_f16_sdwa v27, v39 dst_sel:DWORD dst_unused:UNUSED_PAD src0_sel:WORD_1
	v_mul_f32_e32 v24, s10, v24
	v_mul_f32_e32 v25, s10, v25
	s_nop 0
	v_mul_f32_e32 v24, v2, v24
	v_mul_f32_e32 v25, v3, v25
	v_mul_f32_e32 v26, s10, v26
	v_mul_f32_e32 v27, s10, v27
	s_nop 0
	v_mul_f32_e32 v26, v4, v26
	v_mul_f32_e32 v27, v5, v27
	global_store_dwordx4 v[28:29], v[24:27], off sc1
	s_waitcnt vmcnt(15)
; #define GAS __attribute__((address_space(1)))
; __device__ __forceinline__ float lx_get(float v, int src) { return __int_as_float(__builtin_amdgcn_readlane(__float_as_int(v), src)); }
; __device__ __forceinline__ void p_final(Frame& F) {
;     ...
;         for (int trip = 0; trip < 4; ++trip) {
;             h16x4 xv[4][4];
; #pragma unroll
;             for (int t = 0; t < 4; ++t)
; #pragma unroll
;                 for (int j = 0; j < 4; ++j) xv[t][j] = *(const GAS h16x4*)(X16 + (size_t)(rowb + 4 * trip + t) * D + j * 256 + F.lane * 4);
; #pragma unroll
;             for (int t = 0; t < 4; ++t) { const float rs = lx_get(qs[t], trip); float* orow = p.out + (size_t)(rowb + 4 * trip + t) * D;
; #pragma unroll
;                 for (int j = 0; j < 4; ++j) { const h16x4 v = xv[t][j];
;                     *(GAS f32x4*)(orow + j * 256 + F.lane * 4) = (f32x4){(float)v[0], (float)v[1], (float)v[2], (float)v[3]} * rs * gf[j]; } } }
	s_nop 0
	v_cvt_f32_f16_e32 v24, v40
	v_cvt_f32_f16_sdwa v25, v40 dst_sel:DWORD dst_unused:UNUSED_PAD src0_sel:WORD_1
	v_cvt_f32_f16_e32 v26, v41
	v_cvt_f32_f16_sdwa v27, v41 dst_sel:DWORD dst_unused:UNUSED_PAD src0_sel:WORD_1
	v_mul_f32_e32 v24, s10, v24
	v_mul_f32_e32 v25, s10, v25
	s_nop 0
	v_mul_f32_e32 v24, v6, v24
	v_mul_f32_e32 v25, v7, v25
	v_mul_f32_e32 v26, s10, v26
	v_mul_f32_e32 v27, s10, v27
	s_nop 0
	v_mul_f32_e32 v26, v8, v26
	v_mul_f32_e32 v27, v9, v27
	global_store_dwordx4 v[28:29], v[24:27], off offset:1024 sc1
	s_waitcnt vmcnt(15)
	s_nop 0
	v_cvt_f32_f16_e32 v24, v42
	v_cvt_f32_f16_sdwa v25, v42 dst_sel:DWORD dst_unused:UNUSED_PAD src0_sel:WORD_1
	v_cvt_f32_f16_e32 v26, v43
	v_cvt_f32_f16_sdwa v27, v43 dst_sel:DWORD dst_unused:UNUSED_PAD src0_sel:WORD_1
	v_mul_f32_e32 v24, s10, v24
	v_mul_f32_e32 v25, s10, v25
	s_nop 0
	v_mul_f32_e32 v24, v10, v24
	v_mul_f32_e32 v25, v11, v25
	v_mul_f32_e32 v26, s10, v26
	v_mul_f32_e32 v27, s10, v27
	s_nop 0
	v_mul_f32_e32 v26, v12, v26
	v_mul_f32_e32 v27, v13, v27
	global_store_dwordx4 v[28:29], v[24:27], off offset:2048 sc1
	s_waitcnt vmcnt(15)
	s_nop 0
	v_cvt_f32_f16_e32 v24, v44
	v_cvt_f32_f16_sdwa v25, v44 dst_sel:DWORD dst_unused:UNUSED_PAD src0_sel:WORD_1
	v_cvt_f32_f16_e32 v26, v45
	v_cvt_f32_f16_sdwa v27, v45 dst_sel:DWORD dst_unused:UNUSED_PAD src0_sel:WORD_1
	v_mul_f32_e32 v24, s10, v24
	v_mul_f32_e32 v25, s10, v25
	s_nop 0
	v_mul_f32_e32 v24, v14, v24
	v_mul_f32_e32 v25, v15, v25
	v_mul_f32_e32 v26, s10, v26
	v_mul_f32_e32 v27, s10, v27
	s_add_i32 s10, s2, -7
	v_mul_f32_e32 v26, v16, v26
	v_mul_f32_e32 v27, v17, v27
	global_store_dwordx4 v[28:29], v[24:27], off offset:3072 sc1
	v_lshl_add_u64 v[28:29], v[22:23], 0, s[6:7]
	v_readlane_b32 s6, v0, 1
	s_waitcnt vmcnt(15)
	v_cvt_f32_f16_e32 v24, v46
	v_cvt_f32_f16_sdwa v25, v46 dst_sel:DWORD dst_unused:UNUSED_PAD src0_sel:WORD_1
	v_cvt_f32_f16_e32 v26, v47
	v_cvt_f32_f16_sdwa v27, v47 dst_sel:DWORD dst_unused:UNUSED_PAD src0_sel:WORD_1
	s_ashr_i32 s11, s10, 31
	v_mul_f32_e32 v24, s8, v24
	v_mul_f32_e32 v25, s8, v25
	v_mul_f32_e32 v26, s8, v26
	v_mul_f32_e32 v27, s8, v27
	s_nop 0
	v_mul_f32_e32 v26, v4, v26
	v_mul_f32_e32 v27, v5, v27
	v_mul_f32_e32 v24, v2, v24
	v_mul_f32_e32 v25, v3, v25
	global_store_dwordx4 v[28:29], v[24:27], off sc1
	s_waitcnt vmcnt(15)
	s_nop 0
	v_cvt_f32_f16_e32 v24, v48
	v_cvt_f32_f16_sdwa v25, v48 dst_sel:DWORD dst_unused:UNUSED_PAD src0_sel:WORD_1
	v_cvt_f32_f16_e32 v26, v49
	v_cvt_f32_f16_sdwa v27, v49 dst_sel:DWORD dst_unused:UNUSED_PAD src0_sel:WORD_1
	v_mul_f32_e32 v24, s8, v24
	v_mul_f32_e32 v25, s8, v25
	s_nop 0
	v_mul_f32_e32 v24, v6, v24
	v_mul_f32_e32 v25, v7, v25
	v_mul_f32_e32 v26, s8, v26
	v_mul_f32_e32 v27, s8, v27
	s_nop 0
	v_mul_f32_e32 v26, v8, v26
	v_mul_f32_e32 v27, v9, v27
	global_store_dwordx4 v[28:29], v[24:27], off offset:1024 sc1
	s_waitcnt vmcnt(15)
	s_nop 0
	v_cvt_f32_f16_e32 v24, v50
	v_cvt_f32_f16_sdwa v25, v50 dst_sel:DWORD dst_unused:UNUSED_PAD src0_sel:WORD_1
	v_cvt_f32_f16_e32 v26, v51
	v_cvt_f32_f16_sdwa v27, v51 dst_sel:DWORD dst_unused:UNUSED_PAD src0_sel:WORD_1
	v_mul_f32_e32 v24, s8, v24
	v_mul_f32_e32 v25, s8, v25
	s_nop 0
	v_mul_f32_e32 v24, v10, v24
	v_mul_f32_e32 v25, v11, v25
	v_mul_f32_e32 v26, s8, v26
	v_mul_f32_e32 v27, s8, v27
	s_nop 0
	v_mul_f32_e32 v26, v12, v26
	v_mul_f32_e32 v27, v13, v27
	global_store_dwordx4 v[28:29], v[24:27], off offset:2048 sc1
	s_waitcnt vmcnt(15)
	s_nop 0
	v_cvt_f32_f16_e32 v24, v52
	v_cvt_f32_f16_sdwa v25, v52 dst_sel:DWORD dst_unused:UNUSED_PAD src0_sel:WORD_1
	v_cvt_f32_f16_e32 v26, v53
	v_cvt_f32_f16_sdwa v27, v53 dst_sel:DWORD dst_unused:UNUSED_PAD src0_sel:WORD_1
	v_mul_f32_e32 v24, s8, v24
	v_mul_f32_e32 v25, s8, v25
	s_nop 0
	v_mul_f32_e32 v24, v14, v24
	v_mul_f32_e32 v25, v15, v25
	v_mul_f32_e32 v26, s8, v26
	v_mul_f32_e32 v27, s8, v27
	s_add_i32 s8, s2, -6
	v_mul_f32_e32 v26, v16, v26
	v_mul_f32_e32 v27, v17, v27
	global_store_dwordx4 v[28:29], v[24:27], off offset:3072 sc1
	v_lshl_add_u64 v[28:29], v[22:23], 0, s[4:5]
	s_lshl_b64 s[4:5], s[10:11], 11
	s_waitcnt vmcnt(15)
	v_cvt_f32_f16_e32 v24, v54
	v_cvt_f32_f16_sdwa v25, v54 dst_sel:DWORD dst_unused:UNUSED_PAD src0_sel:WORD_1
	v_cvt_f32_f16_e32 v26, v55
	v_cvt_f32_f16_sdwa v27, v55 dst_sel:DWORD dst_unused:UNUSED_PAD src0_sel:WORD_1
	s_ashr_i32 s9, s8, 31
	v_mul_f32_e32 v24, s6, v24
	v_mul_f32_e32 v25, s6, v25
	s_lshl_b64 s[10:11], s[10:11], 12
	v_mul_f32_e32 v26, s6, v26
	v_mul_f32_e32 v27, s6, v27
	v_mul_f32_e32 v24, v2, v24
	v_mul_f32_e32 v25, v3, v25
	v_mul_f32_e32 v26, v4, v26
	v_mul_f32_e32 v27, v5, v27
	global_store_dwordx4 v[28:29], v[24:27], off sc1
	v_lshl_add_u64 v[62:63], v[22:23], 0, s[10:11]
	v_readlane_b32 s10, v33, 2
	s_waitcnt vmcnt(15)
	v_cvt_f32_f16_e32 v24, v56
	v_cvt_f32_f16_sdwa v25, v56 dst_sel:DWORD dst_unused:UNUSED_PAD src0_sel:WORD_1
	v_cvt_f32_f16_e32 v26, v57
	v_cvt_f32_f16_sdwa v27, v57 dst_sel:DWORD dst_unused:UNUSED_PAD src0_sel:WORD_1
	v_mul_f32_e32 v24, s6, v24
	v_mul_f32_e32 v25, s6, v25
	s_nop 0
	v_mul_f32_e32 v24, v6, v24
	v_mul_f32_e32 v25, v7, v25
	v_mul_f32_e32 v26, s6, v26
	v_mul_f32_e32 v27, s6, v27
	s_nop 0
	v_mul_f32_e32 v26, v8, v26
	v_mul_f32_e32 v27, v9, v27
	global_store_dwordx4 v[28:29], v[24:27], off offset:1024 sc1
	s_waitcnt vmcnt(15)
	s_nop 0
	v_cvt_f32_f16_e32 v24, v58
	v_cvt_f32_f16_sdwa v25, v58 dst_sel:DWORD dst_unused:UNUSED_PAD src0_sel:WORD_1
	v_cvt_f32_f16_e32 v26, v59
	v_cvt_f32_f16_sdwa v27, v59 dst_sel:DWORD dst_unused:UNUSED_PAD src0_sel:WORD_1
	v_mul_f32_e32 v24, s6, v24
	v_mul_f32_e32 v25, s6, v25
	s_nop 0
	v_mul_f32_e32 v24, v10, v24
	v_mul_f32_e32 v25, v11, v25
	v_mul_f32_e32 v26, s6, v26
	v_mul_f32_e32 v27, s6, v27
	s_nop 0
	v_mul_f32_e32 v26, v12, v26
	v_mul_f32_e32 v27, v13, v27
	global_store_dwordx4 v[28:29], v[24:27], off offset:2048 sc1
	s_waitcnt vmcnt(15)
; #define GAS __attribute__((address_space(1)))
; __device__ __forceinline__ float lx_get(float v, int src) { return __int_as_float(__builtin_amdgcn_readlane(__float_as_int(v), src)); }
; __device__ __forceinline__ void p_final(Frame& F) {
;     ...
;         for (int trip = 0; trip < 4; ++trip) {
;             h16x4 xv[4][4];
; #pragma unroll
;             for (int t = 0; t < 4; ++t)
; #pragma unroll
;                 for (int j = 0; j < 4; ++j) xv[t][j] = *(const GAS h16x4*)(X16 + (size_t)(rowb + 4 * trip + t) * D + j * 256 + F.lane * 4);
; #pragma unroll
;             for (int t = 0; t < 4; ++t) { const float rs = lx_get(qs[t], trip); float* orow = p.out + (size_t)(rowb + 4 * trip + t) * D;
; #pragma unroll
;                 for (int j = 0; j < 4; ++j) { const h16x4 v = xv[t][j];
;                     *(GAS f32x4*)(orow + j * 256 + F.lane * 4) = (f32x4){(float)v[0], (float)v[1], (float)v[2], (float)v[3]} * rs * gf[j]; } } }
	s_nop 0
	v_cvt_f32_f16_e32 v24, v60
	v_cvt_f32_f16_sdwa v25, v60 dst_sel:DWORD dst_unused:UNUSED_PAD src0_sel:WORD_1
	v_cvt_f32_f16_e32 v26, v61
	v_cvt_f32_f16_sdwa v27, v61 dst_sel:DWORD dst_unused:UNUSED_PAD src0_sel:WORD_1
	v_mul_f32_e32 v24, s6, v24
	v_mul_f32_e32 v25, s6, v25
	s_nop 0
	v_mul_f32_e32 v24, v14, v24
	v_mul_f32_e32 v25, v15, v25
	v_mul_f32_e32 v26, s6, v26
	v_mul_f32_e32 v27, s6, v27
	s_add_i32 s6, s2, -5
	v_mul_f32_e32 v26, v16, v26
	v_mul_f32_e32 v27, v17, v27
	global_store_dwordx4 v[28:29], v[24:27], off offset:3072 sc1
	s_ashr_i32 s7, s6, 31
	s_nop 0
	v_lshl_add_u64 v[24:25], v[20:21], 0, s[4:5]
	global_load_dwordx2 v[26:27], v[24:25], off
	global_load_dwordx2 v[28:29], v[24:25], off offset:512
	global_load_dwordx2 v[30:31], v[24:25], off offset:1024
	global_load_dwordx2 v[36:37], v[24:25], off offset:1536
	s_lshl_b64 s[4:5], s[8:9], 11
	v_lshl_add_u64 v[24:25], v[20:21], 0, s[4:5]
	global_load_dwordx2 v[38:39], v[24:25], off
	global_load_dwordx2 v[40:41], v[24:25], off offset:512
	global_load_dwordx2 v[42:43], v[24:25], off offset:1024
	global_load_dwordx2 v[44:45], v[24:25], off offset:1536
	s_lshl_b64 s[4:5], s[6:7], 11
	v_lshl_add_u64 v[24:25], v[20:21], 0, s[4:5]
	global_load_dwordx2 v[46:47], v[24:25], off
	global_load_dwordx2 v[48:49], v[24:25], off offset:512
	global_load_dwordx2 v[50:51], v[24:25], off offset:1024
	global_load_dwordx2 v[52:53], v[24:25], off offset:1536
	s_add_i32 s4, s2, -4
	s_ashr_i32 s5, s4, 31
	s_lshl_b64 s[14:15], s[4:5], 11
	v_lshl_add_u64 v[24:25], v[20:21], 0, s[14:15]
	global_load_dwordx2 v[54:55], v[24:25], off
	global_load_dwordx2 v[56:57], v[24:25], off offset:512
	global_load_dwordx2 v[58:59], v[24:25], off offset:1024
	global_load_dwordx2 v[60:61], v[24:25], off offset:1536
	v_readlane_b32 s14, v34, 2
	s_lshl_b64 s[8:9], s[8:9], 12
	s_lshl_b64 s[6:7], s[6:7], 12
	s_lshl_b64 s[4:5], s[4:5], 12
	s_waitcnt vmcnt(15)
	v_cvt_f32_f16_e32 v24, v26
	v_cvt_f32_f16_sdwa v25, v26 dst_sel:DWORD dst_unused:UNUSED_PAD src0_sel:WORD_1
	v_cvt_f32_f16_e32 v26, v27
	v_cvt_f32_f16_sdwa v27, v27 dst_sel:DWORD dst_unused:UNUSED_PAD src0_sel:WORD_1
	v_mul_f32_e32 v24, s14, v24
	v_mul_f32_e32 v25, s14, v25
	s_nop 0
	v_mul_f32_e32 v24, v2, v24
	v_mul_f32_e32 v25, v3, v25
	v_mul_f32_e32 v26, s14, v26
	v_mul_f32_e32 v27, s14, v27
	s_nop 0
	v_mul_f32_e32 v26, v4, v26
	v_mul_f32_e32 v27, v5, v27
	global_store_dwordx4 v[62:63], v[24:27], off sc1
	s_waitcnt vmcnt(15)
	s_nop 0
	v_cvt_f32_f16_e32 v24, v28
	v_cvt_f32_f16_sdwa v25, v28 dst_sel:DWORD dst_unused:UNUSED_PAD src0_sel:WORD_1
	v_cvt_f32_f16_e32 v26, v29
	v_cvt_f32_f16_sdwa v27, v29 dst_sel:DWORD dst_unused:UNUSED_PAD src0_sel:WORD_1
	v_lshl_add_u64 v[28:29], v[22:23], 0, s[8:9]
	v_mul_f32_e32 v24, s14, v24
	v_mul_f32_e32 v25, s14, v25
	v_readlane_b32 s8, v32, 2
	v_mul_f32_e32 v26, s14, v26
	v_mul_f32_e32 v27, s14, v27
	v_mul_f32_e32 v24, v6, v24
	v_mul_f32_e32 v25, v7, v25
	v_mul_f32_e32 v26, v8, v26
	v_mul_f32_e32 v27, v9, v27
	global_store_dwordx4 v[62:63], v[24:27], off offset:1024 sc1
	s_waitcnt vmcnt(15)
	s_nop 0
	v_cvt_f32_f16_e32 v24, v30
	v_cvt_f32_f16_sdwa v25, v30 dst_sel:DWORD dst_unused:UNUSED_PAD src0_sel:WORD_1
	v_cvt_f32_f16_e32 v26, v31
	v_cvt_f32_f16_sdwa v27, v31 dst_sel:DWORD dst_unused:UNUSED_PAD src0_sel:WORD_1
	v_mul_f32_e32 v24, s14, v24
	v_mul_f32_e32 v25, s14, v25
	s_nop 0
	v_mul_f32_e32 v24, v10, v24
	v_mul_f32_e32 v25, v11, v25
	v_mul_f32_e32 v26, s14, v26
	v_mul_f32_e32 v27, s14, v27
	s_nop 0
	v_mul_f32_e32 v26, v12, v26
	v_mul_f32_e32 v27, v13, v27
	global_store_dwordx4 v[62:63], v[24:27], off offset:2048 sc1
	s_waitcnt vmcnt(15)
	s_nop 0
	v_cvt_f32_f16_e32 v24, v36
	v_cvt_f32_f16_sdwa v25, v36 dst_sel:DWORD dst_unused:UNUSED_PAD src0_sel:WORD_1
	v_cvt_f32_f16_e32 v26, v37
	v_cvt_f32_f16_sdwa v27, v37 dst_sel:DWORD dst_unused:UNUSED_PAD src0_sel:WORD_1
	v_mul_f32_e32 v24, s14, v24
	v_mul_f32_e32 v25, s14, v25
	s_nop 0
	v_mul_f32_e32 v24, v14, v24
	v_mul_f32_e32 v25, v15, v25
	v_mul_f32_e32 v26, s14, v26
	v_mul_f32_e32 v27, s14, v27
	s_nop 0
	v_mul_f32_e32 v26, v16, v26
	v_mul_f32_e32 v27, v17, v27
	global_store_dwordx4 v[62:63], v[24:27], off offset:3072 sc1
	s_waitcnt vmcnt(15)
	s_nop 0
	v_cvt_f32_f16_e32 v24, v38
	v_cvt_f32_f16_sdwa v25, v38 dst_sel:DWORD dst_unused:UNUSED_PAD src0_sel:WORD_1
	v_cvt_f32_f16_e32 v26, v39
	v_cvt_f32_f16_sdwa v27, v39 dst_sel:DWORD dst_unused:UNUSED_PAD src0_sel:WORD_1
	v_mul_f32_e32 v24, s10, v24
	v_mul_f32_e32 v25, s10, v25
	s_nop 0
	v_mul_f32_e32 v24, v2, v24
	v_mul_f32_e32 v25, v3, v25
	v_mul_f32_e32 v26, s10, v26
	v_mul_f32_e32 v27, s10, v27
	s_nop 0
	v_mul_f32_e32 v26, v4, v26
	v_mul_f32_e32 v27, v5, v27
	global_store_dwordx4 v[28:29], v[24:27], off sc1
	s_waitcnt vmcnt(15)
	s_nop 0
	v_cvt_f32_f16_e32 v24, v40
	v_cvt_f32_f16_sdwa v25, v40 dst_sel:DWORD dst_unused:UNUSED_PAD src0_sel:WORD_1
	v_cvt_f32_f16_e32 v26, v41
	v_cvt_f32_f16_sdwa v27, v41 dst_sel:DWORD dst_unused:UNUSED_PAD src0_sel:WORD_1
	v_mul_f32_e32 v24, s10, v24
	v_mul_f32_e32 v25, s10, v25
	s_nop 0
	v_mul_f32_e32 v24, v6, v24
	v_mul_f32_e32 v25, v7, v25
	v_mul_f32_e32 v26, s10, v26
	v_mul_f32_e32 v27, s10, v27
	s_nop 0
	v_mul_f32_e32 v26, v8, v26
	v_mul_f32_e32 v27, v9, v27
	global_store_dwordx4 v[28:29], v[24:27], off offset:1024 sc1
	s_waitcnt vmcnt(15)
	s_nop 0
	v_cvt_f32_f16_e32 v24, v42
	v_cvt_f32_f16_sdwa v25, v42 dst_sel:DWORD dst_unused:UNUSED_PAD src0_sel:WORD_1
	v_cvt_f32_f16_e32 v26, v43
	v_cvt_f32_f16_sdwa v27, v43 dst_sel:DWORD dst_unused:UNUSED_PAD src0_sel:WORD_1
	v_mul_f32_e32 v24, s10, v24
	v_mul_f32_e32 v25, s10, v25
	s_nop 0
	v_mul_f32_e32 v24, v10, v24
	v_mul_f32_e32 v25, v11, v25
	v_mul_f32_e32 v26, s10, v26
	v_mul_f32_e32 v27, s10, v27
	s_nop 0
	v_mul_f32_e32 v26, v12, v26
	v_mul_f32_e32 v27, v13, v27
	global_store_dwordx4 v[28:29], v[24:27], off offset:2048 sc1
	s_waitcnt vmcnt(15)
; #define GAS __attribute__((address_space(1)))
; __device__ __forceinline__ float lx_get(float v, int src) { return __int_as_float(__builtin_amdgcn_readlane(__float_as_int(v), src)); }
; __device__ __forceinline__ void p_final(Frame& F) {
;     ...
;         for (int trip = 0; trip < 4; ++trip) {
;             h16x4 xv[4][4];
; #pragma unroll
;             for (int t = 0; t < 4; ++t)
; #pragma unroll
;                 for (int j = 0; j < 4; ++j) xv[t][j] = *(const GAS h16x4*)(X16 + (size_t)(rowb + 4 * trip + t) * D + j * 256 + F.lane * 4);
; #pragma unroll
;             for (int t = 0; t < 4; ++t) { const float rs = lx_get(qs[t], trip); float* orow = p.out + (size_t)(rowb + 4 * trip + t) * D;
; #pragma unroll
;                 for (int j = 0; j < 4; ++j) { const h16x4 v = xv[t][j];
;                     *(GAS f32x4*)(orow + j * 256 + F.lane * 4) = (f32x4){(float)v[0], (float)v[1], (float)v[2], (float)v[3]} * rs * gf[j]; } } }
	s_nop 0
	v_cvt_f32_f16_e32 v24, v44
	v_cvt_f32_f16_sdwa v25, v44 dst_sel:DWORD dst_unused:UNUSED_PAD src0_sel:WORD_1
	v_cvt_f32_f16_e32 v26, v45
	v_cvt_f32_f16_sdwa v27, v45 dst_sel:DWORD dst_unused:UNUSED_PAD src0_sel:WORD_1
	v_mul_f32_e32 v24, s10, v24
	v_mul_f32_e32 v25, s10, v25
	s_nop 0
	v_mul_f32_e32 v24, v14, v24
	v_mul_f32_e32 v25, v15, v25
	v_mul_f32_e32 v26, s10, v26
	v_mul_f32_e32 v27, s10, v27
	s_nop 0
	v_mul_f32_e32 v26, v16, v26
	v_mul_f32_e32 v27, v17, v27
	global_store_dwordx4 v[28:29], v[24:27], off offset:3072 sc1
	v_lshl_add_u64 v[28:29], v[22:23], 0, s[6:7]
	v_readlane_b32 s6, v0, 2
	s_waitcnt vmcnt(15)
	v_cvt_f32_f16_e32 v24, v46
	v_cvt_f32_f16_sdwa v25, v46 dst_sel:DWORD dst_unused:UNUSED_PAD src0_sel:WORD_1
	v_cvt_f32_f16_e32 v26, v47
	v_cvt_f32_f16_sdwa v27, v47 dst_sel:DWORD dst_unused:UNUSED_PAD src0_sel:WORD_1
	v_mul_f32_e32 v24, s8, v24
	v_mul_f32_e32 v25, s8, v25
	s_nop 0
	v_mul_f32_e32 v24, v2, v24
	v_mul_f32_e32 v25, v3, v25
	v_mul_f32_e32 v26, s8, v26
	v_mul_f32_e32 v27, s8, v27
	s_nop 0
	v_mul_f32_e32 v26, v4, v26
	v_mul_f32_e32 v27, v5, v27
	global_store_dwordx4 v[28:29], v[24:27], off sc1
	s_waitcnt vmcnt(15)
	s_nop 0
	v_cvt_f32_f16_e32 v24, v48
	v_cvt_f32_f16_sdwa v25, v48 dst_sel:DWORD dst_unused:UNUSED_PAD src0_sel:WORD_1
	v_cvt_f32_f16_e32 v26, v49
	v_cvt_f32_f16_sdwa v27, v49 dst_sel:DWORD dst_unused:UNUSED_PAD src0_sel:WORD_1
	v_mul_f32_e32 v24, s8, v24
	v_mul_f32_e32 v25, s8, v25
	s_nop 0
	v_mul_f32_e32 v24, v6, v24
	v_mul_f32_e32 v25, v7, v25
	v_mul_f32_e32 v26, s8, v26
	v_mul_f32_e32 v27, s8, v27
	s_nop 0
	v_mul_f32_e32 v26, v8, v26
	v_mul_f32_e32 v27, v9, v27
	global_store_dwordx4 v[28:29], v[24:27], off offset:1024 sc1
	s_waitcnt vmcnt(15)
	s_nop 0
	v_cvt_f32_f16_e32 v24, v50
	v_cvt_f32_f16_sdwa v25, v50 dst_sel:DWORD dst_unused:UNUSED_PAD src0_sel:WORD_1
	v_cvt_f32_f16_e32 v26, v51
	v_cvt_f32_f16_sdwa v27, v51 dst_sel:DWORD dst_unused:UNUSED_PAD src0_sel:WORD_1
	v_mul_f32_e32 v24, s8, v24
	v_mul_f32_e32 v25, s8, v25
	s_nop 0
	v_mul_f32_e32 v24, v10, v24
	v_mul_f32_e32 v25, v11, v25
	v_mul_f32_e32 v26, s8, v26
	v_mul_f32_e32 v27, s8, v27
	s_nop 0
	v_mul_f32_e32 v26, v12, v26
	v_mul_f32_e32 v27, v13, v27
	global_store_dwordx4 v[28:29], v[24:27], off offset:2048 sc1
	s_waitcnt vmcnt(15)
	s_nop 0
	v_cvt_f32_f16_e32 v24, v52
	v_cvt_f32_f16_sdwa v25, v52 dst_sel:DWORD dst_unused:UNUSED_PAD src0_sel:WORD_1
	v_cvt_f32_f16_e32 v26, v53
	v_cvt_f32_f16_sdwa v27, v53 dst_sel:DWORD dst_unused:UNUSED_PAD src0_sel:WORD_1
	v_mul_f32_e32 v24, s8, v24
	v_mul_f32_e32 v25, s8, v25
	s_nop 0
	v_mul_f32_e32 v24, v14, v24
	v_mul_f32_e32 v25, v15, v25
	v_mul_f32_e32 v26, s8, v26
	v_mul_f32_e32 v27, s8, v27
	s_add_i32 s8, s2, -3
	v_mul_f32_e32 v26, v16, v26
	v_mul_f32_e32 v27, v17, v27
	global_store_dwordx4 v[28:29], v[24:27], off offset:3072 sc1
	v_lshl_add_u64 v[28:29], v[22:23], 0, s[4:5]
	s_ashr_i32 s9, s8, 31
	s_waitcnt vmcnt(15)
	v_cvt_f32_f16_e32 v24, v54
	v_cvt_f32_f16_sdwa v25, v54 dst_sel:DWORD dst_unused:UNUSED_PAD src0_sel:WORD_1
	v_cvt_f32_f16_e32 v26, v55
	v_cvt_f32_f16_sdwa v27, v55 dst_sel:DWORD dst_unused:UNUSED_PAD src0_sel:WORD_1
	s_lshl_b64 s[4:5], s[8:9], 11
	v_mul_f32_e32 v24, s6, v24
	v_mul_f32_e32 v25, s6, v25
	s_lshl_b64 s[8:9], s[8:9], 12
	v_mul_f32_e32 v26, s6, v26
	v_mul_f32_e32 v27, s6, v27
	v_mul_f32_e32 v24, v2, v24
	v_mul_f32_e32 v25, v3, v25
	v_mul_f32_e32 v26, v4, v26
	v_mul_f32_e32 v27, v5, v27
	global_store_dwordx4 v[28:29], v[24:27], off sc1
	s_waitcnt vmcnt(15)
	s_nop 0
	v_cvt_f32_f16_e32 v24, v56
	v_cvt_f32_f16_sdwa v25, v56 dst_sel:DWORD dst_unused:UNUSED_PAD src0_sel:WORD_1
	v_cvt_f32_f16_e32 v26, v57
	v_cvt_f32_f16_sdwa v27, v57 dst_sel:DWORD dst_unused:UNUSED_PAD src0_sel:WORD_1
	v_mul_f32_e32 v24, s6, v24
	v_mul_f32_e32 v25, s6, v25
	s_nop 0
	v_mul_f32_e32 v24, v6, v24
	v_mul_f32_e32 v25, v7, v25
	v_mul_f32_e32 v26, s6, v26
	v_mul_f32_e32 v27, s6, v27
	s_nop 0
	v_mul_f32_e32 v26, v8, v26
	v_mul_f32_e32 v27, v9, v27
	global_store_dwordx4 v[28:29], v[24:27], off offset:1024 sc1
	s_waitcnt vmcnt(15)
	s_nop 0
	v_cvt_f32_f16_e32 v24, v58
	v_cvt_f32_f16_sdwa v25, v58 dst_sel:DWORD dst_unused:UNUSED_PAD src0_sel:WORD_1
	v_cvt_f32_f16_e32 v26, v59
	v_cvt_f32_f16_sdwa v27, v59 dst_sel:DWORD dst_unused:UNUSED_PAD src0_sel:WORD_1
	v_mul_f32_e32 v24, s6, v24
	v_mul_f32_e32 v25, s6, v25
	s_nop 0
	v_mul_f32_e32 v24, v10, v24
	v_mul_f32_e32 v25, v11, v25
	v_mul_f32_e32 v26, s6, v26
	v_mul_f32_e32 v27, s6, v27
	s_nop 0
	v_mul_f32_e32 v26, v12, v26
	v_mul_f32_e32 v27, v13, v27
	global_store_dwordx4 v[28:29], v[24:27], off offset:2048 sc1
	s_waitcnt vmcnt(15)
	s_nop 0
	v_cvt_f32_f16_e32 v24, v60
	v_cvt_f32_f16_sdwa v25, v60 dst_sel:DWORD dst_unused:UNUSED_PAD src0_sel:WORD_1
	v_cvt_f32_f16_e32 v26, v61
	v_cvt_f32_f16_sdwa v27, v61 dst_sel:DWORD dst_unused:UNUSED_PAD src0_sel:WORD_1
	v_mul_f32_e32 v24, s6, v24
	v_mul_f32_e32 v25, s6, v25
	s_nop 0
	v_mul_f32_e32 v24, v14, v24
	v_mul_f32_e32 v25, v15, v25
	v_mul_f32_e32 v26, s6, v26
	v_mul_f32_e32 v27, s6, v27
	s_add_i32 s6, s2, -2
	v_mul_f32_e32 v26, v16, v26
	v_mul_f32_e32 v27, v17, v27
	global_store_dwordx4 v[28:29], v[24:27], off offset:3072 sc1
	s_ashr_i32 s7, s6, 31
	s_nop 0
	v_lshl_add_u64 v[24:25], v[20:21], 0, s[4:5]
	global_load_dwordx2 v[26:27], v[24:25], off
	global_load_dwordx2 v[28:29], v[24:25], off offset:512
	global_load_dwordx2 v[30:31], v[24:25], off offset:1024
	global_load_dwordx2 v[36:37], v[24:25], off offset:1536
	s_lshl_b64 s[4:5], s[6:7], 11
	v_lshl_add_u64 v[24:25], v[20:21], 0, s[4:5]
	global_load_dwordx2 v[38:39], v[24:25], off
	global_load_dwordx2 v[40:41], v[24:25], off offset:512
	global_load_dwordx2 v[42:43], v[24:25], off offset:1024
	global_load_dwordx2 v[44:45], v[24:25], off offset:1536
	s_add_i32 s4, s2, -1
	s_ashr_i32 s5, s4, 31
	s_lshl_b64 s[10:11], s[4:5], 11
	v_lshl_add_u64 v[24:25], v[20:21], 0, s[10:11]
	global_load_dwordx2 v[46:47], v[24:25], off
	global_load_dwordx2 v[48:49], v[24:25], off offset:512
	global_load_dwordx2 v[50:51], v[24:25], off offset:1024
	global_load_dwordx2 v[52:53], v[24:25], off offset:1536
	s_lshl_b64 s[10:11], s[2:3], 11
	v_lshl_add_u64 v[24:25], v[20:21], 0, s[10:11]
	global_load_dwordx2 v[54:55], v[24:25], off
	global_load_dwordx2 v[56:57], v[24:25], off offset:512
	global_load_dwordx2 v[58:59], v[24:25], off offset:1024
	global_load_dwordx2 v[60:61], v[24:25], off offset:1536
	v_readlane_b32 s10, v34, 3
	v_lshl_add_u64 v[34:35], v[22:23], 0, s[8:9]
	v_readlane_b32 s8, v33, 3
	s_lshl_b64 s[6:7], s[6:7], 12
	s_lshl_b64 s[4:5], s[4:5], 12
	s_waitcnt vmcnt(15)
; #define GAS __attribute__((address_space(1)))
; __device__ __forceinline__ float lx_get(float v, int src) { return __int_as_float(__builtin_amdgcn_readlane(__float_as_int(v), src)); }
; __device__ __forceinline__ void p_final(Frame& F) {
;     ...
;         for (int trip = 0; trip < 4; ++trip) {
;             h16x4 xv[4][4];
; #pragma unroll
;             for (int t = 0; t < 4; ++t)
; #pragma unroll
;                 for (int j = 0; j < 4; ++j) xv[t][j] = *(const GAS h16x4*)(X16 + (size_t)(rowb + 4 * trip + t) * D + j * 256 + F.lane * 4);
; #pragma unroll
;             for (int t = 0; t < 4; ++t) { const float rs = lx_get(qs[t], trip); float* orow = p.out + (size_t)(rowb + 4 * trip + t) * D;
; #pragma unroll
;                 for (int j = 0; j < 4; ++j) { const h16x4 v = xv[t][j];
;                     *(GAS f32x4*)(orow + j * 256 + F.lane * 4) = (f32x4){(float)v[0], (float)v[1], (float)v[2], (float)v[3]} * rs * gf[j]; } } }
	v_cvt_f32_f16_e32 v24, v26
	v_cvt_f32_f16_sdwa v25, v26 dst_sel:DWORD dst_unused:UNUSED_PAD src0_sel:WORD_1
	v_cvt_f32_f16_e32 v26, v27
	v_cvt_f32_f16_sdwa v27, v27 dst_sel:DWORD dst_unused:UNUSED_PAD src0_sel:WORD_1
	v_mul_f32_e32 v24, s10, v24
	v_mul_f32_e32 v25, s10, v25
	s_nop 0
	v_mul_f32_e32 v24, v2, v24
	v_mul_f32_e32 v25, v3, v25
	v_mul_f32_e32 v26, s10, v26
	v_mul_f32_e32 v27, s10, v27
	s_nop 0
	v_mul_f32_e32 v26, v4, v26
	v_mul_f32_e32 v27, v5, v27
	global_store_dwordx4 v[34:35], v[24:27], off sc1
	s_waitcnt vmcnt(15)
	s_nop 0
	v_cvt_f32_f16_e32 v24, v28
	v_cvt_f32_f16_sdwa v25, v28 dst_sel:DWORD dst_unused:UNUSED_PAD src0_sel:WORD_1
	v_cvt_f32_f16_e32 v26, v29
	v_cvt_f32_f16_sdwa v27, v29 dst_sel:DWORD dst_unused:UNUSED_PAD src0_sel:WORD_1
	v_lshl_add_u64 v[28:29], v[22:23], 0, s[6:7]
	v_mul_f32_e32 v24, s10, v24
	v_mul_f32_e32 v25, s10, v25
	v_readlane_b32 s6, v32, 3
	v_mul_f32_e32 v26, s10, v26
	v_mul_f32_e32 v27, s10, v27
	v_mul_f32_e32 v24, v6, v24
	v_mul_f32_e32 v25, v7, v25
	v_mul_f32_e32 v26, v8, v26
	v_mul_f32_e32 v27, v9, v27
	global_store_dwordx4 v[34:35], v[24:27], off offset:1024 sc1
	s_waitcnt vmcnt(15)
	s_nop 0
	v_cvt_f32_f16_e32 v24, v30
	v_cvt_f32_f16_sdwa v25, v30 dst_sel:DWORD dst_unused:UNUSED_PAD src0_sel:WORD_1
	v_cvt_f32_f16_e32 v26, v31
	v_cvt_f32_f16_sdwa v27, v31 dst_sel:DWORD dst_unused:UNUSED_PAD src0_sel:WORD_1
	v_mul_f32_e32 v24, s10, v24
	v_mul_f32_e32 v25, s10, v25
	s_nop 0
	v_mul_f32_e32 v24, v10, v24
	v_mul_f32_e32 v25, v11, v25
	v_mul_f32_e32 v26, s10, v26
	v_mul_f32_e32 v27, s10, v27
	s_nop 0
	v_mul_f32_e32 v26, v12, v26
	v_mul_f32_e32 v27, v13, v27
	global_store_dwordx4 v[34:35], v[24:27], off offset:2048 sc1
	s_waitcnt vmcnt(15)
	s_nop 0
	v_cvt_f32_f16_e32 v24, v36
	v_cvt_f32_f16_sdwa v25, v36 dst_sel:DWORD dst_unused:UNUSED_PAD src0_sel:WORD_1
	v_cvt_f32_f16_e32 v26, v37
	v_cvt_f32_f16_sdwa v27, v37 dst_sel:DWORD dst_unused:UNUSED_PAD src0_sel:WORD_1
	v_mul_f32_e32 v24, s10, v24
	v_mul_f32_e32 v25, s10, v25
	s_nop 0
	v_mul_f32_e32 v24, v14, v24
	v_mul_f32_e32 v25, v15, v25
	v_mul_f32_e32 v26, s10, v26
	v_mul_f32_e32 v27, s10, v27
	s_nop 0
	v_mul_f32_e32 v26, v16, v26
	v_mul_f32_e32 v27, v17, v27
	global_store_dwordx4 v[34:35], v[24:27], off offset:3072 sc1
	s_waitcnt vmcnt(15)
	s_nop 0
	v_cvt_f32_f16_e32 v24, v38
	v_cvt_f32_f16_sdwa v25, v38 dst_sel:DWORD dst_unused:UNUSED_PAD src0_sel:WORD_1
	v_cvt_f32_f16_e32 v26, v39
	v_cvt_f32_f16_sdwa v27, v39 dst_sel:DWORD dst_unused:UNUSED_PAD src0_sel:WORD_1
	v_mul_f32_e32 v24, s8, v24
	v_mul_f32_e32 v25, s8, v25
	s_nop 0
	v_mul_f32_e32 v24, v2, v24
	v_mul_f32_e32 v25, v3, v25
	v_mul_f32_e32 v26, s8, v26
	v_mul_f32_e32 v27, s8, v27
	s_nop 0
	v_mul_f32_e32 v26, v4, v26
	v_mul_f32_e32 v27, v5, v27
	global_store_dwordx4 v[28:29], v[24:27], off sc1
	s_waitcnt vmcnt(15)
	s_nop 0
	v_cvt_f32_f16_e32 v24, v40
	v_cvt_f32_f16_sdwa v25, v40 dst_sel:DWORD dst_unused:UNUSED_PAD src0_sel:WORD_1
	v_cvt_f32_f16_e32 v26, v41
	v_cvt_f32_f16_sdwa v27, v41 dst_sel:DWORD dst_unused:UNUSED_PAD src0_sel:WORD_1
	v_mul_f32_e32 v24, s8, v24
	v_mul_f32_e32 v25, s8, v25
	s_nop 0
	v_mul_f32_e32 v24, v6, v24
	v_mul_f32_e32 v25, v7, v25
	v_mul_f32_e32 v26, s8, v26
	v_mul_f32_e32 v27, s8, v27
	s_nop 0
	v_mul_f32_e32 v26, v8, v26
	v_mul_f32_e32 v27, v9, v27
	global_store_dwordx4 v[28:29], v[24:27], off offset:1024 sc1
	s_waitcnt vmcnt(15)
	s_nop 0
	v_cvt_f32_f16_e32 v24, v42
	v_cvt_f32_f16_sdwa v25, v42 dst_sel:DWORD dst_unused:UNUSED_PAD src0_sel:WORD_1
	v_cvt_f32_f16_e32 v26, v43
	v_cvt_f32_f16_sdwa v27, v43 dst_sel:DWORD dst_unused:UNUSED_PAD src0_sel:WORD_1
	v_mul_f32_e32 v24, s8, v24
	v_mul_f32_e32 v25, s8, v25
	s_nop 0
	v_mul_f32_e32 v24, v10, v24
	v_mul_f32_e32 v25, v11, v25
	v_mul_f32_e32 v26, s8, v26
	v_mul_f32_e32 v27, s8, v27
	s_nop 0
	v_mul_f32_e32 v26, v12, v26
	v_mul_f32_e32 v27, v13, v27
	global_store_dwordx4 v[28:29], v[24:27], off offset:2048 sc1
	s_waitcnt vmcnt(15)
	s_nop 0
	v_cvt_f32_f16_e32 v24, v44
	v_cvt_f32_f16_sdwa v25, v44 dst_sel:DWORD dst_unused:UNUSED_PAD src0_sel:WORD_1
	v_cvt_f32_f16_e32 v26, v45
	v_cvt_f32_f16_sdwa v27, v45 dst_sel:DWORD dst_unused:UNUSED_PAD src0_sel:WORD_1
	v_mul_f32_e32 v24, s8, v24
	v_mul_f32_e32 v25, s8, v25
	s_nop 0
	v_mul_f32_e32 v24, v14, v24
	v_mul_f32_e32 v25, v15, v25
	v_mul_f32_e32 v26, s8, v26
	v_mul_f32_e32 v27, s8, v27
	s_nop 0
	v_mul_f32_e32 v26, v16, v26
	v_mul_f32_e32 v27, v17, v27
	global_store_dwordx4 v[28:29], v[24:27], off offset:3072 sc1
	v_lshl_add_u64 v[28:29], v[22:23], 0, s[4:5]
	v_readlane_b32 s4, v0, 3
	s_waitcnt vmcnt(15)
; #define GAS __attribute__((address_space(1)))
; __device__ __forceinline__ float lx_get(float v, int src) { return __int_as_float(__builtin_amdgcn_readlane(__float_as_int(v), src)); }
; __device__ __forceinline__ void p_final(Frame& F) {
;     ...
;         for (int trip = 0; trip < 4; ++trip) {
;             h16x4 xv[4][4];
; #pragma unroll
;             for (int t = 0; t < 4; ++t)
; #pragma unroll
;                 for (int j = 0; j < 4; ++j) xv[t][j] = *(const GAS h16x4*)(X16 + (size_t)(rowb + 4 * trip + t) * D + j * 256 + F.lane * 4);
; #pragma unroll
;             for (int t = 0; t < 4; ++t) { const float rs = lx_get(qs[t], trip); float* orow = p.out + (size_t)(rowb + 4 * trip + t) * D;
; #pragma unroll
;                 for (int j = 0; j < 4; ++j) { const h16x4 v = xv[t][j];
;                     *(GAS f32x4*)(orow + j * 256 + F.lane * 4) = (f32x4){(float)v[0], (float)v[1], (float)v[2], (float)v[3]} * rs * gf[j]; } } }
	v_cvt_f32_f16_e32 v24, v46
	v_cvt_f32_f16_sdwa v25, v46 dst_sel:DWORD dst_unused:UNUSED_PAD src0_sel:WORD_1
	v_cvt_f32_f16_e32 v26, v47
	v_cvt_f32_f16_sdwa v27, v47 dst_sel:DWORD dst_unused:UNUSED_PAD src0_sel:WORD_1
	v_mul_f32_e32 v24, s6, v24
	v_mul_f32_e32 v25, s6, v25
	s_nop 0
	v_mul_f32_e32 v24, v2, v24
	v_mul_f32_e32 v25, v3, v25
	v_mul_f32_e32 v26, s6, v26
	v_mul_f32_e32 v27, s6, v27
	s_nop 0
	v_mul_f32_e32 v26, v4, v26
	v_mul_f32_e32 v27, v5, v27
	global_store_dwordx4 v[28:29], v[24:27], off sc1
	s_waitcnt vmcnt(15)
	s_nop 0
	v_cvt_f32_f16_e32 v24, v48
	v_cvt_f32_f16_sdwa v25, v48 dst_sel:DWORD dst_unused:UNUSED_PAD src0_sel:WORD_1
	v_cvt_f32_f16_e32 v26, v49
	v_cvt_f32_f16_sdwa v27, v49 dst_sel:DWORD dst_unused:UNUSED_PAD src0_sel:WORD_1
	v_mul_f32_e32 v24, s6, v24
	v_mul_f32_e32 v25, s6, v25
	s_nop 0
	v_mul_f32_e32 v24, v6, v24
	v_mul_f32_e32 v25, v7, v25
	v_mul_f32_e32 v26, s6, v26
	v_mul_f32_e32 v27, s6, v27
	s_nop 0
	v_mul_f32_e32 v26, v8, v26
	v_mul_f32_e32 v27, v9, v27
	global_store_dwordx4 v[28:29], v[24:27], off offset:1024 sc1
	s_waitcnt vmcnt(15)
	s_nop 0
	v_cvt_f32_f16_e32 v24, v50
	v_cvt_f32_f16_sdwa v25, v50 dst_sel:DWORD dst_unused:UNUSED_PAD src0_sel:WORD_1
	v_cvt_f32_f16_e32 v26, v51
	v_cvt_f32_f16_sdwa v27, v51 dst_sel:DWORD dst_unused:UNUSED_PAD src0_sel:WORD_1
	v_mul_f32_e32 v24, s6, v24
	v_mul_f32_e32 v25, s6, v25
	s_nop 0
	v_mul_f32_e32 v24, v10, v24
	v_mul_f32_e32 v25, v11, v25
	v_mul_f32_e32 v26, s6, v26
	v_mul_f32_e32 v27, s6, v27
	s_nop 0
	v_mul_f32_e32 v26, v12, v26
	v_mul_f32_e32 v27, v13, v27
	global_store_dwordx4 v[28:29], v[24:27], off offset:2048 sc1
	s_waitcnt vmcnt(15)
	s_nop 0
	v_cvt_f32_f16_e32 v24, v52
	v_cvt_f32_f16_sdwa v25, v52 dst_sel:DWORD dst_unused:UNUSED_PAD src0_sel:WORD_1
	v_cvt_f32_f16_e32 v26, v53
	v_cvt_f32_f16_sdwa v27, v53 dst_sel:DWORD dst_unused:UNUSED_PAD src0_sel:WORD_1
	v_mul_f32_e32 v24, s6, v24
	v_mul_f32_e32 v25, s6, v25
	s_nop 0
	v_mul_f32_e32 v24, v14, v24
	v_mul_f32_e32 v25, v15, v25
	v_mul_f32_e32 v26, s6, v26
	v_mul_f32_e32 v27, s6, v27
	s_lshl_b64 s[6:7], s[2:3], 12
	v_mul_f32_e32 v26, v16, v26
	v_mul_f32_e32 v27, v17, v27
	global_store_dwordx4 v[28:29], v[24:27], off offset:3072 sc1
	v_lshl_add_u64 v[28:29], v[22:23], 0, s[6:7]
	s_add_i32 s2, s2, s13
	s_waitcnt vmcnt(15)
	v_cvt_f32_f16_e32 v24, v54
	v_cvt_f32_f16_sdwa v25, v54 dst_sel:DWORD dst_unused:UNUSED_PAD src0_sel:WORD_1
	v_cvt_f32_f16_e32 v26, v55
	v_cvt_f32_f16_sdwa v27, v55 dst_sel:DWORD dst_unused:UNUSED_PAD src0_sel:WORD_1
	s_cmpk_gt_i32 s12, 0x7ff
	v_mul_f32_e32 v24, s4, v24
	v_mul_f32_e32 v25, s4, v25
	v_mul_f32_e32 v26, s4, v26
	v_mul_f32_e32 v27, s4, v27
	s_nop 0
	v_mul_f32_e32 v26, v4, v26
	v_mul_f32_e32 v27, v5, v27
	v_mul_f32_e32 v24, v2, v24
	v_mul_f32_e32 v25, v3, v25
	global_store_dwordx4 v[28:29], v[24:27], off sc1
	s_waitcnt vmcnt(15)
	s_nop 0
	v_cvt_f32_f16_e32 v24, v56
	v_cvt_f32_f16_sdwa v25, v56 dst_sel:DWORD dst_unused:UNUSED_PAD src0_sel:WORD_1
	v_cvt_f32_f16_e32 v26, v57
	v_cvt_f32_f16_sdwa v27, v57 dst_sel:DWORD dst_unused:UNUSED_PAD src0_sel:WORD_1
	v_mul_f32_e32 v24, s4, v24
	v_mul_f32_e32 v25, s4, v25
	s_nop 0
	v_mul_f32_e32 v24, v6, v24
	v_mul_f32_e32 v25, v7, v25
	v_mul_f32_e32 v26, s4, v26
	v_mul_f32_e32 v27, s4, v27
	s_nop 0
	v_mul_f32_e32 v26, v8, v26
	v_mul_f32_e32 v27, v9, v27
	global_store_dwordx4 v[28:29], v[24:27], off offset:1024 sc1
	s_waitcnt vmcnt(15)
	s_nop 0
	v_cvt_f32_f16_e32 v24, v58
	v_cvt_f32_f16_sdwa v25, v58 dst_sel:DWORD dst_unused:UNUSED_PAD src0_sel:WORD_1
	v_cvt_f32_f16_e32 v26, v59
	v_cvt_f32_f16_sdwa v27, v59 dst_sel:DWORD dst_unused:UNUSED_PAD src0_sel:WORD_1
	v_mul_f32_e32 v24, s4, v24
	v_mul_f32_e32 v25, s4, v25
	s_nop 0
	v_mul_f32_e32 v24, v10, v24
	v_mul_f32_e32 v25, v11, v25
	v_mul_f32_e32 v26, s4, v26
	v_mul_f32_e32 v27, s4, v27
	s_nop 0
	v_mul_f32_e32 v26, v12, v26
	v_mul_f32_e32 v27, v13, v27
	global_store_dwordx4 v[28:29], v[24:27], off offset:2048 sc1
	s_waitcnt vmcnt(15)
	s_nop 0
	v_cvt_f32_f16_e32 v24, v60
	v_cvt_f32_f16_sdwa v25, v60 dst_sel:DWORD dst_unused:UNUSED_PAD src0_sel:WORD_1
	v_cvt_f32_f16_e32 v26, v61
	v_cvt_f32_f16_sdwa v27, v61 dst_sel:DWORD dst_unused:UNUSED_PAD src0_sel:WORD_1
	v_mul_f32_e32 v24, s4, v24
	v_mul_f32_e32 v25, s4, v25
	s_nop 0
	v_mul_f32_e32 v24, v14, v24
	v_mul_f32_e32 v25, v15, v25
	v_mul_f32_e32 v26, s4, v26
	v_mul_f32_e32 v27, s4, v27
	s_nop 0
	v_mul_f32_e32 v26, v16, v26
	v_mul_f32_e32 v27, v17, v27
	global_store_dwordx4 v[28:29], v[24:27], off offset:3072 sc1
	s_cbranch_scc0 .LBB0_19

; #define LAS __attribute__((address_space(3)))
; #define GAS __attribute__((address_space(1)))
; __device__ __forceinline__ void gmlp_unit(unsigned char* ws, h16* Y, const h16* Ws16  , const float* bs  , size_t r0, LAS unsigned char* lds, int tid) {
;     const int lane = tid & 63, wid = __builtin_amdgcn_readfirstlane(tid >> 6), r32 = lane & 31, hi = lane >> 5;
;     const h16* VN = (const h16*)(ws + WS_VN); const h16* GU = (const h16*)(ws + WS_GU); const h16* SZ = (const h16*)(ws + WS_SZ);
;     const int g = wid >> 1, ph = wid & 1; const h16* Wg = Ws16 + (size_t)g * 128 * 128;
;     u32x4 stg[8];
; #pragma unroll
;     for (int j = 0; j < 8; ++j) { const int i = tid + 512 * j, row = i >> 5, c8 = i & 31; stg[j] = *(const GAS u32x4*)(VN + (r0 + row) * 256 + c8 * 8); }
;     s16x8 af[2][8];
; #pragma unroll
;     for (int q = 0; q < 2; ++q)
; #pragma unroll
;         for (int ks = 0; ks < 8; ++ks) af[q][ks] = *(const GAS s16x8*)(Wg + (size_t)(32 * (2 * ph + q) + r32) * 128 + 16 * ks + 8 * hi);
;     const int erow = lane >> 3, ech = lane & 7;
;     h16x8 gu[2][4], sz[2][4]; float bias[2][4];
; #pragma unroll
;     for (int q = 0; q < 2; ++q)
; #pragma unroll
;         for (int ps = 0; ps < 4; ++ps) { bias[q][ps] = *(const GAS float*)(bs + g * 128 + 32 * (2 * ph + q) + 8 * ps + erow);
;             const size_t go = (r0 + 32 * (2 * ph + q) + 8 * ps + erow) * 256 + g * 64 + 8 * ech;
;             gu[q][ps] = *(const GAS h16x8*)(GU + go); sz[q][ps] = *(const GAS h16x8*)(SZ + go); }
;     ...
;         if (u < o_attn) {
;             mx::scan_unit(ws, u >> 3, (u >> 1) & 3, u & 1, chain + 64 * u, lds, tid); warm = false;
;         } else if (u < o_gmlp) {
;             const bool isl = u < o_attc; const int a = isl ? u - o_attn : u - o_attc;
;             const int qb = isl ? (a & 7) : 0, g = isl ? (a >> 3) : a, hq = g & 3, kvh = (g >> 2) & 1, b = g >> 3, h = kvh * 4 + hq;
;             const h16* Q = (const h16*)(ws + WS_Q); const h16* KB = (const h16*)(ws + WS_KB); const h16* VB = (const h16*)(ws + WS_VB); const h16* BZ = (const h16*)(ws + WS_BZ); h16* Y = (h16*)F.p.out;
;             const size_t row0 = isl ? (size_t)b * SEQ + qb * 256 : (size_t)MLAT + (size_t)b * CTXL; const size_t kvo = ((size_t)(b * 2 + kvh) * NKEY) * 64;
;             const attn_body::Seam sm{o_attn, o_attc, o_gmlp, Q, KB, VB, (volatile LAS int*)(F.lds + MISC_OFF + 384)};
.LBB0_47:
	s_or_b64 exec, exec, s[0:1]
	v_mov_b32_e32 v247, v212
	s_mov_b32 s50, s40
	s_xor_b64 s[0:1], s[2:3], -1
	s_add_i32 s41, s74, s50
	v_readlane_b32 s22, v253, 0
	v_mov_b32_e32 v211, 0x2880000
	v_readlane_b32 s23, v253, 1
	s_cmpk_gt_i32 s84, 0x7f
	s_mov_b64 s[6:7], -1
	s_cbranch_scc0 .LBB0_228
	s_mov_b64 s[2:3], -1
	s_cmp_ge_i32 s84, s78
	v_lshlrev_b32_e32 v131, 3, v247
	v_bfe_u32 v248, v247, 5, 1
	s_cbranch_scc0 .LBB0_50
	v_readlane_b32 s2, v253, 14
	v_readlane_b32 s3, v253, 15
	s_add_u32 s13, s22, s2
	s_addc_u32 s14, s23, s3
	s_sub_i32 s2, s84, s78
	s_mov_b32 s3, s40
	v_lshlrev_b32_e32 v171, 4, v247
	v_ashrrev_i32_e32 v4, 5, v247
	s_lshl_b64 s[2:3], s[2:3], 7
	v_and_b32_e32 v0, 0x1f0, v171
	v_ashrrev_i32_e32 v5, 31, v4
	v_lshl_add_u64 v[2:3], s[22:23], 0, v[0:1]
	s_mov_b64 s[10:11], 0x9780000
	v_lshl_add_u64 v[4:5], s[2:3], 0, v[4:5]
	v_lshl_add_u64 v[2:3], v[2:3], 0, s[10:11]
	v_lshlrev_b64 v[4:5], 9, v[4:5]
	v_lshl_add_u64 v[4:5], v[2:3], 0, v[4:5]
	global_load_dwordx4 v[160:163], v[4:5], off
	v_add_u32_e32 v0, 0x200, v247
	v_ashrrev_i32_e32 v4, 5, v0
	v_ashrrev_i32_e32 v5, 31, v4
	v_lshl_add_u64 v[4:5], s[2:3], 0, v[4:5]
	v_lshlrev_b64 v[4:5], 9, v[4:5]
	v_lshl_add_u64 v[4:5], v[2:3], 0, v[4:5]
	v_add_u32_e32 v0, 0x400, v247
	global_load_dwordx4 v[156:159], v[4:5], off
	v_ashrrev_i32_e32 v4, 5, v0
	v_ashrrev_i32_e32 v5, 31, v4
	v_lshl_add_u64 v[4:5], s[2:3], 0, v[4:5]
	v_lshlrev_b64 v[4:5], 9, v[4:5]
	v_lshl_add_u64 v[4:5], v[2:3], 0, v[4:5]
	v_add_u32_e32 v0, 0x600, v247
	global_load_dwordx4 v[152:155], v[4:5], off
	v_ashrrev_i32_e32 v4, 5, v0
	v_ashrrev_i32_e32 v5, 31, v4
	v_lshl_add_u64 v[4:5], s[2:3], 0, v[4:5]
	v_lshlrev_b64 v[4:5], 9, v[4:5]
	v_lshl_add_u64 v[4:5], v[2:3], 0, v[4:5]
	v_add_u32_e32 v0, 0x800, v247
	global_load_dwordx4 v[148:151], v[4:5], off
	v_ashrrev_i32_e32 v4, 5, v0
	v_ashrrev_i32_e32 v5, 31, v4
	v_lshl_add_u64 v[4:5], s[2:3], 0, v[4:5]
	v_lshlrev_b64 v[4:5], 9, v[4:5]
	v_lshl_add_u64 v[4:5], v[2:3], 0, v[4:5]
	v_add_u32_e32 v0, 0xa00, v247
	global_load_dwordx4 v[14:17], v[4:5], off
	v_ashrrev_i32_e32 v4, 5, v0
	v_ashrrev_i32_e32 v5, 31, v4
	v_lshl_add_u64 v[4:5], s[2:3], 0, v[4:5]
	v_lshlrev_b64 v[4:5], 9, v[4:5]
	v_lshl_add_u64 v[4:5], v[2:3], 0, v[4:5]
	v_add_u32_e32 v0, 0xc00, v247
	v_readfirstlane_b32 s15, v247
	s_add_u32 s8, s22, 0x8580000
	global_load_dwordx4 v[10:13], v[4:5], off
	v_ashrrev_i32_e32 v4, 5, v0
	s_addc_u32 s9, s23, 0
	s_ashr_i32 s4, s15, 7
	v_ashrrev_i32_e32 v5, 31, v4
	s_ashr_i32 s5, s4, 31
	v_lshl_add_u64 v[4:5], s[2:3], 0, v[4:5]
	s_ashr_i32 s12, s15, 6
	s_lshl_b64 s[6:7], s[4:5], 15
	v_lshlrev_b64 v[4:5], 9, v[4:5]
	s_and_b32 s16, s12, 1
	v_lshl_add_u64 v[4:5], v[2:3], 0, v[4:5]
	v_add_u32_e32 v0, 0xe00, v247
	s_add_u32 s6, s13, s6
	v_and_b32_e32 v169, 31, v247
	global_load_dwordx4 v[6:9], v[4:5], off
	v_ashrrev_i32_e32 v4, 5, v0
	s_addc_u32 s7, s14, s7
	v_lshlrev_b32_e32 v0, 4, v248
	v_lshl_add_u64 v[18:19], s[6:7], 0, v[0:1]
	v_lshlrev_b32_e32 v0, 8, v169
	v_lshl_or_b32 v0, s16, 14, v0
	v_lshl_add_u64 v[18:19], v[18:19], 0, v[0:1]
	s_mov_b64 s[6:7], 0x2500000
	s_mov_b32 s5, 0x2500000
	s_add_u32 s10, s22, 0xa980000
	v_lshl_add_u64 v[20:21], v[18:19], 0, s[6:7]
	s_waitcnt vmcnt(9)
	v_add_co_u32_e32 v22, vcc, s5, v18
	s_addc_u32 s11, s23, 0
	s_and_b32 s6, s15, 0xffffff80
	v_ashrrev_i32_e32 v5, 31, v4
	v_addc_co_u32_e32 v23, vcc, 0, v19, vcc
	s_mov_b32 s5, 0x2502000
	s_ashr_i32 s7, s6, 31
	v_lshl_add_u64 v[4:5], s[2:3], 0, v[4:5]
	v_add_co_u32_e32 v18, vcc, s5, v18
	s_lshl_b64 s[6:7], s[6:7], 2
	v_readlane_b32 s5, v253, 18
	v_lshlrev_b64 v[4:5], 9, v[4:5]
	v_bfe_u32 v167, v247, 3, 3
	s_add_u32 s6, s5, s6
	v_readlane_b32 s5, v253, 20
	v_lshl_add_u64 v[2:3], v[2:3], 0, v[4:5]
	v_addc_co_u32_e32 v19, vcc, 0, v19, vcc
	s_addc_u32 s7, s5, s7
	v_lshlrev_b32_e32 v0, 2, v167
	global_load_dwordx4 v[2:5], v[2:3], off
	s_nop 0
	global_load_dwordx4 v[140:143], v[22:23], off
	global_load_dwordx4 v[144:147], v[20:21], off offset:32
	global_load_dwordx4 v[136:139], v[20:21], off offset:64
	global_load_dwordx4 v[132:135], v[20:21], off offset:96
	global_load_dwordx4 v[126:129], v[20:21], off offset:128
	global_load_dwordx4 v[122:125], v[20:21], off offset:160
	global_load_dwordx4 v[118:121], v[20:21], off offset:192
	global_load_dwordx4 v[114:117], v[20:21], off offset:224
	global_load_dwordx4 v[78:81], v[18:19], off
	global_load_dwordx4 v[74:77], v[18:19], off offset:32
	global_load_dwordx4 v[70:73], v[18:19], off offset:64
	global_load_dwordx4 v[66:69], v[18:19], off offset:96
	global_load_dwordx4 v[62:65], v[18:19], off offset:128
	global_load_dwordx4 v[58:61], v[18:19], off offset:160
	global_load_dwordx4 v[54:57], v[18:19], off offset:192
	global_load_dwordx4 v[50:53], v[18:19], off offset:224
	s_lshl_b32 s5, s16, 6
	v_lshl_add_u64 v[18:19], s[6:7], 0, v[0:1]
	v_or_b32_e32 v28, s2, v167
	s_lshl_b32 s6, s4, 6
	s_ashr_i32 s7, s6, 31
	v_and_b32_e32 v0, 56, v131
	v_or_b32_e32 v164, s5, v28
	v_mov_b32_e32 v165, s3
	v_or_b32_e32 v20, s6, v0
	v_mov_b32_e32 v21, s7
	v_lshlrev_b64 v[22:23], 8, v[164:165]
	v_lshl_add_u64 v[22:23], v[22:23], 0, v[20:21]
	v_lshlrev_b64 v[22:23], 1, v[22:23]
	s_lshl_b32 s14, s16, 8
	s_mov_b32 s15, s40
	v_lshl_add_u64 v[24:25], s[8:9], 0, v[22:23]
	v_lshl_add_u64 v[18:19], v[18:19], 0, s[14:15]
	global_load_dwordx4 v[106:109], v[24:25], off
	v_lshl_add_u64 v[24:25], s[10:11], 0, v[22:23]
	s_mov_b64 s[14:15], 0x1000
	global_load_dword v180, v[18:19], off
	global_load_dwordx4 v[110:113], v[24:25], off
	global_load_dword v178, v[18:19], off offset:32
	v_lshl_add_u64 v[24:25], v[22:23], 0, s[14:15]
	v_lshl_add_u64 v[26:27], s[8:9], 0, v[24:25]
	v_lshl_add_u64 v[24:25], s[10:11], 0, v[24:25]
	s_mov_b64 s[16:17], 0x2000
	global_load_dwordx4 v[98:101], v[26:27], off
	global_load_dwordx4 v[102:105], v[24:25], off
	global_load_dword v176, v[18:19], off offset:64
	v_lshl_add_u64 v[24:25], v[22:23], 0, s[16:17]
	s_mov_b64 s[18:19], 0x3000
	v_lshl_add_u64 v[26:27], s[8:9], 0, v[24:25]
	v_lshl_add_u64 v[24:25], s[10:11], 0, v[24:25]
	v_lshl_add_u64 v[22:23], v[22:23], 0, s[18:19]
	s_or_b32 s3, s5, 32
	global_load_dwordx4 v[90:93], v[26:27], off
	global_load_dwordx4 v[94:97], v[24:25], off
	global_load_dword v174, v[18:19], off offset:96
	v_lshl_add_u64 v[24:25], s[8:9], 0, v[22:23]
	v_lshl_add_u64 v[22:23], s[10:11], 0, v[22:23]
	v_or_b32_e32 v164, s3, v28
	global_load_dwordx4 v[82:85], v[24:25], off
	global_load_dwordx4 v[86:89], v[22:23], off
	v_lshlrev_b64 v[22:23], 8, v[164:165]
	v_lshl_add_u64 v[20:21], v[22:23], 0, v[20:21]
	v_lshlrev_b64 v[20:21], 1, v[20:21]
	v_lshl_add_u64 v[22:23], s[8:9], 0, v[20:21]
	global_load_dwordx4 v[42:45], v[22:23], off
	v_lshl_add_u64 v[22:23], s[10:11], 0, v[20:21]
	global_load_dword v172, v[18:19], off offset:128
	global_load_dwordx4 v[46:49], v[22:23], off
	global_load_dword v170, v[18:19], off offset:160
	v_lshl_add_u64 v[22:23], v[20:21], 0, s[14:15]
	v_lshl_add_u64 v[24:25], s[8:9], 0, v[22:23]
	v_lshl_add_u64 v[22:23], s[10:11], 0, v[22:23]
	s_waitcnt vmcnt(39)
; #define LAS __attribute__((address_space(3)))
; __device__ __forceinline__ float geluf(float x) { return x * __builtin_amdgcn_rcpf(1.f + __builtin_amdgcn_exp2f(x * (-0.10294324f * x * x - 2.3022082f))); }
; __device__ __forceinline__ float lx_xor(float v, int m, int lane) { return __int_as_float(__builtin_amdgcn_ds_bpermute((lane ^ m) << 2, __float_as_int(v))); }
; __device__ __forceinline__ unsigned cvtpk_h(float lo, float hi) { f32x2 v = {lo, hi}; h16x2 b = __builtin_convertvector(v, h16x2); return __builtin_bit_cast(unsigned, b); }
; __device__ __forceinline__ void gmlp_unit(unsigned char* ws, h16* Y, const h16* Ws16  , const float* bs  , size_t r0, LAS unsigned char* lds, int tid) {
;     ...
;     for (int j = 0; j < 8; ++j) { const int i = tid + 512 * j, row = i >> 5, c8 = i & 31, gg = c8 >> 3, cg = (c8 & 7) * 8;
;         const h16x8 hv = __builtin_bit_cast(h16x8, stg[j]); float x[8]; float sm = 0.f;
; #pragma unroll
;         for (int k = 0; k < 8; ++k) { x[k] = geluf((float)hv[k]); sm += x[k]; }
;         sm += lx_xor(sm, 1, lane); sm += lx_xor(sm, 2, lane); sm += lx_xor(sm, 4, lane);
;         const float mu = sm * (1.f / 64.f); float q = 0.f;
; #pragma unroll
;         for (int k = 0; k < 8; ++k) { x[k] -= mu; q += x[k] * x[k]; }
;         q += lx_xor(q, 1, lane); q += lx_xor(q, 2, lane); q += lx_xor(q, 4, lane);
;         const float rd = __builtin_amdgcn_rsqf(q * (1.f / 64.f) + EPS);
;         u32x4 o; o.x = cvtpk_h(x[0] * rd, x[1] * rd); o.y = cvtpk_h(x[2] * rd, x[3] * rd); o.z = cvtpk_h(x[4] * rd, x[5] * rd); o.w = cvtpk_h(x[6] * rd, x[7] * rd);
;         *(LAS u32x4*)(lds + gg * 16384 + (cg >> 5) * 8192 + row * 64 + (cg & 31) * 2) = o; }
	v_cvt_f32_f16_e32 v192, v161
	v_cvt_f32_f16_sdwa v193, v161 dst_sel:DWORD dst_unused:UNUSED_PAD src0_sel:WORD_1
	global_load_dwordx4 v[34:37], v[24:25], off
	global_load_dwordx4 v[38:41], v[22:23], off
	global_load_dword v168, v[18:19], off offset:192
	v_lshl_add_u64 v[22:23], v[20:21], 0, s[16:17]
	v_lshl_add_u64 v[24:25], s[8:9], 0, v[22:23]
	v_lshl_add_u64 v[22:23], s[10:11], 0, v[22:23]
	global_load_dwordx4 v[26:29], v[24:25], off
	global_load_dwordx4 v[30:33], v[22:23], off
	global_load_dword v166, v[18:19], off offset:224
	v_lshl_add_u64 v[22:23], v[20:21], 0, s[18:19]
	v_lshl_add_u64 v[18:19], s[8:9], 0, v[22:23]
	v_cvt_f32_f16_e32 v182, v163
	v_cvt_f32_f16_sdwa v183, v163 dst_sel:DWORD dst_unused:UNUSED_PAD src0_sel:WORD_1
	s_mov_b32 s9, 0xc0135761
	v_mul_f32_e32 v194, 0x3dd2d3e8, v192
	v_mul_f32_e32 v195, 0x3dd2d3e8, v193
	v_fma_mix_f32 v194, -v194, v161, s9 op_sel_hi:[0,1,0]
	v_fma_mix_f32 v161, -v195, v161, s9 op_sel:[0,1,0] op_sel_hi:[0,1,0]
	v_mul_f32_e32 v161, v161, v193
	v_exp_f32_e32 v161, v161
	v_mul_f32_e32 v184, 0x3dd2d3e8, v182
	v_mul_f32_e32 v185, 0x3dd2d3e8, v183
	v_cvt_f32_f16_e32 v198, v160
	v_fma_mix_f32 v184, -v184, v163, s9 op_sel_hi:[0,1,0]
	v_fma_mix_f32 v163, -v185, v163, s9 op_sel:[0,1,0] op_sel_hi:[0,1,0]
	v_mul_f32_e32 v163, v163, v183
	v_exp_f32_e32 v163, v163
	v_add_f32_e32 v161, 1.0, v161
	v_cvt_f32_f16_e32 v186, v162
	v_rcp_f32_e32 v195, v161
	v_mul_f32_e32 v161, 0x3dd2d3e8, v198
	v_fma_mix_f32 v161, -v161, v160, s9 op_sel_hi:[0,1,0]
	v_mul_f32_e32 v161, v161, v198
	v_add_f32_e32 v163, 1.0, v163
	v_exp_f32_e32 v161, v161
	v_rcp_f32_e32 v185, v163
	v_mul_f32_e32 v163, 0x3dd2d3e8, v186
	v_cvt_f32_f16_sdwa v199, v160 dst_sel:DWORD dst_unused:UNUSED_PAD src0_sel:WORD_1
	v_fma_mix_f32 v163, -v163, v162, s9 op_sel_hi:[0,1,0]
	v_mul_f32_e32 v163, v163, v186
	v_exp_f32_e32 v163, v163
	v_add_f32_e32 v161, 1.0, v161
	v_cvt_f32_f16_sdwa v187, v162 dst_sel:DWORD dst_unused:UNUSED_PAD src0_sel:WORD_1
	v_rcp_f32_e32 v200, v161
	v_mul_f32_e32 v161, 0x3dd2d3e8, v199
	v_fma_mix_f32 v160, -v161, v160, s9 op_sel:[0,1,0] op_sel_hi:[0,1,0]
	v_mul_f32_e32 v160, v160, v199
	v_add_f32_e32 v163, 1.0, v163
	v_exp_f32_e32 v160, v160
	v_rcp_f32_e32 v190, v163
	v_mul_f32_e32 v163, 0x3dd2d3e8, v187
	v_mul_f32_e32 v194, v194, v192
	v_fma_mix_f32 v162, -v163, v162, s9 op_sel:[0,1,0] op_sel_hi:[0,1,0]
	v_exp_f32_e32 v194, v194
	v_mul_f32_e32 v162, v162, v187
	v_exp_f32_e32 v162, v162
	v_add_f32_e32 v160, 1.0, v160
	v_mul_f32_e32 v184, v184, v182
	v_rcp_f32_e32 v201, v160
	v_exp_f32_e32 v184, v184
	v_add_f32_e32 v194, 1.0, v194
	v_rcp_f32_e32 v194, v194
	v_add_f32_e32 v162, 1.0, v162
	v_rcp_f32_e32 v191, v162
	v_mul_f32_e32 v160, v200, v198
	v_mul_f32_e32 v161, v201, v199
	v_add_f32_e32 v184, 1.0, v184
	v_add_f32_e32 v160, 0, v160
	v_rcp_f32_e32 v184, v184
	v_mul_f32_e32 v196, v194, v192
	v_mul_f32_e32 v197, v195, v193
	v_add_f32_e32 v160, v161, v160
	v_add_f32_e32 v160, v196, v160
	v_mul_f32_e32 v162, v190, v186
	v_mul_f32_e32 v163, v191, v187
	v_add_f32_e32 v160, v197, v160
	v_add_f32_e32 v160, v162, v160
	v_and_b32_e32 v173, 63, v247
	v_mul_f32_e32 v188, v184, v182
	v_mul_f32_e32 v189, v185, v183
	v_add_f32_e32 v160, v163, v160
	v_lshlrev_b32_e32 v164, 2, v173
	v_add_f32_e32 v160, v188, v160
	v_xor_b32_e32 v177, 4, v164
	v_add_f32_e32 v160, v189, v160
	s_nop 0
	v_xor_b32_e32 v175, 8, v164
	v_xor_b32_e32 v173, 16, v164
	v_lshlrev_b32_e32 v179, 11, v247
	v_and_b32_e32 v181, 0xc000, v179
	s_nop 1
	v_add_f32_dpp v160, v160, v160 quad_perm:[1,0,3,2] row_mask:0xf bank_mask:0xf
	s_nop 0
	v_and_b32_e32 v179, 0x2000, v179
	v_add3_u32 v179, s41, v181, v179
	v_lshlrev_b32_e32 v181, 1, v247
	v_and_b32_e32 v202, 48, v171
	s_nop 1
	v_add_f32_dpp v160, v160, v160 quad_perm:[2,3,0,1] row_mask:0xf bank_mask:0xf
	s_nop 0
	v_and_b32_e32 v181, 0xffffffc0, v181
	v_add3_u32 v179, v179, v202, v181
	s_lshl_b32 s4, s4, 14
	v_lshl_add_u64 v[22:23], s[10:11], 0, v[22:23]
	s_nop 1
	v_add_f32_dpp v160, v160, v160 row_half_mirror row_mask:0xf bank_mask:0xf
	v_mul_f32_e32 v160, 0x3c800000, v160
	v_fma_f32 v162, v200, v198, -v160
	v_fma_f32 v163, v201, v199, -v160
	v_fma_f32 v192, v194, v192, -v160
	v_fma_f32 v193, v195, v193, -v160
	v_mul_f32_e32 v188, v162, v162
	v_mul_f32_e32 v189, v163, v163
	v_mul_f32_e32 v194, v192, v192
	v_mul_f32_e32 v195, v193, v193
	v_fma_f32 v182, v184, v182, -v160
	v_fma_f32 v183, v185, v183, -v160
	v_add_f32_e32 v184, v188, v189
	v_fma_f32 v186, v190, v186, -v160
	v_fma_f32 v187, v191, v187, -v160
	v_add_f32_e32 v184, v194, v184
	v_mul_f32_e32 v190, v186, v186
	v_mul_f32_e32 v191, v187, v187
	v_add_f32_e32 v184, v195, v184
	v_add_f32_e32 v184, v190, v184
	v_mul_f32_e32 v160, v182, v182
	v_mul_f32_e32 v161, v183, v183
	v_add_f32_e32 v184, v191, v184
	v_add_f32_e32 v160, v160, v184
	v_add_f32_e32 v160, v161, v160
	s_nop 0
	s_waitcnt vmcnt(44)
; #define LAS __attribute__((address_space(3)))
; __device__ __forceinline__ float geluf(float x) { return x * __builtin_amdgcn_rcpf(1.f + __builtin_amdgcn_exp2f(x * (-0.10294324f * x * x - 2.3022082f))); }
; __device__ __forceinline__ float lx_xor(float v, int m, int lane) { return __int_as_float(__builtin_amdgcn_ds_bpermute((lane ^ m) << 2, __float_as_int(v))); }
; __device__ __forceinline__ unsigned cvtpk_h(float lo, float hi) { f32x2 v = {lo, hi}; h16x2 b = __builtin_convertvector(v, h16x2); return __builtin_bit_cast(unsigned, b); }
; __device__ __forceinline__ void gmlp_unit(unsigned char* ws, h16* Y, const h16* Ws16  , const float* bs  , size_t r0, LAS unsigned char* lds, int tid) {
;     ...
;     for (int j = 0; j < 8; ++j) { const int i = tid + 512 * j, row = i >> 5, c8 = i & 31, gg = c8 >> 3, cg = (c8 & 7) * 8;
;         const h16x8 hv = __builtin_bit_cast(h16x8, stg[j]); float x[8]; float sm = 0.f;
; #pragma unroll
;         for (int k = 0; k < 8; ++k) { x[k] = geluf((float)hv[k]); sm += x[k]; }
;         sm += lx_xor(sm, 1, lane); sm += lx_xor(sm, 2, lane); sm += lx_xor(sm, 4, lane);
;         const float mu = sm * (1.f / 64.f); float q = 0.f;
; #pragma unroll
;         for (int k = 0; k < 8; ++k) { x[k] -= mu; q += x[k] * x[k]; }
;         q += lx_xor(q, 1, lane); q += lx_xor(q, 2, lane); q += lx_xor(q, 4, lane);
;         const float rd = __builtin_amdgcn_rsqf(q * (1.f / 64.f) + EPS);
;         u32x4 o; o.x = cvtpk_h(x[0] * rd, x[1] * rd); o.y = cvtpk_h(x[2] * rd, x[3] * rd); o.z = cvtpk_h(x[4] * rd, x[5] * rd); o.w = cvtpk_h(x[6] * rd, x[7] * rd);
;         *(LAS u32x4*)(lds + gg * 16384 + (cg >> 5) * 8192 + row * 64 + (cg & 31) * 2) = o; }
	v_cvt_f32_f16_e32 v188, v157
	v_cvt_f32_f16_sdwa v189, v157 dst_sel:DWORD dst_unused:UNUSED_PAD src0_sel:WORD_1
	v_cvt_f32_f16_e32 v194, v156
	v_cvt_f32_f16_sdwa v195, v156 dst_sel:DWORD dst_unused:UNUSED_PAD src0_sel:WORD_1
	s_nop 1
	v_add_f32_dpp v160, v160, v160 quad_perm:[1,0,3,2] row_mask:0xf bank_mask:0xf
	s_nop 0
	v_mul_f32_e32 v181, 0x3dd2d3e8, v188
	v_fma_mix_f32 v181, -v181, v157, s9 op_sel_hi:[0,1,0]
	v_mul_f32_e32 v181, v181, v188
	v_exp_f32_e32 v181, v181
	s_nop 1
	v_add_f32_dpp v160, v160, v160 quad_perm:[2,3,0,1] row_mask:0xf bank_mask:0xf
	s_nop 0
	s_add_i32 s4, s41, s4
	v_add_f32_e32 v181, 1.0, v181
	v_rcp_f32_e32 v190, v181
	v_mul_f32_e32 v181, 0x3dd2d3e8, v189
	s_nop 1
	v_add_f32_dpp v160, v160, v160 row_half_mirror row_mask:0xf bank_mask:0xf
	v_fmamk_f32 v160, v160, 0x3c800000, v229
	v_rsq_f32_e32 v184, v160
	v_fma_mix_f32 v157, -v181, v157, s9 op_sel:[0,1,0] op_sel_hi:[0,1,0]
	v_mul_f32_e32 v157, v157, v189
	v_exp_f32_e32 v157, v157
	v_mul_f32_e32 v160, v162, v184
	v_mul_f32_e32 v161, v163, v184
	v_mul_f32_e32 v162, v192, v184
	v_mul_f32_e32 v163, v193, v184
	v_cvt_pk_f16_f32 v160, v160, v161
	v_cvt_pk_f16_f32 v161, v162, v163
	v_mul_f32_e32 v162, v186, v184
	v_mul_f32_e32 v163, v187, v184
	v_mul_f32_e32 v182, v182, v184
	v_mul_f32_e32 v183, v183, v184
	v_cvt_pk_f16_f32 v162, v162, v163
	v_cvt_pk_f16_f32 v163, v182, v183
	ds_write_b128 v179, v[160:163]
	v_cvt_f32_f16_e32 v160, v159
	v_cvt_f32_f16_sdwa v161, v159 dst_sel:DWORD dst_unused:UNUSED_PAD src0_sel:WORD_1
	v_add_f32_e32 v157, 1.0, v157
	v_cvt_f32_f16_e32 v184, v158
	v_mul_f32_e32 v162, 0x3dd2d3e8, v160
	v_mul_f32_e32 v163, 0x3dd2d3e8, v161
	v_fma_mix_f32 v162, -v162, v159, s9 op_sel_hi:[0,1,0]
	v_fma_mix_f32 v159, -v163, v159, s9 op_sel:[0,1,0] op_sel_hi:[0,1,0]
	v_mul_f32_e32 v159, v159, v161
	v_exp_f32_e32 v159, v159
	v_rcp_f32_e32 v191, v157
	v_mul_f32_e32 v157, 0x3dd2d3e8, v194
	v_fma_mix_f32 v157, -v157, v156, s9 op_sel_hi:[0,1,0]
	v_mul_f32_e32 v157, v157, v194
	v_add_f32_e32 v159, 1.0, v159
	v_exp_f32_e32 v157, v157
	v_rcp_f32_e32 v163, v159
	v_mul_f32_e32 v159, 0x3dd2d3e8, v184
	v_fma_mix_f32 v159, -v159, v158, s9 op_sel_hi:[0,1,0]
	v_mul_f32_e32 v159, v159, v184
	v_exp_f32_e32 v159, v159
	v_add_f32_e32 v157, 1.0, v157
	v_cvt_f32_f16_sdwa v185, v158 dst_sel:DWORD dst_unused:UNUSED_PAD src0_sel:WORD_1
	v_rcp_f32_e32 v196, v157
	v_mul_f32_e32 v157, 0x3dd2d3e8, v195
	v_fma_mix_f32 v156, -v157, v156, s9 op_sel:[0,1,0] op_sel_hi:[0,1,0]
	v_mul_f32_e32 v156, v156, v195
	v_add_f32_e32 v159, 1.0, v159
	v_exp_f32_e32 v156, v156
	v_rcp_f32_e32 v186, v159
	v_mul_f32_e32 v159, 0x3dd2d3e8, v185
	v_fma_mix_f32 v158, -v159, v158, s9 op_sel:[0,1,0] op_sel_hi:[0,1,0]
	v_mul_f32_e32 v158, v158, v185
	v_exp_f32_e32 v158, v158
	v_add_f32_e32 v156, 1.0, v156
	v_mul_f32_e32 v162, v162, v160
	v_rcp_f32_e32 v197, v156
	v_exp_f32_e32 v162, v162
	v_add_f32_e32 v158, 1.0, v158
	v_rcp_f32_e32 v187, v158
	v_mul_f32_e32 v156, v196, v194
	v_mul_f32_e32 v157, v197, v195
	v_add_f32_e32 v162, 1.0, v162
	v_add_f32_e32 v156, 0, v156
	v_rcp_f32_e32 v162, v162
	v_mul_f32_e32 v192, v190, v188
	v_mul_f32_e32 v193, v191, v189
	v_add_f32_e32 v156, v157, v156
	v_add_f32_e32 v156, v192, v156
	v_mul_f32_e32 v158, v186, v184
	v_mul_f32_e32 v159, v187, v185
	v_add_f32_e32 v156, v193, v156
	v_add_f32_e32 v156, v158, v156
	v_mul_f32_e32 v182, v162, v160
	v_mul_f32_e32 v183, v163, v161
	v_add_f32_e32 v156, v159, v156
	v_add_f32_e32 v156, v182, v156
	v_add_f32_e32 v156, v183, v156
	s_nop 0
	global_load_dwordx4 v[18:21], v[18:19], off
	s_mulk_i32 s12, 0x1200
	global_load_dwordx4 v[22:25], v[22:23], off
	s_add_i32 s8, s41, s12
	s_nop 1
	v_add_f32_dpp v156, v156, v156 quad_perm:[1,0,3,2] row_mask:0xf bank_mask:0xf
	s_nop 0
	s_add_i32 s8, s8, 0x10000
	s_lshl_b64 s[6:7], s[6:7], 1
	v_readlane_b32 s12, v251, 0
	v_readlane_b32 s13, v251, 1
	s_nop 1
	v_add_f32_dpp v156, v156, v156 quad_perm:[2,3,0,1] row_mask:0xf bank_mask:0xf
	s_nop 0
	s_add_u32 s6, s12, s6
	v_lshlrev_b32_e32 v0, 1, v0
	s_addc_u32 s7, s13, s7
	v_readlane_b32 s14, v251, 2
	s_nop 1
	v_add_f32_dpp v156, v156, v156 row_half_mirror row_mask:0xf bank_mask:0xf
	v_mul_f32_e32 v156, 0x3c800000, v156
	v_fma_f32 v158, v196, v194, -v156
	v_fma_f32 v159, v197, v195, -v156
	v_fma_f32 v188, v190, v188, -v156
	v_fma_f32 v189, v191, v189, -v156
	v_mul_f32_e32 v182, v158, v158
	v_mul_f32_e32 v183, v159, v159
	v_mul_f32_e32 v190, v188, v188
	v_mul_f32_e32 v191, v189, v189
	v_fma_f32 v160, v162, v160, -v156
	v_fma_f32 v161, v163, v161, -v156
	v_add_f32_e32 v162, v182, v183
	v_fma_f32 v184, v186, v184, -v156
	v_fma_f32 v185, v187, v185, -v156
	v_add_f32_e32 v162, v190, v162
	v_mul_f32_e32 v186, v184, v184
	v_mul_f32_e32 v187, v185, v185
	v_add_f32_e32 v162, v191, v162
	v_add_f32_e32 v162, v186, v162
	v_mul_f32_e32 v156, v160, v160
	v_mul_f32_e32 v157, v161, v161
	v_add_f32_e32 v162, v187, v162
	v_add_f32_e32 v156, v156, v162
	v_add_f32_e32 v156, v157, v156
	s_nop 0
	s_waitcnt vmcnt(45)
; #define LAS __attribute__((address_space(3)))
; __device__ __forceinline__ float geluf(float x) { return x * __builtin_amdgcn_rcpf(1.f + __builtin_amdgcn_exp2f(x * (-0.10294324f * x * x - 2.3022082f))); }
; __device__ __forceinline__ float lx_xor(float v, int m, int lane) { return __int_as_float(__builtin_amdgcn_ds_bpermute((lane ^ m) << 2, __float_as_int(v))); }
; __device__ __forceinline__ unsigned cvtpk_h(float lo, float hi) { f32x2 v = {lo, hi}; h16x2 b = __builtin_convertvector(v, h16x2); return __builtin_bit_cast(unsigned, b); }
; __device__ __forceinline__ void gmlp_unit(unsigned char* ws, h16* Y, const h16* Ws16  , const float* bs  , size_t r0, LAS unsigned char* lds, int tid) {
;     ...
;     for (int j = 0; j < 8; ++j) { const int i = tid + 512 * j, row = i >> 5, c8 = i & 31, gg = c8 >> 3, cg = (c8 & 7) * 8;
;         const h16x8 hv = __builtin_bit_cast(h16x8, stg[j]); float x[8]; float sm = 0.f;
; #pragma unroll
;         for (int k = 0; k < 8; ++k) { x[k] = geluf((float)hv[k]); sm += x[k]; }
;         sm += lx_xor(sm, 1, lane); sm += lx_xor(sm, 2, lane); sm += lx_xor(sm, 4, lane);
;         const float mu = sm * (1.f / 64.f); float q = 0.f;
; #pragma unroll
;         for (int k = 0; k < 8; ++k) { x[k] -= mu; q += x[k] * x[k]; }
;         q += lx_xor(q, 1, lane); q += lx_xor(q, 2, lane); q += lx_xor(q, 4, lane);
;         const float rd = __builtin_amdgcn_rsqf(q * (1.f / 64.f) + EPS);
;         u32x4 o; o.x = cvtpk_h(x[0] * rd, x[1] * rd); o.y = cvtpk_h(x[2] * rd, x[3] * rd); o.z = cvtpk_h(x[4] * rd, x[5] * rd); o.w = cvtpk_h(x[6] * rd, x[7] * rd);
;         *(LAS u32x4*)(lds + gg * 16384 + (cg >> 5) * 8192 + row * 64 + (cg & 31) * 2) = o; }
	v_cvt_f32_f16_e32 v190, v152
	v_cvt_f32_f16_sdwa v191, v152 dst_sel:DWORD dst_unused:UNUSED_PAD src0_sel:WORD_1
	v_readlane_b32 s15, v251, 3
	v_readlane_b32 s16, v251, 4
	s_nop 1
	v_add_f32_dpp v156, v156, v156 quad_perm:[1,0,3,2] row_mask:0xf bank_mask:0xf
	s_nop 0
	v_readlane_b32 s17, v251, 5
	v_readlane_b32 s18, v251, 6
	v_readlane_b32 s19, v251, 7
	s_nop 1
	v_add_f32_dpp v156, v156, v156 quad_perm:[2,3,0,1] row_mask:0xf bank_mask:0xf
	s_nop 0
	s_nop 1
	v_add_f32_dpp v156, v156, v156 row_half_mirror row_mask:0xf bank_mask:0xf
	v_fmamk_f32 v156, v156, 0x3c800000, v229
	v_rsq_f32_e32 v162, v156
	s_nop 0
	v_mul_f32_e32 v156, v158, v162
	v_mul_f32_e32 v157, v159, v162
	v_mul_f32_e32 v158, v188, v162
	v_mul_f32_e32 v159, v189, v162
	v_cvt_pk_f16_f32 v156, v156, v157
	v_cvt_pk_f16_f32 v157, v158, v159
	v_mul_f32_e32 v158, v184, v162
	v_mul_f32_e32 v159, v185, v162
	v_cvt_f32_f16_e32 v184, v153
	v_cvt_f32_f16_sdwa v185, v153 dst_sel:DWORD dst_unused:UNUSED_PAD src0_sel:WORD_1
	v_mul_f32_e32 v160, v160, v162
	v_mul_f32_e32 v161, v161, v162
	v_cvt_pk_f16_f32 v158, v158, v159
	v_mul_f32_e32 v181, 0x3dd2d3e8, v184
	v_fma_mix_f32 v181, -v181, v153, s9 op_sel_hi:[0,1,0]
	v_mul_f32_e32 v181, v181, v184
	v_exp_f32_e32 v181, v181
	v_cvt_pk_f16_f32 v159, v160, v161
	ds_write_b128 v179, v[156:159] offset:1024
	v_cvt_f32_f16_e32 v156, v155
	v_add_f32_e32 v181, 1.0, v181
	v_cvt_f32_f16_sdwa v157, v155 dst_sel:DWORD dst_unused:UNUSED_PAD src0_sel:WORD_1
	v_rcp_f32_e32 v186, v181
	v_mul_f32_e32 v181, 0x3dd2d3e8, v185
	v_fma_mix_f32 v153, -v181, v153, s9 op_sel:[0,1,0] op_sel_hi:[0,1,0]
	v_mul_f32_e32 v153, v153, v185
	v_exp_f32_e32 v153, v153
	v_mul_f32_e32 v158, 0x3dd2d3e8, v156
	v_mul_f32_e32 v159, 0x3dd2d3e8, v157
	v_fma_mix_f32 v158, -v158, v155, s9 op_sel_hi:[0,1,0]
	v_fma_mix_f32 v155, -v159, v155, s9 op_sel:[0,1,0] op_sel_hi:[0,1,0]
	v_mul_f32_e32 v155, v155, v157
	v_exp_f32_e32 v155, v155
	v_add_f32_e32 v153, 1.0, v153
	v_cvt_f32_f16_e32 v162, v154
	v_rcp_f32_e32 v187, v153
	v_mul_f32_e32 v153, 0x3dd2d3e8, v190
	v_fma_mix_f32 v153, -v153, v152, s9 op_sel_hi:[0,1,0]
	v_mul_f32_e32 v153, v153, v190
	v_add_f32_e32 v155, 1.0, v155
	v_exp_f32_e32 v153, v153
	v_rcp_f32_e32 v159, v155
	v_mul_f32_e32 v155, 0x3dd2d3e8, v162
	v_fma_mix_f32 v155, -v155, v154, s9 op_sel_hi:[0,1,0]
	v_mul_f32_e32 v155, v155, v162
	v_exp_f32_e32 v155, v155
	v_add_f32_e32 v153, 1.0, v153
	v_cvt_f32_f16_sdwa v163, v154 dst_sel:DWORD dst_unused:UNUSED_PAD src0_sel:WORD_1
	v_rcp_f32_e32 v192, v153
	v_mul_f32_e32 v153, 0x3dd2d3e8, v191
	v_fma_mix_f32 v152, -v153, v152, s9 op_sel:[0,1,0] op_sel_hi:[0,1,0]
	v_mul_f32_e32 v152, v152, v191
	v_add_f32_e32 v155, 1.0, v155
	v_exp_f32_e32 v152, v152
	v_rcp_f32_e32 v182, v155
	v_mul_f32_e32 v155, 0x3dd2d3e8, v163
	v_fma_mix_f32 v154, -v155, v154, s9 op_sel:[0,1,0] op_sel_hi:[0,1,0]
	v_mul_f32_e32 v154, v154, v163
	v_exp_f32_e32 v154, v154
	v_add_f32_e32 v152, 1.0, v152
	v_mul_f32_e32 v158, v158, v156
	v_rcp_f32_e32 v193, v152
	v_exp_f32_e32 v158, v158
	v_add_f32_e32 v154, 1.0, v154
	v_rcp_f32_e32 v183, v154
	v_mul_f32_e32 v152, v192, v190
	v_mul_f32_e32 v153, v193, v191
	v_add_f32_e32 v158, 1.0, v158
	v_add_f32_e32 v152, 0, v152
	v_rcp_f32_e32 v158, v158
	v_mul_f32_e32 v188, v186, v184
	v_mul_f32_e32 v189, v187, v185
	v_add_f32_e32 v152, v153, v152
	v_add_f32_e32 v152, v188, v152
	v_mul_f32_e32 v154, v182, v162
	v_mul_f32_e32 v155, v183, v163
	v_add_f32_e32 v152, v189, v152
	v_add_f32_e32 v152, v154, v152
	v_mul_f32_e32 v160, v158, v156
	v_mul_f32_e32 v161, v159, v157
	v_add_f32_e32 v152, v155, v152
	v_add_f32_e32 v152, v160, v152
	v_add_f32_e32 v152, v161, v152
	s_nop 0
	s_nop 1
	v_add_f32_dpp v152, v152, v152 quad_perm:[1,0,3,2] row_mask:0xf bank_mask:0xf
	s_nop 0
	s_nop 1
	v_add_f32_dpp v152, v152, v152 quad_perm:[2,3,0,1] row_mask:0xf bank_mask:0xf
	s_nop 0
	s_nop 1
	v_add_f32_dpp v152, v152, v152 row_half_mirror row_mask:0xf bank_mask:0xf
	v_mul_f32_e32 v152, 0x3c800000, v152
	v_fma_f32 v154, v192, v190, -v152
	v_fma_f32 v155, v193, v191, -v152
	v_fma_f32 v184, v186, v184, -v152
	v_fma_f32 v185, v187, v185, -v152
	v_mul_f32_e32 v160, v154, v154
	v_mul_f32_e32 v161, v155, v155
	v_mul_f32_e32 v186, v184, v184
	v_mul_f32_e32 v187, v185, v185
	v_fma_f32 v156, v158, v156, -v152
	v_fma_f32 v157, v159, v157, -v152
	v_add_f32_e32 v158, v160, v161
	v_fma_f32 v162, v182, v162, -v152
	v_fma_f32 v163, v183, v163, -v152
	v_add_f32_e32 v158, v186, v158
	v_mul_f32_e32 v182, v162, v162
	v_mul_f32_e32 v183, v163, v163
	v_add_f32_e32 v158, v187, v158
	v_add_f32_e32 v158, v182, v158
	v_mul_f32_e32 v152, v156, v156
	v_mul_f32_e32 v153, v157, v157
	v_add_f32_e32 v158, v183, v158
	v_add_f32_e32 v152, v152, v158
	v_add_f32_e32 v152, v153, v152
	s_nop 0
	s_waitcnt vmcnt(44)
; #define LAS __attribute__((address_space(3)))
; __device__ __forceinline__ float geluf(float x) { return x * __builtin_amdgcn_rcpf(1.f + __builtin_amdgcn_exp2f(x * (-0.10294324f * x * x - 2.3022082f))); }
; __device__ __forceinline__ float lx_xor(float v, int m, int lane) { return __int_as_float(__builtin_amdgcn_ds_bpermute((lane ^ m) << 2, __float_as_int(v))); }
; __device__ __forceinline__ unsigned cvtpk_h(float lo, float hi) { f32x2 v = {lo, hi}; h16x2 b = __builtin_convertvector(v, h16x2); return __builtin_bit_cast(unsigned, b); }
; __device__ __forceinline__ void gmlp_unit(unsigned char* ws, h16* Y, const h16* Ws16  , const float* bs  , size_t r0, LAS unsigned char* lds, int tid) {
;     ...
;     for (int j = 0; j < 8; ++j) { const int i = tid + 512 * j, row = i >> 5, c8 = i & 31, gg = c8 >> 3, cg = (c8 & 7) * 8;
;         const h16x8 hv = __builtin_bit_cast(h16x8, stg[j]); float x[8]; float sm = 0.f;
; #pragma unroll
;         for (int k = 0; k < 8; ++k) { x[k] = geluf((float)hv[k]); sm += x[k]; }
;         sm += lx_xor(sm, 1, lane); sm += lx_xor(sm, 2, lane); sm += lx_xor(sm, 4, lane);
;         const float mu = sm * (1.f / 64.f); float q = 0.f;
; #pragma unroll
;         for (int k = 0; k < 8; ++k) { x[k] -= mu; q += x[k] * x[k]; }
;         q += lx_xor(q, 1, lane); q += lx_xor(q, 2, lane); q += lx_xor(q, 4, lane);
;         const float rd = __builtin_amdgcn_rsqf(q * (1.f / 64.f) + EPS);
;         u32x4 o; o.x = cvtpk_h(x[0] * rd, x[1] * rd); o.y = cvtpk_h(x[2] * rd, x[3] * rd); o.z = cvtpk_h(x[4] * rd, x[5] * rd); o.w = cvtpk_h(x[6] * rd, x[7] * rd);
;         *(LAS u32x4*)(lds + gg * 16384 + (cg >> 5) * 8192 + row * 64 + (cg & 31) * 2) = o; }
	v_cvt_f32_f16_e32 v186, v148
	v_cvt_f32_f16_sdwa v187, v148 dst_sel:DWORD dst_unused:UNUSED_PAD src0_sel:WORD_1
	s_nop 1
	v_add_f32_dpp v152, v152, v152 quad_perm:[1,0,3,2] row_mask:0xf bank_mask:0xf
	s_nop 0
	s_nop 1
	v_add_f32_dpp v152, v152, v152 quad_perm:[2,3,0,1] row_mask:0xf bank_mask:0xf
	s_nop 0
	s_nop 1
	v_add_f32_dpp v152, v152, v152 row_half_mirror row_mask:0xf bank_mask:0xf
	v_fmamk_f32 v152, v152, 0x3c800000, v229
	v_rsq_f32_e32 v158, v152
	s_nop 0
	v_mul_f32_e32 v152, v154, v158
	v_mul_f32_e32 v153, v155, v158
	v_mul_f32_e32 v154, v184, v158
	v_mul_f32_e32 v155, v185, v158
	v_cvt_pk_f16_f32 v152, v152, v153
	v_cvt_pk_f16_f32 v153, v154, v155
	v_mul_f32_e32 v154, v162, v158
	v_mul_f32_e32 v155, v163, v158
	v_cvt_f32_f16_e32 v162, v149
	v_cvt_f32_f16_sdwa v163, v149 dst_sel:DWORD dst_unused:UNUSED_PAD src0_sel:WORD_1
	v_mul_f32_e32 v156, v156, v158
	v_mul_f32_e32 v157, v157, v158
	v_cvt_pk_f16_f32 v154, v154, v155
	v_mul_f32_e32 v181, 0x3dd2d3e8, v162
	v_fma_mix_f32 v181, -v181, v149, s9 op_sel_hi:[0,1,0]
	v_mul_f32_e32 v181, v181, v162
	v_exp_f32_e32 v181, v181
	v_cvt_pk_f16_f32 v155, v156, v157
	ds_write_b128 v179, v[152:155] offset:2048
	v_cvt_f32_f16_e32 v152, v151
	v_add_f32_e32 v181, 1.0, v181
	v_cvt_f32_f16_sdwa v153, v151 dst_sel:DWORD dst_unused:UNUSED_PAD src0_sel:WORD_1
	v_rcp_f32_e32 v182, v181
	v_mul_f32_e32 v181, 0x3dd2d3e8, v163
	v_fma_mix_f32 v149, -v181, v149, s9 op_sel:[0,1,0] op_sel_hi:[0,1,0]
	v_mul_f32_e32 v149, v149, v163
	v_exp_f32_e32 v149, v149
	v_mul_f32_e32 v154, 0x3dd2d3e8, v152
	v_mul_f32_e32 v155, 0x3dd2d3e8, v153
	v_fma_mix_f32 v154, -v154, v151, s9 op_sel_hi:[0,1,0]
	v_fma_mix_f32 v151, -v155, v151, s9 op_sel:[0,1,0] op_sel_hi:[0,1,0]
	v_mul_f32_e32 v151, v151, v153
	v_exp_f32_e32 v151, v151
	v_add_f32_e32 v149, 1.0, v149
	v_cvt_f32_f16_e32 v158, v150
	v_rcp_f32_e32 v183, v149
	v_mul_f32_e32 v149, 0x3dd2d3e8, v186
	v_fma_mix_f32 v149, -v149, v148, s9 op_sel_hi:[0,1,0]
	v_mul_f32_e32 v149, v149, v186
	v_add_f32_e32 v151, 1.0, v151
	v_exp_f32_e32 v149, v149
	v_rcp_f32_e32 v155, v151
	v_mul_f32_e32 v151, 0x3dd2d3e8, v158
	v_fma_mix_f32 v151, -v151, v150, s9 op_sel_hi:[0,1,0]
	v_mul_f32_e32 v151, v151, v158
	v_exp_f32_e32 v151, v151
	v_add_f32_e32 v149, 1.0, v149
	v_cvt_f32_f16_sdwa v159, v150 dst_sel:DWORD dst_unused:UNUSED_PAD src0_sel:WORD_1
	v_rcp_f32_e32 v188, v149
	v_mul_f32_e32 v149, 0x3dd2d3e8, v187
	v_fma_mix_f32 v148, -v149, v148, s9 op_sel:[0,1,0] op_sel_hi:[0,1,0]
	v_mul_f32_e32 v148, v148, v187
	v_add_f32_e32 v151, 1.0, v151
	v_exp_f32_e32 v148, v148
	v_rcp_f32_e32 v160, v151
	v_mul_f32_e32 v151, 0x3dd2d3e8, v159
	v_fma_mix_f32 v150, -v151, v150, s9 op_sel:[0,1,0] op_sel_hi:[0,1,0]
	v_mul_f32_e32 v150, v150, v159
	v_exp_f32_e32 v150, v150
	v_add_f32_e32 v148, 1.0, v148
	v_mul_f32_e32 v154, v154, v152
	v_rcp_f32_e32 v189, v148
	v_exp_f32_e32 v154, v154
	v_add_f32_e32 v150, 1.0, v150
	v_rcp_f32_e32 v161, v150
	v_mul_f32_e32 v148, v188, v186
	v_mul_f32_e32 v149, v189, v187
	v_add_f32_e32 v154, 1.0, v154
	v_add_f32_e32 v148, 0, v148
	v_rcp_f32_e32 v154, v154
	v_mul_f32_e32 v184, v182, v162
	v_mul_f32_e32 v185, v183, v163
	v_add_f32_e32 v148, v149, v148
	v_add_f32_e32 v148, v184, v148
	v_mul_f32_e32 v150, v160, v158
	v_mul_f32_e32 v151, v161, v159
	v_add_f32_e32 v148, v185, v148
	v_add_f32_e32 v148, v150, v148
	v_mul_f32_e32 v156, v154, v152
	v_mul_f32_e32 v157, v155, v153
	v_add_f32_e32 v148, v151, v148
	v_add_f32_e32 v148, v156, v148
	v_add_f32_e32 v148, v157, v148
	s_nop 0
	s_nop 1
	v_add_f32_dpp v148, v148, v148 quad_perm:[1,0,3,2] row_mask:0xf bank_mask:0xf
	s_nop 0
	s_nop 1
	v_add_f32_dpp v148, v148, v148 quad_perm:[2,3,0,1] row_mask:0xf bank_mask:0xf
	s_nop 0
	s_nop 1
	v_add_f32_dpp v148, v148, v148 row_half_mirror row_mask:0xf bank_mask:0xf
	v_mul_f32_e32 v148, 0x3c800000, v148
	v_fma_f32 v150, v188, v186, -v148
	v_fma_f32 v151, v189, v187, -v148
	v_fma_f32 v162, v182, v162, -v148
	v_fma_f32 v163, v183, v163, -v148
	v_mul_f32_e32 v156, v150, v150
	v_mul_f32_e32 v157, v151, v151
	v_mul_f32_e32 v182, v162, v162
	v_mul_f32_e32 v183, v163, v163
	v_fma_f32 v152, v154, v152, -v148
	v_fma_f32 v153, v155, v153, -v148
	v_add_f32_e32 v154, v156, v157
	v_fma_f32 v158, v160, v158, -v148
	v_fma_f32 v159, v161, v159, -v148
	v_add_f32_e32 v154, v182, v154
	v_mul_f32_e32 v160, v158, v158
	v_mul_f32_e32 v161, v159, v159
	v_add_f32_e32 v154, v183, v154
	v_add_f32_e32 v154, v160, v154
	v_mul_f32_e32 v148, v152, v152
	v_mul_f32_e32 v149, v153, v153
	v_add_f32_e32 v154, v161, v154
	v_add_f32_e32 v148, v148, v154
	v_add_f32_e32 v148, v149, v148
	s_nop 0
	s_waitcnt vmcnt(43)
; #define LAS __attribute__((address_space(3)))
; __device__ __forceinline__ float geluf(float x) { return x * __builtin_amdgcn_rcpf(1.f + __builtin_amdgcn_exp2f(x * (-0.10294324f * x * x - 2.3022082f))); }
; __device__ __forceinline__ float lx_xor(float v, int m, int lane) { return __int_as_float(__builtin_amdgcn_ds_bpermute((lane ^ m) << 2, __float_as_int(v))); }
; __device__ __forceinline__ unsigned cvtpk_h(float lo, float hi) { f32x2 v = {lo, hi}; h16x2 b = __builtin_convertvector(v, h16x2); return __builtin_bit_cast(unsigned, b); }
; __device__ __forceinline__ void gmlp_unit(unsigned char* ws, h16* Y, const h16* Ws16  , const float* bs  , size_t r0, LAS unsigned char* lds, int tid) {
;     ...
;     for (int j = 0; j < 8; ++j) { const int i = tid + 512 * j, row = i >> 5, c8 = i & 31, gg = c8 >> 3, cg = (c8 & 7) * 8;
;         const h16x8 hv = __builtin_bit_cast(h16x8, stg[j]); float x[8]; float sm = 0.f;
; #pragma unroll
;         for (int k = 0; k < 8; ++k) { x[k] = geluf((float)hv[k]); sm += x[k]; }
;         sm += lx_xor(sm, 1, lane); sm += lx_xor(sm, 2, lane); sm += lx_xor(sm, 4, lane);
;         const float mu = sm * (1.f / 64.f); float q = 0.f;
; #pragma unroll
;         for (int k = 0; k < 8; ++k) { x[k] -= mu; q += x[k] * x[k]; }
;         q += lx_xor(q, 1, lane); q += lx_xor(q, 2, lane); q += lx_xor(q, 4, lane);
;         const float rd = __builtin_amdgcn_rsqf(q * (1.f / 64.f) + EPS);
;         u32x4 o; o.x = cvtpk_h(x[0] * rd, x[1] * rd); o.y = cvtpk_h(x[2] * rd, x[3] * rd); o.z = cvtpk_h(x[4] * rd, x[5] * rd); o.w = cvtpk_h(x[6] * rd, x[7] * rd);
;         *(LAS u32x4*)(lds + gg * 16384 + (cg >> 5) * 8192 + row * 64 + (cg & 31) * 2) = o; }
	v_cvt_f32_f16_e32 v182, v14
	v_cvt_f32_f16_sdwa v183, v14 dst_sel:DWORD dst_unused:UNUSED_PAD src0_sel:WORD_1
	s_nop 1
	v_add_f32_dpp v148, v148, v148 quad_perm:[1,0,3,2] row_mask:0xf bank_mask:0xf
	s_nop 0
	s_nop 1
	v_add_f32_dpp v148, v148, v148 quad_perm:[2,3,0,1] row_mask:0xf bank_mask:0xf
	s_nop 0
	s_nop 1
	v_add_f32_dpp v148, v148, v148 row_half_mirror row_mask:0xf bank_mask:0xf
	v_fmamk_f32 v148, v148, 0x3c800000, v229
	v_rsq_f32_e32 v154, v148
	s_nop 0
	v_mul_f32_e32 v148, v150, v154
	v_mul_f32_e32 v149, v151, v154
	v_mul_f32_e32 v150, v162, v154
	v_mul_f32_e32 v151, v163, v154
	v_cvt_pk_f16_f32 v148, v148, v149
	v_cvt_pk_f16_f32 v149, v150, v151
	v_mul_f32_e32 v150, v158, v154
	v_mul_f32_e32 v151, v159, v154
	v_cvt_f32_f16_e32 v158, v15
	v_cvt_f32_f16_sdwa v159, v15 dst_sel:DWORD dst_unused:UNUSED_PAD src0_sel:WORD_1
	v_mul_f32_e32 v152, v152, v154
	v_mul_f32_e32 v153, v153, v154
	v_cvt_pk_f16_f32 v150, v150, v151
	v_cvt_pk_f16_f32 v151, v152, v153
	ds_write_b128 v179, v[148:151] offset:3072
	v_cvt_f32_f16_e32 v148, v17
	v_cvt_f32_f16_sdwa v149, v17 dst_sel:DWORD dst_unused:UNUSED_PAD src0_sel:WORD_1
	v_mul_f32_e32 v160, 0x3dd2d3e8, v158
	v_mul_f32_e32 v161, 0x3dd2d3e8, v159
	v_fma_mix_f32 v160, -v160, v15, s9 op_sel_hi:[0,1,0]
	v_fma_mix_f32 v15, -v161, v15, s9 op_sel:[0,1,0] op_sel_hi:[0,1,0]
	v_mul_f32_e32 v15, v15, v159
	v_exp_f32_e32 v15, v15
	v_mul_f32_e32 v150, 0x3dd2d3e8, v148
	v_mul_f32_e32 v151, 0x3dd2d3e8, v149
	v_fma_mix_f32 v150, -v150, v17, s9 op_sel_hi:[0,1,0]
	v_fma_mix_f32 v17, -v151, v17, s9 op_sel:[0,1,0] op_sel_hi:[0,1,0]
	v_mul_f32_e32 v17, v17, v149
	v_exp_f32_e32 v17, v17
	v_add_f32_e32 v15, 1.0, v15
	v_cvt_f32_f16_e32 v154, v16
	v_rcp_f32_e32 v161, v15
	v_mul_f32_e32 v15, 0x3dd2d3e8, v182
	v_fma_mix_f32 v15, -v15, v14, s9 op_sel_hi:[0,1,0]
	v_mul_f32_e32 v15, v15, v182
	v_add_f32_e32 v17, 1.0, v17
	v_exp_f32_e32 v15, v15
	v_rcp_f32_e32 v151, v17
	v_mul_f32_e32 v17, 0x3dd2d3e8, v154
	v_fma_mix_f32 v17, -v17, v16, s9 op_sel_hi:[0,1,0]
	v_mul_f32_e32 v17, v17, v154
	v_exp_f32_e32 v17, v17
	v_add_f32_e32 v15, 1.0, v15
	v_cvt_f32_f16_sdwa v155, v16 dst_sel:DWORD dst_unused:UNUSED_PAD src0_sel:WORD_1
	v_rcp_f32_e32 v184, v15
	v_mul_f32_e32 v15, 0x3dd2d3e8, v183
	v_fma_mix_f32 v14, -v15, v14, s9 op_sel:[0,1,0] op_sel_hi:[0,1,0]
	v_mul_f32_e32 v14, v14, v183
	v_add_f32_e32 v17, 1.0, v17
	v_exp_f32_e32 v14, v14
	v_rcp_f32_e32 v156, v17
	v_mul_f32_e32 v17, 0x3dd2d3e8, v155
	v_mul_f32_e32 v160, v160, v158
	v_fma_mix_f32 v16, -v17, v16, s9 op_sel:[0,1,0] op_sel_hi:[0,1,0]
	v_exp_f32_e32 v160, v160
	v_mul_f32_e32 v16, v16, v155
	v_exp_f32_e32 v16, v16
	v_add_f32_e32 v14, 1.0, v14
	v_mul_f32_e32 v150, v150, v148
	v_rcp_f32_e32 v185, v14
	v_exp_f32_e32 v150, v150
	v_add_f32_e32 v160, 1.0, v160
	v_rcp_f32_e32 v160, v160
	v_add_f32_e32 v16, 1.0, v16
	v_rcp_f32_e32 v157, v16
	v_mul_f32_e32 v14, v184, v182
	v_mul_f32_e32 v15, v185, v183
	v_add_f32_e32 v150, 1.0, v150
	v_add_f32_e32 v14, 0, v14
	v_rcp_f32_e32 v150, v150
	v_mul_f32_e32 v162, v160, v158
	v_mul_f32_e32 v163, v161, v159
	v_add_f32_e32 v14, v15, v14
	v_add_f32_e32 v14, v162, v14
	v_mul_f32_e32 v16, v156, v154
	v_mul_f32_e32 v17, v157, v155
	v_add_f32_e32 v14, v163, v14
	v_add_f32_e32 v14, v16, v14
	v_mul_f32_e32 v152, v150, v148
	v_mul_f32_e32 v153, v151, v149
	v_add_f32_e32 v14, v17, v14
	v_add_f32_e32 v14, v152, v14
	v_add_f32_e32 v14, v153, v14
	s_nop 0
	s_nop 1
	v_add_f32_dpp v14, v14, v14 quad_perm:[1,0,3,2] row_mask:0xf bank_mask:0xf
	s_nop 0
	s_nop 1
	v_add_f32_dpp v14, v14, v14 quad_perm:[2,3,0,1] row_mask:0xf bank_mask:0xf
	s_nop 0
	s_nop 1
	v_add_f32_dpp v14, v14, v14 row_half_mirror row_mask:0xf bank_mask:0xf
	v_mul_f32_e32 v14, 0x3c800000, v14
	v_fma_f32 v16, v184, v182, -v14
	v_fma_f32 v17, v185, v183, -v14
	v_fma_f32 v158, v160, v158, -v14
	v_fma_f32 v159, v161, v159, -v14
	v_mul_f32_e32 v152, v16, v16
	v_mul_f32_e32 v153, v17, v17
	v_mul_f32_e32 v160, v158, v158
	v_mul_f32_e32 v161, v159, v159
	v_fma_f32 v148, v150, v148, -v14
	v_fma_f32 v149, v151, v149, -v14
	v_add_f32_e32 v150, v152, v153
	v_fma_f32 v154, v156, v154, -v14
	v_fma_f32 v155, v157, v155, -v14
	v_add_f32_e32 v150, v160, v150
	v_mul_f32_e32 v156, v154, v154
	v_mul_f32_e32 v157, v155, v155
	v_add_f32_e32 v150, v161, v150
	v_add_f32_e32 v150, v156, v150
	v_mul_f32_e32 v14, v148, v148
	v_mul_f32_e32 v15, v149, v149
	v_add_f32_e32 v150, v157, v150
	v_add_f32_e32 v14, v14, v150
	v_add_f32_e32 v14, v15, v14
	s_nop 0
	s_waitcnt vmcnt(42)
; #define LAS __attribute__((address_space(3)))
; __device__ __forceinline__ float geluf(float x) { return x * __builtin_amdgcn_rcpf(1.f + __builtin_amdgcn_exp2f(x * (-0.10294324f * x * x - 2.3022082f))); }
; __device__ __forceinline__ float lx_xor(float v, int m, int lane) { return __int_as_float(__builtin_amdgcn_ds_bpermute((lane ^ m) << 2, __float_as_int(v))); }
; __device__ __forceinline__ unsigned cvtpk_h(float lo, float hi) { f32x2 v = {lo, hi}; h16x2 b = __builtin_convertvector(v, h16x2); return __builtin_bit_cast(unsigned, b); }
; __device__ __forceinline__ void gmlp_unit(unsigned char* ws, h16* Y, const h16* Ws16  , const float* bs  , size_t r0, LAS unsigned char* lds, int tid) {
;     ...
;     for (int j = 0; j < 8; ++j) { const int i = tid + 512 * j, row = i >> 5, c8 = i & 31, gg = c8 >> 3, cg = (c8 & 7) * 8;
;         const h16x8 hv = __builtin_bit_cast(h16x8, stg[j]); float x[8]; float sm = 0.f;
; #pragma unroll
;         for (int k = 0; k < 8; ++k) { x[k] = geluf((float)hv[k]); sm += x[k]; }
;         sm += lx_xor(sm, 1, lane); sm += lx_xor(sm, 2, lane); sm += lx_xor(sm, 4, lane);
;         const float mu = sm * (1.f / 64.f); float q = 0.f;
; #pragma unroll
;         for (int k = 0; k < 8; ++k) { x[k] -= mu; q += x[k] * x[k]; }
;         q += lx_xor(q, 1, lane); q += lx_xor(q, 2, lane); q += lx_xor(q, 4, lane);
;         const float rd = __builtin_amdgcn_rsqf(q * (1.f / 64.f) + EPS);
;         u32x4 o; o.x = cvtpk_h(x[0] * rd, x[1] * rd); o.y = cvtpk_h(x[2] * rd, x[3] * rd); o.z = cvtpk_h(x[4] * rd, x[5] * rd); o.w = cvtpk_h(x[6] * rd, x[7] * rd);
;         *(LAS u32x4*)(lds + gg * 16384 + (cg >> 5) * 8192 + row * 64 + (cg & 31) * 2) = o; }
	v_cvt_f32_f16_e32 v160, v10
	v_cvt_f32_f16_sdwa v161, v10 dst_sel:DWORD dst_unused:UNUSED_PAD src0_sel:WORD_1
	s_nop 1
	v_add_f32_dpp v14, v14, v14 quad_perm:[1,0,3,2] row_mask:0xf bank_mask:0xf
	s_nop 0
	s_nop 1
	v_add_f32_dpp v14, v14, v14 quad_perm:[2,3,0,1] row_mask:0xf bank_mask:0xf
	s_nop 0
	s_nop 1
	v_add_f32_dpp v14, v14, v14 row_half_mirror row_mask:0xf bank_mask:0xf
	v_fmamk_f32 v14, v14, 0x3c800000, v229
	v_rsq_f32_e32 v150, v14
	s_nop 0
	v_mul_f32_e32 v14, v16, v150
	v_mul_f32_e32 v15, v17, v150
	v_mul_f32_e32 v16, v158, v150
	v_mul_f32_e32 v17, v159, v150
	v_cvt_pk_f16_f32 v14, v14, v15
	v_cvt_pk_f16_f32 v15, v16, v17
	v_mul_f32_e32 v16, v154, v150
	v_mul_f32_e32 v17, v155, v150
	v_cvt_f32_f16_e32 v154, v11
	v_cvt_f32_f16_sdwa v155, v11 dst_sel:DWORD dst_unused:UNUSED_PAD src0_sel:WORD_1
	v_mul_f32_e32 v148, v148, v150
	v_mul_f32_e32 v149, v149, v150
	v_cvt_pk_f16_f32 v16, v16, v17
	v_cvt_pk_f16_f32 v17, v148, v149
	ds_write_b128 v179, v[14:17] offset:4096
	v_cvt_f32_f16_e32 v14, v13
	v_cvt_f32_f16_sdwa v15, v13 dst_sel:DWORD dst_unused:UNUSED_PAD src0_sel:WORD_1
	v_mul_f32_e32 v156, 0x3dd2d3e8, v154
	v_mul_f32_e32 v157, 0x3dd2d3e8, v155
	v_fma_mix_f32 v156, -v156, v11, s9 op_sel_hi:[0,1,0]
	v_fma_mix_f32 v11, -v157, v11, s9 op_sel:[0,1,0] op_sel_hi:[0,1,0]
	v_mul_f32_e32 v11, v11, v155
	v_exp_f32_e32 v11, v11
	v_mul_f32_e32 v16, 0x3dd2d3e8, v14
	v_mul_f32_e32 v17, 0x3dd2d3e8, v15
	v_fma_mix_f32 v16, -v16, v13, s9 op_sel_hi:[0,1,0]
	v_fma_mix_f32 v13, -v17, v13, s9 op_sel:[0,1,0] op_sel_hi:[0,1,0]
	v_mul_f32_e32 v13, v13, v15
	v_exp_f32_e32 v13, v13
	v_add_f32_e32 v11, 1.0, v11
	v_cvt_f32_f16_e32 v150, v12
	v_rcp_f32_e32 v157, v11
	v_mul_f32_e32 v11, 0x3dd2d3e8, v160
	v_fma_mix_f32 v11, -v11, v10, s9 op_sel_hi:[0,1,0]
	v_mul_f32_e32 v11, v11, v160
	v_add_f32_e32 v13, 1.0, v13
	v_exp_f32_e32 v11, v11
	v_rcp_f32_e32 v17, v13
	v_mul_f32_e32 v13, 0x3dd2d3e8, v150
	v_fma_mix_f32 v13, -v13, v12, s9 op_sel_hi:[0,1,0]
	v_mul_f32_e32 v13, v13, v150
	v_exp_f32_e32 v13, v13
	v_add_f32_e32 v11, 1.0, v11
	v_cvt_f32_f16_sdwa v151, v12 dst_sel:DWORD dst_unused:UNUSED_PAD src0_sel:WORD_1
	v_rcp_f32_e32 v162, v11
	v_mul_f32_e32 v11, 0x3dd2d3e8, v161
	v_fma_mix_f32 v10, -v11, v10, s9 op_sel:[0,1,0] op_sel_hi:[0,1,0]
	v_mul_f32_e32 v10, v10, v161
	v_add_f32_e32 v13, 1.0, v13
	v_exp_f32_e32 v10, v10
	v_rcp_f32_e32 v152, v13
	v_mul_f32_e32 v13, 0x3dd2d3e8, v151
	v_mul_f32_e32 v156, v156, v154
	v_fma_mix_f32 v12, -v13, v12, s9 op_sel:[0,1,0] op_sel_hi:[0,1,0]
	v_exp_f32_e32 v156, v156
	v_mul_f32_e32 v12, v12, v151
	v_exp_f32_e32 v12, v12
	v_add_f32_e32 v10, 1.0, v10
	v_mul_f32_e32 v16, v16, v14
	v_rcp_f32_e32 v163, v10
	v_exp_f32_e32 v16, v16
	v_add_f32_e32 v156, 1.0, v156
	v_rcp_f32_e32 v156, v156
	v_add_f32_e32 v12, 1.0, v12
	v_rcp_f32_e32 v153, v12
	v_mul_f32_e32 v10, v162, v160
	v_mul_f32_e32 v11, v163, v161
	v_add_f32_e32 v16, 1.0, v16
	v_add_f32_e32 v10, 0, v10
	v_rcp_f32_e32 v16, v16
	v_mul_f32_e32 v158, v156, v154
	v_mul_f32_e32 v159, v157, v155
	v_add_f32_e32 v10, v11, v10
	v_add_f32_e32 v10, v158, v10
	v_mul_f32_e32 v12, v152, v150
	v_mul_f32_e32 v13, v153, v151
	v_add_f32_e32 v10, v159, v10
	v_add_f32_e32 v10, v12, v10
	v_mul_f32_e32 v148, v16, v14
	v_mul_f32_e32 v149, v17, v15
	v_add_f32_e32 v10, v13, v10
	v_add_f32_e32 v10, v148, v10
	v_add_f32_e32 v10, v149, v10
	s_nop 0
	s_nop 1
	v_add_f32_dpp v10, v10, v10 quad_perm:[1,0,3,2] row_mask:0xf bank_mask:0xf
	s_nop 0
	s_nop 1
	v_add_f32_dpp v10, v10, v10 quad_perm:[2,3,0,1] row_mask:0xf bank_mask:0xf
	s_nop 0
	s_nop 1
	v_add_f32_dpp v10, v10, v10 row_half_mirror row_mask:0xf bank_mask:0xf
	v_mul_f32_e32 v10, 0x3c800000, v10
	v_fma_f32 v12, v162, v160, -v10
	v_fma_f32 v13, v163, v161, -v10
	v_fma_f32 v154, v156, v154, -v10
	v_fma_f32 v155, v157, v155, -v10
	v_mul_f32_e32 v148, v12, v12
	v_mul_f32_e32 v149, v13, v13
	v_mul_f32_e32 v156, v154, v154
	v_mul_f32_e32 v157, v155, v155
	v_fma_f32 v14, v16, v14, -v10
	v_fma_f32 v15, v17, v15, -v10
	v_add_f32_e32 v16, v148, v149
	v_fma_f32 v150, v152, v150, -v10
	v_fma_f32 v151, v153, v151, -v10
	v_add_f32_e32 v16, v156, v16
	v_mul_f32_e32 v152, v150, v150
	v_mul_f32_e32 v153, v151, v151
	v_add_f32_e32 v16, v157, v16
	v_add_f32_e32 v16, v152, v16
	v_mul_f32_e32 v10, v14, v14
	v_mul_f32_e32 v11, v15, v15
	v_add_f32_e32 v16, v153, v16
	v_add_f32_e32 v10, v10, v16
	v_add_f32_e32 v10, v11, v10
	s_nop 0
	s_waitcnt vmcnt(41)
; #define LAS __attribute__((address_space(3)))
; __device__ __forceinline__ float geluf(float x) { return x * __builtin_amdgcn_rcpf(1.f + __builtin_amdgcn_exp2f(x * (-0.10294324f * x * x - 2.3022082f))); }
; __device__ __forceinline__ float lx_xor(float v, int m, int lane) { return __int_as_float(__builtin_amdgcn_ds_bpermute((lane ^ m) << 2, __float_as_int(v))); }
; __device__ __forceinline__ unsigned cvtpk_h(float lo, float hi) { f32x2 v = {lo, hi}; h16x2 b = __builtin_convertvector(v, h16x2); return __builtin_bit_cast(unsigned, b); }
; __device__ __forceinline__ void gmlp_unit(unsigned char* ws, h16* Y, const h16* Ws16  , const float* bs  , size_t r0, LAS unsigned char* lds, int tid) {
;     ...
;     for (int j = 0; j < 8; ++j) { const int i = tid + 512 * j, row = i >> 5, c8 = i & 31, gg = c8 >> 3, cg = (c8 & 7) * 8;
;         const h16x8 hv = __builtin_bit_cast(h16x8, stg[j]); float x[8]; float sm = 0.f;
; #pragma unroll
;         for (int k = 0; k < 8; ++k) { x[k] = geluf((float)hv[k]); sm += x[k]; }
;         sm += lx_xor(sm, 1, lane); sm += lx_xor(sm, 2, lane); sm += lx_xor(sm, 4, lane);
;         const float mu = sm * (1.f / 64.f); float q = 0.f;
; #pragma unroll
;         for (int k = 0; k < 8; ++k) { x[k] -= mu; q += x[k] * x[k]; }
;         q += lx_xor(q, 1, lane); q += lx_xor(q, 2, lane); q += lx_xor(q, 4, lane);
;         const float rd = __builtin_amdgcn_rsqf(q * (1.f / 64.f) + EPS);
;         u32x4 o; o.x = cvtpk_h(x[0] * rd, x[1] * rd); o.y = cvtpk_h(x[2] * rd, x[3] * rd); o.z = cvtpk_h(x[4] * rd, x[5] * rd); o.w = cvtpk_h(x[6] * rd, x[7] * rd);
;         *(LAS u32x4*)(lds + gg * 16384 + (cg >> 5) * 8192 + row * 64 + (cg & 31) * 2) = o; }
	v_cvt_f32_f16_e32 v156, v6
	v_cvt_f32_f16_sdwa v157, v6 dst_sel:DWORD dst_unused:UNUSED_PAD src0_sel:WORD_1
	s_nop 1
	v_add_f32_dpp v10, v10, v10 quad_perm:[1,0,3,2] row_mask:0xf bank_mask:0xf
	s_nop 0
	s_nop 1
	v_add_f32_dpp v10, v10, v10 quad_perm:[2,3,0,1] row_mask:0xf bank_mask:0xf
	s_nop 0
	s_nop 1
	v_add_f32_dpp v10, v10, v10 row_half_mirror row_mask:0xf bank_mask:0xf
	v_fmamk_f32 v10, v10, 0x3c800000, v229
	v_rsq_f32_e32 v16, v10
	s_nop 0
	v_mul_f32_e32 v10, v12, v16
	v_mul_f32_e32 v11, v13, v16
	v_mul_f32_e32 v12, v154, v16
	v_mul_f32_e32 v13, v155, v16
	v_cvt_pk_f16_f32 v10, v10, v11
	v_cvt_pk_f16_f32 v11, v12, v13
	v_mul_f32_e32 v12, v150, v16
	v_mul_f32_e32 v13, v151, v16
	v_cvt_f32_f16_e32 v150, v7
	v_cvt_f32_f16_sdwa v151, v7 dst_sel:DWORD dst_unused:UNUSED_PAD src0_sel:WORD_1
	v_mul_f32_e32 v14, v14, v16
	v_mul_f32_e32 v15, v15, v16
	v_cvt_pk_f16_f32 v12, v12, v13
	v_cvt_pk_f16_f32 v13, v14, v15
	ds_write_b128 v179, v[10:13] offset:5120
	v_cvt_f32_f16_e32 v10, v9
	v_cvt_f32_f16_sdwa v11, v9 dst_sel:DWORD dst_unused:UNUSED_PAD src0_sel:WORD_1
	v_mul_f32_e32 v152, 0x3dd2d3e8, v150
	v_mul_f32_e32 v153, 0x3dd2d3e8, v151
	v_fma_mix_f32 v152, -v152, v7, s9 op_sel_hi:[0,1,0]
	v_fma_mix_f32 v7, -v153, v7, s9 op_sel:[0,1,0] op_sel_hi:[0,1,0]
	v_mul_f32_e32 v7, v7, v151
	v_exp_f32_e32 v7, v7
	v_mul_f32_e32 v12, 0x3dd2d3e8, v10
	v_mul_f32_e32 v13, 0x3dd2d3e8, v11
	v_fma_mix_f32 v12, -v12, v9, s9 op_sel_hi:[0,1,0]
	v_fma_mix_f32 v9, -v13, v9, s9 op_sel:[0,1,0] op_sel_hi:[0,1,0]
	v_mul_f32_e32 v9, v9, v11
	v_exp_f32_e32 v9, v9
	v_add_f32_e32 v7, 1.0, v7
	v_cvt_f32_f16_e32 v16, v8
	v_rcp_f32_e32 v153, v7
	v_mul_f32_e32 v7, 0x3dd2d3e8, v156
	v_fma_mix_f32 v7, -v7, v6, s9 op_sel_hi:[0,1,0]
	v_mul_f32_e32 v7, v7, v156
	v_add_f32_e32 v9, 1.0, v9
	v_exp_f32_e32 v7, v7
	v_rcp_f32_e32 v13, v9
	v_mul_f32_e32 v9, 0x3dd2d3e8, v16
	v_fma_mix_f32 v9, -v9, v8, s9 op_sel_hi:[0,1,0]
	v_mul_f32_e32 v9, v9, v16
	v_exp_f32_e32 v9, v9
	v_add_f32_e32 v7, 1.0, v7
	v_cvt_f32_f16_sdwa v17, v8 dst_sel:DWORD dst_unused:UNUSED_PAD src0_sel:WORD_1
	v_rcp_f32_e32 v158, v7
	v_mul_f32_e32 v7, 0x3dd2d3e8, v157
	v_fma_mix_f32 v6, -v7, v6, s9 op_sel:[0,1,0] op_sel_hi:[0,1,0]
	v_mul_f32_e32 v6, v6, v157
	v_add_f32_e32 v9, 1.0, v9
	v_exp_f32_e32 v6, v6
	v_rcp_f32_e32 v148, v9
	v_mul_f32_e32 v9, 0x3dd2d3e8, v17
	v_mul_f32_e32 v152, v152, v150
	v_fma_mix_f32 v8, -v9, v8, s9 op_sel:[0,1,0] op_sel_hi:[0,1,0]
	v_exp_f32_e32 v152, v152
	v_mul_f32_e32 v8, v8, v17
	v_exp_f32_e32 v8, v8
	v_add_f32_e32 v6, 1.0, v6
	v_mul_f32_e32 v12, v12, v10
	v_rcp_f32_e32 v159, v6
	v_exp_f32_e32 v12, v12
	v_add_f32_e32 v152, 1.0, v152
	v_rcp_f32_e32 v152, v152
	v_add_f32_e32 v8, 1.0, v8
	v_rcp_f32_e32 v149, v8
	v_mul_f32_e32 v6, v158, v156
	v_mul_f32_e32 v7, v159, v157
	v_add_f32_e32 v12, 1.0, v12
	v_add_f32_e32 v6, 0, v6
	v_rcp_f32_e32 v12, v12
	v_mul_f32_e32 v154, v152, v150
	v_mul_f32_e32 v155, v153, v151
	v_add_f32_e32 v6, v7, v6
	v_add_f32_e32 v6, v154, v6
	v_mul_f32_e32 v8, v148, v16
	v_mul_f32_e32 v9, v149, v17
	v_add_f32_e32 v6, v155, v6
	v_add_f32_e32 v6, v8, v6
	v_mul_f32_e32 v14, v12, v10
	v_mul_f32_e32 v15, v13, v11
	v_add_f32_e32 v6, v9, v6
	v_add_f32_e32 v6, v14, v6
	v_add_f32_e32 v6, v15, v6
	s_nop 0
	s_nop 1
	v_add_f32_dpp v6, v6, v6 quad_perm:[1,0,3,2] row_mask:0xf bank_mask:0xf
	s_nop 0
	s_nop 1
	v_add_f32_dpp v6, v6, v6 quad_perm:[2,3,0,1] row_mask:0xf bank_mask:0xf
	s_nop 0
	s_nop 1
	v_add_f32_dpp v6, v6, v6 row_half_mirror row_mask:0xf bank_mask:0xf
	v_mul_f32_e32 v6, 0x3c800000, v6
	v_fma_f32 v8, v158, v156, -v6
	v_fma_f32 v9, v159, v157, -v6
	v_fma_f32 v150, v152, v150, -v6
	v_fma_f32 v151, v153, v151, -v6
	v_mul_f32_e32 v14, v8, v8
	v_mul_f32_e32 v15, v9, v9
	v_mul_f32_e32 v152, v150, v150
	v_mul_f32_e32 v153, v151, v151
	v_fma_f32 v10, v12, v10, -v6
	v_fma_f32 v11, v13, v11, -v6
	v_add_f32_e32 v12, v14, v15
	v_fma_f32 v16, v148, v16, -v6
	v_fma_f32 v17, v149, v17, -v6
	v_add_f32_e32 v12, v152, v12
	v_mul_f32_e32 v148, v16, v16
	v_mul_f32_e32 v149, v17, v17
	v_add_f32_e32 v12, v153, v12
	v_add_f32_e32 v12, v148, v12
	v_mul_f32_e32 v6, v10, v10
	v_mul_f32_e32 v7, v11, v11
	v_add_f32_e32 v12, v149, v12
	v_add_f32_e32 v6, v6, v12
	v_add_f32_e32 v6, v7, v6
	s_nop 0
	s_waitcnt vmcnt(40)
	v_cvt_f32_f16_e32 v152, v2
	v_cvt_f32_f16_sdwa v153, v2 dst_sel:DWORD dst_unused:UNUSED_PAD src0_sel:WORD_1
	s_nop 1
	v_add_f32_dpp v6, v6, v6 quad_perm:[1,0,3,2] row_mask:0xf bank_mask:0xf
	s_nop 0
	s_nop 1
	v_add_f32_dpp v6, v6, v6 quad_perm:[2,3,0,1] row_mask:0xf bank_mask:0xf
	s_nop 0
	s_nop 1
	v_add_f32_dpp v6, v6, v6 row_half_mirror row_mask:0xf bank_mask:0xf
	v_fmamk_f32 v6, v6, 0x3c800000, v229
	v_rsq_f32_e32 v12, v6
	s_nop 0
	v_mul_f32_e32 v6, v8, v12
	v_mul_f32_e32 v7, v9, v12
	v_mul_f32_e32 v8, v150, v12
	v_mul_f32_e32 v9, v151, v12
	v_cvt_pk_f16_f32 v6, v6, v7
	v_cvt_pk_f16_f32 v7, v8, v9
	v_mul_f32_e32 v8, v16, v12
	v_mul_f32_e32 v9, v17, v12
	v_cvt_f32_f16_e32 v16, v3
	v_cvt_f32_f16_sdwa v17, v3 dst_sel:DWORD dst_unused:UNUSED_PAD src0_sel:WORD_1
	v_mul_f32_e32 v10, v10, v12
	v_mul_f32_e32 v11, v11, v12
	v_cvt_pk_f16_f32 v8, v8, v9
	v_cvt_pk_f16_f32 v9, v10, v11
	ds_write_b128 v179, v[6:9] offset:6144
	v_cvt_f32_f16_e32 v6, v5
	v_cvt_f32_f16_sdwa v7, v5 dst_sel:DWORD dst_unused:UNUSED_PAD src0_sel:WORD_1
	v_mul_f32_e32 v148, 0x3dd2d3e8, v16
	v_mul_f32_e32 v149, 0x3dd2d3e8, v17
	v_fma_mix_f32 v148, -v148, v3, s9 op_sel_hi:[0,1,0]
	v_fma_mix_f32 v3, -v149, v3, s9 op_sel:[0,1,0] op_sel_hi:[0,1,0]
	v_mul_f32_e32 v3, v3, v17
	v_exp_f32_e32 v3, v3
	v_mul_f32_e32 v8, 0x3dd2d3e8, v6
	v_mul_f32_e32 v9, 0x3dd2d3e8, v7
	v_fma_mix_f32 v8, -v8, v5, s9 op_sel_hi:[0,1,0]
; #define LAS __attribute__((address_space(3)))
; __device__ __forceinline__ float geluf(float x) { return x * __builtin_amdgcn_rcpf(1.f + __builtin_amdgcn_exp2f(x * (-0.10294324f * x * x - 2.3022082f))); }
; __device__ __forceinline__ float lx_xor(float v, int m, int lane) { return __int_as_float(__builtin_amdgcn_ds_bpermute((lane ^ m) << 2, __float_as_int(v))); }
; __device__ __forceinline__ unsigned cvtpk_h(float lo, float hi) { f32x2 v = {lo, hi}; h16x2 b = __builtin_convertvector(v, h16x2); return __builtin_bit_cast(unsigned, b); }
; #define BAR_LDS() asm volatile("s_waitcnt lgkmcnt(0)\n\ts_barrier" ::: "memory")
; __device__ __forceinline__ void gmlp_unit(unsigned char* ws, h16* Y, const h16* Ws16  , const float* bs  , size_t r0, LAS unsigned char* lds, int tid) {
;     ...
;     for (int j = 0; j < 8; ++j) { const int i = tid + 512 * j, row = i >> 5, c8 = i & 31, gg = c8 >> 3, cg = (c8 & 7) * 8;
;         const h16x8 hv = __builtin_bit_cast(h16x8, stg[j]); float x[8]; float sm = 0.f;
; #pragma unroll
;         for (int k = 0; k < 8; ++k) { x[k] = geluf((float)hv[k]); sm += x[k]; }
;         sm += lx_xor(sm, 1, lane); sm += lx_xor(sm, 2, lane); sm += lx_xor(sm, 4, lane);
;         const float mu = sm * (1.f / 64.f); float q = 0.f;
; #pragma unroll
;         for (int k = 0; k < 8; ++k) { x[k] -= mu; q += x[k] * x[k]; }
;         q += lx_xor(q, 1, lane); q += lx_xor(q, 2, lane); q += lx_xor(q, 4, lane);
;         const float rd = __builtin_amdgcn_rsqf(q * (1.f / 64.f) + EPS);
;         u32x4 o; o.x = cvtpk_h(x[0] * rd, x[1] * rd); o.y = cvtpk_h(x[2] * rd, x[3] * rd); o.z = cvtpk_h(x[4] * rd, x[5] * rd); o.w = cvtpk_h(x[6] * rd, x[7] * rd);
;         *(LAS u32x4*)(lds + gg * 16384 + (cg >> 5) * 8192 + row * 64 + (cg & 31) * 2) = o; }
;     BAR_LDS();
;     LAS h16* scr = (LAS h16*)(lds + GM_SCR) + wid * (32 * 72);
; #pragma unroll
;     for (int q = 0; q < 2; ++q) {
; #pragma unroll
;         for (int db = 0; db < 2; ++db) {
;             s16x8 bf[8];
; #pragma unroll
;             for (int ks = 0; ks < 8; ++ks) bf[ks] = tr_frag((LAS const char*)lds + g * 16384, 8192, db, ks, lane);
;             f32x16 acc = f32x16{};
; #pragma unroll
;             for (int ks = 0; ks < 8; ++ks) acc = __builtin_amdgcn_mfma_f32_32x32x16_f16(H8(af[q][ks]), H8(bf[ks]), acc, 0, 0, 0);
	v_fma_mix_f32 v5, -v9, v5, s9 op_sel:[0,1,0] op_sel_hi:[0,1,0]
	v_mul_f32_e32 v5, v5, v7
	v_exp_f32_e32 v5, v5
	v_add_f32_e32 v3, 1.0, v3
	v_cvt_f32_f16_e32 v12, v4
	v_rcp_f32_e32 v149, v3
	v_mul_f32_e32 v3, 0x3dd2d3e8, v152
	v_fma_mix_f32 v3, -v3, v2, s9 op_sel_hi:[0,1,0]
	v_mul_f32_e32 v3, v3, v152
	v_add_f32_e32 v5, 1.0, v5
	v_exp_f32_e32 v3, v3
	v_rcp_f32_e32 v9, v5
	v_mul_f32_e32 v5, 0x3dd2d3e8, v12
	v_fma_mix_f32 v5, -v5, v4, s9 op_sel_hi:[0,1,0]
	v_mul_f32_e32 v5, v5, v12
	v_exp_f32_e32 v5, v5
	v_add_f32_e32 v3, 1.0, v3
	v_cvt_f32_f16_sdwa v13, v4 dst_sel:DWORD dst_unused:UNUSED_PAD src0_sel:WORD_1
	v_rcp_f32_e32 v154, v3
	v_mul_f32_e32 v3, 0x3dd2d3e8, v153
	v_fma_mix_f32 v2, -v3, v2, s9 op_sel:[0,1,0] op_sel_hi:[0,1,0]
	v_mul_f32_e32 v2, v2, v153
	v_add_f32_e32 v5, 1.0, v5
	v_exp_f32_e32 v2, v2
	v_rcp_f32_e32 v14, v5
	v_mul_f32_e32 v5, 0x3dd2d3e8, v13
	v_mul_f32_e32 v148, v148, v16
	v_fma_mix_f32 v4, -v5, v4, s9 op_sel:[0,1,0] op_sel_hi:[0,1,0]
	v_exp_f32_e32 v148, v148
	v_mul_f32_e32 v4, v4, v13
	v_exp_f32_e32 v4, v4
	v_add_f32_e32 v2, 1.0, v2
	v_mul_f32_e32 v8, v8, v6
	v_rcp_f32_e32 v155, v2
	v_exp_f32_e32 v8, v8
	v_add_f32_e32 v148, 1.0, v148
	v_rcp_f32_e32 v148, v148
	v_add_f32_e32 v4, 1.0, v4
	v_rcp_f32_e32 v15, v4
	v_mul_f32_e32 v2, v154, v152
	v_mul_f32_e32 v3, v155, v153
	v_add_f32_e32 v8, 1.0, v8
	v_add_f32_e32 v2, 0, v2
	v_rcp_f32_e32 v8, v8
	v_mul_f32_e32 v150, v148, v16
	v_mul_f32_e32 v151, v149, v17
	v_add_f32_e32 v2, v3, v2
	v_add_f32_e32 v2, v150, v2
	v_mul_f32_e32 v4, v14, v12
	v_mul_f32_e32 v5, v15, v13
	v_add_f32_e32 v2, v151, v2
	v_add_f32_e32 v2, v4, v2
	v_mul_f32_e32 v10, v8, v6
	v_mul_f32_e32 v11, v9, v7
	v_add_f32_e32 v2, v5, v2
	v_add_f32_e32 v2, v10, v2
	v_add_f32_e32 v2, v11, v2
	s_nop 0
	v_lshlrev_b32_e32 v150, 1, v169
	s_nop 1
	v_add_f32_dpp v2, v2, v2 quad_perm:[1,0,3,2] row_mask:0xf bank_mask:0xf
	s_nop 0
	s_nop 1
	v_add_f32_dpp v2, v2, v2 quad_perm:[2,3,0,1] row_mask:0xf bank_mask:0xf
	s_nop 0
	s_nop 1
	v_add_f32_dpp v2, v2, v2 row_half_mirror row_mask:0xf bank_mask:0xf
	v_mul_f32_e32 v2, 0x3c800000, v2
	v_fma_f32 v4, v154, v152, -v2
	v_fma_f32 v5, v155, v153, -v2
	v_fma_f32 v16, v148, v16, -v2
	v_fma_f32 v17, v149, v17, -v2
	v_mul_f32_e32 v10, v4, v4
	v_mul_f32_e32 v11, v5, v5
	v_mul_f32_e32 v148, v16, v16
	v_mul_f32_e32 v149, v17, v17
	v_fma_f32 v6, v8, v6, -v2
	v_fma_f32 v7, v9, v7, -v2
	v_add_f32_e32 v8, v10, v11
	v_fma_f32 v12, v14, v12, -v2
	v_fma_f32 v13, v15, v13, -v2
	v_add_f32_e32 v8, v148, v8
	v_mul_f32_e32 v14, v12, v12
	v_mul_f32_e32 v15, v13, v13
	v_add_f32_e32 v8, v149, v8
	v_add_f32_e32 v8, v14, v8
	v_mul_f32_e32 v2, v6, v6
	v_mul_f32_e32 v3, v7, v7
	v_add_f32_e32 v8, v15, v8
	v_add_f32_e32 v2, v2, v8
	v_add_f32_e32 v2, v3, v2
	s_nop 0
	v_lshl_add_u64 v[148:149], s[6:7], 0, v[0:1]
	s_nop 1
	v_add_f32_dpp v2, v2, v2 quad_perm:[1,0,3,2] row_mask:0xf bank_mask:0xf
	s_nop 0
	s_nop 1
	v_add_f32_dpp v2, v2, v2 quad_perm:[2,3,0,1] row_mask:0xf bank_mask:0xf
	s_nop 0
	s_nop 1
	v_add_f32_dpp v2, v2, v2 row_half_mirror row_mask:0xf bank_mask:0xf
	v_fmamk_f32 v2, v2, 0x3c800000, v229
	v_rsq_f32_e32 v8, v2
	s_nop 0
	v_mul_f32_e32 v2, v4, v8
	v_mul_f32_e32 v3, v5, v8
	v_mul_f32_e32 v4, v16, v8
	v_mul_f32_e32 v5, v17, v8
	v_cvt_pk_f16_f32 v2, v2, v3
	v_cvt_pk_f16_f32 v3, v4, v5
	v_mul_f32_e32 v4, v12, v8
	v_mul_f32_e32 v5, v13, v8
	v_mul_f32_e32 v6, v6, v8
	v_mul_f32_e32 v7, v7, v8
	v_cvt_pk_f16_f32 v4, v4, v5
	v_cvt_pk_f16_f32 v5, v6, v7
	ds_write_b128 v179, v[2:5] offset:7168
	v_and_b32_e32 v3, 16, v247
	v_and_or_b32 v3, v164, 12, v3
	v_and_b32_e32 v2, 0x2c0, v171
	v_lshlrev_b32_e32 v3, 1, v3
	s_waitcnt lgkmcnt(0)
	s_barrier
	v_add3_u32 v151, s4, v2, v3
	ds_read_b64_tr_b16 v[2:3], v151
	ds_read_b64_tr_b16 v[4:5], v151 offset:256
	ds_read_b64_tr_b16 v[152:153], v151 offset:1024
	ds_read_b64_tr_b16 v[154:155], v151 offset:1280
	ds_read_b64_tr_b16 v[156:157], v151 offset:2048
	ds_read_b64_tr_b16 v[158:159], v151 offset:2304
	ds_read_b64_tr_b16 v[160:161], v151 offset:3072
	ds_read_b64_tr_b16 v[162:163], v151 offset:3328
	ds_read_b64_tr_b16 v[182:183], v151 offset:4096
	ds_read_b64_tr_b16 v[184:185], v151 offset:4352
	ds_read_b64_tr_b16 v[186:187], v151 offset:5120
	ds_read_b64_tr_b16 v[188:189], v151 offset:5376
	ds_read_b64_tr_b16 v[190:191], v151 offset:6144
	ds_read_b64_tr_b16 v[192:193], v151 offset:6400
	ds_read_b64_tr_b16 v[194:195], v151 offset:7168
	ds_read_b64_tr_b16 v[196:197], v151 offset:7424
	s_waitcnt vmcnt(39) lgkmcnt(14)
	v_mfma_f32_32x32x16_f16 v[2:17], v[140:143], v[2:5], 0
	s_or_b32 s4, s2, s5
	v_or_b32_e32 v164, s4, v167
	s_or_b32 s2, s2, s3
	s_waitcnt vmcnt(38) lgkmcnt(12)
	v_mfma_f32_32x32x16_f16 v[2:17], v[144:147], v[152:155], v[2:17]
	v_mul_u32_u24_e32 v152, 0x240, v248
	v_add3_u32 v150, s8, v150, v152
	s_waitcnt vmcnt(37) lgkmcnt(10)
	v_mfma_f32_32x32x16_f16 v[2:17], v[136:139], v[156:159], v[2:17]
	s_waitcnt vmcnt(36) lgkmcnt(8)
	v_mfma_f32_32x32x16_f16 v[2:17], v[132:135], v[160:163], v[2:17]
	s_waitcnt vmcnt(35) lgkmcnt(6)
	v_mfma_f32_32x32x16_f16 v[2:17], v[126:129], v[182:185], v[2:17]
	s_waitcnt vmcnt(34) lgkmcnt(4)
	v_mfma_f32_32x32x16_f16 v[2:17], v[122:125], v[186:189], v[2:17]
	s_waitcnt vmcnt(33) lgkmcnt(2)
	v_mfma_f32_32x32x16_f16 v[2:17], v[118:121], v[190:193], v[2:17]
	s_waitcnt vmcnt(32) lgkmcnt(0)
; #define LAS __attribute__((address_space(3)))
; __device__ __forceinline__ float siluf(float x) { return x * __builtin_amdgcn_rcpf(1.f + __builtin_amdgcn_exp2f(-1.4426950408889634f * x)); }
; __device__ __forceinline__ float geluf(float x) { return x * __builtin_amdgcn_rcpf(1.f + __builtin_amdgcn_exp2f(x * (-0.10294324f * x * x - 2.3022082f))); }
; #define LDS_WAIT() asm volatile("s_waitcnt lgkmcnt(0)" ::: "memory")
; __device__ __forceinline__ int crow(int r, int hi) { return (r & 3) + 8 * (r >> 2) + 4 * hi; }
; __device__ __forceinline__ void gmlp_unit(unsigned char* ws, h16* Y, const h16* Ws16  , const float* bs  , size_t r0, LAS unsigned char* lds, int tid) {
;     ...
;     for (int q = 0; q < 2; ++q) {
; #pragma unroll
;         for (int db = 0; db < 2; ++db) {
;             s16x8 bf[8];
; #pragma unroll
;             for (int ks = 0; ks < 8; ++ks) bf[ks] = tr_frag((LAS const char*)lds + g * 16384, 8192, db, ks, lane);
;             f32x16 acc = f32x16{};
; #pragma unroll
;             for (int ks = 0; ks < 8; ++ks) acc = __builtin_amdgcn_mfma_f32_32x32x16_f16(H8(af[q][ks]), H8(bf[ks]), acc, 0, 0, 0);
; #pragma unroll
;             for (int r = 0; r < 16; ++r) scr[crow(r, hi) * 72 + 32 * db + r32] = (h16)acc[r];
;         }
;         LDS_WAIT();
; #pragma unroll
;         for (int ps = 0; ps < 4; ++ps) { const int row = 8 * ps + erow;
;             const h16x8 sv = *(const LAS h16x8*)(scr + row * 72 + 8 * ech);
;             float y[8];
; #pragma unroll
;             for (int k = 0; k < 8; ++k) y[k] = geluf((float)gu[q][ps][k]) * ((float)sv[k] + bias[q][ps]) * siluf((float)sz[q][ps][k]);
	v_mfma_f32_32x32x16_f16 v[2:17], v[114:117], v[194:197], v[2:17]
	s_nop 11
	v_cvt_f16_f32_e32 v2, v2
	ds_write_b16 v150, v2
	v_cvt_f16_f32_e32 v2, v3
	ds_write_b16 v150, v2 offset:144
	v_cvt_f16_f32_e32 v2, v4
	ds_write_b16 v150, v2 offset:288
	v_cvt_f16_f32_e32 v2, v5
	ds_write_b16 v150, v2 offset:432
	v_cvt_f16_f32_e32 v2, v6
	ds_write_b16 v150, v2 offset:1152
	v_cvt_f16_f32_e32 v2, v7
	ds_write_b16 v150, v2 offset:1296
	v_cvt_f16_f32_e32 v2, v8
	ds_write_b16 v150, v2 offset:1440
	v_cvt_f16_f32_e32 v2, v9
	ds_write_b16 v150, v2 offset:1584
	v_cvt_f16_f32_e32 v2, v10
	ds_write_b16 v150, v2 offset:2304
	v_cvt_f16_f32_e32 v2, v11
	ds_write_b16 v150, v2 offset:2448
	v_cvt_f16_f32_e32 v2, v12
	ds_write_b16 v150, v2 offset:2592
	v_cvt_f16_f32_e32 v2, v13
	ds_write_b16 v150, v2 offset:2736
	v_cvt_f16_f32_e32 v2, v14
	ds_write_b16 v150, v2 offset:3456
	v_cvt_f16_f32_e32 v2, v15
	ds_write_b16 v150, v2 offset:3600
	v_cvt_f16_f32_e32 v2, v16
	ds_write_b16 v150, v2 offset:3744
	v_cvt_f16_f32_e32 v2, v17
	ds_write_b16 v150, v2 offset:3888
	ds_read_b64_tr_b16 v[2:3], v151 offset:8192
	ds_read_b64_tr_b16 v[4:5], v151 offset:8448
	ds_read_b64_tr_b16 v[152:153], v151 offset:9216
	ds_read_b64_tr_b16 v[154:155], v151 offset:9472
	ds_read_b64_tr_b16 v[156:157], v151 offset:10240
	ds_read_b64_tr_b16 v[158:159], v151 offset:10496
	ds_read_b64_tr_b16 v[160:161], v151 offset:11264
	ds_read_b64_tr_b16 v[162:163], v151 offset:11520
	ds_read_b64_tr_b16 v[182:183], v151 offset:12288
	ds_read_b64_tr_b16 v[184:185], v151 offset:12544
	ds_read_b64_tr_b16 v[186:187], v151 offset:13312
	ds_read_b64_tr_b16 v[188:189], v151 offset:13568
	ds_read_b64_tr_b16 v[190:191], v151 offset:14336
	ds_read_b64_tr_b16 v[192:193], v151 offset:14592
	ds_read_b64_tr_b16 v[194:195], v151 offset:15360
	ds_read_b64_tr_b16 v[196:197], v151 offset:15616
	s_waitcnt lgkmcnt(14)
	v_mfma_f32_32x32x16_f16 v[2:17], v[140:143], v[2:5], 0
	s_waitcnt lgkmcnt(12)
	v_mfma_f32_32x32x16_f16 v[2:17], v[144:147], v[152:155], v[2:17]
	s_waitcnt lgkmcnt(10)
	v_mfma_f32_32x32x16_f16 v[2:17], v[136:139], v[156:159], v[2:17]
	s_waitcnt lgkmcnt(8)
	v_mfma_f32_32x32x16_f16 v[2:17], v[132:135], v[160:163], v[2:17]
	s_waitcnt lgkmcnt(6)
	v_mfma_f32_32x32x16_f16 v[2:17], v[126:129], v[182:185], v[2:17]
	s_waitcnt lgkmcnt(4)
	v_mfma_f32_32x32x16_f16 v[2:17], v[122:125], v[186:189], v[2:17]
	s_waitcnt lgkmcnt(2)
	v_mfma_f32_32x32x16_f16 v[2:17], v[118:121], v[190:193], v[2:17]
	s_waitcnt lgkmcnt(0)
	v_mfma_f32_32x32x16_f16 v[2:17], v[114:117], v[194:197], v[2:17]
	s_nop 11
	v_cvt_f16_f32_e32 v2, v2
	ds_write_b16 v150, v2 offset:64
	v_cvt_f16_f32_e32 v2, v3
	ds_write_b16 v150, v2 offset:208
	v_cvt_f16_f32_e32 v2, v4
	ds_write_b16 v150, v2 offset:352
	v_cvt_f16_f32_e32 v2, v5
	ds_write_b16 v150, v2 offset:496
	v_cvt_f16_f32_e32 v2, v6
	s_waitcnt vmcnt(23)
	v_cvt_f32_f16_e32 v6, v106
	ds_write_b16 v150, v2 offset:1216
	v_cvt_f16_f32_e32 v2, v7
	v_cvt_f32_f16_sdwa v7, v106 dst_sel:DWORD dst_unused:UNUSED_PAD src0_sel:WORD_1
	ds_write_b16 v150, v2 offset:1360
	v_cvt_f16_f32_e32 v2, v8
	v_mul_f32_e32 v8, 0x3dd2d3e8, v6
	v_fma_mix_f32 v8, -v8, v106, s9 op_sel_hi:[0,1,0]
	v_mul_f32_e32 v8, v8, v6
	ds_write_b16 v150, v2 offset:1504
	v_cvt_f16_f32_e32 v2, v9
	v_exp_f32_e32 v8, v8
	ds_write_b16 v150, v2 offset:1648
	v_cvt_f16_f32_e32 v2, v10
	s_waitcnt vmcnt(21)
	v_cvt_f32_f16_e32 v10, v110
	v_add_f32_e32 v8, 1.0, v8
	v_rcp_f32_e32 v8, v8
	ds_write_b16 v150, v2 offset:2368
	v_cvt_f16_f32_e32 v2, v11
	v_mul_f32_e32 v9, 0xbfb8aa3b, v10
	v_exp_f32_e32 v9, v9
	v_cvt_f32_f16_sdwa v11, v110 dst_sel:DWORD dst_unused:UNUSED_PAD src0_sel:WORD_1
	ds_write_b16 v150, v2 offset:2512
	v_cvt_f16_f32_e32 v2, v12
	v_add_f32_e32 v9, 1.0, v9
	v_rcp_f32_e32 v12, v9
	v_mul_f32_e32 v9, 0x3dd2d3e8, v7
	ds_write_b16 v150, v2 offset:2656
	v_cvt_f16_f32_e32 v2, v13
	v_fma_mix_f32 v9, -v9, v106, s9 op_sel:[0,1,0] op_sel_hi:[0,1,0]
	v_mul_f32_e32 v9, v9, v7
	v_exp_f32_e32 v9, v9
	ds_write_b16 v150, v2 offset:2800
	v_cvt_f16_f32_e32 v2, v14
	v_or_b32_e32 v106, 8, v167
	v_add_f32_e32 v9, 1.0, v9
	v_rcp_f32_e32 v9, v9
	ds_write_b16 v150, v2 offset:3520
	v_cvt_f16_f32_e32 v2, v15
	v_mul_f32_e32 v6, v8, v6
	v_mul_f32_e32 v7, v9, v7
	ds_write_b16 v150, v2 offset:3664
	v_cvt_f16_f32_e32 v2, v16
	ds_write_b16 v150, v2 offset:3808
	v_cvt_f16_f32_e32 v2, v17
	ds_write_b16 v150, v2 offset:3952
	v_mul_u32_u24_e32 v2, 0x90, v167
	s_waitcnt lgkmcnt(0)
	v_add3_u32 v0, s8, v0, v2
	ds_read_b128 v[2:5], v0
	s_waitcnt lgkmcnt(0)
; #define LAS __attribute__((address_space(3)))
; #define GAS __attribute__((address_space(1)))
; __device__ __forceinline__ float siluf(float x) { return x * __builtin_amdgcn_rcpf(1.f + __builtin_amdgcn_exp2f(-1.4426950408889634f * x)); }
; __device__ __forceinline__ float geluf(float x) { return x * __builtin_amdgcn_rcpf(1.f + __builtin_amdgcn_exp2f(x * (-0.10294324f * x * x - 2.3022082f))); }
; __device__ __forceinline__ unsigned cvtpk_h(float lo, float hi) { f32x2 v = {lo, hi}; h16x2 b = __builtin_convertvector(v, h16x2); return __builtin_bit_cast(unsigned, b); }
; __device__ __forceinline__ void gmlp_unit(unsigned char* ws, h16* Y, const h16* Ws16  , const float* bs  , size_t r0, LAS unsigned char* lds, int tid) {
;     ...
;         for (int ps = 0; ps < 4; ++ps) { const int row = 8 * ps + erow;
;             const h16x8 sv = *(const LAS h16x8*)(scr + row * 72 + 8 * ech);
;             float y[8];
; #pragma unroll
;             for (int k = 0; k < 8; ++k) y[k] = geluf((float)gu[q][ps][k]) * ((float)sv[k] + bias[q][ps]) * siluf((float)sz[q][ps][k]);
;             u32x4 w0; w0.x = cvtpk_h(y[0], y[1]); w0.y = cvtpk_h(y[2], y[3]); w0.z = cvtpk_h(y[4], y[5]); w0.w = cvtpk_h(y[6], y[7]);
;             *(GAS u32x4*)(Y + (r0 + 32 * (2 * ph + q) + row) * D + g * 64 + 8 * ech) = w0; }
	v_cvt_f32_f16_e32 v8, v2
	v_cvt_f32_f16_sdwa v9, v2 dst_sel:DWORD dst_unused:UNUSED_PAD src0_sel:WORD_1
	v_mul_f32_e32 v2, 0xbfb8aa3b, v11
	v_exp_f32_e32 v2, v2
	v_add_f32_e32 v8, v180, v8
	v_add_f32_e32 v9, v180, v9
	v_mul_f32_e32 v6, v6, v8
	v_mul_f32_e32 v7, v7, v9
	v_add_f32_e32 v2, 1.0, v2
	v_rcp_f32_e32 v13, v2
	s_nop 0
	v_mul_f32_e32 v8, v12, v10
	v_mul_f32_e32 v9, v13, v11
	s_nop 0
	v_mul_f32_e32 v6, v8, v6
	v_mul_f32_e32 v7, v9, v7
	v_cvt_f32_f16_e32 v8, v107
	v_cvt_f32_f16_sdwa v9, v107 dst_sel:DWORD dst_unused:UNUSED_PAD src0_sel:WORD_1
	v_cvt_f32_f16_e32 v12, v111
	v_cvt_f32_f16_sdwa v13, v111 dst_sel:DWORD dst_unused:UNUSED_PAD src0_sel:WORD_1
	v_mul_f32_e32 v2, 0x3dd2d3e8, v8
	v_mul_f32_e32 v11, 0x3dd2d3e8, v9
	v_fma_mix_f32 v2, -v2, v107, s9 op_sel_hi:[0,1,0]
	v_fma_mix_f32 v11, -v11, v107, s9 op_sel:[0,1,0] op_sel_hi:[0,1,0]
	v_mul_f32_e32 v2, v2, v8
	v_mul_f32_e32 v11, v11, v9
	v_exp_f32_e32 v2, v2
	v_exp_f32_e32 v11, v11
	v_add_f32_e32 v2, 1.0, v2
	v_add_f32_e32 v11, 1.0, v11
	v_rcp_f32_e32 v10, v2
	v_rcp_f32_e32 v11, v11
	v_mul_f32_e32 v2, 0xbfb8aa3b, v12
	v_exp_f32_e32 v2, v2
	v_mul_f32_e32 v8, v10, v8
	v_mul_f32_e32 v9, v11, v9
	v_cvt_f32_f16_e32 v10, v3
	v_cvt_f32_f16_sdwa v11, v3 dst_sel:DWORD dst_unused:UNUSED_PAD src0_sel:WORD_1
	v_mul_f32_e32 v3, 0xbfb8aa3b, v13
	v_exp_f32_e32 v3, v3
	v_add_f32_e32 v2, 1.0, v2
	v_rcp_f32_e32 v2, v2
	v_add_f32_e32 v10, v180, v10
	v_add_f32_e32 v11, v180, v11
	v_add_f32_e32 v3, 1.0, v3
	v_rcp_f32_e32 v3, v3
	v_mul_f32_e32 v8, v8, v10
	v_mul_f32_e32 v9, v9, v11
	v_mul_f32_e32 v2, v2, v12
	v_mul_f32_e32 v3, v3, v13
	v_cvt_f32_f16_e32 v12, v112
	v_mul_f32_e32 v8, v2, v8
	v_mul_f32_e32 v9, v3, v9
	v_cvt_f32_f16_e32 v2, v108
	v_cvt_f32_f16_sdwa v3, v108 dst_sel:DWORD dst_unused:UNUSED_PAD src0_sel:WORD_1
	v_mul_f32_e32 v11, 0xbfb8aa3b, v12
	v_exp_f32_e32 v11, v11
	v_mul_f32_e32 v10, 0x3dd2d3e8, v2
	v_fma_mix_f32 v10, -v10, v108, s9 op_sel_hi:[0,1,0]
	v_mul_f32_e32 v10, v10, v2
	v_add_f32_e32 v11, 1.0, v11
	v_rcp_f32_e32 v14, v11
	v_mul_f32_e32 v11, 0x3dd2d3e8, v3
	v_fma_mix_f32 v11, -v11, v108, s9 op_sel:[0,1,0] op_sel_hi:[0,1,0]
	v_mul_f32_e32 v11, v11, v3
	v_exp_f32_e32 v10, v10
	v_exp_f32_e32 v11, v11
	v_cvt_f32_f16_sdwa v13, v112 dst_sel:DWORD dst_unused:UNUSED_PAD src0_sel:WORD_1
	v_add_f32_e32 v10, 1.0, v10
	v_add_f32_e32 v11, 1.0, v11
	v_rcp_f32_e32 v10, v10
	v_rcp_f32_e32 v11, v11
	s_nop 0
	v_mul_f32_e32 v2, v10, v2
	v_mul_f32_e32 v3, v11, v3
	v_cvt_f32_f16_e32 v10, v4
	v_cvt_f32_f16_sdwa v11, v4 dst_sel:DWORD dst_unused:UNUSED_PAD src0_sel:WORD_1
	v_mul_f32_e32 v4, 0xbfb8aa3b, v13
	v_exp_f32_e32 v4, v4
	v_add_f32_e32 v10, v180, v10
	v_add_f32_e32 v11, v180, v11
	v_mul_f32_e32 v2, v2, v10
	v_mul_f32_e32 v3, v3, v11
	v_add_f32_e32 v4, 1.0, v4
	v_rcp_f32_e32 v15, v4
	s_nop 0
	v_mul_f32_e32 v10, v14, v12
	v_mul_f32_e32 v11, v15, v13
	s_nop 0
	v_mul_f32_e32 v10, v10, v2
	v_mul_f32_e32 v11, v11, v3
	v_cvt_f32_f16_e32 v2, v109
	v_cvt_f32_f16_sdwa v3, v109 dst_sel:DWORD dst_unused:UNUSED_PAD src0_sel:WORD_1
	v_cvt_f32_f16_e32 v14, v113
	v_cvt_f32_f16_sdwa v15, v113 dst_sel:DWORD dst_unused:UNUSED_PAD src0_sel:WORD_1
	v_mul_f32_e32 v4, 0x3dd2d3e8, v2
	v_mul_f32_e32 v13, 0x3dd2d3e8, v3
	v_fma_mix_f32 v4, -v4, v109, s9 op_sel_hi:[0,1,0]
	v_fma_mix_f32 v13, -v13, v109, s9 op_sel:[0,1,0] op_sel_hi:[0,1,0]
	v_mul_f32_e32 v4, v4, v2
	v_mul_f32_e32 v13, v13, v3
	v_exp_f32_e32 v4, v4
	v_exp_f32_e32 v13, v13
	v_add_f32_e32 v4, 1.0, v4
	v_add_f32_e32 v13, 1.0, v13
	v_rcp_f32_e32 v12, v4
	v_rcp_f32_e32 v13, v13
	v_mul_f32_e32 v4, 0xbfb8aa3b, v14
	v_exp_f32_e32 v4, v4
	v_mul_f32_e32 v2, v12, v2
	v_mul_f32_e32 v3, v13, v3
	v_cvt_f32_f16_e32 v12, v5
	v_cvt_f32_f16_sdwa v13, v5 dst_sel:DWORD dst_unused:UNUSED_PAD src0_sel:WORD_1
	v_mul_f32_e32 v5, 0xbfb8aa3b, v15
	v_exp_f32_e32 v5, v5
	v_add_f32_e32 v4, 1.0, v4
	v_rcp_f32_e32 v4, v4
	v_add_f32_e32 v12, v180, v12
	v_add_f32_e32 v13, v180, v13
	v_add_f32_e32 v5, 1.0, v5
	v_rcp_f32_e32 v5, v5
	v_mul_f32_e32 v2, v2, v12
	v_mul_f32_e32 v3, v3, v13
	v_mul_f32_e32 v4, v4, v14
	v_mul_f32_e32 v5, v5, v15
	s_nop 0
	v_mul_f32_e32 v12, v4, v2
	v_mul_f32_e32 v13, v5, v3
	v_cvt_pk_f16_f32 v4, v10, v11
	s_waitcnt vmcnt(18)
	v_cvt_f32_f16_e32 v10, v102
	v_cvt_pk_f16_f32 v2, v6, v7
	v_cvt_pk_f16_f32 v3, v8, v9
	v_lshlrev_b64 v[6:7], 11, v[164:165]
	v_mul_f32_e32 v9, 0xbfb8aa3b, v10
	v_cvt_pk_f16_f32 v5, v12, v13
	v_lshl_add_u64 v[6:7], v[148:149], 0, v[6:7]
	v_exp_f32_e32 v9, v9
	global_store_dwordx4 v[6:7], v[2:5], off sc1
	v_cvt_f32_f16_e32 v6, v98
	v_cvt_f32_f16_sdwa v7, v98 dst_sel:DWORD dst_unused:UNUSED_PAD src0_sel:WORD_1
	v_add_f32_e32 v9, 1.0, v9
	v_rcp_f32_e32 v12, v9
	v_mul_f32_e32 v8, 0x3dd2d3e8, v6
	v_mul_f32_e32 v9, 0x3dd2d3e8, v7
	v_fma_mix_f32 v8, -v8, v98, s9 op_sel_hi:[0,1,0]
	v_fma_mix_f32 v9, -v9, v98, s9 op_sel:[0,1,0] op_sel_hi:[0,1,0]
	v_mul_f32_e32 v8, v8, v6
	v_mul_f32_e32 v9, v9, v7
	v_exp_f32_e32 v8, v8
	v_exp_f32_e32 v9, v9
	ds_read_b128 v[2:5], v0 offset:1152
	v_cvt_f32_f16_sdwa v11, v102 dst_sel:DWORD dst_unused:UNUSED_PAD src0_sel:WORD_1
	v_add_f32_e32 v8, 1.0, v8
	v_add_f32_e32 v9, 1.0, v9
	v_rcp_f32_e32 v8, v8
	v_rcp_f32_e32 v9, v9
	v_or_b32_e32 v164, s4, v106
	v_or_b32_e32 v98, 16, v167
	v_mul_f32_e32 v6, v8, v6
	v_mul_f32_e32 v7, v9, v7
	s_waitcnt lgkmcnt(0)
; #define LAS __attribute__((address_space(3)))
; #define GAS __attribute__((address_space(1)))
; __device__ __forceinline__ float siluf(float x) { return x * __builtin_amdgcn_rcpf(1.f + __builtin_amdgcn_exp2f(-1.4426950408889634f * x)); }
; __device__ __forceinline__ float geluf(float x) { return x * __builtin_amdgcn_rcpf(1.f + __builtin_amdgcn_exp2f(x * (-0.10294324f * x * x - 2.3022082f))); }
; __device__ __forceinline__ unsigned cvtpk_h(float lo, float hi) { f32x2 v = {lo, hi}; h16x2 b = __builtin_convertvector(v, h16x2); return __builtin_bit_cast(unsigned, b); }
; __device__ __forceinline__ void gmlp_unit(unsigned char* ws, h16* Y, const h16* Ws16  , const float* bs  , size_t r0, LAS unsigned char* lds, int tid) {
;     ...
;         for (int ps = 0; ps < 4; ++ps) { const int row = 8 * ps + erow;
;             const h16x8 sv = *(const LAS h16x8*)(scr + row * 72 + 8 * ech);
;             float y[8];
; #pragma unroll
;             for (int k = 0; k < 8; ++k) y[k] = geluf((float)gu[q][ps][k]) * ((float)sv[k] + bias[q][ps]) * siluf((float)sz[q][ps][k]);
;             u32x4 w0; w0.x = cvtpk_h(y[0], y[1]); w0.y = cvtpk_h(y[2], y[3]); w0.z = cvtpk_h(y[4], y[5]); w0.w = cvtpk_h(y[6], y[7]);
;             *(GAS u32x4*)(Y + (r0 + 32 * (2 * ph + q) + row) * D + g * 64 + 8 * ech) = w0; }
	v_cvt_f32_f16_e32 v8, v2
	v_cvt_f32_f16_sdwa v9, v2 dst_sel:DWORD dst_unused:UNUSED_PAD src0_sel:WORD_1
	v_mul_f32_e32 v2, 0xbfb8aa3b, v11
	v_exp_f32_e32 v2, v2
	v_add_f32_e32 v8, v178, v8
	v_add_f32_e32 v9, v178, v9
	v_mul_f32_e32 v6, v6, v8
	v_mul_f32_e32 v7, v7, v9
	v_add_f32_e32 v2, 1.0, v2
	v_rcp_f32_e32 v13, v2
	s_nop 0
	v_mul_f32_e32 v8, v12, v10
	v_mul_f32_e32 v9, v13, v11
	s_nop 0
	v_mul_f32_e32 v6, v8, v6
	v_mul_f32_e32 v7, v9, v7
	v_cvt_f32_f16_e32 v8, v99
	v_cvt_f32_f16_sdwa v9, v99 dst_sel:DWORD dst_unused:UNUSED_PAD src0_sel:WORD_1
	v_cvt_f32_f16_e32 v12, v103
	v_cvt_f32_f16_sdwa v13, v103 dst_sel:DWORD dst_unused:UNUSED_PAD src0_sel:WORD_1
	v_mul_f32_e32 v2, 0x3dd2d3e8, v8
	v_mul_f32_e32 v11, 0x3dd2d3e8, v9
	v_fma_mix_f32 v2, -v2, v99, s9 op_sel_hi:[0,1,0]
	v_fma_mix_f32 v11, -v11, v99, s9 op_sel:[0,1,0] op_sel_hi:[0,1,0]
	v_mul_f32_e32 v2, v2, v8
	v_mul_f32_e32 v11, v11, v9
	v_exp_f32_e32 v2, v2
	v_exp_f32_e32 v11, v11
	v_add_f32_e32 v2, 1.0, v2
	v_add_f32_e32 v11, 1.0, v11
	v_rcp_f32_e32 v10, v2
	v_rcp_f32_e32 v11, v11
	v_mul_f32_e32 v2, 0xbfb8aa3b, v12
	v_exp_f32_e32 v2, v2
	v_mul_f32_e32 v8, v10, v8
	v_mul_f32_e32 v9, v11, v9
	v_cvt_f32_f16_e32 v10, v3
	v_cvt_f32_f16_sdwa v11, v3 dst_sel:DWORD dst_unused:UNUSED_PAD src0_sel:WORD_1
	v_mul_f32_e32 v3, 0xbfb8aa3b, v13
	v_exp_f32_e32 v3, v3
	v_add_f32_e32 v2, 1.0, v2
	v_rcp_f32_e32 v2, v2
	v_add_f32_e32 v10, v178, v10
	v_add_f32_e32 v11, v178, v11
	v_add_f32_e32 v3, 1.0, v3
	v_rcp_f32_e32 v3, v3
	v_mul_f32_e32 v8, v8, v10
	v_mul_f32_e32 v9, v9, v11
	v_mul_f32_e32 v2, v2, v12
	v_mul_f32_e32 v3, v3, v13
	v_cvt_f32_f16_e32 v12, v104
	v_mul_f32_e32 v2, v2, v8
	v_mul_f32_e32 v3, v3, v9
	v_cvt_f32_f16_e32 v8, v100
	v_cvt_f32_f16_sdwa v9, v100 dst_sel:DWORD dst_unused:UNUSED_PAD src0_sel:WORD_1
	v_mul_f32_e32 v11, 0xbfb8aa3b, v12
	v_exp_f32_e32 v11, v11
	v_mul_f32_e32 v10, 0x3dd2d3e8, v8
	v_fma_mix_f32 v10, -v10, v100, s9 op_sel_hi:[0,1,0]
	v_mul_f32_e32 v10, v10, v8
	v_add_f32_e32 v11, 1.0, v11
	v_rcp_f32_e32 v14, v11
	v_mul_f32_e32 v11, 0x3dd2d3e8, v9
	v_fma_mix_f32 v11, -v11, v100, s9 op_sel:[0,1,0] op_sel_hi:[0,1,0]
	v_mul_f32_e32 v11, v11, v9
	v_exp_f32_e32 v10, v10
	v_exp_f32_e32 v11, v11
	v_cvt_f32_f16_sdwa v13, v104 dst_sel:DWORD dst_unused:UNUSED_PAD src0_sel:WORD_1
	v_add_f32_e32 v10, 1.0, v10
	v_add_f32_e32 v11, 1.0, v11
	v_rcp_f32_e32 v10, v10
	v_rcp_f32_e32 v11, v11
	s_nop 0
	v_mul_f32_e32 v8, v10, v8
	v_mul_f32_e32 v9, v11, v9
	v_cvt_f32_f16_e32 v10, v4
	v_cvt_f32_f16_sdwa v11, v4 dst_sel:DWORD dst_unused:UNUSED_PAD src0_sel:WORD_1
	v_mul_f32_e32 v4, 0xbfb8aa3b, v13
	v_exp_f32_e32 v4, v4
	v_add_f32_e32 v10, v178, v10
	v_add_f32_e32 v11, v178, v11
	v_mul_f32_e32 v8, v8, v10
	v_mul_f32_e32 v9, v9, v11
	v_add_f32_e32 v4, 1.0, v4
	v_rcp_f32_e32 v15, v4
	s_nop 0
	v_mul_f32_e32 v10, v14, v12
	v_mul_f32_e32 v11, v15, v13
	s_nop 0
	v_mul_f32_e32 v8, v10, v8
	v_mul_f32_e32 v9, v11, v9
	v_cvt_f32_f16_e32 v10, v101
	v_cvt_f32_f16_sdwa v11, v101 dst_sel:DWORD dst_unused:UNUSED_PAD src0_sel:WORD_1
	v_cvt_f32_f16_e32 v14, v105
	v_cvt_f32_f16_sdwa v15, v105 dst_sel:DWORD dst_unused:UNUSED_PAD src0_sel:WORD_1
	v_mul_f32_e32 v4, 0x3dd2d3e8, v10
	v_mul_f32_e32 v13, 0x3dd2d3e8, v11
	v_fma_mix_f32 v4, -v4, v101, s9 op_sel_hi:[0,1,0]
	v_fma_mix_f32 v13, -v13, v101, s9 op_sel:[0,1,0] op_sel_hi:[0,1,0]
	v_mul_f32_e32 v4, v4, v10
	v_mul_f32_e32 v13, v13, v11
	v_exp_f32_e32 v4, v4
	v_exp_f32_e32 v13, v13
	v_add_f32_e32 v4, 1.0, v4
	v_add_f32_e32 v13, 1.0, v13
	v_rcp_f32_e32 v12, v4
	v_rcp_f32_e32 v13, v13
	v_mul_f32_e32 v4, 0xbfb8aa3b, v14
	v_exp_f32_e32 v4, v4
	v_mul_f32_e32 v10, v12, v10
	v_mul_f32_e32 v11, v13, v11
	v_cvt_f32_f16_e32 v12, v5
	v_cvt_f32_f16_sdwa v13, v5 dst_sel:DWORD dst_unused:UNUSED_PAD src0_sel:WORD_1
	v_mul_f32_e32 v5, 0xbfb8aa3b, v15
	v_exp_f32_e32 v5, v5
	v_add_f32_e32 v4, 1.0, v4
	v_rcp_f32_e32 v4, v4
	v_add_f32_e32 v12, v178, v12
	v_add_f32_e32 v13, v178, v13
	v_add_f32_e32 v5, 1.0, v5
	v_rcp_f32_e32 v5, v5
	v_mul_f32_e32 v10, v10, v12
	v_mul_f32_e32 v11, v11, v13
	v_mul_f32_e32 v4, v4, v14
	v_mul_f32_e32 v5, v5, v15
	s_nop 0
	v_mul_f32_e32 v10, v4, v10
	v_mul_f32_e32 v11, v5, v11
	v_cvt_pk_f16_f32 v4, v6, v7
	v_cvt_pk_f16_f32 v7, v10, v11
	s_waitcnt vmcnt(16)
	v_cvt_f32_f16_e32 v10, v94
	v_cvt_pk_f16_f32 v5, v2, v3
	v_cvt_pk_f16_f32 v6, v8, v9
	v_lshlrev_b64 v[2:3], 11, v[164:165]
	v_mul_f32_e32 v9, 0xbfb8aa3b, v10
	v_lshl_add_u64 v[2:3], v[148:149], 0, v[2:3]
	v_exp_f32_e32 v9, v9
	global_store_dwordx4 v[2:3], v[4:7], off sc1
	ds_read_b128 v[2:5], v0 offset:2304
	v_cvt_f32_f16_sdwa v11, v94 dst_sel:DWORD dst_unused:UNUSED_PAD src0_sel:WORD_1
	v_cvt_f32_f16_e32 v6, v90
	v_cvt_f32_f16_sdwa v7, v90 dst_sel:DWORD dst_unused:UNUSED_PAD src0_sel:WORD_1
	v_add_f32_e32 v9, 1.0, v9
	v_rcp_f32_e32 v12, v9
	v_mul_f32_e32 v8, 0x3dd2d3e8, v6
	v_mul_f32_e32 v9, 0x3dd2d3e8, v7
	v_fma_mix_f32 v8, -v8, v90, s9 op_sel_hi:[0,1,0]
	v_fma_mix_f32 v9, -v9, v90, s9 op_sel:[0,1,0] op_sel_hi:[0,1,0]
	v_mul_f32_e32 v8, v8, v6
	v_mul_f32_e32 v9, v9, v7
	v_exp_f32_e32 v8, v8
	v_exp_f32_e32 v9, v9
	v_or_b32_e32 v164, s4, v98
	v_or_b32_e32 v90, 24, v167
	v_add_f32_e32 v8, 1.0, v8
	v_add_f32_e32 v9, 1.0, v9
	v_rcp_f32_e32 v8, v8
	v_rcp_f32_e32 v9, v9
	s_nop 0
	v_mul_f32_e32 v6, v8, v6
	v_mul_f32_e32 v7, v9, v7
	s_waitcnt lgkmcnt(0)
; #define LAS __attribute__((address_space(3)))
; #define GAS __attribute__((address_space(1)))
; __device__ __forceinline__ float siluf(float x) { return x * __builtin_amdgcn_rcpf(1.f + __builtin_amdgcn_exp2f(-1.4426950408889634f * x)); }
; __device__ __forceinline__ float geluf(float x) { return x * __builtin_amdgcn_rcpf(1.f + __builtin_amdgcn_exp2f(x * (-0.10294324f * x * x - 2.3022082f))); }
; __device__ __forceinline__ unsigned cvtpk_h(float lo, float hi) { f32x2 v = {lo, hi}; h16x2 b = __builtin_convertvector(v, h16x2); return __builtin_bit_cast(unsigned, b); }
; __device__ __forceinline__ void gmlp_unit(unsigned char* ws, h16* Y, const h16* Ws16  , const float* bs  , size_t r0, LAS unsigned char* lds, int tid) {
;     ...
;         for (int ps = 0; ps < 4; ++ps) { const int row = 8 * ps + erow;
;             const h16x8 sv = *(const LAS h16x8*)(scr + row * 72 + 8 * ech);
;             float y[8];
; #pragma unroll
;             for (int k = 0; k < 8; ++k) y[k] = geluf((float)gu[q][ps][k]) * ((float)sv[k] + bias[q][ps]) * siluf((float)sz[q][ps][k]);
;             u32x4 w0; w0.x = cvtpk_h(y[0], y[1]); w0.y = cvtpk_h(y[2], y[3]); w0.z = cvtpk_h(y[4], y[5]); w0.w = cvtpk_h(y[6], y[7]);
;             *(GAS u32x4*)(Y + (r0 + 32 * (2 * ph + q) + row) * D + g * 64 + 8 * ech) = w0; }
	v_cvt_f32_f16_e32 v8, v2
	v_cvt_f32_f16_sdwa v9, v2 dst_sel:DWORD dst_unused:UNUSED_PAD src0_sel:WORD_1
	v_mul_f32_e32 v2, 0xbfb8aa3b, v11
	v_exp_f32_e32 v2, v2
	v_add_f32_e32 v8, v176, v8
	v_add_f32_e32 v9, v176, v9
	v_mul_f32_e32 v6, v6, v8
	v_mul_f32_e32 v7, v7, v9
	v_add_f32_e32 v2, 1.0, v2
	v_rcp_f32_e32 v13, v2
	s_nop 0
	v_mul_f32_e32 v8, v12, v10
	v_mul_f32_e32 v9, v13, v11
	s_nop 0
	v_mul_f32_e32 v6, v8, v6
	v_mul_f32_e32 v7, v9, v7
	v_cvt_f32_f16_e32 v8, v91
	v_cvt_f32_f16_sdwa v9, v91 dst_sel:DWORD dst_unused:UNUSED_PAD src0_sel:WORD_1
	v_cvt_f32_f16_e32 v12, v95
	v_cvt_f32_f16_sdwa v13, v95 dst_sel:DWORD dst_unused:UNUSED_PAD src0_sel:WORD_1
	v_mul_f32_e32 v2, 0x3dd2d3e8, v8
	v_mul_f32_e32 v11, 0x3dd2d3e8, v9
	v_fma_mix_f32 v2, -v2, v91, s9 op_sel_hi:[0,1,0]
	v_fma_mix_f32 v11, -v11, v91, s9 op_sel:[0,1,0] op_sel_hi:[0,1,0]
	v_mul_f32_e32 v2, v2, v8
	v_mul_f32_e32 v11, v11, v9
	v_exp_f32_e32 v2, v2
	v_exp_f32_e32 v11, v11
	v_add_f32_e32 v2, 1.0, v2
	v_add_f32_e32 v11, 1.0, v11
	v_rcp_f32_e32 v10, v2
	v_rcp_f32_e32 v11, v11
	v_mul_f32_e32 v2, 0xbfb8aa3b, v12
	v_exp_f32_e32 v2, v2
	v_mul_f32_e32 v8, v10, v8
	v_mul_f32_e32 v9, v11, v9
	v_cvt_f32_f16_e32 v10, v3
	v_cvt_f32_f16_sdwa v11, v3 dst_sel:DWORD dst_unused:UNUSED_PAD src0_sel:WORD_1
	v_mul_f32_e32 v3, 0xbfb8aa3b, v13
	v_exp_f32_e32 v3, v3
	v_add_f32_e32 v2, 1.0, v2
	v_rcp_f32_e32 v2, v2
	v_add_f32_e32 v10, v176, v10
	v_add_f32_e32 v11, v176, v11
	v_add_f32_e32 v3, 1.0, v3
	v_rcp_f32_e32 v3, v3
	v_mul_f32_e32 v8, v8, v10
	v_mul_f32_e32 v9, v9, v11
	v_mul_f32_e32 v2, v2, v12
	v_mul_f32_e32 v3, v3, v13
	v_cvt_f32_f16_e32 v12, v96
	v_mul_f32_e32 v8, v2, v8
	v_mul_f32_e32 v9, v3, v9
	v_cvt_f32_f16_e32 v2, v92
	v_cvt_f32_f16_sdwa v3, v92 dst_sel:DWORD dst_unused:UNUSED_PAD src0_sel:WORD_1
	v_mul_f32_e32 v11, 0xbfb8aa3b, v12
	v_exp_f32_e32 v11, v11
	v_mul_f32_e32 v10, 0x3dd2d3e8, v2
	v_fma_mix_f32 v10, -v10, v92, s9 op_sel_hi:[0,1,0]
	v_mul_f32_e32 v10, v10, v2
	v_add_f32_e32 v11, 1.0, v11
	v_rcp_f32_e32 v14, v11
	v_mul_f32_e32 v11, 0x3dd2d3e8, v3
	v_fma_mix_f32 v11, -v11, v92, s9 op_sel:[0,1,0] op_sel_hi:[0,1,0]
	v_mul_f32_e32 v11, v11, v3
	v_exp_f32_e32 v10, v10
	v_exp_f32_e32 v11, v11
	v_cvt_f32_f16_sdwa v13, v96 dst_sel:DWORD dst_unused:UNUSED_PAD src0_sel:WORD_1
	v_add_f32_e32 v10, 1.0, v10
	v_add_f32_e32 v11, 1.0, v11
	v_rcp_f32_e32 v10, v10
	v_rcp_f32_e32 v11, v11
	s_nop 0
	v_mul_f32_e32 v2, v10, v2
	v_mul_f32_e32 v3, v11, v3
	v_cvt_f32_f16_e32 v10, v4
	v_cvt_f32_f16_sdwa v11, v4 dst_sel:DWORD dst_unused:UNUSED_PAD src0_sel:WORD_1
	v_mul_f32_e32 v4, 0xbfb8aa3b, v13
	v_exp_f32_e32 v4, v4
	v_add_f32_e32 v10, v176, v10
	v_add_f32_e32 v11, v176, v11
	v_mul_f32_e32 v2, v2, v10
	v_mul_f32_e32 v3, v3, v11
	v_add_f32_e32 v4, 1.0, v4
	v_rcp_f32_e32 v15, v4
	s_nop 0
	v_mul_f32_e32 v10, v14, v12
	v_mul_f32_e32 v11, v15, v13
	s_nop 0
	v_mul_f32_e32 v10, v10, v2
	v_mul_f32_e32 v11, v11, v3
	v_cvt_f32_f16_e32 v2, v93
	v_cvt_f32_f16_sdwa v3, v93 dst_sel:DWORD dst_unused:UNUSED_PAD src0_sel:WORD_1
	v_cvt_f32_f16_e32 v14, v97
	v_cvt_f32_f16_sdwa v15, v97 dst_sel:DWORD dst_unused:UNUSED_PAD src0_sel:WORD_1
	v_mul_f32_e32 v4, 0x3dd2d3e8, v2
	v_mul_f32_e32 v13, 0x3dd2d3e8, v3
	v_fma_mix_f32 v4, -v4, v93, s9 op_sel_hi:[0,1,0]
	v_fma_mix_f32 v13, -v13, v93, s9 op_sel:[0,1,0] op_sel_hi:[0,1,0]
	v_mul_f32_e32 v4, v4, v2
	v_mul_f32_e32 v13, v13, v3
	v_exp_f32_e32 v4, v4
	v_exp_f32_e32 v13, v13
	v_add_f32_e32 v4, 1.0, v4
	v_add_f32_e32 v13, 1.0, v13
	v_rcp_f32_e32 v12, v4
	v_rcp_f32_e32 v13, v13
	v_mul_f32_e32 v4, 0xbfb8aa3b, v14
	v_exp_f32_e32 v4, v4
	v_mul_f32_e32 v2, v12, v2
	v_mul_f32_e32 v3, v13, v3
	v_cvt_f32_f16_e32 v12, v5
	v_cvt_f32_f16_sdwa v13, v5 dst_sel:DWORD dst_unused:UNUSED_PAD src0_sel:WORD_1
	v_mul_f32_e32 v5, 0xbfb8aa3b, v15
	v_exp_f32_e32 v5, v5
	v_add_f32_e32 v4, 1.0, v4
	v_rcp_f32_e32 v4, v4
	v_add_f32_e32 v12, v176, v12
	v_add_f32_e32 v13, v176, v13
	v_add_f32_e32 v5, 1.0, v5
	v_rcp_f32_e32 v5, v5
	v_mul_f32_e32 v2, v2, v12
	v_mul_f32_e32 v3, v3, v13
	v_mul_f32_e32 v4, v4, v14
	v_mul_f32_e32 v5, v5, v15
	s_nop 0
	v_mul_f32_e32 v12, v4, v2
	v_mul_f32_e32 v13, v5, v3
	v_cvt_pk_f16_f32 v4, v10, v11
	s_waitcnt vmcnt(14)
	v_cvt_f32_f16_e32 v10, v86
	v_cvt_pk_f16_f32 v2, v6, v7
	v_cvt_pk_f16_f32 v3, v8, v9
	v_lshlrev_b64 v[6:7], 11, v[164:165]
	v_mul_f32_e32 v9, 0xbfb8aa3b, v10
	v_cvt_pk_f16_f32 v5, v12, v13
	v_lshl_add_u64 v[6:7], v[148:149], 0, v[6:7]
	v_exp_f32_e32 v9, v9
	global_store_dwordx4 v[6:7], v[2:5], off sc1
	v_cvt_f32_f16_e32 v6, v82
	v_cvt_f32_f16_sdwa v7, v82 dst_sel:DWORD dst_unused:UNUSED_PAD src0_sel:WORD_1
	v_add_f32_e32 v9, 1.0, v9
	v_rcp_f32_e32 v12, v9
	v_mul_f32_e32 v8, 0x3dd2d3e8, v6
	v_mul_f32_e32 v9, 0x3dd2d3e8, v7
	v_fma_mix_f32 v8, -v8, v82, s9 op_sel_hi:[0,1,0]
	v_fma_mix_f32 v9, -v9, v82, s9 op_sel:[0,1,0] op_sel_hi:[0,1,0]
	v_mul_f32_e32 v8, v8, v6
	v_mul_f32_e32 v9, v9, v7
	v_exp_f32_e32 v8, v8
	v_exp_f32_e32 v9, v9
	ds_read_b128 v[2:5], v0 offset:3456
	v_cvt_f32_f16_sdwa v11, v86 dst_sel:DWORD dst_unused:UNUSED_PAD src0_sel:WORD_1
	v_add_f32_e32 v8, 1.0, v8
	v_add_f32_e32 v9, 1.0, v9
	v_rcp_f32_e32 v8, v8
	v_rcp_f32_e32 v9, v9
	v_or_b32_e32 v164, s4, v90
	v_mul_f32_e32 v6, v8, v6
	v_mul_f32_e32 v7, v9, v7
	s_waitcnt lgkmcnt(0)
; #define LAS __attribute__((address_space(3)))
; #define GAS __attribute__((address_space(1)))
; __device__ __forceinline__ float siluf(float x) { return x * __builtin_amdgcn_rcpf(1.f + __builtin_amdgcn_exp2f(-1.4426950408889634f * x)); }
; __device__ __forceinline__ float geluf(float x) { return x * __builtin_amdgcn_rcpf(1.f + __builtin_amdgcn_exp2f(x * (-0.10294324f * x * x - 2.3022082f))); }
; __device__ __forceinline__ unsigned cvtpk_h(float lo, float hi) { f32x2 v = {lo, hi}; h16x2 b = __builtin_convertvector(v, h16x2); return __builtin_bit_cast(unsigned, b); }
; __device__ __forceinline__ int crow(int r, int hi) { return (r & 3) + 8 * (r >> 2) + 4 * hi; }
; __device__ __forceinline__ void gmlp_unit(unsigned char* ws, h16* Y, const h16* Ws16  , const float* bs  , size_t r0, LAS unsigned char* lds, int tid) {
;     ...
;         for (int db = 0; db < 2; ++db) {
;             s16x8 bf[8];
; #pragma unroll
;             for (int ks = 0; ks < 8; ++ks) bf[ks] = tr_frag((LAS const char*)lds + g * 16384, 8192, db, ks, lane);
;             f32x16 acc = f32x16{};
; #pragma unroll
;             for (int ks = 0; ks < 8; ++ks) acc = __builtin_amdgcn_mfma_f32_32x32x16_f16(H8(af[q][ks]), H8(bf[ks]), acc, 0, 0, 0);
; #pragma unroll
;             for (int r = 0; r < 16; ++r) scr[crow(r, hi) * 72 + 32 * db + r32] = (h16)acc[r];
;     ...
;         for (int ps = 0; ps < 4; ++ps) { const int row = 8 * ps + erow;
;             const h16x8 sv = *(const LAS h16x8*)(scr + row * 72 + 8 * ech);
;             float y[8];
; #pragma unroll
;             for (int k = 0; k < 8; ++k) y[k] = geluf((float)gu[q][ps][k]) * ((float)sv[k] + bias[q][ps]) * siluf((float)sz[q][ps][k]);
;             u32x4 w0; w0.x = cvtpk_h(y[0], y[1]); w0.y = cvtpk_h(y[2], y[3]); w0.z = cvtpk_h(y[4], y[5]); w0.w = cvtpk_h(y[6], y[7]);
;             *(GAS u32x4*)(Y + (r0 + 32 * (2 * ph + q) + row) * D + g * 64 + 8 * ech) = w0; }
	v_cvt_f32_f16_e32 v8, v2
	v_cvt_f32_f16_sdwa v9, v2 dst_sel:DWORD dst_unused:UNUSED_PAD src0_sel:WORD_1
	v_mul_f32_e32 v2, 0xbfb8aa3b, v11
	v_exp_f32_e32 v2, v2
	v_add_f32_e32 v8, v174, v8
	v_add_f32_e32 v9, v174, v9
	v_mul_f32_e32 v6, v6, v8
	v_mul_f32_e32 v7, v7, v9
	v_add_f32_e32 v2, 1.0, v2
	v_rcp_f32_e32 v13, v2
	s_nop 0
	v_mul_f32_e32 v8, v12, v10
	v_mul_f32_e32 v9, v13, v11
	s_nop 0
	v_mul_f32_e32 v6, v8, v6
	v_mul_f32_e32 v7, v9, v7
	v_cvt_f32_f16_e32 v8, v83
	v_cvt_f32_f16_sdwa v9, v83 dst_sel:DWORD dst_unused:UNUSED_PAD src0_sel:WORD_1
	v_cvt_f32_f16_e32 v12, v87
	v_cvt_f32_f16_sdwa v13, v87 dst_sel:DWORD dst_unused:UNUSED_PAD src0_sel:WORD_1
	v_mul_f32_e32 v2, 0x3dd2d3e8, v8
	v_mul_f32_e32 v11, 0x3dd2d3e8, v9
	v_fma_mix_f32 v2, -v2, v83, s9 op_sel_hi:[0,1,0]
	v_fma_mix_f32 v11, -v11, v83, s9 op_sel:[0,1,0] op_sel_hi:[0,1,0]
	v_mul_f32_e32 v2, v2, v8
	v_mul_f32_e32 v11, v11, v9
	v_exp_f32_e32 v2, v2
	v_exp_f32_e32 v11, v11
	v_add_f32_e32 v2, 1.0, v2
	v_add_f32_e32 v11, 1.0, v11
	v_rcp_f32_e32 v10, v2
	v_rcp_f32_e32 v11, v11
	v_mul_f32_e32 v2, 0xbfb8aa3b, v12
	v_exp_f32_e32 v2, v2
	v_mul_f32_e32 v8, v10, v8
	v_mul_f32_e32 v9, v11, v9
	v_cvt_f32_f16_e32 v10, v3
	v_cvt_f32_f16_sdwa v11, v3 dst_sel:DWORD dst_unused:UNUSED_PAD src0_sel:WORD_1
	v_mul_f32_e32 v3, 0xbfb8aa3b, v13
	v_exp_f32_e32 v3, v3
	v_add_f32_e32 v2, 1.0, v2
	v_rcp_f32_e32 v2, v2
	v_add_f32_e32 v10, v174, v10
	v_add_f32_e32 v11, v174, v11
	v_add_f32_e32 v3, 1.0, v3
	v_rcp_f32_e32 v3, v3
	v_mul_f32_e32 v8, v8, v10
	v_mul_f32_e32 v9, v9, v11
	v_mul_f32_e32 v2, v2, v12
	v_mul_f32_e32 v3, v3, v13
	v_cvt_f32_f16_e32 v12, v88
	v_mul_f32_e32 v2, v2, v8
	v_mul_f32_e32 v3, v3, v9
	v_cvt_f32_f16_e32 v8, v84
	v_cvt_f32_f16_sdwa v9, v84 dst_sel:DWORD dst_unused:UNUSED_PAD src0_sel:WORD_1
	v_mul_f32_e32 v11, 0xbfb8aa3b, v12
	v_exp_f32_e32 v11, v11
	v_mul_f32_e32 v10, 0x3dd2d3e8, v8
	v_fma_mix_f32 v10, -v10, v84, s9 op_sel_hi:[0,1,0]
	v_mul_f32_e32 v10, v10, v8
	v_add_f32_e32 v11, 1.0, v11
	v_rcp_f32_e32 v14, v11
	v_mul_f32_e32 v11, 0x3dd2d3e8, v9
	v_fma_mix_f32 v11, -v11, v84, s9 op_sel:[0,1,0] op_sel_hi:[0,1,0]
	v_mul_f32_e32 v11, v11, v9
	v_exp_f32_e32 v10, v10
	v_exp_f32_e32 v11, v11
	v_cvt_f32_f16_sdwa v13, v88 dst_sel:DWORD dst_unused:UNUSED_PAD src0_sel:WORD_1
	v_add_f32_e32 v10, 1.0, v10
	v_add_f32_e32 v11, 1.0, v11
	v_rcp_f32_e32 v10, v10
	v_rcp_f32_e32 v11, v11
	s_nop 0
	v_mul_f32_e32 v8, v10, v8
	v_mul_f32_e32 v9, v11, v9
	v_cvt_f32_f16_e32 v10, v4
	v_cvt_f32_f16_sdwa v11, v4 dst_sel:DWORD dst_unused:UNUSED_PAD src0_sel:WORD_1
	v_mul_f32_e32 v4, 0xbfb8aa3b, v13
	v_exp_f32_e32 v4, v4
	v_add_f32_e32 v10, v174, v10
	v_add_f32_e32 v11, v174, v11
	v_mul_f32_e32 v8, v8, v10
	v_mul_f32_e32 v9, v9, v11
	v_add_f32_e32 v4, 1.0, v4
	v_rcp_f32_e32 v15, v4
	s_nop 0
	v_mul_f32_e32 v10, v14, v12
	v_mul_f32_e32 v11, v15, v13
	s_nop 0
	v_mul_f32_e32 v8, v10, v8
	v_mul_f32_e32 v9, v11, v9
	v_cvt_f32_f16_e32 v10, v85
	v_cvt_f32_f16_sdwa v11, v85 dst_sel:DWORD dst_unused:UNUSED_PAD src0_sel:WORD_1
	v_cvt_f32_f16_e32 v14, v89
	v_cvt_f32_f16_sdwa v15, v89 dst_sel:DWORD dst_unused:UNUSED_PAD src0_sel:WORD_1
	v_mul_f32_e32 v4, 0x3dd2d3e8, v10
	v_mul_f32_e32 v13, 0x3dd2d3e8, v11
	v_fma_mix_f32 v4, -v4, v85, s9 op_sel_hi:[0,1,0]
	v_fma_mix_f32 v13, -v13, v85, s9 op_sel:[0,1,0] op_sel_hi:[0,1,0]
	v_mul_f32_e32 v4, v4, v10
	v_mul_f32_e32 v13, v13, v11
	v_exp_f32_e32 v4, v4
	v_exp_f32_e32 v13, v13
	v_add_f32_e32 v4, 1.0, v4
	v_add_f32_e32 v13, 1.0, v13
	v_rcp_f32_e32 v12, v4
	v_rcp_f32_e32 v13, v13
	v_mul_f32_e32 v4, 0xbfb8aa3b, v14
	v_exp_f32_e32 v4, v4
	v_mul_f32_e32 v10, v12, v10
	v_mul_f32_e32 v11, v13, v11
	v_cvt_f32_f16_e32 v12, v5
	v_cvt_f32_f16_sdwa v13, v5 dst_sel:DWORD dst_unused:UNUSED_PAD src0_sel:WORD_1
	v_mul_f32_e32 v5, 0xbfb8aa3b, v15
	v_exp_f32_e32 v5, v5
	v_add_f32_e32 v4, 1.0, v4
	v_rcp_f32_e32 v4, v4
	v_add_f32_e32 v12, v174, v12
	v_add_f32_e32 v13, v174, v13
	v_add_f32_e32 v5, 1.0, v5
	v_rcp_f32_e32 v5, v5
	v_mul_f32_e32 v10, v10, v12
	v_mul_f32_e32 v11, v11, v13
	v_mul_f32_e32 v4, v4, v14
	v_mul_f32_e32 v5, v5, v15
	s_nop 0
	v_mul_f32_e32 v10, v4, v10
	v_mul_f32_e32 v11, v5, v11
	v_cvt_pk_f16_f32 v5, v2, v3
	v_lshlrev_b64 v[2:3], 11, v[164:165]
	v_cvt_pk_f16_f32 v4, v6, v7
	v_cvt_pk_f16_f32 v6, v8, v9
	v_cvt_pk_f16_f32 v7, v10, v11
	v_lshl_add_u64 v[2:3], v[148:149], 0, v[2:3]
	global_store_dwordx4 v[2:3], v[4:7], off sc1
	s_waitcnt lgkmcnt(0)
	ds_read_b64_tr_b16 v[2:3], v151
	ds_read_b64_tr_b16 v[4:5], v151 offset:256
	ds_read_b64_tr_b16 v[82:83], v151 offset:1024
	ds_read_b64_tr_b16 v[84:85], v151 offset:1280
	ds_read_b64_tr_b16 v[86:87], v151 offset:2048
	ds_read_b64_tr_b16 v[88:89], v151 offset:2304
	ds_read_b64_tr_b16 v[92:93], v151 offset:3072
	ds_read_b64_tr_b16 v[94:95], v151 offset:3328
	ds_read_b64_tr_b16 v[100:101], v151 offset:4096
	ds_read_b64_tr_b16 v[102:103], v151 offset:4352
	ds_read_b64_tr_b16 v[108:109], v151 offset:5120
	ds_read_b64_tr_b16 v[110:111], v151 offset:5376
	ds_read_b64_tr_b16 v[112:113], v151 offset:6144
	ds_read_b64_tr_b16 v[114:115], v151 offset:6400
	ds_read_b64_tr_b16 v[116:117], v151 offset:7168
	ds_read_b64_tr_b16 v[118:119], v151 offset:7424
	s_waitcnt lgkmcnt(14)
	v_mfma_f32_32x32x16_f16 v[2:17], v[78:81], v[2:5], 0
	v_or_b32_e32 v164, s2, v167
	s_waitcnt lgkmcnt(12)
	v_mfma_f32_32x32x16_f16 v[2:17], v[74:77], v[82:85], v[2:17]
	s_waitcnt lgkmcnt(10)
	v_mfma_f32_32x32x16_f16 v[2:17], v[70:73], v[86:89], v[2:17]
	s_waitcnt lgkmcnt(8)
	v_mfma_f32_32x32x16_f16 v[2:17], v[66:69], v[92:95], v[2:17]
	s_waitcnt lgkmcnt(6)
	v_mfma_f32_32x32x16_f16 v[2:17], v[62:65], v[100:103], v[2:17]
	s_waitcnt lgkmcnt(4)
; #define LAS __attribute__((address_space(3)))
; #define GAS __attribute__((address_space(1)))
; __device__ __forceinline__ float siluf(float x) { return x * __builtin_amdgcn_rcpf(1.f + __builtin_amdgcn_exp2f(-1.4426950408889634f * x)); }
; __device__ __forceinline__ float geluf(float x) { return x * __builtin_amdgcn_rcpf(1.f + __builtin_amdgcn_exp2f(x * (-0.10294324f * x * x - 2.3022082f))); }
; __device__ __forceinline__ unsigned cvtpk_h(float lo, float hi) { f32x2 v = {lo, hi}; h16x2 b = __builtin_convertvector(v, h16x2); return __builtin_bit_cast(unsigned, b); }
; #define LDS_WAIT() asm volatile("s_waitcnt lgkmcnt(0)" ::: "memory")
; __device__ __forceinline__ int crow(int r, int hi) { return (r & 3) + 8 * (r >> 2) + 4 * hi; }
; __device__ __forceinline__ void gmlp_unit(unsigned char* ws, h16* Y, const h16* Ws16  , const float* bs  , size_t r0, LAS unsigned char* lds, int tid) {
;     ...
;         for (int db = 0; db < 2; ++db) {
;             s16x8 bf[8];
; #pragma unroll
;             for (int ks = 0; ks < 8; ++ks) bf[ks] = tr_frag((LAS const char*)lds + g * 16384, 8192, db, ks, lane);
;             f32x16 acc = f32x16{};
; #pragma unroll
;             for (int ks = 0; ks < 8; ++ks) acc = __builtin_amdgcn_mfma_f32_32x32x16_f16(H8(af[q][ks]), H8(bf[ks]), acc, 0, 0, 0);
; #pragma unroll
;             for (int r = 0; r < 16; ++r) scr[crow(r, hi) * 72 + 32 * db + r32] = (h16)acc[r];
;         }
;         LDS_WAIT();
; #pragma unroll
;         for (int ps = 0; ps < 4; ++ps) { const int row = 8 * ps + erow;
;             const h16x8 sv = *(const LAS h16x8*)(scr + row * 72 + 8 * ech);
;             float y[8];
; #pragma unroll
;             for (int k = 0; k < 8; ++k) y[k] = geluf((float)gu[q][ps][k]) * ((float)sv[k] + bias[q][ps]) * siluf((float)sz[q][ps][k]);
;             u32x4 w0; w0.x = cvtpk_h(y[0], y[1]); w0.y = cvtpk_h(y[2], y[3]); w0.z = cvtpk_h(y[4], y[5]); w0.w = cvtpk_h(y[6], y[7]);
;             *(GAS u32x4*)(Y + (r0 + 32 * (2 * ph + q) + row) * D + g * 64 + 8 * ech) = w0; }
	v_mfma_f32_32x32x16_f16 v[2:17], v[58:61], v[108:111], v[2:17]
	s_waitcnt lgkmcnt(2)
	v_mfma_f32_32x32x16_f16 v[2:17], v[54:57], v[112:115], v[2:17]
	s_waitcnt lgkmcnt(0)
	v_mfma_f32_32x32x16_f16 v[2:17], v[50:53], v[116:119], v[2:17]
	s_nop 11
	v_cvt_f16_f32_e32 v2, v2
	ds_write_b16 v150, v2
	v_cvt_f16_f32_e32 v2, v3
	ds_write_b16 v150, v2 offset:144
	v_cvt_f16_f32_e32 v2, v4
	ds_write_b16 v150, v2 offset:288
	v_cvt_f16_f32_e32 v2, v5
	ds_write_b16 v150, v2 offset:432
	v_cvt_f16_f32_e32 v2, v6
	ds_write_b16 v150, v2 offset:1152
	v_cvt_f16_f32_e32 v2, v7
	ds_write_b16 v150, v2 offset:1296
	v_cvt_f16_f32_e32 v2, v8
	ds_write_b16 v150, v2 offset:1440
	v_cvt_f16_f32_e32 v2, v9
	ds_write_b16 v150, v2 offset:1584
	v_cvt_f16_f32_e32 v2, v10
	ds_write_b16 v150, v2 offset:2304
	v_cvt_f16_f32_e32 v2, v11
	ds_write_b16 v150, v2 offset:2448
	v_cvt_f16_f32_e32 v2, v12
	ds_write_b16 v150, v2 offset:2592
	v_cvt_f16_f32_e32 v2, v13
	ds_write_b16 v150, v2 offset:2736
	v_cvt_f16_f32_e32 v2, v14
	ds_write_b16 v150, v2 offset:3456
	v_cvt_f16_f32_e32 v2, v15
	ds_write_b16 v150, v2 offset:3600
	v_cvt_f16_f32_e32 v2, v16
	ds_write_b16 v150, v2 offset:3744
	v_cvt_f16_f32_e32 v2, v17
	ds_write_b16 v150, v2 offset:3888
	ds_read_b64_tr_b16 v[2:3], v151 offset:8192
	ds_read_b64_tr_b16 v[4:5], v151 offset:8448
	ds_read_b64_tr_b16 v[82:83], v151 offset:9216
	ds_read_b64_tr_b16 v[84:85], v151 offset:9472
	ds_read_b64_tr_b16 v[86:87], v151 offset:10240
	ds_read_b64_tr_b16 v[88:89], v151 offset:10496
	ds_read_b64_tr_b16 v[92:93], v151 offset:11264
	ds_read_b64_tr_b16 v[94:95], v151 offset:11520
	ds_read_b64_tr_b16 v[100:101], v151 offset:12288
	ds_read_b64_tr_b16 v[102:103], v151 offset:12544
	ds_read_b64_tr_b16 v[108:109], v151 offset:13312
	ds_read_b64_tr_b16 v[110:111], v151 offset:13568
	ds_read_b64_tr_b16 v[112:113], v151 offset:14336
	ds_read_b64_tr_b16 v[114:115], v151 offset:14592
	ds_read_b64_tr_b16 v[116:117], v151 offset:15360
	ds_read_b64_tr_b16 v[118:119], v151 offset:15616
	s_waitcnt lgkmcnt(14)
	v_mfma_f32_32x32x16_f16 v[2:17], v[78:81], v[2:5], 0
	s_waitcnt lgkmcnt(12)
	v_mfma_f32_32x32x16_f16 v[2:17], v[74:77], v[82:85], v[2:17]
	s_waitcnt lgkmcnt(10)
	v_mfma_f32_32x32x16_f16 v[2:17], v[70:73], v[86:89], v[2:17]
	s_waitcnt lgkmcnt(8)
	v_mfma_f32_32x32x16_f16 v[2:17], v[66:69], v[92:95], v[2:17]
	s_waitcnt lgkmcnt(6)
	v_mfma_f32_32x32x16_f16 v[2:17], v[62:65], v[100:103], v[2:17]
	s_waitcnt lgkmcnt(4)
	v_mfma_f32_32x32x16_f16 v[2:17], v[58:61], v[108:111], v[2:17]
	s_waitcnt lgkmcnt(2)
	v_mfma_f32_32x32x16_f16 v[2:17], v[54:57], v[112:115], v[2:17]
	s_waitcnt lgkmcnt(0)
	v_mfma_f32_32x32x16_f16 v[2:17], v[50:53], v[116:119], v[2:17]
	s_nop 11
	v_cvt_f16_f32_e32 v2, v2
	ds_write_b16 v150, v2 offset:64
	v_cvt_f16_f32_e32 v2, v3
	ds_write_b16 v150, v2 offset:208
	v_cvt_f16_f32_e32 v2, v4
	ds_write_b16 v150, v2 offset:352
	v_cvt_f16_f32_e32 v2, v5
	ds_write_b16 v150, v2 offset:496
	v_cvt_f16_f32_e32 v2, v6
	s_waitcnt vmcnt(15)
	v_cvt_f32_f16_e32 v6, v42
	ds_write_b16 v150, v2 offset:1216
	v_cvt_f16_f32_e32 v2, v7
	v_cvt_f32_f16_sdwa v7, v42 dst_sel:DWORD dst_unused:UNUSED_PAD src0_sel:WORD_1
	ds_write_b16 v150, v2 offset:1360
	v_cvt_f16_f32_e32 v2, v8
	v_mul_f32_e32 v8, 0x3dd2d3e8, v6
	v_fma_mix_f32 v8, -v8, v42, s9 op_sel_hi:[0,1,0]
	v_mul_f32_e32 v8, v8, v6
	ds_write_b16 v150, v2 offset:1504
	v_cvt_f16_f32_e32 v2, v9
	v_exp_f32_e32 v8, v8
	ds_write_b16 v150, v2 offset:1648
	v_cvt_f16_f32_e32 v2, v10
	s_waitcnt vmcnt(13)
	v_cvt_f32_f16_e32 v10, v46
	v_add_f32_e32 v8, 1.0, v8
	v_rcp_f32_e32 v8, v8
	ds_write_b16 v150, v2 offset:2368
	v_cvt_f16_f32_e32 v2, v11
	v_mul_f32_e32 v9, 0xbfb8aa3b, v10
	v_exp_f32_e32 v9, v9
	v_cvt_f32_f16_sdwa v11, v46 dst_sel:DWORD dst_unused:UNUSED_PAD src0_sel:WORD_1
	ds_write_b16 v150, v2 offset:2512
	v_cvt_f16_f32_e32 v2, v12
	v_add_f32_e32 v9, 1.0, v9
	v_rcp_f32_e32 v12, v9
	v_mul_f32_e32 v9, 0x3dd2d3e8, v7
	ds_write_b16 v150, v2 offset:2656
	v_cvt_f16_f32_e32 v2, v13
	v_fma_mix_f32 v9, -v9, v42, s9 op_sel:[0,1,0] op_sel_hi:[0,1,0]
	v_mul_f32_e32 v9, v9, v7
	v_exp_f32_e32 v9, v9
	ds_write_b16 v150, v2 offset:2800
	v_cvt_f16_f32_e32 v2, v14
	v_add_f32_e32 v9, 1.0, v9
	v_rcp_f32_e32 v9, v9
	ds_write_b16 v150, v2 offset:3520
	v_cvt_f16_f32_e32 v2, v15
	v_mul_f32_e32 v6, v8, v6
	v_mul_f32_e32 v7, v9, v7
	ds_write_b16 v150, v2 offset:3664
	v_cvt_f16_f32_e32 v2, v16
	ds_write_b16 v150, v2 offset:3808
	v_cvt_f16_f32_e32 v2, v17
	ds_write_b16 v150, v2 offset:3952
	s_waitcnt lgkmcnt(0)
	ds_read_b128 v[2:5], v0
	s_waitcnt lgkmcnt(0)
; #define LAS __attribute__((address_space(3)))
; #define GAS __attribute__((address_space(1)))
; __device__ __forceinline__ float siluf(float x) { return x * __builtin_amdgcn_rcpf(1.f + __builtin_amdgcn_exp2f(-1.4426950408889634f * x)); }
; __device__ __forceinline__ float geluf(float x) { return x * __builtin_amdgcn_rcpf(1.f + __builtin_amdgcn_exp2f(x * (-0.10294324f * x * x - 2.3022082f))); }
; __device__ __forceinline__ unsigned cvtpk_h(float lo, float hi) { f32x2 v = {lo, hi}; h16x2 b = __builtin_convertvector(v, h16x2); return __builtin_bit_cast(unsigned, b); }
; __device__ __forceinline__ void gmlp_unit(unsigned char* ws, h16* Y, const h16* Ws16  , const float* bs  , size_t r0, LAS unsigned char* lds, int tid) {
;     ...
;         for (int ps = 0; ps < 4; ++ps) { const int row = 8 * ps + erow;
;             const h16x8 sv = *(const LAS h16x8*)(scr + row * 72 + 8 * ech);
;             float y[8];
; #pragma unroll
;             for (int k = 0; k < 8; ++k) y[k] = geluf((float)gu[q][ps][k]) * ((float)sv[k] + bias[q][ps]) * siluf((float)sz[q][ps][k]);
;             u32x4 w0; w0.x = cvtpk_h(y[0], y[1]); w0.y = cvtpk_h(y[2], y[3]); w0.z = cvtpk_h(y[4], y[5]); w0.w = cvtpk_h(y[6], y[7]);
;             *(GAS u32x4*)(Y + (r0 + 32 * (2 * ph + q) + row) * D + g * 64 + 8 * ech) = w0; }
	v_cvt_f32_f16_e32 v8, v2
	v_cvt_f32_f16_sdwa v9, v2 dst_sel:DWORD dst_unused:UNUSED_PAD src0_sel:WORD_1
	v_mul_f32_e32 v2, 0xbfb8aa3b, v11
	v_exp_f32_e32 v2, v2
	v_add_f32_e32 v8, v172, v8
	v_add_f32_e32 v9, v172, v9
	v_mul_f32_e32 v6, v6, v8
	v_mul_f32_e32 v7, v7, v9
	v_add_f32_e32 v2, 1.0, v2
	v_rcp_f32_e32 v13, v2
	s_nop 0
	v_mul_f32_e32 v8, v12, v10
	v_mul_f32_e32 v9, v13, v11
	s_nop 0
	v_mul_f32_e32 v6, v8, v6
	v_mul_f32_e32 v7, v9, v7
	v_cvt_f32_f16_e32 v8, v43
	v_cvt_f32_f16_sdwa v9, v43 dst_sel:DWORD dst_unused:UNUSED_PAD src0_sel:WORD_1
	v_cvt_f32_f16_e32 v12, v47
	v_cvt_f32_f16_sdwa v13, v47 dst_sel:DWORD dst_unused:UNUSED_PAD src0_sel:WORD_1
	v_mul_f32_e32 v2, 0x3dd2d3e8, v8
	v_mul_f32_e32 v11, 0x3dd2d3e8, v9
	v_fma_mix_f32 v2, -v2, v43, s9 op_sel_hi:[0,1,0]
	v_fma_mix_f32 v11, -v11, v43, s9 op_sel:[0,1,0] op_sel_hi:[0,1,0]
	v_mul_f32_e32 v2, v2, v8
	v_mul_f32_e32 v11, v11, v9
	v_exp_f32_e32 v2, v2
	v_exp_f32_e32 v11, v11
	v_add_f32_e32 v2, 1.0, v2
	v_add_f32_e32 v11, 1.0, v11
	v_rcp_f32_e32 v10, v2
	v_rcp_f32_e32 v11, v11
	v_mul_f32_e32 v2, 0xbfb8aa3b, v12
	v_exp_f32_e32 v2, v2
	v_mul_f32_e32 v8, v10, v8
	v_mul_f32_e32 v9, v11, v9
	v_cvt_f32_f16_e32 v10, v3
	v_cvt_f32_f16_sdwa v11, v3 dst_sel:DWORD dst_unused:UNUSED_PAD src0_sel:WORD_1
	v_mul_f32_e32 v3, 0xbfb8aa3b, v13
	v_exp_f32_e32 v3, v3
	v_add_f32_e32 v2, 1.0, v2
	v_rcp_f32_e32 v2, v2
	v_add_f32_e32 v10, v172, v10
	v_add_f32_e32 v11, v172, v11
	v_add_f32_e32 v3, 1.0, v3
	v_rcp_f32_e32 v3, v3
	v_mul_f32_e32 v8, v8, v10
	v_mul_f32_e32 v9, v9, v11
	v_mul_f32_e32 v2, v2, v12
	v_mul_f32_e32 v3, v3, v13
	v_cvt_f32_f16_e32 v12, v48
	v_mul_f32_e32 v8, v2, v8
	v_mul_f32_e32 v9, v3, v9
	v_cvt_f32_f16_e32 v2, v44
	v_cvt_f32_f16_sdwa v3, v44 dst_sel:DWORD dst_unused:UNUSED_PAD src0_sel:WORD_1
	v_mul_f32_e32 v11, 0xbfb8aa3b, v12
	v_exp_f32_e32 v11, v11
	v_mul_f32_e32 v10, 0x3dd2d3e8, v2
	v_fma_mix_f32 v10, -v10, v44, s9 op_sel_hi:[0,1,0]
	v_mul_f32_e32 v10, v10, v2
	v_add_f32_e32 v11, 1.0, v11
	v_rcp_f32_e32 v14, v11
	v_mul_f32_e32 v11, 0x3dd2d3e8, v3
	v_fma_mix_f32 v11, -v11, v44, s9 op_sel:[0,1,0] op_sel_hi:[0,1,0]
	v_mul_f32_e32 v11, v11, v3
	v_exp_f32_e32 v10, v10
	v_exp_f32_e32 v11, v11
	v_cvt_f32_f16_sdwa v13, v48 dst_sel:DWORD dst_unused:UNUSED_PAD src0_sel:WORD_1
	v_add_f32_e32 v10, 1.0, v10
	v_add_f32_e32 v11, 1.0, v11
	v_rcp_f32_e32 v10, v10
	v_rcp_f32_e32 v11, v11
	s_nop 0
	v_mul_f32_e32 v2, v10, v2
	v_mul_f32_e32 v3, v11, v3
	v_cvt_f32_f16_e32 v10, v4
	v_cvt_f32_f16_sdwa v11, v4 dst_sel:DWORD dst_unused:UNUSED_PAD src0_sel:WORD_1
	v_mul_f32_e32 v4, 0xbfb8aa3b, v13
	v_exp_f32_e32 v4, v4
	v_add_f32_e32 v10, v172, v10
	v_add_f32_e32 v11, v172, v11
	v_mul_f32_e32 v2, v2, v10
	v_mul_f32_e32 v3, v3, v11
	v_add_f32_e32 v4, 1.0, v4
	v_rcp_f32_e32 v15, v4
	s_nop 0
	v_mul_f32_e32 v10, v14, v12
	v_mul_f32_e32 v11, v15, v13
	s_nop 0
	v_mul_f32_e32 v10, v10, v2
	v_mul_f32_e32 v11, v11, v3
	v_cvt_f32_f16_e32 v2, v45
	v_cvt_f32_f16_sdwa v3, v45 dst_sel:DWORD dst_unused:UNUSED_PAD src0_sel:WORD_1
	v_cvt_f32_f16_e32 v14, v49
	v_cvt_f32_f16_sdwa v15, v49 dst_sel:DWORD dst_unused:UNUSED_PAD src0_sel:WORD_1
	v_mul_f32_e32 v4, 0x3dd2d3e8, v2
	v_mul_f32_e32 v13, 0x3dd2d3e8, v3
	v_fma_mix_f32 v4, -v4, v45, s9 op_sel_hi:[0,1,0]
	v_fma_mix_f32 v13, -v13, v45, s9 op_sel:[0,1,0] op_sel_hi:[0,1,0]
	v_mul_f32_e32 v4, v4, v2
	v_mul_f32_e32 v13, v13, v3
	v_exp_f32_e32 v4, v4
	v_exp_f32_e32 v13, v13
	v_add_f32_e32 v4, 1.0, v4
	v_add_f32_e32 v13, 1.0, v13
	v_rcp_f32_e32 v12, v4
	v_rcp_f32_e32 v13, v13
	v_mul_f32_e32 v4, 0xbfb8aa3b, v14
	v_exp_f32_e32 v4, v4
	v_mul_f32_e32 v2, v12, v2
	v_mul_f32_e32 v3, v13, v3
	v_cvt_f32_f16_e32 v12, v5
	v_cvt_f32_f16_sdwa v13, v5 dst_sel:DWORD dst_unused:UNUSED_PAD src0_sel:WORD_1
	v_mul_f32_e32 v5, 0xbfb8aa3b, v15
	v_exp_f32_e32 v5, v5
	v_add_f32_e32 v4, 1.0, v4
	v_rcp_f32_e32 v4, v4
	v_add_f32_e32 v12, v172, v12
	v_add_f32_e32 v13, v172, v13
	v_add_f32_e32 v5, 1.0, v5
	v_rcp_f32_e32 v5, v5
	v_mul_f32_e32 v2, v2, v12
	v_mul_f32_e32 v3, v3, v13
	v_mul_f32_e32 v4, v4, v14
	v_mul_f32_e32 v5, v5, v15
	s_nop 0
	v_mul_f32_e32 v12, v4, v2
	v_mul_f32_e32 v13, v5, v3
	v_cvt_pk_f16_f32 v4, v10, v11
	s_waitcnt vmcnt(10)
	v_cvt_f32_f16_e32 v10, v38
	v_cvt_pk_f16_f32 v2, v6, v7
	v_cvt_pk_f16_f32 v3, v8, v9
	v_lshlrev_b64 v[6:7], 11, v[164:165]
	v_mul_f32_e32 v9, 0xbfb8aa3b, v10
	v_cvt_pk_f16_f32 v5, v12, v13
	v_lshl_add_u64 v[6:7], v[148:149], 0, v[6:7]
	v_exp_f32_e32 v9, v9
	global_store_dwordx4 v[6:7], v[2:5], off sc1
	v_cvt_f32_f16_e32 v6, v34
	v_cvt_f32_f16_sdwa v7, v34 dst_sel:DWORD dst_unused:UNUSED_PAD src0_sel:WORD_1
	v_add_f32_e32 v9, 1.0, v9
	v_rcp_f32_e32 v12, v9
	v_mul_f32_e32 v8, 0x3dd2d3e8, v6
	v_mul_f32_e32 v9, 0x3dd2d3e8, v7
	v_fma_mix_f32 v8, -v8, v34, s9 op_sel_hi:[0,1,0]
	v_fma_mix_f32 v9, -v9, v34, s9 op_sel:[0,1,0] op_sel_hi:[0,1,0]
	v_mul_f32_e32 v8, v8, v6
	v_mul_f32_e32 v9, v9, v7
	v_exp_f32_e32 v8, v8
	v_exp_f32_e32 v9, v9
	ds_read_b128 v[2:5], v0 offset:1152
	v_cvt_f32_f16_sdwa v11, v38 dst_sel:DWORD dst_unused:UNUSED_PAD src0_sel:WORD_1
	v_add_f32_e32 v8, 1.0, v8
	v_add_f32_e32 v9, 1.0, v9
	v_rcp_f32_e32 v8, v8
	v_rcp_f32_e32 v9, v9
	v_or_b32_e32 v164, s2, v106
	v_mul_f32_e32 v6, v8, v6
	v_mul_f32_e32 v7, v9, v7
	s_waitcnt lgkmcnt(0)
; #define LAS __attribute__((address_space(3)))
; #define GAS __attribute__((address_space(1)))
; __device__ __forceinline__ float siluf(float x) { return x * __builtin_amdgcn_rcpf(1.f + __builtin_amdgcn_exp2f(-1.4426950408889634f * x)); }
; __device__ __forceinline__ float geluf(float x) { return x * __builtin_amdgcn_rcpf(1.f + __builtin_amdgcn_exp2f(x * (-0.10294324f * x * x - 2.3022082f))); }
; __device__ __forceinline__ unsigned cvtpk_h(float lo, float hi) { f32x2 v = {lo, hi}; h16x2 b = __builtin_convertvector(v, h16x2); return __builtin_bit_cast(unsigned, b); }
; __device__ __forceinline__ void gmlp_unit(unsigned char* ws, h16* Y, const h16* Ws16  , const float* bs  , size_t r0, LAS unsigned char* lds, int tid) {
;     ...
;         for (int ps = 0; ps < 4; ++ps) { const int row = 8 * ps + erow;
;             const h16x8 sv = *(const LAS h16x8*)(scr + row * 72 + 8 * ech);
;             float y[8];
; #pragma unroll
;             for (int k = 0; k < 8; ++k) y[k] = geluf((float)gu[q][ps][k]) * ((float)sv[k] + bias[q][ps]) * siluf((float)sz[q][ps][k]);
;             u32x4 w0; w0.x = cvtpk_h(y[0], y[1]); w0.y = cvtpk_h(y[2], y[3]); w0.z = cvtpk_h(y[4], y[5]); w0.w = cvtpk_h(y[6], y[7]);
;             *(GAS u32x4*)(Y + (r0 + 32 * (2 * ph + q) + row) * D + g * 64 + 8 * ech) = w0; }
	v_cvt_f32_f16_e32 v8, v2
	v_cvt_f32_f16_sdwa v9, v2 dst_sel:DWORD dst_unused:UNUSED_PAD src0_sel:WORD_1
	v_mul_f32_e32 v2, 0xbfb8aa3b, v11
	v_exp_f32_e32 v2, v2
	v_add_f32_e32 v8, v170, v8
	v_add_f32_e32 v9, v170, v9
	v_mul_f32_e32 v6, v6, v8
	v_mul_f32_e32 v7, v7, v9
	v_add_f32_e32 v2, 1.0, v2
	v_rcp_f32_e32 v13, v2
	s_nop 0
	v_mul_f32_e32 v8, v12, v10
	v_mul_f32_e32 v9, v13, v11
	s_nop 0
	v_mul_f32_e32 v6, v8, v6
	v_mul_f32_e32 v7, v9, v7
	v_cvt_f32_f16_e32 v8, v35
	v_cvt_f32_f16_sdwa v9, v35 dst_sel:DWORD dst_unused:UNUSED_PAD src0_sel:WORD_1
	v_cvt_f32_f16_e32 v12, v39
	v_cvt_f32_f16_sdwa v13, v39 dst_sel:DWORD dst_unused:UNUSED_PAD src0_sel:WORD_1
	v_mul_f32_e32 v2, 0x3dd2d3e8, v8
	v_mul_f32_e32 v11, 0x3dd2d3e8, v9
	v_fma_mix_f32 v2, -v2, v35, s9 op_sel_hi:[0,1,0]
	v_fma_mix_f32 v11, -v11, v35, s9 op_sel:[0,1,0] op_sel_hi:[0,1,0]
	v_mul_f32_e32 v2, v2, v8
	v_mul_f32_e32 v11, v11, v9
	v_exp_f32_e32 v2, v2
	v_exp_f32_e32 v11, v11
	v_add_f32_e32 v2, 1.0, v2
	v_add_f32_e32 v11, 1.0, v11
	v_rcp_f32_e32 v10, v2
	v_rcp_f32_e32 v11, v11
	v_mul_f32_e32 v2, 0xbfb8aa3b, v12
	v_exp_f32_e32 v2, v2
	v_mul_f32_e32 v8, v10, v8
	v_mul_f32_e32 v9, v11, v9
	v_cvt_f32_f16_e32 v10, v3
	v_cvt_f32_f16_sdwa v11, v3 dst_sel:DWORD dst_unused:UNUSED_PAD src0_sel:WORD_1
	v_mul_f32_e32 v3, 0xbfb8aa3b, v13
	v_exp_f32_e32 v3, v3
	v_add_f32_e32 v2, 1.0, v2
	v_rcp_f32_e32 v2, v2
	v_add_f32_e32 v10, v170, v10
	v_add_f32_e32 v11, v170, v11
	v_add_f32_e32 v3, 1.0, v3
	v_rcp_f32_e32 v3, v3
	v_mul_f32_e32 v8, v8, v10
	v_mul_f32_e32 v9, v9, v11
	v_mul_f32_e32 v2, v2, v12
	v_mul_f32_e32 v3, v3, v13
	v_cvt_f32_f16_e32 v12, v40
	v_mul_f32_e32 v2, v2, v8
	v_mul_f32_e32 v3, v3, v9
	v_cvt_f32_f16_e32 v8, v36
	v_cvt_f32_f16_sdwa v9, v36 dst_sel:DWORD dst_unused:UNUSED_PAD src0_sel:WORD_1
	v_mul_f32_e32 v11, 0xbfb8aa3b, v12
	v_exp_f32_e32 v11, v11
	v_mul_f32_e32 v10, 0x3dd2d3e8, v8
	v_fma_mix_f32 v10, -v10, v36, s9 op_sel_hi:[0,1,0]
	v_mul_f32_e32 v10, v10, v8
	v_add_f32_e32 v11, 1.0, v11
	v_rcp_f32_e32 v14, v11
	v_mul_f32_e32 v11, 0x3dd2d3e8, v9
	v_fma_mix_f32 v11, -v11, v36, s9 op_sel:[0,1,0] op_sel_hi:[0,1,0]
	v_mul_f32_e32 v11, v11, v9
	v_exp_f32_e32 v10, v10
	v_exp_f32_e32 v11, v11
	v_cvt_f32_f16_sdwa v13, v40 dst_sel:DWORD dst_unused:UNUSED_PAD src0_sel:WORD_1
	v_add_f32_e32 v10, 1.0, v10
	v_add_f32_e32 v11, 1.0, v11
	v_rcp_f32_e32 v10, v10
	v_rcp_f32_e32 v11, v11
	s_nop 0
	v_mul_f32_e32 v8, v10, v8
	v_mul_f32_e32 v9, v11, v9
	v_cvt_f32_f16_e32 v10, v4
	v_cvt_f32_f16_sdwa v11, v4 dst_sel:DWORD dst_unused:UNUSED_PAD src0_sel:WORD_1
	v_mul_f32_e32 v4, 0xbfb8aa3b, v13
	v_exp_f32_e32 v4, v4
	v_add_f32_e32 v10, v170, v10
	v_add_f32_e32 v11, v170, v11
	v_mul_f32_e32 v8, v8, v10
	v_mul_f32_e32 v9, v9, v11
	v_add_f32_e32 v4, 1.0, v4
	v_rcp_f32_e32 v15, v4
	s_nop 0
	v_mul_f32_e32 v10, v14, v12
	v_mul_f32_e32 v11, v15, v13
	s_nop 0
	v_mul_f32_e32 v8, v10, v8
	v_mul_f32_e32 v9, v11, v9
	v_cvt_f32_f16_e32 v10, v37
	v_cvt_f32_f16_sdwa v11, v37 dst_sel:DWORD dst_unused:UNUSED_PAD src0_sel:WORD_1
	v_cvt_f32_f16_e32 v14, v41
	v_cvt_f32_f16_sdwa v15, v41 dst_sel:DWORD dst_unused:UNUSED_PAD src0_sel:WORD_1
	v_mul_f32_e32 v4, 0x3dd2d3e8, v10
	v_mul_f32_e32 v13, 0x3dd2d3e8, v11
	v_fma_mix_f32 v4, -v4, v37, s9 op_sel_hi:[0,1,0]
	v_fma_mix_f32 v13, -v13, v37, s9 op_sel:[0,1,0] op_sel_hi:[0,1,0]
	v_mul_f32_e32 v4, v4, v10
	v_mul_f32_e32 v13, v13, v11
	v_exp_f32_e32 v4, v4
	v_exp_f32_e32 v13, v13
	v_add_f32_e32 v4, 1.0, v4
	v_add_f32_e32 v13, 1.0, v13
	v_rcp_f32_e32 v12, v4
	v_rcp_f32_e32 v13, v13
	v_mul_f32_e32 v4, 0xbfb8aa3b, v14
	v_exp_f32_e32 v4, v4
	v_mul_f32_e32 v10, v12, v10
	v_mul_f32_e32 v11, v13, v11
	v_cvt_f32_f16_e32 v12, v5
	v_cvt_f32_f16_sdwa v13, v5 dst_sel:DWORD dst_unused:UNUSED_PAD src0_sel:WORD_1
	v_mul_f32_e32 v5, 0xbfb8aa3b, v15
	v_exp_f32_e32 v5, v5
	v_add_f32_e32 v4, 1.0, v4
	v_rcp_f32_e32 v4, v4
	v_add_f32_e32 v12, v170, v12
	v_add_f32_e32 v13, v170, v13
	v_add_f32_e32 v5, 1.0, v5
	v_rcp_f32_e32 v5, v5
	v_mul_f32_e32 v10, v10, v12
	v_mul_f32_e32 v11, v11, v13
	v_mul_f32_e32 v4, v4, v14
	v_mul_f32_e32 v5, v5, v15
	s_nop 0
	v_mul_f32_e32 v10, v4, v10
	v_mul_f32_e32 v11, v5, v11
	v_cvt_pk_f16_f32 v4, v6, v7
	v_cvt_pk_f16_f32 v7, v10, v11
	s_waitcnt vmcnt(8)
	v_cvt_f32_f16_e32 v10, v30
	v_cvt_pk_f16_f32 v5, v2, v3
	v_cvt_pk_f16_f32 v6, v8, v9
	v_lshlrev_b64 v[2:3], 11, v[164:165]
	v_mul_f32_e32 v9, 0xbfb8aa3b, v10
	v_lshl_add_u64 v[2:3], v[148:149], 0, v[2:3]
	v_exp_f32_e32 v9, v9
	global_store_dwordx4 v[2:3], v[4:7], off sc1
	ds_read_b128 v[2:5], v0 offset:2304
	v_cvt_f32_f16_sdwa v11, v30 dst_sel:DWORD dst_unused:UNUSED_PAD src0_sel:WORD_1
	v_cvt_f32_f16_e32 v6, v26
	v_cvt_f32_f16_sdwa v7, v26 dst_sel:DWORD dst_unused:UNUSED_PAD src0_sel:WORD_1
	v_add_f32_e32 v9, 1.0, v9
	v_rcp_f32_e32 v12, v9
	v_mul_f32_e32 v8, 0x3dd2d3e8, v6
	v_mul_f32_e32 v9, 0x3dd2d3e8, v7
	v_fma_mix_f32 v8, -v8, v26, s9 op_sel_hi:[0,1,0]
	v_fma_mix_f32 v9, -v9, v26, s9 op_sel:[0,1,0] op_sel_hi:[0,1,0]
	v_mul_f32_e32 v8, v8, v6
	v_mul_f32_e32 v9, v9, v7
	v_exp_f32_e32 v8, v8
	v_exp_f32_e32 v9, v9
	v_or_b32_e32 v164, s2, v98
	v_add_f32_e32 v8, 1.0, v8
	v_add_f32_e32 v9, 1.0, v9
	v_rcp_f32_e32 v8, v8
	v_rcp_f32_e32 v9, v9
	s_nop 0
	v_mul_f32_e32 v6, v8, v6
	v_mul_f32_e32 v7, v9, v7
	s_waitcnt lgkmcnt(0)
; #define LAS __attribute__((address_space(3)))
; #define GAS __attribute__((address_space(1)))
; __device__ __forceinline__ float siluf(float x) { return x * __builtin_amdgcn_rcpf(1.f + __builtin_amdgcn_exp2f(-1.4426950408889634f * x)); }
; __device__ __forceinline__ float geluf(float x) { return x * __builtin_amdgcn_rcpf(1.f + __builtin_amdgcn_exp2f(x * (-0.10294324f * x * x - 2.3022082f))); }
; __device__ __forceinline__ unsigned cvtpk_h(float lo, float hi) { f32x2 v = {lo, hi}; h16x2 b = __builtin_convertvector(v, h16x2); return __builtin_bit_cast(unsigned, b); }
; __device__ __forceinline__ void gmlp_unit(unsigned char* ws, h16* Y, const h16* Ws16  , const float* bs  , size_t r0, LAS unsigned char* lds, int tid) {
;     ...
;         for (int ps = 0; ps < 4; ++ps) { const int row = 8 * ps + erow;
;             const h16x8 sv = *(const LAS h16x8*)(scr + row * 72 + 8 * ech);
;             float y[8];
; #pragma unroll
;             for (int k = 0; k < 8; ++k) y[k] = geluf((float)gu[q][ps][k]) * ((float)sv[k] + bias[q][ps]) * siluf((float)sz[q][ps][k]);
;             u32x4 w0; w0.x = cvtpk_h(y[0], y[1]); w0.y = cvtpk_h(y[2], y[3]); w0.z = cvtpk_h(y[4], y[5]); w0.w = cvtpk_h(y[6], y[7]);
;             *(GAS u32x4*)(Y + (r0 + 32 * (2 * ph + q) + row) * D + g * 64 + 8 * ech) = w0; }
	v_cvt_f32_f16_e32 v8, v2
	v_cvt_f32_f16_sdwa v9, v2 dst_sel:DWORD dst_unused:UNUSED_PAD src0_sel:WORD_1
	v_mul_f32_e32 v2, 0xbfb8aa3b, v11
	v_exp_f32_e32 v2, v2
	v_add_f32_e32 v8, v168, v8
	v_add_f32_e32 v9, v168, v9
	v_mul_f32_e32 v6, v6, v8
	v_mul_f32_e32 v7, v7, v9
	v_add_f32_e32 v2, 1.0, v2
	v_rcp_f32_e32 v13, v2
	s_nop 0
	v_mul_f32_e32 v8, v12, v10
	v_mul_f32_e32 v9, v13, v11
	s_nop 0
	v_mul_f32_e32 v6, v8, v6
	v_mul_f32_e32 v7, v9, v7
	v_cvt_f32_f16_e32 v8, v27
	v_cvt_f32_f16_sdwa v9, v27 dst_sel:DWORD dst_unused:UNUSED_PAD src0_sel:WORD_1
	v_cvt_f32_f16_e32 v12, v31
	v_cvt_f32_f16_sdwa v13, v31 dst_sel:DWORD dst_unused:UNUSED_PAD src0_sel:WORD_1
	v_mul_f32_e32 v2, 0x3dd2d3e8, v8
	v_mul_f32_e32 v11, 0x3dd2d3e8, v9
	v_fma_mix_f32 v2, -v2, v27, s9 op_sel_hi:[0,1,0]
	v_fma_mix_f32 v11, -v11, v27, s9 op_sel:[0,1,0] op_sel_hi:[0,1,0]
	v_mul_f32_e32 v2, v2, v8
	v_mul_f32_e32 v11, v11, v9
	v_exp_f32_e32 v2, v2
	v_exp_f32_e32 v11, v11
	v_add_f32_e32 v2, 1.0, v2
	v_add_f32_e32 v11, 1.0, v11
	v_rcp_f32_e32 v10, v2
	v_rcp_f32_e32 v11, v11
	v_mul_f32_e32 v2, 0xbfb8aa3b, v12
	v_exp_f32_e32 v2, v2
	v_mul_f32_e32 v8, v10, v8
	v_mul_f32_e32 v9, v11, v9
	v_cvt_f32_f16_e32 v10, v3
	v_cvt_f32_f16_sdwa v11, v3 dst_sel:DWORD dst_unused:UNUSED_PAD src0_sel:WORD_1
	v_mul_f32_e32 v3, 0xbfb8aa3b, v13
	v_exp_f32_e32 v3, v3
	v_add_f32_e32 v2, 1.0, v2
	v_rcp_f32_e32 v2, v2
	v_add_f32_e32 v10, v168, v10
	v_add_f32_e32 v11, v168, v11
	v_add_f32_e32 v3, 1.0, v3
	v_rcp_f32_e32 v3, v3
	v_mul_f32_e32 v8, v8, v10
	v_mul_f32_e32 v9, v9, v11
	v_mul_f32_e32 v2, v2, v12
	v_mul_f32_e32 v3, v3, v13
	v_cvt_f32_f16_e32 v12, v32
	v_mul_f32_e32 v8, v2, v8
	v_mul_f32_e32 v9, v3, v9
	v_cvt_f32_f16_e32 v2, v28
	v_cvt_f32_f16_sdwa v3, v28 dst_sel:DWORD dst_unused:UNUSED_PAD src0_sel:WORD_1
	v_mul_f32_e32 v11, 0xbfb8aa3b, v12
	v_exp_f32_e32 v11, v11
	v_mul_f32_e32 v10, 0x3dd2d3e8, v2
	v_fma_mix_f32 v10, -v10, v28, s9 op_sel_hi:[0,1,0]
	v_mul_f32_e32 v10, v10, v2
	v_add_f32_e32 v11, 1.0, v11
	v_rcp_f32_e32 v14, v11
	v_mul_f32_e32 v11, 0x3dd2d3e8, v3
	v_fma_mix_f32 v11, -v11, v28, s9 op_sel:[0,1,0] op_sel_hi:[0,1,0]
	v_mul_f32_e32 v11, v11, v3
	v_exp_f32_e32 v10, v10
	v_exp_f32_e32 v11, v11
	v_cvt_f32_f16_sdwa v13, v32 dst_sel:DWORD dst_unused:UNUSED_PAD src0_sel:WORD_1
	v_add_f32_e32 v10, 1.0, v10
	v_add_f32_e32 v11, 1.0, v11
	v_rcp_f32_e32 v10, v10
	v_rcp_f32_e32 v11, v11
	s_nop 0
	v_mul_f32_e32 v2, v10, v2
	v_mul_f32_e32 v3, v11, v3
	v_cvt_f32_f16_e32 v10, v4
	v_cvt_f32_f16_sdwa v11, v4 dst_sel:DWORD dst_unused:UNUSED_PAD src0_sel:WORD_1
	v_mul_f32_e32 v4, 0xbfb8aa3b, v13
	v_exp_f32_e32 v4, v4
	v_add_f32_e32 v10, v168, v10
	v_add_f32_e32 v11, v168, v11
	v_mul_f32_e32 v2, v2, v10
	v_mul_f32_e32 v3, v3, v11
	v_add_f32_e32 v4, 1.0, v4
	v_rcp_f32_e32 v15, v4
	s_nop 0
	v_mul_f32_e32 v10, v14, v12
	v_mul_f32_e32 v11, v15, v13
	s_nop 0
	v_mul_f32_e32 v10, v10, v2
	v_mul_f32_e32 v11, v11, v3
	v_cvt_f32_f16_e32 v2, v29
	v_cvt_f32_f16_sdwa v3, v29 dst_sel:DWORD dst_unused:UNUSED_PAD src0_sel:WORD_1
	v_cvt_f32_f16_e32 v14, v33
	v_cvt_f32_f16_sdwa v15, v33 dst_sel:DWORD dst_unused:UNUSED_PAD src0_sel:WORD_1
	v_mul_f32_e32 v4, 0x3dd2d3e8, v2
	v_mul_f32_e32 v13, 0x3dd2d3e8, v3
	v_fma_mix_f32 v4, -v4, v29, s9 op_sel_hi:[0,1,0]
	v_fma_mix_f32 v13, -v13, v29, s9 op_sel:[0,1,0] op_sel_hi:[0,1,0]
	v_mul_f32_e32 v4, v4, v2
	v_mul_f32_e32 v13, v13, v3
	v_exp_f32_e32 v4, v4
	v_exp_f32_e32 v13, v13
	v_add_f32_e32 v4, 1.0, v4
	v_add_f32_e32 v13, 1.0, v13
	v_rcp_f32_e32 v12, v4
	v_rcp_f32_e32 v13, v13
	v_mul_f32_e32 v4, 0xbfb8aa3b, v14
	v_exp_f32_e32 v4, v4
	v_mul_f32_e32 v2, v12, v2
	v_mul_f32_e32 v3, v13, v3
	v_cvt_f32_f16_e32 v12, v5
	v_cvt_f32_f16_sdwa v13, v5 dst_sel:DWORD dst_unused:UNUSED_PAD src0_sel:WORD_1
	v_mul_f32_e32 v5, 0xbfb8aa3b, v15
	v_exp_f32_e32 v5, v5
	v_add_f32_e32 v4, 1.0, v4
	v_rcp_f32_e32 v4, v4
	v_add_f32_e32 v12, v168, v12
	v_add_f32_e32 v13, v168, v13
	v_add_f32_e32 v5, 1.0, v5
	v_rcp_f32_e32 v5, v5
	v_mul_f32_e32 v2, v2, v12
	v_mul_f32_e32 v3, v3, v13
	v_mul_f32_e32 v4, v4, v14
	v_mul_f32_e32 v5, v5, v15
	s_nop 0
	v_mul_f32_e32 v12, v4, v2
	v_mul_f32_e32 v13, v5, v3
	v_cvt_pk_f16_f32 v2, v6, v7
	v_lshlrev_b64 v[6:7], 11, v[164:165]
	v_cvt_pk_f16_f32 v3, v8, v9
	v_cvt_pk_f16_f32 v4, v10, v11
	v_cvt_pk_f16_f32 v5, v12, v13
	v_lshl_add_u64 v[6:7], v[148:149], 0, v[6:7]
	global_store_dwordx4 v[6:7], v[2:5], off sc1
	s_waitcnt vmcnt(8)
	v_cvt_f32_f16_e32 v6, v18
	ds_read_b128 v[2:5], v0 offset:3456
	s_waitcnt vmcnt(7)
; #define LAS __attribute__((address_space(3)))
; #define GAS __attribute__((address_space(1)))
; __device__ __forceinline__ float siluf(float x) { return x * __builtin_amdgcn_rcpf(1.f + __builtin_amdgcn_exp2f(-1.4426950408889634f * x)); }
; __device__ __forceinline__ float geluf(float x) { return x * __builtin_amdgcn_rcpf(1.f + __builtin_amdgcn_exp2f(x * (-0.10294324f * x * x - 2.3022082f))); }
; __device__ __forceinline__ unsigned cvtpk_h(float lo, float hi) { f32x2 v = {lo, hi}; h16x2 b = __builtin_convertvector(v, h16x2); return __builtin_bit_cast(unsigned, b); }
; #define LDS_WAIT() asm volatile("s_waitcnt lgkmcnt(0)" ::: "memory")
; #define BAR_LDS() asm volatile("s_waitcnt lgkmcnt(0)\n\ts_barrier" ::: "memory")
; __device__ __forceinline__ void gmlp_unit(unsigned char* ws, h16* Y, const h16* Ws16  , const float* bs  , size_t r0, LAS unsigned char* lds, int tid) {
;     ...
;         for (int ps = 0; ps < 4; ++ps) { const int row = 8 * ps + erow;
;             const h16x8 sv = *(const LAS h16x8*)(scr + row * 72 + 8 * ech);
;             float y[8];
; #pragma unroll
;             for (int k = 0; k < 8; ++k) y[k] = geluf((float)gu[q][ps][k]) * ((float)sv[k] + bias[q][ps]) * siluf((float)sz[q][ps][k]);
;             u32x4 w0; w0.x = cvtpk_h(y[0], y[1]); w0.y = cvtpk_h(y[2], y[3]); w0.z = cvtpk_h(y[4], y[5]); w0.w = cvtpk_h(y[6], y[7]);
;             *(GAS u32x4*)(Y + (r0 + 32 * (2 * ph + q) + row) * D + g * 64 + 8 * ech) = w0; }
;         LDS_WAIT();
;     }
;     BAR_LDS();
	v_cvt_f32_f16_e32 v10, v22
	v_cvt_f32_f16_sdwa v7, v18 dst_sel:DWORD dst_unused:UNUSED_PAD src0_sel:WORD_1
	v_mul_f32_e32 v0, 0x3dd2d3e8, v6
	v_fma_mix_f32 v0, -v0, v18, s9 op_sel_hi:[0,1,0]
	v_mul_f32_e32 v0, v0, v6
	v_exp_f32_e32 v0, v0
	v_cvt_f32_f16_sdwa v11, v22 dst_sel:DWORD dst_unused:UNUSED_PAD src0_sel:WORD_1
	v_or_b32_e32 v164, s2, v90
	s_mov_b64 s[2:3], 0
	v_add_f32_e32 v0, 1.0, v0
	v_rcp_f32_e32 v8, v0
	v_mul_f32_e32 v0, 0xbfb8aa3b, v10
	v_exp_f32_e32 v0, v0
	s_nop 0
	v_add_f32_e32 v0, 1.0, v0
	v_rcp_f32_e32 v12, v0
	v_mul_f32_e32 v0, 0x3dd2d3e8, v7
	v_fma_mix_f32 v0, -v0, v18, s9 op_sel:[0,1,0] op_sel_hi:[0,1,0]
	v_mul_f32_e32 v0, v0, v7
	v_exp_f32_e32 v0, v0
	s_nop 0
	v_add_f32_e32 v0, 1.0, v0
	v_rcp_f32_e32 v9, v0
	v_mul_f32_e32 v0, 0xbfb8aa3b, v11
	v_exp_f32_e32 v0, v0
	v_mul_f32_e32 v6, v8, v6
	v_mul_f32_e32 v7, v9, v7
	s_waitcnt lgkmcnt(0)
	v_cvt_f32_f16_e32 v8, v2
	v_cvt_f32_f16_sdwa v9, v2 dst_sel:DWORD dst_unused:UNUSED_PAD src0_sel:WORD_1
	v_add_f32_e32 v0, 1.0, v0
	v_rcp_f32_e32 v13, v0
	v_add_f32_e32 v8, v166, v8
	v_add_f32_e32 v9, v166, v9
	v_mul_f32_e32 v6, v6, v8
	v_mul_f32_e32 v7, v7, v9
	v_mul_f32_e32 v8, v12, v10
	v_mul_f32_e32 v9, v13, v11
	v_cvt_f32_f16_e32 v12, v23
	v_mul_f32_e32 v6, v8, v6
	v_mul_f32_e32 v7, v9, v7
	v_cvt_f32_f16_e32 v8, v19
	v_cvt_f32_f16_sdwa v9, v19 dst_sel:DWORD dst_unused:UNUSED_PAD src0_sel:WORD_1
	v_cvt_f32_f16_sdwa v13, v23 dst_sel:DWORD dst_unused:UNUSED_PAD src0_sel:WORD_1
	v_mul_f32_e32 v0, 0x3dd2d3e8, v8
	v_fma_mix_f32 v0, -v0, v19, s9 op_sel_hi:[0,1,0]
	v_mul_f32_e32 v0, v0, v8
	v_exp_f32_e32 v0, v0
	s_nop 0
	v_add_f32_e32 v0, 1.0, v0
	v_rcp_f32_e32 v10, v0
	v_mul_f32_e32 v0, 0xbfb8aa3b, v12
	v_exp_f32_e32 v0, v0
	s_nop 0
	v_add_f32_e32 v0, 1.0, v0
	v_rcp_f32_e32 v2, v0
	v_mul_f32_e32 v0, 0x3dd2d3e8, v9
	v_fma_mix_f32 v0, -v0, v19, s9 op_sel:[0,1,0] op_sel_hi:[0,1,0]
	v_mul_f32_e32 v0, v0, v9
	v_exp_f32_e32 v0, v0
	s_nop 0
	v_add_f32_e32 v0, 1.0, v0
	v_rcp_f32_e32 v11, v0
	v_mul_f32_e32 v0, 0xbfb8aa3b, v13
	v_exp_f32_e32 v0, v0
	v_mul_f32_e32 v8, v10, v8
	v_mul_f32_e32 v9, v11, v9
	v_cvt_f32_f16_e32 v10, v3
	v_cvt_f32_f16_sdwa v11, v3 dst_sel:DWORD dst_unused:UNUSED_PAD src0_sel:WORD_1
	v_add_f32_e32 v0, 1.0, v0
	v_rcp_f32_e32 v3, v0
	v_add_f32_e32 v10, v166, v10
	v_add_f32_e32 v11, v166, v11
	v_mul_f32_e32 v8, v8, v10
	v_mul_f32_e32 v9, v9, v11
	v_mul_f32_e32 v2, v2, v12
	v_mul_f32_e32 v3, v3, v13
	v_cvt_f32_f16_e32 v12, v24
	v_mul_f32_e32 v2, v2, v8
	v_mul_f32_e32 v3, v3, v9
	v_cvt_f32_f16_e32 v8, v20
	v_cvt_f32_f16_sdwa v9, v20 dst_sel:DWORD dst_unused:UNUSED_PAD src0_sel:WORD_1
	v_cvt_f32_f16_sdwa v13, v24 dst_sel:DWORD dst_unused:UNUSED_PAD src0_sel:WORD_1
	v_mul_f32_e32 v0, 0x3dd2d3e8, v8
	v_fma_mix_f32 v0, -v0, v20, s9 op_sel_hi:[0,1,0]
	v_mul_f32_e32 v0, v0, v8
	v_exp_f32_e32 v0, v0
	s_nop 0
	v_add_f32_e32 v0, 1.0, v0
	v_rcp_f32_e32 v10, v0
	v_mul_f32_e32 v0, 0xbfb8aa3b, v12
	v_exp_f32_e32 v0, v0
	s_nop 0
	v_add_f32_e32 v0, 1.0, v0
	v_rcp_f32_e32 v14, v0
	v_mul_f32_e32 v0, 0x3dd2d3e8, v9
	v_fma_mix_f32 v0, -v0, v20, s9 op_sel:[0,1,0] op_sel_hi:[0,1,0]
	v_mul_f32_e32 v0, v0, v9
	v_exp_f32_e32 v0, v0
	s_nop 0
	v_add_f32_e32 v0, 1.0, v0
	v_rcp_f32_e32 v11, v0
	v_mul_f32_e32 v0, 0xbfb8aa3b, v13
	v_exp_f32_e32 v0, v0
	v_mul_f32_e32 v8, v10, v8
	v_mul_f32_e32 v9, v11, v9
	v_cvt_f32_f16_e32 v10, v4
	v_cvt_f32_f16_sdwa v11, v4 dst_sel:DWORD dst_unused:UNUSED_PAD src0_sel:WORD_1
	v_add_f32_e32 v0, 1.0, v0
	v_rcp_f32_e32 v15, v0
	v_add_f32_e32 v10, v166, v10
	v_add_f32_e32 v11, v166, v11
	v_mul_f32_e32 v8, v8, v10
	v_mul_f32_e32 v9, v9, v11
	v_mul_f32_e32 v10, v14, v12
	v_mul_f32_e32 v11, v15, v13
	v_cvt_f32_f16_e32 v14, v25
	v_mul_f32_e32 v8, v10, v8
	v_mul_f32_e32 v9, v11, v9
	v_cvt_f32_f16_e32 v10, v21
	v_cvt_f32_f16_sdwa v11, v21 dst_sel:DWORD dst_unused:UNUSED_PAD src0_sel:WORD_1
	v_cvt_f32_f16_sdwa v15, v25 dst_sel:DWORD dst_unused:UNUSED_PAD src0_sel:WORD_1
	v_mul_f32_e32 v0, 0x3dd2d3e8, v10
	v_fma_mix_f32 v0, -v0, v21, s9 op_sel_hi:[0,1,0]
	v_mul_f32_e32 v0, v0, v10
	v_exp_f32_e32 v0, v0
	s_nop 0
	v_add_f32_e32 v0, 1.0, v0
	v_rcp_f32_e32 v12, v0
	v_mul_f32_e32 v0, 0xbfb8aa3b, v14
	v_exp_f32_e32 v0, v0
	s_nop 0
	v_add_f32_e32 v0, 1.0, v0
	v_rcp_f32_e32 v4, v0
	v_mul_f32_e32 v0, 0x3dd2d3e8, v11
	v_fma_mix_f32 v0, -v0, v21, s9 op_sel:[0,1,0] op_sel_hi:[0,1,0]
	v_mul_f32_e32 v0, v0, v11
	v_exp_f32_e32 v0, v0
	s_nop 0
	v_add_f32_e32 v0, 1.0, v0
	v_rcp_f32_e32 v13, v0
	v_mul_f32_e32 v0, 0xbfb8aa3b, v15
	v_exp_f32_e32 v0, v0
	v_mul_f32_e32 v10, v12, v10
	v_mul_f32_e32 v11, v13, v11
	v_cvt_f32_f16_e32 v12, v5
	v_cvt_f32_f16_sdwa v13, v5 dst_sel:DWORD dst_unused:UNUSED_PAD src0_sel:WORD_1
	v_add_f32_e32 v0, 1.0, v0
	v_rcp_f32_e32 v5, v0
	v_add_f32_e32 v12, v166, v12
	v_add_f32_e32 v13, v166, v13
	v_mul_f32_e32 v10, v10, v12
	v_mul_f32_e32 v11, v11, v13
	v_mul_f32_e32 v4, v4, v14
	v_mul_f32_e32 v5, v5, v15
	s_nop 0
	v_mul_f32_e32 v10, v4, v10
	v_mul_f32_e32 v11, v5, v11
	v_cvt_pk_f16_f32 v5, v2, v3
	v_lshlrev_b64 v[2:3], 11, v[164:165]
	v_cvt_pk_f16_f32 v4, v6, v7
	v_cvt_pk_f16_f32 v6, v8, v9
	v_cvt_pk_f16_f32 v7, v10, v11
	v_lshl_add_u64 v[2:3], v[148:149], 0, v[2:3]
	global_store_dwordx4 v[2:3], v[4:7], off sc1
	s_waitcnt lgkmcnt(0)
	s_waitcnt lgkmcnt(0)
	s_barrier

; #define SBAR() __builtin_amdgcn_sched_barrier(0)
; #define RESC() do { if (!FIXM && resc) { asm volatile("s_waitcnt lgkmcnt(0)" ::: "memory"); \
;       _Pragma("unroll") for (int d_ = 0; d_ < 2; ++d_) _Pragma("unroll") for (int r = 0; r < 16; ++r) o[d_][r] *= wsf[crow(r, hi)]; } } while (0)
; #define PKW(P, B) cvtpk_h(P[B], P[B + 1])
; #define PKW(P, B) cvtpk_h(P[B], P[B + 1])
; template <int THRL, bool FIXM> __device__ __forceinline__ bool attn_unit(const h16* Qrows, const h16* __restrict__ Kh, const h16* __restrict__ Vh, const int NT, h16* Yrows, const h16* BZrows, char* shm, const int tid, const float mfix, ...
;     ...
;   STEP(pB0, pB1, pA0, pA1, NT - 1, false, false, false); RESC();
;   { float sacc = pB0[0] + pB0[1]; _Pragma("unroll") for (int r = 2; r < 16; ++r) sacc += pB0[r]; _Pragma("unroll") for (int r = 0; r < 16; ++r) sacc += pB1[r]; l_reg += sacc;
;     pw0 = (u32x4){PKW(pB0, 0), PKW(pB0, 2), PKW(pB0, 4), PKW(pB0, 6)}; pw1 = (u32x4){PKW(pB0, 8), PKW(pB0, 10), PKW(pB0, 12), PKW(pB0, 14)}; pw2 = (u32x4){PKW(pB1, 0), PKW(pB1, 2), PKW(pB1, 4), PKW(pB1, 6)}; pw3 = (u32x4){PKW(pB1, 8), PKW(pB1, 10), PKW(pB1, 12), PKW(pB1, 14)};
;     SBAR(); pv(o, vb0 + sl_cur, __builtin_bit_cast(s16x8, pw0), __builtin_bit_cast(s16x8, pw1), __builtin_bit_cast(s16x8, pw2), __builtin_bit_cast(s16x8, pw3)); }
.LBB0_124:
	s_and_b32 s12, s29, 0x3fffffc0
	s_lshl_b32 s12, s12, 2
	s_add_i32 s14, s41, s12
	v_add_u32_e32 v0, s51, v233
	ds_read_b64_tr_b16 v[52:53], v0 offset:24576
	ds_read_b64_tr_b16 v[54:55], v0 offset:25088
	v_add_f32_e32 v51, v82, v83
	v_add_f32_e32 v51, v84, v51
	v_add_f32_e32 v51, v85, v51
	v_add_f32_e32 v51, v86, v51
	v_add_f32_e32 v51, v87, v51
	v_cvt_pk_f16_f32 v160, v82, v83
	v_cvt_pk_f16_f32 v161, v84, v85
	s_waitcnt lgkmcnt(9)
	v_mfma_f32_32x32x16_f16 v[98:113], v[192:195], v[144:147], v[2:17]
	ds_read_b64_tr_b16 v[56:57], v0 offset:28672
	ds_read_b64_tr_b16 v[58:59], v0 offset:29184
	s_waitcnt lgkmcnt(10)
	v_mfma_f32_32x32x16_f16 v[2:17], v[188:191], v[144:147], v[2:17]
	v_add_f32_e32 v51, v88, v51
	v_add_f32_e32 v51, v89, v51
	v_add_f32_e32 v51, v90, v51
	v_add_f32_e32 v51, v91, v51
	v_cvt_pk_f16_f32 v162, v86, v87
	v_cvt_pk_f16_f32 v163, v88, v89
	ds_read_b64_tr_b16 v[60:61], v0 offset:25600
	ds_read_b64_tr_b16 v[62:63], v0 offset:26112
	v_add_f32_e32 v51, v92, v51
	v_add_f32_e32 v51, v93, v51
	v_add_f32_e32 v51, v94, v51
	v_add_f32_e32 v51, v95, v51
	v_cvt_pk_f16_f32 v156, v90, v91
	v_cvt_pk_f16_f32 v157, v92, v93
	s_waitcnt lgkmcnt(11)
	v_mfma_f32_32x32x16_f16 v[98:113], v[184:187], v[140:143], v[98:113]
	ds_read_b64_tr_b16 v[82:83], v0 offset:29696
	ds_read_b64_tr_b16 v[84:85], v0 offset:30208
	s_waitcnt lgkmcnt(12)
	v_mfma_f32_32x32x16_f16 v[2:17], v[180:183], v[140:143], v[2:17]
	v_add_f32_e32 v51, v96, v51
	v_add_f32_e32 v51, v97, v51
	v_add_f32_e32 v51, v66, v51
	v_add_f32_e32 v51, v67, v51
	v_cvt_pk_f16_f32 v158, v94, v95
	v_cvt_pk_f16_f32 v159, v96, v97
	ds_read_b64_tr_b16 v[86:87], v0 offset:26624
	ds_read_b64_tr_b16 v[88:89], v0 offset:27136
	v_add_f32_e32 v51, v68, v51
	v_add_f32_e32 v51, v69, v51
	v_add_f32_e32 v51, v70, v51
	v_add_f32_e32 v51, v71, v51
	v_cvt_pk_f16_f32 v152, v66, v67
	v_cvt_pk_f16_f32 v153, v68, v69
	s_waitcnt lgkmcnt(13)
	v_mfma_f32_32x32x16_f16 v[98:113], v[176:179], v[136:139], v[98:113]
	ds_read_b64_tr_b16 v[64:65], v0 offset:30720
	ds_read_b64_tr_b16 v[66:67], v0 offset:31232
	s_waitcnt lgkmcnt(14)
	v_mfma_f32_32x32x16_f16 v[2:17], v[172:175], v[136:139], v[2:17]
	v_add_f32_e32 v51, v72, v51
	v_add_f32_e32 v51, v73, v51
	v_add_f32_e32 v51, v74, v51
	v_add_f32_e32 v51, v75, v51
	v_cvt_pk_f16_f32 v154, v70, v71
	v_cvt_pk_f16_f32 v155, v72, v73
	ds_read_b64_tr_b16 v[68:69], v0 offset:27648
	ds_read_b64_tr_b16 v[70:71], v0 offset:28160
	v_add_f32_e32 v51, v76, v51
	v_add_f32_e32 v51, v77, v51
	v_add_f32_e32 v51, v78, v51
	v_add_f32_e32 v51, v79, v51
	v_cvt_pk_f16_f32 v148, v74, v75
	v_cvt_pk_f16_f32 v149, v76, v77
	s_waitcnt lgkmcnt(14)
	v_mfma_f32_32x32x16_f16 v[98:113], v[168:171], v[132:135], v[98:113]
	ds_read_b64_tr_b16 v[72:73], v0 offset:31744
	ds_read_b64_tr_b16 v[74:75], v0 offset:32256
	v_mfma_f32_32x32x16_f16 v[2:17], v[164:167], v[132:135], v[2:17]
	v_add_f32_e32 v0, v80, v51
	v_add_f32_e32 v0, v81, v0
	v_add_f32_e32 v0, 0, v0
	v_cvt_pk_f16_f32 v150, v78, v79
	v_cvt_pk_f16_f32 v151, v80, v81
	s_waitcnt lgkmcnt(14)
	v_mfma_f32_32x32x16_f16 v[18:33], v[160:163], v[52:55], v[18:33]
	s_nop 1
	v_exp_f32_e32 v98, v98
	v_exp_f32_e32 v99, v99
	v_exp_f32_e32 v100, v100
	v_exp_f32_e32 v101, v101
	s_waitcnt lgkmcnt(12)
	v_mfma_f32_32x32x16_f16 v[34:49], v[160:163], v[56:59], v[34:49]
	v_exp_f32_e32 v102, v102
	v_exp_f32_e32 v103, v103
	v_exp_f32_e32 v104, v104
	v_exp_f32_e32 v105, v105
	s_waitcnt lgkmcnt(10)
	v_mfma_f32_32x32x16_f16 v[18:33], v[156:159], v[60:63], v[18:33]
	v_exp_f32_e32 v106, v106
	v_exp_f32_e32 v107, v107
	v_exp_f32_e32 v108, v108
	v_exp_f32_e32 v109, v109
	s_waitcnt lgkmcnt(8)
	v_mfma_f32_32x32x16_f16 v[34:49], v[156:159], v[82:85], v[34:49]
	v_exp_f32_e32 v110, v110
	v_exp_f32_e32 v111, v111
	v_exp_f32_e32 v112, v112
	v_exp_f32_e32 v113, v113
	s_waitcnt lgkmcnt(6)
	v_mfma_f32_32x32x16_f16 v[18:33], v[152:155], v[86:89], v[18:33]
	v_exp_f32_e32 v2, v2
	v_exp_f32_e32 v3, v3
	v_exp_f32_e32 v4, v4
	v_exp_f32_e32 v5, v5
	s_waitcnt lgkmcnt(4)
	v_mfma_f32_32x32x16_f16 v[34:49], v[152:155], v[64:67], v[34:49]
	v_exp_f32_e32 v6, v6
	v_exp_f32_e32 v7, v7
	v_exp_f32_e32 v8, v8
	v_exp_f32_e32 v9, v9
	s_waitcnt lgkmcnt(2)
	v_mfma_f32_32x32x16_f16 v[18:33], v[148:151], v[68:71], v[18:33]
	v_exp_f32_e32 v10, v10
	v_exp_f32_e32 v11, v11
	v_exp_f32_e32 v12, v12
	v_exp_f32_e32 v13, v13
	s_waitcnt lgkmcnt(0)
	v_mfma_f32_32x32x16_f16 v[34:49], v[148:151], v[72:75], v[34:49]
	v_exp_f32_e32 v14, v14
	v_exp_f32_e32 v15, v15
	v_exp_f32_e32 v16, v16
	v_exp_f32_e32 v17, v17
	v_add_f32_e32 v51, v98, v99
	v_add_f32_e32 v51, v100, v51
	v_add_f32_e32 v51, v101, v51
	v_add_f32_e32 v51, v102, v51
	v_add_f32_e32 v51, v103, v51
	v_add_f32_e32 v51, v104, v51
	v_add_f32_e32 v51, v105, v51
	v_add_f32_e32 v51, v106, v51
	v_add_f32_e32 v51, v107, v51
	v_add_f32_e32 v51, v108, v51
	v_add_f32_e32 v51, v109, v51
	v_add_f32_e32 v51, v110, v51
	v_add_f32_e32 v51, v111, v51
	v_add_f32_e32 v51, v112, v51
	v_add_f32_e32 v82, v113, v51
	v_add_f32_e32 v83, v50, v0
	v_cvt_pk_f16_f32 v50, v98, v99
	v_cvt_pk_f16_f32 v51, v100, v101
	v_cvt_pk_f16_f32 v52, v102, v103
	v_cvt_pk_f16_f32 v53, v104, v105
	v_cvt_pk_f16_f32 v54, v106, v107
	v_cvt_pk_f16_f32 v55, v108, v109
	v_cvt_pk_f16_f32 v56, v110, v111
	v_cvt_pk_f16_f32 v57, v112, v113
	v_cvt_pk_f16_f32 v66, v2, v3
	v_cvt_pk_f16_f32 v67, v4, v5
	v_cvt_pk_f16_f32 v68, v6, v7
	v_cvt_pk_f16_f32 v69, v8, v9
	v_cvt_pk_f16_f32 v70, v10, v11
	v_cvt_pk_f16_f32 v71, v12, v13
	v_cvt_pk_f16_f32 v72, v14, v15
	v_cvt_pk_f16_f32 v73, v16, v17
	v_or3_b32 v0, v243, v232, v231
	s_add_i32 s12, s77, s17
	v_add_u32_e32 v0, s12, v0
	ds_read_b64_tr_b16 v[58:59],v0 offset:0
	ds_read_b64_tr_b16 v[60:61],v0 offset:512
	ds_read_b64_tr_b16 v[62:63],v0 offset:1024
	ds_read_b64_tr_b16 v[64:65],v0 offset:1536
	ds_read_b64_tr_b16 v[74:75],v0 offset:2048
	ds_read_b64_tr_b16 v[76:77],v0 offset:2560
	ds_read_b64_tr_b16 v[78:79],v0 offset:3072
	ds_read_b64_tr_b16 v[80:81],v0 offset:3584
	s_waitcnt lgkmcnt(0)
; #define GAS __attribute__((address_space(1)))
; __device__ __forceinline__ int crow(int r, int hi) { return (r & 3) + 8 * (r >> 2) + 4 * hi; }
; __device__ __forceinline__ void pv(f32x16* o, int vb, s16x8 pa0, s16x8 pa1, s16x8 pa2, s16x8 pa3) {
; #pragma unroll
;   for (int d0 = 0; d0 < 2; ++d0) { s16x4 lo[4], hi[4];
; #pragma unroll
;     for (int ks = 0; ks < 4; ++ks) {
;       asm volatile("ds_read_b64_tr_b16 %0,%1 offset:%c2" : "=&v"(lo[ks]) : "v"(vb), "i"(d0 * 4096 + ks * 1024) : "memory");
;       asm volatile("ds_read_b64_tr_b16 %0,%1 offset:%c2" : "=&v"(hi[ks]) : "v"(vb), "i"(d0 * 4096 + ks * 1024 + 512) : "memory"); }
;     asm volatile("s_waitcnt lgkmcnt(0)" ::: "memory"); SBAR();
;     ...
;     o[d0] = __builtin_amdgcn_mfma_f32_32x32x16_f16(H8(pa0), H8(PK(0)), o[d0], 0, 0, 0);
;     o[d0] = __builtin_amdgcn_mfma_f32_32x32x16_f16(H8(pa1), H8(PK(1)), o[d0], 0, 0, 0);
;     o[d0] = __builtin_amdgcn_mfma_f32_32x32x16_f16(H8(pa2), H8(PK(2)), o[d0], 0, 0, 0);
;     o[d0] = __builtin_amdgcn_mfma_f32_32x32x16_f16(H8(pa3), H8(PK(3)), o[d0], 0, 0, 0);
;     ...
;   }
; template <int THRL, bool FIXM> __device__ __forceinline__ bool attn_unit(const h16* Qrows, const h16* __restrict__ Kh, const h16* __restrict__ Vh, const int NT, h16* Yrows, const h16* BZrows, char* shm, const int tid, const float mfix, ...
;     ...
;     SBAR(); pv(o, vb0 + sl_cur, __builtin_bit_cast(s16x8, pw0), __builtin_bit_cast(s16x8, pw1), __builtin_bit_cast(s16x8, pw2), __builtin_bit_cast(s16x8, pw3)); }
;   h16x8 zg[4];
;   { const h16* Zw0 = BZrows + (long)(wid * QBLK) * ZP;
; #pragma unroll
;     for (int i = 0; i < 4; ++i) zg[i] = *(const GAS h16x8*)(Zw0 + (long)(i * 8 + (lane >> 3)) * ZP + (lane & 7) * 8); }
;     ...
;   { auto rr = __builtin_amdgcn_permlane32_swap(__float_as_uint(l_reg), __float_as_uint(l_reg), false, false); l_reg = __uint_as_float(rr[0]) + __uint_as_float(rr[1]); }
;   if (hi == 0) wsf[32 + r32] = l_reg; asm volatile("s_waitcnt lgkmcnt(0)" ::: "memory");
;   float rli[16];
; #pragma unroll
;   for (int r = 0; r < 16; ++r) rli[r] = __builtin_amdgcn_rcpf(wsf[32 + crow(r, hi)]);
;   h16* Yw = Yrows + (long)(wid * QBLK) * YP;
;   { h16* stg = (h16*)(shm + LDS_OST) + wid * 2048;
; #pragma unroll
;     for (int r = 0; r < 16; ++r) { const int orow = crow(r, hi);
; #pragma unroll
;       for (int d0 = 0; d0 < 2; ++d0) stg[orow * 64 + d0 * 32 + r32] = (h16)(o[d0][r] * rli[r]); }
	s_nop 0
	v_mfma_f32_32x32x16_f16 v[18:33], v[50:53], v[58:61], v[18:33]
	ds_read_b64_tr_b16 v[58:59],v0 offset:4096
	ds_read_b64_tr_b16 v[60:61],v0 offset:4608
	v_mfma_f32_32x32x16_f16 v[18:33], v[54:57], v[62:65], v[18:33]
	ds_read_b64_tr_b16 v[62:63],v0 offset:5120
	ds_read_b64_tr_b16 v[64:65],v0 offset:5632
	v_mfma_f32_32x32x16_f16 v[18:33], v[66:69], v[74:77], v[18:33]
	ds_read_b64_tr_b16 v[74:75],v0 offset:6144
	ds_read_b64_tr_b16 v[76:77],v0 offset:6656
	v_mfma_f32_32x32x16_f16 v[18:33], v[70:73], v[78:81], v[18:33]
	ds_read_b64_tr_b16 v[78:79],v0 offset:7168
	ds_read_b64_tr_b16 v[80:81],v0 offset:7680
	s_waitcnt lgkmcnt(0)
	v_mfma_f32_32x32x16_f16 v[34:49], v[50:53], v[58:61], v[34:49]
	s_lshl_b64 s[12:13], s[24:25], 1
	s_add_u32 s12, s82, s12
	v_and_b32_e32 v0, 56, v131
	s_addc_u32 s13, s81, s13
	v_and_b32_e32 v52, 0xe00, v230
	v_lshlrev_b32_e32 v0, 1, v0
	v_lshl_add_u64 v[50:51], s[12:13], 0, v[0:1]
	v_lshlrev_b32_e32 v52, 1, v52
	v_mov_b32_e32 v53, v1
	v_lshl_add_u64 v[50:51], v[50:51], 0, v[52:53]
	s_movk_i32 s12, 0x2000
	v_add_co_u32_e32 v52, vcc, s12, v50
	s_movk_i32 s12, 0x4000
	s_nop 0
	v_addc_co_u32_e32 v53, vcc, 0, v51, vcc
	v_mfma_f32_32x32x16_f16 v[34:49], v[54:57], v[62:65], v[34:49]
	global_load_dwordx4 v[62:65], v[50:51], off
	global_load_dwordx4 v[58:61], v[52:53], off
	v_add_co_u32_e32 v52, vcc, s12, v50
	v_add_f32_e32 v2, v2, v82
	s_nop 0
	v_addc_co_u32_e32 v53, vcc, 0, v51, vcc
	v_add_co_u32_e32 v50, vcc, s90, v50
	v_add_f32_e32 v2, v3, v2
	s_nop 0
	v_addc_co_u32_e32 v51, vcc, 0, v51, vcc
	global_load_dwordx4 v[54:57], v[52:53], off
	s_nop 0
	global_load_dwordx4 v[50:53], v[50:51], off
	v_add_f32_e32 v2, v4, v2
	v_mfma_f32_32x32x16_f16 v[34:49], v[66:69], v[74:77], v[34:49]
	v_add_f32_e32 v2, v5, v2
	v_add_f32_e32 v2, v6, v2
	v_add_f32_e32 v2, v7, v2
	v_add_f32_e32 v2, v8, v2
	v_add_f32_e32 v2, v9, v2
	v_add_f32_e32 v2, v10, v2
	v_add_f32_e32 v2, v11, v2
	v_add_f32_e32 v2, v12, v2
	v_mfma_f32_32x32x16_f16 v[34:49], v[70:73], v[78:81], v[34:49]
	v_add_f32_e32 v2, v13, v2
	v_add_f32_e32 v2, v14, v2
	v_add_f32_e32 v2, v15, v2
	v_add_f32_e32 v2, v16, v2
	v_add_f32_e32 v2, v17, v2
	v_add_f32_e32 v2, v83, v2
	v_mov_b32_e32 v3, v2
	s_nop 1
	v_permlane32_swap_b32_e32 v2, v3
	v_cmp_gt_u32_e32 vcc, 32, v249
	s_and_saveexec_b64 s[12:13], vcc
	v_lshl_add_u32 v4, v250, 2, s14
	v_add_f32_e32 v2, v2, v3
	ds_write_b32 v4, v2 offset:49280
	s_or_b64 exec, exec, s[12:13]
	v_lshl_add_u32 v4, v248, 4, s14
	s_waitcnt lgkmcnt(0)
	v_add_u32_e32 v2, 0xc080, v4
	ds_read2_b32 v[164:165], v2 offset1:1
	ds_read2_b32 v[166:167], v2 offset0:2 offset1:3
	ds_read2_b32 v[168:169], v2 offset0:8 offset1:9
	ds_read2_b32 v[170:171], v2 offset0:10 offset1:11
	ds_read2_b32 v[172:173], v2 offset0:16 offset1:17
	ds_read2_b32 v[174:175], v2 offset0:18 offset1:19
	ds_read2_b32 v[176:177], v2 offset0:24 offset1:25
	ds_read2_b32 v[178:179], v2 offset0:26 offset1:27
	s_lshl_b32 s12, s16, 12
	s_add_i32 s12, s41, s12
	v_lshlrev_b32_e32 v67, 1, v250
	s_lshl_b64 s[10:11], s[10:11], 11
	s_add_u32 s10, s79, s10
	s_addc_u32 s11, s80, s11
	s_mov_b32 s51, 0x41000000
	s_waitcnt lgkmcnt(0)
	v_rcp_f32_e32 v5, v164
	v_rcp_f32_e32 v6, v165
	v_rcp_f32_e32 v7, v166
	v_rcp_f32_e32 v8, v167
	v_rcp_f32_e32 v9, v168
	v_rcp_f32_e32 v10, v169
	v_rcp_f32_e32 v11, v170
	v_rcp_f32_e32 v12, v171
	v_rcp_f32_e32 v13, v172
	v_rcp_f32_e32 v14, v173
	v_rcp_f32_e32 v15, v174
	v_rcp_f32_e32 v16, v175
	v_rcp_f32_e32 v17, v176
	v_fma_mixlo_f16 v4, v18, v5, 0
	v_lshlrev_b32_e32 v18, 1, v240
	v_add3_u32 v18, s12, v18, v67
	ds_write_b16 v18, v4 offset:51200
	v_fma_mixlo_f16 v4, v34, v5, 0
	ds_write_b16 v18, v4 offset:51264
	v_fma_mixlo_f16 v4, v19, v6, 0
	ds_write_b16 v18, v4 offset:51328
	v_fma_mixlo_f16 v4, v35, v6, 0
	ds_write_b16 v18, v4 offset:51392
	v_fma_mixlo_f16 v4, v20, v7, 0
	ds_write_b16 v18, v4 offset:51456
	v_fma_mixlo_f16 v4, v36, v7, 0
	ds_write_b16 v18, v4 offset:51520
	v_fma_mixlo_f16 v4, v21, v8, 0
	ds_write_b16 v18, v4 offset:51584
	v_fma_mixlo_f16 v4, v37, v8, 0
	ds_write_b16 v18, v4 offset:51648
	v_fma_mixlo_f16 v4, v22, v9, 0
	ds_write_b16 v18, v4 offset:52224
	v_fma_mixlo_f16 v4, v38, v9, 0
	ds_write_b16 v18, v4 offset:52288
	v_fma_mixlo_f16 v4, v23, v10, 0
	ds_write_b16 v18, v4 offset:52352
	v_fma_mixlo_f16 v4, v39, v10, 0
	ds_write_b16 v18, v4 offset:52416
	v_fma_mixlo_f16 v4, v24, v11, 0
	ds_write_b16 v18, v4 offset:52480
	v_fma_mixlo_f16 v4, v40, v11, 0
	ds_write_b16 v18, v4 offset:52544
	v_fma_mixlo_f16 v4, v25, v12, 0
	ds_write_b16 v18, v4 offset:52608
	v_fma_mixlo_f16 v4, v41, v12, 0
	ds_write_b16 v18, v4 offset:52672
	v_fma_mixlo_f16 v4, v26, v13, 0
	ds_write_b16 v18, v4 offset:53248
	v_fma_mixlo_f16 v4, v42, v13, 0
	ds_write_b16 v18, v4 offset:53312
	v_fma_mixlo_f16 v4, v27, v14, 0
	v_rcp_f32_e32 v66, v177
	s_nop 0
	ds_write_b16 v18, v4 offset:53376
	v_fma_mixlo_f16 v4, v43, v14, 0
	ds_write_b16 v18, v4 offset:53440
	v_fma_mixlo_f16 v4, v28, v15, 0
	ds_write_b16 v18, v4 offset:53504
	v_fma_mixlo_f16 v4, v44, v15, 0
	ds_write_b16 v18, v4 offset:53568
	v_fma_mixlo_f16 v4, v29, v16, 0
	ds_write_b16 v18, v4 offset:53632
	v_fma_mixlo_f16 v4, v45, v16, 0
	s_nop 0
	v_rcp_f32_e32 v2, v178
	ds_write_b16 v18, v4 offset:53696
	v_fma_mixlo_f16 v4, v30, v17, 0
	v_rcp_f32_e32 v3, v179
	ds_write_b16 v18, v4 offset:54272
	v_fma_mixlo_f16 v4, v46, v17, 0
	ds_write_b16 v18, v4 offset:54336
	v_fma_mixlo_f16 v4, v31, v66, 0
	ds_write_b16 v18, v4 offset:54400
	v_fma_mixlo_f16 v4, v47, v66, 0
	ds_write_b16 v18, v4 offset:54464
	v_fma_mixlo_f16 v4, v32, v2, 0
	v_fma_mixlo_f16 v2, v48, v2, 0
	ds_write_b16 v18, v2 offset:54592
	v_fma_mixlo_f16 v2, v33, v3, 0
	s_waitcnt vmcnt(3)
; #define GAS __attribute__((address_space(1)))
; __device__ __forceinline__ float siluf(float x) { return x * __builtin_amdgcn_rcpf(1.f + __builtin_amdgcn_exp2f(-1.4426950408889634f * x)); }
; __device__ __forceinline__ unsigned cvtpk_h(float lo, float hi) { f32x2 v = {lo, hi}; h16x2 b = __builtin_convertvector(v, h16x2); return __builtin_bit_cast(unsigned, b); }
; template <int THRL, bool FIXM> __device__ __forceinline__ bool attn_unit(const h16* Qrows, const h16* __restrict__ Kh, const h16* __restrict__ Vh, const int NT, h16* Yrows, const h16* BZrows, char* shm, const int tid, const float mfix, ...
;     ...
;     for (int i = 0; i < 4; ++i) { const int row = i * 8 + (lane >> 3), ch = lane & 7; const h16x8 v = *(const h16x8*)(stg + row * 64 + ch * 8); const h16x8 z = zg[i];
;       u32x4 w; w.x = cvtpk_h((float)v[0] * siluf((float)z[0]), (float)v[1] * siluf((float)z[1])); w.y = cvtpk_h((float)v[2] * siluf((float)z[2]), (float)v[3] * siluf((float)z[3]));
;       w.z = cvtpk_h((float)v[4] * siluf((float)z[4]), (float)v[5] * siluf((float)z[5])); w.w = cvtpk_h((float)v[6] * siluf((float)z[6]), (float)v[7] * siluf((float)z[7]));
;       *(GAS u32x4*)(Yw + (long)row * YP + ch * 8) = w; } }
	v_cvt_f32_f16_e32 v8, v62
	ds_write_b16 v18, v2 offset:54656
	v_fma_mixlo_f16 v2, v49, v3, 0
	ds_write_b16 v18, v4 offset:54528
	ds_write_b16 v18, v2 offset:54720
	v_lshrrev_b32_e32 v10, 3, v249
	v_add_u32_e32 v11, s12, v0
	s_waitcnt lgkmcnt(0)
	v_lshl_add_u64 v[6:7], s[10:11], 0, v[0:1]
	v_lshl_add_u32 v0, v10, 7, v11
	ds_read_b128 v[2:5], v0 offset:51200
	v_mul_f32_e32 v0, 0xbfb8aa3b, v8
	v_exp_f32_e32 v0, v0
	v_cvt_f32_f16_sdwa v9, v62 dst_sel:DWORD dst_unused:UNUSED_PAD src0_sel:WORD_1
	s_mov_b64 s[10:11], 0
	s_waitcnt lgkmcnt(0)
	v_cvt_f32_f16_e32 v14, v2
	v_add_f32_e32 v0, 1.0, v0
	v_rcp_f32_e32 v12, v0
	v_mul_f32_e32 v0, 0xbfb8aa3b, v9
	v_exp_f32_e32 v0, v0
	v_cvt_f32_f16_sdwa v15, v2 dst_sel:DWORD dst_unused:UNUSED_PAD src0_sel:WORD_1
	v_add_f32_e32 v0, 1.0, v0
	v_rcp_f32_e32 v13, v0
	s_nop 0
	v_mul_f32_e32 v8, v12, v8
	v_mul_f32_e32 v9, v13, v9
	s_nop 0
	v_mul_f32_e32 v8, v8, v14
	v_mul_f32_e32 v9, v9, v15
	v_cvt_f32_f16_e32 v14, v3
	v_cvt_pk_f16_f32 v2, v8, v9
	v_cvt_f32_f16_e32 v8, v63
	v_cvt_f32_f16_sdwa v9, v63 dst_sel:DWORD dst_unused:UNUSED_PAD src0_sel:WORD_1
	v_cvt_f32_f16_sdwa v15, v3 dst_sel:DWORD dst_unused:UNUSED_PAD src0_sel:WORD_1
	v_mul_f32_e32 v0, 0xbfb8aa3b, v8
	v_exp_f32_e32 v0, v0
	s_nop 0
	v_add_f32_e32 v0, 1.0, v0
	v_rcp_f32_e32 v12, v0
	v_mul_f32_e32 v0, 0xbfb8aa3b, v9
	v_exp_f32_e32 v0, v0
	s_nop 0
	v_add_f32_e32 v0, 1.0, v0
	v_rcp_f32_e32 v13, v0
	s_nop 0
	v_mul_f32_e32 v8, v12, v8
	v_mul_f32_e32 v9, v13, v9
	s_nop 0
	v_mul_f32_e32 v8, v8, v14
	v_mul_f32_e32 v9, v9, v15
	v_cvt_f32_f16_e32 v14, v4
	v_cvt_pk_f16_f32 v3, v8, v9
	v_cvt_f32_f16_e32 v8, v64
	v_cvt_f32_f16_sdwa v9, v64 dst_sel:DWORD dst_unused:UNUSED_PAD src0_sel:WORD_1
	v_cvt_f32_f16_sdwa v15, v4 dst_sel:DWORD dst_unused:UNUSED_PAD src0_sel:WORD_1
	v_mul_f32_e32 v0, 0xbfb8aa3b, v8
	v_exp_f32_e32 v0, v0
	s_nop 0
	v_add_f32_e32 v0, 1.0, v0
	v_rcp_f32_e32 v12, v0
	v_mul_f32_e32 v0, 0xbfb8aa3b, v9
	v_exp_f32_e32 v0, v0
	s_nop 0
	v_add_f32_e32 v0, 1.0, v0
	v_rcp_f32_e32 v13, v0
	s_nop 0
	v_mul_f32_e32 v8, v12, v8
	v_mul_f32_e32 v9, v13, v9
	s_nop 0
	v_mul_f32_e32 v8, v8, v14
	v_mul_f32_e32 v9, v9, v15
	v_cvt_f32_f16_e32 v14, v5
	v_cvt_pk_f16_f32 v4, v8, v9
	v_cvt_f32_f16_e32 v8, v65
	v_cvt_f32_f16_sdwa v9, v65 dst_sel:DWORD dst_unused:UNUSED_PAD src0_sel:WORD_1
	v_cvt_f32_f16_sdwa v15, v5 dst_sel:DWORD dst_unused:UNUSED_PAD src0_sel:WORD_1
	v_mul_f32_e32 v0, 0xbfb8aa3b, v8
	v_exp_f32_e32 v0, v0
	s_nop 0
	v_add_f32_e32 v0, 1.0, v0
	v_rcp_f32_e32 v12, v0
	v_mul_f32_e32 v0, 0xbfb8aa3b, v9
	v_exp_f32_e32 v0, v0
	s_nop 0
	v_add_f32_e32 v0, 1.0, v0
	v_rcp_f32_e32 v13, v0
	v_lshlrev_b32_e32 v0, 11, v10
	v_mul_f32_e32 v8, v12, v8
	v_mul_f32_e32 v9, v13, v9
	s_nop 0
	v_mul_f32_e32 v8, v8, v14
	v_mul_f32_e32 v9, v9, v15
	s_nop 0
	v_cvt_pk_f16_f32 v5, v8, v9
	v_lshl_add_u64 v[8:9], v[6:7], 0, v[0:1]
	v_or_b32_e32 v0, 8, v10
	global_store_dwordx4 v[8:9], v[2:5], off offset:512 sc1
	s_waitcnt vmcnt(3)
	v_cvt_f32_f16_sdwa v9, v58 dst_sel:DWORD dst_unused:UNUSED_PAD src0_sel:WORD_1
	v_cvt_f32_f16_e32 v8, v58
	v_lshl_add_u32 v2, v0, 7, v11
	ds_read_b128 v[2:5], v2 offset:51200
	v_lshlrev_b32_e32 v0, 11, v0
	v_mul_f32_e32 v12, 0xbfb8aa3b, v8
	v_exp_f32_e32 v12, v12
	s_waitcnt lgkmcnt(0)
	v_cvt_f32_f16_e32 v14, v2
	v_cvt_f32_f16_sdwa v15, v2 dst_sel:DWORD dst_unused:UNUSED_PAD src0_sel:WORD_1
	v_mul_f32_e32 v2, 0xbfb8aa3b, v9
	v_exp_f32_e32 v2, v2
	v_add_f32_e32 v12, 1.0, v12
	v_rcp_f32_e32 v12, v12
	v_add_f32_e32 v2, 1.0, v2
	v_rcp_f32_e32 v13, v2
	s_nop 0
	v_mul_f32_e32 v8, v12, v8
	v_mul_f32_e32 v9, v13, v9
	s_nop 0
	v_mul_f32_e32 v8, v8, v14
	v_mul_f32_e32 v9, v9, v15
	v_cvt_f32_f16_e32 v14, v3
	v_cvt_pk_f16_f32 v2, v8, v9
	v_cvt_f32_f16_sdwa v9, v59 dst_sel:DWORD dst_unused:UNUSED_PAD src0_sel:WORD_1
	v_cvt_f32_f16_e32 v8, v59
	v_cvt_f32_f16_sdwa v15, v3 dst_sel:DWORD dst_unused:UNUSED_PAD src0_sel:WORD_1
	v_mul_f32_e32 v3, 0xbfb8aa3b, v9
	v_mul_f32_e32 v12, 0xbfb8aa3b, v8
	v_exp_f32_e32 v12, v12
	v_exp_f32_e32 v3, v3
	v_add_f32_e32 v12, 1.0, v12
	v_add_f32_e32 v3, 1.0, v3
	v_rcp_f32_e32 v12, v12
	v_rcp_f32_e32 v13, v3
	s_nop 0
	v_mul_f32_e32 v8, v12, v8
	v_mul_f32_e32 v9, v13, v9
	s_nop 0
	v_mul_f32_e32 v8, v8, v14
	v_mul_f32_e32 v9, v9, v15
	v_cvt_f32_f16_e32 v14, v4
	v_cvt_pk_f16_f32 v3, v8, v9
	v_cvt_f32_f16_sdwa v9, v60 dst_sel:DWORD dst_unused:UNUSED_PAD src0_sel:WORD_1
	v_cvt_f32_f16_e32 v8, v60
	v_cvt_f32_f16_sdwa v15, v4 dst_sel:DWORD dst_unused:UNUSED_PAD src0_sel:WORD_1
	v_mul_f32_e32 v4, 0xbfb8aa3b, v9
	v_mul_f32_e32 v12, 0xbfb8aa3b, v8
	v_exp_f32_e32 v12, v12
	v_exp_f32_e32 v4, v4
	v_add_f32_e32 v12, 1.0, v12
	v_add_f32_e32 v4, 1.0, v4
	v_rcp_f32_e32 v12, v12
	v_rcp_f32_e32 v13, v4
	s_nop 0
	v_mul_f32_e32 v8, v12, v8
	v_mul_f32_e32 v9, v13, v9
	s_nop 0
	v_mul_f32_e32 v8, v8, v14
	v_mul_f32_e32 v9, v9, v15
	v_cvt_f32_f16_e32 v14, v5
	v_cvt_pk_f16_f32 v4, v8, v9
	v_cvt_f32_f16_sdwa v9, v61 dst_sel:DWORD dst_unused:UNUSED_PAD src0_sel:WORD_1
	v_cvt_f32_f16_e32 v8, v61
	v_cvt_f32_f16_sdwa v15, v5 dst_sel:DWORD dst_unused:UNUSED_PAD src0_sel:WORD_1
	v_mul_f32_e32 v5, 0xbfb8aa3b, v9
	v_mul_f32_e32 v12, 0xbfb8aa3b, v8
	v_exp_f32_e32 v12, v12
	v_exp_f32_e32 v5, v5
	v_add_f32_e32 v12, 1.0, v12
	v_add_f32_e32 v5, 1.0, v5
	v_rcp_f32_e32 v12, v12
	v_rcp_f32_e32 v13, v5
	s_nop 0
	v_mul_f32_e32 v8, v12, v8
	v_mul_f32_e32 v9, v13, v9
	s_nop 0
	v_mul_f32_e32 v8, v8, v14
	v_mul_f32_e32 v9, v9, v15
	s_nop 0
	v_cvt_pk_f16_f32 v5, v8, v9
	v_lshl_add_u64 v[8:9], v[6:7], 0, v[0:1]
	v_or_b32_e32 v0, 16, v10
	global_store_dwordx4 v[8:9], v[2:5], off offset:512 sc1
	s_waitcnt vmcnt(3)
; #define GAS __attribute__((address_space(1)))
; __device__ __forceinline__ float siluf(float x) { return x * __builtin_amdgcn_rcpf(1.f + __builtin_amdgcn_exp2f(-1.4426950408889634f * x)); }
; __device__ __forceinline__ unsigned cvtpk_h(float lo, float hi) { f32x2 v = {lo, hi}; h16x2 b = __builtin_convertvector(v, h16x2); return __builtin_bit_cast(unsigned, b); }
; template <int THRL, bool FIXM> __device__ __forceinline__ bool attn_unit(const h16* Qrows, const h16* __restrict__ Kh, const h16* __restrict__ Vh, const int NT, h16* Yrows, const h16* BZrows, char* shm, const int tid, const float mfix, ...
;     ...
;     for (int i = 0; i < 4; ++i) { const int row = i * 8 + (lane >> 3), ch = lane & 7; const h16x8 v = *(const h16x8*)(stg + row * 64 + ch * 8); const h16x8 z = zg[i];
;       u32x4 w; w.x = cvtpk_h((float)v[0] * siluf((float)z[0]), (float)v[1] * siluf((float)z[1])); w.y = cvtpk_h((float)v[2] * siluf((float)z[2]), (float)v[3] * siluf((float)z[3]));
;       w.z = cvtpk_h((float)v[4] * siluf((float)z[4]), (float)v[5] * siluf((float)z[5])); w.w = cvtpk_h((float)v[6] * siluf((float)z[6]), (float)v[7] * siluf((float)z[7]));
;       *(GAS u32x4*)(Yw + (long)row * YP + ch * 8) = w; } }
;   asm volatile("s_waitcnt lgkmcnt(0)\n\ts_barrier" ::: "memory");
	v_cvt_f32_f16_sdwa v9, v54 dst_sel:DWORD dst_unused:UNUSED_PAD src0_sel:WORD_1
	v_cvt_f32_f16_e32 v8, v54
	v_lshl_add_u32 v2, v0, 7, v11
	ds_read_b128 v[2:5], v2 offset:51200
	v_lshlrev_b32_e32 v0, 11, v0
	v_mul_f32_e32 v12, 0xbfb8aa3b, v8
	v_exp_f32_e32 v12, v12
	s_waitcnt lgkmcnt(0)
	v_cvt_f32_f16_e32 v14, v2
	v_cvt_f32_f16_sdwa v15, v2 dst_sel:DWORD dst_unused:UNUSED_PAD src0_sel:WORD_1
	v_mul_f32_e32 v2, 0xbfb8aa3b, v9
	v_exp_f32_e32 v2, v2
	v_add_f32_e32 v12, 1.0, v12
	v_rcp_f32_e32 v12, v12
	v_add_f32_e32 v2, 1.0, v2
	v_rcp_f32_e32 v13, v2
	s_nop 0
	v_mul_f32_e32 v8, v12, v8
	v_mul_f32_e32 v9, v13, v9
	s_nop 0
	v_mul_f32_e32 v8, v8, v14
	v_mul_f32_e32 v9, v9, v15
	v_cvt_f32_f16_e32 v14, v3
	v_cvt_pk_f16_f32 v2, v8, v9
	v_cvt_f32_f16_sdwa v9, v55 dst_sel:DWORD dst_unused:UNUSED_PAD src0_sel:WORD_1
	v_cvt_f32_f16_e32 v8, v55
	v_cvt_f32_f16_sdwa v15, v3 dst_sel:DWORD dst_unused:UNUSED_PAD src0_sel:WORD_1
	v_mul_f32_e32 v3, 0xbfb8aa3b, v9
	v_mul_f32_e32 v12, 0xbfb8aa3b, v8
	v_exp_f32_e32 v12, v12
	v_exp_f32_e32 v3, v3
	v_add_f32_e32 v12, 1.0, v12
	v_add_f32_e32 v3, 1.0, v3
	v_rcp_f32_e32 v12, v12
	v_rcp_f32_e32 v13, v3
	s_nop 0
	v_mul_f32_e32 v8, v12, v8
	v_mul_f32_e32 v9, v13, v9
	s_nop 0
	v_mul_f32_e32 v8, v8, v14
	v_mul_f32_e32 v9, v9, v15
	v_cvt_f32_f16_e32 v14, v4
	v_cvt_pk_f16_f32 v3, v8, v9
	v_cvt_f32_f16_sdwa v9, v56 dst_sel:DWORD dst_unused:UNUSED_PAD src0_sel:WORD_1
	v_cvt_f32_f16_e32 v8, v56
	v_cvt_f32_f16_sdwa v15, v4 dst_sel:DWORD dst_unused:UNUSED_PAD src0_sel:WORD_1
	v_mul_f32_e32 v4, 0xbfb8aa3b, v9
	v_mul_f32_e32 v12, 0xbfb8aa3b, v8
	v_exp_f32_e32 v12, v12
	v_exp_f32_e32 v4, v4
	v_add_f32_e32 v12, 1.0, v12
	v_add_f32_e32 v4, 1.0, v4
	v_rcp_f32_e32 v12, v12
	v_rcp_f32_e32 v13, v4
	s_nop 0
	v_mul_f32_e32 v8, v12, v8
	v_mul_f32_e32 v9, v13, v9
	s_nop 0
	v_mul_f32_e32 v8, v8, v14
	v_mul_f32_e32 v9, v9, v15
	v_cvt_f32_f16_e32 v14, v5
	v_cvt_pk_f16_f32 v4, v8, v9
	v_cvt_f32_f16_sdwa v9, v57 dst_sel:DWORD dst_unused:UNUSED_PAD src0_sel:WORD_1
	v_cvt_f32_f16_e32 v8, v57
	v_cvt_f32_f16_sdwa v15, v5 dst_sel:DWORD dst_unused:UNUSED_PAD src0_sel:WORD_1
	v_mul_f32_e32 v5, 0xbfb8aa3b, v9
	v_mul_f32_e32 v12, 0xbfb8aa3b, v8
	v_exp_f32_e32 v12, v12
	v_exp_f32_e32 v5, v5
	v_add_f32_e32 v12, 1.0, v12
	v_add_f32_e32 v5, 1.0, v5
	v_rcp_f32_e32 v12, v12
	v_rcp_f32_e32 v13, v5
	s_nop 0
	v_mul_f32_e32 v8, v12, v8
	v_mul_f32_e32 v9, v13, v9
	s_nop 0
	v_mul_f32_e32 v8, v8, v14
	v_mul_f32_e32 v9, v9, v15
	s_nop 0
	v_cvt_pk_f16_f32 v5, v8, v9
	v_lshl_add_u64 v[8:9], v[6:7], 0, v[0:1]
	v_or_b32_e32 v0, 24, v10
	global_store_dwordx4 v[8:9], v[2:5], off offset:512 sc1
	s_waitcnt vmcnt(3)
	v_cvt_f32_f16_sdwa v9, v50 dst_sel:DWORD dst_unused:UNUSED_PAD src0_sel:WORD_1
	v_cvt_f32_f16_e32 v8, v50
	v_lshl_add_u32 v2, v0, 7, v11
	ds_read_b128 v[2:5], v2 offset:51200
	v_lshlrev_b32_e32 v0, 11, v0
	v_mul_f32_e32 v10, 0xbfb8aa3b, v8
	v_exp_f32_e32 v10, v10
	v_lshl_add_u64 v[6:7], v[6:7], 0, v[0:1]
	s_waitcnt lgkmcnt(0)
	v_cvt_f32_f16_e32 v12, v2
	v_cvt_f32_f16_sdwa v13, v2 dst_sel:DWORD dst_unused:UNUSED_PAD src0_sel:WORD_1
	v_mul_f32_e32 v2, 0xbfb8aa3b, v9
	v_exp_f32_e32 v2, v2
	v_add_f32_e32 v10, 1.0, v10
	v_rcp_f32_e32 v10, v10
	v_add_f32_e32 v2, 1.0, v2
	v_rcp_f32_e32 v11, v2
	s_nop 0
	v_mul_f32_e32 v8, v10, v8
	v_mul_f32_e32 v9, v11, v9
	s_nop 0
	v_mul_f32_e32 v8, v8, v12
	v_mul_f32_e32 v9, v9, v13
	v_cvt_f32_f16_e32 v12, v3
	v_cvt_pk_f16_f32 v2, v8, v9
	v_cvt_f32_f16_sdwa v9, v51 dst_sel:DWORD dst_unused:UNUSED_PAD src0_sel:WORD_1
	v_cvt_f32_f16_e32 v8, v51
	v_cvt_f32_f16_sdwa v13, v3 dst_sel:DWORD dst_unused:UNUSED_PAD src0_sel:WORD_1
	v_mul_f32_e32 v3, 0xbfb8aa3b, v9
	v_mul_f32_e32 v10, 0xbfb8aa3b, v8
	v_exp_f32_e32 v10, v10
	v_exp_f32_e32 v3, v3
	v_add_f32_e32 v10, 1.0, v10
	v_add_f32_e32 v3, 1.0, v3
	v_rcp_f32_e32 v10, v10
	v_rcp_f32_e32 v11, v3
	s_nop 0
	v_mul_f32_e32 v8, v10, v8
	v_mul_f32_e32 v9, v11, v9
	s_nop 0
	v_mul_f32_e32 v8, v8, v12
	v_mul_f32_e32 v9, v9, v13
	v_cvt_f32_f16_e32 v12, v4
	v_cvt_pk_f16_f32 v3, v8, v9
	v_cvt_f32_f16_sdwa v9, v52 dst_sel:DWORD dst_unused:UNUSED_PAD src0_sel:WORD_1
	v_cvt_f32_f16_e32 v8, v52
	v_cvt_f32_f16_sdwa v13, v4 dst_sel:DWORD dst_unused:UNUSED_PAD src0_sel:WORD_1
	v_mul_f32_e32 v4, 0xbfb8aa3b, v9
	v_mul_f32_e32 v10, 0xbfb8aa3b, v8
	v_exp_f32_e32 v10, v10
	v_exp_f32_e32 v4, v4
	v_add_f32_e32 v10, 1.0, v10
	v_add_f32_e32 v4, 1.0, v4
	v_rcp_f32_e32 v10, v10
	v_rcp_f32_e32 v11, v4
	s_nop 0
	v_mul_f32_e32 v8, v10, v8
	v_mul_f32_e32 v9, v11, v9
	s_nop 0
	v_mul_f32_e32 v8, v8, v12
	v_mul_f32_e32 v9, v9, v13
	v_cvt_f32_f16_e32 v12, v5
	v_cvt_pk_f16_f32 v4, v8, v9
	v_cvt_f32_f16_sdwa v9, v53 dst_sel:DWORD dst_unused:UNUSED_PAD src0_sel:WORD_1
	v_cvt_f32_f16_e32 v8, v53
	v_cvt_f32_f16_sdwa v13, v5 dst_sel:DWORD dst_unused:UNUSED_PAD src0_sel:WORD_1
	v_mul_f32_e32 v5, 0xbfb8aa3b, v9
	v_mul_f32_e32 v10, 0xbfb8aa3b, v8
	v_exp_f32_e32 v10, v10
	v_exp_f32_e32 v5, v5
	v_add_f32_e32 v10, 1.0, v10
	v_add_f32_e32 v5, 1.0, v5
	v_rcp_f32_e32 v10, v10
	v_rcp_f32_e32 v11, v5
	s_nop 0
	v_mul_f32_e32 v8, v10, v8
	v_mul_f32_e32 v9, v11, v9
	s_nop 0
	v_mul_f32_e32 v8, v8, v12
	v_mul_f32_e32 v9, v9, v13
	s_nop 0
	v_cvt_pk_f16_f32 v5, v8, v9
	global_store_dwordx4 v[6:7], v[2:5], off offset:512 sc1
	s_waitcnt lgkmcnt(0)
	s_barrier

; #define WAIT_BAR(N) asm volatile("s_waitcnt vmcnt(" #N ") lgkmcnt(0)\n\ts_barrier" ::: "memory")
; #define RESC() do { if (!FIXM && resc) { asm volatile("s_waitcnt lgkmcnt(0)" ::: "memory"); \
;       _Pragma("unroll") for (int d_ = 0; d_ < 2; ++d_) _Pragma("unroll") for (int r = 0; r < 16; ++r) o[d_][r] *= wsf[crow(r, hi)]; } } while (0)
; #define ROT() do { sl_prev = sl_cur; sl_cur = sl_next; sl_next = (sl_next == (NSLOT - 1) * SLOTB) ? 0 : sl_next + SLOTB; } while (0)
; template <int THRL, bool FIXM> __device__ __forceinline__ bool attn_unit(const h16* Qrows, const h16* __restrict__ Kh, const h16* __restrict__ Vh, const int NT, h16* Yrows, const h16* BZrows, char* shm, const int tid, const float mfix, ...
;     ...
;   int t = 1;
;   for (; t + 5 < NT; t += 2) {
;     STEP(pB0, pB1, pA0, pA1, t, true, true, true);     WAIT_BAR(2); RESC(); ROT();
.LBB0_150:
	s_waitcnt lgkmcnt(14)
	v_mfma_f32_32x32x16_f16 v[18:33], v[144:147], v[180:183], v[18:33]
	v_exp_f32_e32 v98, v98
	v_exp_f32_e32 v99, v99
	v_exp_f32_e32 v100, v100
	v_exp_f32_e32 v101, v101
	s_waitcnt lgkmcnt(12)
	v_mfma_f32_32x32x16_f16 v[2:17], v[144:147], v[176:179], v[2:17]
	v_exp_f32_e32 v102, v102
	v_exp_f32_e32 v103, v103
	v_exp_f32_e32 v104, v104
	v_exp_f32_e32 v105, v105
	v_add_u32_e32 v78, s43, v193
	ds_read_b128 v[62:65], v78
	ds_read_b128 v[176:179], v78 offset:512
	s_waitcnt lgkmcnt(12)
	v_mfma_f32_32x32x16_f16 v[18:33], v[140:143], v[66:69], v[18:33]
	v_exp_f32_e32 v106, v106
	v_exp_f32_e32 v107, v107
	v_exp_f32_e32 v108, v108
	v_exp_f32_e32 v109, v109
	ds_read_b128 v[180:183], v78 offset:2048
	ds_read_b128 v[172:175], v78 offset:2560
	s_waitcnt lgkmcnt(12)
	v_mfma_f32_32x32x16_f16 v[2:17], v[140:143], v[70:73], v[2:17]
	v_exp_f32_e32 v110, v110
	v_exp_f32_e32 v111, v111
	v_exp_f32_e32 v112, v112
	v_exp_f32_e32 v113, v113
	ds_read_b128 v[168:171], v78 offset:4096
	ds_read_b128 v[164:167], v78 offset:4608
	s_waitcnt lgkmcnt(12)
	v_mfma_f32_32x32x16_f16 v[18:33], v[132:135], v[74:77], v[18:33]
	v_exp_f32_e32 v82, v82
	v_exp_f32_e32 v83, v83
	v_exp_f32_e32 v84, v84
	v_exp_f32_e32 v85, v85
	ds_read_b128 v[160:163], v78 offset:6144
	ds_read_b128 v[156:159], v78 offset:6656
	s_waitcnt lgkmcnt(12)
	v_mfma_f32_32x32x16_f16 v[2:17], v[132:135], v[50:53], v[2:17]
	v_exp_f32_e32 v86, v86
	v_exp_f32_e32 v87, v87
	v_exp_f32_e32 v88, v88
	v_exp_f32_e32 v89, v89
	s_waitcnt lgkmcnt(10)
	v_mfma_f32_32x32x16_f16 v[18:33], v[122:125], v[54:57], v[18:33]
	v_exp_f32_e32 v90, v90
	v_exp_f32_e32 v91, v91
	v_exp_f32_e32 v92, v92
	v_exp_f32_e32 v93, v93
	s_waitcnt lgkmcnt(8)
	v_mfma_f32_32x32x16_f16 v[2:17], v[122:125], v[58:61], v[2:17]
	v_exp_f32_e32 v94, v94
	v_exp_f32_e32 v95, v95
	v_exp_f32_e32 v96, v96
	v_exp_f32_e32 v97, v97
	s_waitcnt vmcnt(2) lgkmcnt(0)
	s_barrier
	v_add_u32_e32 v50, s49, v0
	s_andn2_b64 vcc, exec, s[14:15]
	v_add_u32_e32 v197, 0xc000, v50
	v_add_u32_e32 v199, 0xc008, v50
	v_add_u32_e32 v200, 0xc020, v50
	v_add_u32_e32 v201, 0xc028, v50
	v_add_u32_e32 v215, 0xc040, v50
	v_add_u32_e32 v216, 0xc048, v50
	v_add_u32_e32 v217, 0xc060, v50
	v_add_u32_e32 v218, 0xc068, v50
	s_cbranch_vccnz .LBB0_152
	s_waitcnt lgkmcnt(0)
	ds_read2_b32 v[50:51], v215 offset1:1
	ds_read2_b32 v[52:53], v216 offset1:1
	ds_read2_b32 v[54:55], v217 offset1:1
	ds_read2_b32 v[56:57], v218 offset1:1
	ds_read2_b32 v[58:59], v197 offset1:1
	ds_read2_b32 v[60:61], v199 offset1:1
	ds_read2_b32 v[66:67], v200 offset1:1
	ds_read2_b32 v[68:69], v201 offset1:1
	s_waitcnt lgkmcnt(4)
	v_mul_f32_e32 v32, v32, v56
	v_mul_f32_e32 v33, v33, v57
	v_mul_f32_e32 v30, v30, v54
	v_mul_f32_e32 v31, v31, v55
	v_mul_f32_e32 v28, v28, v52
	v_mul_f32_e32 v29, v29, v53
	v_mul_f32_e32 v26, v26, v50
	v_mul_f32_e32 v27, v27, v51
	s_waitcnt lgkmcnt(0)
	v_mul_f32_e32 v24, v24, v68
	v_mul_f32_e32 v25, v25, v69
	v_mul_f32_e32 v22, v22, v66
	v_mul_f32_e32 v23, v23, v67
	v_mul_f32_e32 v20, v20, v60
	v_mul_f32_e32 v21, v21, v61
	v_mul_f32_e32 v18, v18, v58
	v_mul_f32_e32 v19, v19, v59
	v_mul_f32_e32 v16, v16, v56
	v_mul_f32_e32 v17, v17, v57
	v_mul_f32_e32 v14, v14, v54
	v_mul_f32_e32 v15, v15, v55
	v_mul_f32_e32 v12, v12, v52
	v_mul_f32_e32 v13, v13, v53
	v_mul_f32_e32 v10, v10, v50
	v_mul_f32_e32 v11, v11, v51
	v_mul_f32_e32 v8, v8, v68
	v_mul_f32_e32 v9, v9, v69
	v_mul_f32_e32 v6, v6, v66
	v_mul_f32_e32 v7, v7, v67
	v_mul_f32_e32 v4, v4, v60
	v_mul_f32_e32 v5, v5, v61
	v_mul_f32_e32 v2, v2, v58
	v_mul_f32_e32 v3, v3, v59

; #define WAIT_BAR(N) asm volatile("s_waitcnt vmcnt(" #N ") lgkmcnt(0)\n\ts_barrier" ::: "memory")
; #define RESC() do { if (!FIXM && resc) { asm volatile("s_waitcnt lgkmcnt(0)" ::: "memory"); \
;       _Pragma("unroll") for (int d_ = 0; d_ < 2; ++d_) _Pragma("unroll") for (int r = 0; r < 16; ++r) o[d_][r] *= wsf[crow(r, hi)]; } } while (0)
; #define ROT() do { sl_prev = sl_cur; sl_cur = sl_next; sl_next = (sl_next == (NSLOT - 1) * SLOTB) ? 0 : sl_next + SLOTB; } while (0)
; template <int THRL, bool FIXM> __device__ __forceinline__ bool attn_unit(const h16* Qrows, const h16* __restrict__ Kh, const h16* __restrict__ Vh, const int NT, h16* Yrows, const h16* BZrows, char* shm, const int tid, const float mfix, ...
;     ...
;   int t = 1;
;   for (; t + 5 < NT; t += 2) {
;     STEP(pB0, pB1, pA0, pA1, t, true, true, true);     WAIT_BAR(2); RESC(); ROT();
;     STEP(pA0, pA1, pB0, pB1, t + 1, true, true, true); WAIT_BAR(2); RESC(); ROT();
.LBB0_153:
	s_waitcnt lgkmcnt(14)
	v_mfma_f32_32x32x16_f16 v[18:33], v[144:147], v[152:155], v[18:33]
	v_exp_f32_e32 v66, v66
	v_exp_f32_e32 v67, v67
	v_exp_f32_e32 v68, v68
	v_exp_f32_e32 v69, v69
	s_waitcnt lgkmcnt(12)
	v_mfma_f32_32x32x16_f16 v[2:17], v[144:147], v[148:151], v[2:17]
	v_exp_f32_e32 v70, v70
	v_exp_f32_e32 v71, v71
	v_exp_f32_e32 v72, v72
	v_exp_f32_e32 v73, v73
	v_add_u32_e32 v94, s17, v193
	ds_read_b128 v[176:179], v94
	ds_read_b128 v[172:175], v94 offset:512
	s_waitcnt lgkmcnt(12)
	v_mfma_f32_32x32x16_f16 v[18:33], v[140:143], v[98:101], v[18:33]
	v_exp_f32_e32 v74, v74
	v_exp_f32_e32 v75, v75
	v_exp_f32_e32 v76, v76
	v_exp_f32_e32 v77, v77
	ds_read_b128 v[168:171], v94 offset:2048
	ds_read_b128 v[164:167], v94 offset:2560
	s_waitcnt lgkmcnt(12)
	v_mfma_f32_32x32x16_f16 v[2:17], v[140:143], v[102:105], v[2:17]
	v_exp_f32_e32 v78, v78
	v_exp_f32_e32 v79, v79
	v_exp_f32_e32 v80, v80
	v_exp_f32_e32 v81, v81
	ds_read_b128 v[160:163], v94 offset:4096
	ds_read_b128 v[156:159], v94 offset:4608
	s_waitcnt lgkmcnt(12)
	v_mfma_f32_32x32x16_f16 v[18:33], v[132:135], v[106:109], v[18:33]
	v_exp_f32_e32 v50, v50
	v_exp_f32_e32 v51, v51
	v_exp_f32_e32 v52, v52
	v_exp_f32_e32 v53, v53
	ds_read_b128 v[152:155], v94 offset:6144
	ds_read_b128 v[148:151], v94 offset:6656
	s_waitcnt lgkmcnt(12)
	v_mfma_f32_32x32x16_f16 v[2:17], v[132:135], v[82:85], v[2:17]
	v_exp_f32_e32 v54, v54
	v_exp_f32_e32 v55, v55
	v_exp_f32_e32 v56, v56
	v_exp_f32_e32 v57, v57
	s_waitcnt lgkmcnt(10)
	v_mfma_f32_32x32x16_f16 v[18:33], v[122:125], v[86:89], v[18:33]
	v_exp_f32_e32 v58, v58
	v_exp_f32_e32 v59, v59
	v_exp_f32_e32 v60, v60
	v_exp_f32_e32 v61, v61
	s_waitcnt lgkmcnt(8)
	v_mfma_f32_32x32x16_f16 v[2:17], v[122:125], v[90:93], v[2:17]
	v_exp_f32_e32 v62, v62
	v_exp_f32_e32 v63, v63
	v_exp_f32_e32 v64, v64
	v_exp_f32_e32 v65, v65
	s_waitcnt vmcnt(2) lgkmcnt(0)
	s_barrier
	s_andn2_b64 vcc, exec, s[14:15]
	s_cbranch_vccnz .LBB0_155
	s_waitcnt lgkmcnt(0)
	ds_read2_b32 v[82:83], v215 offset1:1
	ds_read2_b32 v[84:85], v216 offset1:1
	ds_read2_b32 v[86:87], v217 offset1:1
	ds_read2_b32 v[88:89], v218 offset1:1
	ds_read2_b32 v[90:91], v197 offset1:1
	ds_read2_b32 v[92:93], v199 offset1:1
	ds_read2_b32 v[94:95], v200 offset1:1
	ds_read2_b32 v[96:97], v201 offset1:1
	s_waitcnt lgkmcnt(4)
	v_mul_f32_e32 v32, v32, v88
	v_mul_f32_e32 v33, v33, v89
	v_mul_f32_e32 v30, v30, v86
	v_mul_f32_e32 v31, v31, v87
	v_mul_f32_e32 v28, v28, v84
	v_mul_f32_e32 v29, v29, v85
	v_mul_f32_e32 v26, v26, v82
	v_mul_f32_e32 v27, v27, v83
	s_waitcnt lgkmcnt(0)
	v_mul_f32_e32 v24, v24, v96
	v_mul_f32_e32 v25, v25, v97
	v_mul_f32_e32 v22, v22, v94
	v_mul_f32_e32 v23, v23, v95
	v_mul_f32_e32 v20, v20, v92
	v_mul_f32_e32 v21, v21, v93
	v_mul_f32_e32 v18, v18, v90
	v_mul_f32_e32 v19, v19, v91
	v_mul_f32_e32 v16, v16, v88
	v_mul_f32_e32 v17, v17, v89
	v_mul_f32_e32 v14, v14, v86
	v_mul_f32_e32 v15, v15, v87
	v_mul_f32_e32 v12, v12, v84
	v_mul_f32_e32 v13, v13, v85
	v_mul_f32_e32 v10, v10, v82
	v_mul_f32_e32 v11, v11, v83
	v_mul_f32_e32 v8, v8, v96
	v_mul_f32_e32 v9, v9, v97
	v_mul_f32_e32 v6, v6, v94
	v_mul_f32_e32 v7, v7, v95
	v_mul_f32_e32 v4, v4, v92
	v_mul_f32_e32 v5, v5, v93
	v_mul_f32_e32 v2, v2, v90
	v_mul_f32_e32 v3, v3, v91

.LBB0_180:
	v_add_u32_e32 v50, s49, v0
	s_andn2_b64 vcc, exec, s[2:3]
	v_add_u32_e32 v214, 0xc000, v50
	v_add_u32_e32 v215, 0xc008, v50
	v_add_u32_e32 v218, 0xc020, v50
	v_add_u32_e32 v219, 0xc028, v50
	v_add_u32_e32 v220, 0xc040, v50
	v_add_u32_e32 v221, 0xc048, v50
	v_add_u32_e32 v222, 0xc060, v50
	v_add_u32_e32 v223, 0xc068, v50
	s_cbranch_vccnz .LBB0_182
	s_waitcnt lgkmcnt(0)
	ds_read2_b32 v[50:51], v220 offset1:1
	ds_read2_b32 v[52:53], v221 offset1:1
	ds_read2_b32 v[54:55], v222 offset1:1
	ds_read2_b32 v[56:57], v223 offset1:1
	ds_read2_b32 v[58:59], v214 offset1:1
	ds_read2_b32 v[60:61], v215 offset1:1
	ds_read2_b32 v[62:63], v218 offset1:1
	ds_read2_b32 v[64:65], v219 offset1:1
	s_waitcnt lgkmcnt(4)
	v_mul_f32_e32 v32, v32, v56
	v_mul_f32_e32 v33, v33, v57
	v_mul_f32_e32 v30, v30, v54
	v_mul_f32_e32 v31, v31, v55
	v_mul_f32_e32 v28, v28, v52
	v_mul_f32_e32 v29, v29, v53
	v_mul_f32_e32 v26, v26, v50
	v_mul_f32_e32 v27, v27, v51
	s_waitcnt lgkmcnt(0)
	v_mul_f32_e32 v24, v24, v64
	v_mul_f32_e32 v25, v25, v65
	v_mul_f32_e32 v22, v22, v62
	v_mul_f32_e32 v23, v23, v63
	v_mul_f32_e32 v20, v20, v60
	v_mul_f32_e32 v21, v21, v61
	v_mul_f32_e32 v18, v18, v58
	v_mul_f32_e32 v19, v19, v59
	v_mul_f32_e32 v16, v16, v56
	v_mul_f32_e32 v17, v17, v57
	v_mul_f32_e32 v14, v14, v54
	v_mul_f32_e32 v15, v15, v55
	v_mul_f32_e32 v12, v12, v52
	v_mul_f32_e32 v13, v13, v53
	v_mul_f32_e32 v10, v10, v50
	v_mul_f32_e32 v11, v11, v51
	v_mul_f32_e32 v8, v8, v64
	v_mul_f32_e32 v9, v9, v65
	v_mul_f32_e32 v6, v6, v62
	v_mul_f32_e32 v7, v7, v63
	v_mul_f32_e32 v4, v4, v60
	v_mul_f32_e32 v5, v5, v61
	v_mul_f32_e32 v2, v2, v58
	v_mul_f32_e32 v3, v3, v59

.LBB0_198:
	s_waitcnt lgkmcnt(0)
	ds_read2_b32 v[82:83], v220 offset1:1
	ds_read2_b32 v[84:85], v221 offset1:1
	ds_read2_b32 v[86:87], v222 offset1:1
	ds_read2_b32 v[88:89], v223 offset1:1
	ds_read2_b32 v[90:91], v214 offset1:1
	ds_read2_b32 v[92:93], v215 offset1:1
	ds_read2_b32 v[94:95], v218 offset1:1
	ds_read2_b32 v[96:97], v219 offset1:1
	s_waitcnt lgkmcnt(4)
	v_mul_f32_e32 v32, v32, v88
	v_mul_f32_e32 v33, v33, v89
	v_mul_f32_e32 v30, v30, v86
	v_mul_f32_e32 v31, v31, v87
	v_mul_f32_e32 v28, v28, v84
	v_mul_f32_e32 v29, v29, v85
	v_mul_f32_e32 v26, v26, v82
	v_mul_f32_e32 v27, v27, v83
	s_waitcnt lgkmcnt(0)
	v_mul_f32_e32 v24, v24, v96
	v_mul_f32_e32 v25, v25, v97
	v_mul_f32_e32 v22, v22, v94
	v_mul_f32_e32 v23, v23, v95
	v_mul_f32_e32 v20, v20, v92
	v_mul_f32_e32 v21, v21, v93
	v_mul_f32_e32 v18, v18, v90
	v_mul_f32_e32 v19, v19, v91
	v_mul_f32_e32 v16, v16, v88
	v_mul_f32_e32 v17, v17, v89
	v_mul_f32_e32 v14, v14, v86
	v_mul_f32_e32 v15, v15, v87
	v_mul_f32_e32 v12, v12, v84
	v_mul_f32_e32 v13, v13, v85
	v_mul_f32_e32 v10, v10, v82
	v_mul_f32_e32 v11, v11, v83
	v_mul_f32_e32 v8, v8, v96
	v_mul_f32_e32 v9, v9, v97
	v_mul_f32_e32 v6, v6, v94
	v_mul_f32_e32 v7, v7, v95
	v_mul_f32_e32 v4, v4, v92
	v_mul_f32_e32 v5, v5, v93
	v_mul_f32_e32 v2, v2, v90
	v_mul_f32_e32 v3, v3, v91

; #define SBAR() __builtin_amdgcn_sched_barrier(0)
; #define RESC() do { if (!FIXM && resc) { asm volatile("s_waitcnt lgkmcnt(0)" ::: "memory"); \
;       _Pragma("unroll") for (int d_ = 0; d_ < 2; ++d_) _Pragma("unroll") for (int r = 0; r < 16; ++r) o[d_][r] *= wsf[crow(r, hi)]; } } while (0)
; #define PKW(P, B) cvtpk_h(P[B], P[B + 1])
; #define PKW(P, B) cvtpk_h(P[B], P[B + 1])
; template <int THRL, bool FIXM> __device__ __forceinline__ bool attn_unit(const h16* Qrows, const h16* __restrict__ Kh, const h16* __restrict__ Vh, const int NT, h16* Yrows, const h16* BZrows, char* shm, const int tid, const float mfix, ...
;     ...
;   STEP(pB0, pB1, pA0, pA1, NT - 1, false, false, false); RESC();
;   { float sacc = pB0[0] + pB0[1]; _Pragma("unroll") for (int r = 2; r < 16; ++r) sacc += pB0[r]; _Pragma("unroll") for (int r = 0; r < 16; ++r) sacc += pB1[r]; l_reg += sacc;
;     pw0 = (u32x4){PKW(pB0, 0), PKW(pB0, 2), PKW(pB0, 4), PKW(pB0, 6)}; pw1 = (u32x4){PKW(pB0, 8), PKW(pB0, 10), PKW(pB0, 12), PKW(pB0, 14)}; pw2 = (u32x4){PKW(pB1, 0), PKW(pB1, 2), PKW(pB1, 4), PKW(pB1, 6)}; pw3 = (u32x4){PKW(pB1, 8), PKW(pB1, 10), PKW(pB1, 12), PKW(pB1, 14)};
;     SBAR(); pv(o, vb0 + sl_cur, __builtin_bit_cast(s16x8, pw0), __builtin_bit_cast(s16x8, pw1), __builtin_bit_cast(s16x8, pw2), __builtin_bit_cast(s16x8, pw3)); }
.LBB0_222:
	s_waitcnt lgkmcnt(14)
	v_mfma_f32_32x32x16_f16 v[18:33], v[144:147], v[98:101], v[18:33]
	v_exp_f32_e32 v82, v82
	v_exp_f32_e32 v83, v83
	v_exp_f32_e32 v84, v84
	v_exp_f32_e32 v85, v85
	s_waitcnt lgkmcnt(12)
	v_mfma_f32_32x32x16_f16 v[2:17], v[144:147], v[66:69], v[2:17]
	v_exp_f32_e32 v86, v86
	v_exp_f32_e32 v87, v87
	v_exp_f32_e32 v88, v88
	v_exp_f32_e32 v89, v89
	s_waitcnt lgkmcnt(10)
	v_mfma_f32_32x32x16_f16 v[18:33], v[140:143], v[70:73], v[18:33]
	v_exp_f32_e32 v90, v90
	v_exp_f32_e32 v91, v91
	v_exp_f32_e32 v92, v92
	v_exp_f32_e32 v93, v93
	s_waitcnt lgkmcnt(8)
	v_mfma_f32_32x32x16_f16 v[2:17], v[140:143], v[74:77], v[2:17]
	v_exp_f32_e32 v94, v94
	v_exp_f32_e32 v95, v95
	v_exp_f32_e32 v96, v96
	v_exp_f32_e32 v97, v97
	s_waitcnt lgkmcnt(6)
	v_mfma_f32_32x32x16_f16 v[18:33], v[132:135], v[78:81], v[18:33]
	v_exp_f32_e32 v34, v34
	v_exp_f32_e32 v35, v35
	v_exp_f32_e32 v36, v36
	v_exp_f32_e32 v37, v37
	s_waitcnt lgkmcnt(4)
	v_mfma_f32_32x32x16_f16 v[2:17], v[132:135], v[102:105], v[2:17]
	v_exp_f32_e32 v38, v38
	v_exp_f32_e32 v39, v39
	v_exp_f32_e32 v40, v40
	v_exp_f32_e32 v41, v41
	s_waitcnt lgkmcnt(2)
	v_mfma_f32_32x32x16_f16 v[18:33], v[122:125], v[106:109], v[18:33]
	v_exp_f32_e32 v42, v42
	v_exp_f32_e32 v43, v43
	v_exp_f32_e32 v44, v44
	v_exp_f32_e32 v45, v45
	s_waitcnt lgkmcnt(0)
	v_mfma_f32_32x32x16_f16 v[2:17], v[122:125], v[110:113], v[2:17]
	v_exp_f32_e32 v46, v46
	v_exp_f32_e32 v47, v47
	v_exp_f32_e32 v48, v48
	v_exp_f32_e32 v49, v49
	s_andn2_b64 vcc, exec, s[0:1]
	v_lshl_add_u32 v50, v248, 4, s49
	s_cbranch_vccnz .LBB0_224
	s_waitcnt lgkmcnt(0)
	v_add_u32_e32 v64, 0xc020, v50
	v_add_u32_e32 v66, 0xc028, v50
	v_add_u32_e32 v52, 0xc040, v50
	v_add_u32_e32 v54, 0xc048, v50
	v_add_u32_e32 v56, 0xc060, v50
	v_add_u32_e32 v58, 0xc068, v50
	v_add_u32_e32 v0, 0xc000, v50
	v_add_u32_e32 v51, 0xc008, v50
	ds_read2_b32 v[52:53], v52 offset1:1
	ds_read2_b32 v[54:55], v54 offset1:1
	ds_read2_b32 v[56:57], v56 offset1:1
	ds_read2_b32 v[58:59], v58 offset1:1
	ds_read2_b32 v[60:61], v0 offset1:1
	ds_read2_b32 v[62:63], v51 offset1:1
	ds_read2_b32 v[64:65], v64 offset1:1
	ds_read2_b32 v[66:67], v66 offset1:1
	s_waitcnt lgkmcnt(4)
	v_mul_f32_e32 v32, v32, v58
	v_mul_f32_e32 v33, v33, v59
	v_mul_f32_e32 v30, v30, v56
	v_mul_f32_e32 v31, v31, v57
	v_mul_f32_e32 v28, v28, v54
	v_mul_f32_e32 v29, v29, v55
	v_mul_f32_e32 v26, v26, v52
	v_mul_f32_e32 v27, v27, v53
	s_waitcnt lgkmcnt(0)
	v_mul_f32_e32 v24, v24, v66
	v_mul_f32_e32 v25, v25, v67
	v_mul_f32_e32 v22, v22, v64
	v_mul_f32_e32 v23, v23, v65
	v_mul_f32_e32 v20, v20, v62
	v_mul_f32_e32 v21, v21, v63
	v_mul_f32_e32 v18, v18, v60
	v_mul_f32_e32 v19, v19, v61
	v_mul_f32_e32 v16, v16, v58
	v_mul_f32_e32 v17, v17, v59
	v_mul_f32_e32 v14, v14, v56
	v_mul_f32_e32 v15, v15, v57
	v_mul_f32_e32 v12, v12, v54
	v_mul_f32_e32 v13, v13, v55
	v_mul_f32_e32 v10, v10, v52
	v_mul_f32_e32 v11, v11, v53
	v_mul_f32_e32 v8, v8, v66
	v_mul_f32_e32 v9, v9, v67
	v_mul_f32_e32 v6, v6, v64
	v_mul_f32_e32 v7, v7, v65
	v_mul_f32_e32 v4, v4, v62
	v_mul_f32_e32 v5, v5, v63
	v_mul_f32_e32 v2, v2, v60
	v_mul_f32_e32 v3, v3, v61
.LBB0_224:
	v_add_f32_e32 v0, v82, v83
	v_add_f32_e32 v0, v84, v0
	v_add_f32_e32 v0, v85, v0
	v_add_f32_e32 v0, v86, v0
	v_add_f32_e32 v0, v87, v0
	v_add_f32_e32 v0, v88, v0
	v_add_f32_e32 v0, v89, v0
	v_add_f32_e32 v0, v90, v0
	v_add_f32_e32 v0, v91, v0
	v_add_f32_e32 v0, v92, v0
	v_add_f32_e32 v0, v93, v0
	v_add_f32_e32 v0, v94, v0
	v_add_f32_e32 v0, v95, v0
	v_add_f32_e32 v0, v96, v0
	v_add_f32_e32 v0, v97, v0
	v_add_f32_e32 v0, v34, v0
	v_add_f32_e32 v0, v35, v0
	v_add_f32_e32 v0, v36, v0
	v_add_f32_e32 v0, v37, v0
	v_add_f32_e32 v0, v38, v0
	v_add_f32_e32 v0, v39, v0
	v_add_f32_e32 v0, v40, v0
	v_add_f32_e32 v0, v41, v0
	v_add_f32_e32 v0, v42, v0
	v_add_f32_e32 v0, v43, v0
	v_add_f32_e32 v0, v44, v0
	v_add_f32_e32 v0, v45, v0
	v_add_f32_e32 v0, v46, v0
	v_add_f32_e32 v0, v47, v0
	v_add_f32_e32 v0, v48, v0
	v_add_f32_e32 v51, v49, v0
	v_cvt_pk_f16_f32 v52, v82, v83
	v_cvt_pk_f16_f32 v34, v34, v35
	v_cvt_pk_f16_f32 v35, v36, v37
	v_cvt_pk_f16_f32 v36, v38, v39
	v_cvt_pk_f16_f32 v37, v40, v41
	v_cvt_pk_f16_f32 v53, v84, v85
	v_cvt_pk_f16_f32 v54, v86, v87
	v_cvt_pk_f16_f32 v55, v88, v89
	v_cvt_pk_f16_f32 v56, v90, v91
	v_cvt_pk_f16_f32 v57, v92, v93
	v_cvt_pk_f16_f32 v58, v94, v95
	v_cvt_pk_f16_f32 v59, v96, v97
	v_cvt_pk_f16_f32 v60, v42, v43
	v_cvt_pk_f16_f32 v61, v44, v45
	v_cvt_pk_f16_f32 v62, v46, v47
	v_cvt_pk_f16_f32 v63, v48, v49
	v_or3_b32 v0, v243, v204, v205
	s_add_i32 s0, s17, s48
	v_add_u32_e32 v0, s0, v0
	ds_read_b64_tr_b16 v[38:39],v0 offset:0
	ds_read_b64_tr_b16 v[40:41],v0 offset:512
	ds_read_b64_tr_b16 v[64:65],v0 offset:1024
	ds_read_b64_tr_b16 v[66:67],v0 offset:1536
	ds_read_b64_tr_b16 v[68:69],v0 offset:2048
	ds_read_b64_tr_b16 v[70:71],v0 offset:2560
	ds_read_b64_tr_b16 v[72:73],v0 offset:3072
	ds_read_b64_tr_b16 v[74:75],v0 offset:3584
	s_waitcnt lgkmcnt(0)
	ds_read_b64_tr_b16 v[42:43],v0 offset:4096
	ds_read_b64_tr_b16 v[44:45],v0 offset:4608
	ds_read_b64_tr_b16 v[46:47],v0 offset:5120
	ds_read_b64_tr_b16 v[48:49],v0 offset:5632
	ds_read_b64_tr_b16 v[76:77],v0 offset:6144
	ds_read_b64_tr_b16 v[78:79],v0 offset:6656
	ds_read_b64_tr_b16 v[80:81],v0 offset:7168
	ds_read_b64_tr_b16 v[82:83],v0 offset:7680
	s_waitcnt lgkmcnt(0)
; #define GAS __attribute__((address_space(1)))
; __device__ __forceinline__ int crow(int r, int hi) { return (r & 3) + 8 * (r >> 2) + 4 * hi; }
; __device__ __forceinline__ void pv(f32x16* o, int vb, s16x8 pa0, s16x8 pa1, s16x8 pa2, s16x8 pa3) {
; #pragma unroll
;   for (int d0 = 0; d0 < 2; ++d0) { s16x4 lo[4], hi[4];
; #pragma unroll
;     for (int ks = 0; ks < 4; ++ks) {
;       asm volatile("ds_read_b64_tr_b16 %0,%1 offset:%c2" : "=&v"(lo[ks]) : "v"(vb), "i"(d0 * 4096 + ks * 1024) : "memory");
;       asm volatile("ds_read_b64_tr_b16 %0,%1 offset:%c2" : "=&v"(hi[ks]) : "v"(vb), "i"(d0 * 4096 + ks * 1024 + 512) : "memory"); }
;     asm volatile("s_waitcnt lgkmcnt(0)" ::: "memory"); SBAR();
;     ...
;     o[d0] = __builtin_amdgcn_mfma_f32_32x32x16_f16(H8(pa0), H8(PK(0)), o[d0], 0, 0, 0);
;     o[d0] = __builtin_amdgcn_mfma_f32_32x32x16_f16(H8(pa1), H8(PK(1)), o[d0], 0, 0, 0);
;     o[d0] = __builtin_amdgcn_mfma_f32_32x32x16_f16(H8(pa2), H8(PK(2)), o[d0], 0, 0, 0);
;     o[d0] = __builtin_amdgcn_mfma_f32_32x32x16_f16(H8(pa3), H8(PK(3)), o[d0], 0, 0, 0);
;     ...
;   }
; template <int THRL, bool FIXM> __device__ __forceinline__ bool attn_unit(const h16* Qrows, const h16* __restrict__ Kh, const h16* __restrict__ Vh, const int NT, h16* Yrows, const h16* BZrows, char* shm, const int tid, const float mfix, ...
;     ...
;     SBAR(); pv(o, vb0 + sl_cur, __builtin_bit_cast(s16x8, pw0), __builtin_bit_cast(s16x8, pw1), __builtin_bit_cast(s16x8, pw2), __builtin_bit_cast(s16x8, pw3)); }
;   h16x8 zg[4];
;   { const h16* Zw0 = BZrows + (long)(wid * QBLK) * ZP;
; #pragma unroll
;     for (int i = 0; i < 4; ++i) zg[i] = *(const GAS h16x8*)(Zw0 + (long)(i * 8 + (lane >> 3)) * ZP + (lane & 7) * 8); }
;     ...
;   { auto rr = __builtin_amdgcn_permlane32_swap(__float_as_uint(l_reg), __float_as_uint(l_reg), false, false); l_reg = __uint_as_float(rr[0]) + __uint_as_float(rr[1]); }
;   if (hi == 0) wsf[32 + r32] = l_reg; asm volatile("s_waitcnt lgkmcnt(0)" ::: "memory");
;   float rli[16];
; #pragma unroll
;   for (int r = 0; r < 16; ++r) rli[r] = __builtin_amdgcn_rcpf(wsf[32 + crow(r, hi)]);
;   h16* Yw = Yrows + (long)(wid * QBLK) * YP;
;   { h16* stg = (h16*)(shm + LDS_OST) + wid * 2048;
; #pragma unroll
;     for (int r = 0; r < 16; ++r) { const int orow = crow(r, hi);
; #pragma unroll
;       for (int d0 = 0; d0 < 2; ++d0) stg[orow * 64 + d0 * 32 + r32] = (h16)(o[d0][r] * rli[r]); }
	s_nop 0
	v_mfma_f32_32x32x16_f16 v[2:17], v[52:55], v[42:45], v[2:17]
	s_lshl_b64 s[0:1], s[14:15], 1
	s_add_u32 s0, s82, s0
	v_and_b32_e32 v0, 56, v131
	v_and_b32_e32 v44, 0xe00, v230
	s_addc_u32 s1, s81, s1
	v_lshlrev_b32_e32 v0, 1, v0
	v_lshl_add_u64 v[42:43], s[0:1], 0, v[0:1]
	v_mfma_f32_32x32x16_f16 v[18:33], v[52:55], v[38:41], v[18:33]
	v_lshlrev_b32_e32 v44, 1, v44
	v_mov_b32_e32 v45, v1
	s_movk_i32 s0, 0x2000
	v_add_f32_e32 v51, v114, v51
	v_mfma_f32_32x32x16_f16 v[2:17], v[56:59], v[46:49], v[2:17]
	v_mfma_f32_32x32x16_f16 v[18:33], v[56:59], v[64:67], v[18:33]
	v_mfma_f32_32x32x16_f16 v[2:17], v[34:37], v[76:79], v[2:17]
	v_lshl_add_u64 v[76:77], v[42:43], 0, v[44:45]
	v_add_co_u32_e32 v42, vcc, s0, v76
	s_nop 1
	v_addc_co_u32_e32 v43, vcc, 0, v77, vcc
	v_add_co_u32_e32 v38, vcc, 0x4000, v76
	global_load_dwordx4 v[46:49], v[76:77], off
	s_nop 0
	global_load_dwordx4 v[42:45], v[42:43], off
	v_addc_co_u32_e32 v39, vcc, 0, v77, vcc
	v_add_co_u32_e32 v52, vcc, 0x6000, v76
	v_mfma_f32_32x32x16_f16 v[18:33], v[34:37], v[68:71], v[18:33]
	s_nop 0
	v_addc_co_u32_e32 v53, vcc, 0, v77, vcc
	global_load_dwordx4 v[38:41], v[38:39], off
	s_nop 0
	global_load_dwordx4 v[34:37], v[52:53], off
	v_mov_b32_e32 v52, v51
	s_nop 1
	v_permlane32_swap_b32_e32 v51, v52
	v_cmp_gt_u32_e32 vcc, 32, v249
	v_mfma_f32_32x32x16_f16 v[2:17], v[60:63], v[80:83], v[2:17]
	v_mfma_f32_32x32x16_f16 v[18:33], v[60:63], v[72:75], v[18:33]
	s_and_saveexec_b64 s[0:1], vcc
	v_add_f32_e32 v51, v51, v52
	ds_write_b32 v203, v51 offset:49280
	s_or_b64 exec, exec, s[0:1]
	s_waitcnt lgkmcnt(0)
	v_add_u32_e32 v51, 0xc080, v50
	ds_read2_b32 v[52:53], v51 offset1:1
	v_add_u32_e32 v51, 0xc088, v50
	s_lshl_b32 s4, s29, 12
	s_add_i32 s4, s41, s4
	v_lshlrev_b32_e32 v66, 1, v202
	s_waitcnt lgkmcnt(0)
	v_rcp_f32_e32 v54, v52
	v_rcp_f32_e32 v55, v53
	ds_read2_b32 v[52:53], v51 offset1:1
	v_add_u32_e32 v51, 0xc0a0, v50
	v_lshlrev_b32_e32 v67, 1, v250
	v_add3_u32 v66, s4, v66, v67
	v_fma_mixlo_f16 v2, v2, v54, 0
	s_waitcnt lgkmcnt(0)
	v_rcp_f32_e32 v56, v52
	v_rcp_f32_e32 v57, v53
	ds_read2_b32 v[52:53], v51 offset1:1
	v_add_u32_e32 v51, 0xc0a8, v50
	ds_write_b16 v66, v2 offset:51264
	v_fma_mixlo_f16 v2, v19, v55, 0
	ds_write_b16 v66, v2 offset:51328
	s_waitcnt lgkmcnt(2)
	v_rcp_f32_e32 v58, v52
	v_rcp_f32_e32 v59, v53
	ds_read2_b32 v[52:53], v51 offset1:1
	v_fma_mixlo_f16 v2, v3, v55, 0
	v_add_u32_e32 v51, 0xc0c0, v50
	ds_write_b16 v66, v2 offset:51392
	v_fma_mixlo_f16 v2, v20, v56, 0
	s_waitcnt lgkmcnt(1)
	v_rcp_f32_e32 v60, v52
	v_rcp_f32_e32 v61, v53
	ds_read2_b32 v[52:53], v51 offset1:1
	ds_write_b16 v66, v2 offset:51456
	v_fma_mixlo_f16 v2, v4, v56, 0
	ds_write_b16 v66, v2 offset:51520
	v_fma_mixlo_f16 v2, v21, v57, 0
	ds_write_b16 v66, v2 offset:51584
	v_fma_mixlo_f16 v2, v5, v57, 0
	ds_write_b16 v66, v2 offset:51648
	v_fma_mixlo_f16 v2, v22, v58, 0
	v_add_u32_e32 v51, 0xc0c8, v50
	ds_write_b16 v66, v2 offset:52224
	v_fma_mixlo_f16 v2, v6, v58, 0
	s_waitcnt lgkmcnt(5)
	v_rcp_f32_e32 v62, v52
	v_rcp_f32_e32 v63, v53
	ds_read2_b32 v[52:53], v51 offset1:1
	ds_write_b16 v66, v2 offset:52288
	v_fma_mixlo_f16 v2, v23, v59, 0
	ds_write_b16 v66, v2 offset:52352
	v_fma_mixlo_f16 v2, v7, v59, 0
	ds_write_b16 v66, v2 offset:52416
	v_fma_mixlo_f16 v2, v24, v60, 0
	ds_write_b16 v66, v2 offset:52480
	v_fma_mixlo_f16 v2, v8, v60, 0
	v_add_u32_e32 v51, 0xc0e0, v50
	ds_write_b16 v66, v2 offset:52544
	v_fma_mixlo_f16 v2, v25, v61, 0
	s_waitcnt lgkmcnt(5)
	v_rcp_f32_e32 v64, v52
	v_rcp_f32_e32 v65, v53
	ds_read2_b32 v[52:53], v51 offset1:1
	ds_write_b16 v66, v2 offset:52608
	v_fma_mixlo_f16 v2, v9, v61, 0
	ds_write_b16 v66, v2 offset:52672
	v_fma_mixlo_f16 v2, v26, v62, 0
	ds_write_b16 v66, v2 offset:53248
	v_fma_mixlo_f16 v2, v10, v62, 0
	v_add_u32_e32 v50, 0xc0e8, v50
	ds_write_b16 v66, v2 offset:53312
	v_fma_mixlo_f16 v2, v27, v63, 0
	ds_read2_b32 v[50:51], v50 offset1:1
	ds_write_b16 v66, v2 offset:53376
	v_fma_mixlo_f16 v2, v11, v63, 0
	s_waitcnt lgkmcnt(6)
	v_rcp_f32_e32 v52, v52
	ds_write_b16 v66, v2 offset:53440
	v_fma_mixlo_f16 v2, v28, v64, 0
	ds_write_b16 v66, v2 offset:53504
	v_fma_mixlo_f16 v2, v12, v64, 0
	v_rcp_f32_e32 v53, v53
	ds_write_b16 v66, v2 offset:53568
	v_fma_mixlo_f16 v2, v29, v65, 0
	ds_write_b16 v66, v2 offset:53632
	v_fma_mixlo_f16 v2, v13, v65, 0
	s_waitcnt lgkmcnt(5)
	v_rcp_f32_e32 v50, v50
	ds_write_b16 v66, v2 offset:53696
	v_fma_mixlo_f16 v2, v30, v52, 0
	ds_write_b16 v66, v2 offset:54272
	v_fma_mixlo_f16 v2, v14, v52, 0
	v_rcp_f32_e32 v51, v51
	ds_write_b16 v66, v2 offset:54336
	v_fma_mixlo_f16 v2, v31, v53, 0
	ds_write_b16 v66, v2 offset:54400
	v_fma_mixlo_f16 v2, v15, v53, 0
	ds_write_b16 v66, v2 offset:54464
	v_fma_mixlo_f16 v2, v32, v50, 0
	ds_write_b16 v66, v2 offset:54528
	v_fma_mixlo_f16 v2, v16, v50, 0
	s_lshl_b64 s[0:1], s[8:9], 11
	ds_write_b16 v66, v2 offset:54592
	v_fma_mixlo_f16 v2, v33, v51, 0
	s_waitcnt vmcnt(3)
	v_cvt_f32_f16_e32 v8, v46
	v_fma_mixlo_f16 v18, v18, v54, 0
	ds_write_b16 v66, v2 offset:54656
	v_fma_mixlo_f16 v2, v17, v51, 0
	s_add_u32 s0, s79, s0
	ds_write_b16 v66, v18 offset:51200
	ds_write_b16 v66, v2 offset:54720
	s_addc_u32 s1, s80, s1
	v_lshrrev_b32_e32 v10, 3, v249
	v_add_u32_e32 v11, s4, v0
	s_waitcnt lgkmcnt(0)
	v_lshl_add_u64 v[6:7], s[0:1], 0, v[0:1]
	v_lshl_add_u32 v0, v10, 7, v11
	ds_read_b128 v[2:5], v0 offset:51200
	v_mul_f32_e32 v0, 0xbfb8aa3b, v8
	v_exp_f32_e32 v0, v0
	v_cvt_f32_f16_sdwa v9, v46 dst_sel:DWORD dst_unused:UNUSED_PAD src0_sel:WORD_1
	s_waitcnt lgkmcnt(0)
; #define GAS __attribute__((address_space(1)))
; __device__ __forceinline__ float siluf(float x) { return x * __builtin_amdgcn_rcpf(1.f + __builtin_amdgcn_exp2f(-1.4426950408889634f * x)); }
; __device__ __forceinline__ unsigned cvtpk_h(float lo, float hi) { f32x2 v = {lo, hi}; h16x2 b = __builtin_convertvector(v, h16x2); return __builtin_bit_cast(unsigned, b); }
; template <int THRL, bool FIXM> __device__ __forceinline__ bool attn_unit(const h16* Qrows, const h16* __restrict__ Kh, const h16* __restrict__ Vh, const int NT, h16* Yrows, const h16* BZrows, char* shm, const int tid, const float mfix, ...
;     ...
;     for (int i = 0; i < 4; ++i) { const int row = i * 8 + (lane >> 3), ch = lane & 7; const h16x8 v = *(const h16x8*)(stg + row * 64 + ch * 8); const h16x8 z = zg[i];
;       u32x4 w; w.x = cvtpk_h((float)v[0] * siluf((float)z[0]), (float)v[1] * siluf((float)z[1])); w.y = cvtpk_h((float)v[2] * siluf((float)z[2]), (float)v[3] * siluf((float)z[3]));
;       w.z = cvtpk_h((float)v[4] * siluf((float)z[4]), (float)v[5] * siluf((float)z[5])); w.w = cvtpk_h((float)v[6] * siluf((float)z[6]), (float)v[7] * siluf((float)z[7]));
;       *(GAS u32x4*)(Yw + (long)row * YP + ch * 8) = w; } }
	v_cvt_f32_f16_e32 v14, v2
	v_add_f32_e32 v0, 1.0, v0
	v_rcp_f32_e32 v12, v0
	v_mul_f32_e32 v0, 0xbfb8aa3b, v9
	v_exp_f32_e32 v0, v0
	v_cvt_f32_f16_sdwa v15, v2 dst_sel:DWORD dst_unused:UNUSED_PAD src0_sel:WORD_1
	v_add_f32_e32 v0, 1.0, v0
	v_rcp_f32_e32 v13, v0
	s_nop 0
	v_mul_f32_e32 v8, v12, v8
	v_mul_f32_e32 v9, v13, v9
	s_nop 0
	v_mul_f32_e32 v8, v8, v14
	v_mul_f32_e32 v9, v9, v15
	v_cvt_f32_f16_e32 v14, v3
	v_cvt_pk_f16_f32 v2, v8, v9
	v_cvt_f32_f16_e32 v8, v47
	v_cvt_f32_f16_sdwa v9, v47 dst_sel:DWORD dst_unused:UNUSED_PAD src0_sel:WORD_1
	v_cvt_f32_f16_sdwa v15, v3 dst_sel:DWORD dst_unused:UNUSED_PAD src0_sel:WORD_1
	v_mul_f32_e32 v0, 0xbfb8aa3b, v8
	v_exp_f32_e32 v0, v0
	s_nop 0
	v_add_f32_e32 v0, 1.0, v0
	v_rcp_f32_e32 v12, v0
	v_mul_f32_e32 v0, 0xbfb8aa3b, v9
	v_exp_f32_e32 v0, v0
	s_nop 0
	v_add_f32_e32 v0, 1.0, v0
	v_rcp_f32_e32 v13, v0
	s_nop 0
	v_mul_f32_e32 v8, v12, v8
	v_mul_f32_e32 v9, v13, v9
	s_nop 0
	v_mul_f32_e32 v8, v8, v14
	v_mul_f32_e32 v9, v9, v15
	v_cvt_f32_f16_e32 v14, v4
	v_cvt_pk_f16_f32 v3, v8, v9
	v_cvt_f32_f16_e32 v8, v48
	v_cvt_f32_f16_sdwa v9, v48 dst_sel:DWORD dst_unused:UNUSED_PAD src0_sel:WORD_1
	v_cvt_f32_f16_sdwa v15, v4 dst_sel:DWORD dst_unused:UNUSED_PAD src0_sel:WORD_1
	v_mul_f32_e32 v0, 0xbfb8aa3b, v8
	v_exp_f32_e32 v0, v0
	s_nop 0
	v_add_f32_e32 v0, 1.0, v0
	v_rcp_f32_e32 v12, v0
	v_mul_f32_e32 v0, 0xbfb8aa3b, v9
	v_exp_f32_e32 v0, v0
	s_nop 0
	v_add_f32_e32 v0, 1.0, v0
	v_rcp_f32_e32 v13, v0
	s_nop 0
	v_mul_f32_e32 v8, v12, v8
	v_mul_f32_e32 v9, v13, v9
	s_nop 0
	v_mul_f32_e32 v8, v8, v14
	v_mul_f32_e32 v9, v9, v15
	v_cvt_f32_f16_e32 v14, v5
	v_cvt_pk_f16_f32 v4, v8, v9
	v_cvt_f32_f16_e32 v8, v49
	v_cvt_f32_f16_sdwa v9, v49 dst_sel:DWORD dst_unused:UNUSED_PAD src0_sel:WORD_1
	v_cvt_f32_f16_sdwa v15, v5 dst_sel:DWORD dst_unused:UNUSED_PAD src0_sel:WORD_1
	v_mul_f32_e32 v0, 0xbfb8aa3b, v8
	v_exp_f32_e32 v0, v0
	s_nop 0
	v_add_f32_e32 v0, 1.0, v0
	v_rcp_f32_e32 v12, v0
	v_mul_f32_e32 v0, 0xbfb8aa3b, v9
	v_exp_f32_e32 v0, v0
	s_nop 0
	v_add_f32_e32 v0, 1.0, v0
	v_rcp_f32_e32 v13, v0
	v_lshlrev_b32_e32 v0, 11, v10
	v_mul_f32_e32 v8, v12, v8
	v_mul_f32_e32 v9, v13, v9
	s_nop 0
	v_mul_f32_e32 v8, v8, v14
	v_mul_f32_e32 v9, v9, v15
	s_nop 0
	v_cvt_pk_f16_f32 v5, v8, v9
	v_lshl_add_u64 v[8:9], v[6:7], 0, v[0:1]
	v_or_b32_e32 v0, 8, v10
	global_store_dwordx4 v[8:9], v[2:5], off offset:512 sc1
	s_waitcnt vmcnt(3)
	v_cvt_f32_f16_sdwa v9, v42 dst_sel:DWORD dst_unused:UNUSED_PAD src0_sel:WORD_1
	v_cvt_f32_f16_e32 v8, v42
	v_lshl_add_u32 v2, v0, 7, v11
	ds_read_b128 v[2:5], v2 offset:51200
	v_lshlrev_b32_e32 v0, 11, v0
	v_mul_f32_e32 v12, 0xbfb8aa3b, v8
	v_exp_f32_e32 v12, v12
	s_waitcnt lgkmcnt(0)
	v_cvt_f32_f16_e32 v14, v2
	v_cvt_f32_f16_sdwa v15, v2 dst_sel:DWORD dst_unused:UNUSED_PAD src0_sel:WORD_1
	v_mul_f32_e32 v2, 0xbfb8aa3b, v9
	v_exp_f32_e32 v2, v2
	v_add_f32_e32 v12, 1.0, v12
	v_rcp_f32_e32 v12, v12
	v_add_f32_e32 v2, 1.0, v2
	v_rcp_f32_e32 v13, v2
	s_nop 0
	v_mul_f32_e32 v8, v12, v8
	v_mul_f32_e32 v9, v13, v9
	s_nop 0
	v_mul_f32_e32 v8, v8, v14
	v_mul_f32_e32 v9, v9, v15
	v_cvt_f32_f16_e32 v14, v3
	v_cvt_pk_f16_f32 v2, v8, v9
	v_cvt_f32_f16_sdwa v9, v43 dst_sel:DWORD dst_unused:UNUSED_PAD src0_sel:WORD_1
	v_cvt_f32_f16_e32 v8, v43
	v_cvt_f32_f16_sdwa v15, v3 dst_sel:DWORD dst_unused:UNUSED_PAD src0_sel:WORD_1
	v_mul_f32_e32 v3, 0xbfb8aa3b, v9
	v_mul_f32_e32 v12, 0xbfb8aa3b, v8
	v_exp_f32_e32 v12, v12
	v_exp_f32_e32 v3, v3
	v_add_f32_e32 v12, 1.0, v12
	v_add_f32_e32 v3, 1.0, v3
	v_rcp_f32_e32 v12, v12
	v_rcp_f32_e32 v13, v3
	s_nop 0
	v_mul_f32_e32 v8, v12, v8
	v_mul_f32_e32 v9, v13, v9
	s_nop 0
	v_mul_f32_e32 v8, v8, v14
	v_mul_f32_e32 v9, v9, v15
	v_cvt_f32_f16_e32 v14, v4
	v_cvt_pk_f16_f32 v3, v8, v9
	v_cvt_f32_f16_sdwa v9, v44 dst_sel:DWORD dst_unused:UNUSED_PAD src0_sel:WORD_1
	v_cvt_f32_f16_e32 v8, v44
	v_cvt_f32_f16_sdwa v15, v4 dst_sel:DWORD dst_unused:UNUSED_PAD src0_sel:WORD_1
	v_mul_f32_e32 v4, 0xbfb8aa3b, v9
	v_mul_f32_e32 v12, 0xbfb8aa3b, v8
	v_exp_f32_e32 v12, v12
	v_exp_f32_e32 v4, v4
	v_add_f32_e32 v12, 1.0, v12
	v_add_f32_e32 v4, 1.0, v4
	v_rcp_f32_e32 v12, v12
	v_rcp_f32_e32 v13, v4
	s_nop 0
	v_mul_f32_e32 v8, v12, v8
	v_mul_f32_e32 v9, v13, v9
	s_nop 0
	v_mul_f32_e32 v8, v8, v14
	v_mul_f32_e32 v9, v9, v15
	v_cvt_f32_f16_e32 v14, v5
	v_cvt_pk_f16_f32 v4, v8, v9
	v_cvt_f32_f16_sdwa v9, v45 dst_sel:DWORD dst_unused:UNUSED_PAD src0_sel:WORD_1
	v_cvt_f32_f16_e32 v8, v45
	v_cvt_f32_f16_sdwa v15, v5 dst_sel:DWORD dst_unused:UNUSED_PAD src0_sel:WORD_1
	v_mul_f32_e32 v5, 0xbfb8aa3b, v9
	v_mul_f32_e32 v12, 0xbfb8aa3b, v8
	v_exp_f32_e32 v12, v12
	v_exp_f32_e32 v5, v5
	v_add_f32_e32 v12, 1.0, v12
	v_add_f32_e32 v5, 1.0, v5
	v_rcp_f32_e32 v12, v12
	v_rcp_f32_e32 v13, v5
	s_nop 0
	v_mul_f32_e32 v8, v12, v8
	v_mul_f32_e32 v9, v13, v9
	s_nop 0
	v_mul_f32_e32 v8, v8, v14
	v_mul_f32_e32 v9, v9, v15
	s_nop 0
	v_cvt_pk_f16_f32 v5, v8, v9
	v_lshl_add_u64 v[8:9], v[6:7], 0, v[0:1]
	v_or_b32_e32 v0, 16, v10
	global_store_dwordx4 v[8:9], v[2:5], off offset:512 sc1
	s_waitcnt vmcnt(3)
; #define GAS __attribute__((address_space(1)))
; __device__ __forceinline__ float siluf(float x) { return x * __builtin_amdgcn_rcpf(1.f + __builtin_amdgcn_exp2f(-1.4426950408889634f * x)); }
; __device__ __forceinline__ unsigned cvtpk_h(float lo, float hi) { f32x2 v = {lo, hi}; h16x2 b = __builtin_convertvector(v, h16x2); return __builtin_bit_cast(unsigned, b); }
; template <int THRL, bool FIXM> __device__ __forceinline__ bool attn_unit(const h16* Qrows, const h16* __restrict__ Kh, const h16* __restrict__ Vh, const int NT, h16* Yrows, const h16* BZrows, char* shm, const int tid, const float mfix, ...
;     ...
;     for (int i = 0; i < 4; ++i) { const int row = i * 8 + (lane >> 3), ch = lane & 7; const h16x8 v = *(const h16x8*)(stg + row * 64 + ch * 8); const h16x8 z = zg[i];
;       u32x4 w; w.x = cvtpk_h((float)v[0] * siluf((float)z[0]), (float)v[1] * siluf((float)z[1])); w.y = cvtpk_h((float)v[2] * siluf((float)z[2]), (float)v[3] * siluf((float)z[3]));
;       w.z = cvtpk_h((float)v[4] * siluf((float)z[4]), (float)v[5] * siluf((float)z[5])); w.w = cvtpk_h((float)v[6] * siluf((float)z[6]), (float)v[7] * siluf((float)z[7]));
;       *(GAS u32x4*)(Yw + (long)row * YP + ch * 8) = w; } }
;   asm volatile("s_waitcnt lgkmcnt(0)\n\ts_barrier" ::: "memory");
	v_cvt_f32_f16_sdwa v9, v38 dst_sel:DWORD dst_unused:UNUSED_PAD src0_sel:WORD_1
	v_cvt_f32_f16_e32 v8, v38
	v_lshl_add_u32 v2, v0, 7, v11
	ds_read_b128 v[2:5], v2 offset:51200
	v_lshlrev_b32_e32 v0, 11, v0
	v_mul_f32_e32 v12, 0xbfb8aa3b, v8
	v_exp_f32_e32 v12, v12
	s_waitcnt lgkmcnt(0)
	v_cvt_f32_f16_e32 v14, v2
	v_cvt_f32_f16_sdwa v15, v2 dst_sel:DWORD dst_unused:UNUSED_PAD src0_sel:WORD_1
	v_mul_f32_e32 v2, 0xbfb8aa3b, v9
	v_exp_f32_e32 v2, v2
	v_add_f32_e32 v12, 1.0, v12
	v_rcp_f32_e32 v12, v12
	v_add_f32_e32 v2, 1.0, v2
	v_rcp_f32_e32 v13, v2
	s_nop 0
	v_mul_f32_e32 v8, v12, v8
	v_mul_f32_e32 v9, v13, v9
	s_nop 0
	v_mul_f32_e32 v8, v8, v14
	v_mul_f32_e32 v9, v9, v15
	v_cvt_f32_f16_e32 v14, v3
	v_cvt_pk_f16_f32 v2, v8, v9
	v_cvt_f32_f16_sdwa v9, v39 dst_sel:DWORD dst_unused:UNUSED_PAD src0_sel:WORD_1
	v_cvt_f32_f16_e32 v8, v39
	v_cvt_f32_f16_sdwa v15, v3 dst_sel:DWORD dst_unused:UNUSED_PAD src0_sel:WORD_1
	v_mul_f32_e32 v3, 0xbfb8aa3b, v9
	v_mul_f32_e32 v12, 0xbfb8aa3b, v8
	v_exp_f32_e32 v12, v12
	v_exp_f32_e32 v3, v3
	v_add_f32_e32 v12, 1.0, v12
	v_add_f32_e32 v3, 1.0, v3
	v_rcp_f32_e32 v12, v12
	v_rcp_f32_e32 v13, v3
	s_nop 0
	v_mul_f32_e32 v8, v12, v8
	v_mul_f32_e32 v9, v13, v9
	s_nop 0
	v_mul_f32_e32 v8, v8, v14
	v_mul_f32_e32 v9, v9, v15
	v_cvt_f32_f16_e32 v14, v4
	v_cvt_pk_f16_f32 v3, v8, v9
	v_cvt_f32_f16_sdwa v9, v40 dst_sel:DWORD dst_unused:UNUSED_PAD src0_sel:WORD_1
	v_cvt_f32_f16_e32 v8, v40
	v_cvt_f32_f16_sdwa v15, v4 dst_sel:DWORD dst_unused:UNUSED_PAD src0_sel:WORD_1
	v_mul_f32_e32 v4, 0xbfb8aa3b, v9
	v_mul_f32_e32 v12, 0xbfb8aa3b, v8
	v_exp_f32_e32 v12, v12
	v_exp_f32_e32 v4, v4
	v_add_f32_e32 v12, 1.0, v12
	v_add_f32_e32 v4, 1.0, v4
	v_rcp_f32_e32 v12, v12
	v_rcp_f32_e32 v13, v4
	s_nop 0
	v_mul_f32_e32 v8, v12, v8
	v_mul_f32_e32 v9, v13, v9
	s_nop 0
	v_mul_f32_e32 v8, v8, v14
	v_mul_f32_e32 v9, v9, v15
	v_cvt_f32_f16_e32 v14, v5
	v_cvt_pk_f16_f32 v4, v8, v9
	v_cvt_f32_f16_sdwa v9, v41 dst_sel:DWORD dst_unused:UNUSED_PAD src0_sel:WORD_1
	v_cvt_f32_f16_e32 v8, v41
	v_cvt_f32_f16_sdwa v15, v5 dst_sel:DWORD dst_unused:UNUSED_PAD src0_sel:WORD_1
	v_mul_f32_e32 v5, 0xbfb8aa3b, v9
	v_mul_f32_e32 v12, 0xbfb8aa3b, v8
	v_exp_f32_e32 v12, v12
	v_exp_f32_e32 v5, v5
	v_add_f32_e32 v12, 1.0, v12
	v_add_f32_e32 v5, 1.0, v5
	v_rcp_f32_e32 v12, v12
	v_rcp_f32_e32 v13, v5
	s_nop 0
	v_mul_f32_e32 v8, v12, v8
	v_mul_f32_e32 v9, v13, v9
	s_nop 0
	v_mul_f32_e32 v8, v8, v14
	v_mul_f32_e32 v9, v9, v15
	s_nop 0
	v_cvt_pk_f16_f32 v5, v8, v9
	v_lshl_add_u64 v[8:9], v[6:7], 0, v[0:1]
	v_or_b32_e32 v0, 24, v10
	global_store_dwordx4 v[8:9], v[2:5], off offset:512 sc1
	s_waitcnt vmcnt(3)
	v_cvt_f32_f16_sdwa v9, v34 dst_sel:DWORD dst_unused:UNUSED_PAD src0_sel:WORD_1
	v_cvt_f32_f16_e32 v8, v34
	v_lshl_add_u32 v2, v0, 7, v11
	ds_read_b128 v[2:5], v2 offset:51200
	v_lshlrev_b32_e32 v0, 11, v0
	v_mul_f32_e32 v10, 0xbfb8aa3b, v8
	v_exp_f32_e32 v10, v10
	v_lshl_add_u64 v[6:7], v[6:7], 0, v[0:1]
	s_waitcnt lgkmcnt(0)
	v_cvt_f32_f16_e32 v12, v2
	v_cvt_f32_f16_sdwa v13, v2 dst_sel:DWORD dst_unused:UNUSED_PAD src0_sel:WORD_1
	v_mul_f32_e32 v2, 0xbfb8aa3b, v9
	v_exp_f32_e32 v2, v2
	v_add_f32_e32 v10, 1.0, v10
	v_rcp_f32_e32 v10, v10
	v_add_f32_e32 v2, 1.0, v2
	v_rcp_f32_e32 v11, v2
	s_nop 0
	v_mul_f32_e32 v8, v10, v8
	v_mul_f32_e32 v9, v11, v9
	s_nop 0
	v_mul_f32_e32 v8, v8, v12
	v_mul_f32_e32 v9, v9, v13
	v_cvt_f32_f16_e32 v12, v3
	v_cvt_pk_f16_f32 v2, v8, v9
	v_cvt_f32_f16_sdwa v9, v35 dst_sel:DWORD dst_unused:UNUSED_PAD src0_sel:WORD_1
	v_cvt_f32_f16_e32 v8, v35
	v_cvt_f32_f16_sdwa v13, v3 dst_sel:DWORD dst_unused:UNUSED_PAD src0_sel:WORD_1
	v_mul_f32_e32 v3, 0xbfb8aa3b, v9
	v_mul_f32_e32 v10, 0xbfb8aa3b, v8
	v_exp_f32_e32 v10, v10
	v_exp_f32_e32 v3, v3
	v_add_f32_e32 v10, 1.0, v10
	v_add_f32_e32 v3, 1.0, v3
	v_rcp_f32_e32 v10, v10
	v_rcp_f32_e32 v11, v3
	s_nop 0
	v_mul_f32_e32 v8, v10, v8
	v_mul_f32_e32 v9, v11, v9
	s_nop 0
	v_mul_f32_e32 v8, v8, v12
	v_mul_f32_e32 v9, v9, v13
	v_cvt_f32_f16_e32 v12, v4
	v_cvt_pk_f16_f32 v3, v8, v9
	v_cvt_f32_f16_sdwa v9, v36 dst_sel:DWORD dst_unused:UNUSED_PAD src0_sel:WORD_1
	v_cvt_f32_f16_e32 v8, v36
	v_cvt_f32_f16_sdwa v13, v4 dst_sel:DWORD dst_unused:UNUSED_PAD src0_sel:WORD_1
	v_mul_f32_e32 v4, 0xbfb8aa3b, v9
	v_mul_f32_e32 v10, 0xbfb8aa3b, v8
	v_exp_f32_e32 v10, v10
	v_exp_f32_e32 v4, v4
	v_add_f32_e32 v10, 1.0, v10
	v_add_f32_e32 v4, 1.0, v4
	v_rcp_f32_e32 v10, v10
	v_rcp_f32_e32 v11, v4
	s_nop 0
	v_mul_f32_e32 v8, v10, v8
	v_mul_f32_e32 v9, v11, v9
	s_nop 0
	v_mul_f32_e32 v8, v8, v12
	v_mul_f32_e32 v9, v9, v13
	v_cvt_f32_f16_e32 v12, v5
	v_cvt_pk_f16_f32 v4, v8, v9
	v_cvt_f32_f16_sdwa v9, v37 dst_sel:DWORD dst_unused:UNUSED_PAD src0_sel:WORD_1
	v_cvt_f32_f16_e32 v8, v37
	v_cvt_f32_f16_sdwa v13, v5 dst_sel:DWORD dst_unused:UNUSED_PAD src0_sel:WORD_1
	v_mul_f32_e32 v5, 0xbfb8aa3b, v9
	v_mul_f32_e32 v10, 0xbfb8aa3b, v8
	v_exp_f32_e32 v10, v10
	v_exp_f32_e32 v5, v5
	v_add_f32_e32 v10, 1.0, v10
	v_add_f32_e32 v5, 1.0, v5
	v_rcp_f32_e32 v10, v10
	v_rcp_f32_e32 v11, v5
	s_nop 0
	v_mul_f32_e32 v8, v10, v8
	v_mul_f32_e32 v9, v11, v9
	s_nop 0
	v_mul_f32_e32 v8, v8, v12
	v_mul_f32_e32 v9, v9, v13
	s_nop 0
	v_cvt_pk_f16_f32 v5, v8, v9
	global_store_dwordx4 v[6:7], v[2:5], off offset:512 sc1
	s_waitcnt lgkmcnt(0)
	s_barrier

.LBB0_260:
	s_nop 10
	v_sub_f32_e32 v4, v139, v138
	v_sub_f32_e32 v3, v111, v138
	v_mul_f32_e32 v4, 0x3fb8aa3b, v4
	v_mul_f32_e32 v3, 0x3fb8aa3b, v3
	v_exp_f32_e32 v4, v4
	v_exp_f32_e32 v6, v3
	v_mul_f32_e32 v8, v4, v18
	v_mul_f32_e32 v9, v4, v19
	v_fma_f32 v112, v112, v6, v8
	v_fma_f32 v113, v113, v6, v9
	v_mul_f32_e32 v8, v4, v20
	v_mul_f32_e32 v9, v4, v21
	v_fma_f32 v114, v114, v6, v8
	v_fma_f32 v115, v115, v6, v9
	v_mul_f32_e32 v8, v4, v22
	v_mul_f32_e32 v9, v4, v23
	v_fma_f32 v116, v116, v6, v8
	v_fma_f32 v117, v117, v6, v9
	v_mul_f32_e32 v8, v4, v24
	v_mul_f32_e32 v9, v4, v25
	v_fma_f32 v118, v118, v6, v8
	v_fma_f32 v119, v119, v6, v9
	v_mul_f32_e32 v8, v4, v26
	v_mul_f32_e32 v9, v4, v27
	v_fma_f32 v120, v120, v6, v8
	v_fma_f32 v121, v121, v6, v9
	v_mul_f32_e32 v8, v4, v28
	v_mul_f32_e32 v9, v4, v29
	v_fma_f32 v122, v122, v6, v8
	v_fma_f32 v123, v123, v6, v9
	v_mul_f32_e32 v8, v4, v30
	v_mul_f32_e32 v9, v4, v31
	v_fma_f32 v124, v124, v6, v8
	v_fma_f32 v125, v125, v6, v9
	v_mul_f32_e32 v10, v4, v32
	v_mov_b32_e32 v32, v127
	v_mov_b32_e32 v7, v4
	v_mul_f32_e32 v12, v32, v6
	v_mul_f32_e32 v13, v33, v7
	v_mov_b32_e32 v111, v4
	v_mov_b32_e32 v7, v2
	v_mul_f32_e32 v2, v110, v6
	v_mul_f32_e32 v3, v111, v7
	v_mul_f32_e32 v8, v126, v6
	v_mov_b32_e32 v9, v12
	v_mov_b32_e32 v11, v13
	v_add_f32_e32 v2, v2, v3
	v_add_f32_e32 v126, v8, v10
	v_add_f32_e32 v127, v9, v11
	v_cndmask_b32_e64 v110, v110, v2, s[2:3]

.LBB0_263:
	s_waitcnt vmcnt(16)
	v_add_u32_e32 v138, s75, v136
	v_add_u32_e32 v0, 0x10000, v138
	ds_write_b128 v137, v[38:41]
	ds_read_b32 v0, v0
	v_cvt_f32_f16_sdwa v3, v34 dst_sel:DWORD dst_unused:UNUSED_PAD src0_sel:WORD_1
	v_cvt_f32_f16_e32 v2, v34
	v_cvt_f32_f16_sdwa v5, v35 dst_sel:DWORD dst_unused:UNUSED_PAD src0_sel:WORD_1
	v_cvt_f32_f16_e32 v4, v35
	v_cvt_f32_f16_sdwa v7, v37 dst_sel:DWORD dst_unused:UNUSED_PAD src0_sel:WORD_1
	s_waitcnt lgkmcnt(0)
	v_mul_f32_e32 v2, v0, v2
	v_mul_f32_e32 v3, v0, v3
	v_cvt_pk_f16_f32 v2, v2, v3
	v_mul_f32_e32 v4, v0, v4
	v_mul_f32_e32 v5, v0, v5
	v_cvt_pk_f16_f32 v3, v4, v5
	v_cvt_f32_f16_sdwa v5, v36 dst_sel:DWORD dst_unused:UNUSED_PAD src0_sel:WORD_1
	v_cvt_f32_f16_e32 v4, v36
	v_cvt_f32_f16_e32 v6, v37
	s_add_i32 s76, s19, -5
	s_cmp_gt_u32 s76, 13
	v_mul_f32_e32 v4, v0, v4
	v_mul_f32_e32 v5, v0, v5
	v_mul_f32_e32 v6, v0, v6
	v_mul_f32_e32 v7, v0, v7
	v_cvt_pk_f16_f32 v4, v4, v5
	v_cvt_pk_f16_f32 v5, v6, v7
	ds_write_b128 v137, v[2:5] offset:32768
	s_nop 0
	ds_write_b128 v137, v[50:53] offset:4096
	v_add_u32_e32 v0, 0x10100, v138
	ds_read_b32 v0, v0
	v_cvt_f32_f16_sdwa v3, v42 dst_sel:DWORD dst_unused:UNUSED_PAD src0_sel:WORD_1
	v_cvt_f32_f16_e32 v2, v42
	v_cvt_f32_f16_sdwa v5, v43 dst_sel:DWORD dst_unused:UNUSED_PAD src0_sel:WORD_1
	v_cvt_f32_f16_e32 v4, v43
	v_cvt_f32_f16_sdwa v7, v45 dst_sel:DWORD dst_unused:UNUSED_PAD src0_sel:WORD_1
	s_waitcnt lgkmcnt(0)
	v_mul_f32_e32 v2, v0, v2
	v_mul_f32_e32 v3, v0, v3
	v_cvt_pk_f16_f32 v2, v2, v3
	v_mul_f32_e32 v4, v0, v4
	v_mul_f32_e32 v5, v0, v5
	v_cvt_pk_f16_f32 v3, v4, v5
	v_cvt_f32_f16_sdwa v5, v44 dst_sel:DWORD dst_unused:UNUSED_PAD src0_sel:WORD_1
	v_cvt_f32_f16_e32 v4, v44
	v_cvt_f32_f16_e32 v6, v45
	v_mul_f32_e32 v4, v0, v4
	v_mul_f32_e32 v5, v0, v5
	v_mul_f32_e32 v6, v0, v6
	v_mul_f32_e32 v7, v0, v7
	v_cvt_pk_f16_f32 v4, v4, v5
	v_cvt_pk_f16_f32 v5, v6, v7
	ds_write_b128 v137, v[2:5] offset:36864
	s_nop 0
	s_add_i32 s12, s29, 3
	s_add_i32 s13, s19, -3
	s_and_b64 s[6:7], s[0:1], exec
	s_cselect_b32 s6, s13, s12
	s_cmp_gt_u32 s76, 13
	s_cselect_b32 s6, 0, s6
	s_lshl_b32 s6, s6, 7
	s_or_b32 s6, s6, s24
	s_mov_b32 s7, s25
	s_lshl_b64 s[12:13], s[6:7], 9
	s_or_b32 s6, s6, 64
	v_lshl_add_u64 v[2:3], v[102:103], 0, s[12:13]
	s_lshl_b64 s[6:7], s[6:7], 9
	v_lshl_add_u64 v[4:5], v[104:105], 0, s[12:13]
	global_load_dwordx4 v[34:37], v[2:3], off
	global_load_dwordx4 v[38:41], v[4:5], off
	v_lshl_add_u64 v[2:3], v[102:103], 0, s[6:7]
	v_lshl_add_u64 v[4:5], v[104:105], 0, s[6:7]
	global_load_dwordx4 v[42:45], v[2:3], off
	global_load_dwordx4 v[50:53], v[4:5], off

.LBB0_288:
	s_nop 11
	v_sub_f32_e32 v4, v141, v139
	v_sub_f32_e32 v3, v111, v139
	v_mul_f32_e32 v4, 0x3fb8aa3b, v4
	v_mul_f32_e32 v3, 0x3fb8aa3b, v3
	v_exp_f32_e32 v4, v4
	v_exp_f32_e32 v6, v3
	v_mul_f32_e32 v8, v4, v18
	v_mul_f32_e32 v9, v4, v19
	v_fma_f32 v112, v112, v6, v8
	v_fma_f32 v113, v113, v6, v9
	v_mul_f32_e32 v8, v4, v20
	v_mul_f32_e32 v9, v4, v21
	v_fma_f32 v114, v114, v6, v8
	v_fma_f32 v115, v115, v6, v9
	v_mul_f32_e32 v8, v4, v22
	v_mul_f32_e32 v9, v4, v23
	v_fma_f32 v116, v116, v6, v8
	v_fma_f32 v117, v117, v6, v9
	v_mul_f32_e32 v8, v4, v24
	v_mul_f32_e32 v9, v4, v25
	v_fma_f32 v118, v118, v6, v8
	v_fma_f32 v119, v119, v6, v9
	v_mul_f32_e32 v8, v4, v26
	v_mul_f32_e32 v9, v4, v27
	v_fma_f32 v120, v120, v6, v8
	v_fma_f32 v121, v121, v6, v9
	v_mul_f32_e32 v8, v4, v28
	v_mul_f32_e32 v9, v4, v29
	v_fma_f32 v122, v122, v6, v8
	v_fma_f32 v123, v123, v6, v9
	v_mul_f32_e32 v8, v4, v30
	v_mul_f32_e32 v9, v4, v31
	v_fma_f32 v124, v124, v6, v8
	v_fma_f32 v125, v125, v6, v9
	v_mul_f32_e32 v10, v4, v32
	v_mov_b32_e32 v32, v127
	v_mov_b32_e32 v7, v4
	v_mul_f32_e32 v12, v32, v6
	v_mul_f32_e32 v13, v33, v7
	v_mov_b32_e32 v111, v4
	v_mov_b32_e32 v7, v2
	v_mul_f32_e32 v2, v110, v6
	v_mul_f32_e32 v3, v111, v7
	v_mul_f32_e32 v8, v126, v6
	v_mov_b32_e32 v9, v12
	v_mov_b32_e32 v11, v13
	v_add_f32_e32 v2, v2, v3
	v_add_f32_e32 v126, v8, v10
	v_add_f32_e32 v127, v9, v11
	v_cndmask_b32_e64 v110, v110, v2, s[2:3]
.LBB0_289:
	s_waitcnt vmcnt(16)
	v_add_u32_e32 v2, 0x10200, v138
	ds_write_b128 v137, v[54:57] offset:16384
	ds_read_b32 v6, v2
	v_cvt_f32_f16_sdwa v3, v46 dst_sel:DWORD dst_unused:UNUSED_PAD src0_sel:WORD_1
	v_cvt_f32_f16_e32 v2, v46
	v_cvt_f32_f16_sdwa v5, v47 dst_sel:DWORD dst_unused:UNUSED_PAD src0_sel:WORD_1
	v_cvt_f32_f16_e32 v4, v47
	s_nop 0
	v_cvt_f32_f16_sdwa v9, v49 dst_sel:DWORD dst_unused:UNUSED_PAD src0_sel:WORD_1
	s_waitcnt lgkmcnt(0)
	v_mul_f32_e32 v2, v6, v2
	v_mul_f32_e32 v3, v6, v3
	v_cvt_pk_f16_f32 v2, v2, v3
	v_mul_f32_e32 v4, v6, v4
	v_mul_f32_e32 v5, v6, v5
	v_cvt_pk_f16_f32 v3, v4, v5
	v_cvt_f32_f16_sdwa v5, v48 dst_sel:DWORD dst_unused:UNUSED_PAD src0_sel:WORD_1
	v_cvt_f32_f16_e32 v4, v48
	v_cvt_f32_f16_e32 v8, v49
	s_cmp_gt_u32 s76, 12
	v_mul_f32_e32 v4, v6, v4
	v_mul_f32_e32 v5, v6, v5
	v_mul_f32_e32 v7, v6, v9
	v_mul_f32_e32 v6, v6, v8
	v_cvt_pk_f16_f32 v4, v4, v5
	v_cvt_pk_f16_f32 v5, v6, v7
	ds_write_b128 v137, v[2:5] offset:49152
	s_nop 0
	ds_write_b128 v137, v[62:65] offset:20480
	v_add_u32_e32 v2, 0x10300, v138
	ds_read_b32 v6, v2
	v_cvt_f32_f16_sdwa v3, v58 dst_sel:DWORD dst_unused:UNUSED_PAD src0_sel:WORD_1
	v_cvt_f32_f16_e32 v2, v58
	v_cvt_f32_f16_sdwa v5, v59 dst_sel:DWORD dst_unused:UNUSED_PAD src0_sel:WORD_1
	v_cvt_f32_f16_e32 v4, v59
	v_cvt_f32_f16_sdwa v9, v61 dst_sel:DWORD dst_unused:UNUSED_PAD src0_sel:WORD_1
	s_waitcnt lgkmcnt(0)
	v_mul_f32_e32 v2, v6, v2
	v_mul_f32_e32 v3, v6, v3
	v_cvt_pk_f16_f32 v2, v2, v3
	v_mul_f32_e32 v4, v6, v4
	v_mul_f32_e32 v5, v6, v5
	v_cvt_pk_f16_f32 v3, v4, v5
	v_cvt_f32_f16_sdwa v5, v60 dst_sel:DWORD dst_unused:UNUSED_PAD src0_sel:WORD_1
	v_cvt_f32_f16_e32 v4, v60
	v_cvt_f32_f16_e32 v8, v61
	v_mul_f32_e32 v4, v6, v4
	v_mul_f32_e32 v5, v6, v5
	v_mul_f32_e32 v7, v6, v9
	v_mul_f32_e32 v6, v6, v8
	v_cvt_pk_f16_f32 v4, v4, v5
	v_cvt_pk_f16_f32 v5, v6, v7
	ds_write_b128 v137, v[2:5] offset:53248
	s_nop 0
	s_add_i32 s14, s29, 2
	s_add_i32 s15, s19, -2
	s_and_b64 s[12:13], s[0:1], exec
	s_cselect_b32 s12, s15, s14
	s_cmp_gt_u32 s76, 12
	s_cselect_b32 s12, 0, s12
	s_lshl_b32 s12, s12, 7
	s_or_b32 s12, s12, s24
	s_mov_b32 s13, s25
	s_lshl_b64 s[14:15], s[12:13], 9
	s_or_b32 s12, s12, 64
	v_lshl_add_u64 v[2:3], v[102:103], 0, s[14:15]
	s_lshl_b64 s[12:13], s[12:13], 9
	v_lshl_add_u64 v[4:5], v[104:105], 0, s[14:15]
	global_load_dwordx4 v[46:49], v[2:3], off
	global_load_dwordx4 v[54:57], v[4:5], off
	v_lshl_add_u64 v[2:3], v[102:103], 0, s[12:13]
	v_lshl_add_u64 v[4:5], v[104:105], 0, s[12:13]
	global_load_dwordx4 v[58:61], v[2:3], off
	global_load_dwordx4 v[62:65], v[4:5], off

.LBB0_316:
	s_nop 11
	v_sub_f32_e32 v4, v142, v141
	v_sub_f32_e32 v3, v111, v141
	v_mul_f32_e32 v4, 0x3fb8aa3b, v4
	v_mul_f32_e32 v3, 0x3fb8aa3b, v3
	v_exp_f32_e32 v4, v4
	v_exp_f32_e32 v6, v3
	v_mul_f32_e32 v8, v4, v18
	v_mul_f32_e32 v9, v4, v19
	v_fma_f32 v112, v112, v6, v8
	v_fma_f32 v113, v113, v6, v9
	v_mul_f32_e32 v8, v4, v20
	v_mul_f32_e32 v9, v4, v21
	v_fma_f32 v114, v114, v6, v8
	v_fma_f32 v115, v115, v6, v9
	v_mul_f32_e32 v8, v4, v22
	v_mul_f32_e32 v9, v4, v23
	v_fma_f32 v116, v116, v6, v8
	v_fma_f32 v117, v117, v6, v9
	v_mul_f32_e32 v8, v4, v24
	v_mul_f32_e32 v9, v4, v25
	v_fma_f32 v118, v118, v6, v8
	v_fma_f32 v119, v119, v6, v9
	v_mul_f32_e32 v8, v4, v26
	v_mul_f32_e32 v9, v4, v27
	v_fma_f32 v120, v120, v6, v8
	v_fma_f32 v121, v121, v6, v9
	v_mul_f32_e32 v8, v4, v28
	v_mul_f32_e32 v9, v4, v29
	v_fma_f32 v122, v122, v6, v8
	v_fma_f32 v123, v123, v6, v9
	v_mul_f32_e32 v8, v4, v30
	v_mul_f32_e32 v9, v4, v31
	v_fma_f32 v124, v124, v6, v8
	v_fma_f32 v125, v125, v6, v9
	v_mul_f32_e32 v10, v4, v32
	v_mov_b32_e32 v32, v127
	v_mov_b32_e32 v7, v4
	v_mul_f32_e32 v12, v32, v6
	v_mul_f32_e32 v13, v33, v7
	v_mov_b32_e32 v111, v4
	v_mov_b32_e32 v7, v2
	v_mul_f32_e32 v2, v110, v6
	v_mul_f32_e32 v3, v111, v7
	v_mul_f32_e32 v8, v126, v6
	v_mov_b32_e32 v9, v12
	v_mov_b32_e32 v11, v13
	v_add_f32_e32 v2, v2, v3
	v_add_f32_e32 v126, v8, v10
	v_add_f32_e32 v127, v9, v11
	v_cndmask_b32_e64 v110, v110, v2, s[2:3]
	s_add_i32 s12, s19, -3
	s_cmp_gt_u32 s12, 17
	v_add_f32_e32 v111, v0, v141
	s_cbranch_scc1 .LBB0_299
.LBB0_317:
	s_waitcnt vmcnt(16)
	v_add_u32_e32 v0, 0x10400, v138
	ds_write_b128 v137, v[70:73]
	ds_read_b32 v0, v0
	v_cvt_f32_f16_sdwa v3, v66 dst_sel:DWORD dst_unused:UNUSED_PAD src0_sel:WORD_1
	v_cvt_f32_f16_e32 v2, v66
	v_cvt_f32_f16_sdwa v5, v67 dst_sel:DWORD dst_unused:UNUSED_PAD src0_sel:WORD_1
	v_cvt_f32_f16_e32 v4, v67
	v_cvt_f32_f16_sdwa v7, v69 dst_sel:DWORD dst_unused:UNUSED_PAD src0_sel:WORD_1
	s_waitcnt lgkmcnt(0)
	v_mul_f32_e32 v2, v0, v2
	v_mul_f32_e32 v3, v0, v3
	v_cvt_pk_f16_f32 v2, v2, v3
	v_mul_f32_e32 v4, v0, v4
	v_mul_f32_e32 v5, v0, v5
	v_cvt_pk_f16_f32 v3, v4, v5
	v_cvt_f32_f16_sdwa v5, v68 dst_sel:DWORD dst_unused:UNUSED_PAD src0_sel:WORD_1
	v_cvt_f32_f16_e32 v4, v68
	v_cvt_f32_f16_e32 v6, v69
	s_cmp_gt_u32 s76, 11
	v_mul_f32_e32 v4, v0, v4
	v_mul_f32_e32 v5, v0, v5
	v_mul_f32_e32 v6, v0, v6
	v_mul_f32_e32 v7, v0, v7
	v_cvt_pk_f16_f32 v4, v4, v5
	v_cvt_pk_f16_f32 v5, v6, v7
	ds_write_b128 v137, v[2:5] offset:32768
	ds_write_b128 v137, v[78:81] offset:4096
	v_add_u32_e32 v0, 0x10500, v138
	ds_read_b32 v0, v0
	v_cvt_f32_f16_sdwa v3, v74 dst_sel:DWORD dst_unused:UNUSED_PAD src0_sel:WORD_1
	v_cvt_f32_f16_e32 v2, v74
	v_cvt_f32_f16_sdwa v5, v75 dst_sel:DWORD dst_unused:UNUSED_PAD src0_sel:WORD_1
	v_cvt_f32_f16_e32 v4, v75
	v_cvt_f32_f16_sdwa v7, v77 dst_sel:DWORD dst_unused:UNUSED_PAD src0_sel:WORD_1
	s_waitcnt lgkmcnt(0)
	v_mul_f32_e32 v2, v0, v2
	v_mul_f32_e32 v3, v0, v3
	v_cvt_pk_f16_f32 v2, v2, v3
	v_mul_f32_e32 v4, v0, v4
	v_mul_f32_e32 v5, v0, v5
	v_cvt_pk_f16_f32 v3, v4, v5
	v_cvt_f32_f16_sdwa v5, v76 dst_sel:DWORD dst_unused:UNUSED_PAD src0_sel:WORD_1
	v_cvt_f32_f16_e32 v4, v76
	v_cvt_f32_f16_e32 v6, v77
	v_mul_f32_e32 v4, v0, v4
	v_mul_f32_e32 v5, v0, v5
	v_mul_f32_e32 v6, v0, v6
	v_mul_f32_e32 v7, v0, v7
	v_cvt_pk_f16_f32 v4, v4, v5
	v_cvt_pk_f16_f32 v5, v6, v7
	ds_write_b128 v137, v[2:5] offset:36864
	s_nop 0
	s_add_i32 s14, s29, 1
	s_add_i32 s15, s19, -1
	s_and_b64 s[12:13], s[0:1], exec
	s_cselect_b32 s12, s15, s14
	s_cmp_gt_u32 s76, 11
	s_cselect_b32 s12, 0, s12
	s_lshl_b32 s12, s12, 7
	s_add_u32 s12, s24, s12
	s_addc_u32 s13, s25, 0
	s_lshl_b64 s[12:13], s[12:13], 9
	v_lshl_add_u64 v[2:3], v[102:103], 0, s[12:13]
	v_lshl_add_u64 v[4:5], v[104:105], 0, s[12:13]
	s_bitset1_b32 s12, 15
	global_load_dwordx4 v[66:69], v[2:3], off
	global_load_dwordx4 v[70:73], v[4:5], off
	v_lshl_add_u64 v[2:3], v[102:103], 0, s[12:13]
	v_lshl_add_u64 v[4:5], v[104:105], 0, s[12:13]
	global_load_dwordx4 v[74:77], v[2:3], off
	global_load_dwordx4 v[78:81], v[4:5], off

.LBB0_342:
	s_nop 11
	v_sub_f32_e32 v4, v141, v140
	v_sub_f32_e32 v3, v111, v140
	v_mul_f32_e32 v4, 0x3fb8aa3b, v4
	v_mul_f32_e32 v3, 0x3fb8aa3b, v3
	v_exp_f32_e32 v4, v4
	v_exp_f32_e32 v6, v3
	v_mul_f32_e32 v8, v4, v18
	v_mul_f32_e32 v9, v4, v19
	v_fma_f32 v112, v112, v6, v8
	v_fma_f32 v113, v113, v6, v9
	v_mul_f32_e32 v8, v4, v20
	v_mul_f32_e32 v9, v4, v21
	v_fma_f32 v114, v114, v6, v8
	v_fma_f32 v115, v115, v6, v9
	v_mul_f32_e32 v8, v4, v22
	v_mul_f32_e32 v9, v4, v23
	v_fma_f32 v116, v116, v6, v8
	v_fma_f32 v117, v117, v6, v9
	v_mul_f32_e32 v8, v4, v24
	v_mul_f32_e32 v9, v4, v25
	v_fma_f32 v118, v118, v6, v8
	v_fma_f32 v119, v119, v6, v9
	v_mul_f32_e32 v8, v4, v26
	v_mul_f32_e32 v9, v4, v27
	v_fma_f32 v120, v120, v6, v8
	v_fma_f32 v121, v121, v6, v9
	v_mul_f32_e32 v8, v4, v28
	v_mul_f32_e32 v9, v4, v29
	v_fma_f32 v122, v122, v6, v8
	v_fma_f32 v123, v123, v6, v9
	v_mul_f32_e32 v8, v4, v30
	v_mul_f32_e32 v9, v4, v31
	v_fma_f32 v124, v124, v6, v8
	v_fma_f32 v125, v125, v6, v9
	v_mul_f32_e32 v10, v4, v32
	v_mov_b32_e32 v32, v127
	v_mov_b32_e32 v7, v4
	v_mul_f32_e32 v12, v32, v6
	v_mul_f32_e32 v13, v33, v7
	v_mov_b32_e32 v111, v4
	v_mov_b32_e32 v7, v2
	v_mul_f32_e32 v2, v110, v6
	v_mul_f32_e32 v3, v111, v7
	v_mul_f32_e32 v8, v126, v6
	v_mov_b32_e32 v9, v12
	v_mov_b32_e32 v11, v13
	v_add_f32_e32 v2, v2, v3
	v_add_f32_e32 v126, v8, v10
	v_add_f32_e32 v127, v9, v11
	v_cndmask_b32_e64 v110, v110, v2, s[2:3]

.LBB0_344:
	s_waitcnt vmcnt(16)
	v_add_u32_e32 v0, 0x10600, v138
	ds_write_b128 v137, v[86:89] offset:16384
	ds_read_b32 v0, v0
	v_cvt_f32_f16_sdwa v3, v82 dst_sel:DWORD dst_unused:UNUSED_PAD src0_sel:WORD_1
	v_cvt_f32_f16_e32 v2, v82
	v_cvt_f32_f16_sdwa v5, v83 dst_sel:DWORD dst_unused:UNUSED_PAD src0_sel:WORD_1
	v_cvt_f32_f16_e32 v4, v83
	v_cvt_f32_f16_sdwa v7, v85 dst_sel:DWORD dst_unused:UNUSED_PAD src0_sel:WORD_1
	s_waitcnt lgkmcnt(0)
	v_mul_f32_e32 v2, v0, v2
	v_mul_f32_e32 v3, v0, v3
	v_cvt_pk_f16_f32 v2, v2, v3
	v_mul_f32_e32 v4, v0, v4
	v_mul_f32_e32 v5, v0, v5
	v_cvt_pk_f16_f32 v3, v4, v5
	v_cvt_f32_f16_sdwa v5, v84 dst_sel:DWORD dst_unused:UNUSED_PAD src0_sel:WORD_1
	v_cvt_f32_f16_e32 v4, v84
	v_cvt_f32_f16_e32 v6, v85
	s_cmp_gt_u32 s76, 10
	v_mul_f32_e32 v4, v0, v4
	v_mul_f32_e32 v5, v0, v5
	v_mul_f32_e32 v6, v0, v6
	v_mul_f32_e32 v7, v0, v7
	v_cvt_pk_f16_f32 v4, v4, v5
	v_cvt_pk_f16_f32 v5, v6, v7
	ds_write_b128 v137, v[2:5] offset:49152
	s_nop 0
	ds_write_b128 v137, v[94:97] offset:20480
	v_add_u32_e32 v0, 0x10700, v138
	ds_read_b32 v0, v0
	v_cvt_f32_f16_sdwa v3, v90 dst_sel:DWORD dst_unused:UNUSED_PAD src0_sel:WORD_1
	v_cvt_f32_f16_e32 v2, v90
	v_cvt_f32_f16_sdwa v5, v91 dst_sel:DWORD dst_unused:UNUSED_PAD src0_sel:WORD_1
	v_cvt_f32_f16_e32 v4, v91
	v_cvt_f32_f16_sdwa v7, v93 dst_sel:DWORD dst_unused:UNUSED_PAD src0_sel:WORD_1
	s_waitcnt lgkmcnt(0)
	v_mul_f32_e32 v2, v0, v2
	v_mul_f32_e32 v3, v0, v3
	v_cvt_pk_f16_f32 v2, v2, v3
	v_mul_f32_e32 v4, v0, v4
	v_mul_f32_e32 v5, v0, v5
	v_cvt_pk_f16_f32 v3, v4, v5
	v_cvt_f32_f16_sdwa v5, v92 dst_sel:DWORD dst_unused:UNUSED_PAD src0_sel:WORD_1
	v_cvt_f32_f16_e32 v4, v92
	v_cvt_f32_f16_e32 v6, v93
	v_mul_f32_e32 v4, v0, v4
	v_mul_f32_e32 v5, v0, v5
	v_mul_f32_e32 v6, v0, v6
	v_mul_f32_e32 v7, v0, v7
	v_cvt_pk_f16_f32 v4, v4, v5
	v_cvt_pk_f16_f32 v5, v6, v7
	ds_write_b128 v137, v[2:5] offset:53248
	s_nop 0
	s_and_b64 s[12:13], s[0:1], exec
	s_cselect_b32 s12, s19, s29
	s_cmp_gt_u32 s76, 10
	s_cselect_b32 s12, 0, s12
	s_lshl_b32 s12, s12, 7
	s_add_u32 s12, s24, s12
	s_addc_u32 s13, s25, 0
	s_lshl_b64 s[12:13], s[12:13], 9
	v_lshl_add_u64 v[2:3], v[102:103], 0, s[12:13]
	v_lshl_add_u64 v[4:5], v[104:105], 0, s[12:13]
	s_bitset1_b32 s12, 15
	global_load_dwordx4 v[82:85], v[2:3], off
	global_load_dwordx4 v[86:89], v[4:5], off
	v_lshl_add_u64 v[2:3], v[102:103], 0, s[12:13]
	v_lshl_add_u64 v[4:5], v[104:105], 0, s[12:13]
	global_load_dwordx4 v[90:93], v[2:3], off
	global_load_dwordx4 v[94:97], v[4:5], off

; #define LAS __attribute__((address_space(3)))
; __device__ __forceinline__ float siluf(float x) { return x * __builtin_amdgcn_rcpf(1.f + __builtin_amdgcn_exp2f(-1.4426950408889634f * x)); }
; __device__ __forceinline__ float sigmf(float x) { return __builtin_amdgcn_rcpf(1.f + __builtin_amdgcn_exp2f(-1.4426950408889634f * x)); }
; __device__ __forceinline__ float oct_sum(float s) { s += dpp_f<0xB1>(s); s += dpp_f<0x4E>(s); s += dpp_f<0x141>(s); return s; }
; #define LDS_WAIT() asm volatile("s_waitcnt lgkmcnt(0)" ::: "memory")
; #define BAR_LDS() asm volatile("s_waitcnt lgkmcnt(0)\n\ts_barrier" ::: "memory")
; __device__ __forceinline__ int crow(int r, int hi) { return (r & 3) + 8 * (r >> 2) + 4 * hi; }
; __device__ __forceinline__ void mlstm_out_loop(unsigned char* ws, h16* Y, const float* ghead  , int u  , const int o_mout, const int o_end, const int ntc, const bool ctx_out, ...
;     ...
;         if (hi == 0) wsf[r32] = __builtin_amdgcn_rcpf(hden);
;         LDS_WAIT();
;         LAS h16* ost = (LAS h16*)(lds + MO_OST) + wid * 2048;
; #pragma unroll
;         for (int r = 0; r < 16; ++r) { const int orow = crow(r, hi); const float rl = wsf[orow];
; #pragma unroll
;             for (int d0 = 0; d0 < 2; ++d0) ost[orow * 64 + d0 * 32 + r32] = (h16)(o[d0][r] * rl); }
;         BAR_LDS();
; #pragma unroll
;         for (int ps = 0; ps < 2; ++ps) { const int row = 64 * ps + frow, wt = row >> 5, tr = row & 31; const LAS h16* pf = (const LAS h16*)(lds + MO_OST) + wt * 2048 + tr * 64 + fc8 * 8; const LAS h16* pb = pf + 4 * 2048;
;           const h16x8 af = *(const LAS h16x8*)pf, ab = *(const LAS h16x8*)pb;
;           float x[8]; float ss = 0.f;
; #pragma unroll
;           for (int j = 0; j < 8; ++j) { x[j] = (float)af[j] + (float)ab[j]; ss += x[j] * x[j]; }
;           ss = oct_sum(ss);
;           const float rn = __builtin_amdgcn_rsqf(ss * (1.f / 64.f) + EPS); const LAS float* gh = (const LAS float*)(lds + MO_GH) + h * 64 + fc8 * 8;
;           const h16x8 co = ps ? co1 : co0, cz = ps ? cz1 : cz0;
;           float y[8];
; #pragma unroll
;           for (int j = 0; j < 8; ++j) y[j] = sigmf((float)co[j]) * (x[j] * rn * gh[j]) * siluf((float)cz[j]);
.LBB0_391:
	s_or_b64 exec, exec, s[0:1]
	s_waitcnt lgkmcnt(0)
	v_add_u32_e32 v34, 0x9400, v180
	ds_read2_b32 v[34:35], v34 offset1:1
	s_waitcnt vmcnt(1)
	v_cvt_f32_f16_e32 v38, v106
	v_cvt_f32_f16_sdwa v39, v106 dst_sel:DWORD dst_unused:UNUSED_PAD src0_sel:WORD_1
	v_readlane_b32 s44, v251, 0
	v_readlane_b32 s45, v251, 1
	s_waitcnt lgkmcnt(0)
	v_fma_mixlo_f16 v2, v2, v34, 0
	ds_write_b16 v193, v2 offset:40960
	v_fma_mixlo_f16 v2, v18, v34, 0
	ds_write_b16 v193, v2 offset:41024
	v_fma_mixlo_f16 v2, v3, v35, 0
	ds_write_b16 v194, v2 offset:40960
	v_fma_mixlo_f16 v2, v19, v35, 0
	ds_write_b16 v194, v2 offset:41024
	v_add_u32_e32 v2, 0x9408, v180
	ds_read2_b32 v[2:3], v2 offset1:1
	s_mov_b32 s21, s40
	s_and_b64 vcc, exec, s[6:7]
	s_mov_b32 s76, s25
	v_readlane_b32 s46, v251, 2
	s_waitcnt lgkmcnt(0)
	v_fma_mixlo_f16 v4, v4, v2, 0
	v_fma_mixlo_f16 v2, v20, v2, 0
	ds_write_b16 v195, v2 offset:41024
	v_fma_mixlo_f16 v2, v5, v3, 0
	ds_write_b16 v196, v2 offset:40960
	v_fma_mixlo_f16 v2, v21, v3, 0
	ds_write_b16 v196, v2 offset:41024
	v_add_u32_e32 v2, 0x9420, v180
	ds_read2_b32 v[2:3], v2 offset1:1
	ds_write_b16 v195, v4 offset:40960
	v_readlane_b32 s47, v251, 3
	v_readlane_b32 s48, v251, 4
	v_readlane_b32 s49, v251, 5
	s_waitcnt lgkmcnt(1)
	v_fma_mixlo_f16 v4, v6, v2, 0
	v_fma_mixlo_f16 v2, v22, v2, 0
	ds_write_b16 v197, v2 offset:41024
	v_fma_mixlo_f16 v2, v7, v3, 0
	ds_write_b16 v198, v2 offset:40960
	v_fma_mixlo_f16 v2, v23, v3, 0
	ds_write_b16 v198, v2 offset:41024
	v_add_u32_e32 v2, 0x9428, v180
	ds_read2_b32 v[2:3], v2 offset1:1
	ds_write_b16 v197, v4 offset:40960
	v_readlane_b32 s50, v251, 6
	v_readlane_b32 s51, v251, 7
	s_waitcnt lgkmcnt(1)
	v_fma_mixlo_f16 v4, v8, v2, 0
	v_fma_mixlo_f16 v2, v24, v2, 0
	ds_write_b16 v199, v2 offset:41024
	v_fma_mixlo_f16 v2, v9, v3, 0
	ds_write_b16 v200, v2 offset:40960
	v_fma_mixlo_f16 v2, v25, v3, 0
	ds_write_b16 v200, v2 offset:41024
	v_add_u32_e32 v2, 0x9440, v180
	ds_read2_b32 v[2:3], v2 offset1:1
	ds_write_b16 v199, v4 offset:40960
	s_waitcnt lgkmcnt(1)
	v_fma_mixlo_f16 v4, v10, v2, 0
	v_fma_mixlo_f16 v2, v26, v2, 0
	ds_write_b16 v201, v2 offset:41024
	v_fma_mixlo_f16 v2, v11, v3, 0
	ds_write_b16 v202, v2 offset:40960
	v_fma_mixlo_f16 v2, v27, v3, 0
	ds_write_b16 v202, v2 offset:41024
	v_add_u32_e32 v2, 0x9448, v180
	ds_read2_b32 v[2:3], v2 offset1:1
	ds_write_b16 v201, v4 offset:40960
	v_cvt_f32_f16_e32 v10, v110
	s_waitcnt lgkmcnt(1)
	v_fma_mixlo_f16 v4, v12, v2, 0
	v_fma_mixlo_f16 v2, v28, v2, 0
	ds_write_b16 v203, v2 offset:41024
	v_fma_mixlo_f16 v2, v13, v3, 0
	ds_write_b16 v204, v2 offset:40960
	v_fma_mixlo_f16 v2, v29, v3, 0
	ds_write_b16 v204, v2 offset:41024
	v_add_u32_e32 v2, 0x9460, v180
	ds_read2_b32 v[2:3], v2 offset1:1
	ds_write_b16 v203, v4 offset:40960
	v_mul_f32_e32 v10, 0xbfb8aa3b, v10
	v_exp_f32_e32 v10, v10
	v_lshl_add_u32 v28, s20, 2, v164
	s_waitcnt lgkmcnt(1)
	v_fma_mixlo_f16 v4, v14, v2, 0
	v_fma_mixlo_f16 v2, v30, v2, 0
	ds_write_b16 v205, v2 offset:41024
	v_fma_mixlo_f16 v2, v15, v3, 0
	ds_write_b16 v206, v2 offset:40960
	v_fma_mixlo_f16 v2, v31, v3, 0
	ds_write_b16 v206, v2 offset:41024
	v_add_u32_e32 v2, 0x9468, v180
	ds_read2_b32 v[2:3], v2 offset1:1
	v_add_f32_e32 v10, 1.0, v10
	ds_write_b16 v205, v4 offset:40960
	v_mul_f32_e32 v29, 0xbfb8aa3b, v39
	v_exp_f32_e32 v29, v29
	s_waitcnt lgkmcnt(1)
	v_fma_mixlo_f16 v4, v16, v2, 0
	v_rcp_f32_e32 v16, v10
	v_cvt_f32_f16_sdwa v10, v110 dst_sel:DWORD dst_unused:UNUSED_PAD src0_sel:WORD_1
	v_fma_mixlo_f16 v2, v32, v2, 0
	ds_write_b16 v207, v2 offset:41024
	v_fma_mixlo_f16 v2, v17, v3, 0
	v_mul_f32_e32 v10, 0xbfb8aa3b, v10
	v_exp_f32_e32 v10, v10
	ds_write_b16 v213, v2 offset:40960
	v_fma_mixlo_f16 v2, v33, v3, 0
	ds_write_b16 v207, v4 offset:40960
	v_add_f32_e32 v10, 1.0, v10
	v_rcp_f32_e32 v17, v10
	v_cvt_f32_f16_e32 v10, v111
	ds_write_b16 v213, v2 offset:41024
	s_waitcnt lgkmcnt(0)
	s_barrier
	ds_read_b128 v[6:9], v181 offset:40960
	ds_read_b128 v[2:5], v181 offset:57344
	v_mul_f32_e32 v10, 0xbfb8aa3b, v10
	v_exp_f32_e32 v10, v10
	v_add_f32_e32 v29, 1.0, v29
	s_waitcnt lgkmcnt(1)
	v_cvt_f32_f16_sdwa v11, v9 dst_sel:DWORD dst_unused:UNUSED_PAD src0_sel:WORD_1
	s_waitcnt lgkmcnt(0)
	v_cvt_f32_f16_sdwa v13, v5 dst_sel:DWORD dst_unused:UNUSED_PAD src0_sel:WORD_1
	v_add_f32_e32 v10, 1.0, v10
	v_rcp_f32_e32 v18, v10
	v_cvt_f32_f16_sdwa v10, v111 dst_sel:DWORD dst_unused:UNUSED_PAD src0_sel:WORD_1
	v_cvt_f32_f16_e32 v12, v5
	v_cvt_f32_f16_sdwa v5, v4 dst_sel:DWORD dst_unused:UNUSED_PAD src0_sel:WORD_1
	v_cvt_f32_f16_e32 v4, v4
	v_mul_f32_e32 v10, 0xbfb8aa3b, v10
	v_exp_f32_e32 v10, v10
	v_rcp_f32_e32 v41, v29
	s_lshl_b32 s20, s20, 1
	v_add_f32_e32 v10, 1.0, v10
	v_rcp_f32_e32 v19, v10
	v_cvt_f32_f16_e32 v10, v112
	v_mul_f32_e32 v10, 0xbfb8aa3b, v10
	v_exp_f32_e32 v10, v10
	s_nop 0
	v_add_f32_e32 v10, 1.0, v10
	v_rcp_f32_e32 v22, v10
	v_cvt_f32_f16_sdwa v10, v112 dst_sel:DWORD dst_unused:UNUSED_PAD src0_sel:WORD_1
	v_mul_f32_e32 v10, 0xbfb8aa3b, v10
	v_exp_f32_e32 v10, v10
	s_nop 0
	v_add_f32_e32 v10, 1.0, v10
	v_rcp_f32_e32 v23, v10
	v_cvt_f32_f16_e32 v10, v113
	v_mul_f32_e32 v10, 0xbfb8aa3b, v10
	v_exp_f32_e32 v10, v10
	s_nop 0
	v_add_f32_e32 v10, 1.0, v10
	v_rcp_f32_e32 v20, v10
	v_cvt_f32_f16_sdwa v10, v113 dst_sel:DWORD dst_unused:UNUSED_PAD src0_sel:WORD_1
	v_mul_f32_e32 v10, 0xbfb8aa3b, v10
	v_exp_f32_e32 v10, v10
	s_nop 0
	v_add_f32_e32 v10, 1.0, v10
	v_rcp_f32_e32 v21, v10
	v_cvt_f32_f16_e32 v10, v9
	v_cvt_f32_f16_sdwa v9, v8 dst_sel:DWORD dst_unused:UNUSED_PAD src0_sel:WORD_1
	v_cvt_f32_f16_e32 v8, v8
	v_add_f32_e32 v24, v10, v12
	v_add_f32_e32 v25, v11, v13
	v_cvt_f32_f16_sdwa v13, v108 dst_sel:DWORD dst_unused:UNUSED_PAD src0_sel:WORD_1
; #define LAS __attribute__((address_space(3)))
; #define GAS __attribute__((address_space(1)))
; __device__ __forceinline__ float siluf(float x) { return x * __builtin_amdgcn_rcpf(1.f + __builtin_amdgcn_exp2f(-1.4426950408889634f * x)); }
; __device__ __forceinline__ float sigmf(float x) { return __builtin_amdgcn_rcpf(1.f + __builtin_amdgcn_exp2f(-1.4426950408889634f * x)); }
; __device__ __forceinline__ float oct_sum(float s) { s += dpp_f<0xB1>(s); s += dpp_f<0x4E>(s); s += dpp_f<0x141>(s); return s; }
; __device__ __forceinline__ unsigned cvtpk_h(float lo, float hi) { f32x2 v = {lo, hi}; h16x2 b = __builtin_convertvector(v, h16x2); return __builtin_bit_cast(unsigned, b); }
; __device__ __forceinline__ void mlstm_out_loop(unsigned char* ws, h16* Y, const float* ghead  , int u  , const int o_mout, const int o_end, const int ntc, const bool ctx_out, ...
;     ...
;         for (int ps = 0; ps < 2; ++ps) { const int row = 64 * ps + frow, wt = row >> 5, tr = row & 31; const LAS h16* pf = (const LAS h16*)(lds + MO_OST) + wt * 2048 + tr * 64 + fc8 * 8; const LAS h16* pb = pf + 4 * 2048;
;           const h16x8 af = *(const LAS h16x8*)pf, ab = *(const LAS h16x8*)pb;
;           float x[8]; float ss = 0.f;
; #pragma unroll
;           for (int j = 0; j < 8; ++j) { x[j] = (float)af[j] + (float)ab[j]; ss += x[j] * x[j]; }
;           ss = oct_sum(ss);
;           const float rn = __builtin_amdgcn_rsqf(ss * (1.f / 64.f) + EPS); const LAS float* gh = (const LAS float*)(lds + MO_GH) + h * 64 + fc8 * 8;
;           const h16x8 co = ps ? co1 : co0, cz = ps ? cz1 : cz0;
;           float y[8];
; #pragma unroll
;           for (int j = 0; j < 8; ++j) y[j] = sigmf((float)co[j]) * (x[j] * rn * gh[j]) * siluf((float)cz[j]);
;           u32x4 w0; w0.x = cvtpk_h(y[0], y[1]); w0.y = cvtpk_h(y[2], y[3]); w0.z = cvtpk_h(y[4], y[5]); w0.w = cvtpk_h(y[6], y[7]);
;           *(GAS u32x4*)(Y + (rb + row) * D + 768 + h * 64 + fc8 * 8) = w0; }
	v_cvt_f32_f16_e32 v12, v108
	v_add_f32_e32 v8, v8, v4
	v_add_f32_e32 v9, v9, v5
	v_mul_f32_e32 v26, v24, v24
	v_mul_f32_e32 v27, v25, v25
	v_mul_f32_e32 v15, 0xbfb8aa3b, v13
	v_mul_f32_e32 v10, 0xbfb8aa3b, v12
	v_exp_f32_e32 v10, v10
	v_exp_f32_e32 v15, v15
	v_mul_f32_e32 v4, v8, v8
	v_mul_f32_e32 v5, v9, v9
	v_add_f32_e32 v10, 1.0, v10
	v_add_f32_e32 v15, 1.0, v15
	v_rcp_f32_e32 v14, v10
	v_rcp_f32_e32 v15, v15
	ds_read2_b32 v[10:11], v28 offset0:4 offset1:5
	v_mul_f32_e32 v30, v14, v12
	v_mul_f32_e32 v31, v15, v13
	v_cvt_f32_f16_sdwa v13, v7 dst_sel:DWORD dst_unused:UNUSED_PAD src0_sel:WORD_1
	v_cvt_f32_f16_e32 v12, v7
	v_cvt_f32_f16_sdwa v15, v3 dst_sel:DWORD dst_unused:UNUSED_PAD src0_sel:WORD_1
	v_cvt_f32_f16_e32 v14, v3
	v_cvt_f32_f16_sdwa v7, v6 dst_sel:DWORD dst_unused:UNUSED_PAD src0_sel:WORD_1
	v_cvt_f32_f16_e32 v6, v6
	v_add_f32_e32 v32, v12, v14
	v_add_f32_e32 v33, v13, v15
	v_cvt_f32_f16_e32 v14, v107
	v_cvt_f32_f16_sdwa v15, v107 dst_sel:DWORD dst_unused:UNUSED_PAD src0_sel:WORD_1
	v_mul_f32_e32 v34, v32, v32
	v_mul_f32_e32 v35, v33, v33
	ds_read2_b32 v[12:13], v28 offset0:2 offset1:3
	v_mul_f32_e32 v3, 0xbfb8aa3b, v14
	v_exp_f32_e32 v3, v3
	s_nop 0
	v_add_f32_e32 v3, 1.0, v3
	v_rcp_f32_e32 v36, v3
	v_mul_f32_e32 v3, 0xbfb8aa3b, v15
	v_exp_f32_e32 v3, v3
	s_nop 0
	v_add_f32_e32 v3, 1.0, v3
	v_rcp_f32_e32 v37, v3
	v_cvt_f32_f16_sdwa v3, v2 dst_sel:DWORD dst_unused:UNUSED_PAD src0_sel:WORD_1
	v_cvt_f32_f16_e32 v2, v2
	v_mul_f32_e32 v36, v36, v14
	v_mul_f32_e32 v37, v37, v15
	v_mul_f32_e32 v14, 0xbfb8aa3b, v38
	v_add_f32_e32 v2, v6, v2
	v_add_f32_e32 v3, v7, v3
	v_exp_f32_e32 v14, v14
	v_mul_f32_e32 v6, v2, v2
	v_mul_f32_e32 v7, v3, v3
	v_add_f32_e32 v14, 1.0, v14
	v_add_f32_e32 v6, v6, v7
	v_add_f32_e32 v6, v34, v6
	v_add_f32_e32 v6, v35, v6
	v_add_f32_e32 v4, v4, v6
	v_add_f32_e32 v4, v5, v4
	v_add_f32_e32 v4, v26, v4
	v_add_f32_e32 v4, v27, v4
	v_rcp_f32_e32 v40, v14
	ds_read2_b32 v[14:15], v28 offset1:1
	v_add_f32_dpp v4, v4, v4 quad_perm:[1,0,3,2] row_mask:0xf bank_mask:0xf bound_ctrl:1
	v_mul_f32_e32 v38, v40, v38
	v_mul_f32_e32 v39, v41, v39
	s_nop 0
	v_add_f32_dpp v4, v4, v4 quad_perm:[2,3,0,1] row_mask:0xf bank_mask:0xf bound_ctrl:1
	s_nop 1
	v_add_f32_dpp v4, v4, v4 row_half_mirror row_mask:0xf bank_mask:0xf bound_ctrl:1
	v_fmamk_f32 v4, v4, 0x3c800000, v229
	v_rsq_f32_e32 v26, v4
	s_nop 0
	v_mul_f32_e32 v6, v8, v26
	v_mul_f32_e32 v7, v9, v26
	v_cvt_f32_f16_e32 v8, v109
	v_mul_f32_e32 v2, v2, v26
	v_mul_f32_e32 v3, v3, v26
	v_cvt_f32_f16_sdwa v9, v109 dst_sel:DWORD dst_unused:UNUSED_PAD src0_sel:WORD_1
	s_waitcnt lgkmcnt(0)
	v_mul_f32_e32 v2, v14, v2
	v_mul_f32_e32 v3, v15, v3
	v_mul_f32_e32 v4, v32, v26
	v_mul_f32_e32 v5, v33, v26
	v_mul_f32_e32 v2, v16, v2
	v_mul_f32_e32 v3, v17, v3
	v_mul_f32_e32 v16, 0xbfb8aa3b, v8
	v_mul_f32_e32 v4, v12, v4
	v_mul_f32_e32 v5, v13, v5
	v_exp_f32_e32 v16, v16
	v_mul_f32_e32 v4, v18, v4
	v_mul_f32_e32 v5, v19, v5
	v_mul_f32_e32 v19, 0xbfb8aa3b, v9
	v_exp_f32_e32 v19, v19
	v_add_f32_e32 v16, 1.0, v16
	v_rcp_f32_e32 v18, v16
	ds_read2_b32 v[16:17], v28 offset0:6 offset1:7
	v_add_f32_e32 v19, 1.0, v19
	v_mul_f32_e32 v6, v10, v6
	v_mul_f32_e32 v7, v11, v7
	v_rcp_f32_e32 v19, v19
	v_mul_f32_e32 v6, v22, v6
	v_mul_f32_e32 v7, v23, v7
	v_mul_f32_e32 v2, v38, v2
	v_mul_f32_e32 v3, v39, v3
	v_mul_f32_e32 v4, v36, v4
	v_mul_f32_e32 v5, v37, v5
	v_mul_f32_e32 v6, v30, v6
	v_mul_f32_e32 v7, v31, v7
	v_mul_f32_e32 v22, v24, v26
	v_mul_f32_e32 v23, v25, v26
	v_cvt_pk_f16_f32 v2, v2, v3
	s_waitcnt lgkmcnt(0)
	v_mul_f32_e32 v22, v16, v22
	v_mul_f32_e32 v23, v17, v23
	v_cvt_pk_f16_f32 v3, v4, v5
	v_cvt_pk_f16_f32 v4, v6, v7
	v_lshlrev_b64 v[6:7], 11, v[158:159]
	v_mul_f32_e32 v20, v20, v22
	v_mul_f32_e32 v21, v21, v23
	v_mul_f32_e32 v8, v18, v8
	v_mul_f32_e32 v9, v19, v9
	v_lshl_add_u64 v[6:7], s[44:45], 0, v[6:7]
	v_mul_f32_e32 v8, v8, v20
	v_mul_f32_e32 v9, v9, v21
	v_lshl_add_u64 v[6:7], v[6:7], 0, s[20:21]
	v_cvt_pk_f16_f32 v5, v8, v9
	v_lshl_add_u64 v[6:7], v[6:7], 0, v[0:1]
	global_store_dwordx4 v[6:7], v[2:5], off offset:1536 sc1
	ds_read_b128 v[6:9], v182 offset:40960
	ds_read_b128 v[2:5], v182 offset:57344
	s_waitcnt vmcnt(1)
	v_cvt_f32_f16_e32 v36, v99
	v_cvt_f32_f16_sdwa v31, v100 dst_sel:DWORD dst_unused:UNUSED_PAD src0_sel:WORD_1
	v_cvt_f32_f16_e32 v30, v100
	v_cvt_f32_f16_sdwa v37, v99 dst_sel:DWORD dst_unused:UNUSED_PAD src0_sel:WORD_1
	s_waitcnt lgkmcnt(0)
; #define LAS __attribute__((address_space(3)))
; #define GAS __attribute__((address_space(1)))
; __device__ __forceinline__ float siluf(float x) { return x * __builtin_amdgcn_rcpf(1.f + __builtin_amdgcn_exp2f(-1.4426950408889634f * x)); }
; __device__ __forceinline__ float sigmf(float x) { return __builtin_amdgcn_rcpf(1.f + __builtin_amdgcn_exp2f(-1.4426950408889634f * x)); }
; __device__ __forceinline__ float oct_sum(float s) { s += dpp_f<0xB1>(s); s += dpp_f<0x4E>(s); s += dpp_f<0x141>(s); return s; }
; __device__ __forceinline__ unsigned cvtpk_h(float lo, float hi) { f32x2 v = {lo, hi}; h16x2 b = __builtin_convertvector(v, h16x2); return __builtin_bit_cast(unsigned, b); }
; #define BAR_LDS() asm volatile("s_waitcnt lgkmcnt(0)\n\ts_barrier" ::: "memory")
; __device__ __forceinline__ void mlstm_out_loop(unsigned char* ws, h16* Y, const float* ghead  , int u  , const int o_mout, const int o_end, const int ntc, const bool ctx_out, ...
;     ...
;         for (int ps = 0; ps < 2; ++ps) { const int row = 64 * ps + frow, wt = row >> 5, tr = row & 31; const LAS h16* pf = (const LAS h16*)(lds + MO_OST) + wt * 2048 + tr * 64 + fc8 * 8; const LAS h16* pb = pf + 4 * 2048;
;           const h16x8 af = *(const LAS h16x8*)pf, ab = *(const LAS h16x8*)pb;
;           float x[8]; float ss = 0.f;
; #pragma unroll
;           for (int j = 0; j < 8; ++j) { x[j] = (float)af[j] + (float)ab[j]; ss += x[j] * x[j]; }
;           ss = oct_sum(ss);
;           const float rn = __builtin_amdgcn_rsqf(ss * (1.f / 64.f) + EPS); const LAS float* gh = (const LAS float*)(lds + MO_GH) + h * 64 + fc8 * 8;
;           const h16x8 co = ps ? co1 : co0, cz = ps ? cz1 : cz0;
;           float y[8];
; #pragma unroll
;           for (int j = 0; j < 8; ++j) y[j] = sigmf((float)co[j]) * (x[j] * rn * gh[j]) * siluf((float)cz[j]);
;           u32x4 w0; w0.x = cvtpk_h(y[0], y[1]); w0.y = cvtpk_h(y[2], y[3]); w0.z = cvtpk_h(y[4], y[5]); w0.w = cvtpk_h(y[6], y[7]);
;           *(GAS u32x4*)(Y + (rb + row) * D + 768 + h * 64 + fc8 * 8) = w0; }
;         BAR_LDS();
	v_cvt_f32_f16_sdwa v35, v3 dst_sel:DWORD dst_unused:UNUSED_PAD src0_sel:WORD_1
	v_cvt_f32_f16_e32 v34, v3
	v_mul_f32_e32 v3, 0xbfb8aa3b, v36
	v_exp_f32_e32 v3, v3
	v_mul_f32_e32 v32, 0xbfb8aa3b, v30
	v_mul_f32_e32 v33, 0xbfb8aa3b, v31
	v_exp_f32_e32 v32, v32
	v_exp_f32_e32 v33, v33
	v_add_f32_e32 v3, 1.0, v3
	v_rcp_f32_e32 v38, v3
	v_mul_f32_e32 v3, 0xbfb8aa3b, v37
	v_add_f32_e32 v32, 1.0, v32
	v_add_f32_e32 v33, 1.0, v33
	v_exp_f32_e32 v3, v3
	v_rcp_f32_e32 v32, v32
	v_rcp_f32_e32 v33, v33
	v_cvt_f32_f16_sdwa v27, v9 dst_sel:DWORD dst_unused:UNUSED_PAD src0_sel:WORD_1
	v_add_f32_e32 v3, 1.0, v3
	v_rcp_f32_e32 v39, v3
	v_mul_f32_e32 v30, v32, v30
	v_mul_f32_e32 v31, v33, v31
	v_cvt_f32_f16_sdwa v33, v7 dst_sel:DWORD dst_unused:UNUSED_PAD src0_sel:WORD_1
	v_cvt_f32_f16_e32 v32, v7
	v_cvt_f32_f16_sdwa v7, v6 dst_sel:DWORD dst_unused:UNUSED_PAD src0_sel:WORD_1
	v_cvt_f32_f16_e32 v6, v6
	v_cvt_f32_f16_sdwa v3, v2 dst_sel:DWORD dst_unused:UNUSED_PAD src0_sel:WORD_1
	v_cvt_f32_f16_e32 v2, v2
	v_cvt_f32_f16_e32 v26, v9
	v_cvt_f32_f16_sdwa v29, v5 dst_sel:DWORD dst_unused:UNUSED_PAD src0_sel:WORD_1
	v_cvt_f32_f16_e32 v28, v5
	v_cvt_f32_f16_sdwa v9, v8 dst_sel:DWORD dst_unused:UNUSED_PAD src0_sel:WORD_1
	v_cvt_f32_f16_e32 v8, v8
	v_cvt_f32_f16_sdwa v5, v4 dst_sel:DWORD dst_unused:UNUSED_PAD src0_sel:WORD_1
	v_cvt_f32_f16_e32 v4, v4
	v_add_f32_e32 v2, v6, v2
	v_add_f32_e32 v3, v7, v3
	v_add_f32_e32 v32, v32, v34
	v_add_f32_e32 v33, v33, v35
	v_mul_f32_e32 v6, v2, v2
	v_mul_f32_e32 v7, v3, v3
	v_mul_f32_e32 v34, v32, v32
	v_mul_f32_e32 v35, v33, v33
	v_add_f32_e32 v6, v6, v7
	v_add_f32_e32 v4, v8, v4
	v_add_f32_e32 v5, v9, v5
	v_add_f32_e32 v6, v34, v6
	v_mul_f32_e32 v8, v4, v4
	v_mul_f32_e32 v9, v5, v5
	v_add_f32_e32 v6, v35, v6
	v_add_f32_e32 v26, v26, v28
	v_add_f32_e32 v27, v27, v29
	v_add_f32_e32 v6, v8, v6
	v_mul_f32_e32 v28, v26, v26
	v_mul_f32_e32 v29, v27, v27
	v_add_f32_e32 v6, v9, v6
	v_add_f32_e32 v6, v28, v6
	v_add_f32_e32 v6, v29, v6
	v_cvt_f32_f16_e32 v22, v104
	v_cvt_f32_f16_sdwa v23, v104 dst_sel:DWORD dst_unused:UNUSED_PAD src0_sel:WORD_1
	v_add_f32_dpp v6, v6, v6 quad_perm:[1,0,3,2] row_mask:0xf bank_mask:0xf bound_ctrl:1
	v_cvt_f32_f16_e32 v24, v105
	v_cvt_f32_f16_sdwa v25, v105 dst_sel:DWORD dst_unused:UNUSED_PAD src0_sel:WORD_1
	v_add_f32_dpp v6, v6, v6 quad_perm:[2,3,0,1] row_mask:0xf bank_mask:0xf bound_ctrl:1
	v_cvt_f32_f16_e32 v18, v102
	v_cvt_f32_f16_sdwa v19, v102 dst_sel:DWORD dst_unused:UNUSED_PAD src0_sel:WORD_1
	v_add_f32_dpp v6, v6, v6 row_half_mirror row_mask:0xf bank_mask:0xf bound_ctrl:1
	v_fmamk_f32 v6, v6, 0x3c800000, v229
	v_rsq_f32_e32 v6, v6
	v_cvt_f32_f16_e32 v20, v103
	v_cvt_f32_f16_sdwa v21, v103 dst_sel:DWORD dst_unused:UNUSED_PAD src0_sel:WORD_1
	v_mul_f32_e32 v22, 0xbfb8aa3b, v22
	v_mul_f32_e32 v4, v4, v6
	v_mul_f32_e32 v5, v5, v6
	v_mul_f32_e32 v8, v32, v6
	v_mul_f32_e32 v9, v33, v6
	v_mul_f32_e32 v4, v10, v4
	v_mul_f32_e32 v5, v11, v5
	v_cvt_f32_f16_sdwa v11, v101 dst_sel:DWORD dst_unused:UNUSED_PAD src0_sel:WORD_1
	v_cvt_f32_f16_e32 v10, v101
	v_mul_f32_e32 v23, 0xbfb8aa3b, v23
	v_mul_f32_e32 v24, 0xbfb8aa3b, v24
	v_mul_f32_e32 v25, 0xbfb8aa3b, v25
	v_mul_f32_e32 v36, v38, v36
	v_mul_f32_e32 v37, v39, v37
	v_cvt_f32_f16_sdwa v39, v98 dst_sel:DWORD dst_unused:UNUSED_PAD src0_sel:WORD_1
	v_cvt_f32_f16_e32 v38, v98
	v_mul_f32_e32 v2, v2, v6
	v_mul_f32_e32 v3, v3, v6
	v_mul_f32_e32 v8, v12, v8
	v_mul_f32_e32 v9, v13, v9
	v_mul_f32_e32 v7, 0xbfb8aa3b, v10
	v_mul_f32_e32 v13, 0xbfb8aa3b, v11
	v_exp_f32_e32 v22, v22
	v_exp_f32_e32 v23, v23
	v_exp_f32_e32 v24, v24
	v_exp_f32_e32 v25, v25
	v_exp_f32_e32 v7, v7
	v_exp_f32_e32 v13, v13
	v_mul_f32_e32 v18, 0xbfb8aa3b, v18
	v_mul_f32_e32 v19, 0xbfb8aa3b, v19
	v_mul_f32_e32 v20, 0xbfb8aa3b, v20
	v_mul_f32_e32 v21, 0xbfb8aa3b, v21
	v_mul_f32_e32 v40, 0xbfb8aa3b, v38
	v_mul_f32_e32 v41, 0xbfb8aa3b, v39
	v_exp_f32_e32 v18, v18
	v_exp_f32_e32 v19, v19
	v_exp_f32_e32 v20, v20
	v_exp_f32_e32 v21, v21
	v_add_f32_e32 v22, 1.0, v22
	v_add_f32_e32 v23, 1.0, v23
	v_add_f32_e32 v24, 1.0, v24
	v_add_f32_e32 v25, 1.0, v25
	v_exp_f32_e32 v40, v40
	v_exp_f32_e32 v41, v41
	v_add_f32_e32 v7, 1.0, v7
	v_add_f32_e32 v13, 1.0, v13
	v_rcp_f32_e32 v22, v22
	v_rcp_f32_e32 v23, v23
	v_rcp_f32_e32 v24, v24
	v_rcp_f32_e32 v25, v25
	v_rcp_f32_e32 v12, v7
	v_rcp_f32_e32 v13, v13
	v_mul_f32_e32 v7, v27, v6
	v_mul_f32_e32 v6, v26, v6
	v_add_f32_e32 v18, 1.0, v18
	v_add_f32_e32 v19, 1.0, v19
	v_add_f32_e32 v20, 1.0, v20
	v_add_f32_e32 v21, 1.0, v21
	v_add_f32_e32 v40, 1.0, v40
	v_add_f32_e32 v41, 1.0, v41
	v_mul_f32_e32 v6, v16, v6
	v_mul_f32_e32 v7, v17, v7
	v_rcp_f32_e32 v18, v18
	v_rcp_f32_e32 v19, v19
	v_rcp_f32_e32 v20, v20
	v_rcp_f32_e32 v21, v21
	v_rcp_f32_e32 v40, v40
	v_rcp_f32_e32 v41, v41
	v_mul_f32_e32 v4, v22, v4
	v_mul_f32_e32 v5, v23, v5
	v_mul_f32_e32 v6, v24, v6
	v_mul_f32_e32 v7, v25, v7
	v_mul_f32_e32 v10, v12, v10
	v_mul_f32_e32 v11, v13, v11
	v_mul_f32_e32 v4, v30, v4
	v_mul_f32_e32 v5, v31, v5
	v_mul_f32_e32 v6, v10, v6
	v_mul_f32_e32 v7, v11, v7
	v_cvt_pk_f16_f32 v4, v4, v5
	v_cvt_pk_f16_f32 v5, v6, v7
	v_lshl_add_u64 v[6:7], s[16:17], 0, v[156:157]
	v_mul_f32_e32 v2, v14, v2
	v_mul_f32_e32 v3, v15, v3
	v_lshlrev_b64 v[6:7], 11, v[6:7]
	v_mul_f32_e32 v38, v40, v38
	v_mul_f32_e32 v39, v41, v39
	v_mul_f32_e32 v2, v18, v2
	v_mul_f32_e32 v3, v19, v3
	v_mul_f32_e32 v8, v20, v8
	v_mul_f32_e32 v9, v21, v9
	v_lshl_add_u64 v[6:7], s[44:45], 0, v[6:7]
	v_mul_f32_e32 v2, v38, v2
	v_mul_f32_e32 v3, v39, v3
	v_mul_f32_e32 v8, v36, v8
	v_mul_f32_e32 v9, v37, v9
	v_lshl_add_u64 v[6:7], v[6:7], 0, s[20:21]
	v_cvt_pk_f16_f32 v2, v2, v3
	v_cvt_pk_f16_f32 v3, v8, v9
	v_lshl_add_u64 v[6:7], v[6:7], 0, v[0:1]
	global_store_dwordx4 v[6:7], v[2:5], off offset:1536 sc1
	s_waitcnt lgkmcnt(0)
	s_barrier
	s_mov_b64 s[16:17], -1
	s_nop 0
	v_mov_b32_e32 v3, v215
	s_cbranch_vccnz .LBB0_436

; #define LAS __attribute__((address_space(3)))
; #define GAS __attribute__((address_space(1)))
; __device__ __forceinline__ void mlstm_out_loop(unsigned char* ws, h16* Y, const float* ghead  , int u  , const int o_mout, const int o_end, const int ntc, const bool ctx_out, ...
;     ...
;         const int frow = tid >> 3, fc8 = tid & 7; const size_t fgo = (rb + frow) * 256 + h * 64 + fc8 * 8;
;         const h16x8 co0 = *(const GAS h16x8*)((const h16*)(ws + WS_CO) + fgo), co1 = *(const GAS h16x8*)((const h16*)(ws + WS_CO) + fgo + 64 * 256), cz0 = *(const GAS h16x8*)((const h16*)(ws + WS_CZ) + fgo), cz1 = *(const GAS h16x8*)((const h16*)(ws + WS_CZ) + fgo + 64 * 256);
;         s16x8 qr[4], cf[4][2];
; #pragma unroll
;         for (int d0 = 0; d0 < 4; ++d0) qr[d0] = *(const LAS s16x8*)(lds + MO_Q + (2 * d0 + hi) * 2048 + (32 * wl + r32) * 16);
; #pragma unroll
;         for (int ks = 0; ks < 4; ++ks)
; #pragma unroll
;             for (int d0 = 0; d0 < 2; ++d0) cf[ks][d0] = *(const LAS s16x8*)(lds + MO_CF + dir * 8192 + (2 * ks + hi) * 1024 + (32 * d0 + r32) * 16);
;         const int t = 32 * wl + r32;
;         const float m0 = M0[dir], Mt = ML[t], bt = bL[t], inter = __builtin_amdgcn_exp2f((m0 - Mt) * LOG2E);
;         f32x16 o[2]; o[0] = f32x16{}; o[1] = f32x16{}; float sacc = 0.f; const f32x16 zero16 = f32x16{};
;         const unsigned lds0 = (unsigned)(uintptr_t)shm;
;         { float dq = 0.f; const h16 ih = (h16)inter;
; #pragma unroll
;           for (int ks = 0; ks < 4; ++ks) { const h16x8 q8 = H8(qr[ks]); const f32x4 n0 = *(const LAS f32x4*)(NL + 16 * ks + 8 * hi), n1 = *(const LAS f32x4*)(NL + 16 * ks + 8 * hi + 4);
;               dq += ((float)q8[0] * n0[0] + (float)q8[1] * n0[1]) + ((float)q8[2] * n0[2] + (float)q8[3] * n0[3]) + ((float)q8[4] * n1[0] + (float)q8[5] * n1[1]) + ((float)q8[6] * n1[2] + (float)q8[7] * n1[3]);
;               const h16x8 qs = q8 * ih;
; #pragma unroll
;               for (int d0 = 0; d0 < 2; ++d0) o[d0] = __builtin_amdgcn_mfma_f32_32x32x16_f16(qs, H8(cf[ks][d0]), o[d0], 0, 0, 0); }
;           sacc += inter * dq; }
.LBB0_427:
	v_lshl_add_u64 v[158:159], s[16:17], 0, v[138:139]
	v_lshlrev_b64 v[2:3], 8, v[158:159]
	s_lshl_b32 s20, s76, 6
	s_mov_b32 s21, s40
	v_lshl_add_u64 v[2:3], v[2:3], 0, s[20:21]
	v_or_b32_e32 v2, v2, v136
	v_lshlrev_b64 v[2:3], 1, v[2:3]
	v_lshl_add_u64 v[4:5], s[8:9], 0, v[2:3]
	v_add_co_u32_e32 v6, vcc, 0x8000, v4
	v_lshl_add_u64 v[2:3], s[18:19], 0, v[2:3]
	s_nop 0
	v_addc_co_u32_e32 v7, vcc, 0, v5, vcc
	global_load_dwordx4 v[110:113], v[4:5], off
	global_load_dwordx4 v[102:105], v[6:7], off
	v_add_co_u32_e32 v4, vcc, 0x8000, v2
	s_add_i32 s0, s83, s84
	s_nop 0
	v_addc_co_u32_e32 v5, vcc, 0, v3, vcc
	global_load_dwordx4 v[106:109], v[2:3], off
	global_load_dwordx4 v[98:101], v[4:5], off
	v_mov_b32_e32 v2, s0
	ds_read_b128 v[126:129], v190
	ds_read_b128 v[122:125], v190 offset:4096
	ds_read_b128 v[118:121], v190 offset:8192
	ds_read_b128 v[114:117], v190 offset:12288
	ds_read_b32 v10, v2 offset:37376
	ds_read2st64_b32 v[160:161], v175 offset0:128 offset1:132
	ds_read_b128 v[2:5], v191
	ds_read_b128 v[18:21], v191 offset:512
	ds_read_b128 v[38:41], v191 offset:2048
	ds_read_b128 v[42:45], v191 offset:2560
	ds_read_b128 v[6:9], v192 offset:36864
	s_waitcnt lgkmcnt(5)
	v_sub_f32_e32 v10, v10, v161
	v_mul_f32_e32 v10, 0x3fb8aa3b, v10
	v_exp_f32_e32 v210, v10
	ds_read_b128 v[46:49], v191 offset:4096
	ds_read_b128 v[50:53], v191 offset:4608
	ds_read_b128 v[54:57], v191 offset:6144
	ds_read_b128 v[34:37], v191 offset:6656
	ds_read_b128 v[22:25], v192 offset:36880
	ds_read_b128 v[58:61], v192 offset:36928
	v_cvt_f16_f32_e32 v211, v210
	v_cvt_f32_f16_e32 v12, v126
	v_cvt_f32_f16_sdwa v13, v127 dst_sel:DWORD dst_unused:UNUSED_PAD src0_sel:WORD_1
	v_cvt_f32_f16_e32 v11, v127
	v_cvt_f32_f16_sdwa v10, v126 dst_sel:DWORD dst_unused:UNUSED_PAD src0_sel:WORD_1
	v_pk_mul_f16 v29, v129, v211 op_sel_hi:[1,0]
	v_pk_mul_f16 v28, v128, v211 op_sel_hi:[1,0]
	v_pk_mul_f16 v27, v127, v211 op_sel_hi:[1,0]
	v_pk_mul_f16 v26, v126, v211 op_sel_hi:[1,0]
	v_cvt_f32_f16_sdwa v65, v128 dst_sel:DWORD dst_unused:UNUSED_PAD src0_sel:WORD_1
	v_cvt_f32_f16_sdwa v64, v129 dst_sel:DWORD dst_unused:UNUSED_PAD src0_sel:WORD_1
	v_cvt_f32_f16_e32 v33, v128
	v_cvt_f32_f16_e32 v32, v129
	s_waitcnt lgkmcnt(6)
	v_mov_b32_e32 v14, v7
	v_mov_b32_e32 v7, v9
	v_mov_b32_e32 v15, v8
	v_mul_f32_e32 v6, v6, v12
	v_mul_f32_e32 v7, v7, v13
	s_waitcnt lgkmcnt(1)
	v_mov_b32_e32 v63, v22
	v_mov_b32_e32 v22, v25
	v_fma_f32 v30, v14, v10, v6
	v_fma_f32 v31, v15, v11, v7
	v_mov_b32_e32 v62, v24
	v_mul_f32_e32 v22, v22, v64
	v_mul_f32_e32 v23, v23, v65
	v_mfma_f32_32x32x16_f16 v[2:17], v[26:29], v[2:5], 0
	v_fma_f32 v22, v62, v32, v22
	v_fma_f32 v23, v63, v33, v23
	v_add_f32_e32 v24, v30, v31
	v_add_f32_e32 v23, v24, v23
	v_add_f32_e32 v62, v22, v23
	v_add_f32_e32 v132, 0, v62
	v_pk_mul_f16 v65, v125, v211 op_sel_hi:[1,0]
	v_pk_mul_f16 v64, v124, v211 op_sel_hi:[1,0]
	v_mfma_f32_32x32x16_f16 v[18:33], v[26:29], v[18:21], 0
	v_pk_mul_f16 v63, v123, v211 op_sel_hi:[1,0]
	v_pk_mul_f16 v62, v122, v211 op_sel_hi:[1,0]
	v_cvt_f32_f16_e32 v220, v122
	v_cvt_f32_f16_sdwa v221, v123 dst_sel:DWORD dst_unused:UNUSED_PAD src0_sel:WORD_1
	v_cvt_f32_f16_e32 v135, v123
	v_cvt_f32_f16_sdwa v134, v122 dst_sel:DWORD dst_unused:UNUSED_PAD src0_sel:WORD_1
	s_waitcnt lgkmcnt(0)
	v_mov_b32_e32 v218, v59
	v_mov_b32_e32 v59, v61
	v_mov_b32_e32 v219, v60
	v_mfma_f32_32x32x16_f16 v[2:17], v[62:65], v[38:41], v[2:17]
	v_mul_f32_e64 v38, v58, v220
	v_mul_f32_e64 v39, v59, v221
	v_cvt_f32_f16_sdwa v221, v124 dst_sel:DWORD dst_unused:UNUSED_PAD src0_sel:WORD_1
	v_fma_f32 v38, v218, v134, v38
	v_fma_f32 v39, v219, v135, v39
	v_cvt_f32_f16_sdwa v220, v125 dst_sel:DWORD dst_unused:UNUSED_PAD src0_sel:WORD_1
	v_add_f32_e32 v134, v38, v39
	v_add_f32_e32 v135, v39, v38
	v_cvt_f32_f16_e32 v219, v124
	v_cvt_f32_f16_e32 v218, v125
	v_mfma_f32_32x32x16_f16 v[18:33], v[62:65], v[42:45], v[18:33]
	ds_read_b128 v[38:41], v192 offset:36944
	ds_read_b128 v[42:45], v192 offset:36992
	v_pk_mul_f16 v61, v121, v211 op_sel_hi:[1,0]
	v_pk_mul_f16 v60, v120, v211 op_sel_hi:[1,0]
	v_pk_mul_f16 v59, v119, v211 op_sel_hi:[1,0]
	v_pk_mul_f16 v58, v118, v211 op_sel_hi:[1,0]
	s_waitcnt lgkmcnt(1)
	v_mov_b32_e32 v63, v38
	v_mov_b32_e32 v38, v41
	v_mov_b32_e32 v62, v40
	v_mul_f32_e32 v38, v38, v220
	v_mul_f32_e32 v39, v39, v221
	v_mfma_f32_32x32x16_f16 v[2:17], v[58:61], v[46:49], v[2:17]
	v_fma_f32 v38, v62, v218, v38
	v_fma_f32 v39, v63, v219, v39
	v_cvt_f32_f16_sdwa v65, v118 dst_sel:DWORD dst_unused:UNUSED_PAD src0_sel:WORD_1
	v_add_f32_e64 v40, v134, v39
	v_add_f32_e64 v41, v135, v38
	v_cvt_f32_f16_e32 v64, v118
	v_add_f32_e32 v62, v38, v40
	v_add_f32_e32 v63, v39, v41
	v_cvt_f32_f16_sdwa v135, v119 dst_sel:DWORD dst_unused:UNUSED_PAD src0_sel:WORD_1
	v_cvt_f32_f16_e32 v134, v119
	v_mfma_f32_32x32x16_f16 v[18:33], v[58:61], v[50:53], v[18:33]
	ds_read_b128 v[38:41], v192 offset:37008
	ds_read_b128 v[46:49], v192 offset:37056
	ds_read_b128 v[50:53], v192 offset:37072
	v_cvt_f32_f16_e32 v60, v117
	v_cvt_f32_f16_sdwa v61, v117 dst_sel:DWORD dst_unused:UNUSED_PAD src0_sel:WORD_1
	v_cvt_f32_f16_sdwa v59, v115 dst_sel:DWORD dst_unused:UNUSED_PAD src0_sel:WORD_1
	v_cvt_f32_f16_e32 v58, v115
	s_waitcnt lgkmcnt(0)
; #define LAS __attribute__((address_space(3)))
; __device__ __forceinline__ void mlstm_out_loop(unsigned char* ws, h16* Y, const float* ghead  , int u  , const int o_mout, const int o_end, const int ntc, const bool ctx_out, ...
;     ...
;           for (int ks = 0; ks < 4; ++ks) { const h16x8 q8 = H8(qr[ks]); const f32x4 n0 = *(const LAS f32x4*)(NL + 16 * ks + 8 * hi), n1 = *(const LAS f32x4*)(NL + 16 * ks + 8 * hi + 4);
;               dq += ((float)q8[0] * n0[0] + (float)q8[1] * n0[1]) + ((float)q8[2] * n0[2] + (float)q8[3] * n0[3]) + ((float)q8[4] * n1[0] + (float)q8[5] * n1[1]) + ((float)q8[6] * n1[2] + (float)q8[7] * n1[3]);
;               const h16x8 qs = q8 * ih;
; #pragma unroll
;               for (int d0 = 0; d0 < 2; ++d0) o[d0] = __builtin_amdgcn_mfma_f32_32x32x16_f16(qs, H8(cf[ks][d0]), o[d0], 0, 0, 0); }
;           sacc += inter * dq; }
; #pragma unroll
;         for (int kb = 0; kb < 2; ++kb) {
;             const bool need = dir ? (kb == 1 || wl <= 1) : (kb == 0 || wl >= 2);
;             if (need) {
;                 f32x16 p0, p1; attn_body::qkt(p0, p1, shm + MO_K + kb * 8192, qr, zero16, r32, hi);
; #pragma unroll
;                 for (int i = 0; i < 4; ++i) { const f32x4 ga = *(const LAS f32x4*)(gL + 64 * kb + 8 * i + 4 * hi), gb = *(const LAS f32x4*)(gL + 64 * kb + 32 + 8 * i + 4 * hi);
; #pragma unroll
;                     for (int jj = 0; jj < 4; ++jj) { const int r = 4 * i + jj, s0 = 64 * kb + 8 * i + 4 * hi + jj, s1 = s0 + 32;
;                         const bool k0 = dir ? (s0 >= t) : (s0 <= t), k1 = dir ? (s1 >= t) : (s1 <= t);
;                         const float w0 = k0 ? p0[r] * __builtin_amdgcn_exp2f((ga[jj] - Mt) * LOG2E) : 0.f, w1 = k1 ? p1[r] * __builtin_amdgcn_exp2f((gb[jj] - Mt) * LOG2E) : 0.f;
;                         p0[r] = w0; p1[r] = w1; sacc += w0 + w1; } }
	v_mul_f32_e32 v133, v52, v60
	v_mul_f32_e32 v63, v53, v61
	v_cvt_f32_f16_sdwa v53, v114 dst_sel:DWORD dst_unused:UNUSED_PAD src0_sel:WORD_1
	v_cvt_f32_f16_sdwa v52, v120 dst_sel:DWORD dst_unused:UNUSED_PAD src0_sel:WORD_1
	v_mul_f32_e32 v219, v49, v59
	v_mov_b32_e32 v59, v46
	v_mov_b32_e32 v46, v39
	v_mul_f32_e32 v218, v48, v58
	v_cvt_f32_f16_e32 v49, v114
	v_cvt_f32_f16_e32 v48, v120
	v_mov_b32_e32 v58, v38
	v_mul_f32_e32 v38, v46, v52
	v_mul_f32_e32 v39, v47, v53
	v_mul_f32_e32 v46, v43, v65
	v_fma_f32 v42, v42, v64, v46
	v_fma_f32 v43, v43, v65, v46
	v_mul_f32_e32 v46, v45, v135
	v_fma_f32 v44, v44, v134, v46
	v_fma_f32 v45, v45, v135, v46
	v_mov_b32_e32 v43, v218
	v_mov_b32_e32 v45, v219
	v_fma_f32 v38, v58, v48, v38
	v_fma_f32 v39, v59, v49, v39
	v_add_f32_e32 v42, v42, v44
	v_add_f32_e32 v43, v43, v45
	v_pk_mul_f16 v45, v117, v211 op_sel_hi:[1,0]
	v_add_f32_e32 v38, v38, v42
	v_add_f32_e32 v39, v39, v43
	v_pk_mul_f16 v44, v116, v211 op_sel_hi:[1,0]
	v_pk_mul_f16 v43, v115, v211 op_sel_hi:[1,0]
	v_pk_mul_f16 v42, v114, v211 op_sel_hi:[1,0]
	v_cvt_f32_f16_sdwa v53, v116 dst_sel:DWORD dst_unused:UNUSED_PAD src0_sel:WORD_1
	v_cvt_f32_f16_sdwa v52, v121 dst_sel:DWORD dst_unused:UNUSED_PAD src0_sel:WORD_1
	v_cvt_f32_f16_e32 v47, v116
	v_cvt_f32_f16_e32 v46, v121
	v_mfma_f32_32x32x16_f16 v[2:17], v[42:45], v[54:57], v[2:17]
	v_mov_b32_e32 v49, v50
	v_mov_b32_e32 v50, v41
	v_mov_b32_e32 v48, v40
	v_mul_f32_e64 v40, v50, v52
	v_mul_f32_e64 v41, v51, v53
	s_andn2_b64 vcc, exec, s[12:13]
	v_fma_f32 v40, v48, v46, v40
	v_fma_f32 v41, v49, v47, v41
	v_mfma_f32_32x32x16_f16 v[18:33], v[42:45], v[34:37], v[18:33]
	v_add_f32_e64 v38, v38, v40
	v_add_f32_e64 v39, v39, v41
	v_add_f32_e64 v40, v132, v62
	v_add_f32_e64 v41, v133, v63
	v_add_f32_e64 v38, v40, v38
	v_add_f32_e64 v39, v41, v39
	v_add_f32_e32 v34, v38, v39
	v_fma_f32 v222, v210, v34, 0
	s_cbranch_vccnz .LBB0_429
	ds_read_b128 v[34:37], v214 offset:512
	ds_read_b128 v[38:41], v214
	ds_read_b128 v[132:135], v214 offset:2560
	ds_read_b128 v[218:221], v214 offset:2048
	v_readlane_b32 s0, v253, 14
	v_readlane_b32 s1, v253, 15
	s_waitcnt lgkmcnt(2)
	v_mfma_f32_32x32x16_f16 v[50:65], v[38:41], v[126:129], 0
	v_mfma_f32_32x32x16_f16 v[34:49], v[34:37], v[126:129], 0
	s_waitcnt lgkmcnt(0)
	v_mfma_f32_32x32x16_f16 v[50:65], v[218:221], v[122:125], v[50:65]
	v_mfma_f32_32x32x16_f16 v[34:49], v[132:135], v[122:125], v[34:49]
	ds_read_b128 v[132:135], v214 offset:4608
	ds_read_b128 v[218:221], v214 offset:4096
	s_waitcnt lgkmcnt(0)
	v_mfma_f32_32x32x16_f16 v[50:65], v[218:221], v[118:121], v[50:65]
	v_mfma_f32_32x32x16_f16 v[34:49], v[132:135], v[118:121], v[34:49]
	ds_read_b128 v[132:135], v214 offset:6656
	ds_read_b128 v[218:221], v214 offset:6144
	s_waitcnt lgkmcnt(0)
	v_mfma_f32_32x32x16_f16 v[50:65], v[218:221], v[114:117], v[50:65]
	v_mfma_f32_32x32x16_f16 v[34:49], v[132:135], v[114:117], v[34:49]
	ds_read_b128 v[224:227], v178 offset:33408
	ds_read_b128 v[218:221], v178 offset:33280
	ds_read_b128 v[132:135], v178 offset:33312
	s_waitcnt lgkmcnt(1)
	v_sub_f32_e32 v210, v218, v161
	v_mul_f32_e32 v210, 0x3fb8aa3b, v210
	v_exp_f32_e32 v210, v210
	s_waitcnt lgkmcnt(0)
	v_sub_f32_e32 v132, v132, v161
	v_mul_f32_e32 v132, 0x3fb8aa3b, v132
	v_exp_f32_e32 v132, v132
	v_mul_f32_e32 v50, v50, v210
	v_cndmask_b32_e64 v218, 0, v50, s[0:1]
	v_sub_f32_e32 v50, v224, v161
	v_mul_f32_e32 v50, 0x3fb8aa3b, v50
	v_exp_f32_e32 v50, v50
	v_sub_f32_e32 v210, v219, v161
	v_mul_f32_e32 v210, 0x3fb8aa3b, v210
	v_exp_f32_e32 v210, v210
	v_readlane_b32 s0, v253, 16
	v_mul_f32_e32 v34, v34, v50
	v_readlane_b32 s1, v253, 17
	v_mul_f32_e32 v51, v51, v210
	v_mul_f32_e32 v54, v54, v132
	v_cndmask_b32_e64 v50, 0, v34, s[0:1]
	v_readlane_b32 s0, v253, 18
	v_readlane_b32 s1, v253, 19
	v_add_f32_e32 v34, v218, v50
	v_add_f32_e32 v34, v222, v34
	v_cndmask_b32_e64 v219, 0, v51, s[0:1]
	v_sub_f32_e32 v51, v225, v161
	v_mul_f32_e32 v51, 0x3fb8aa3b, v51
	v_exp_f32_e32 v51, v51
	v_readlane_b32 s0, v253, 20
	v_readlane_b32 s1, v253, 21
	v_mul_f32_e32 v35, v35, v51
	s_nop 0
	v_cndmask_b32_e64 v51, 0, v35, s[0:1]
	v_add_f32_e32 v35, v219, v51
	v_add_f32_e32 v34, v35, v34
	v_sub_f32_e32 v35, v220, v161
	v_mul_f32_e32 v35, 0x3fb8aa3b, v35
	v_exp_f32_e32 v35, v35
	v_readlane_b32 s0, v253, 22
	v_readlane_b32 s1, v253, 23
	v_mul_f32_e32 v35, v52, v35
	s_nop 0
	v_cndmask_b32_e64 v220, 0, v35, s[0:1]
	v_sub_f32_e32 v35, v226, v161
	v_mul_f32_e32 v35, 0x3fb8aa3b, v35
	v_exp_f32_e32 v35, v35
	v_readlane_b32 s0, v253, 10
	v_readlane_b32 s1, v253, 11
	v_mul_f32_e32 v35, v36, v35
	s_nop 0
	v_cndmask_b32_e64 v52, 0, v35, s[0:1]
	v_add_f32_e32 v35, v220, v52
	v_add_f32_e32 v34, v35, v34
	v_sub_f32_e32 v35, v221, v161
	v_mul_f32_e32 v35, 0x3fb8aa3b, v35
	v_exp_f32_e32 v35, v35
	v_readlane_b32 s0, v253, 28
	v_readlane_b32 s1, v253, 29
	v_mul_f32_e32 v35, v53, v35
	s_nop 0
	v_cndmask_b32_e64 v221, 0, v35, s[0:1]
	v_sub_f32_e32 v35, v227, v161
	v_mul_f32_e32 v35, 0x3fb8aa3b, v35
	v_exp_f32_e32 v35, v35
	v_readlane_b32 s0, v253, 30
	v_readlane_b32 s1, v253, 31
	v_mul_f32_e32 v35, v37, v35
	s_nop 0
	v_cndmask_b32_e64 v53, 0, v35, s[0:1]
	v_add_f32_e32 v35, v221, v53
	v_add_f32_e32 v210, v35, v34
	ds_read_b128 v[34:37], v178 offset:33440
	v_readlane_b32 s0, v253, 32
	v_readlane_b32 s1, v253, 33
	s_waitcnt lgkmcnt(0)
; #define LAS __attribute__((address_space(3)))
; __device__ __forceinline__ void mlstm_out_loop(unsigned char* ws, h16* Y, const float* ghead  , int u  , const int o_mout, const int o_end, const int ntc, const bool ctx_out, ...
;     ...
;                 for (int i = 0; i < 4; ++i) { const f32x4 ga = *(const LAS f32x4*)(gL + 64 * kb + 8 * i + 4 * hi), gb = *(const LAS f32x4*)(gL + 64 * kb + 32 + 8 * i + 4 * hi);
; #pragma unroll
;                     for (int jj = 0; jj < 4; ++jj) { const int r = 4 * i + jj, s0 = 64 * kb + 8 * i + 4 * hi + jj, s1 = s0 + 32;
;                         const bool k0 = dir ? (s0 >= t) : (s0 <= t), k1 = dir ? (s1 >= t) : (s1 <= t);
;                         const float w0 = k0 ? p0[r] * __builtin_amdgcn_exp2f((ga[jj] - Mt) * LOG2E) : 0.f, w1 = k1 ? p1[r] * __builtin_amdgcn_exp2f((gb[jj] - Mt) * LOG2E) : 0.f;
;                         p0[r] = w0; p1[r] = w1; sacc += w0 + w1; } }
	v_sub_f32_e32 v34, v34, v161
	v_mul_f32_e32 v34, 0x3fb8aa3b, v34
	v_exp_f32_e32 v34, v34
	v_sub_f32_e32 v35, v35, v161
	v_cndmask_b32_e64 v54, 0, v54, s[0:1]
	v_readlane_b32 s0, v253, 34
	v_mul_f32_e32 v34, v38, v34
	v_sub_f32_e32 v38, v133, v161
	v_mul_f32_e32 v38, 0x3fb8aa3b, v38
	v_exp_f32_e32 v38, v38
	v_mul_f32_e32 v35, 0x3fb8aa3b, v35
	v_readlane_b32 s1, v253, 35
	v_exp_f32_e32 v35, v35
	v_mul_f32_e32 v38, v55, v38
	v_cndmask_b32_e64 v132, 0, v34, s[0:1]
	v_readlane_b32 s0, v253, 36
	v_readlane_b32 s1, v253, 37
	v_mul_f32_e32 v35, v39, v35
	v_add_f32_e32 v34, v54, v132
	v_cndmask_b32_e64 v55, 0, v38, s[0:1]
	v_readlane_b32 s0, v253, 38
	v_readlane_b32 s1, v253, 39
	v_add_f32_e32 v34, v34, v210
	s_nop 0
	v_cndmask_b32_e64 v133, 0, v35, s[0:1]
	v_add_f32_e32 v35, v55, v133
	v_add_f32_e32 v34, v35, v34
	v_sub_f32_e32 v35, v134, v161
	v_mul_f32_e32 v35, 0x3fb8aa3b, v35
	v_exp_f32_e32 v35, v35
	v_readlane_b32 s0, v253, 40
	v_readlane_b32 s1, v253, 41
	v_mul_f32_e32 v35, v56, v35
	s_nop 0
	v_cndmask_b32_e64 v56, 0, v35, s[0:1]
	v_sub_f32_e32 v35, v36, v161
	v_mul_f32_e32 v35, 0x3fb8aa3b, v35
	v_exp_f32_e32 v35, v35
	v_readlane_b32 s0, v253, 42
	v_readlane_b32 s1, v253, 43
	v_mul_f32_e32 v35, v40, v35
	s_nop 0
	v_cndmask_b32_e64 v134, 0, v35, s[0:1]
	v_add_f32_e32 v35, v56, v134
	v_add_f32_e32 v34, v35, v34
	v_sub_f32_e32 v35, v135, v161
	v_mul_f32_e32 v35, 0x3fb8aa3b, v35
	v_exp_f32_e32 v35, v35
	v_readlane_b32 s0, v253, 44
	v_readlane_b32 s1, v253, 45
	v_mul_f32_e32 v35, v57, v35
	s_nop 0
	v_cndmask_b32_e64 v57, 0, v35, s[0:1]
	v_sub_f32_e32 v35, v37, v161
	v_mul_f32_e32 v35, 0x3fb8aa3b, v35
	v_exp_f32_e32 v35, v35
	v_readlane_b32 s0, v253, 46
	v_readlane_b32 s1, v253, 47
	v_mul_f32_e32 v35, v41, v35
	s_nop 0
	v_cndmask_b32_e64 v135, 0, v35, s[0:1]
	v_add_f32_e32 v35, v57, v135
	v_add_f32_e32 v210, v35, v34
	ds_read_b128 v[34:37], v178 offset:33344
	ds_read_b128 v[38:41], v178 offset:33472
	v_readlane_b32 s0, v253, 48
	v_readlane_b32 s1, v253, 49
	s_waitcnt lgkmcnt(1)
	v_sub_f32_e32 v34, v34, v161
	v_mul_f32_e32 v34, 0x3fb8aa3b, v34
	v_exp_f32_e32 v34, v34
	v_sub_f32_e32 v35, v35, v161
	v_mul_f32_e32 v35, 0x3fb8aa3b, v35
	v_exp_f32_e32 v35, v35
	v_mul_f32_e32 v34, v58, v34
	v_cndmask_b32_e64 v58, 0, v34, s[0:1]
	s_waitcnt lgkmcnt(0)
	v_sub_f32_e32 v34, v38, v161
	v_mul_f32_e32 v34, 0x3fb8aa3b, v34
	v_exp_f32_e32 v34, v34
	v_readlane_b32 s0, v253, 50
	v_readlane_b32 s1, v253, 51
	v_mul_f32_e32 v35, v59, v35
	v_mul_f32_e32 v34, v42, v34
	v_cndmask_b32_e64 v42, 0, v34, s[0:1]
	v_readlane_b32 s0, v253, 52
	v_readlane_b32 s1, v253, 53
	v_add_f32_e32 v34, v58, v42
	v_add_f32_e32 v34, v34, v210
	v_cndmask_b32_e64 v59, 0, v35, s[0:1]
	v_sub_f32_e32 v35, v39, v161
	v_mul_f32_e32 v35, 0x3fb8aa3b, v35
	v_exp_f32_e32 v35, v35
	v_readlane_b32 s0, v253, 54
	v_readlane_b32 s1, v253, 55
	v_mul_f32_e32 v35, v43, v35
	s_nop 0
	v_cndmask_b32_e64 v43, 0, v35, s[0:1]
	v_add_f32_e32 v35, v59, v43
	v_add_f32_e32 v34, v35, v34
	v_sub_f32_e32 v35, v36, v161
	v_mul_f32_e32 v35, 0x3fb8aa3b, v35
	v_exp_f32_e32 v35, v35
	v_readlane_b32 s0, v253, 56
	v_readlane_b32 s1, v253, 57
	v_cvt_pk_f16_f32 v42, v42, v43
	v_mul_f32_e32 v35, v60, v35
	v_cndmask_b32_e64 v60, 0, v35, s[0:1]
	v_sub_f32_e32 v35, v40, v161
	v_mul_f32_e32 v35, 0x3fb8aa3b, v35
	v_exp_f32_e32 v35, v35
	v_readlane_b32 s0, v253, 58
	v_readlane_b32 s1, v253, 59
	v_mul_f32_e32 v35, v44, v35
	s_nop 0
	v_cndmask_b32_e64 v44, 0, v35, s[0:1]
	v_add_f32_e32 v35, v60, v44
	v_add_f32_e32 v34, v35, v34
	v_sub_f32_e32 v35, v37, v161
	v_mul_f32_e32 v35, 0x3fb8aa3b, v35
	v_exp_f32_e32 v35, v35
	v_readlane_b32 s0, v253, 60
	v_readlane_b32 s1, v253, 61
	v_mul_f32_e32 v35, v61, v35
	s_nop 0
	v_cndmask_b32_e64 v61, 0, v35, s[0:1]
	v_sub_f32_e32 v35, v41, v161
	v_mul_f32_e32 v35, 0x3fb8aa3b, v35
	v_exp_f32_e32 v35, v35
	v_readlane_b32 s0, v253, 62
	v_readlane_b32 s1, v253, 63
	v_mul_f32_e32 v35, v45, v35
	s_nop 0
	v_cndmask_b32_e64 v45, 0, v35, s[0:1]
	v_add_f32_e32 v35, v61, v45
	v_add_f32_e32 v210, v35, v34
	ds_read_b128 v[38:41], v178 offset:33376
	ds_read_b128 v[34:37], v178 offset:33504
	v_readlane_b32 s0, v254, 0
	v_readlane_b32 s1, v254, 1
	v_cvt_pk_f16_f32 v43, v44, v45
	s_waitcnt lgkmcnt(1)
; #define LAS __attribute__((address_space(3)))
; __device__ __forceinline__ void pv(f32x16* o, int vb, s16x8 pa0, s16x8 pa1, s16x8 pa2, s16x8 pa3) {
; #pragma unroll
;   for (int d0 = 0; d0 < 2; ++d0) { s16x4 lo[4], hi[4];
; #pragma unroll
;     for (int ks = 0; ks < 4; ++ks) {
;       asm volatile("ds_read_b64_tr_b16 %0,%1 offset:%c2" : "=&v"(lo[ks]) : "v"(vb), "i"(d0 * 4096 + ks * 1024) : "memory");
;       asm volatile("ds_read_b64_tr_b16 %0,%1 offset:%c2" : "=&v"(hi[ks]) : "v"(vb), "i"(d0 * 4096 + ks * 1024 + 512) : "memory"); }
;     asm volatile("s_waitcnt lgkmcnt(0)" ::: "memory"); SBAR();
;     ...
;     o[d0] = __builtin_amdgcn_mfma_f32_32x32x16_f16(H8(pa0), H8(PK(0)), o[d0], 0, 0, 0);
;     o[d0] = __builtin_amdgcn_mfma_f32_32x32x16_f16(H8(pa1), H8(PK(1)), o[d0], 0, 0, 0);
;     o[d0] = __builtin_amdgcn_mfma_f32_32x32x16_f16(H8(pa2), H8(PK(2)), o[d0], 0, 0, 0);
; __device__ __forceinline__ void mlstm_out_loop(unsigned char* ws, h16* Y, const float* ghead  , int u  , const int o_mout, const int o_end, const int ntc, const bool ctx_out, ...
;     ...
;                 for (int i = 0; i < 4; ++i) { const f32x4 ga = *(const LAS f32x4*)(gL + 64 * kb + 8 * i + 4 * hi), gb = *(const LAS f32x4*)(gL + 64 * kb + 32 + 8 * i + 4 * hi);
; #pragma unroll
;                     for (int jj = 0; jj < 4; ++jj) { const int r = 4 * i + jj, s0 = 64 * kb + 8 * i + 4 * hi + jj, s1 = s0 + 32;
;                         const bool k0 = dir ? (s0 >= t) : (s0 <= t), k1 = dir ? (s1 >= t) : (s1 <= t);
;                         const float w0 = k0 ? p0[r] * __builtin_amdgcn_exp2f((ga[jj] - Mt) * LOG2E) : 0.f, w1 = k1 ? p1[r] * __builtin_amdgcn_exp2f((gb[jj] - Mt) * LOG2E) : 0.f;
;                         p0[r] = w0; p1[r] = w1; sacc += w0 + w1; } }
;                 u32x4 pw0, pw1, pw2, pw3;
;     ...
;                 pw0 = (u32x4){PKW(p0, 0), PKW(p0, 2), PKW(p0, 4), PKW(p0, 6)}; pw1 = (u32x4){PKW(p0, 8), PKW(p0, 10), PKW(p0, 12), PKW(p0, 14)};
;                 pw2 = (u32x4){PKW(p1, 0), PKW(p1, 2), PKW(p1, 4), PKW(p1, 6)}; pw3 = (u32x4){PKW(p1, 8), PKW(p1, 10), PKW(p1, 12), PKW(p1, 14)};
;     ...
;                 const int vb = (int)(lds0 + MO_V + kb * 8192) + ((lane >> 4) & 1) * 32 + (lane & 3) * 8 + (4 * hi + ((lane & 15) >> 2)) * 64;
;                 attn_body::pv(o, vb, __builtin_bit_cast(s16x8, pw0), __builtin_bit_cast(s16x8, pw1), __builtin_bit_cast(s16x8, pw2), __builtin_bit_cast(s16x8, pw3));
	v_sub_f32_e32 v38, v38, v161
	v_mul_f32_e32 v38, 0x3fb8aa3b, v38
	v_exp_f32_e32 v38, v38
	s_waitcnt lgkmcnt(0)
	v_sub_f32_e32 v34, v34, v161
	v_mul_f32_e32 v34, 0x3fb8aa3b, v34
	v_exp_f32_e32 v34, v34
	v_mul_f32_e32 v38, v62, v38
	v_cndmask_b32_e64 v62, 0, v38, s[0:1]
	v_sub_f32_e32 v38, v39, v161
	v_mul_f32_e32 v38, 0x3fb8aa3b, v38
	v_exp_f32_e32 v38, v38
	v_sub_f32_e32 v35, v35, v161
	v_readlane_b32 s0, v254, 2
	v_mul_f32_e32 v35, 0x3fb8aa3b, v35
	v_mul_f32_e32 v34, v46, v34
	v_readlane_b32 s1, v254, 3
	v_exp_f32_e32 v35, v35
	v_mul_f32_e32 v38, v63, v38
	v_cndmask_b32_e64 v211, 0, v34, s[0:1]
	v_readlane_b32 s0, v254, 4
	v_readlane_b32 s1, v254, 5
	v_mul_f32_e32 v35, v47, v35
	v_add_f32_e32 v34, v62, v211
	v_cndmask_b32_e64 v46, 0, v38, s[0:1]
	v_readlane_b32 s0, v254, 6
	v_readlane_b32 s1, v254, 7
	v_add_f32_e32 v34, v34, v210
	v_cvt_pk_f16_f32 v38, v58, v59
	v_cndmask_b32_e64 v63, 0, v35, s[0:1]
	v_add_f32_e32 v35, v46, v63
	v_add_f32_e32 v34, v35, v34
	v_sub_f32_e32 v35, v40, v161
	v_mul_f32_e32 v35, 0x3fb8aa3b, v35
	v_exp_f32_e32 v35, v35
	v_readlane_b32 s0, v254, 8
	v_readlane_b32 s1, v254, 9
	v_cvt_pk_f16_f32 v40, v62, v46
	v_mul_f32_e32 v35, v64, v35
	v_cndmask_b32_e64 v47, 0, v35, s[0:1]
	v_sub_f32_e32 v35, v36, v161
	v_mul_f32_e32 v35, 0x3fb8aa3b, v35
	v_exp_f32_e32 v35, v35
	v_readlane_b32 s0, v254, 10
	v_readlane_b32 s1, v254, 11
	v_cvt_pk_f16_f32 v46, v50, v51
	v_mul_f32_e32 v35, v48, v35
	v_cndmask_b32_e64 v64, 0, v35, s[0:1]
	v_add_f32_e32 v35, v47, v64
	v_add_f32_e32 v34, v35, v34
	v_sub_f32_e32 v35, v41, v161
	v_mul_f32_e32 v35, 0x3fb8aa3b, v35
	v_exp_f32_e32 v35, v35
	v_readlane_b32 s0, v254, 12
	v_readlane_b32 s1, v254, 13
	ds_read_b64_tr_b16 v[50:51],v176 offset:0
	v_mul_f32_e32 v35, v65, v35
	v_cvt_pk_f16_f32 v36, v54, v55
	v_cndmask_b32_e64 v41, 0, v35, s[0:1]
	v_sub_f32_e32 v35, v37, v161
	v_mul_f32_e32 v35, 0x3fb8aa3b, v35
	v_exp_f32_e32 v35, v35
	v_readlane_b32 s0, v254, 14
	v_readlane_b32 s1, v254, 15
	v_cvt_pk_f16_f32 v37, v56, v57
	v_mul_f32_e32 v35, v49, v35
	v_cndmask_b32_e64 v65, 0, v35, s[0:1]
	v_add_f32_e32 v35, v41, v65
	v_cvt_pk_f16_f32 v41, v47, v41
	v_cvt_pk_f16_f32 v47, v52, v53
	ds_read_b64_tr_b16 v[52:53],v176 offset:512
	ds_read_b64_tr_b16 v[54:55],v176 offset:1024
	ds_read_b64_tr_b16 v[56:57],v176 offset:1536
	ds_read_b64_tr_b16 v[58:59],v176 offset:2048
	v_cvt_pk_f16_f32 v39, v60, v61
	ds_read_b64_tr_b16 v[60:61],v176 offset:2560
	v_cvt_pk_f16_f32 v44, v211, v63
	ds_read_b64_tr_b16 v[62:63],v176 offset:3072
	v_cvt_pk_f16_f32 v45, v64, v65
	ds_read_b64_tr_b16 v[64:65],v176 offset:3584
	s_waitcnt lgkmcnt(0)
	v_add_f32_e32 v222, v35, v34
	v_cvt_pk_f16_f32 v34, v218, v219
	v_cvt_pk_f16_f32 v35, v220, v221
	v_cvt_pk_f16_f32 v48, v132, v133
	v_cvt_pk_f16_f32 v49, v134, v135
	v_mfma_f32_32x32x16_f16 v[2:17], v[34:37], v[50:53], v[2:17]
	ds_read_b64_tr_b16 v[50:51],v176 offset:4096
	ds_read_b64_tr_b16 v[52:53],v176 offset:4608
	v_mfma_f32_32x32x16_f16 v[2:17], v[38:41], v[54:57], v[2:17]
	ds_read_b64_tr_b16 v[54:55],v176 offset:5120
	ds_read_b64_tr_b16 v[56:57],v176 offset:5632
	v_mfma_f32_32x32x16_f16 v[2:17], v[46:49], v[58:61], v[2:17]
	ds_read_b64_tr_b16 v[58:59],v176 offset:6144
	ds_read_b64_tr_b16 v[60:61],v176 offset:6656
	v_mfma_f32_32x32x16_f16 v[2:17], v[42:45], v[62:65], v[2:17]
	ds_read_b64_tr_b16 v[62:63],v176 offset:7168
	ds_read_b64_tr_b16 v[64:65],v176 offset:7680
	s_waitcnt lgkmcnt(0)
	v_mfma_f32_32x32x16_f16 v[18:33], v[34:37], v[50:53], v[18:33]
	v_mfma_f32_32x32x16_f16 v[18:33], v[38:41], v[54:57], v[18:33]
	v_mfma_f32_32x32x16_f16 v[18:33], v[46:49], v[58:61], v[18:33]
	v_mfma_f32_32x32x16_f16 v[18:33], v[42:45], v[62:65], v[18:33]

; #define GAS __attribute__((address_space(1)))
; __device__ __forceinline__ unsigned cvtpk_h(float lo, float hi) { f32x2 v = {lo, hi}; h16x2 b = __builtin_convertvector(v, h16x2); return __builtin_bit_cast(unsigned, b); }
;     __device__ __forceinline__ void operator()(const f32x4 (&acc)[2][2][4][2], const pg8::Unit& u, int wr, int wc, int fr, int fq) const {
;     ...
;             for (int m = 0; m < 4; ++m) { if (half && ai == 1) continue; const unsigned rr = (unsigned)(ai * 128 + m * 16); const unsigned o = eoA + rr * (D * 2u); float ss = 0.f;
;                 const u32x4 la = *(const GAS u32x4*)((const GAS char*)ws + (unsigned)WS_X16 + o), lb = *(const GAS u32x4*)((const GAS char*)ws + (unsigned)WS_X16 + o + D * 2u);
;                 u32x4 xr[2];
; #pragma unroll
;                 for (int c = 0; c < 4; ++c) { const unsigned pa = (unsigned)__builtin_amdgcn_update_dpp(0, (int)la[c], 0xB1, 0xF, 0xF, false), pb = (unsigned)__builtin_amdgcn_update_dpp(0, (int)lb[c], 0xB1, 0xF, 0xF, false);
;                     xr[0][c] = odd ? pb : la[c]; xr[1][c] = odd ? lb[c] : pa; }
;                 u32x4 w[2], v[2];
; #pragma unroll
;                 for (int bj = 0; bj < 2; ++bj) { const h16x8 xb = __builtin_bit_cast(h16x8, xr[bj]);
;                     const f32x4 x0 = (f32x4){(float)xb[0], (float)xb[1], (float)xb[2], (float)xb[3]} + g4[bj][0] * acc[ai][bj][m][0], x1 = (f32x4){(float)xb[4], (float)xb[5], (float)xb[6], (float)xb[7]} + g4[bj][1] * acc[ai][bj][m][1];
;                     ss += ((x0[0] * x0[0] + x0[1] * x0[1]) + (x0[2] * x0[2] + x0[3] * x0[3])) + ((x1[0] * x1[0] + x1[1] * x1[1]) + (x1[2] * x1[2] + x1[3] * x1[3]));
;                     w[bj].x = cvtpk_h(x0[0], x0[1]); w[bj].y = cvtpk_h(x0[2], x0[3]); w[bj].z = cvtpk_h(x1[0], x1[1]); w[bj].w = cvtpk_h(x1[2], x1[3]);
;                     const f32x4 y0 = x0 * a4[bj][0], y1 = x1 * a4[bj][1]; v[bj].x = cvtpk_h(y0[0], y0[1]); v[bj].y = cvtpk_h(y0[2], y0[3]); v[bj].z = cvtpk_h(y1[0], y1[1]); v[bj].w = cvtpk_h(y1[2], y1[3]); }
;                 stg_line_pair(ws, (unsigned)WS_X16 + o, D * 2u, w[0], w[1], odd);
;                 if (an_off) stg_line_pair(ws, (unsigned)WS_XS + o, D * 2u, v[0], v[1], odd);
.LBB0_463:
	s_lshl_b32 s19, s0, 8
	v_and_b32_e32 v172, 0x1ffffe, v191
	s_add_i32 s19, s19, s84
	v_add_u32_e32 v172, s19, v172
	v_lshl_add_u32 v172, v172, 10, s5
	v_and_b32_e32 v0, 1, v191
	v_or_b32_e32 v172, s29, v172
	v_cmp_eq_u32_e64 s[0:1], 0, v0
	v_lshlrev_b32_e32 v172, 1, v172
	v_lshlrev_b32_e32 v0, 6, v0
	v_lshlrev_b32_e32 v173, 4, v192
	s_add_u32 s42, s38, 0x16f80000
	v_add3_u32 v0, v0, v173, v172
	s_addc_u32 s43, s39, 0
	global_load_dwordx4 v[172:175], v0, s[42:43]
	global_load_dwordx4 v[176:179], v0, s[42:43] offset:2048
	v_mov_b32_e32 v193, v1
	v_mov_b32_e32 v194, v1
	s_and_b64 vcc, exec, s[2:3]
	s_waitcnt vmcnt(0)
	v_add_u32_e32 v222, 0x8000, v0
	global_load_dwordx4 v[214:217], v222, s[42:43]
	global_load_dwordx4 v[218:221], v222, s[42:43] offset:2048
	v_mov_b32_dpp v193, v172 quad_perm:[1,0,3,2] row_mask:0xf bank_mask:0xf
	v_mov_b32_dpp v194, v176 quad_perm:[1,0,3,2] row_mask:0xf bank_mask:0xf
	v_cndmask_b32_e64 v194, v194, v172, s[0:1]
	v_cndmask_b32_e64 v195, v176, v193, s[0:1]
	v_mov_b32_e32 v172, v1
	v_mov_b32_e32 v176, v1
	s_nop 0
	v_mov_b32_dpp v172, v173 quad_perm:[1,0,3,2] row_mask:0xf bank_mask:0xf
	v_mov_b32_dpp v176, v177 quad_perm:[1,0,3,2] row_mask:0xf bank_mask:0xf
	v_cndmask_b32_e64 v176, v176, v173, s[0:1]
	v_cndmask_b32_e64 v196, v177, v172, s[0:1]
	v_mov_b32_e32 v172, v1
	v_mov_b32_e32 v173, v1
	s_nop 0
	v_mov_b32_dpp v172, v174 quad_perm:[1,0,3,2] row_mask:0xf bank_mask:0xf
	v_mov_b32_dpp v173, v178 quad_perm:[1,0,3,2] row_mask:0xf bank_mask:0xf
	v_cndmask_b32_e64 v193, v173, v174, s[0:1]
	v_cndmask_b32_e64 v197, v178, v172, s[0:1]
	v_mov_b32_e32 v172, v1
	v_mov_b32_e32 v173, v1
	v_cvt_f32_f16_e32 v174, v176
	v_mov_b32_dpp v172, v175 quad_perm:[1,0,3,2] row_mask:0xf bank_mask:0xf
	v_mov_b32_dpp v173, v179 quad_perm:[1,0,3,2] row_mask:0xf bank_mask:0xf
	v_cndmask_b32_e64 v178, v173, v175, s[0:1]
	v_cndmask_b32_e64 v198, v179, v172, s[0:1]
	v_cvt_f32_f16_e32 v172, v194
	v_cvt_f32_f16_sdwa v173, v194 dst_sel:DWORD dst_unused:UNUSED_PAD src0_sel:WORD_1
	v_cvt_f32_f16_sdwa v175, v176 dst_sel:DWORD dst_unused:UNUSED_PAD src0_sel:WORD_1
	v_add_u32_e32 v194, 0x16f80000, v0
	v_fma_f32 v176, v160, v50, v172
	v_fma_f32 v177, v161, v51, v173
	v_cvt_f32_f16_e32 v160, v193
	v_cvt_f32_f16_sdwa v161, v193 dst_sel:DWORD dst_unused:UNUSED_PAD src0_sel:WORD_1
	v_cvt_f32_f16_e32 v172, v178
	v_cvt_f32_f16_sdwa v173, v178 dst_sel:DWORD dst_unused:UNUSED_PAD src0_sel:WORD_1
	v_fma_f32 v162, v162, v52, v174
	v_fma_f32 v163, v163, v53, v175
	v_cvt_pk_f16_f32 v199, v176, v177
	v_cvt_pk_f16_f32 v200, v162, v163
	v_fma_f32 v158, v158, v56, v172
	v_fma_f32 v159, v159, v57, v173
	v_fma_f32 v172, v156, v54, v160
	v_fma_f32 v173, v157, v55, v161
	v_cvt_f32_f16_e32 v156, v195
	v_cvt_f32_f16_sdwa v157, v195 dst_sel:DWORD dst_unused:UNUSED_PAD src0_sel:WORD_1
	v_cvt_f32_f16_e32 v160, v196
	v_cvt_f32_f16_sdwa v161, v196 dst_sel:DWORD dst_unused:UNUSED_PAD src0_sel:WORD_1
	v_cvt_pk_f16_f32 v201, v172, v173
	v_fma_f32 v178, v152, v58, v156
	v_fma_f32 v179, v153, v59, v157
	v_cvt_f32_f16_e32 v152, v197
	v_cvt_f32_f16_sdwa v153, v197 dst_sel:DWORD dst_unused:UNUSED_PAD src0_sel:WORD_1
	v_fma_f32 v160, v154, v60, v160
	v_fma_f32 v161, v155, v61, v161
	v_cvt_f32_f16_e32 v154, v198
	v_cvt_f32_f16_sdwa v155, v198 dst_sel:DWORD dst_unused:UNUSED_PAD src0_sel:WORD_1
	v_fma_f32 v174, v148, v62, v152
	v_fma_f32 v175, v149, v63, v153
	v_mov_b32_e32 v153, v1
	v_cvt_pk_f16_f32 v148, v178, v179
	v_fma_f32 v156, v150, v64, v154
	v_fma_f32 v157, v151, v65, v155
	v_mov_b32_e32 v152, v1
	v_mov_b32_dpp v153, v199 quad_perm:[1,0,3,2] row_mask:0xf bank_mask:0xf
	v_mov_b32_e32 v154, v1
	v_cvt_pk_f16_f32 v149, v160, v161
	v_mov_b32_dpp v152, v148 quad_perm:[1,0,3,2] row_mask:0xf bank_mask:0xf
	v_cndmask_b32_e64 v148, v148, v153, s[0:1]
	v_mov_b32_e32 v153, v1
	v_mov_b32_dpp v154, v200 quad_perm:[1,0,3,2] row_mask:0xf bank_mask:0xf
	v_mov_b32_e32 v155, v1
	v_cvt_pk_f16_f32 v150, v174, v175
	v_mov_b32_dpp v153, v149 quad_perm:[1,0,3,2] row_mask:0xf bank_mask:0xf
	v_cndmask_b32_e64 v149, v149, v154, s[0:1]
	v_mov_b32_e32 v154, v1
	v_mov_b32_dpp v155, v201 quad_perm:[1,0,3,2] row_mask:0xf bank_mask:0xf
	v_cvt_pk_f16_f32 v151, v156, v157
	v_mov_b32_dpp v154, v150 quad_perm:[1,0,3,2] row_mask:0xf bank_mask:0xf
	v_cndmask_b32_e64 v150, v150, v155, s[0:1]
	v_mov_b32_e32 v155, v1
	v_cvt_pk_f16_f32 v193, v158, v159
	v_mov_b32_e32 v195, v1
	v_mov_b32_dpp v155, v151 quad_perm:[1,0,3,2] row_mask:0xf bank_mask:0xf
	v_cndmask_b32_e64 v152, v152, v199, s[0:1]
	v_cndmask_b32_e64 v153, v153, v200, s[0:1]
	v_cndmask_b32_e64 v154, v154, v201, s[0:1]
	v_mov_b32_dpp v195, v193 quad_perm:[1,0,3,2] row_mask:0xf bank_mask:0xf
	v_cndmask_b32_e64 v155, v155, v193, s[0:1]
	v_cndmask_b32_e64 v151, v151, v195, s[0:1]
	global_store_dwordx4 v194, v[152:155], s[38:39] sc1
	s_nop 1
	v_add_u32_e32 v152, 0x16f80800, v0
	global_store_dwordx4 v152, v[148:151], s[38:39] sc1
	s_cbranch_vccnz .LBB0_465
	s_nop 0
	v_mul_f32_e32 v148, v32, v156
	v_mul_f32_e32 v149, v33, v157
	v_mul_f32_e32 v150, v30, v174
	v_mul_f32_e32 v151, v31, v175
	v_cvt_pk_f16_f32 v155, v148, v149
	v_cvt_pk_f16_f32 v154, v150, v151
	v_mul_f32_e32 v148, v28, v160
	v_mul_f32_e32 v149, v29, v161
	v_mul_f32_e32 v150, v26, v178
	v_mul_f32_e32 v151, v27, v179
	v_cvt_pk_f16_f32 v153, v148, v149
	v_cvt_pk_f16_f32 v152, v150, v151
	v_mul_f32_e32 v148, v24, v158
	v_mul_f32_e32 v149, v25, v159
	v_mul_f32_e32 v150, v22, v172
	v_mul_f32_e32 v151, v23, v173
	v_cvt_pk_f16_f32 v193, v148, v149
	v_cvt_pk_f16_f32 v194, v150, v151
	v_mul_f32_e32 v148, v20, v162
	v_mul_f32_e32 v149, v21, v163
	v_mul_f32_e32 v150, v18, v176
	v_mul_f32_e32 v151, v19, v177
	v_cvt_pk_f16_f32 v149, v148, v149
	v_cvt_pk_f16_f32 v148, v150, v151
	v_mov_b32_e32 v151, v1
	v_mov_b32_e32 v150, v1
	v_add_u32_e32 v195, 0x3d80000, v0
	v_mov_b32_dpp v151, v148 quad_perm:[1,0,3,2] row_mask:0xf bank_mask:0xf
	v_mov_b32_dpp v150, v152 quad_perm:[1,0,3,2] row_mask:0xf bank_mask:0xf
	v_cndmask_b32_e64 v152, v152, v151, s[0:1]
	v_mov_b32_e32 v151, v1
	v_cndmask_b32_e64 v148, v150, v148, s[0:1]
	v_mov_b32_e32 v150, v1
	v_mov_b32_dpp v151, v149 quad_perm:[1,0,3,2] row_mask:0xf bank_mask:0xf
	s_nop 0
	v_mov_b32_dpp v150, v153 quad_perm:[1,0,3,2] row_mask:0xf bank_mask:0xf
	v_cndmask_b32_e64 v153, v153, v151, s[0:1]
	v_mov_b32_e32 v151, v1
	v_cndmask_b32_e64 v149, v150, v149, s[0:1]
	v_mov_b32_e32 v150, v1
	v_mov_b32_dpp v151, v194 quad_perm:[1,0,3,2] row_mask:0xf bank_mask:0xf
	s_nop 0
	v_mov_b32_dpp v150, v154 quad_perm:[1,0,3,2] row_mask:0xf bank_mask:0xf
	v_cndmask_b32_e64 v154, v154, v151, s[0:1]
	v_mov_b32_e32 v151, v1
	v_cndmask_b32_e64 v150, v150, v194, s[0:1]
	v_mov_b32_e32 v194, v1
	v_mov_b32_dpp v151, v155 quad_perm:[1,0,3,2] row_mask:0xf bank_mask:0xf
	v_cndmask_b32_e64 v151, v151, v193, s[0:1]
	v_mov_b32_dpp v194, v193 quad_perm:[1,0,3,2] row_mask:0xf bank_mask:0xf
	v_cndmask_b32_e64 v155, v155, v194, s[0:1]
	global_store_dwordx4 v195, v[148:151], s[38:39] sc1
	s_nop 1
	v_add_u32_e32 v148, 0x3d80800, v0
	global_store_dwordx4 v148, v[152:155], s[38:39] sc1

; #define GAS __attribute__((address_space(1)))
; __device__ __forceinline__ unsigned cvtpk_h(float lo, float hi) { f32x2 v = {lo, hi}; h16x2 b = __builtin_convertvector(v, h16x2); return __builtin_bit_cast(unsigned, b); }
;     __device__ __forceinline__ void operator()(const f32x4 (&acc)[2][2][4][2], const pg8::Unit& u, int wr, int wc, int fr, int fq) const {
;     ...
;             for (int m = 0; m < 4; ++m) { if (half && ai == 1) continue; const unsigned rr = (unsigned)(ai * 128 + m * 16); const unsigned o = eoA + rr * (D * 2u); float ss = 0.f;
;                 const u32x4 la = *(const GAS u32x4*)((const GAS char*)ws + (unsigned)WS_X16 + o), lb = *(const GAS u32x4*)((const GAS char*)ws + (unsigned)WS_X16 + o + D * 2u);
;                 u32x4 xr[2];
; #pragma unroll
;                 for (int c = 0; c < 4; ++c) { const unsigned pa = (unsigned)__builtin_amdgcn_update_dpp(0, (int)la[c], 0xB1, 0xF, 0xF, false), pb = (unsigned)__builtin_amdgcn_update_dpp(0, (int)lb[c], 0xB1, 0xF, 0xF, false);
;                     xr[0][c] = odd ? pb : la[c]; xr[1][c] = odd ? lb[c] : pa; }
;                 u32x4 w[2], v[2];
; #pragma unroll
;                 for (int bj = 0; bj < 2; ++bj) { const h16x8 xb = __builtin_bit_cast(h16x8, xr[bj]);
;                     const f32x4 x0 = (f32x4){(float)xb[0], (float)xb[1], (float)xb[2], (float)xb[3]} + g4[bj][0] * acc[ai][bj][m][0], x1 = (f32x4){(float)xb[4], (float)xb[5], (float)xb[6], (float)xb[7]} + g4[bj][1] * acc[ai][bj][m][1];
;                     ss += ((x0[0] * x0[0] + x0[1] * x0[1]) + (x0[2] * x0[2] + x0[3] * x0[3])) + ((x1[0] * x1[0] + x1[1] * x1[1]) + (x1[2] * x1[2] + x1[3] * x1[3]));
;                     w[bj].x = cvtpk_h(x0[0], x0[1]); w[bj].y = cvtpk_h(x0[2], x0[3]); w[bj].z = cvtpk_h(x1[0], x1[1]); w[bj].w = cvtpk_h(x1[2], x1[3]);
;                     const f32x4 y0 = x0 * a4[bj][0], y1 = x1 * a4[bj][1]; v[bj].x = cvtpk_h(y0[0], y0[1]); v[bj].y = cvtpk_h(y0[2], y0[3]); v[bj].z = cvtpk_h(y1[0], y1[1]); v[bj].w = cvtpk_h(y1[2], y1[3]); }
;                 stg_line_pair(ws, (unsigned)WS_X16 + o, D * 2u, w[0], w[1], odd);
;                 if (an_off) stg_line_pair(ws, (unsigned)WS_XS + o, D * 2u, v[0], v[1], odd);
.Lo_wd_1:
	v_mov_b32_e32 v150, v214
	v_mov_b32_e32 v151, v215
	v_mov_b32_e32 v152, v216
	v_mov_b32_e32 v153, v217
	v_mov_b32_e32 v154, v218
	v_mov_b32_e32 v155, v219
	v_mov_b32_e32 v156, v220
	v_mov_b32_e32 v157, v221
	v_add_u32_e32 v222, 0x10000, v0
	global_load_dwordx4 v[214:217], v222, s[42:43]
	global_load_dwordx4 v[218:221], v222, s[42:43] offset:2048
	v_mov_b32_e32 v149, v1
	v_mov_b32_e32 v158, v1
	v_add_u32_e32 v161, 0x16f88000, v0
	s_and_b64 vcc, exec, s[2:3]
	v_mov_b32_dpp v149, v150 quad_perm:[1,0,3,2] row_mask:0xf bank_mask:0xf
	v_mov_b32_dpp v158, v154 quad_perm:[1,0,3,2] row_mask:0xf bank_mask:0xf
	v_cndmask_b32_e64 v158, v158, v150, s[0:1]
	v_cndmask_b32_e64 v149, v154, v149, s[0:1]
	v_mov_b32_e32 v150, v1
	v_mov_b32_e32 v154, v1
	s_nop 0
	v_mov_b32_dpp v150, v151 quad_perm:[1,0,3,2] row_mask:0xf bank_mask:0xf
	v_mov_b32_dpp v154, v155 quad_perm:[1,0,3,2] row_mask:0xf bank_mask:0xf
	v_cndmask_b32_e64 v154, v154, v151, s[0:1]
	v_cndmask_b32_e64 v155, v155, v150, s[0:1]
	v_mov_b32_e32 v150, v1
	v_mov_b32_e32 v151, v1
	s_nop 0
	v_mov_b32_dpp v150, v152 quad_perm:[1,0,3,2] row_mask:0xf bank_mask:0xf
	v_mov_b32_dpp v151, v156 quad_perm:[1,0,3,2] row_mask:0xf bank_mask:0xf
	v_cndmask_b32_e64 v159, v151, v152, s[0:1]
	v_cndmask_b32_e64 v156, v156, v150, s[0:1]
	v_mov_b32_e32 v150, v1
	v_mov_b32_e32 v151, v1
	v_cvt_f32_f16_e32 v152, v154
	v_mov_b32_dpp v150, v153 quad_perm:[1,0,3,2] row_mask:0xf bank_mask:0xf
	v_mov_b32_dpp v151, v157 quad_perm:[1,0,3,2] row_mask:0xf bank_mask:0xf
	v_cndmask_b32_e64 v160, v151, v153, s[0:1]
	v_cndmask_b32_e64 v157, v157, v150, s[0:1]
	v_cvt_f32_f16_e32 v150, v158
	v_cvt_f32_f16_sdwa v151, v158 dst_sel:DWORD dst_unused:UNUSED_PAD src0_sel:WORD_1
	v_cvt_f32_f16_sdwa v153, v154 dst_sel:DWORD dst_unused:UNUSED_PAD src0_sel:WORD_1
	v_fma_f32 v144, v144, v50, v150
	v_fma_f32 v145, v145, v51, v151
	v_cvt_f32_f16_e32 v150, v159
	v_cvt_f32_f16_sdwa v151, v159 dst_sel:DWORD dst_unused:UNUSED_PAD src0_sel:WORD_1
	v_fma_f32 v146, v146, v52, v152
	v_fma_f32 v147, v147, v53, v153
	v_cvt_f32_f16_e32 v152, v160
	v_cvt_f32_f16_sdwa v153, v160 dst_sel:DWORD dst_unused:UNUSED_PAD src0_sel:WORD_1
	v_fma_f32 v140, v140, v54, v150
	v_fma_f32 v141, v141, v55, v151
	v_cvt_f32_f16_e32 v150, v149
	v_cvt_f32_f16_sdwa v151, v149 dst_sel:DWORD dst_unused:UNUSED_PAD src0_sel:WORD_1
	v_fma_f32 v142, v142, v56, v152
	v_fma_f32 v143, v143, v57, v153
	v_cvt_f32_f16_e32 v152, v155
	v_cvt_f32_f16_sdwa v153, v155 dst_sel:DWORD dst_unused:UNUSED_PAD src0_sel:WORD_1
	v_fma_f32 v136, v136, v58, v150
	v_fma_f32 v137, v137, v59, v151
	v_cvt_f32_f16_e32 v150, v156
	v_cvt_f32_f16_sdwa v151, v156 dst_sel:DWORD dst_unused:UNUSED_PAD src0_sel:WORD_1
	v_fma_f32 v138, v138, v60, v152
	v_fma_f32 v139, v139, v61, v153
	v_cvt_f32_f16_e32 v152, v157
	v_cvt_f32_f16_sdwa v153, v157 dst_sel:DWORD dst_unused:UNUSED_PAD src0_sel:WORD_1
	v_cvt_pk_f16_f32 v154, v144, v145
	v_fma_f32 v132, v132, v62, v150
	v_fma_f32 v133, v133, v63, v151
	v_cvt_pk_f16_f32 v149, v136, v137
	v_mov_b32_e32 v150, v1
	v_mov_b32_e32 v151, v1
	v_fma_f32 v134, v134, v64, v152
	v_fma_f32 v135, v135, v65, v153
	v_mov_b32_dpp v150, v149 quad_perm:[1,0,3,2] row_mask:0xf bank_mask:0xf
	v_mov_b32_dpp v151, v154 quad_perm:[1,0,3,2] row_mask:0xf bank_mask:0xf
	v_cvt_pk_f16_f32 v152, v138, v139
	v_cndmask_b32_e64 v150, v150, v154, s[0:1]
	v_cndmask_b32_e64 v154, v149, v151, s[0:1]
	v_mov_b32_e32 v149, v1
	v_cvt_pk_f16_f32 v158, v146, v147
	v_cvt_pk_f16_f32 v153, v132, v133
	v_mov_b32_dpp v149, v152 quad_perm:[1,0,3,2] row_mask:0xf bank_mask:0xf
	v_mov_b32_e32 v155, v1
	v_cndmask_b32_e64 v151, v149, v158, s[0:1]
	v_mov_b32_e32 v149, v1
	v_cvt_pk_f16_f32 v159, v140, v141
	v_mov_b32_dpp v155, v158 quad_perm:[1,0,3,2] row_mask:0xf bank_mask:0xf
	v_mov_b32_dpp v149, v153 quad_perm:[1,0,3,2] row_mask:0xf bank_mask:0xf
	v_cvt_pk_f16_f32 v160, v142, v143
	v_cvt_pk_f16_f32 v157, v134, v135
	v_cndmask_b32_e64 v155, v152, v155, s[0:1]
	v_mov_b32_e32 v156, v1
	v_cndmask_b32_e64 v152, v149, v159, s[0:1]
	v_mov_b32_e32 v149, v1
	v_mov_b32_e32 v158, v1
	v_mov_b32_dpp v156, v159 quad_perm:[1,0,3,2] row_mask:0xf bank_mask:0xf
	v_mov_b32_dpp v149, v157 quad_perm:[1,0,3,2] row_mask:0xf bank_mask:0xf
	v_mov_b32_dpp v158, v160 quad_perm:[1,0,3,2] row_mask:0xf bank_mask:0xf
	v_cndmask_b32_e64 v156, v153, v156, s[0:1]
	v_cndmask_b32_e64 v153, v149, v160, s[0:1]
	v_cndmask_b32_e64 v157, v157, v158, s[0:1]
	v_add_u32_e32 v149, 0x16f88800, v0
	global_store_dwordx4 v161, v[150:153], s[38:39] sc1
	global_store_dwordx4 v149, v[154:157], s[38:39] sc1
	s_cbranch_vccnz .LBB0_469
	v_mul_f32_e32 v150, v32, v134
	v_mul_f32_e32 v151, v33, v135
	v_mul_f32_e32 v152, v30, v132
	v_mul_f32_e32 v153, v31, v133
	v_cvt_pk_f16_f32 v149, v150, v151
	v_cvt_pk_f16_f32 v156, v152, v153
	v_mul_f32_e32 v150, v28, v138
	v_mul_f32_e32 v151, v29, v139
	v_mul_f32_e32 v152, v26, v136
	v_mul_f32_e32 v153, v27, v137
	v_cvt_pk_f16_f32 v155, v150, v151
	v_cvt_pk_f16_f32 v154, v152, v153
	v_mul_f32_e32 v150, v24, v142
	v_mul_f32_e32 v151, v25, v143
	v_mul_f32_e32 v152, v22, v140
	v_mul_f32_e32 v153, v23, v141
	v_cvt_pk_f16_f32 v157, v150, v151
	v_cvt_pk_f16_f32 v158, v152, v153
	v_mul_f32_e32 v150, v20, v146
	v_mul_f32_e32 v151, v21, v147
	v_mul_f32_e32 v152, v18, v144
	v_mul_f32_e32 v153, v19, v145
	v_cvt_pk_f16_f32 v151, v150, v151
	v_cvt_pk_f16_f32 v150, v152, v153
	v_mov_b32_e32 v152, v1
	v_mov_b32_e32 v153, v1
	v_add_u32_e32 v159, 0x3d88000, v0
	v_mov_b32_dpp v152, v154 quad_perm:[1,0,3,2] row_mask:0xf bank_mask:0xf
	v_mov_b32_dpp v153, v150 quad_perm:[1,0,3,2] row_mask:0xf bank_mask:0xf
	v_cndmask_b32_e64 v150, v152, v150, s[0:1]
	v_cndmask_b32_e64 v154, v154, v153, s[0:1]
	v_mov_b32_e32 v152, v1
	v_mov_b32_e32 v153, v1
	s_nop 0
	v_mov_b32_dpp v152, v155 quad_perm:[1,0,3,2] row_mask:0xf bank_mask:0xf
	v_mov_b32_dpp v153, v151 quad_perm:[1,0,3,2] row_mask:0xf bank_mask:0xf
	v_cndmask_b32_e64 v151, v152, v151, s[0:1]
	v_cndmask_b32_e64 v155, v155, v153, s[0:1]
	v_mov_b32_e32 v152, v1
	v_mov_b32_e32 v153, v1
	s_nop 0
	v_mov_b32_dpp v152, v156 quad_perm:[1,0,3,2] row_mask:0xf bank_mask:0xf
	v_mov_b32_dpp v153, v158 quad_perm:[1,0,3,2] row_mask:0xf bank_mask:0xf
	v_cndmask_b32_e64 v152, v152, v158, s[0:1]
	v_cndmask_b32_e64 v156, v156, v153, s[0:1]
	v_mov_b32_e32 v153, v1
	v_mov_b32_e32 v158, v1
	s_nop 0
	v_mov_b32_dpp v153, v149 quad_perm:[1,0,3,2] row_mask:0xf bank_mask:0xf
	v_mov_b32_dpp v158, v157 quad_perm:[1,0,3,2] row_mask:0xf bank_mask:0xf
	v_cndmask_b32_e64 v153, v153, v157, s[0:1]
	v_cndmask_b32_e64 v157, v149, v158, s[0:1]
	v_add_u32_e32 v149, 0x3d88800, v0
	global_store_dwordx4 v159, v[150:153], s[38:39] sc1
	global_store_dwordx4 v149, v[154:157], s[38:39] sc1

; #define GAS __attribute__((address_space(1)))
; __device__ __forceinline__ unsigned cvtpk_h(float lo, float hi) { f32x2 v = {lo, hi}; h16x2 b = __builtin_convertvector(v, h16x2); return __builtin_bit_cast(unsigned, b); }
;     __device__ __forceinline__ void operator()(const f32x4 (&acc)[2][2][4][2], const pg8::Unit& u, int wr, int wc, int fr, int fq) const {
;     ...
;             for (int m = 0; m < 4; ++m) { if (half && ai == 1) continue; const unsigned rr = (unsigned)(ai * 128 + m * 16); const unsigned o = eoA + rr * (D * 2u); float ss = 0.f;
;                 const u32x4 la = *(const GAS u32x4*)((const GAS char*)ws + (unsigned)WS_X16 + o), lb = *(const GAS u32x4*)((const GAS char*)ws + (unsigned)WS_X16 + o + D * 2u);
;                 u32x4 xr[2];
; #pragma unroll
;                 for (int c = 0; c < 4; ++c) { const unsigned pa = (unsigned)__builtin_amdgcn_update_dpp(0, (int)la[c], 0xB1, 0xF, 0xF, false), pb = (unsigned)__builtin_amdgcn_update_dpp(0, (int)lb[c], 0xB1, 0xF, 0xF, false);
;                     xr[0][c] = odd ? pb : la[c]; xr[1][c] = odd ? lb[c] : pa; }
;                 u32x4 w[2], v[2];
; #pragma unroll
;                 for (int bj = 0; bj < 2; ++bj) { const h16x8 xb = __builtin_bit_cast(h16x8, xr[bj]);
;                     const f32x4 x0 = (f32x4){(float)xb[0], (float)xb[1], (float)xb[2], (float)xb[3]} + g4[bj][0] * acc[ai][bj][m][0], x1 = (f32x4){(float)xb[4], (float)xb[5], (float)xb[6], (float)xb[7]} + g4[bj][1] * acc[ai][bj][m][1];
;                     ss += ((x0[0] * x0[0] + x0[1] * x0[1]) + (x0[2] * x0[2] + x0[3] * x0[3])) + ((x1[0] * x1[0] + x1[1] * x1[1]) + (x1[2] * x1[2] + x1[3] * x1[3]));
;                     w[bj].x = cvtpk_h(x0[0], x0[1]); w[bj].y = cvtpk_h(x0[2], x0[3]); w[bj].z = cvtpk_h(x1[0], x1[1]); w[bj].w = cvtpk_h(x1[2], x1[3]);
;                     const f32x4 y0 = x0 * a4[bj][0], y1 = x1 * a4[bj][1]; v[bj].x = cvtpk_h(y0[0], y0[1]); v[bj].y = cvtpk_h(y0[2], y0[3]); v[bj].z = cvtpk_h(y1[0], y1[1]); v[bj].w = cvtpk_h(y1[2], y1[3]); }
;                 stg_line_pair(ws, (unsigned)WS_X16 + o, D * 2u, w[0], w[1], odd);
;                 if (an_off) stg_line_pair(ws, (unsigned)WS_XS + o, D * 2u, v[0], v[1], odd);
.Lo_wd_2:
	v_mov_b32_e32 v132, v214
	v_mov_b32_e32 v133, v215
	v_mov_b32_e32 v134, v216
	v_mov_b32_e32 v135, v217
	v_mov_b32_e32 v136, v218
	v_mov_b32_e32 v137, v219
	v_mov_b32_e32 v138, v220
	v_mov_b32_e32 v139, v221
	v_add_u32_e32 v222, 0x18000, v0
	global_load_dwordx4 v[214:217], v222, s[42:43]
	global_load_dwordx4 v[218:221], v222, s[42:43] offset:2048
	v_mov_b32_e32 v140, v1
	v_mov_b32_e32 v141, v1
	v_add_u32_e32 v144, 0x16f90000, v0
	s_and_b64 vcc, exec, s[2:3]
	v_mov_b32_dpp v140, v132 quad_perm:[1,0,3,2] row_mask:0xf bank_mask:0xf
	v_mov_b32_dpp v141, v136 quad_perm:[1,0,3,2] row_mask:0xf bank_mask:0xf
	v_cndmask_b32_e64 v141, v141, v132, s[0:1]
	v_cndmask_b32_e64 v136, v136, v140, s[0:1]
	v_mov_b32_e32 v132, v1
	v_mov_b32_e32 v140, v1
	s_nop 0
	v_mov_b32_dpp v132, v133 quad_perm:[1,0,3,2] row_mask:0xf bank_mask:0xf
	v_mov_b32_dpp v140, v137 quad_perm:[1,0,3,2] row_mask:0xf bank_mask:0xf
	v_cndmask_b32_e64 v140, v140, v133, s[0:1]
	v_cndmask_b32_e64 v137, v137, v132, s[0:1]
	v_mov_b32_e32 v132, v1
	v_mov_b32_e32 v133, v1
	s_nop 0
	v_mov_b32_dpp v132, v134 quad_perm:[1,0,3,2] row_mask:0xf bank_mask:0xf
	v_mov_b32_dpp v133, v138 quad_perm:[1,0,3,2] row_mask:0xf bank_mask:0xf
	v_cndmask_b32_e64 v142, v133, v134, s[0:1]
	v_cndmask_b32_e64 v138, v138, v132, s[0:1]
	v_mov_b32_e32 v132, v1
	v_mov_b32_e32 v133, v1
	v_cvt_f32_f16_e32 v134, v140
	v_mov_b32_dpp v132, v135 quad_perm:[1,0,3,2] row_mask:0xf bank_mask:0xf
	v_mov_b32_dpp v133, v139 quad_perm:[1,0,3,2] row_mask:0xf bank_mask:0xf
	v_cndmask_b32_e64 v143, v133, v135, s[0:1]
	v_cndmask_b32_e64 v139, v139, v132, s[0:1]
	v_cvt_f32_f16_e32 v132, v141
	v_cvt_f32_f16_sdwa v133, v141 dst_sel:DWORD dst_unused:UNUSED_PAD src0_sel:WORD_1
	v_cvt_f32_f16_sdwa v135, v140 dst_sel:DWORD dst_unused:UNUSED_PAD src0_sel:WORD_1
	v_fma_f32 v126, v126, v50, v132
	v_fma_f32 v127, v127, v51, v133
	v_cvt_f32_f16_e32 v132, v142
	v_cvt_f32_f16_sdwa v133, v142 dst_sel:DWORD dst_unused:UNUSED_PAD src0_sel:WORD_1
	v_fma_f32 v128, v128, v52, v134
	v_fma_f32 v129, v129, v53, v135
	v_cvt_f32_f16_e32 v134, v143
	v_cvt_f32_f16_sdwa v135, v143 dst_sel:DWORD dst_unused:UNUSED_PAD src0_sel:WORD_1
	v_fma_f32 v122, v122, v54, v132
	v_fma_f32 v123, v123, v55, v133
	v_cvt_f32_f16_e32 v132, v136
	v_cvt_f32_f16_sdwa v133, v136 dst_sel:DWORD dst_unused:UNUSED_PAD src0_sel:WORD_1
	v_fma_f32 v124, v124, v56, v134
	v_fma_f32 v125, v125, v57, v135
	v_cvt_f32_f16_e32 v134, v137
	v_cvt_f32_f16_sdwa v135, v137 dst_sel:DWORD dst_unused:UNUSED_PAD src0_sel:WORD_1
	v_fma_f32 v118, v118, v58, v132
	v_fma_f32 v119, v119, v59, v133
	v_cvt_f32_f16_e32 v132, v138
	v_cvt_f32_f16_sdwa v133, v138 dst_sel:DWORD dst_unused:UNUSED_PAD src0_sel:WORD_1
	v_fma_f32 v120, v120, v60, v134
	v_fma_f32 v121, v121, v61, v135
	v_cvt_f32_f16_e32 v134, v139
	v_cvt_f32_f16_sdwa v135, v139 dst_sel:DWORD dst_unused:UNUSED_PAD src0_sel:WORD_1
	v_cvt_pk_f16_f32 v140, v126, v127
	v_mov_b32_e32 v136, v1
	v_cvt_pk_f16_f32 v141, v128, v129
	v_fma_f32 v114, v114, v62, v132
	v_fma_f32 v115, v115, v63, v133
	v_cvt_pk_f16_f32 v133, v118, v119
	v_mov_b32_e32 v132, v1
	v_mov_b32_dpp v136, v140 quad_perm:[1,0,3,2] row_mask:0xf bank_mask:0xf
	v_mov_b32_e32 v137, v1
	v_cvt_pk_f16_f32 v142, v122, v123
	v_fma_f32 v116, v116, v64, v134
	v_fma_f32 v117, v117, v65, v135
	v_cvt_pk_f16_f32 v134, v120, v121
	v_mov_b32_dpp v132, v133 quad_perm:[1,0,3,2] row_mask:0xf bank_mask:0xf
	v_cndmask_b32_e64 v136, v133, v136, s[0:1]
	v_mov_b32_e32 v133, v1
	v_mov_b32_dpp v137, v141 quad_perm:[1,0,3,2] row_mask:0xf bank_mask:0xf
	v_mov_b32_e32 v138, v1
	v_cvt_pk_f16_f32 v135, v114, v115
	v_mov_b32_dpp v133, v134 quad_perm:[1,0,3,2] row_mask:0xf bank_mask:0xf
	v_cndmask_b32_e64 v137, v134, v137, s[0:1]
	v_mov_b32_e32 v134, v1
	v_mov_b32_dpp v138, v142 quad_perm:[1,0,3,2] row_mask:0xf bank_mask:0xf
	v_cvt_pk_f16_f32 v139, v116, v117
	v_mov_b32_dpp v134, v135 quad_perm:[1,0,3,2] row_mask:0xf bank_mask:0xf
	v_cndmask_b32_e64 v138, v135, v138, s[0:1]
	v_mov_b32_e32 v135, v1
	v_cvt_pk_f16_f32 v143, v124, v125
	v_cndmask_b32_e64 v132, v132, v140, s[0:1]
	v_mov_b32_dpp v135, v139 quad_perm:[1,0,3,2] row_mask:0xf bank_mask:0xf
	v_mov_b32_e32 v140, v1
	v_cndmask_b32_e64 v133, v133, v141, s[0:1]
	v_cndmask_b32_e64 v134, v134, v142, s[0:1]
	v_mov_b32_dpp v140, v143 quad_perm:[1,0,3,2] row_mask:0xf bank_mask:0xf
	v_cndmask_b32_e64 v135, v135, v143, s[0:1]
	v_cndmask_b32_e64 v139, v139, v140, s[0:1]
	global_store_dwordx4 v144, v[132:135], s[38:39] sc1
	s_nop 1
	v_add_u32_e32 v132, 0x16f90800, v0
	global_store_dwordx4 v132, v[136:139], s[38:39] sc1
	s_cbranch_vccnz .LBB0_473
	v_mul_f32_e32 v132, v32, v116
	v_mul_f32_e32 v133, v33, v117
	v_mul_f32_e32 v134, v30, v114
	v_mul_f32_e32 v135, v31, v115
	v_cvt_pk_f16_f32 v139, v132, v133
	v_cvt_pk_f16_f32 v138, v134, v135
	v_mul_f32_e32 v132, v28, v120
	v_mul_f32_e32 v133, v29, v121
	v_mul_f32_e32 v134, v26, v118
	v_mul_f32_e32 v135, v27, v119
	v_cvt_pk_f16_f32 v137, v132, v133
	v_cvt_pk_f16_f32 v136, v134, v135
	v_mul_f32_e32 v132, v24, v124
	v_mul_f32_e32 v133, v25, v125
	v_mul_f32_e32 v134, v22, v122
	v_mul_f32_e32 v135, v23, v123
	v_cvt_pk_f16_f32 v140, v132, v133
	v_cvt_pk_f16_f32 v141, v134, v135
	v_mul_f32_e32 v132, v20, v128
	v_mul_f32_e32 v133, v21, v129
	v_mul_f32_e32 v134, v18, v126
	v_mul_f32_e32 v135, v19, v127
	v_cvt_pk_f16_f32 v133, v132, v133
	v_cvt_pk_f16_f32 v132, v134, v135
	v_mov_b32_e32 v135, v1
	v_mov_b32_e32 v134, v1
	v_add_u32_e32 v142, 0x3d90000, v0
	v_mov_b32_dpp v135, v132 quad_perm:[1,0,3,2] row_mask:0xf bank_mask:0xf
	v_mov_b32_dpp v134, v136 quad_perm:[1,0,3,2] row_mask:0xf bank_mask:0xf
	v_cndmask_b32_e64 v136, v136, v135, s[0:1]
	v_mov_b32_e32 v135, v1
	v_cndmask_b32_e64 v132, v134, v132, s[0:1]
	v_mov_b32_e32 v134, v1
	v_mov_b32_dpp v135, v133 quad_perm:[1,0,3,2] row_mask:0xf bank_mask:0xf
	s_nop 0
	v_mov_b32_dpp v134, v137 quad_perm:[1,0,3,2] row_mask:0xf bank_mask:0xf
	v_cndmask_b32_e64 v137, v137, v135, s[0:1]
	v_mov_b32_e32 v135, v1
	v_cndmask_b32_e64 v133, v134, v133, s[0:1]
	v_mov_b32_e32 v134, v1
	v_mov_b32_dpp v135, v141 quad_perm:[1,0,3,2] row_mask:0xf bank_mask:0xf
	s_nop 0
	v_mov_b32_dpp v134, v138 quad_perm:[1,0,3,2] row_mask:0xf bank_mask:0xf
	v_cndmask_b32_e64 v138, v138, v135, s[0:1]
	v_mov_b32_e32 v135, v1
	v_cndmask_b32_e64 v134, v134, v141, s[0:1]
	v_mov_b32_e32 v141, v1
	v_mov_b32_dpp v135, v139 quad_perm:[1,0,3,2] row_mask:0xf bank_mask:0xf
	v_cndmask_b32_e64 v135, v135, v140, s[0:1]
	v_mov_b32_dpp v141, v140 quad_perm:[1,0,3,2] row_mask:0xf bank_mask:0xf
	v_cndmask_b32_e64 v139, v139, v141, s[0:1]
	global_store_dwordx4 v142, v[132:135], s[38:39] sc1
	s_nop 1
	v_add_u32_e32 v132, 0x3d90800, v0
	global_store_dwordx4 v132, v[136:139], s[38:39] sc1

; #define GAS __attribute__((address_space(1)))
; __device__ __forceinline__ unsigned cvtpk_h(float lo, float hi) { f32x2 v = {lo, hi}; h16x2 b = __builtin_convertvector(v, h16x2); return __builtin_bit_cast(unsigned, b); }
;     __device__ __forceinline__ void operator()(const f32x4 (&acc)[2][2][4][2], const pg8::Unit& u, int wr, int wc, int fr, int fq) const {
;     ...
;             for (int m = 0; m < 4; ++m) { if (half && ai == 1) continue; const unsigned rr = (unsigned)(ai * 128 + m * 16); const unsigned o = eoA + rr * (D * 2u); float ss = 0.f;
;                 const u32x4 la = *(const GAS u32x4*)((const GAS char*)ws + (unsigned)WS_X16 + o), lb = *(const GAS u32x4*)((const GAS char*)ws + (unsigned)WS_X16 + o + D * 2u);
;                 u32x4 xr[2];
; #pragma unroll
;                 for (int c = 0; c < 4; ++c) { const unsigned pa = (unsigned)__builtin_amdgcn_update_dpp(0, (int)la[c], 0xB1, 0xF, 0xF, false), pb = (unsigned)__builtin_amdgcn_update_dpp(0, (int)lb[c], 0xB1, 0xF, 0xF, false);
;                     xr[0][c] = odd ? pb : la[c]; xr[1][c] = odd ? lb[c] : pa; }
;                 u32x4 w[2], v[2];
; #pragma unroll
;                 for (int bj = 0; bj < 2; ++bj) { const h16x8 xb = __builtin_bit_cast(h16x8, xr[bj]);
;                     const f32x4 x0 = (f32x4){(float)xb[0], (float)xb[1], (float)xb[2], (float)xb[3]} + g4[bj][0] * acc[ai][bj][m][0], x1 = (f32x4){(float)xb[4], (float)xb[5], (float)xb[6], (float)xb[7]} + g4[bj][1] * acc[ai][bj][m][1];
;                     ss += ((x0[0] * x0[0] + x0[1] * x0[1]) + (x0[2] * x0[2] + x0[3] * x0[3])) + ((x1[0] * x1[0] + x1[1] * x1[1]) + (x1[2] * x1[2] + x1[3] * x1[3]));
;                     w[bj].x = cvtpk_h(x0[0], x0[1]); w[bj].y = cvtpk_h(x0[2], x0[3]); w[bj].z = cvtpk_h(x1[0], x1[1]); w[bj].w = cvtpk_h(x1[2], x1[3]);
;                     const f32x4 y0 = x0 * a4[bj][0], y1 = x1 * a4[bj][1]; v[bj].x = cvtpk_h(y0[0], y0[1]); v[bj].y = cvtpk_h(y0[2], y0[3]); v[bj].z = cvtpk_h(y1[0], y1[1]); v[bj].w = cvtpk_h(y1[2], y1[3]); }
;                 stg_line_pair(ws, (unsigned)WS_X16 + o, D * 2u, w[0], w[1], odd);
;                 if (an_off) stg_line_pair(ws, (unsigned)WS_XS + o, D * 2u, v[0], v[1], odd);
.Lo_wd_3:
	v_mov_b32_e32 v114, v214
	v_mov_b32_e32 v115, v215
	v_mov_b32_e32 v116, v216
	v_mov_b32_e32 v117, v217
	v_mov_b32_e32 v118, v218
	v_mov_b32_e32 v119, v219
	v_mov_b32_e32 v120, v220
	v_mov_b32_e32 v121, v221
	v_add_u32_e32 v222, 0x40000, v0
	global_load_dwordx4 v[214:217], v222, s[42:43]
	global_load_dwordx4 v[218:221], v222, s[42:43] offset:2048
	v_mov_b32_e32 v122, v1
	v_mov_b32_e32 v123, v1
	v_add_u32_e32 v126, 0x16f98000, v0
	s_and_b64 vcc, exec, s[2:3]
	v_mov_b32_dpp v122, v114 quad_perm:[1,0,3,2] row_mask:0xf bank_mask:0xf
	v_mov_b32_dpp v123, v118 quad_perm:[1,0,3,2] row_mask:0xf bank_mask:0xf
	v_cndmask_b32_e64 v123, v123, v114, s[0:1]
	v_cndmask_b32_e64 v118, v118, v122, s[0:1]
	v_mov_b32_e32 v114, v1
	v_mov_b32_e32 v122, v1
	s_nop 0
	v_mov_b32_dpp v114, v115 quad_perm:[1,0,3,2] row_mask:0xf bank_mask:0xf
	v_mov_b32_dpp v122, v119 quad_perm:[1,0,3,2] row_mask:0xf bank_mask:0xf
	v_cndmask_b32_e64 v122, v122, v115, s[0:1]
	v_cndmask_b32_e64 v119, v119, v114, s[0:1]
	v_mov_b32_e32 v114, v1
	v_mov_b32_e32 v115, v1
	s_nop 0
	v_mov_b32_dpp v114, v116 quad_perm:[1,0,3,2] row_mask:0xf bank_mask:0xf
	v_mov_b32_dpp v115, v120 quad_perm:[1,0,3,2] row_mask:0xf bank_mask:0xf
	v_cndmask_b32_e64 v124, v115, v116, s[0:1]
	v_cndmask_b32_e64 v120, v120, v114, s[0:1]
	v_mov_b32_e32 v114, v1
	v_mov_b32_e32 v115, v1
	v_cvt_f32_f16_e32 v116, v122
	v_mov_b32_dpp v114, v117 quad_perm:[1,0,3,2] row_mask:0xf bank_mask:0xf
	v_mov_b32_dpp v115, v121 quad_perm:[1,0,3,2] row_mask:0xf bank_mask:0xf
	v_cndmask_b32_e64 v125, v115, v117, s[0:1]
	v_cndmask_b32_e64 v121, v121, v114, s[0:1]
	v_cvt_f32_f16_e32 v114, v123
	v_cvt_f32_f16_sdwa v115, v123 dst_sel:DWORD dst_unused:UNUSED_PAD src0_sel:WORD_1
	v_cvt_f32_f16_sdwa v117, v122 dst_sel:DWORD dst_unused:UNUSED_PAD src0_sel:WORD_1
	v_fma_f32 v110, v110, v50, v114
	v_fma_f32 v111, v111, v51, v115
	v_cvt_f32_f16_e32 v114, v124
	v_cvt_f32_f16_sdwa v115, v124 dst_sel:DWORD dst_unused:UNUSED_PAD src0_sel:WORD_1
	v_fma_f32 v112, v112, v52, v116
	v_fma_f32 v113, v113, v53, v117
	v_cvt_f32_f16_e32 v116, v125
	v_cvt_f32_f16_sdwa v117, v125 dst_sel:DWORD dst_unused:UNUSED_PAD src0_sel:WORD_1
	v_fma_f32 v106, v106, v54, v114
	v_fma_f32 v107, v107, v55, v115
	v_cvt_f32_f16_e32 v114, v118
	v_cvt_f32_f16_sdwa v115, v118 dst_sel:DWORD dst_unused:UNUSED_PAD src0_sel:WORD_1
	v_fma_f32 v108, v108, v56, v116
	v_fma_f32 v109, v109, v57, v117
	v_cvt_f32_f16_e32 v116, v119
	v_cvt_f32_f16_sdwa v117, v119 dst_sel:DWORD dst_unused:UNUSED_PAD src0_sel:WORD_1
	v_fma_f32 v102, v102, v58, v114
	v_fma_f32 v103, v103, v59, v115
	v_cvt_f32_f16_e32 v114, v120
	v_cvt_f32_f16_sdwa v115, v120 dst_sel:DWORD dst_unused:UNUSED_PAD src0_sel:WORD_1
	v_fma_f32 v104, v104, v60, v116
	v_fma_f32 v105, v105, v61, v117
	v_cvt_f32_f16_e32 v116, v121
	v_cvt_f32_f16_sdwa v117, v121 dst_sel:DWORD dst_unused:UNUSED_PAD src0_sel:WORD_1
	v_cvt_pk_f16_f32 v122, v110, v111
	v_mov_b32_e32 v118, v1
	v_cvt_pk_f16_f32 v123, v112, v113
	v_fma_f32 v98, v98, v62, v114
	v_fma_f32 v99, v99, v63, v115
	v_cvt_pk_f16_f32 v115, v102, v103
	v_mov_b32_e32 v114, v1
	v_mov_b32_dpp v118, v122 quad_perm:[1,0,3,2] row_mask:0xf bank_mask:0xf
	v_mov_b32_e32 v119, v1
	v_cvt_pk_f16_f32 v124, v106, v107
	v_fma_f32 v100, v100, v64, v116
	v_fma_f32 v101, v101, v65, v117
	v_cvt_pk_f16_f32 v116, v104, v105
	v_mov_b32_dpp v114, v115 quad_perm:[1,0,3,2] row_mask:0xf bank_mask:0xf
	v_cndmask_b32_e64 v118, v115, v118, s[0:1]
	v_mov_b32_e32 v115, v1
	v_mov_b32_dpp v119, v123 quad_perm:[1,0,3,2] row_mask:0xf bank_mask:0xf
	v_mov_b32_e32 v120, v1
	v_cvt_pk_f16_f32 v117, v98, v99
	v_mov_b32_dpp v115, v116 quad_perm:[1,0,3,2] row_mask:0xf bank_mask:0xf
	v_cndmask_b32_e64 v119, v116, v119, s[0:1]
	v_mov_b32_e32 v116, v1
	v_mov_b32_dpp v120, v124 quad_perm:[1,0,3,2] row_mask:0xf bank_mask:0xf
	v_cvt_pk_f16_f32 v121, v100, v101
	v_mov_b32_dpp v116, v117 quad_perm:[1,0,3,2] row_mask:0xf bank_mask:0xf
	v_cndmask_b32_e64 v120, v117, v120, s[0:1]
	v_mov_b32_e32 v117, v1
	v_cvt_pk_f16_f32 v125, v108, v109
	v_cndmask_b32_e64 v114, v114, v122, s[0:1]
	v_mov_b32_dpp v117, v121 quad_perm:[1,0,3,2] row_mask:0xf bank_mask:0xf
	v_mov_b32_e32 v122, v1
	v_cndmask_b32_e64 v115, v115, v123, s[0:1]
	v_cndmask_b32_e64 v116, v116, v124, s[0:1]
	v_mov_b32_dpp v122, v125 quad_perm:[1,0,3,2] row_mask:0xf bank_mask:0xf
	v_cndmask_b32_e64 v117, v117, v125, s[0:1]
	v_cndmask_b32_e64 v121, v121, v122, s[0:1]
	global_store_dwordx4 v126, v[114:117], s[38:39] sc1
	s_nop 1
	v_add_u32_e32 v114, 0x16f98800, v0
	global_store_dwordx4 v114, v[118:121], s[38:39] sc1
	s_cbranch_vccnz .LBB0_477
	v_mul_f32_e32 v114, v32, v100
	v_mul_f32_e32 v115, v33, v101
	v_mul_f32_e32 v116, v30, v98
	v_mul_f32_e32 v117, v31, v99
	v_cvt_pk_f16_f32 v121, v114, v115
	v_cvt_pk_f16_f32 v120, v116, v117
	v_mul_f32_e32 v114, v28, v104
	v_mul_f32_e32 v115, v29, v105
	v_mul_f32_e32 v116, v26, v102
	v_mul_f32_e32 v117, v27, v103
	v_cvt_pk_f16_f32 v119, v114, v115
	v_cvt_pk_f16_f32 v118, v116, v117
	v_mul_f32_e32 v114, v24, v108
	v_mul_f32_e32 v115, v25, v109
	v_mul_f32_e32 v116, v22, v106
	v_mul_f32_e32 v117, v23, v107
	v_cvt_pk_f16_f32 v122, v114, v115
	v_cvt_pk_f16_f32 v123, v116, v117
	v_mul_f32_e32 v114, v20, v112
	v_mul_f32_e32 v115, v21, v113
	v_mul_f32_e32 v116, v18, v110
	v_mul_f32_e32 v117, v19, v111
	v_cvt_pk_f16_f32 v115, v114, v115
	v_cvt_pk_f16_f32 v114, v116, v117
	v_mov_b32_e32 v117, v1
	v_mov_b32_e32 v116, v1
	v_add_u32_e32 v124, 0x3d98000, v0
	v_mov_b32_dpp v117, v114 quad_perm:[1,0,3,2] row_mask:0xf bank_mask:0xf
	v_mov_b32_dpp v116, v118 quad_perm:[1,0,3,2] row_mask:0xf bank_mask:0xf
	v_cndmask_b32_e64 v118, v118, v117, s[0:1]
	v_mov_b32_e32 v117, v1
	v_cndmask_b32_e64 v114, v116, v114, s[0:1]
	v_mov_b32_e32 v116, v1
	v_mov_b32_dpp v117, v115 quad_perm:[1,0,3,2] row_mask:0xf bank_mask:0xf
	s_nop 0
	v_mov_b32_dpp v116, v119 quad_perm:[1,0,3,2] row_mask:0xf bank_mask:0xf
	v_cndmask_b32_e64 v119, v119, v117, s[0:1]
	v_mov_b32_e32 v117, v1
	v_cndmask_b32_e64 v115, v116, v115, s[0:1]
	v_mov_b32_e32 v116, v1
	v_mov_b32_dpp v117, v123 quad_perm:[1,0,3,2] row_mask:0xf bank_mask:0xf
	s_nop 0
	v_mov_b32_dpp v116, v120 quad_perm:[1,0,3,2] row_mask:0xf bank_mask:0xf
	v_cndmask_b32_e64 v120, v120, v117, s[0:1]
	v_mov_b32_e32 v117, v1
	v_cndmask_b32_e64 v116, v116, v123, s[0:1]
	v_mov_b32_e32 v123, v1
	v_mov_b32_dpp v117, v121 quad_perm:[1,0,3,2] row_mask:0xf bank_mask:0xf
	v_cndmask_b32_e64 v117, v117, v122, s[0:1]
	v_mov_b32_dpp v123, v122 quad_perm:[1,0,3,2] row_mask:0xf bank_mask:0xf
	v_cndmask_b32_e64 v121, v121, v123, s[0:1]
	global_store_dwordx4 v124, v[114:117], s[38:39] sc1
	s_nop 1
	v_add_u32_e32 v114, 0x3d98800, v0
	global_store_dwordx4 v114, v[118:121], s[38:39] sc1

; #define GAS __attribute__((address_space(1)))
; __device__ __forceinline__ unsigned cvtpk_h(float lo, float hi) { f32x2 v = {lo, hi}; h16x2 b = __builtin_convertvector(v, h16x2); return __builtin_bit_cast(unsigned, b); }
;     __device__ __forceinline__ void operator()(const f32x4 (&acc)[2][2][4][2], const pg8::Unit& u, int wr, int wc, int fr, int fq) const {
;     ...
;             for (int m = 0; m < 4; ++m) { if (half && ai == 1) continue; const unsigned rr = (unsigned)(ai * 128 + m * 16); const unsigned o = eoA + rr * (D * 2u); float ss = 0.f;
;                 const u32x4 la = *(const GAS u32x4*)((const GAS char*)ws + (unsigned)WS_X16 + o), lb = *(const GAS u32x4*)((const GAS char*)ws + (unsigned)WS_X16 + o + D * 2u);
;                 u32x4 xr[2];
; #pragma unroll
;                 for (int c = 0; c < 4; ++c) { const unsigned pa = (unsigned)__builtin_amdgcn_update_dpp(0, (int)la[c], 0xB1, 0xF, 0xF, false), pb = (unsigned)__builtin_amdgcn_update_dpp(0, (int)lb[c], 0xB1, 0xF, 0xF, false);
;                     xr[0][c] = odd ? pb : la[c]; xr[1][c] = odd ? lb[c] : pa; }
;                 u32x4 w[2], v[2];
; #pragma unroll
;                 for (int bj = 0; bj < 2; ++bj) { const h16x8 xb = __builtin_bit_cast(h16x8, xr[bj]);
;                     const f32x4 x0 = (f32x4){(float)xb[0], (float)xb[1], (float)xb[2], (float)xb[3]} + g4[bj][0] * acc[ai][bj][m][0], x1 = (f32x4){(float)xb[4], (float)xb[5], (float)xb[6], (float)xb[7]} + g4[bj][1] * acc[ai][bj][m][1];
;                     ss += ((x0[0] * x0[0] + x0[1] * x0[1]) + (x0[2] * x0[2] + x0[3] * x0[3])) + ((x1[0] * x1[0] + x1[1] * x1[1]) + (x1[2] * x1[2] + x1[3] * x1[3]));
;                     w[bj].x = cvtpk_h(x0[0], x0[1]); w[bj].y = cvtpk_h(x0[2], x0[3]); w[bj].z = cvtpk_h(x1[0], x1[1]); w[bj].w = cvtpk_h(x1[2], x1[3]);
;                     const f32x4 y0 = x0 * a4[bj][0], y1 = x1 * a4[bj][1]; v[bj].x = cvtpk_h(y0[0], y0[1]); v[bj].y = cvtpk_h(y0[2], y0[3]); v[bj].z = cvtpk_h(y1[0], y1[1]); v[bj].w = cvtpk_h(y1[2], y1[3]); }
;                 stg_line_pair(ws, (unsigned)WS_X16 + o, D * 2u, w[0], w[1], odd);
;                 if (an_off) stg_line_pair(ws, (unsigned)WS_XS + o, D * 2u, v[0], v[1], odd);
.Lo_wd_4:
	v_mov_b32_e32 v98, v214
	v_mov_b32_e32 v99, v215
	v_mov_b32_e32 v100, v216
	v_mov_b32_e32 v101, v217
	v_mov_b32_e32 v102, v218
	v_mov_b32_e32 v103, v219
	v_mov_b32_e32 v104, v220
	v_mov_b32_e32 v105, v221
	v_add_u32_e32 v222, 0x48000, v0
	global_load_dwordx4 v[214:217], v222, s[42:43]
	global_load_dwordx4 v[218:221], v222, s[42:43] offset:2048
	v_mov_b32_e32 v106, v1
	v_mov_b32_e32 v107, v1
	v_add_u32_e32 v110, 0x16fc0000, v0
	s_and_b64 vcc, exec, s[2:3]
	v_mov_b32_dpp v106, v98 quad_perm:[1,0,3,2] row_mask:0xf bank_mask:0xf
	v_mov_b32_dpp v107, v102 quad_perm:[1,0,3,2] row_mask:0xf bank_mask:0xf
	v_cndmask_b32_e64 v107, v107, v98, s[0:1]
	v_cndmask_b32_e64 v102, v102, v106, s[0:1]
	v_mov_b32_e32 v98, v1
	v_mov_b32_e32 v106, v1
	s_nop 0
	v_mov_b32_dpp v98, v99 quad_perm:[1,0,3,2] row_mask:0xf bank_mask:0xf
	v_mov_b32_dpp v106, v103 quad_perm:[1,0,3,2] row_mask:0xf bank_mask:0xf
	v_cndmask_b32_e64 v106, v106, v99, s[0:1]
	v_cndmask_b32_e64 v103, v103, v98, s[0:1]
	v_mov_b32_e32 v98, v1
	v_mov_b32_e32 v99, v1
	s_nop 0
	v_mov_b32_dpp v98, v100 quad_perm:[1,0,3,2] row_mask:0xf bank_mask:0xf
	v_mov_b32_dpp v99, v104 quad_perm:[1,0,3,2] row_mask:0xf bank_mask:0xf
	v_cndmask_b32_e64 v108, v99, v100, s[0:1]
	v_cndmask_b32_e64 v104, v104, v98, s[0:1]
	v_mov_b32_e32 v98, v1
	v_mov_b32_e32 v99, v1
	v_cvt_f32_f16_e32 v100, v106
	v_mov_b32_dpp v98, v101 quad_perm:[1,0,3,2] row_mask:0xf bank_mask:0xf
	v_mov_b32_dpp v99, v105 quad_perm:[1,0,3,2] row_mask:0xf bank_mask:0xf
	v_cndmask_b32_e64 v109, v99, v101, s[0:1]
	v_cndmask_b32_e64 v105, v105, v98, s[0:1]
	v_cvt_f32_f16_e32 v98, v107
	v_cvt_f32_f16_sdwa v99, v107 dst_sel:DWORD dst_unused:UNUSED_PAD src0_sel:WORD_1
	v_cvt_f32_f16_sdwa v101, v106 dst_sel:DWORD dst_unused:UNUSED_PAD src0_sel:WORD_1
	v_fma_f32 v94, v94, v50, v98
	v_fma_f32 v95, v95, v51, v99
	v_cvt_f32_f16_e32 v98, v108
	v_cvt_f32_f16_sdwa v99, v108 dst_sel:DWORD dst_unused:UNUSED_PAD src0_sel:WORD_1
	v_fma_f32 v96, v96, v52, v100
	v_fma_f32 v97, v97, v53, v101
	v_cvt_f32_f16_e32 v100, v109
	v_cvt_f32_f16_sdwa v101, v109 dst_sel:DWORD dst_unused:UNUSED_PAD src0_sel:WORD_1
	v_fma_f32 v90, v90, v54, v98
	v_fma_f32 v91, v91, v55, v99
	v_cvt_f32_f16_e32 v98, v102
	v_cvt_f32_f16_sdwa v99, v102 dst_sel:DWORD dst_unused:UNUSED_PAD src0_sel:WORD_1
	v_fma_f32 v92, v92, v56, v100
	v_fma_f32 v93, v93, v57, v101
	v_cvt_f32_f16_e32 v100, v103
	v_cvt_f32_f16_sdwa v101, v103 dst_sel:DWORD dst_unused:UNUSED_PAD src0_sel:WORD_1
	v_fma_f32 v86, v86, v58, v98
	v_fma_f32 v87, v87, v59, v99
	v_cvt_f32_f16_e32 v98, v104
	v_cvt_f32_f16_sdwa v99, v104 dst_sel:DWORD dst_unused:UNUSED_PAD src0_sel:WORD_1
	v_fma_f32 v88, v88, v60, v100
	v_fma_f32 v89, v89, v61, v101
	v_cvt_f32_f16_e32 v100, v105
	v_cvt_f32_f16_sdwa v101, v105 dst_sel:DWORD dst_unused:UNUSED_PAD src0_sel:WORD_1
	v_cvt_pk_f16_f32 v106, v94, v95
	v_mov_b32_e32 v102, v1
	v_cvt_pk_f16_f32 v107, v96, v97
	v_fma_f32 v82, v82, v62, v98
	v_fma_f32 v83, v83, v63, v99
	v_cvt_pk_f16_f32 v99, v86, v87
	v_mov_b32_e32 v98, v1
	v_mov_b32_dpp v102, v106 quad_perm:[1,0,3,2] row_mask:0xf bank_mask:0xf
	v_mov_b32_e32 v103, v1
	v_cvt_pk_f16_f32 v108, v90, v91
	v_fma_f32 v84, v84, v64, v100
	v_fma_f32 v85, v85, v65, v101
	v_cvt_pk_f16_f32 v100, v88, v89
	v_mov_b32_dpp v98, v99 quad_perm:[1,0,3,2] row_mask:0xf bank_mask:0xf
	v_cndmask_b32_e64 v102, v99, v102, s[0:1]
	v_mov_b32_e32 v99, v1
	v_mov_b32_dpp v103, v107 quad_perm:[1,0,3,2] row_mask:0xf bank_mask:0xf
	v_mov_b32_e32 v104, v1
	v_cvt_pk_f16_f32 v101, v82, v83
	v_mov_b32_dpp v99, v100 quad_perm:[1,0,3,2] row_mask:0xf bank_mask:0xf
	v_cndmask_b32_e64 v103, v100, v103, s[0:1]
	v_mov_b32_e32 v100, v1
	v_mov_b32_dpp v104, v108 quad_perm:[1,0,3,2] row_mask:0xf bank_mask:0xf
	v_cvt_pk_f16_f32 v105, v84, v85
	v_mov_b32_dpp v100, v101 quad_perm:[1,0,3,2] row_mask:0xf bank_mask:0xf
	v_cndmask_b32_e64 v104, v101, v104, s[0:1]
	v_mov_b32_e32 v101, v1
	v_cvt_pk_f16_f32 v109, v92, v93
	v_cndmask_b32_e64 v98, v98, v106, s[0:1]
	v_mov_b32_dpp v101, v105 quad_perm:[1,0,3,2] row_mask:0xf bank_mask:0xf
	v_mov_b32_e32 v106, v1
	v_cndmask_b32_e64 v99, v99, v107, s[0:1]
	v_cndmask_b32_e64 v100, v100, v108, s[0:1]
	v_mov_b32_dpp v106, v109 quad_perm:[1,0,3,2] row_mask:0xf bank_mask:0xf
	v_cndmask_b32_e64 v101, v101, v109, s[0:1]
	v_cndmask_b32_e64 v105, v105, v106, s[0:1]
	global_store_dwordx4 v110, v[98:101], s[38:39] sc1
	s_nop 1
	v_add_u32_e32 v98, 0x16fc0800, v0
	global_store_dwordx4 v98, v[102:105], s[38:39] sc1
	s_cbranch_vccnz .LBB0_481
	v_mul_f32_e32 v98, v32, v84
	v_mul_f32_e32 v99, v33, v85
	v_mul_f32_e32 v100, v30, v82
	v_mul_f32_e32 v101, v31, v83
	v_cvt_pk_f16_f32 v105, v98, v99
	v_cvt_pk_f16_f32 v104, v100, v101
	v_mul_f32_e32 v98, v28, v88
	v_mul_f32_e32 v99, v29, v89
	v_mul_f32_e32 v100, v26, v86
	v_mul_f32_e32 v101, v27, v87
	v_cvt_pk_f16_f32 v103, v98, v99
	v_cvt_pk_f16_f32 v102, v100, v101
	v_mul_f32_e32 v98, v24, v92
	v_mul_f32_e32 v99, v25, v93
	v_mul_f32_e32 v100, v22, v90
	v_mul_f32_e32 v101, v23, v91
	v_cvt_pk_f16_f32 v106, v98, v99
	v_cvt_pk_f16_f32 v107, v100, v101
	v_mul_f32_e32 v98, v20, v96
	v_mul_f32_e32 v99, v21, v97
	v_mul_f32_e32 v100, v18, v94
	v_mul_f32_e32 v101, v19, v95
	v_cvt_pk_f16_f32 v99, v98, v99
	v_cvt_pk_f16_f32 v98, v100, v101
	v_mov_b32_e32 v101, v1
	v_mov_b32_e32 v100, v1
	v_add_u32_e32 v108, 0x3dc0000, v0
	v_mov_b32_dpp v101, v98 quad_perm:[1,0,3,2] row_mask:0xf bank_mask:0xf
	v_mov_b32_dpp v100, v102 quad_perm:[1,0,3,2] row_mask:0xf bank_mask:0xf
	v_cndmask_b32_e64 v102, v102, v101, s[0:1]
	v_mov_b32_e32 v101, v1
	v_cndmask_b32_e64 v98, v100, v98, s[0:1]
	v_mov_b32_e32 v100, v1
	v_mov_b32_dpp v101, v99 quad_perm:[1,0,3,2] row_mask:0xf bank_mask:0xf
	s_nop 0
	v_mov_b32_dpp v100, v103 quad_perm:[1,0,3,2] row_mask:0xf bank_mask:0xf
	v_cndmask_b32_e64 v103, v103, v101, s[0:1]
	v_mov_b32_e32 v101, v1
	v_cndmask_b32_e64 v99, v100, v99, s[0:1]
	v_mov_b32_e32 v100, v1
	v_mov_b32_dpp v101, v107 quad_perm:[1,0,3,2] row_mask:0xf bank_mask:0xf
	s_nop 0
	v_mov_b32_dpp v100, v104 quad_perm:[1,0,3,2] row_mask:0xf bank_mask:0xf
	v_cndmask_b32_e64 v104, v104, v101, s[0:1]
	v_mov_b32_e32 v101, v1
	v_cndmask_b32_e64 v100, v100, v107, s[0:1]
	v_mov_b32_e32 v107, v1
	v_mov_b32_dpp v101, v105 quad_perm:[1,0,3,2] row_mask:0xf bank_mask:0xf
	v_cndmask_b32_e64 v101, v101, v106, s[0:1]
	v_mov_b32_dpp v107, v106 quad_perm:[1,0,3,2] row_mask:0xf bank_mask:0xf
	v_cndmask_b32_e64 v105, v105, v107, s[0:1]
	global_store_dwordx4 v108, v[98:101], s[38:39] sc1
	s_nop 1
	v_add_u32_e32 v98, 0x3dc0800, v0
	global_store_dwordx4 v98, v[102:105], s[38:39] sc1

; #define GAS __attribute__((address_space(1)))
; __device__ __forceinline__ unsigned cvtpk_h(float lo, float hi) { f32x2 v = {lo, hi}; h16x2 b = __builtin_convertvector(v, h16x2); return __builtin_bit_cast(unsigned, b); }
;     __device__ __forceinline__ void operator()(const f32x4 (&acc)[2][2][4][2], const pg8::Unit& u, int wr, int wc, int fr, int fq) const {
;     ...
;             for (int m = 0; m < 4; ++m) { if (half && ai == 1) continue; const unsigned rr = (unsigned)(ai * 128 + m * 16); const unsigned o = eoA + rr * (D * 2u); float ss = 0.f;
;                 const u32x4 la = *(const GAS u32x4*)((const GAS char*)ws + (unsigned)WS_X16 + o), lb = *(const GAS u32x4*)((const GAS char*)ws + (unsigned)WS_X16 + o + D * 2u);
;                 u32x4 xr[2];
; #pragma unroll
;                 for (int c = 0; c < 4; ++c) { const unsigned pa = (unsigned)__builtin_amdgcn_update_dpp(0, (int)la[c], 0xB1, 0xF, 0xF, false), pb = (unsigned)__builtin_amdgcn_update_dpp(0, (int)lb[c], 0xB1, 0xF, 0xF, false);
;                     xr[0][c] = odd ? pb : la[c]; xr[1][c] = odd ? lb[c] : pa; }
;                 u32x4 w[2], v[2];
; #pragma unroll
;                 for (int bj = 0; bj < 2; ++bj) { const h16x8 xb = __builtin_bit_cast(h16x8, xr[bj]);
;                     const f32x4 x0 = (f32x4){(float)xb[0], (float)xb[1], (float)xb[2], (float)xb[3]} + g4[bj][0] * acc[ai][bj][m][0], x1 = (f32x4){(float)xb[4], (float)xb[5], (float)xb[6], (float)xb[7]} + g4[bj][1] * acc[ai][bj][m][1];
;                     ss += ((x0[0] * x0[0] + x0[1] * x0[1]) + (x0[2] * x0[2] + x0[3] * x0[3])) + ((x1[0] * x1[0] + x1[1] * x1[1]) + (x1[2] * x1[2] + x1[3] * x1[3]));
;                     w[bj].x = cvtpk_h(x0[0], x0[1]); w[bj].y = cvtpk_h(x0[2], x0[3]); w[bj].z = cvtpk_h(x1[0], x1[1]); w[bj].w = cvtpk_h(x1[2], x1[3]);
;                     const f32x4 y0 = x0 * a4[bj][0], y1 = x1 * a4[bj][1]; v[bj].x = cvtpk_h(y0[0], y0[1]); v[bj].y = cvtpk_h(y0[2], y0[3]); v[bj].z = cvtpk_h(y1[0], y1[1]); v[bj].w = cvtpk_h(y1[2], y1[3]); }
;                 stg_line_pair(ws, (unsigned)WS_X16 + o, D * 2u, w[0], w[1], odd);
;                 if (an_off) stg_line_pair(ws, (unsigned)WS_XS + o, D * 2u, v[0], v[1], odd);
.Lo_wd_5:
	v_mov_b32_e32 v82, v214
	v_mov_b32_e32 v83, v215
	v_mov_b32_e32 v84, v216
	v_mov_b32_e32 v85, v217
	v_mov_b32_e32 v86, v218
	v_mov_b32_e32 v87, v219
	v_mov_b32_e32 v88, v220
	v_mov_b32_e32 v89, v221
	v_add_u32_e32 v222, 0x50000, v0
	global_load_dwordx4 v[214:217], v222, s[42:43]
	global_load_dwordx4 v[218:221], v222, s[42:43] offset:2048
	v_mov_b32_e32 v90, v1
	v_mov_b32_e32 v91, v1
	v_add_u32_e32 v94, 0x16fc8000, v0
	s_and_b64 vcc, exec, s[2:3]
	v_mov_b32_dpp v90, v82 quad_perm:[1,0,3,2] row_mask:0xf bank_mask:0xf
	v_mov_b32_dpp v91, v86 quad_perm:[1,0,3,2] row_mask:0xf bank_mask:0xf
	v_cndmask_b32_e64 v91, v91, v82, s[0:1]
	v_cndmask_b32_e64 v86, v86, v90, s[0:1]
	v_mov_b32_e32 v82, v1
	v_mov_b32_e32 v90, v1
	s_nop 0
	v_mov_b32_dpp v82, v83 quad_perm:[1,0,3,2] row_mask:0xf bank_mask:0xf
	v_mov_b32_dpp v90, v87 quad_perm:[1,0,3,2] row_mask:0xf bank_mask:0xf
	v_cndmask_b32_e64 v90, v90, v83, s[0:1]
	v_cndmask_b32_e64 v87, v87, v82, s[0:1]
	v_mov_b32_e32 v82, v1
	v_mov_b32_e32 v83, v1
	s_nop 0
	v_mov_b32_dpp v82, v84 quad_perm:[1,0,3,2] row_mask:0xf bank_mask:0xf
	v_mov_b32_dpp v83, v88 quad_perm:[1,0,3,2] row_mask:0xf bank_mask:0xf
	v_cndmask_b32_e64 v92, v83, v84, s[0:1]
	v_cndmask_b32_e64 v88, v88, v82, s[0:1]
	v_mov_b32_e32 v82, v1
	v_mov_b32_e32 v83, v1
	v_cvt_f32_f16_e32 v84, v90
	v_mov_b32_dpp v82, v85 quad_perm:[1,0,3,2] row_mask:0xf bank_mask:0xf
	v_mov_b32_dpp v83, v89 quad_perm:[1,0,3,2] row_mask:0xf bank_mask:0xf
	v_cndmask_b32_e64 v93, v83, v85, s[0:1]
	v_cndmask_b32_e64 v89, v89, v82, s[0:1]
	v_cvt_f32_f16_e32 v82, v91
	v_cvt_f32_f16_sdwa v83, v91 dst_sel:DWORD dst_unused:UNUSED_PAD src0_sel:WORD_1
	v_cvt_f32_f16_sdwa v85, v90 dst_sel:DWORD dst_unused:UNUSED_PAD src0_sel:WORD_1
	v_fma_f32 v78, v78, v50, v82
	v_fma_f32 v79, v79, v51, v83
	v_cvt_f32_f16_e32 v82, v92
	v_cvt_f32_f16_sdwa v83, v92 dst_sel:DWORD dst_unused:UNUSED_PAD src0_sel:WORD_1
	v_fma_f32 v80, v80, v52, v84
	v_fma_f32 v81, v81, v53, v85
	v_cvt_f32_f16_e32 v84, v93
	v_cvt_f32_f16_sdwa v85, v93 dst_sel:DWORD dst_unused:UNUSED_PAD src0_sel:WORD_1
	v_fma_f32 v74, v74, v54, v82
	v_fma_f32 v75, v75, v55, v83
	v_cvt_f32_f16_e32 v82, v86
	v_cvt_f32_f16_sdwa v83, v86 dst_sel:DWORD dst_unused:UNUSED_PAD src0_sel:WORD_1
	v_fma_f32 v76, v76, v56, v84
	v_fma_f32 v77, v77, v57, v85
	v_cvt_f32_f16_e32 v84, v87
	v_cvt_f32_f16_sdwa v85, v87 dst_sel:DWORD dst_unused:UNUSED_PAD src0_sel:WORD_1
	v_fma_f32 v70, v70, v58, v82
	v_fma_f32 v71, v71, v59, v83
	v_cvt_f32_f16_e32 v82, v88
	v_cvt_f32_f16_sdwa v83, v88 dst_sel:DWORD dst_unused:UNUSED_PAD src0_sel:WORD_1
	v_fma_f32 v72, v72, v60, v84
	v_fma_f32 v73, v73, v61, v85
	v_cvt_f32_f16_e32 v84, v89
	v_cvt_f32_f16_sdwa v85, v89 dst_sel:DWORD dst_unused:UNUSED_PAD src0_sel:WORD_1
	v_cvt_pk_f16_f32 v90, v78, v79
	v_mov_b32_e32 v86, v1
	v_cvt_pk_f16_f32 v91, v80, v81
	v_fma_f32 v66, v66, v62, v82
	v_fma_f32 v67, v67, v63, v83
	v_cvt_pk_f16_f32 v83, v70, v71
	v_mov_b32_e32 v82, v1
	v_mov_b32_dpp v86, v90 quad_perm:[1,0,3,2] row_mask:0xf bank_mask:0xf
	v_mov_b32_e32 v87, v1
	v_cvt_pk_f16_f32 v92, v74, v75
	v_fma_f32 v68, v68, v64, v84
	v_fma_f32 v69, v69, v65, v85
	v_cvt_pk_f16_f32 v84, v72, v73
	v_mov_b32_dpp v82, v83 quad_perm:[1,0,3,2] row_mask:0xf bank_mask:0xf
	v_cndmask_b32_e64 v86, v83, v86, s[0:1]
	v_mov_b32_e32 v83, v1
	v_mov_b32_dpp v87, v91 quad_perm:[1,0,3,2] row_mask:0xf bank_mask:0xf
	v_mov_b32_e32 v88, v1
	v_cvt_pk_f16_f32 v85, v66, v67
	v_mov_b32_dpp v83, v84 quad_perm:[1,0,3,2] row_mask:0xf bank_mask:0xf
	v_cndmask_b32_e64 v87, v84, v87, s[0:1]
	v_mov_b32_e32 v84, v1
	v_mov_b32_dpp v88, v92 quad_perm:[1,0,3,2] row_mask:0xf bank_mask:0xf
	v_cvt_pk_f16_f32 v89, v68, v69
	v_mov_b32_dpp v84, v85 quad_perm:[1,0,3,2] row_mask:0xf bank_mask:0xf
	v_cndmask_b32_e64 v88, v85, v88, s[0:1]
	v_mov_b32_e32 v85, v1
	v_cvt_pk_f16_f32 v93, v76, v77
	v_cndmask_b32_e64 v82, v82, v90, s[0:1]
	v_mov_b32_dpp v85, v89 quad_perm:[1,0,3,2] row_mask:0xf bank_mask:0xf
	v_mov_b32_e32 v90, v1
	v_cndmask_b32_e64 v83, v83, v91, s[0:1]
	v_cndmask_b32_e64 v84, v84, v92, s[0:1]
	v_mov_b32_dpp v90, v93 quad_perm:[1,0,3,2] row_mask:0xf bank_mask:0xf
	v_cndmask_b32_e64 v85, v85, v93, s[0:1]
	v_cndmask_b32_e64 v89, v89, v90, s[0:1]
	global_store_dwordx4 v94, v[82:85], s[38:39] sc1
	s_nop 1
	v_add_u32_e32 v82, 0x16fc8800, v0
	global_store_dwordx4 v82, v[86:89], s[38:39] sc1
	s_cbranch_vccnz .LBB0_485
	v_mul_f32_e32 v82, v32, v68
	v_mul_f32_e32 v83, v33, v69
	v_mul_f32_e32 v84, v30, v66
	v_mul_f32_e32 v85, v31, v67
	v_cvt_pk_f16_f32 v89, v82, v83
	v_cvt_pk_f16_f32 v88, v84, v85
	v_mul_f32_e32 v82, v28, v72
	v_mul_f32_e32 v83, v29, v73
	v_mul_f32_e32 v84, v26, v70
	v_mul_f32_e32 v85, v27, v71
	v_cvt_pk_f16_f32 v87, v82, v83
	v_cvt_pk_f16_f32 v86, v84, v85
	v_mul_f32_e32 v82, v24, v76
	v_mul_f32_e32 v83, v25, v77
	v_mul_f32_e32 v84, v22, v74
	v_mul_f32_e32 v85, v23, v75
	v_cvt_pk_f16_f32 v90, v82, v83
	v_cvt_pk_f16_f32 v91, v84, v85
	v_mul_f32_e32 v82, v20, v80
	v_mul_f32_e32 v83, v21, v81
	v_mul_f32_e32 v84, v18, v78
	v_mul_f32_e32 v85, v19, v79
	v_cvt_pk_f16_f32 v83, v82, v83
	v_cvt_pk_f16_f32 v82, v84, v85
	v_mov_b32_e32 v85, v1
	v_mov_b32_e32 v84, v1
	v_add_u32_e32 v92, 0x3dc8000, v0
	v_mov_b32_dpp v85, v82 quad_perm:[1,0,3,2] row_mask:0xf bank_mask:0xf
	v_mov_b32_dpp v84, v86 quad_perm:[1,0,3,2] row_mask:0xf bank_mask:0xf
	v_cndmask_b32_e64 v86, v86, v85, s[0:1]
	v_mov_b32_e32 v85, v1
	v_cndmask_b32_e64 v82, v84, v82, s[0:1]
	v_mov_b32_e32 v84, v1
	v_mov_b32_dpp v85, v83 quad_perm:[1,0,3,2] row_mask:0xf bank_mask:0xf
	s_nop 0
	v_mov_b32_dpp v84, v87 quad_perm:[1,0,3,2] row_mask:0xf bank_mask:0xf
	v_cndmask_b32_e64 v87, v87, v85, s[0:1]
	v_mov_b32_e32 v85, v1
	v_cndmask_b32_e64 v83, v84, v83, s[0:1]
	v_mov_b32_e32 v84, v1
	v_mov_b32_dpp v85, v91 quad_perm:[1,0,3,2] row_mask:0xf bank_mask:0xf
	s_nop 0
	v_mov_b32_dpp v84, v88 quad_perm:[1,0,3,2] row_mask:0xf bank_mask:0xf
	v_cndmask_b32_e64 v88, v88, v85, s[0:1]
	v_mov_b32_e32 v85, v1
	v_cndmask_b32_e64 v84, v84, v91, s[0:1]
	v_mov_b32_e32 v91, v1
	v_mov_b32_dpp v85, v89 quad_perm:[1,0,3,2] row_mask:0xf bank_mask:0xf
	v_cndmask_b32_e64 v85, v85, v90, s[0:1]
	v_mov_b32_dpp v91, v90 quad_perm:[1,0,3,2] row_mask:0xf bank_mask:0xf
	v_cndmask_b32_e64 v89, v89, v91, s[0:1]
	global_store_dwordx4 v92, v[82:85], s[38:39] sc1
	s_nop 1
	v_add_u32_e32 v82, 0x3dc8800, v0
	global_store_dwordx4 v82, v[86:89], s[38:39] sc1

; #define GAS __attribute__((address_space(1)))
; __device__ __forceinline__ unsigned cvtpk_h(float lo, float hi) { f32x2 v = {lo, hi}; h16x2 b = __builtin_convertvector(v, h16x2); return __builtin_bit_cast(unsigned, b); }
;     __device__ __forceinline__ void operator()(const f32x4 (&acc)[2][2][4][2], const pg8::Unit& u, int wr, int wc, int fr, int fq) const {
;     ...
;             for (int m = 0; m < 4; ++m) { if (half && ai == 1) continue; const unsigned rr = (unsigned)(ai * 128 + m * 16); const unsigned o = eoA + rr * (D * 2u); float ss = 0.f;
;                 const u32x4 la = *(const GAS u32x4*)((const GAS char*)ws + (unsigned)WS_X16 + o), lb = *(const GAS u32x4*)((const GAS char*)ws + (unsigned)WS_X16 + o + D * 2u);
;                 u32x4 xr[2];
; #pragma unroll
;                 for (int c = 0; c < 4; ++c) { const unsigned pa = (unsigned)__builtin_amdgcn_update_dpp(0, (int)la[c], 0xB1, 0xF, 0xF, false), pb = (unsigned)__builtin_amdgcn_update_dpp(0, (int)lb[c], 0xB1, 0xF, 0xF, false);
;                     xr[0][c] = odd ? pb : la[c]; xr[1][c] = odd ? lb[c] : pa; }
;                 u32x4 w[2], v[2];
; #pragma unroll
;                 for (int bj = 0; bj < 2; ++bj) { const h16x8 xb = __builtin_bit_cast(h16x8, xr[bj]);
;                     const f32x4 x0 = (f32x4){(float)xb[0], (float)xb[1], (float)xb[2], (float)xb[3]} + g4[bj][0] * acc[ai][bj][m][0], x1 = (f32x4){(float)xb[4], (float)xb[5], (float)xb[6], (float)xb[7]} + g4[bj][1] * acc[ai][bj][m][1];
;                     ss += ((x0[0] * x0[0] + x0[1] * x0[1]) + (x0[2] * x0[2] + x0[3] * x0[3])) + ((x1[0] * x1[0] + x1[1] * x1[1]) + (x1[2] * x1[2] + x1[3] * x1[3]));
;                     w[bj].x = cvtpk_h(x0[0], x0[1]); w[bj].y = cvtpk_h(x0[2], x0[3]); w[bj].z = cvtpk_h(x1[0], x1[1]); w[bj].w = cvtpk_h(x1[2], x1[3]);
;                     const f32x4 y0 = x0 * a4[bj][0], y1 = x1 * a4[bj][1]; v[bj].x = cvtpk_h(y0[0], y0[1]); v[bj].y = cvtpk_h(y0[2], y0[3]); v[bj].z = cvtpk_h(y1[0], y1[1]); v[bj].w = cvtpk_h(y1[2], y1[3]); }
;                 stg_line_pair(ws, (unsigned)WS_X16 + o, D * 2u, w[0], w[1], odd);
;                 if (an_off) stg_line_pair(ws, (unsigned)WS_XS + o, D * 2u, v[0], v[1], odd);
.Lo_wd_6:
	v_mov_b32_e32 v66, v214
	v_mov_b32_e32 v67, v215
	v_mov_b32_e32 v68, v216
	v_mov_b32_e32 v69, v217
	v_mov_b32_e32 v70, v218
	v_mov_b32_e32 v71, v219
	v_mov_b32_e32 v72, v220
	v_mov_b32_e32 v73, v221
	v_add_u32_e32 v222, 0x58000, v0
	global_load_dwordx4 v[214:217], v222, s[42:43]
	global_load_dwordx4 v[218:221], v222, s[42:43] offset:2048
	v_mov_b32_e32 v74, v1
	v_mov_b32_e32 v75, v1
	v_add_u32_e32 v78, 0x16fd0000, v0
	s_and_b64 vcc, exec, s[2:3]
	v_mov_b32_dpp v74, v66 quad_perm:[1,0,3,2] row_mask:0xf bank_mask:0xf
	v_mov_b32_dpp v75, v70 quad_perm:[1,0,3,2] row_mask:0xf bank_mask:0xf
	v_cndmask_b32_e64 v75, v75, v66, s[0:1]
	v_cndmask_b32_e64 v70, v70, v74, s[0:1]
	v_mov_b32_e32 v66, v1
	v_mov_b32_e32 v74, v1
	s_nop 0
	v_mov_b32_dpp v66, v67 quad_perm:[1,0,3,2] row_mask:0xf bank_mask:0xf
	v_mov_b32_dpp v74, v71 quad_perm:[1,0,3,2] row_mask:0xf bank_mask:0xf
	v_cndmask_b32_e64 v74, v74, v67, s[0:1]
	v_cndmask_b32_e64 v71, v71, v66, s[0:1]
	v_mov_b32_e32 v66, v1
	v_mov_b32_e32 v67, v1
	s_nop 0
	v_mov_b32_dpp v66, v68 quad_perm:[1,0,3,2] row_mask:0xf bank_mask:0xf
	v_mov_b32_dpp v67, v72 quad_perm:[1,0,3,2] row_mask:0xf bank_mask:0xf
	v_cndmask_b32_e64 v76, v67, v68, s[0:1]
	v_cndmask_b32_e64 v72, v72, v66, s[0:1]
	v_mov_b32_e32 v66, v1
	v_mov_b32_e32 v67, v1
	v_cvt_f32_f16_e32 v68, v74
	v_mov_b32_dpp v66, v69 quad_perm:[1,0,3,2] row_mask:0xf bank_mask:0xf
	v_mov_b32_dpp v67, v73 quad_perm:[1,0,3,2] row_mask:0xf bank_mask:0xf
	v_cndmask_b32_e64 v77, v67, v69, s[0:1]
	v_cndmask_b32_e64 v73, v73, v66, s[0:1]
	v_cvt_f32_f16_e32 v66, v75
	v_cvt_f32_f16_sdwa v67, v75 dst_sel:DWORD dst_unused:UNUSED_PAD src0_sel:WORD_1
	v_cvt_f32_f16_sdwa v69, v74 dst_sel:DWORD dst_unused:UNUSED_PAD src0_sel:WORD_1
	v_fma_f32 v46, v46, v50, v66
	v_fma_f32 v47, v47, v51, v67
	v_cvt_f32_f16_e32 v66, v76
	v_cvt_f32_f16_sdwa v67, v76 dst_sel:DWORD dst_unused:UNUSED_PAD src0_sel:WORD_1
	v_fma_f32 v48, v48, v52, v68
	v_fma_f32 v49, v49, v53, v69
	v_cvt_f32_f16_e32 v68, v77
	v_cvt_f32_f16_sdwa v69, v77 dst_sel:DWORD dst_unused:UNUSED_PAD src0_sel:WORD_1
	v_fma_f32 v42, v42, v54, v66
	v_fma_f32 v43, v43, v55, v67
	v_cvt_f32_f16_e32 v66, v70
	v_cvt_f32_f16_sdwa v67, v70 dst_sel:DWORD dst_unused:UNUSED_PAD src0_sel:WORD_1
	v_fma_f32 v44, v44, v56, v68
	v_fma_f32 v45, v45, v57, v69
	v_cvt_f32_f16_e32 v68, v71
	v_cvt_f32_f16_sdwa v69, v71 dst_sel:DWORD dst_unused:UNUSED_PAD src0_sel:WORD_1
	v_fma_f32 v38, v38, v58, v66
	v_fma_f32 v39, v39, v59, v67
	v_cvt_f32_f16_e32 v66, v72
	v_cvt_f32_f16_sdwa v67, v72 dst_sel:DWORD dst_unused:UNUSED_PAD src0_sel:WORD_1
	v_fma_f32 v40, v40, v60, v68
	v_fma_f32 v41, v41, v61, v69
	v_cvt_f32_f16_e32 v68, v73
	v_cvt_f32_f16_sdwa v69, v73 dst_sel:DWORD dst_unused:UNUSED_PAD src0_sel:WORD_1
	v_cvt_pk_f16_f32 v74, v46, v47
	v_mov_b32_e32 v70, v1
	v_cvt_pk_f16_f32 v75, v48, v49
	v_fma_f32 v34, v34, v62, v66
	v_fma_f32 v35, v35, v63, v67
	v_cvt_pk_f16_f32 v67, v38, v39
	v_mov_b32_e32 v66, v1
	v_mov_b32_dpp v70, v74 quad_perm:[1,0,3,2] row_mask:0xf bank_mask:0xf
	v_mov_b32_e32 v71, v1
	v_cvt_pk_f16_f32 v76, v42, v43
	v_fma_f32 v36, v36, v64, v68
	v_fma_f32 v37, v37, v65, v69
	v_cvt_pk_f16_f32 v68, v40, v41
	v_mov_b32_dpp v66, v67 quad_perm:[1,0,3,2] row_mask:0xf bank_mask:0xf
	v_cndmask_b32_e64 v70, v67, v70, s[0:1]
	v_mov_b32_e32 v67, v1
	v_mov_b32_dpp v71, v75 quad_perm:[1,0,3,2] row_mask:0xf bank_mask:0xf
	v_mov_b32_e32 v72, v1
	v_cvt_pk_f16_f32 v69, v34, v35
	v_mov_b32_dpp v67, v68 quad_perm:[1,0,3,2] row_mask:0xf bank_mask:0xf
	v_cndmask_b32_e64 v71, v68, v71, s[0:1]
	v_mov_b32_e32 v68, v1
	v_mov_b32_dpp v72, v76 quad_perm:[1,0,3,2] row_mask:0xf bank_mask:0xf
	v_cvt_pk_f16_f32 v73, v36, v37
	v_mov_b32_dpp v68, v69 quad_perm:[1,0,3,2] row_mask:0xf bank_mask:0xf
	v_cndmask_b32_e64 v72, v69, v72, s[0:1]
	v_mov_b32_e32 v69, v1
	v_cvt_pk_f16_f32 v77, v44, v45
	v_cndmask_b32_e64 v66, v66, v74, s[0:1]
	v_mov_b32_dpp v69, v73 quad_perm:[1,0,3,2] row_mask:0xf bank_mask:0xf
	v_mov_b32_e32 v74, v1
	v_cndmask_b32_e64 v67, v67, v75, s[0:1]
	v_cndmask_b32_e64 v68, v68, v76, s[0:1]
	v_mov_b32_dpp v74, v77 quad_perm:[1,0,3,2] row_mask:0xf bank_mask:0xf
	v_cndmask_b32_e64 v69, v69, v77, s[0:1]
	v_cndmask_b32_e64 v73, v73, v74, s[0:1]
	global_store_dwordx4 v78, v[66:69], s[38:39] sc1
	s_nop 1
	v_add_u32_e32 v66, 0x16fd0800, v0
	global_store_dwordx4 v66, v[70:73], s[38:39] sc1
	s_cbranch_vccnz .LBB0_489
	v_mul_f32_e32 v66, v32, v36
	v_mul_f32_e32 v67, v33, v37
	v_mul_f32_e32 v68, v30, v34
	v_mul_f32_e32 v69, v31, v35
	v_cvt_pk_f16_f32 v73, v66, v67
	v_cvt_pk_f16_f32 v72, v68, v69
	v_mul_f32_e32 v66, v28, v40
	v_mul_f32_e32 v67, v29, v41
	v_mul_f32_e32 v68, v26, v38
	v_mul_f32_e32 v69, v27, v39
	v_cvt_pk_f16_f32 v71, v66, v67
	v_cvt_pk_f16_f32 v70, v68, v69
	v_mul_f32_e32 v66, v24, v44
	v_mul_f32_e32 v67, v25, v45
	v_mul_f32_e32 v68, v22, v42
	v_mul_f32_e32 v69, v23, v43
	v_cvt_pk_f16_f32 v74, v66, v67
	v_cvt_pk_f16_f32 v75, v68, v69
	v_mul_f32_e32 v66, v20, v48
	v_mul_f32_e32 v67, v21, v49
	v_mul_f32_e32 v68, v18, v46
	v_mul_f32_e32 v69, v19, v47
	v_cvt_pk_f16_f32 v67, v66, v67
	v_cvt_pk_f16_f32 v66, v68, v69
	v_mov_b32_e32 v69, v1
	v_mov_b32_e32 v68, v1
	v_add_u32_e32 v76, 0x3dd0000, v0
	v_mov_b32_dpp v69, v66 quad_perm:[1,0,3,2] row_mask:0xf bank_mask:0xf
	v_mov_b32_dpp v68, v70 quad_perm:[1,0,3,2] row_mask:0xf bank_mask:0xf
	v_cndmask_b32_e64 v70, v70, v69, s[0:1]
	v_mov_b32_e32 v69, v1
	v_cndmask_b32_e64 v66, v68, v66, s[0:1]
	v_mov_b32_e32 v68, v1
	v_mov_b32_dpp v69, v67 quad_perm:[1,0,3,2] row_mask:0xf bank_mask:0xf
	s_nop 0
	v_mov_b32_dpp v68, v71 quad_perm:[1,0,3,2] row_mask:0xf bank_mask:0xf
	v_cndmask_b32_e64 v71, v71, v69, s[0:1]
	v_mov_b32_e32 v69, v1
	v_cndmask_b32_e64 v67, v68, v67, s[0:1]
	v_mov_b32_e32 v68, v1
	v_mov_b32_dpp v69, v75 quad_perm:[1,0,3,2] row_mask:0xf bank_mask:0xf
	s_nop 0
	v_mov_b32_dpp v68, v72 quad_perm:[1,0,3,2] row_mask:0xf bank_mask:0xf
	v_cndmask_b32_e64 v72, v72, v69, s[0:1]
	v_mov_b32_e32 v69, v1
	v_cndmask_b32_e64 v68, v68, v75, s[0:1]
	v_mov_b32_e32 v75, v1
	v_mov_b32_dpp v69, v73 quad_perm:[1,0,3,2] row_mask:0xf bank_mask:0xf
	v_cndmask_b32_e64 v69, v69, v74, s[0:1]
	v_mov_b32_dpp v75, v74 quad_perm:[1,0,3,2] row_mask:0xf bank_mask:0xf
	v_cndmask_b32_e64 v73, v73, v75, s[0:1]
	global_store_dwordx4 v76, v[66:69], s[38:39] sc1
	s_nop 1
	v_add_u32_e32 v66, 0x3dd0800, v0
	global_store_dwordx4 v66, v[70:73], s[38:39] sc1

; #define GAS __attribute__((address_space(1)))
; __device__ __forceinline__ unsigned cvtpk_h(float lo, float hi) { f32x2 v = {lo, hi}; h16x2 b = __builtin_convertvector(v, h16x2); return __builtin_bit_cast(unsigned, b); }
;     __device__ __forceinline__ void operator()(const f32x4 (&acc)[2][2][4][2], const pg8::Unit& u, int wr, int wc, int fr, int fq) const {
;     ...
;             for (int m = 0; m < 4; ++m) { if (half && ai == 1) continue; const unsigned rr = (unsigned)(ai * 128 + m * 16); const unsigned o = eoA + rr * (D * 2u); float ss = 0.f;
;                 const u32x4 la = *(const GAS u32x4*)((const GAS char*)ws + (unsigned)WS_X16 + o), lb = *(const GAS u32x4*)((const GAS char*)ws + (unsigned)WS_X16 + o + D * 2u);
;                 u32x4 xr[2];
; #pragma unroll
;                 for (int c = 0; c < 4; ++c) { const unsigned pa = (unsigned)__builtin_amdgcn_update_dpp(0, (int)la[c], 0xB1, 0xF, 0xF, false), pb = (unsigned)__builtin_amdgcn_update_dpp(0, (int)lb[c], 0xB1, 0xF, 0xF, false);
;                     xr[0][c] = odd ? pb : la[c]; xr[1][c] = odd ? lb[c] : pa; }
;                 u32x4 w[2], v[2];
; #pragma unroll
;                 for (int bj = 0; bj < 2; ++bj) { const h16x8 xb = __builtin_bit_cast(h16x8, xr[bj]);
;                     const f32x4 x0 = (f32x4){(float)xb[0], (float)xb[1], (float)xb[2], (float)xb[3]} + g4[bj][0] * acc[ai][bj][m][0], x1 = (f32x4){(float)xb[4], (float)xb[5], (float)xb[6], (float)xb[7]} + g4[bj][1] * acc[ai][bj][m][1];
;                     ss += ((x0[0] * x0[0] + x0[1] * x0[1]) + (x0[2] * x0[2] + x0[3] * x0[3])) + ((x1[0] * x1[0] + x1[1] * x1[1]) + (x1[2] * x1[2] + x1[3] * x1[3]));
;                     w[bj].x = cvtpk_h(x0[0], x0[1]); w[bj].y = cvtpk_h(x0[2], x0[3]); w[bj].z = cvtpk_h(x1[0], x1[1]); w[bj].w = cvtpk_h(x1[2], x1[3]);
;                     const f32x4 y0 = x0 * a4[bj][0], y1 = x1 * a4[bj][1]; v[bj].x = cvtpk_h(y0[0], y0[1]); v[bj].y = cvtpk_h(y0[2], y0[3]); v[bj].z = cvtpk_h(y1[0], y1[1]); v[bj].w = cvtpk_h(y1[2], y1[3]); }
;                 stg_line_pair(ws, (unsigned)WS_X16 + o, D * 2u, w[0], w[1], odd);
;                 if (an_off) stg_line_pair(ws, (unsigned)WS_XS + o, D * 2u, v[0], v[1], odd);
.Lo_wd_7:
	v_mov_b32_e32 v34, v214
	v_mov_b32_e32 v35, v215
	v_mov_b32_e32 v36, v216
	v_mov_b32_e32 v37, v217
	v_mov_b32_e32 v38, v218
	v_mov_b32_e32 v39, v219
	v_mov_b32_e32 v40, v220
	v_mov_b32_e32 v41, v221
	v_mov_b32_e32 v42, v1
	v_mov_b32_e32 v43, v1
	v_add_u32_e32 v46, 0x16fd8000, v0
	s_and_b64 vcc, exec, s[2:3]
	v_mov_b32_dpp v42, v34 quad_perm:[1,0,3,2] row_mask:0xf bank_mask:0xf
	v_mov_b32_dpp v43, v38 quad_perm:[1,0,3,2] row_mask:0xf bank_mask:0xf
	v_cndmask_b32_e64 v43, v43, v34, s[0:1]
	v_cndmask_b32_e64 v38, v38, v42, s[0:1]
	v_mov_b32_e32 v34, v1
	v_mov_b32_e32 v42, v1
	s_nop 0
	v_mov_b32_dpp v34, v35 quad_perm:[1,0,3,2] row_mask:0xf bank_mask:0xf
	v_mov_b32_dpp v42, v39 quad_perm:[1,0,3,2] row_mask:0xf bank_mask:0xf
	v_cndmask_b32_e64 v42, v42, v35, s[0:1]
	v_cndmask_b32_e64 v39, v39, v34, s[0:1]
	v_mov_b32_e32 v34, v1
	v_mov_b32_e32 v35, v1
	s_nop 0
	v_mov_b32_dpp v34, v36 quad_perm:[1,0,3,2] row_mask:0xf bank_mask:0xf
	v_mov_b32_dpp v35, v40 quad_perm:[1,0,3,2] row_mask:0xf bank_mask:0xf
	v_cndmask_b32_e64 v44, v35, v36, s[0:1]
	v_cndmask_b32_e64 v40, v40, v34, s[0:1]
	v_mov_b32_e32 v34, v1
	v_mov_b32_e32 v35, v1
	v_cvt_f32_f16_e32 v36, v42
	v_mov_b32_dpp v34, v37 quad_perm:[1,0,3,2] row_mask:0xf bank_mask:0xf
	v_mov_b32_dpp v35, v41 quad_perm:[1,0,3,2] row_mask:0xf bank_mask:0xf
	v_cndmask_b32_e64 v45, v35, v37, s[0:1]
	v_cndmask_b32_e64 v41, v41, v34, s[0:1]
	v_cvt_f32_f16_e32 v34, v43
	v_cvt_f32_f16_sdwa v35, v43 dst_sel:DWORD dst_unused:UNUSED_PAD src0_sel:WORD_1
	v_cvt_f32_f16_sdwa v37, v42 dst_sel:DWORD dst_unused:UNUSED_PAD src0_sel:WORD_1
	v_fma_f32 v14, v14, v50, v34
	v_fma_f32 v15, v15, v51, v35
	v_cvt_f32_f16_e32 v34, v44
	v_cvt_f32_f16_sdwa v35, v44 dst_sel:DWORD dst_unused:UNUSED_PAD src0_sel:WORD_1
	v_fma_f32 v16, v16, v52, v36
	v_fma_f32 v17, v17, v53, v37
	v_cvt_f32_f16_e32 v36, v45
	v_cvt_f32_f16_sdwa v37, v45 dst_sel:DWORD dst_unused:UNUSED_PAD src0_sel:WORD_1
	v_fma_f32 v10, v10, v54, v34
	v_fma_f32 v11, v11, v55, v35
	v_cvt_f32_f16_e32 v34, v38
	v_cvt_f32_f16_sdwa v35, v38 dst_sel:DWORD dst_unused:UNUSED_PAD src0_sel:WORD_1
	v_fma_f32 v12, v12, v56, v36
	v_fma_f32 v13, v13, v57, v37
	v_cvt_f32_f16_e32 v36, v39
	v_cvt_f32_f16_sdwa v37, v39 dst_sel:DWORD dst_unused:UNUSED_PAD src0_sel:WORD_1
	v_fma_f32 v6, v6, v58, v34
	v_fma_f32 v7, v7, v59, v35
	v_cvt_f32_f16_e32 v34, v40
	v_cvt_f32_f16_sdwa v35, v40 dst_sel:DWORD dst_unused:UNUSED_PAD src0_sel:WORD_1
	v_fma_f32 v8, v8, v60, v36
	v_fma_f32 v9, v9, v61, v37
	v_cvt_f32_f16_e32 v36, v41
	v_cvt_f32_f16_sdwa v37, v41 dst_sel:DWORD dst_unused:UNUSED_PAD src0_sel:WORD_1
	v_cvt_pk_f16_f32 v42, v14, v15
	v_mov_b32_e32 v38, v1
	v_cvt_pk_f16_f32 v43, v16, v17
	v_fma_f32 v2, v2, v62, v34
	v_fma_f32 v3, v3, v63, v35
	v_cvt_pk_f16_f32 v35, v6, v7
	v_mov_b32_e32 v34, v1
	v_mov_b32_dpp v38, v42 quad_perm:[1,0,3,2] row_mask:0xf bank_mask:0xf
	v_mov_b32_e32 v39, v1
	v_cvt_pk_f16_f32 v44, v10, v11
	v_fma_f32 v4, v4, v64, v36
	v_fma_f32 v5, v5, v65, v37
	v_cvt_pk_f16_f32 v36, v8, v9
	v_mov_b32_dpp v34, v35 quad_perm:[1,0,3,2] row_mask:0xf bank_mask:0xf
	v_cndmask_b32_e64 v38, v35, v38, s[0:1]
	v_mov_b32_e32 v35, v1
	v_mov_b32_dpp v39, v43 quad_perm:[1,0,3,2] row_mask:0xf bank_mask:0xf
	v_mov_b32_e32 v40, v1
	v_cvt_pk_f16_f32 v37, v2, v3
	v_mov_b32_dpp v35, v36 quad_perm:[1,0,3,2] row_mask:0xf bank_mask:0xf
	v_cndmask_b32_e64 v39, v36, v39, s[0:1]
	v_mov_b32_e32 v36, v1
	v_mov_b32_dpp v40, v44 quad_perm:[1,0,3,2] row_mask:0xf bank_mask:0xf
	v_cvt_pk_f16_f32 v41, v4, v5
	v_mov_b32_dpp v36, v37 quad_perm:[1,0,3,2] row_mask:0xf bank_mask:0xf
	v_cndmask_b32_e64 v40, v37, v40, s[0:1]
	v_mov_b32_e32 v37, v1
	v_cvt_pk_f16_f32 v45, v12, v13
	v_cndmask_b32_e64 v34, v34, v42, s[0:1]
	v_mov_b32_dpp v37, v41 quad_perm:[1,0,3,2] row_mask:0xf bank_mask:0xf
	v_mov_b32_e32 v42, v1
	v_cndmask_b32_e64 v35, v35, v43, s[0:1]
	v_cndmask_b32_e64 v36, v36, v44, s[0:1]
	v_mov_b32_dpp v42, v45 quad_perm:[1,0,3,2] row_mask:0xf bank_mask:0xf
	v_cndmask_b32_e64 v37, v37, v45, s[0:1]
	v_cndmask_b32_e64 v41, v41, v42, s[0:1]
	global_store_dwordx4 v46, v[34:37], s[38:39] sc1
	s_nop 1
	v_add_u32_e32 v34, 0x16fd8800, v0
	global_store_dwordx4 v34, v[38:41], s[38:39] sc1
	s_cbranch_vccnz .LBB0_493
	v_mul_f32_e32 v26, v26, v6
	v_mul_f32_e32 v27, v27, v7
	v_mul_f32_e32 v20, v20, v16
	v_mul_f32_e32 v21, v21, v17
	v_mul_f32_e32 v18, v18, v14
	v_mul_f32_e32 v19, v19, v15
	v_cvt_pk_f16_f32 v26, v26, v27
	v_cvt_pk_f16_f32 v20, v20, v21
	v_cvt_pk_f16_f32 v18, v18, v19
	v_mov_b32_e32 v19, v1
	v_mov_b32_e32 v21, v1
	v_mul_f32_e32 v28, v28, v8
	v_mul_f32_e32 v29, v29, v9
	v_mul_f32_e32 v24, v24, v12
	v_mul_f32_e32 v25, v25, v13
	v_mul_f32_e32 v22, v22, v10
	v_mul_f32_e32 v23, v23, v11
	v_mov_b32_dpp v19, v26 quad_perm:[1,0,3,2] row_mask:0xf bank_mask:0xf
	v_mov_b32_dpp v21, v18 quad_perm:[1,0,3,2] row_mask:0xf bank_mask:0xf
	v_cvt_pk_f16_f32 v28, v28, v29
	v_cvt_pk_f16_f32 v25, v24, v25
	v_cvt_pk_f16_f32 v24, v22, v23
	v_cndmask_b32_e64 v18, v19, v18, s[0:1]
	v_cndmask_b32_e64 v22, v26, v21, s[0:1]
	v_mov_b32_e32 v19, v1
	v_mov_b32_e32 v21, v1
	v_mul_f32_e32 v30, v30, v2
	v_mul_f32_e32 v31, v31, v3
	v_mov_b32_dpp v19, v28 quad_perm:[1,0,3,2] row_mask:0xf bank_mask:0xf
	v_mov_b32_dpp v21, v20 quad_perm:[1,0,3,2] row_mask:0xf bank_mask:0xf
	v_cvt_pk_f16_f32 v30, v30, v31
	v_cndmask_b32_e64 v19, v19, v20, s[0:1]
	v_cndmask_b32_e64 v23, v28, v21, s[0:1]
	v_mov_b32_e32 v20, v1
	v_mov_b32_e32 v21, v1
	v_mul_f32_e32 v32, v32, v4
	v_mul_f32_e32 v33, v33, v5
	v_mov_b32_dpp v20, v30 quad_perm:[1,0,3,2] row_mask:0xf bank_mask:0xf
	v_mov_b32_dpp v21, v24 quad_perm:[1,0,3,2] row_mask:0xf bank_mask:0xf
	v_cvt_pk_f16_f32 v32, v32, v33
	v_cndmask_b32_e64 v20, v20, v24, s[0:1]
	v_cndmask_b32_e64 v24, v30, v21, s[0:1]
	v_mov_b32_e32 v21, v1
	v_mov_b32_e32 v26, v1
	v_add_u32_e32 v27, 0x3dd8000, v0
	v_mov_b32_dpp v21, v32 quad_perm:[1,0,3,2] row_mask:0xf bank_mask:0xf
	v_mov_b32_dpp v26, v25 quad_perm:[1,0,3,2] row_mask:0xf bank_mask:0xf
	v_cndmask_b32_e64 v21, v21, v25, s[0:1]
	v_cndmask_b32_e64 v25, v32, v26, s[0:1]
	v_add_u32_e32 v0, 0x3dd8800, v0
	global_store_dwordx4 v27, v[18:21], s[38:39] sc1
	global_store_dwordx4 v0, v[22:25], s[38:39] sc1

; #define GAS __attribute__((address_space(1)))
; __device__ __forceinline__ unsigned cvtpk_h(float lo, float hi) { f32x2 v = {lo, hi}; h16x2 b = __builtin_convertvector(v, h16x2); return __builtin_bit_cast(unsigned, b); }
;     __device__ __forceinline__ void operator()(const f32x4 (&acc)[2][2][4][2], const pg8::Unit& u, int wr, int wc, int fr, int fq) const {
;     ...
;             for (int m = 0; m < 4; ++m) { if (half && ai == 1) continue; const unsigned rr = (unsigned)(ai * 128 + m * 16); const unsigned o = eoA + rr * (D * 2u); float ss = 0.f;
;                 const u32x4 la = *(const GAS u32x4*)((const GAS char*)ws + (unsigned)WS_X16 + o), lb = *(const GAS u32x4*)((const GAS char*)ws + (unsigned)WS_X16 + o + D * 2u);
;                 u32x4 xr[2];
; #pragma unroll
;                 for (int c = 0; c < 4; ++c) { const unsigned pa = (unsigned)__builtin_amdgcn_update_dpp(0, (int)la[c], 0xB1, 0xF, 0xF, false), pb = (unsigned)__builtin_amdgcn_update_dpp(0, (int)lb[c], 0xB1, 0xF, 0xF, false);
;                     xr[0][c] = odd ? pb : la[c]; xr[1][c] = odd ? lb[c] : pa; }
;                 u32x4 w[2], v[2];
; #pragma unroll
;                 for (int bj = 0; bj < 2; ++bj) { const h16x8 xb = __builtin_bit_cast(h16x8, xr[bj]);
;                     const f32x4 x0 = (f32x4){(float)xb[0], (float)xb[1], (float)xb[2], (float)xb[3]} + g4[bj][0] * acc[ai][bj][m][0], x1 = (f32x4){(float)xb[4], (float)xb[5], (float)xb[6], (float)xb[7]} + g4[bj][1] * acc[ai][bj][m][1];
;                     ss += ((x0[0] * x0[0] + x0[1] * x0[1]) + (x0[2] * x0[2] + x0[3] * x0[3])) + ((x1[0] * x1[0] + x1[1] * x1[1]) + (x1[2] * x1[2] + x1[3] * x1[3]));
;                     w[bj].x = cvtpk_h(x0[0], x0[1]); w[bj].y = cvtpk_h(x0[2], x0[3]); w[bj].z = cvtpk_h(x1[0], x1[1]); w[bj].w = cvtpk_h(x1[2], x1[3]);
;                     const f32x4 y0 = x0 * a4[bj][0], y1 = x1 * a4[bj][1]; v[bj].x = cvtpk_h(y0[0], y0[1]); v[bj].y = cvtpk_h(y0[2], y0[3]); v[bj].z = cvtpk_h(y1[0], y1[1]); v[bj].w = cvtpk_h(y1[2], y1[3]); }
;                 stg_line_pair(ws, (unsigned)WS_X16 + o, D * 2u, w[0], w[1], odd);
;                 if (an_off) stg_line_pair(ws, (unsigned)WS_XS + o, D * 2u, v[0], v[1], odd);
.LBB0_515:
	s_lshl_b32 s8, s14, 7
	s_lshl_b32 s0, s0, 8
	s_add_i32 s10, s1, s8
	v_and_b32_e32 v0, 0x1ffffe, v131
	s_add_i32 s10, s10, s0
	v_add_u32_e32 v0, s10, v0
	v_lshl_add_u32 v0, v0, 10, s12
	v_and_b32_e32 v106, 1, v131
	v_or_b32_e32 v0, s11, v0
	v_lshlrev_b32_e32 v0, 1, v0
	v_lshlrev_b32_e32 v98, 6, v106
	v_lshlrev_b32_e32 v99, 4, v180
	s_add_u32 s8, s6, 0x16f80000
	v_add3_u32 v0, v98, v99, v0
	s_addc_u32 s9, s7, 0
	global_load_dwordx4 v[98:101], v0, s[8:9]
	global_load_dwordx4 v[102:105], v0, s[8:9] offset:2048
	v_mov_b32_e32 v107, v1
	v_mov_b32_e32 v108, v1
	v_mov_b32_e32 v109, v1
	v_mov_b32_e32 v111, v1
	v_mov_b32_e32 v113, v1
	v_mov_b32_e32 v114, v1
	v_mov_b32_e32 v110, v1
	v_mov_b32_e32 v112, v1
	v_cmp_eq_u32_e64 s[0:1], 0, v106
	v_mov_b32_e32 v115, v1
	v_mov_b32_e32 v117, v1
	v_mov_b32_e32 v119, v1
	v_mov_b32_e32 v121, v1
	v_mov_b32_e32 v116, v1
	v_mov_b32_e32 v118, v1
	v_mov_b32_e32 v120, v1
	v_mov_b32_e32 v122, v1
	v_add_u32_e32 v123, 0x16f80000, v0
	s_and_b64 vcc, exec, s[2:3]
	s_waitcnt vmcnt(0)
	v_mov_b32_dpp v107, v98 quad_perm:[1,0,3,2] row_mask:0xf bank_mask:0xf
	v_mov_b32_dpp v108, v102 quad_perm:[1,0,3,2] row_mask:0xf bank_mask:0xf
	v_mov_b32_dpp v109, v99 quad_perm:[1,0,3,2] row_mask:0xf bank_mask:0xf
	v_mov_b32_dpp v111, v100 quad_perm:[1,0,3,2] row_mask:0xf bank_mask:0xf
	v_mov_b32_dpp v113, v101 quad_perm:[1,0,3,2] row_mask:0xf bank_mask:0xf
	v_mov_b32_dpp v114, v105 quad_perm:[1,0,3,2] row_mask:0xf bank_mask:0xf
	v_mov_b32_dpp v110, v103 quad_perm:[1,0,3,2] row_mask:0xf bank_mask:0xf
	v_mov_b32_dpp v112, v104 quad_perm:[1,0,3,2] row_mask:0xf bank_mask:0xf
	v_cndmask_b32_e64 v106, v108, v98, s[0:1]
	v_cndmask_b32_e64 v107, v102, v107, s[0:1]
	v_cndmask_b32_e64 v109, v103, v109, s[0:1]
	v_cndmask_b32_e64 v111, v104, v111, s[0:1]
	v_cndmask_b32_e64 v108, v114, v101, s[0:1]
	v_cndmask_b32_e64 v113, v105, v113, s[0:1]
	v_cndmask_b32_e64 v102, v110, v99, s[0:1]
	v_cndmask_b32_e64 v103, v112, v100, s[0:1]
	v_cvt_f32_f16_e32 v98, v106
	v_cvt_f32_f16_sdwa v99, v106 dst_sel:DWORD dst_unused:UNUSED_PAD src0_sel:WORD_1
	v_cvt_f32_f16_e32 v104, v108
	v_cvt_f32_f16_sdwa v105, v108 dst_sel:DWORD dst_unused:UNUSED_PAD src0_sel:WORD_1
	v_cvt_f32_f16_e32 v106, v107
	v_cvt_f32_f16_sdwa v107, v107 dst_sel:DWORD dst_unused:UNUSED_PAD src0_sel:WORD_1
	v_cvt_f32_f16_e32 v108, v109
	v_cvt_f32_f16_sdwa v109, v109 dst_sel:DWORD dst_unused:UNUSED_PAD src0_sel:WORD_1
	v_cvt_f32_f16_e32 v110, v111
	v_cvt_f32_f16_sdwa v111, v111 dst_sel:DWORD dst_unused:UNUSED_PAD src0_sel:WORD_1
	v_cvt_f32_f16_e32 v112, v113
	v_cvt_f32_f16_sdwa v113, v113 dst_sel:DWORD dst_unused:UNUSED_PAD src0_sel:WORD_1
	v_cvt_f32_f16_e32 v100, v102
	v_cvt_f32_f16_sdwa v101, v102 dst_sel:DWORD dst_unused:UNUSED_PAD src0_sel:WORD_1
	v_cvt_f32_f16_e32 v102, v103
	v_cvt_f32_f16_sdwa v103, v103 dst_sel:DWORD dst_unused:UNUSED_PAD src0_sel:WORD_1
	v_fma_f32 v88, v88, v44, v108
	v_fma_f32 v89, v89, v45, v109
	v_fma_f32 v86, v86, v42, v106
	v_fma_f32 v87, v87, v43, v107
	v_fma_f32 v84, v84, v48, v112
	v_fma_f32 v85, v85, v49, v113
	v_fma_f32 v82, v82, v46, v110
	v_fma_f32 v83, v83, v47, v111
	v_fma_f32 v96, v96, v36, v100
	v_fma_f32 v97, v97, v37, v101
	v_fma_f32 v94, v94, v34, v98
	v_fma_f32 v95, v95, v35, v99
	v_fma_f32 v92, v92, v40, v104
	v_fma_f32 v93, v93, v41, v105
	v_fma_f32 v90, v90, v38, v102
	v_fma_f32 v91, v91, v39, v103
	v_cvt_pk_f16_f32 v102, v86, v87
	v_cvt_pk_f16_f32 v103, v88, v89
	v_cvt_pk_f16_f32 v104, v82, v83
	v_cvt_pk_f16_f32 v105, v84, v85
	v_cvt_pk_f16_f32 v98, v94, v95
	v_cvt_pk_f16_f32 v99, v96, v97
	v_cvt_pk_f16_f32 v100, v90, v91
	v_cvt_pk_f16_f32 v101, v92, v93
	v_mov_b32_dpp v115, v102 quad_perm:[1,0,3,2] row_mask:0xf bank_mask:0xf
	v_mov_b32_dpp v117, v103 quad_perm:[1,0,3,2] row_mask:0xf bank_mask:0xf
	v_mov_b32_dpp v119, v104 quad_perm:[1,0,3,2] row_mask:0xf bank_mask:0xf
	v_mov_b32_dpp v121, v105 quad_perm:[1,0,3,2] row_mask:0xf bank_mask:0xf
	v_mov_b32_dpp v116, v98 quad_perm:[1,0,3,2] row_mask:0xf bank_mask:0xf
	v_mov_b32_dpp v118, v99 quad_perm:[1,0,3,2] row_mask:0xf bank_mask:0xf
	v_mov_b32_dpp v120, v100 quad_perm:[1,0,3,2] row_mask:0xf bank_mask:0xf
	v_mov_b32_dpp v122, v101 quad_perm:[1,0,3,2] row_mask:0xf bank_mask:0xf
	v_cndmask_b32_e64 v98, v115, v98, s[0:1]
	v_cndmask_b32_e64 v99, v117, v99, s[0:1]
	v_cndmask_b32_e64 v100, v119, v100, s[0:1]
	v_cndmask_b32_e64 v101, v121, v101, s[0:1]
	v_cndmask_b32_e64 v102, v102, v116, s[0:1]
	v_cndmask_b32_e64 v103, v103, v118, s[0:1]
	v_cndmask_b32_e64 v104, v104, v120, s[0:1]
	v_cndmask_b32_e64 v105, v105, v122, s[0:1]
	global_store_dwordx4 v123, v[98:101], s[6:7] sc1
	s_nop 1
	v_add_u32_e32 v98, 0x16f80800, v0
	global_store_dwordx4 v98, v[102:105], s[6:7] sc1
	s_cbranch_vccnz .LBB0_517
	v_mul_f32_e32 v98, v16, v84
	v_mul_f32_e32 v99, v17, v85
	v_mul_f32_e32 v100, v14, v82
	v_mul_f32_e32 v101, v15, v83
	v_cvt_pk_f16_f32 v105, v98, v99
	v_cvt_pk_f16_f32 v104, v100, v101
	v_mul_f32_e32 v98, v12, v88
	v_mul_f32_e32 v99, v13, v89
	v_mul_f32_e32 v100, v10, v86
	v_mul_f32_e32 v101, v11, v87
	v_cvt_pk_f16_f32 v103, v98, v99
	v_cvt_pk_f16_f32 v102, v100, v101
	v_mul_f32_e32 v98, v8, v92
	v_mul_f32_e32 v99, v9, v93
	v_mul_f32_e32 v100, v6, v90
	v_mul_f32_e32 v101, v7, v91
	v_cvt_pk_f16_f32 v106, v98, v99
	v_cvt_pk_f16_f32 v107, v100, v101
	v_mul_f32_e32 v98, v4, v96
	v_mul_f32_e32 v99, v5, v97
	v_mul_f32_e32 v100, v2, v94
	v_mul_f32_e32 v101, v3, v95
	v_cvt_pk_f16_f32 v99, v98, v99
	v_cvt_pk_f16_f32 v98, v100, v101
	v_mov_b32_e32 v101, v1
	v_mov_b32_e32 v100, v1
	v_add_u32_e32 v108, 0x3d80000, v0
	v_mov_b32_dpp v101, v98 quad_perm:[1,0,3,2] row_mask:0xf bank_mask:0xf
	v_mov_b32_dpp v100, v102 quad_perm:[1,0,3,2] row_mask:0xf bank_mask:0xf
	v_cndmask_b32_e64 v102, v102, v101, s[0:1]
	v_mov_b32_e32 v101, v1
	v_cndmask_b32_e64 v98, v100, v98, s[0:1]
	v_mov_b32_e32 v100, v1
	v_mov_b32_dpp v101, v99 quad_perm:[1,0,3,2] row_mask:0xf bank_mask:0xf
	s_nop 0
	v_mov_b32_dpp v100, v103 quad_perm:[1,0,3,2] row_mask:0xf bank_mask:0xf
	v_cndmask_b32_e64 v103, v103, v101, s[0:1]
	v_mov_b32_e32 v101, v1
	v_cndmask_b32_e64 v99, v100, v99, s[0:1]
	v_mov_b32_e32 v100, v1
	v_mov_b32_dpp v101, v107 quad_perm:[1,0,3,2] row_mask:0xf bank_mask:0xf
	s_nop 0
	v_mov_b32_dpp v100, v104 quad_perm:[1,0,3,2] row_mask:0xf bank_mask:0xf
	v_cndmask_b32_e64 v104, v104, v101, s[0:1]
	v_mov_b32_e32 v101, v1
	v_cndmask_b32_e64 v100, v100, v107, s[0:1]
	v_mov_b32_e32 v107, v1
	v_mov_b32_dpp v101, v105 quad_perm:[1,0,3,2] row_mask:0xf bank_mask:0xf
	v_cndmask_b32_e64 v101, v101, v106, s[0:1]
	v_mov_b32_dpp v107, v106 quad_perm:[1,0,3,2] row_mask:0xf bank_mask:0xf
	v_cndmask_b32_e64 v105, v105, v107, s[0:1]
	global_store_dwordx4 v108, v[98:101], s[6:7] sc1
	s_nop 1
	v_add_u32_e32 v98, 0x3d80800, v0
	global_store_dwordx4 v98, v[102:105], s[6:7] sc1

; #define GAS __attribute__((address_space(1)))
; __device__ __forceinline__ unsigned cvtpk_h(float lo, float hi) { f32x2 v = {lo, hi}; h16x2 b = __builtin_convertvector(v, h16x2); return __builtin_bit_cast(unsigned, b); }
;     __device__ __forceinline__ void operator()(const f32x4 (&acc)[2][2][4][2], const pg8::Unit& u, int wr, int wc, int fr, int fq) const {
;     ...
;             for (int m = 0; m < 4; ++m) { if (half && ai == 1) continue; const unsigned rr = (unsigned)(ai * 128 + m * 16); const unsigned o = eoA + rr * (D * 2u); float ss = 0.f;
;                 const u32x4 la = *(const GAS u32x4*)((const GAS char*)ws + (unsigned)WS_X16 + o), lb = *(const GAS u32x4*)((const GAS char*)ws + (unsigned)WS_X16 + o + D * 2u);
;                 u32x4 xr[2];
; #pragma unroll
;                 for (int c = 0; c < 4; ++c) { const unsigned pa = (unsigned)__builtin_amdgcn_update_dpp(0, (int)la[c], 0xB1, 0xF, 0xF, false), pb = (unsigned)__builtin_amdgcn_update_dpp(0, (int)lb[c], 0xB1, 0xF, 0xF, false);
;                     xr[0][c] = odd ? pb : la[c]; xr[1][c] = odd ? lb[c] : pa; }
;                 u32x4 w[2], v[2];
; #pragma unroll
;                 for (int bj = 0; bj < 2; ++bj) { const h16x8 xb = __builtin_bit_cast(h16x8, xr[bj]);
;                     const f32x4 x0 = (f32x4){(float)xb[0], (float)xb[1], (float)xb[2], (float)xb[3]} + g4[bj][0] * acc[ai][bj][m][0], x1 = (f32x4){(float)xb[4], (float)xb[5], (float)xb[6], (float)xb[7]} + g4[bj][1] * acc[ai][bj][m][1];
;                     ss += ((x0[0] * x0[0] + x0[1] * x0[1]) + (x0[2] * x0[2] + x0[3] * x0[3])) + ((x1[0] * x1[0] + x1[1] * x1[1]) + (x1[2] * x1[2] + x1[3] * x1[3]));
;                     w[bj].x = cvtpk_h(x0[0], x0[1]); w[bj].y = cvtpk_h(x0[2], x0[3]); w[bj].z = cvtpk_h(x1[0], x1[1]); w[bj].w = cvtpk_h(x1[2], x1[3]);
;                     const f32x4 y0 = x0 * a4[bj][0], y1 = x1 * a4[bj][1]; v[bj].x = cvtpk_h(y0[0], y0[1]); v[bj].y = cvtpk_h(y0[2], y0[3]); v[bj].z = cvtpk_h(y1[0], y1[1]); v[bj].w = cvtpk_h(y1[2], y1[3]); }
;                 stg_line_pair(ws, (unsigned)WS_X16 + o, D * 2u, w[0], w[1], odd);
;                 if (an_off) stg_line_pair(ws, (unsigned)WS_XS + o, D * 2u, v[0], v[1], odd);
.LBB0_519:
	s_or_b64 exec, exec, s[10:11]
	v_add_u32_e32 v86, 0x8000, v0
	global_load_dwordx4 v[82:85], v86, s[8:9]
	s_nop 0
	global_load_dwordx4 v[86:89], v86, s[8:9] offset:2048
	v_mov_b32_e32 v90, v1
	v_mov_b32_e32 v91, v1
	v_add_u32_e32 v94, 0x16f88000, v0
	s_and_b64 vcc, exec, s[2:3]
	s_waitcnt vmcnt(0)
	v_mov_b32_dpp v90, v82 quad_perm:[1,0,3,2] row_mask:0xf bank_mask:0xf
	v_mov_b32_dpp v91, v86 quad_perm:[1,0,3,2] row_mask:0xf bank_mask:0xf
	v_cndmask_b32_e64 v91, v91, v82, s[0:1]
	v_cndmask_b32_e64 v86, v86, v90, s[0:1]
	v_mov_b32_e32 v82, v1
	v_mov_b32_e32 v90, v1
	s_nop 0
	v_mov_b32_dpp v82, v83 quad_perm:[1,0,3,2] row_mask:0xf bank_mask:0xf
	v_mov_b32_dpp v90, v87 quad_perm:[1,0,3,2] row_mask:0xf bank_mask:0xf
	v_cndmask_b32_e64 v90, v90, v83, s[0:1]
	v_cndmask_b32_e64 v87, v87, v82, s[0:1]
	v_mov_b32_e32 v82, v1
	v_mov_b32_e32 v83, v1
	s_nop 0
	v_mov_b32_dpp v82, v84 quad_perm:[1,0,3,2] row_mask:0xf bank_mask:0xf
	v_mov_b32_dpp v83, v88 quad_perm:[1,0,3,2] row_mask:0xf bank_mask:0xf
	v_cndmask_b32_e64 v92, v83, v84, s[0:1]
	v_cndmask_b32_e64 v88, v88, v82, s[0:1]
	v_mov_b32_e32 v82, v1
	v_mov_b32_e32 v83, v1
	v_cvt_f32_f16_e32 v84, v90
	v_mov_b32_dpp v82, v85 quad_perm:[1,0,3,2] row_mask:0xf bank_mask:0xf
	v_mov_b32_dpp v83, v89 quad_perm:[1,0,3,2] row_mask:0xf bank_mask:0xf
	v_cndmask_b32_e64 v93, v83, v85, s[0:1]
	v_cndmask_b32_e64 v89, v89, v82, s[0:1]
	v_cvt_f32_f16_e32 v82, v91
	v_cvt_f32_f16_sdwa v83, v91 dst_sel:DWORD dst_unused:UNUSED_PAD src0_sel:WORD_1
	v_cvt_f32_f16_sdwa v85, v90 dst_sel:DWORD dst_unused:UNUSED_PAD src0_sel:WORD_1
	v_fma_f32 v78, v78, v34, v82
	v_fma_f32 v79, v79, v35, v83
	v_cvt_f32_f16_e32 v82, v92
	v_cvt_f32_f16_sdwa v83, v92 dst_sel:DWORD dst_unused:UNUSED_PAD src0_sel:WORD_1
	v_fma_f32 v80, v80, v36, v84
	v_fma_f32 v81, v81, v37, v85
	v_cvt_f32_f16_e32 v84, v93
	v_cvt_f32_f16_sdwa v85, v93 dst_sel:DWORD dst_unused:UNUSED_PAD src0_sel:WORD_1
	v_fma_f32 v74, v74, v38, v82
	v_fma_f32 v75, v75, v39, v83
	v_cvt_f32_f16_e32 v82, v86
	v_cvt_f32_f16_sdwa v83, v86 dst_sel:DWORD dst_unused:UNUSED_PAD src0_sel:WORD_1
	v_fma_f32 v76, v76, v40, v84
	v_fma_f32 v77, v77, v41, v85
	v_cvt_f32_f16_e32 v84, v87
	v_cvt_f32_f16_sdwa v85, v87 dst_sel:DWORD dst_unused:UNUSED_PAD src0_sel:WORD_1
	v_fma_f32 v70, v70, v42, v82
	v_fma_f32 v71, v71, v43, v83
	v_cvt_f32_f16_e32 v82, v88
	v_cvt_f32_f16_sdwa v83, v88 dst_sel:DWORD dst_unused:UNUSED_PAD src0_sel:WORD_1
	v_fma_f32 v72, v72, v44, v84
	v_fma_f32 v73, v73, v45, v85
	v_cvt_f32_f16_e32 v84, v89
	v_cvt_f32_f16_sdwa v85, v89 dst_sel:DWORD dst_unused:UNUSED_PAD src0_sel:WORD_1
	v_cvt_pk_f16_f32 v90, v78, v79
	v_mov_b32_e32 v86, v1
	v_cvt_pk_f16_f32 v91, v80, v81
	v_fma_f32 v66, v66, v46, v82
	v_fma_f32 v67, v67, v47, v83
	v_cvt_pk_f16_f32 v83, v70, v71
	v_mov_b32_e32 v82, v1
	v_mov_b32_dpp v86, v90 quad_perm:[1,0,3,2] row_mask:0xf bank_mask:0xf
	v_mov_b32_e32 v87, v1
	v_cvt_pk_f16_f32 v92, v74, v75
	v_fma_f32 v68, v68, v48, v84
	v_fma_f32 v69, v69, v49, v85
	v_cvt_pk_f16_f32 v84, v72, v73
	v_mov_b32_dpp v82, v83 quad_perm:[1,0,3,2] row_mask:0xf bank_mask:0xf
	v_cndmask_b32_e64 v86, v83, v86, s[0:1]
	v_mov_b32_e32 v83, v1
	v_mov_b32_dpp v87, v91 quad_perm:[1,0,3,2] row_mask:0xf bank_mask:0xf
	v_mov_b32_e32 v88, v1
	v_cvt_pk_f16_f32 v85, v66, v67
	v_mov_b32_dpp v83, v84 quad_perm:[1,0,3,2] row_mask:0xf bank_mask:0xf
	v_cndmask_b32_e64 v87, v84, v87, s[0:1]
	v_mov_b32_e32 v84, v1
	v_mov_b32_dpp v88, v92 quad_perm:[1,0,3,2] row_mask:0xf bank_mask:0xf
	v_cvt_pk_f16_f32 v89, v68, v69
	v_mov_b32_dpp v84, v85 quad_perm:[1,0,3,2] row_mask:0xf bank_mask:0xf
	v_cndmask_b32_e64 v88, v85, v88, s[0:1]
	v_mov_b32_e32 v85, v1
	v_cvt_pk_f16_f32 v93, v76, v77
	v_cndmask_b32_e64 v82, v82, v90, s[0:1]
	v_mov_b32_dpp v85, v89 quad_perm:[1,0,3,2] row_mask:0xf bank_mask:0xf
	v_mov_b32_e32 v90, v1
	v_cndmask_b32_e64 v83, v83, v91, s[0:1]
	v_cndmask_b32_e64 v84, v84, v92, s[0:1]
	v_mov_b32_dpp v90, v93 quad_perm:[1,0,3,2] row_mask:0xf bank_mask:0xf
	v_cndmask_b32_e64 v85, v85, v93, s[0:1]
	v_cndmask_b32_e64 v89, v89, v90, s[0:1]
	global_store_dwordx4 v94, v[82:85], s[6:7] sc1
	s_nop 1
	v_add_u32_e32 v82, 0x16f88800, v0
	global_store_dwordx4 v82, v[86:89], s[6:7] sc1
	s_cbranch_vccnz .LBB0_521
	v_mul_f32_e32 v82, v16, v68
	v_mul_f32_e32 v83, v17, v69
	v_mul_f32_e32 v84, v14, v66
	v_mul_f32_e32 v85, v15, v67
	v_cvt_pk_f16_f32 v89, v82, v83
	v_cvt_pk_f16_f32 v88, v84, v85
	v_mul_f32_e32 v82, v12, v72
	v_mul_f32_e32 v83, v13, v73
	v_mul_f32_e32 v84, v10, v70
	v_mul_f32_e32 v85, v11, v71
	v_cvt_pk_f16_f32 v87, v82, v83
	v_cvt_pk_f16_f32 v86, v84, v85
	v_mul_f32_e32 v82, v8, v76
	v_mul_f32_e32 v83, v9, v77
	v_mul_f32_e32 v84, v6, v74
	v_mul_f32_e32 v85, v7, v75
	v_cvt_pk_f16_f32 v90, v82, v83
	v_cvt_pk_f16_f32 v91, v84, v85
	v_mul_f32_e32 v82, v4, v80
	v_mul_f32_e32 v83, v5, v81
	v_mul_f32_e32 v84, v2, v78
	v_mul_f32_e32 v85, v3, v79
	v_cvt_pk_f16_f32 v83, v82, v83
	v_cvt_pk_f16_f32 v82, v84, v85
	v_mov_b32_e32 v85, v1
	v_mov_b32_e32 v84, v1
	v_add_u32_e32 v92, 0x3d88000, v0
	v_mov_b32_dpp v85, v82 quad_perm:[1,0,3,2] row_mask:0xf bank_mask:0xf
	v_mov_b32_dpp v84, v86 quad_perm:[1,0,3,2] row_mask:0xf bank_mask:0xf
	v_cndmask_b32_e64 v86, v86, v85, s[0:1]
	v_mov_b32_e32 v85, v1
	v_cndmask_b32_e64 v82, v84, v82, s[0:1]
	v_mov_b32_e32 v84, v1
	v_mov_b32_dpp v85, v83 quad_perm:[1,0,3,2] row_mask:0xf bank_mask:0xf
	s_nop 0
	v_mov_b32_dpp v84, v87 quad_perm:[1,0,3,2] row_mask:0xf bank_mask:0xf
	v_cndmask_b32_e64 v87, v87, v85, s[0:1]
	v_mov_b32_e32 v85, v1
	v_cndmask_b32_e64 v83, v84, v83, s[0:1]
	v_mov_b32_e32 v84, v1
	v_mov_b32_dpp v85, v91 quad_perm:[1,0,3,2] row_mask:0xf bank_mask:0xf
	s_nop 0
	v_mov_b32_dpp v84, v88 quad_perm:[1,0,3,2] row_mask:0xf bank_mask:0xf
	v_cndmask_b32_e64 v88, v88, v85, s[0:1]
	v_mov_b32_e32 v85, v1
	v_cndmask_b32_e64 v84, v84, v91, s[0:1]
	v_mov_b32_e32 v91, v1
	v_mov_b32_dpp v85, v89 quad_perm:[1,0,3,2] row_mask:0xf bank_mask:0xf
	v_cndmask_b32_e64 v85, v85, v90, s[0:1]
	v_mov_b32_dpp v91, v90 quad_perm:[1,0,3,2] row_mask:0xf bank_mask:0xf
	v_cndmask_b32_e64 v89, v89, v91, s[0:1]
	global_store_dwordx4 v92, v[82:85], s[6:7] sc1
	s_nop 1
	v_add_u32_e32 v82, 0x3d88800, v0
	global_store_dwordx4 v82, v[86:89], s[6:7] sc1

; #define GAS __attribute__((address_space(1)))
; __device__ __forceinline__ unsigned cvtpk_h(float lo, float hi) { f32x2 v = {lo, hi}; h16x2 b = __builtin_convertvector(v, h16x2); return __builtin_bit_cast(unsigned, b); }
;     __device__ __forceinline__ void operator()(const f32x4 (&acc)[2][2][4][2], const pg8::Unit& u, int wr, int wc, int fr, int fq) const {
;     ...
;             for (int m = 0; m < 4; ++m) { if (half && ai == 1) continue; const unsigned rr = (unsigned)(ai * 128 + m * 16); const unsigned o = eoA + rr * (D * 2u); float ss = 0.f;
;                 const u32x4 la = *(const GAS u32x4*)((const GAS char*)ws + (unsigned)WS_X16 + o), lb = *(const GAS u32x4*)((const GAS char*)ws + (unsigned)WS_X16 + o + D * 2u);
;                 u32x4 xr[2];
; #pragma unroll
;                 for (int c = 0; c < 4; ++c) { const unsigned pa = (unsigned)__builtin_amdgcn_update_dpp(0, (int)la[c], 0xB1, 0xF, 0xF, false), pb = (unsigned)__builtin_amdgcn_update_dpp(0, (int)lb[c], 0xB1, 0xF, 0xF, false);
;                     xr[0][c] = odd ? pb : la[c]; xr[1][c] = odd ? lb[c] : pa; }
;                 u32x4 w[2], v[2];
; #pragma unroll
;                 for (int bj = 0; bj < 2; ++bj) { const h16x8 xb = __builtin_bit_cast(h16x8, xr[bj]);
;                     const f32x4 x0 = (f32x4){(float)xb[0], (float)xb[1], (float)xb[2], (float)xb[3]} + g4[bj][0] * acc[ai][bj][m][0], x1 = (f32x4){(float)xb[4], (float)xb[5], (float)xb[6], (float)xb[7]} + g4[bj][1] * acc[ai][bj][m][1];
;                     ss += ((x0[0] * x0[0] + x0[1] * x0[1]) + (x0[2] * x0[2] + x0[3] * x0[3])) + ((x1[0] * x1[0] + x1[1] * x1[1]) + (x1[2] * x1[2] + x1[3] * x1[3]));
;                     w[bj].x = cvtpk_h(x0[0], x0[1]); w[bj].y = cvtpk_h(x0[2], x0[3]); w[bj].z = cvtpk_h(x1[0], x1[1]); w[bj].w = cvtpk_h(x1[2], x1[3]);
;                     const f32x4 y0 = x0 * a4[bj][0], y1 = x1 * a4[bj][1]; v[bj].x = cvtpk_h(y0[0], y0[1]); v[bj].y = cvtpk_h(y0[2], y0[3]); v[bj].z = cvtpk_h(y1[0], y1[1]); v[bj].w = cvtpk_h(y1[2], y1[3]); }
;                 stg_line_pair(ws, (unsigned)WS_X16 + o, D * 2u, w[0], w[1], odd);
;                 if (an_off) stg_line_pair(ws, (unsigned)WS_XS + o, D * 2u, v[0], v[1], odd);
.LBB0_523:
	s_or_b64 exec, exec, s[10:11]
	v_add_u32_e32 v70, 0x10000, v0
	global_load_dwordx4 v[66:69], v70, s[8:9]
	s_nop 0
	global_load_dwordx4 v[70:73], v70, s[8:9] offset:2048
	v_mov_b32_e32 v74, v1
	v_mov_b32_e32 v75, v1
	v_add_u32_e32 v78, 0x16f90000, v0
	s_and_b64 vcc, exec, s[2:3]
	s_waitcnt vmcnt(0)
	v_mov_b32_dpp v74, v66 quad_perm:[1,0,3,2] row_mask:0xf bank_mask:0xf
	v_mov_b32_dpp v75, v70 quad_perm:[1,0,3,2] row_mask:0xf bank_mask:0xf
	v_cndmask_b32_e64 v75, v75, v66, s[0:1]
	v_cndmask_b32_e64 v70, v70, v74, s[0:1]
	v_mov_b32_e32 v66, v1
	v_mov_b32_e32 v74, v1
	s_nop 0
	v_mov_b32_dpp v66, v67 quad_perm:[1,0,3,2] row_mask:0xf bank_mask:0xf
	v_mov_b32_dpp v74, v71 quad_perm:[1,0,3,2] row_mask:0xf bank_mask:0xf
	v_cndmask_b32_e64 v74, v74, v67, s[0:1]
	v_cndmask_b32_e64 v71, v71, v66, s[0:1]
	v_mov_b32_e32 v66, v1
	v_mov_b32_e32 v67, v1
	s_nop 0
	v_mov_b32_dpp v66, v68 quad_perm:[1,0,3,2] row_mask:0xf bank_mask:0xf
	v_mov_b32_dpp v67, v72 quad_perm:[1,0,3,2] row_mask:0xf bank_mask:0xf
	v_cndmask_b32_e64 v76, v67, v68, s[0:1]
	v_cndmask_b32_e64 v72, v72, v66, s[0:1]
	v_mov_b32_e32 v66, v1
	v_mov_b32_e32 v67, v1
	v_cvt_f32_f16_e32 v68, v74
	v_mov_b32_dpp v66, v69 quad_perm:[1,0,3,2] row_mask:0xf bank_mask:0xf
	v_mov_b32_dpp v67, v73 quad_perm:[1,0,3,2] row_mask:0xf bank_mask:0xf
	v_cndmask_b32_e64 v77, v67, v69, s[0:1]
	v_cndmask_b32_e64 v73, v73, v66, s[0:1]
	v_cvt_f32_f16_e32 v66, v75
	v_cvt_f32_f16_sdwa v67, v75 dst_sel:DWORD dst_unused:UNUSED_PAD src0_sel:WORD_1
	v_cvt_f32_f16_sdwa v69, v74 dst_sel:DWORD dst_unused:UNUSED_PAD src0_sel:WORD_1
	v_fma_f32 v62, v62, v34, v66
	v_fma_f32 v63, v63, v35, v67
	v_cvt_f32_f16_e32 v66, v76
	v_cvt_f32_f16_sdwa v67, v76 dst_sel:DWORD dst_unused:UNUSED_PAD src0_sel:WORD_1
	v_fma_f32 v64, v64, v36, v68
	v_fma_f32 v65, v65, v37, v69
	v_cvt_f32_f16_e32 v68, v77
	v_cvt_f32_f16_sdwa v69, v77 dst_sel:DWORD dst_unused:UNUSED_PAD src0_sel:WORD_1
	v_fma_f32 v58, v58, v38, v66
	v_fma_f32 v59, v59, v39, v67
	v_cvt_f32_f16_e32 v66, v70
	v_cvt_f32_f16_sdwa v67, v70 dst_sel:DWORD dst_unused:UNUSED_PAD src0_sel:WORD_1
	v_fma_f32 v60, v60, v40, v68
	v_fma_f32 v61, v61, v41, v69
	v_cvt_f32_f16_e32 v68, v71
	v_cvt_f32_f16_sdwa v69, v71 dst_sel:DWORD dst_unused:UNUSED_PAD src0_sel:WORD_1
	v_fma_f32 v54, v54, v42, v66
	v_fma_f32 v55, v55, v43, v67
	v_cvt_f32_f16_e32 v66, v72
	v_cvt_f32_f16_sdwa v67, v72 dst_sel:DWORD dst_unused:UNUSED_PAD src0_sel:WORD_1
	v_fma_f32 v56, v56, v44, v68
	v_fma_f32 v57, v57, v45, v69
	v_cvt_f32_f16_e32 v68, v73
	v_cvt_f32_f16_sdwa v69, v73 dst_sel:DWORD dst_unused:UNUSED_PAD src0_sel:WORD_1
	v_cvt_pk_f16_f32 v74, v62, v63
	v_mov_b32_e32 v70, v1
	v_cvt_pk_f16_f32 v75, v64, v65
	v_fma_f32 v50, v50, v46, v66
	v_fma_f32 v51, v51, v47, v67
	v_cvt_pk_f16_f32 v67, v54, v55
	v_mov_b32_e32 v66, v1
	v_mov_b32_dpp v70, v74 quad_perm:[1,0,3,2] row_mask:0xf bank_mask:0xf
	v_mov_b32_e32 v71, v1
	v_cvt_pk_f16_f32 v76, v58, v59
	v_fma_f32 v52, v52, v48, v68
	v_fma_f32 v53, v53, v49, v69
	v_cvt_pk_f16_f32 v68, v56, v57
	v_mov_b32_dpp v66, v67 quad_perm:[1,0,3,2] row_mask:0xf bank_mask:0xf
	v_cndmask_b32_e64 v70, v67, v70, s[0:1]
	v_mov_b32_e32 v67, v1
	v_mov_b32_dpp v71, v75 quad_perm:[1,0,3,2] row_mask:0xf bank_mask:0xf
	v_mov_b32_e32 v72, v1
	v_cvt_pk_f16_f32 v69, v50, v51
	v_mov_b32_dpp v67, v68 quad_perm:[1,0,3,2] row_mask:0xf bank_mask:0xf
	v_cndmask_b32_e64 v71, v68, v71, s[0:1]
	v_mov_b32_e32 v68, v1
	v_mov_b32_dpp v72, v76 quad_perm:[1,0,3,2] row_mask:0xf bank_mask:0xf
	v_cvt_pk_f16_f32 v73, v52, v53
	v_mov_b32_dpp v68, v69 quad_perm:[1,0,3,2] row_mask:0xf bank_mask:0xf
	v_cndmask_b32_e64 v72, v69, v72, s[0:1]
	v_mov_b32_e32 v69, v1
	v_cvt_pk_f16_f32 v77, v60, v61
	v_cndmask_b32_e64 v66, v66, v74, s[0:1]
	v_mov_b32_dpp v69, v73 quad_perm:[1,0,3,2] row_mask:0xf bank_mask:0xf
	v_mov_b32_e32 v74, v1
	v_cndmask_b32_e64 v67, v67, v75, s[0:1]
	v_cndmask_b32_e64 v68, v68, v76, s[0:1]
	v_mov_b32_dpp v74, v77 quad_perm:[1,0,3,2] row_mask:0xf bank_mask:0xf
	v_cndmask_b32_e64 v69, v69, v77, s[0:1]
	v_cndmask_b32_e64 v73, v73, v74, s[0:1]
	global_store_dwordx4 v78, v[66:69], s[6:7] sc1
	s_nop 1
	v_add_u32_e32 v66, 0x16f90800, v0
	global_store_dwordx4 v66, v[70:73], s[6:7] sc1
	s_cbranch_vccnz .LBB0_525
	v_mul_f32_e32 v66, v16, v52
	v_mul_f32_e32 v67, v17, v53
	v_mul_f32_e32 v68, v14, v50
	v_mul_f32_e32 v69, v15, v51
	v_cvt_pk_f16_f32 v73, v66, v67
	v_cvt_pk_f16_f32 v72, v68, v69
	v_mul_f32_e32 v66, v12, v56
	v_mul_f32_e32 v67, v13, v57
	v_mul_f32_e32 v68, v10, v54
	v_mul_f32_e32 v69, v11, v55
	v_cvt_pk_f16_f32 v71, v66, v67
	v_cvt_pk_f16_f32 v70, v68, v69
	v_mul_f32_e32 v66, v8, v60
	v_mul_f32_e32 v67, v9, v61
	v_mul_f32_e32 v68, v6, v58
	v_mul_f32_e32 v69, v7, v59
	v_cvt_pk_f16_f32 v74, v66, v67
	v_cvt_pk_f16_f32 v75, v68, v69
	v_mul_f32_e32 v66, v4, v64
	v_mul_f32_e32 v67, v5, v65
	v_mul_f32_e32 v68, v2, v62
	v_mul_f32_e32 v69, v3, v63
	v_cvt_pk_f16_f32 v67, v66, v67
	v_cvt_pk_f16_f32 v66, v68, v69
	v_mov_b32_e32 v69, v1
	v_mov_b32_e32 v68, v1
	v_add_u32_e32 v76, 0x3d90000, v0
	v_mov_b32_dpp v69, v66 quad_perm:[1,0,3,2] row_mask:0xf bank_mask:0xf
	v_mov_b32_dpp v68, v70 quad_perm:[1,0,3,2] row_mask:0xf bank_mask:0xf
	v_cndmask_b32_e64 v70, v70, v69, s[0:1]
	v_mov_b32_e32 v69, v1
	v_cndmask_b32_e64 v66, v68, v66, s[0:1]
	v_mov_b32_e32 v68, v1
	v_mov_b32_dpp v69, v67 quad_perm:[1,0,3,2] row_mask:0xf bank_mask:0xf
	s_nop 0
	v_mov_b32_dpp v68, v71 quad_perm:[1,0,3,2] row_mask:0xf bank_mask:0xf
	v_cndmask_b32_e64 v71, v71, v69, s[0:1]
	v_mov_b32_e32 v69, v1
	v_cndmask_b32_e64 v67, v68, v67, s[0:1]
	v_mov_b32_e32 v68, v1
	v_mov_b32_dpp v69, v75 quad_perm:[1,0,3,2] row_mask:0xf bank_mask:0xf
	s_nop 0
	v_mov_b32_dpp v68, v72 quad_perm:[1,0,3,2] row_mask:0xf bank_mask:0xf
	v_cndmask_b32_e64 v72, v72, v69, s[0:1]
	v_mov_b32_e32 v69, v1
	v_cndmask_b32_e64 v68, v68, v75, s[0:1]
	v_mov_b32_e32 v75, v1
	v_mov_b32_dpp v69, v73 quad_perm:[1,0,3,2] row_mask:0xf bank_mask:0xf
	v_cndmask_b32_e64 v69, v69, v74, s[0:1]
	v_mov_b32_dpp v75, v74 quad_perm:[1,0,3,2] row_mask:0xf bank_mask:0xf
	v_cndmask_b32_e64 v73, v73, v75, s[0:1]
	global_store_dwordx4 v76, v[66:69], s[6:7] sc1
	s_nop 1
	v_add_u32_e32 v66, 0x3d90800, v0
	global_store_dwordx4 v66, v[70:73], s[6:7] sc1

; #define GAS __attribute__((address_space(1)))
; __device__ __forceinline__ unsigned cvtpk_h(float lo, float hi) { f32x2 v = {lo, hi}; h16x2 b = __builtin_convertvector(v, h16x2); return __builtin_bit_cast(unsigned, b); }
;     __device__ __forceinline__ void operator()(const f32x4 (&acc)[2][2][4][2], const pg8::Unit& u, int wr, int wc, int fr, int fq) const {
;     ...
;             for (int m = 0; m < 4; ++m) { if (half && ai == 1) continue; const unsigned rr = (unsigned)(ai * 128 + m * 16); const unsigned o = eoA + rr * (D * 2u); float ss = 0.f;
;                 const u32x4 la = *(const GAS u32x4*)((const GAS char*)ws + (unsigned)WS_X16 + o), lb = *(const GAS u32x4*)((const GAS char*)ws + (unsigned)WS_X16 + o + D * 2u);
;                 u32x4 xr[2];
; #pragma unroll
;                 for (int c = 0; c < 4; ++c) { const unsigned pa = (unsigned)__builtin_amdgcn_update_dpp(0, (int)la[c], 0xB1, 0xF, 0xF, false), pb = (unsigned)__builtin_amdgcn_update_dpp(0, (int)lb[c], 0xB1, 0xF, 0xF, false);
;                     xr[0][c] = odd ? pb : la[c]; xr[1][c] = odd ? lb[c] : pa; }
;                 u32x4 w[2], v[2];
; #pragma unroll
;                 for (int bj = 0; bj < 2; ++bj) { const h16x8 xb = __builtin_bit_cast(h16x8, xr[bj]);
;                     const f32x4 x0 = (f32x4){(float)xb[0], (float)xb[1], (float)xb[2], (float)xb[3]} + g4[bj][0] * acc[ai][bj][m][0], x1 = (f32x4){(float)xb[4], (float)xb[5], (float)xb[6], (float)xb[7]} + g4[bj][1] * acc[ai][bj][m][1];
;                     ss += ((x0[0] * x0[0] + x0[1] * x0[1]) + (x0[2] * x0[2] + x0[3] * x0[3])) + ((x1[0] * x1[0] + x1[1] * x1[1]) + (x1[2] * x1[2] + x1[3] * x1[3]));
;                     w[bj].x = cvtpk_h(x0[0], x0[1]); w[bj].y = cvtpk_h(x0[2], x0[3]); w[bj].z = cvtpk_h(x1[0], x1[1]); w[bj].w = cvtpk_h(x1[2], x1[3]);
;                     const f32x4 y0 = x0 * a4[bj][0], y1 = x1 * a4[bj][1]; v[bj].x = cvtpk_h(y0[0], y0[1]); v[bj].y = cvtpk_h(y0[2], y0[3]); v[bj].z = cvtpk_h(y1[0], y1[1]); v[bj].w = cvtpk_h(y1[2], y1[3]); }
;                 stg_line_pair(ws, (unsigned)WS_X16 + o, D * 2u, w[0], w[1], odd);
;                 if (an_off) stg_line_pair(ws, (unsigned)WS_XS + o, D * 2u, v[0], v[1], odd);
.LBB0_527:
	s_or_b64 exec, exec, s[10:11]
	v_add_u32_e32 v54, 0x18000, v0
	global_load_dwordx4 v[50:53], v54, s[8:9]
	s_nop 0
	global_load_dwordx4 v[54:57], v54, s[8:9] offset:2048
	v_mov_b32_e32 v58, v1
	v_mov_b32_e32 v59, v1
	s_and_b64 vcc, exec, s[2:3]
	s_waitcnt vmcnt(0)
	v_mov_b32_dpp v58, v50 quad_perm:[1,0,3,2] row_mask:0xf bank_mask:0xf
	v_mov_b32_dpp v59, v54 quad_perm:[1,0,3,2] row_mask:0xf bank_mask:0xf
	v_cndmask_b32_e64 v59, v59, v50, s[0:1]
	v_cndmask_b32_e64 v54, v54, v58, s[0:1]
	v_mov_b32_e32 v50, v1
	v_mov_b32_e32 v58, v1
	s_nop 0
	v_mov_b32_dpp v50, v51 quad_perm:[1,0,3,2] row_mask:0xf bank_mask:0xf
	v_mov_b32_dpp v58, v55 quad_perm:[1,0,3,2] row_mask:0xf bank_mask:0xf
	v_cndmask_b32_e64 v58, v58, v51, s[0:1]
	v_cndmask_b32_e64 v55, v55, v50, s[0:1]
	v_mov_b32_e32 v50, v1
	v_mov_b32_e32 v51, v1
	s_nop 0
	v_mov_b32_dpp v50, v52 quad_perm:[1,0,3,2] row_mask:0xf bank_mask:0xf
	v_mov_b32_dpp v51, v56 quad_perm:[1,0,3,2] row_mask:0xf bank_mask:0xf
	v_cndmask_b32_e64 v60, v51, v52, s[0:1]
	v_cndmask_b32_e64 v56, v56, v50, s[0:1]
	v_mov_b32_e32 v50, v1
	v_mov_b32_e32 v51, v1
	v_cvt_f32_f16_e32 v52, v58
	v_mov_b32_dpp v50, v53 quad_perm:[1,0,3,2] row_mask:0xf bank_mask:0xf
	v_mov_b32_dpp v51, v57 quad_perm:[1,0,3,2] row_mask:0xf bank_mask:0xf
	v_cndmask_b32_e64 v61, v51, v53, s[0:1]
	v_cndmask_b32_e64 v57, v57, v50, s[0:1]
	v_cvt_f32_f16_e32 v50, v59
	v_cvt_f32_f16_sdwa v51, v59 dst_sel:DWORD dst_unused:UNUSED_PAD src0_sel:WORD_1
	v_cvt_f32_f16_sdwa v53, v58 dst_sel:DWORD dst_unused:UNUSED_PAD src0_sel:WORD_1
	v_fma_f32 v30, v30, v34, v50
	v_fma_f32 v31, v31, v35, v51
	v_cvt_f32_f16_e32 v34, v60
	v_cvt_f32_f16_sdwa v35, v60 dst_sel:DWORD dst_unused:UNUSED_PAD src0_sel:WORD_1
	v_fma_f32 v32, v32, v36, v52
	v_fma_f32 v33, v33, v37, v53
	v_cvt_f32_f16_e32 v36, v61
	v_cvt_f32_f16_sdwa v37, v61 dst_sel:DWORD dst_unused:UNUSED_PAD src0_sel:WORD_1
	v_fma_f32 v26, v26, v38, v34
	v_fma_f32 v27, v27, v39, v35
	v_cvt_f32_f16_e32 v34, v54
	v_cvt_f32_f16_sdwa v35, v54 dst_sel:DWORD dst_unused:UNUSED_PAD src0_sel:WORD_1
	v_fma_f32 v28, v28, v40, v36
	v_fma_f32 v29, v29, v41, v37
	v_cvt_f32_f16_e32 v36, v55
	v_cvt_f32_f16_sdwa v37, v55 dst_sel:DWORD dst_unused:UNUSED_PAD src0_sel:WORD_1
	v_fma_f32 v22, v22, v42, v34
	v_fma_f32 v23, v23, v43, v35
	v_cvt_f32_f16_e32 v34, v56
	v_cvt_f32_f16_sdwa v35, v56 dst_sel:DWORD dst_unused:UNUSED_PAD src0_sel:WORD_1
	v_fma_f32 v24, v24, v44, v36
	v_fma_f32 v25, v25, v45, v37
	v_cvt_f32_f16_e32 v36, v57
	v_cvt_f32_f16_sdwa v37, v57 dst_sel:DWORD dst_unused:UNUSED_PAD src0_sel:WORD_1
	v_cvt_pk_f16_f32 v38, v30, v31
	v_fma_f32 v18, v18, v46, v34
	v_fma_f32 v19, v19, v47, v35
	v_cvt_pk_f16_f32 v35, v22, v23
	v_mov_b32_e32 v34, v1
	v_mov_b32_e32 v44, v1
	v_cvt_pk_f16_f32 v39, v32, v33
	v_mov_b32_dpp v34, v35 quad_perm:[1,0,3,2] row_mask:0xf bank_mask:0xf
	v_mov_b32_dpp v44, v38 quad_perm:[1,0,3,2] row_mask:0xf bank_mask:0xf
	v_fma_f32 v20, v20, v48, v36
	v_fma_f32 v21, v21, v49, v37
	v_cvt_pk_f16_f32 v36, v24, v25
	v_cndmask_b32_e64 v34, v34, v38, s[0:1]
	v_cndmask_b32_e64 v38, v35, v44, s[0:1]
	v_mov_b32_e32 v35, v1
	v_mov_b32_e32 v44, v1
	v_cvt_pk_f16_f32 v40, v26, v27
	v_mov_b32_dpp v35, v36 quad_perm:[1,0,3,2] row_mask:0xf bank_mask:0xf
	v_mov_b32_dpp v44, v39 quad_perm:[1,0,3,2] row_mask:0xf bank_mask:0xf
	v_cvt_pk_f16_f32 v37, v18, v19
	v_cndmask_b32_e64 v35, v35, v39, s[0:1]
	v_cndmask_b32_e64 v39, v36, v44, s[0:1]
	v_mov_b32_e32 v36, v1
	v_mov_b32_e32 v44, v1
	v_cvt_pk_f16_f32 v42, v20, v21
	v_mov_b32_dpp v36, v37 quad_perm:[1,0,3,2] row_mask:0xf bank_mask:0xf
	v_mov_b32_dpp v44, v40 quad_perm:[1,0,3,2] row_mask:0xf bank_mask:0xf
	v_cndmask_b32_e64 v36, v36, v40, s[0:1]
	v_cndmask_b32_e64 v40, v37, v44, s[0:1]
	v_mov_b32_e32 v37, v1
	v_cvt_pk_f16_f32 v41, v28, v29
	v_mov_b32_e32 v44, v1
	v_mov_b32_dpp v37, v42 quad_perm:[1,0,3,2] row_mask:0xf bank_mask:0xf
	v_add_u32_e32 v43, 0x16f98000, v0
	v_mov_b32_dpp v44, v41 quad_perm:[1,0,3,2] row_mask:0xf bank_mask:0xf
	v_cndmask_b32_e64 v37, v37, v41, s[0:1]
	v_cndmask_b32_e64 v41, v42, v44, s[0:1]
	global_store_dwordx4 v43, v[34:37], s[6:7] sc1
	s_nop 1
	v_add_u32_e32 v34, 0x16f98800, v0
	global_store_dwordx4 v34, v[38:41], s[6:7] sc1
	s_cbranch_vccnz .LBB0_529
	v_mul_f32_e32 v10, v10, v22
	v_mul_f32_e32 v11, v11, v23
	v_mul_f32_e32 v4, v4, v32
	v_mul_f32_e32 v5, v5, v33
	v_mul_f32_e32 v2, v2, v30
	v_mul_f32_e32 v3, v3, v31
	v_cvt_pk_f16_f32 v10, v10, v11
	v_cvt_pk_f16_f32 v4, v4, v5
	v_cvt_pk_f16_f32 v2, v2, v3
	v_mov_b32_e32 v3, v1
	v_mov_b32_e32 v5, v1
	v_mul_f32_e32 v12, v12, v24
	v_mul_f32_e32 v13, v13, v25
	v_mul_f32_e32 v8, v8, v28
	v_mul_f32_e32 v9, v9, v29
	v_mul_f32_e32 v6, v6, v26
	v_mul_f32_e32 v7, v7, v27
	v_mov_b32_dpp v3, v10 quad_perm:[1,0,3,2] row_mask:0xf bank_mask:0xf
	v_mov_b32_dpp v5, v2 quad_perm:[1,0,3,2] row_mask:0xf bank_mask:0xf
	v_cvt_pk_f16_f32 v12, v12, v13
	v_cvt_pk_f16_f32 v9, v8, v9
	v_cvt_pk_f16_f32 v8, v6, v7
	v_cndmask_b32_e64 v2, v3, v2, s[0:1]
	v_cndmask_b32_e64 v6, v10, v5, s[0:1]
	v_mov_b32_e32 v3, v1
	v_mov_b32_e32 v5, v1
	v_mul_f32_e32 v14, v14, v18
	v_mul_f32_e32 v15, v15, v19
	v_mov_b32_dpp v3, v12 quad_perm:[1,0,3,2] row_mask:0xf bank_mask:0xf
	v_mov_b32_dpp v5, v4 quad_perm:[1,0,3,2] row_mask:0xf bank_mask:0xf
	v_cvt_pk_f16_f32 v14, v14, v15
	v_cndmask_b32_e64 v3, v3, v4, s[0:1]
	v_cndmask_b32_e64 v7, v12, v5, s[0:1]
	v_mov_b32_e32 v4, v1
	v_mov_b32_e32 v5, v1
	v_mul_f32_e32 v16, v16, v20
	v_mul_f32_e32 v17, v17, v21
	v_mov_b32_dpp v4, v14 quad_perm:[1,0,3,2] row_mask:0xf bank_mask:0xf
	v_mov_b32_dpp v5, v8 quad_perm:[1,0,3,2] row_mask:0xf bank_mask:0xf
	v_cvt_pk_f16_f32 v16, v16, v17
	v_cndmask_b32_e64 v4, v4, v8, s[0:1]
	v_cndmask_b32_e64 v8, v14, v5, s[0:1]
	v_mov_b32_e32 v5, v1
	v_mov_b32_e32 v10, v1
	v_add_u32_e32 v11, 0x3d98000, v0
	v_mov_b32_dpp v5, v16 quad_perm:[1,0,3,2] row_mask:0xf bank_mask:0xf
	v_mov_b32_dpp v10, v9 quad_perm:[1,0,3,2] row_mask:0xf bank_mask:0xf
	v_cndmask_b32_e64 v5, v5, v9, s[0:1]
	v_cndmask_b32_e64 v9, v16, v10, s[0:1]
	v_add_u32_e32 v0, 0x3d98800, v0
	global_store_dwordx4 v11, v[2:5], s[6:7] sc1
	global_store_dwordx4 v0, v[6:9], s[6:7] sc1

; #define LAS __attribute__((address_space(3)))
; #define GAS __attribute__((address_space(1)))
;     __device__ __forceinline__ void operator()(const f32x4 (&acc)[2][2][4][2], const pg8::Unit& u, int wr, int wc, int fr, int fq) const {
;     ...
;         const bool isq = s < 20; const float* gv = isq ? gq : gk; const float osc = isq ? QSCALE : 1.f;
;         f32x4 g4[2][2];
; #pragma unroll
;         for (int bj = 0; bj < 2; ++bj)
; #pragma unroll
;             for (int n = 0; n < 2; ++n) g4[bj][n] = *(const GAS f32x4*)(gv + 32 * bj + 16 * n + 4 * fq) * osc;
;         const unsigned pitch = isq ? 512u : 64u;
;         const bool odd = (fr & 1) != 0; const unsigned rpair = (unsigned)(wr * 64 + (fr & ~1)), cb = (odd ? 64u : 0u) + 16u * fq;
;         const unsigned offA = isq ? (unsigned)WS_Q + (((unsigned)u.pm * 256u + rpair) * 512u + (s - 12) * 64) * 2u + cb
;                                   : (unsigned)WS_KB + (((unsigned)(b * 2 + (s - 20)) * NKEY + key0 + rpair) * 64u) * 2u + cb;
; #pragma unroll
;         for (int ai = 0; ai < 2; ++ai)
; #pragma unroll
;             for (int m = 0; m < 4; ++m) { const float r = rs[ai][m]; f32x4 v[2][2]; float ss = 0.f;
; #pragma unroll
;                 for (int bj = 0; bj < 2; ++bj)
; #pragma unroll
;                     for (int n = 0; n < 2; ++n) { v[bj][n] = acc[ai][bj][m][n] * r + bv[bj][n]; ss += (v[bj][n][0] * v[bj][n][0] + v[bj][n][1] * v[bj][n][1]) + (v[bj][n][2] * v[bj][n][2] + v[bj][n][3] * v[bj][n][3]); }
;                 const float rn = __builtin_amdgcn_rsqf(red4(ss, fq * 16 + fr) * (1.f / 64.f) + EPS);
; #pragma unroll
;                 for (int bj = 0; bj < 2; ++bj)
; #pragma unroll
;                     for (int n = 0; n < 2; ++n) v[bj][n] = v[bj][n] * rn * g4[bj][n];
;                 if (lat) { const unsigned t = (rbase + ai * 128 + m * 16) & (SEQ - 1);
; #pragma unroll
;                     for (int bj = 0; bj < 2; ++bj) { const unsigned pos = bj ? (t & 63u) : (t >> 6); const f32x4 cs = *(const LAS f32x4*)(ropel + pos * 16u + 4u * fq), sn = *(const LAS f32x4*)(ropel + 1024u + pos * 16u + 4u * fq);
;                         const f32x4 x1 = v[bj][0], x2 = v[bj][1]; v[bj][0] = x1 * cs - x2 * sn; v[bj][1] = x2 * cs + x1 * sn; } }
;                 const unsigned ro = offA + (unsigned)(ai * 8 + m) * 32u * pitch;
;                 u32x4 w[2];
; #pragma unroll
.LBB0_575:
	v_mov_b32_e32 v178, 0x3e38aa3b
	v_cndmask_b32_e64 v188, 1.0, v178, s[2:3]
	s_waitcnt vmcnt(2)
	v_mul_f32_e32 v178, v188, v158
	v_mul_f32_e32 v179, v188, v159
	v_mul_f32_e32 v180, v188, v156
	v_mul_f32_e32 v181, v188, v157
	s_waitcnt vmcnt(0)
	v_mul_f32_e32 v156, v188, v150
	v_mul_f32_e32 v157, v188, v151
	v_mul_f32_e32 v158, v188, v148
	v_mul_f32_e32 v159, v188, v149
	v_fma_f32 v148, v72, v176, v138
	v_fma_f32 v149, v73, v176, v139
	v_fma_f32 v150, v70, v176, v136
	v_fma_f32 v151, v71, v176, v137
	v_mul_f32_e32 v182, v188, v162
	v_mul_f32_e32 v183, v188, v163
	v_mul_f32_e32 v162, v188, v152
	v_mul_f32_e32 v163, v188, v153
	v_mul_f32_e32 v152, v151, v151
	v_mul_f32_e32 v153, v149, v149
	v_mul_f32_e32 v184, v188, v160
	v_mul_f32_e32 v185, v188, v161
	v_mul_f32_e32 v160, v188, v154
	v_mul_f32_e32 v161, v188, v155
	v_fmac_f32_e32 v152, v150, v150
	v_fmac_f32_e32 v153, v148, v148
	v_fma_f32 v188, v68, v176, v134
	v_fma_f32 v189, v69, v176, v135
	v_fma_f32 v190, v66, v176, v132
	v_fma_f32 v191, v67, v176, v133
	v_add_f32_e32 v152, v152, v153
	v_mul_f32_e32 v153, v191, v191
	v_mul_f32_e32 v154, v189, v189
	v_fmac_f32_e32 v153, v190, v190
	v_fmac_f32_e32 v154, v188, v188
	v_add_f32_e32 v153, v153, v154
	v_fma_f32 v192, v128, v176, v142
	v_fma_f32 v193, v129, v176, v143
	v_fma_f32 v194, v126, v176, v140
	v_fma_f32 v195, v127, v176, v141
	v_add_f32_e32 v152, v152, v153
	v_mul_f32_e32 v153, v195, v195
	v_mul_f32_e32 v154, v193, v193
	v_fmac_f32_e32 v153, v194, v194
	v_fmac_f32_e32 v154, v192, v192
	v_add_f32_e32 v153, v153, v154
	v_fma_f32 v204, v124, v176, v146
	v_fma_f32 v205, v125, v176, v147
	v_fma_f32 v206, v122, v176, v144
	v_fma_f32 v207, v123, v176, v145
	v_add_f32_e32 v152, v152, v153
	v_mul_f32_e32 v153, v207, v207
	v_mul_f32_e32 v154, v205, v205
	v_fmac_f32_e32 v153, v206, v206
	v_fmac_f32_e32 v154, v204, v204
	v_add_f32_e32 v153, v153, v154
	v_add_f32_e32 v152, v152, v153
	v_mov_b32_e32 v153, v152
	s_nop 1
	v_permlane16_swap_b32_e32 v152, v153
	v_add_f32_e32 v152, v152, v153
	v_mov_b32_e32 v153, v152
	s_nop 1
	v_permlane32_swap_b32_e32 v152, v153
	v_add_f32_e32 v152, v152, v153
	v_fmamk_f32 v152, v152, 0x3c800000, v229
	v_rsq_f32_e32 v216, v152
	v_lshlrev_b32_e32 v186, 2, v186
	v_readlane_b32 s2, v253, 7
	v_readlane_b32 s70, v252, 58
	v_mul_f32_e32 v150, v150, v216
	v_mul_f32_e32 v151, v151, v216
	v_mul_f32_e32 v148, v148, v216
	v_mul_f32_e32 v149, v149, v216
	v_mul_f32_e32 v152, v184, v150
	v_mul_f32_e32 v153, v185, v151
	v_mul_f32_e32 v154, v182, v148
	v_mul_f32_e32 v155, v183, v149
	v_mul_f32_e32 v148, v190, v216
	v_mul_f32_e32 v149, v191, v216
	v_mul_f32_e32 v150, v188, v216
	v_mul_f32_e32 v151, v189, v216
	v_and_b32_e32 v214, 63, v202
	v_mul_f32_e32 v188, v178, v150
	v_mul_f32_e32 v189, v179, v151
	v_mul_f32_e32 v190, v180, v148
	v_mul_f32_e32 v191, v181, v149
	v_mul_f32_e32 v148, v194, v216
	v_mul_f32_e32 v149, v195, v216
	v_mul_f32_e32 v150, v192, v216
	v_mul_f32_e32 v151, v193, v216
	v_mul_f32_e32 v194, v206, v216
	v_mul_f32_e32 v195, v207, v216
	v_mul_f32_e32 v192, v204, v216
	v_mul_f32_e32 v193, v205, v216
	v_cndmask_b32_e64 v204, 0, 1, s[38:39]
	v_add_u32_e32 v205, s2, v186
	v_readlane_b32 s2, v253, 8
	v_readlane_b32 s71, v252, 59
	v_mul_f32_e32 v150, v160, v150
	v_mul_f32_e32 v151, v161, v151
	v_mul_f32_e32 v148, v162, v148
	v_mul_f32_e32 v149, v163, v149
	v_mul_f32_e32 v192, v156, v192
	v_mul_f32_e32 v193, v157, v193
	v_mul_f32_e32 v194, v158, v194
	v_mul_f32_e32 v195, v159, v195
	v_cmp_ne_u32_e64 s[4:5], 1, v204
	s_andn2_b64 vcc, exec, s[38:39]
	v_lshlrev_b32_e32 v207, 6, v214
	v_add_u32_e32 v204, s2, v186
	s_cbranch_vccnz .LBB0_577
	v_and_b32_e32 v186, 0x7c0, v201
	v_add_u32_e32 v206, v205, v186
	v_add_u32_e32 v186, v204, v186
	ds_read_b128 v[216:219], v206
	ds_read_b128 v[220:223], v186
	v_add_u32_e32 v186, v204, v207
	s_waitcnt lgkmcnt(0)
	v_mul_f32_e32 v224, v188, v222
	v_mul_f32_e32 v225, v189, v223
	v_mul_f32_e32 v230, v190, v220
	v_mul_f32_e32 v231, v191, v221
	v_fma_f32 v226, v154, v218, -v224
	v_fma_f32 v227, v155, v219, -v225
	v_fma_f32 v224, v152, v216, -v230
	v_fma_f32 v225, v153, v217, -v231
	v_mul_f32_e32 v152, v152, v220
	v_mul_f32_e32 v153, v153, v221
	v_mul_f32_e32 v154, v154, v222
	v_mul_f32_e32 v155, v155, v223
	v_fma_f32 v190, v190, v216, v152
	v_fma_f32 v191, v191, v217, v153
	v_add_u32_e32 v152, v205, v207
	v_fma_f32 v188, v188, v218, v154
	v_fma_f32 v189, v189, v219, v155
	ds_read_b128 v[152:155], v152
	ds_read_b128 v[216:219], v186
	s_waitcnt lgkmcnt(0)
	v_mul_f32_e32 v220, v192, v218
	v_mul_f32_e32 v221, v193, v219
	v_mul_f32_e32 v230, v194, v216
	v_mul_f32_e32 v231, v195, v217
	v_fma_f32 v222, v150, v154, -v220
	v_fma_f32 v223, v151, v155, -v221
	v_fma_f32 v220, v148, v152, -v230
	v_fma_f32 v221, v149, v153, -v231
	v_mul_f32_e32 v150, v150, v218
	v_mul_f32_e32 v151, v151, v219
	v_mul_f32_e32 v148, v148, v216
	v_mul_f32_e32 v149, v149, v217
	v_fma_f32 v192, v192, v154, v150
	v_fma_f32 v193, v193, v155, v151
	v_fma_f32 v194, v194, v152, v148
	v_fma_f32 v195, v195, v153, v149
	v_mov_b64_e32 v[148:149], v[220:221]
	v_mov_b64_e32 v[152:153], v[224:225]
	v_mov_b64_e32 v[150:151], v[222:223]
	v_mov_b64_e32 v[154:155], v[226:227]
; #define LAS __attribute__((address_space(3)))
; __device__ __forceinline__ unsigned cvtpk_h(float lo, float hi) { f32x2 v = {lo, hi}; h16x2 b = __builtin_convertvector(v, h16x2); return __builtin_bit_cast(unsigned, b); }
;     __device__ __forceinline__ void operator()(const f32x4 (&acc)[2][2][4][2], const pg8::Unit& u, int wr, int wc, int fr, int fq) const {
;     ...
;             for (int m = 0; m < 4; ++m) { const float r = rs[ai][m]; f32x4 v[2][2]; float ss = 0.f;
; #pragma unroll
;                 for (int bj = 0; bj < 2; ++bj)
; #pragma unroll
;                     for (int n = 0; n < 2; ++n) { v[bj][n] = acc[ai][bj][m][n] * r + bv[bj][n]; ss += (v[bj][n][0] * v[bj][n][0] + v[bj][n][1] * v[bj][n][1]) + (v[bj][n][2] * v[bj][n][2] + v[bj][n][3] * v[bj][n][3]); }
;                 const float rn = __builtin_amdgcn_rsqf(red4(ss, fq * 16 + fr) * (1.f / 64.f) + EPS);
; #pragma unroll
;                 for (int bj = 0; bj < 2; ++bj)
; #pragma unroll
;                     for (int n = 0; n < 2; ++n) v[bj][n] = v[bj][n] * rn * g4[bj][n];
;                 if (lat) { const unsigned t = (rbase + ai * 128 + m * 16) & (SEQ - 1);
; #pragma unroll
;                     for (int bj = 0; bj < 2; ++bj) { const unsigned pos = bj ? (t & 63u) : (t >> 6); const f32x4 cs = *(const LAS f32x4*)(ropel + pos * 16u + 4u * fq), sn = *(const LAS f32x4*)(ropel + 1024u + pos * 16u + 4u * fq);
;                         const f32x4 x1 = v[bj][0], x2 = v[bj][1]; v[bj][0] = x1 * cs - x2 * sn; v[bj][1] = x2 * cs + x1 * sn; } }
;                 const unsigned ro = offA + (unsigned)(ai * 8 + m) * 32u * pitch;
;                 u32x4 w[2];
; #pragma unroll
;                 for (int bj = 0; bj < 2; ++bj) { w[bj].x = cvtpk_h(v[bj][0][0], v[bj][0][1]); w[bj].y = cvtpk_h(v[bj][0][2], v[bj][0][3]); w[bj].z = cvtpk_h(v[bj][1][0], v[bj][1][1]); w[bj].w = cvtpk_h(v[bj][1][2], v[bj][1][3]); }
;                 stg_line_pair(wst, ro, 2u * pitch, w[0], w[1], odd);
;                 asm volatile("" ::: "memory"); }
.LBB0_577:
	v_and_b32_e32 v186, 1, v202
	v_lshlrev_b32_e32 v206, 6, v186
	v_add3_u32 v206, v206, v203, v187
	v_add_u32_e32 v187, 16, v202
	v_and_b32_e32 v210, 63, v187
	v_cvt_pk_f16_f32 v152, v152, v153
	v_cvt_pk_f16_f32 v149, v148, v149
	v_mov_b32_e32 v148, v1
	v_mov_b32_e32 v187, v1
	v_cmp_eq_u32_e64 s[2:3], 0, v186
	v_mov_b32_dpp v148, v149 quad_perm:[1,0,3,2] row_mask:0xf bank_mask:0xf
	v_mov_b32_dpp v187, v152 quad_perm:[1,0,3,2] row_mask:0xf bank_mask:0xf
	v_cvt_pk_f16_f32 v153, v154, v155
	v_cvt_pk_f16_f32 v150, v150, v151
	v_cndmask_b32_e64 v148, v148, v152, s[2:3]
	v_cndmask_b32_e64 v152, v149, v187, s[2:3]
	v_mov_b32_e32 v149, v1
	v_mov_b32_e32 v187, v1
	v_cvt_pk_f16_f32 v154, v190, v191
	v_mov_b32_dpp v149, v150 quad_perm:[1,0,3,2] row_mask:0xf bank_mask:0xf
	v_mov_b32_dpp v187, v153 quad_perm:[1,0,3,2] row_mask:0xf bank_mask:0xf
	v_cvt_pk_f16_f32 v151, v194, v195
	v_cndmask_b32_e64 v149, v149, v153, s[2:3]
	v_cndmask_b32_e64 v153, v150, v187, s[2:3]
	v_mov_b32_e32 v150, v1
	v_mov_b32_e32 v187, v1
	v_cvt_pk_f16_f32 v186, v192, v193
	v_mov_b32_dpp v150, v151 quad_perm:[1,0,3,2] row_mask:0xf bank_mask:0xf
	v_mov_b32_dpp v187, v154 quad_perm:[1,0,3,2] row_mask:0xf bank_mask:0xf
	v_cndmask_b32_e64 v150, v150, v154, s[2:3]
	v_cndmask_b32_e64 v154, v151, v187, s[2:3]
	v_mov_b32_e32 v151, v1
	v_cvt_pk_f16_f32 v155, v188, v189
	v_mov_b32_e32 v187, v1
	v_mov_b32_dpp v151, v186 quad_perm:[1,0,3,2] row_mask:0xf bank_mask:0xf
	v_cndmask_b32_e64 v151, v151, v155, s[2:3]
	v_mov_b32_dpp v187, v155 quad_perm:[1,0,3,2] row_mask:0xf bank_mask:0xf
	v_cndmask_b32_e64 v155, v186, v187, s[2:3]
	s_mov_b32 s100, 2
	global_store_dwordx4 v206, v[148:151], s[36:37] sc1
	s_and_b64 vcc, exec, s[4:5]
	v_lshlrev_b32_e32 v213, 6, v210
	v_add_u32_e32 v148, s9, v206
	s_mov_b32 s100, 2
	global_store_dwordx4 v148, v[152:155], s[36:37] sc1
	v_mov_b32_e32 v148, v177
	v_fma_f32 v150, v52, v148, v138
	v_fma_f32 v151, v53, v148, v139
	v_fma_f32 v152, v50, v148, v136
	v_fma_f32 v153, v51, v148, v137
	v_mul_f32_e32 v154, v151, v151
	v_mul_f32_e32 v149, v153, v153
	v_fmac_f32_e32 v149, v152, v152
	v_fmac_f32_e32 v154, v150, v150
	v_add_f32_e32 v149, v149, v154
	v_fma_f32 v186, v48, v148, v134
	v_fma_f32 v187, v49, v148, v135
	v_fma_f32 v188, v46, v148, v132
	v_fma_f32 v189, v47, v148, v133
	v_mul_f32_e32 v155, v187, v187
	v_mul_f32_e32 v154, v189, v189
	v_fmac_f32_e32 v154, v188, v188
	v_fmac_f32_e32 v155, v186, v186
	v_add_f32_e32 v154, v154, v155
	v_add_f32_e32 v149, v149, v154
	v_fma_f32 v190, v120, v148, v142
	v_fma_f32 v191, v121, v148, v143
	v_fma_f32 v192, v118, v148, v140
	v_fma_f32 v193, v119, v148, v141
	v_mul_f32_e32 v155, v191, v191
	v_mul_f32_e32 v154, v193, v193
	v_fmac_f32_e32 v154, v192, v192
	v_fmac_f32_e32 v155, v190, v190
	v_add_f32_e32 v154, v154, v155
	v_add_f32_e32 v149, v149, v154
	v_fma_f32 v194, v116, v148, v146
	v_fma_f32 v195, v117, v148, v147
	v_fma_f32 v216, v114, v148, v144
	v_fma_f32 v217, v115, v148, v145
	v_mul_f32_e32 v154, v195, v195
	v_mul_f32_e32 v148, v217, v217
	v_fmac_f32_e32 v148, v216, v216
	v_fmac_f32_e32 v154, v194, v194
	v_add_f32_e32 v148, v148, v154
	v_add_f32_e32 v148, v149, v148
	v_mov_b32_e32 v149, v148
	s_nop 1
	v_permlane16_swap_b32_e32 v148, v149
	v_add_f32_e32 v148, v148, v149
	v_mov_b32_e32 v149, v148
	s_nop 1
	v_permlane32_swap_b32_e32 v148, v149
	v_add_f32_e32 v148, v148, v149
	v_fmamk_f32 v148, v148, 0x3c800000, v229
	v_rsq_f32_e32 v218, v148
	s_nop 0
	v_mul_f32_e32 v148, v152, v218
	v_mul_f32_e32 v149, v153, v218
	v_mul_f32_e32 v150, v150, v218
	v_mul_f32_e32 v151, v151, v218
	v_mul_f32_e32 v152, v184, v148
	v_mul_f32_e32 v153, v185, v149
	v_mul_f32_e32 v154, v182, v150
	v_mul_f32_e32 v155, v183, v151
	v_mul_f32_e32 v148, v188, v218
	v_mul_f32_e32 v149, v189, v218
	v_mul_f32_e32 v150, v186, v218
	v_mul_f32_e32 v151, v187, v218
	v_mul_f32_e32 v188, v180, v148
	v_mul_f32_e32 v189, v181, v149
	v_mul_f32_e32 v186, v178, v150
	v_mul_f32_e32 v187, v179, v151
	v_mul_f32_e32 v148, v192, v218
	v_mul_f32_e32 v149, v193, v218
	v_mul_f32_e32 v150, v190, v218
	v_mul_f32_e32 v151, v191, v218
	v_mul_f32_e32 v192, v216, v218
	v_mul_f32_e32 v193, v217, v218
	v_mul_f32_e32 v190, v194, v218
	v_mul_f32_e32 v191, v195, v218
	v_mul_f32_e32 v150, v160, v150
	v_mul_f32_e32 v151, v161, v151
	v_mul_f32_e32 v148, v162, v148
	v_mul_f32_e32 v149, v163, v149
	v_mul_f32_e32 v190, v156, v190
	v_mul_f32_e32 v191, v157, v191
	v_mul_f32_e32 v192, v158, v192
	v_mul_f32_e32 v193, v159, v193
	s_cbranch_vccnz .LBB0_579
	v_add_u32_e32 v194, 16, v201
	v_and_b32_e32 v194, 0x7c0, v194
	v_add_u32_e32 v195, v205, v194
	v_add_u32_e32 v194, v204, v194
	ds_read_b128 v[216:219], v195
	ds_read_b128 v[220:223], v194
	s_waitcnt lgkmcnt(0)
	v_mul_f32_e32 v224, v188, v220
	v_mul_f32_e32 v225, v189, v221
	v_mul_f32_e32 v194, v186, v222
	v_mul_f32_e32 v195, v187, v223
	v_fma_f32 v224, v152, v216, -v224
	v_fma_f32 v225, v153, v217, -v225
	v_mul_f32_e32 v152, v152, v220
	v_mul_f32_e32 v153, v153, v221
	v_fma_f32 v226, v154, v218, -v194
	v_fma_f32 v227, v155, v219, -v195
	v_mul_f32_e32 v154, v154, v222
	v_mul_f32_e32 v155, v155, v223
	v_fma_f32 v188, v188, v216, v152
	v_fma_f32 v189, v189, v217, v153
	v_add_u32_e32 v152, v205, v213
	v_add_u32_e32 v194, v204, v213
	v_fma_f32 v186, v186, v218, v154
	v_fma_f32 v187, v187, v219, v155
	ds_read_b128 v[152:155], v152
	ds_read_b128 v[216:219], v194
	s_waitcnt lgkmcnt(0)
	v_mul_f32_e32 v194, v190, v218
	v_mul_f32_e32 v195, v191, v219
	v_mul_f32_e32 v220, v192, v216
	v_mul_f32_e32 v221, v193, v217
	v_fma_f32 v222, v150, v154, -v194
	v_fma_f32 v223, v151, v155, -v195
	v_fma_f32 v220, v148, v152, -v220
	v_fma_f32 v221, v149, v153, -v221
	v_mul_f32_e32 v150, v150, v218
	v_mul_f32_e32 v151, v151, v219
	v_mul_f32_e32 v148, v148, v216
	v_mul_f32_e32 v149, v149, v217
	v_fma_f32 v190, v190, v154, v150
	v_fma_f32 v191, v191, v155, v151
	v_fma_f32 v192, v192, v152, v148
	v_fma_f32 v193, v193, v153, v149
	v_mov_b64_e32 v[148:149], v[220:221]
	v_mov_b64_e32 v[152:153], v[224:225]
	v_mov_b64_e32 v[150:151], v[222:223]
	v_mov_b64_e32 v[154:155], v[226:227]
; #define LAS __attribute__((address_space(3)))
; __device__ __forceinline__ unsigned cvtpk_h(float lo, float hi) { f32x2 v = {lo, hi}; h16x2 b = __builtin_convertvector(v, h16x2); return __builtin_bit_cast(unsigned, b); }
;     __device__ __forceinline__ void operator()(const f32x4 (&acc)[2][2][4][2], const pg8::Unit& u, int wr, int wc, int fr, int fq) const {
;     ...
;             for (int m = 0; m < 4; ++m) { const float r = rs[ai][m]; f32x4 v[2][2]; float ss = 0.f;
; #pragma unroll
;                 for (int bj = 0; bj < 2; ++bj)
; #pragma unroll
;                     for (int n = 0; n < 2; ++n) { v[bj][n] = acc[ai][bj][m][n] * r + bv[bj][n]; ss += (v[bj][n][0] * v[bj][n][0] + v[bj][n][1] * v[bj][n][1]) + (v[bj][n][2] * v[bj][n][2] + v[bj][n][3] * v[bj][n][3]); }
;                 const float rn = __builtin_amdgcn_rsqf(red4(ss, fq * 16 + fr) * (1.f / 64.f) + EPS);
; #pragma unroll
;                 for (int bj = 0; bj < 2; ++bj)
; #pragma unroll
;                     for (int n = 0; n < 2; ++n) v[bj][n] = v[bj][n] * rn * g4[bj][n];
;                 if (lat) { const unsigned t = (rbase + ai * 128 + m * 16) & (SEQ - 1);
; #pragma unroll
;                     for (int bj = 0; bj < 2; ++bj) { const unsigned pos = bj ? (t & 63u) : (t >> 6); const f32x4 cs = *(const LAS f32x4*)(ropel + pos * 16u + 4u * fq), sn = *(const LAS f32x4*)(ropel + 1024u + pos * 16u + 4u * fq);
;                         const f32x4 x1 = v[bj][0], x2 = v[bj][1]; v[bj][0] = x1 * cs - x2 * sn; v[bj][1] = x2 * cs + x1 * sn; } }
;                 const unsigned ro = offA + (unsigned)(ai * 8 + m) * 32u * pitch;
;                 u32x4 w[2];
; #pragma unroll
;                 for (int bj = 0; bj < 2; ++bj) { w[bj].x = cvtpk_h(v[bj][0][0], v[bj][0][1]); w[bj].y = cvtpk_h(v[bj][0][2], v[bj][0][3]); w[bj].z = cvtpk_h(v[bj][1][0], v[bj][1][1]); w[bj].w = cvtpk_h(v[bj][1][2], v[bj][1][3]); }
;                 stg_line_pair(wst, ro, 2u * pitch, w[0], w[1], odd);
;                 asm volatile("" ::: "memory"); }
.LBB0_579:
	v_cvt_pk_f16_f32 v152, v152, v153
	v_cvt_pk_f16_f32 v153, v154, v155
	v_cvt_pk_f16_f32 v154, v188, v189
	v_cvt_pk_f16_f32 v149, v148, v149
	v_mov_b32_e32 v148, v1
	v_mov_b32_e32 v188, v1
	v_cvt_pk_f16_f32 v150, v150, v151
	v_mov_b32_dpp v148, v149 quad_perm:[1,0,3,2] row_mask:0xf bank_mask:0xf
	v_mov_b32_dpp v188, v152 quad_perm:[1,0,3,2] row_mask:0xf bank_mask:0xf
	v_cndmask_b32_e64 v148, v148, v152, s[2:3]
	v_cndmask_b32_e64 v152, v149, v188, s[2:3]
	v_mov_b32_e32 v149, v1
	v_mov_b32_e32 v188, v1
	v_cvt_pk_f16_f32 v151, v192, v193
	v_mov_b32_dpp v149, v150 quad_perm:[1,0,3,2] row_mask:0xf bank_mask:0xf
	v_mov_b32_dpp v188, v153 quad_perm:[1,0,3,2] row_mask:0xf bank_mask:0xf
	v_cndmask_b32_e64 v149, v149, v153, s[2:3]
	v_cndmask_b32_e64 v153, v150, v188, s[2:3]
	v_mov_b32_e32 v150, v1
	v_mov_b32_e32 v188, v1
	v_cvt_pk_f16_f32 v155, v186, v187
	v_mov_b32_dpp v150, v151 quad_perm:[1,0,3,2] row_mask:0xf bank_mask:0xf
	v_mov_b32_dpp v188, v154 quad_perm:[1,0,3,2] row_mask:0xf bank_mask:0xf
	v_cvt_pk_f16_f32 v186, v190, v191
	v_cndmask_b32_e64 v150, v150, v154, s[2:3]
	v_cndmask_b32_e64 v154, v151, v188, s[2:3]
	v_mov_b32_e32 v151, v1
	v_mov_b32_e32 v188, v1
	v_lshl_add_u32 v187, 32, s42, v206
	v_mov_b32_dpp v151, v186 quad_perm:[1,0,3,2] row_mask:0xf bank_mask:0xf
	v_mov_b32_dpp v188, v155 quad_perm:[1,0,3,2] row_mask:0xf bank_mask:0xf
	v_cndmask_b32_e64 v151, v151, v155, s[2:3]
	v_cndmask_b32_e64 v155, v186, v188, s[2:3]
	s_mov_b32 s100, 2
	global_store_dwordx4 v187, v[148:151], s[36:37] sc1
	v_fma_f32 v188, v42, v174, v132
	v_fma_f32 v189, v43, v174, v133
	v_fma_f32 v190, v112, v174, v142
	v_fma_f32 v191, v113, v174, v143
	v_add_u32_e32 v148, s9, v187
	s_mov_b32 s100, 2
	global_store_dwordx4 v148, v[152:155], s[36:37] sc1
	v_fma_f32 v148, v56, v174, v138
	v_fma_f32 v149, v57, v174, v139
	v_fma_f32 v150, v54, v174, v136
	v_fma_f32 v151, v55, v174, v137
	v_mul_f32_e32 v153, v149, v149
	v_mul_f32_e32 v152, v151, v151
	v_fmac_f32_e32 v152, v150, v150
	v_fmac_f32_e32 v153, v148, v148
	v_fma_f32 v186, v44, v174, v134
	v_fma_f32 v187, v45, v174, v135
	v_add_f32_e32 v152, v152, v153
	v_mul_f32_e32 v153, v189, v189
	v_mul_f32_e32 v154, v187, v187
	v_fmac_f32_e32 v153, v188, v188
	v_fmac_f32_e32 v154, v186, v186
	v_add_f32_e32 v153, v153, v154
	v_fma_f32 v192, v110, v174, v140
	v_fma_f32 v193, v111, v174, v141
	v_add_f32_e32 v152, v152, v153
	v_mul_f32_e32 v153, v193, v193
	v_mul_f32_e32 v154, v191, v191
	v_fmac_f32_e32 v153, v192, v192
	v_fmac_f32_e32 v154, v190, v190
	v_xor_b32_e32 v210, 32, v214
	v_add_f32_e32 v153, v153, v154
	v_fma_f32 v194, v108, v174, v146
	v_fma_f32 v195, v109, v174, v147
	v_fma_f32 v214, v106, v174, v144
	v_fma_f32 v215, v107, v174, v145
	v_add_f32_e32 v152, v152, v153
	v_mul_f32_e32 v153, v215, v215
	v_mul_f32_e32 v154, v195, v195
	v_fmac_f32_e32 v153, v214, v214
	v_fmac_f32_e32 v154, v194, v194
	v_add_f32_e32 v153, v153, v154
	v_add_f32_e32 v152, v152, v153
	v_mov_b32_e32 v153, v152
	s_nop 1
	v_permlane16_swap_b32_e32 v152, v153
	v_add_f32_e32 v152, v152, v153
	v_mov_b32_e32 v153, v152
	s_nop 1
	v_permlane32_swap_b32_e32 v152, v153
	v_add_f32_e32 v152, v152, v153
	v_fmamk_f32 v152, v152, 0x3c800000, v229
	v_rsq_f32_e32 v216, v152
	s_and_b64 vcc, exec, s[4:5]
	v_mul_f32_e32 v150, v150, v216
	v_mul_f32_e32 v151, v151, v216
	v_mul_f32_e32 v148, v148, v216
	v_mul_f32_e32 v149, v149, v216
	v_mul_f32_e32 v152, v184, v150
	v_mul_f32_e32 v153, v185, v151
	v_mul_f32_e32 v154, v182, v148
	v_mul_f32_e32 v155, v183, v149
	v_mul_f32_e32 v148, v188, v216
	v_mul_f32_e32 v149, v189, v216
	v_mul_f32_e32 v150, v186, v216
	v_mul_f32_e32 v151, v187, v216
	v_mul_f32_e32 v188, v180, v148
	v_mul_f32_e32 v189, v181, v149
	v_mul_f32_e32 v186, v178, v150
	v_mul_f32_e32 v187, v179, v151
	v_mul_f32_e32 v148, v192, v216
	v_mul_f32_e32 v149, v193, v216
	v_mul_f32_e32 v150, v190, v216
	v_mul_f32_e32 v151, v191, v216
	v_mul_f32_e32 v192, v214, v216
	v_mul_f32_e32 v193, v215, v216
	v_mul_f32_e32 v190, v194, v216
	v_mul_f32_e32 v191, v195, v216
	v_mul_f32_e32 v150, v160, v150
	v_mul_f32_e32 v151, v161, v151
	v_mul_f32_e32 v148, v162, v148
	v_mul_f32_e32 v149, v163, v149
	v_mul_f32_e32 v190, v156, v190
	v_mul_f32_e32 v191, v157, v191
	v_mul_f32_e32 v192, v158, v192
	v_mul_f32_e32 v193, v159, v193
	v_lshlrev_b32_e32 v195, 6, v210
	s_cbranch_vccnz .LBB0_581
	v_add_u32_e32 v194, 32, v201
	v_and_b32_e32 v194, 0x7c0, v194
	v_add_u32_e32 v210, v205, v194
	v_add_u32_e32 v194, v204, v194
	ds_read_b128 v[214:217], v210
	ds_read_b128 v[218:221], v194
	v_add_u32_e32 v194, v204, v195
	s_waitcnt lgkmcnt(0)
	v_mul_f32_e32 v222, v186, v220
	v_mul_f32_e32 v223, v187, v221
	v_mul_f32_e32 v226, v188, v218
	v_mul_f32_e32 v227, v189, v219
	v_fma_f32 v224, v154, v216, -v222
	v_fma_f32 v225, v155, v217, -v223
	v_fma_f32 v222, v152, v214, -v226
	v_fma_f32 v223, v153, v215, -v227
	v_mul_f32_e32 v152, v152, v218
	v_mul_f32_e32 v153, v153, v219
	v_mul_f32_e32 v154, v154, v220
	v_mul_f32_e32 v155, v155, v221
	v_fma_f32 v188, v188, v214, v152
	v_fma_f32 v189, v189, v215, v153
	v_add_u32_e32 v152, v205, v195
	v_fma_f32 v186, v186, v216, v154
	v_fma_f32 v187, v187, v217, v155
	ds_read_b128 v[152:155], v152
	ds_read_b128 v[214:217], v194
	s_waitcnt lgkmcnt(0)
	v_mul_f32_e32 v218, v190, v216
	v_mul_f32_e32 v219, v191, v217
	v_mul_f32_e32 v226, v192, v214
	v_mul_f32_e32 v227, v193, v215
	v_fma_f32 v220, v150, v154, -v218
	v_fma_f32 v221, v151, v155, -v219
	v_fma_f32 v218, v148, v152, -v226
	v_fma_f32 v219, v149, v153, -v227
	v_mul_f32_e32 v150, v150, v216
	v_mul_f32_e32 v151, v151, v217
	v_mul_f32_e32 v148, v148, v214
	v_mul_f32_e32 v149, v149, v215
	v_fma_f32 v190, v190, v154, v150
	v_fma_f32 v191, v191, v155, v151
	v_fma_f32 v192, v192, v152, v148
	v_fma_f32 v193, v193, v153, v149
	v_mov_b64_e32 v[148:149], v[218:219]
	v_mov_b64_e32 v[152:153], v[222:223]
	v_mov_b64_e32 v[150:151], v[220:221]
	v_mov_b64_e32 v[154:155], v[224:225]
; #define LAS __attribute__((address_space(3)))
; __device__ __forceinline__ unsigned cvtpk_h(float lo, float hi) { f32x2 v = {lo, hi}; h16x2 b = __builtin_convertvector(v, h16x2); return __builtin_bit_cast(unsigned, b); }
;     __device__ __forceinline__ void operator()(const f32x4 (&acc)[2][2][4][2], const pg8::Unit& u, int wr, int wc, int fr, int fq) const {
;     ...
;             for (int m = 0; m < 4; ++m) { const float r = rs[ai][m]; f32x4 v[2][2]; float ss = 0.f;
; #pragma unroll
;                 for (int bj = 0; bj < 2; ++bj)
; #pragma unroll
;                     for (int n = 0; n < 2; ++n) { v[bj][n] = acc[ai][bj][m][n] * r + bv[bj][n]; ss += (v[bj][n][0] * v[bj][n][0] + v[bj][n][1] * v[bj][n][1]) + (v[bj][n][2] * v[bj][n][2] + v[bj][n][3] * v[bj][n][3]); }
;                 const float rn = __builtin_amdgcn_rsqf(red4(ss, fq * 16 + fr) * (1.f / 64.f) + EPS);
; #pragma unroll
;                 for (int bj = 0; bj < 2; ++bj)
; #pragma unroll
;                     for (int n = 0; n < 2; ++n) v[bj][n] = v[bj][n] * rn * g4[bj][n];
;                 if (lat) { const unsigned t = (rbase + ai * 128 + m * 16) & (SEQ - 1);
; #pragma unroll
;                     for (int bj = 0; bj < 2; ++bj) { const unsigned pos = bj ? (t & 63u) : (t >> 6); const f32x4 cs = *(const LAS f32x4*)(ropel + pos * 16u + 4u * fq), sn = *(const LAS f32x4*)(ropel + 1024u + pos * 16u + 4u * fq);
;                         const f32x4 x1 = v[bj][0], x2 = v[bj][1]; v[bj][0] = x1 * cs - x2 * sn; v[bj][1] = x2 * cs + x1 * sn; } }
;                 const unsigned ro = offA + (unsigned)(ai * 8 + m) * 32u * pitch;
;                 u32x4 w[2];
; #pragma unroll
;                 for (int bj = 0; bj < 2; ++bj) { w[bj].x = cvtpk_h(v[bj][0][0], v[bj][0][1]); w[bj].y = cvtpk_h(v[bj][0][2], v[bj][0][3]); w[bj].z = cvtpk_h(v[bj][1][0], v[bj][1][1]); w[bj].w = cvtpk_h(v[bj][1][2], v[bj][1][3]); }
;                 stg_line_pair(wst, ro, 2u * pitch, w[0], w[1], odd);
;                 asm volatile("" ::: "memory"); }
.LBB0_581:
	v_cvt_pk_f16_f32 v152, v152, v153
	v_cvt_pk_f16_f32 v153, v154, v155
	v_cvt_pk_f16_f32 v154, v188, v189
	v_cvt_pk_f16_f32 v149, v148, v149
	v_mov_b32_e32 v148, v1
	v_mov_b32_e32 v188, v1
	v_cvt_pk_f16_f32 v150, v150, v151
	v_mov_b32_dpp v148, v149 quad_perm:[1,0,3,2] row_mask:0xf bank_mask:0xf
	v_mov_b32_dpp v188, v152 quad_perm:[1,0,3,2] row_mask:0xf bank_mask:0xf
	v_cndmask_b32_e64 v148, v148, v152, s[2:3]
	v_cndmask_b32_e64 v152, v149, v188, s[2:3]
	v_mov_b32_e32 v149, v1
	v_mov_b32_e32 v188, v1
	v_cvt_pk_f16_f32 v151, v192, v193
	v_mov_b32_dpp v149, v150 quad_perm:[1,0,3,2] row_mask:0xf bank_mask:0xf
	v_mov_b32_dpp v188, v153 quad_perm:[1,0,3,2] row_mask:0xf bank_mask:0xf
	v_cndmask_b32_e64 v149, v149, v153, s[2:3]
	v_cndmask_b32_e64 v153, v150, v188, s[2:3]
	v_mov_b32_e32 v150, v1
	v_mov_b32_e32 v188, v1
	v_cvt_pk_f16_f32 v155, v186, v187
	v_mov_b32_dpp v150, v151 quad_perm:[1,0,3,2] row_mask:0xf bank_mask:0xf
	v_mov_b32_dpp v188, v154 quad_perm:[1,0,3,2] row_mask:0xf bank_mask:0xf
	v_cvt_pk_f16_f32 v186, v190, v191
	v_cndmask_b32_e64 v150, v150, v154, s[2:3]
	v_cndmask_b32_e64 v154, v151, v188, s[2:3]
	v_mov_b32_e32 v151, v1
	v_mov_b32_e32 v188, v1
	v_lshl_add_u32 v187, 64, s42, v206
	v_mov_b32_dpp v151, v186 quad_perm:[1,0,3,2] row_mask:0xf bank_mask:0xf
	v_mov_b32_dpp v188, v155 quad_perm:[1,0,3,2] row_mask:0xf bank_mask:0xf
	v_cndmask_b32_e64 v151, v151, v155, s[2:3]
	v_cndmask_b32_e64 v155, v186, v188, s[2:3]
	s_mov_b32 s100, 2
	global_store_dwordx4 v187, v[148:151], s[36:37] sc1
	v_add_u32_e32 v194, 48, v202
	v_and_b32_e32 v210, 63, v194
	v_add_u32_e32 v148, s9, v187
	s_mov_b32 s100, 2
	global_store_dwordx4 v148, v[152:155], s[36:37] sc1
	v_mov_b32_e32 v148, v175
	v_fma_f32 v150, v40, v148, v138
	v_fma_f32 v151, v41, v148, v139
	v_fma_f32 v152, v38, v148, v136
	v_fma_f32 v153, v39, v148, v137
	v_mul_f32_e32 v154, v151, v151
	v_mul_f32_e32 v149, v153, v153
	v_fmac_f32_e32 v149, v152, v152
	v_fmac_f32_e32 v154, v150, v150
	v_add_f32_e32 v149, v149, v154
	v_fma_f32 v186, v36, v148, v134
	v_fma_f32 v187, v37, v148, v135
	v_fma_f32 v188, v34, v148, v132
	v_fma_f32 v189, v35, v148, v133
	v_mul_f32_e32 v155, v187, v187
	v_mul_f32_e32 v154, v189, v189
	v_fmac_f32_e32 v154, v188, v188
	v_fmac_f32_e32 v155, v186, v186
	v_add_f32_e32 v154, v154, v155
	v_add_f32_e32 v149, v149, v154
	v_fma_f32 v190, v104, v148, v142
	v_fma_f32 v191, v105, v148, v143
	v_fma_f32 v192, v102, v148, v140
	v_fma_f32 v193, v103, v148, v141
	v_mul_f32_e32 v155, v191, v191
	v_mul_f32_e32 v154, v193, v193
	v_fmac_f32_e32 v154, v192, v192
	v_fmac_f32_e32 v155, v190, v190
	v_add_f32_e32 v154, v154, v155
	v_add_f32_e32 v149, v149, v154
	v_fma_f32 v214, v100, v148, v146
	v_fma_f32 v215, v101, v148, v147
	v_fma_f32 v216, v98, v148, v144
	v_fma_f32 v217, v99, v148, v145
	v_mul_f32_e32 v154, v215, v215
	v_mul_f32_e32 v148, v217, v217
	v_fmac_f32_e32 v148, v216, v216
	v_fmac_f32_e32 v154, v214, v214
	v_add_f32_e32 v148, v148, v154
	v_add_f32_e32 v148, v149, v148
	v_mov_b32_e32 v149, v148
	s_nop 1
	v_permlane16_swap_b32_e32 v148, v149
	v_add_f32_e32 v148, v148, v149
	v_mov_b32_e32 v149, v148
	s_nop 1
	v_permlane32_swap_b32_e32 v148, v149
	v_add_f32_e32 v148, v148, v149
	v_fmamk_f32 v148, v148, 0x3c800000, v229
	v_rsq_f32_e32 v194, v148
	s_and_b64 vcc, exec, s[4:5]
	v_mul_f32_e32 v148, v152, v194
	v_mul_f32_e32 v149, v153, v194
	v_mul_f32_e32 v150, v150, v194
	v_mul_f32_e32 v151, v151, v194
	v_mul_f32_e32 v152, v184, v148
	v_mul_f32_e32 v153, v185, v149
	v_mul_f32_e32 v154, v182, v150
	v_mul_f32_e32 v155, v183, v151
	v_mul_f32_e32 v148, v188, v194
	v_mul_f32_e32 v149, v189, v194
	v_mul_f32_e32 v150, v186, v194
	v_mul_f32_e32 v151, v187, v194
	v_mul_f32_e32 v188, v180, v148
	v_mul_f32_e32 v189, v181, v149
	v_mul_f32_e32 v186, v178, v150
	v_mul_f32_e32 v187, v179, v151
	v_mul_f32_e32 v148, v192, v194
	v_mul_f32_e32 v149, v193, v194
	v_mul_f32_e32 v150, v190, v194
	v_mul_f32_e32 v151, v191, v194
	v_mul_f32_e32 v192, v216, v194
	v_mul_f32_e32 v193, v217, v194
	v_mul_f32_e32 v190, v214, v194
	v_mul_f32_e32 v191, v215, v194
	v_mul_f32_e32 v150, v160, v150
	v_mul_f32_e32 v151, v161, v151
	v_mul_f32_e32 v148, v162, v148
	v_mul_f32_e32 v149, v163, v149
	v_mul_f32_e32 v190, v156, v190
	v_mul_f32_e32 v191, v157, v191
	v_mul_f32_e32 v192, v158, v192
	v_mul_f32_e32 v193, v159, v193
	v_lshlrev_b32_e32 v194, 6, v210
	s_cbranch_vccnz .LBB0_583
	v_add_u32_e32 v210, 48, v201
	v_and_b32_e32 v210, 0x7c0, v210
	v_add_u32_e32 v211, v205, v210
	v_add_u32_e32 v210, v204, v210
	ds_read_b128 v[214:217], v211
	ds_read_b128 v[218:221], v210
	v_add_u32_e32 v210, v204, v194
	s_waitcnt lgkmcnt(0)
	v_mul_f32_e32 v222, v186, v220
	v_mul_f32_e32 v223, v187, v221
	v_mul_f32_e32 v226, v188, v218
	v_mul_f32_e32 v227, v189, v219
	v_fma_f32 v224, v154, v216, -v222
	v_fma_f32 v225, v155, v217, -v223
	v_fma_f32 v222, v152, v214, -v226
	v_fma_f32 v223, v153, v215, -v227
	v_mul_f32_e32 v152, v152, v218
	v_mul_f32_e32 v153, v153, v219
	v_mul_f32_e32 v154, v154, v220
	v_mul_f32_e32 v155, v155, v221
	v_fma_f32 v188, v188, v214, v152
	v_fma_f32 v189, v189, v215, v153
	v_add_u32_e32 v152, v205, v194
	v_fma_f32 v186, v186, v216, v154
	v_fma_f32 v187, v187, v217, v155
	ds_read_b128 v[152:155], v152
	ds_read_b128 v[214:217], v210
	s_waitcnt lgkmcnt(0)
	v_mul_f32_e32 v218, v190, v216
	v_mul_f32_e32 v219, v191, v217
	v_mul_f32_e32 v226, v192, v214
	v_mul_f32_e32 v227, v193, v215
	v_fma_f32 v220, v150, v154, -v218
	v_fma_f32 v221, v151, v155, -v219
	v_fma_f32 v218, v148, v152, -v226
	v_fma_f32 v219, v149, v153, -v227
	v_mul_f32_e32 v150, v150, v216
	v_mul_f32_e32 v151, v151, v217
	v_mul_f32_e32 v148, v148, v214
	v_mul_f32_e32 v149, v149, v215
	v_fma_f32 v190, v190, v154, v150
	v_fma_f32 v191, v191, v155, v151
	v_fma_f32 v192, v192, v152, v148
	v_fma_f32 v193, v193, v153, v149
	v_mov_b64_e32 v[148:149], v[218:219]
	v_mov_b64_e32 v[152:153], v[222:223]
	v_mov_b64_e32 v[150:151], v[220:221]
	v_mov_b64_e32 v[154:155], v[224:225]
; #define LAS __attribute__((address_space(3)))
; __device__ __forceinline__ unsigned cvtpk_h(float lo, float hi) { f32x2 v = {lo, hi}; h16x2 b = __builtin_convertvector(v, h16x2); return __builtin_bit_cast(unsigned, b); }
;     __device__ __forceinline__ void operator()(const f32x4 (&acc)[2][2][4][2], const pg8::Unit& u, int wr, int wc, int fr, int fq) const {
;     ...
;             for (int m = 0; m < 4; ++m) { const float r = rs[ai][m]; f32x4 v[2][2]; float ss = 0.f;
; #pragma unroll
;                 for (int bj = 0; bj < 2; ++bj)
; #pragma unroll
;                     for (int n = 0; n < 2; ++n) { v[bj][n] = acc[ai][bj][m][n] * r + bv[bj][n]; ss += (v[bj][n][0] * v[bj][n][0] + v[bj][n][1] * v[bj][n][1]) + (v[bj][n][2] * v[bj][n][2] + v[bj][n][3] * v[bj][n][3]); }
;                 const float rn = __builtin_amdgcn_rsqf(red4(ss, fq * 16 + fr) * (1.f / 64.f) + EPS);
; #pragma unroll
;                 for (int bj = 0; bj < 2; ++bj)
; #pragma unroll
;                     for (int n = 0; n < 2; ++n) v[bj][n] = v[bj][n] * rn * g4[bj][n];
;                 if (lat) { const unsigned t = (rbase + ai * 128 + m * 16) & (SEQ - 1);
; #pragma unroll
;                     for (int bj = 0; bj < 2; ++bj) { const unsigned pos = bj ? (t & 63u) : (t >> 6); const f32x4 cs = *(const LAS f32x4*)(ropel + pos * 16u + 4u * fq), sn = *(const LAS f32x4*)(ropel + 1024u + pos * 16u + 4u * fq);
;                         const f32x4 x1 = v[bj][0], x2 = v[bj][1]; v[bj][0] = x1 * cs - x2 * sn; v[bj][1] = x2 * cs + x1 * sn; } }
;                 const unsigned ro = offA + (unsigned)(ai * 8 + m) * 32u * pitch;
;                 u32x4 w[2];
; #pragma unroll
;                 for (int bj = 0; bj < 2; ++bj) { w[bj].x = cvtpk_h(v[bj][0][0], v[bj][0][1]); w[bj].y = cvtpk_h(v[bj][0][2], v[bj][0][3]); w[bj].z = cvtpk_h(v[bj][1][0], v[bj][1][1]); w[bj].w = cvtpk_h(v[bj][1][2], v[bj][1][3]); }
;                 stg_line_pair(wst, ro, 2u * pitch, w[0], w[1], odd);
;                 asm volatile("" ::: "memory"); }
.LBB0_583:
	v_cvt_pk_f16_f32 v152, v152, v153
	v_cvt_pk_f16_f32 v153, v154, v155
	v_cvt_pk_f16_f32 v154, v188, v189
	v_cvt_pk_f16_f32 v149, v148, v149
	v_mov_b32_e32 v148, v1
	v_mov_b32_e32 v188, v1
	v_cvt_pk_f16_f32 v150, v150, v151
	v_mov_b32_dpp v148, v149 quad_perm:[1,0,3,2] row_mask:0xf bank_mask:0xf
	v_mov_b32_dpp v188, v152 quad_perm:[1,0,3,2] row_mask:0xf bank_mask:0xf
	v_cndmask_b32_e64 v148, v148, v152, s[2:3]
	v_cndmask_b32_e64 v152, v149, v188, s[2:3]
	v_mov_b32_e32 v149, v1
	v_mov_b32_e32 v188, v1
	v_cvt_pk_f16_f32 v151, v192, v193
	v_mov_b32_dpp v149, v150 quad_perm:[1,0,3,2] row_mask:0xf bank_mask:0xf
	v_mov_b32_dpp v188, v153 quad_perm:[1,0,3,2] row_mask:0xf bank_mask:0xf
	v_cndmask_b32_e64 v149, v149, v153, s[2:3]
	v_cndmask_b32_e64 v153, v150, v188, s[2:3]
	v_mov_b32_e32 v150, v1
	v_mov_b32_e32 v188, v1
	v_cvt_pk_f16_f32 v155, v186, v187
	v_mov_b32_dpp v150, v151 quad_perm:[1,0,3,2] row_mask:0xf bank_mask:0xf
	v_mov_b32_dpp v188, v154 quad_perm:[1,0,3,2] row_mask:0xf bank_mask:0xf
	v_cvt_pk_f16_f32 v186, v190, v191
	v_cndmask_b32_e64 v150, v150, v154, s[2:3]
	v_cndmask_b32_e64 v154, v151, v188, s[2:3]
	v_mov_b32_e32 v151, v1
	s_lshl_b32 s38, 0x60, s42
	v_mov_b32_e32 v188, v1
	v_mov_b32_dpp v151, v186 quad_perm:[1,0,3,2] row_mask:0xf bank_mask:0xf
	v_add_u32_e32 v187, s38, v206
	v_mov_b32_dpp v188, v155 quad_perm:[1,0,3,2] row_mask:0xf bank_mask:0xf
	v_cndmask_b32_e64 v151, v151, v155, s[2:3]
	v_cndmask_b32_e64 v155, v186, v188, s[2:3]
	s_mov_b32 s100, 2
	global_store_dwordx4 v187, v[148:151], s[36:37] sc1
	v_fma_f32 v188, v26, v172, v132
	v_fma_f32 v189, v27, v172, v133
	v_fma_f32 v190, v96, v172, v142
	v_fma_f32 v191, v97, v172, v143
	v_add_u32_e32 v148, s9, v187
	s_mov_b32 s100, 2
	global_store_dwordx4 v148, v[152:155], s[36:37] sc1
	v_fma_f32 v148, v32, v172, v138
	v_fma_f32 v149, v33, v172, v139
	v_fma_f32 v150, v30, v172, v136
	v_fma_f32 v151, v31, v172, v137
	v_mul_f32_e32 v153, v149, v149
	v_mul_f32_e32 v152, v151, v151
	v_fmac_f32_e32 v152, v150, v150
	v_fmac_f32_e32 v153, v148, v148
	v_fma_f32 v186, v28, v172, v134
	v_fma_f32 v187, v29, v172, v135
	v_add_f32_e32 v152, v152, v153
	v_mul_f32_e32 v153, v189, v189
	v_mul_f32_e32 v154, v187, v187
	v_fmac_f32_e32 v153, v188, v188
	v_fmac_f32_e32 v154, v186, v186
	v_add_f32_e32 v153, v153, v154
	v_fma_f32 v192, v94, v172, v140
	v_fma_f32 v193, v95, v172, v141
	v_add_f32_e32 v152, v152, v153
	v_mul_f32_e32 v153, v193, v193
	v_mul_f32_e32 v154, v191, v191
	v_fmac_f32_e32 v153, v192, v192
	v_fmac_f32_e32 v154, v190, v190
	v_add_f32_e32 v153, v153, v154
	v_fma_f32 v214, v92, v172, v146
	v_fma_f32 v215, v93, v172, v147
	v_fma_f32 v216, v90, v172, v144
	v_fma_f32 v217, v91, v172, v145
	v_add_f32_e32 v152, v153, v152
	v_mul_f32_e32 v153, v217, v217
	v_mul_f32_e32 v154, v215, v215
	v_fmac_f32_e32 v153, v216, v216
	v_fmac_f32_e32 v154, v214, v214
	v_add_f32_e32 v153, v153, v154
	v_add_f32_e32 v152, v153, v152
	v_mov_b32_e32 v153, v152
	s_nop 1
	v_permlane16_swap_b32_e32 v152, v153
	v_add_f32_e32 v152, v152, v153
	v_mov_b32_e32 v153, v152
	s_nop 1
	v_permlane32_swap_b32_e32 v152, v153
	v_add_f32_e32 v152, v152, v153
	v_fmamk_f32 v152, v152, 0x3c800000, v229
	v_rsq_f32_e32 v218, v152
	s_and_b64 vcc, exec, s[4:5]
	v_mul_f32_e32 v150, v150, v218
	v_mul_f32_e32 v151, v151, v218
	v_mul_f32_e32 v148, v148, v218
	v_mul_f32_e32 v149, v149, v218
	v_mul_f32_e32 v152, v184, v150
	v_mul_f32_e32 v153, v185, v151
	v_mul_f32_e32 v154, v182, v148
	v_mul_f32_e32 v155, v183, v149
	v_mul_f32_e32 v148, v188, v218
	v_mul_f32_e32 v149, v189, v218
	v_mul_f32_e32 v150, v186, v218
	v_mul_f32_e32 v151, v187, v218
	v_mul_f32_e32 v188, v180, v148
	v_mul_f32_e32 v189, v181, v149
	v_mul_f32_e32 v186, v178, v150
	v_mul_f32_e32 v187, v179, v151
	v_mul_f32_e32 v148, v192, v218
	v_mul_f32_e32 v149, v193, v218
	v_mul_f32_e32 v150, v190, v218
	v_mul_f32_e32 v151, v191, v218
	v_mul_f32_e32 v192, v216, v218
	v_mul_f32_e32 v193, v217, v218
	v_mul_f32_e32 v190, v214, v218
	v_mul_f32_e32 v191, v215, v218
	v_mul_f32_e32 v150, v160, v150
	v_mul_f32_e32 v151, v161, v151
	v_mul_f32_e32 v148, v162, v148
	v_mul_f32_e32 v149, v163, v149
	v_mul_f32_e32 v190, v156, v190
	v_mul_f32_e32 v191, v157, v191
	v_mul_f32_e32 v192, v158, v192
	v_mul_f32_e32 v193, v159, v193
	s_cbranch_vccnz .LBB0_585
	v_add_u32_e32 v210, 0x80, v201
	v_and_b32_e32 v210, 0x7c0, v210
	v_add_u32_e32 v211, v205, v210
	v_add_u32_e32 v210, v204, v210
	ds_read_b128 v[214:217], v211
	ds_read_b128 v[218:221], v210
	s_waitcnt lgkmcnt(0)
	v_mul_f32_e32 v222, v186, v220
	v_mul_f32_e32 v223, v187, v221
	v_mul_f32_e32 v226, v188, v218
	v_mul_f32_e32 v227, v189, v219
	v_fma_f32 v224, v154, v216, -v222
	v_fma_f32 v225, v155, v217, -v223
	v_fma_f32 v222, v152, v214, -v226
	v_fma_f32 v223, v153, v215, -v227
	v_mul_f32_e32 v152, v152, v218
	v_mul_f32_e32 v153, v153, v219
	v_mul_f32_e32 v154, v154, v220
	v_mul_f32_e32 v155, v155, v221
	v_fma_f32 v188, v188, v214, v152
	v_fma_f32 v189, v189, v215, v153
	v_add_u32_e32 v152, v205, v207
	v_add_u32_e32 v207, v204, v207
	v_fma_f32 v186, v186, v216, v154
	v_fma_f32 v187, v187, v217, v155
	ds_read_b128 v[152:155], v152
	ds_read_b128 v[214:217], v207
	s_waitcnt lgkmcnt(0)
	v_mul_f32_e32 v218, v190, v216
	v_mul_f32_e32 v219, v191, v217
	v_mul_f32_e32 v226, v192, v214
	v_mul_f32_e32 v227, v193, v215
	v_fma_f32 v220, v150, v154, -v218
	v_fma_f32 v221, v151, v155, -v219
	v_fma_f32 v218, v148, v152, -v226
	v_fma_f32 v219, v149, v153, -v227
	v_mul_f32_e32 v150, v150, v216
	v_mul_f32_e32 v151, v151, v217
	v_mul_f32_e32 v148, v148, v214
	v_mul_f32_e32 v149, v149, v215
	v_fma_f32 v190, v190, v154, v150
	v_fma_f32 v191, v191, v155, v151
	v_fma_f32 v192, v192, v152, v148
	v_fma_f32 v193, v193, v153, v149
	v_mov_b64_e32 v[148:149], v[218:219]
	v_mov_b64_e32 v[152:153], v[222:223]
	v_mov_b64_e32 v[150:151], v[220:221]
	v_mov_b64_e32 v[154:155], v[224:225]
; #define LAS __attribute__((address_space(3)))
; __device__ __forceinline__ unsigned cvtpk_h(float lo, float hi) { f32x2 v = {lo, hi}; h16x2 b = __builtin_convertvector(v, h16x2); return __builtin_bit_cast(unsigned, b); }
;     __device__ __forceinline__ void operator()(const f32x4 (&acc)[2][2][4][2], const pg8::Unit& u, int wr, int wc, int fr, int fq) const {
;     ...
;             for (int m = 0; m < 4; ++m) { const float r = rs[ai][m]; f32x4 v[2][2]; float ss = 0.f;
; #pragma unroll
;                 for (int bj = 0; bj < 2; ++bj)
; #pragma unroll
;                     for (int n = 0; n < 2; ++n) { v[bj][n] = acc[ai][bj][m][n] * r + bv[bj][n]; ss += (v[bj][n][0] * v[bj][n][0] + v[bj][n][1] * v[bj][n][1]) + (v[bj][n][2] * v[bj][n][2] + v[bj][n][3] * v[bj][n][3]); }
;                 const float rn = __builtin_amdgcn_rsqf(red4(ss, fq * 16 + fr) * (1.f / 64.f) + EPS);
; #pragma unroll
;                 for (int bj = 0; bj < 2; ++bj)
; #pragma unroll
;                     for (int n = 0; n < 2; ++n) v[bj][n] = v[bj][n] * rn * g4[bj][n];
;                 if (lat) { const unsigned t = (rbase + ai * 128 + m * 16) & (SEQ - 1);
; #pragma unroll
;                     for (int bj = 0; bj < 2; ++bj) { const unsigned pos = bj ? (t & 63u) : (t >> 6); const f32x4 cs = *(const LAS f32x4*)(ropel + pos * 16u + 4u * fq), sn = *(const LAS f32x4*)(ropel + 1024u + pos * 16u + 4u * fq);
;                         const f32x4 x1 = v[bj][0], x2 = v[bj][1]; v[bj][0] = x1 * cs - x2 * sn; v[bj][1] = x2 * cs + x1 * sn; } }
;                 const unsigned ro = offA + (unsigned)(ai * 8 + m) * 32u * pitch;
;                 u32x4 w[2];
; #pragma unroll
;                 for (int bj = 0; bj < 2; ++bj) { w[bj].x = cvtpk_h(v[bj][0][0], v[bj][0][1]); w[bj].y = cvtpk_h(v[bj][0][2], v[bj][0][3]); w[bj].z = cvtpk_h(v[bj][1][0], v[bj][1][1]); w[bj].w = cvtpk_h(v[bj][1][2], v[bj][1][3]); }
;                 stg_line_pair(wst, ro, 2u * pitch, w[0], w[1], odd);
;                 asm volatile("" ::: "memory"); }
.LBB0_585:
	v_cvt_pk_f16_f32 v152, v152, v153
	v_cvt_pk_f16_f32 v153, v154, v155
	v_cvt_pk_f16_f32 v154, v188, v189
	v_cvt_pk_f16_f32 v149, v148, v149
	v_mov_b32_e32 v148, v1
	v_mov_b32_e32 v188, v1
	v_cvt_pk_f16_f32 v150, v150, v151
	v_mov_b32_dpp v148, v149 quad_perm:[1,0,3,2] row_mask:0xf bank_mask:0xf
	v_mov_b32_dpp v188, v152 quad_perm:[1,0,3,2] row_mask:0xf bank_mask:0xf
	v_cndmask_b32_e64 v148, v148, v152, s[2:3]
	v_cndmask_b32_e64 v152, v149, v188, s[2:3]
	v_mov_b32_e32 v149, v1
	v_mov_b32_e32 v188, v1
	v_cvt_pk_f16_f32 v151, v192, v193
	v_mov_b32_dpp v149, v150 quad_perm:[1,0,3,2] row_mask:0xf bank_mask:0xf
	v_mov_b32_dpp v188, v153 quad_perm:[1,0,3,2] row_mask:0xf bank_mask:0xf
	v_cndmask_b32_e64 v149, v149, v153, s[2:3]
	v_cndmask_b32_e64 v153, v150, v188, s[2:3]
	v_mov_b32_e32 v150, v1
	v_mov_b32_e32 v188, v1
	v_cvt_pk_f16_f32 v155, v186, v187
	v_mov_b32_dpp v150, v151 quad_perm:[1,0,3,2] row_mask:0xf bank_mask:0xf
	v_mov_b32_dpp v188, v154 quad_perm:[1,0,3,2] row_mask:0xf bank_mask:0xf
	v_cvt_pk_f16_f32 v186, v190, v191
	v_cndmask_b32_e64 v150, v150, v154, s[2:3]
	v_cndmask_b32_e64 v154, v151, v188, s[2:3]
	v_mov_b32_e32 v151, v1
	s_lshl_b32 s38, 0x100, s42
	v_mov_b32_e32 v188, v1
	v_mov_b32_dpp v151, v186 quad_perm:[1,0,3,2] row_mask:0xf bank_mask:0xf
	v_add_u32_e32 v187, s38, v206
	v_mov_b32_dpp v188, v155 quad_perm:[1,0,3,2] row_mask:0xf bank_mask:0xf
	v_cndmask_b32_e64 v151, v151, v155, s[2:3]
	v_cndmask_b32_e64 v155, v186, v188, s[2:3]
	s_mov_b32 s100, 2
	global_store_dwordx4 v187, v[148:151], s[36:37] sc1
	s_and_b64 vcc, exec, s[4:5]
	s_nop 0
	v_add_u32_e32 v148, s9, v187
	s_mov_b32 s100, 2
	global_store_dwordx4 v148, v[152:155], s[36:37] sc1
	v_mov_b32_e32 v148, v173
	v_fma_f32 v150, v24, v148, v138
	v_fma_f32 v151, v25, v148, v139
	v_fma_f32 v152, v22, v148, v136
	v_fma_f32 v153, v23, v148, v137
	v_mul_f32_e32 v154, v151, v151
	v_mul_f32_e32 v149, v153, v153
	v_fmac_f32_e32 v149, v152, v152
	v_fmac_f32_e32 v154, v150, v150
	v_add_f32_e32 v149, v149, v154
	v_fma_f32 v186, v20, v148, v134
	v_fma_f32 v187, v21, v148, v135
	v_fma_f32 v188, v18, v148, v132
	v_fma_f32 v189, v19, v148, v133
	v_mul_f32_e32 v155, v187, v187
	v_mul_f32_e32 v154, v189, v189
	v_fmac_f32_e32 v154, v188, v188
	v_fmac_f32_e32 v155, v186, v186
	v_add_f32_e32 v154, v154, v155
	v_add_f32_e32 v149, v149, v154
	v_fma_f32 v190, v88, v148, v142
	v_fma_f32 v191, v89, v148, v143
	v_fma_f32 v192, v86, v148, v140
	v_fma_f32 v193, v87, v148, v141
	v_mul_f32_e32 v155, v191, v191
	v_mul_f32_e32 v154, v193, v193
	v_fmac_f32_e32 v154, v192, v192
	v_fmac_f32_e32 v155, v190, v190
	v_add_f32_e32 v154, v154, v155
	v_add_f32_e32 v149, v154, v149
	v_fma_f32 v214, v84, v148, v146
	v_fma_f32 v215, v85, v148, v147
	v_fma_f32 v216, v82, v148, v144
	v_fma_f32 v217, v83, v148, v145
	v_mul_f32_e32 v154, v215, v215
	v_mul_f32_e32 v148, v217, v217
	v_fmac_f32_e32 v148, v216, v216
	v_fmac_f32_e32 v154, v214, v214
	v_add_f32_e32 v148, v148, v154
	v_add_f32_e32 v148, v148, v149
	v_mov_b32_e32 v149, v148
	s_nop 1
	v_permlane16_swap_b32_e32 v148, v149
	v_add_f32_e32 v148, v148, v149
	v_mov_b32_e32 v149, v148
	s_nop 1
	v_permlane32_swap_b32_e32 v148, v149
	v_add_f32_e32 v148, v148, v149
	v_fmamk_f32 v148, v148, 0x3c800000, v229
	v_rsq_f32_e32 v218, v148
	s_nop 0
	v_mul_f32_e32 v148, v152, v218
	v_mul_f32_e32 v149, v153, v218
	v_mul_f32_e32 v150, v150, v218
	v_mul_f32_e32 v151, v151, v218
	v_mul_f32_e32 v152, v184, v148
	v_mul_f32_e32 v153, v185, v149
	v_mul_f32_e32 v154, v182, v150
	v_mul_f32_e32 v155, v183, v151
	v_mul_f32_e32 v148, v188, v218
	v_mul_f32_e32 v149, v189, v218
	v_mul_f32_e32 v150, v186, v218
	v_mul_f32_e32 v151, v187, v218
	v_mul_f32_e32 v188, v180, v148
	v_mul_f32_e32 v189, v181, v149
	v_mul_f32_e32 v186, v178, v150
	v_mul_f32_e32 v187, v179, v151
	v_mul_f32_e32 v148, v192, v218
	v_mul_f32_e32 v149, v193, v218
	v_mul_f32_e32 v150, v190, v218
	v_mul_f32_e32 v151, v191, v218
	v_mul_f32_e32 v192, v216, v218
	v_mul_f32_e32 v193, v217, v218
	v_mul_f32_e32 v190, v214, v218
	v_mul_f32_e32 v191, v215, v218
	v_mul_f32_e32 v150, v160, v150
	v_mul_f32_e32 v151, v161, v151
	v_mul_f32_e32 v148, v162, v148
	v_mul_f32_e32 v149, v163, v149
	v_mul_f32_e32 v190, v156, v190
	v_mul_f32_e32 v191, v157, v191
	v_mul_f32_e32 v192, v158, v192
	v_mul_f32_e32 v193, v159, v193
	s_cbranch_vccnz .LBB0_587
	v_add_u32_e32 v207, 0x90, v201
	v_and_b32_e32 v207, 0x7c0, v207
	v_add_u32_e32 v210, v205, v207
	v_add_u32_e32 v207, v204, v207
	ds_read_b128 v[214:217], v210
	ds_read_b128 v[218:221], v207
	v_add_u32_e32 v207, v204, v213
	s_waitcnt lgkmcnt(0)
	v_mul_f32_e32 v222, v186, v220
	v_mul_f32_e32 v223, v187, v221
	v_mul_f32_e32 v226, v188, v218
	v_mul_f32_e32 v227, v189, v219
	v_fma_f32 v224, v154, v216, -v222
	v_fma_f32 v225, v155, v217, -v223
	v_fma_f32 v222, v152, v214, -v226
	v_fma_f32 v223, v153, v215, -v227
	v_mul_f32_e32 v152, v152, v218
	v_mul_f32_e32 v153, v153, v219
	v_mul_f32_e32 v154, v154, v220
	v_mul_f32_e32 v155, v155, v221
	v_fma_f32 v188, v188, v214, v152
	v_fma_f32 v189, v189, v215, v153
	v_add_u32_e32 v152, v205, v213
	v_fma_f32 v186, v186, v216, v154
	v_fma_f32 v187, v187, v217, v155
	ds_read_b128 v[152:155], v152
	ds_read_b128 v[214:217], v207
	s_waitcnt lgkmcnt(0)
	v_mul_f32_e32 v218, v190, v216
	v_mul_f32_e32 v219, v191, v217
	v_mul_f32_e32 v226, v192, v214
	v_mul_f32_e32 v227, v193, v215
	v_fma_f32 v220, v150, v154, -v218
	v_fma_f32 v221, v151, v155, -v219
	v_fma_f32 v218, v148, v152, -v226
	v_fma_f32 v219, v149, v153, -v227
	v_mul_f32_e32 v150, v150, v216
	v_mul_f32_e32 v151, v151, v217
	v_mul_f32_e32 v148, v148, v214
	v_mul_f32_e32 v149, v149, v215
	v_fma_f32 v190, v190, v154, v150
	v_fma_f32 v191, v191, v155, v151
	v_fma_f32 v192, v192, v152, v148
	v_fma_f32 v193, v193, v153, v149
	v_mov_b64_e32 v[148:149], v[218:219]
	v_mov_b64_e32 v[152:153], v[222:223]
	v_mov_b64_e32 v[150:151], v[220:221]
	v_mov_b64_e32 v[154:155], v[224:225]
; #define LAS __attribute__((address_space(3)))
; __device__ __forceinline__ unsigned cvtpk_h(float lo, float hi) { f32x2 v = {lo, hi}; h16x2 b = __builtin_convertvector(v, h16x2); return __builtin_bit_cast(unsigned, b); }
;     __device__ __forceinline__ void operator()(const f32x4 (&acc)[2][2][4][2], const pg8::Unit& u, int wr, int wc, int fr, int fq) const {
;     ...
;             for (int m = 0; m < 4; ++m) { const float r = rs[ai][m]; f32x4 v[2][2]; float ss = 0.f;
; #pragma unroll
;                 for (int bj = 0; bj < 2; ++bj)
; #pragma unroll
;                     for (int n = 0; n < 2; ++n) { v[bj][n] = acc[ai][bj][m][n] * r + bv[bj][n]; ss += (v[bj][n][0] * v[bj][n][0] + v[bj][n][1] * v[bj][n][1]) + (v[bj][n][2] * v[bj][n][2] + v[bj][n][3] * v[bj][n][3]); }
;                 const float rn = __builtin_amdgcn_rsqf(red4(ss, fq * 16 + fr) * (1.f / 64.f) + EPS);
; #pragma unroll
;                 for (int bj = 0; bj < 2; ++bj)
; #pragma unroll
;                     for (int n = 0; n < 2; ++n) v[bj][n] = v[bj][n] * rn * g4[bj][n];
;                 if (lat) { const unsigned t = (rbase + ai * 128 + m * 16) & (SEQ - 1);
; #pragma unroll
;                     for (int bj = 0; bj < 2; ++bj) { const unsigned pos = bj ? (t & 63u) : (t >> 6); const f32x4 cs = *(const LAS f32x4*)(ropel + pos * 16u + 4u * fq), sn = *(const LAS f32x4*)(ropel + 1024u + pos * 16u + 4u * fq);
;                         const f32x4 x1 = v[bj][0], x2 = v[bj][1]; v[bj][0] = x1 * cs - x2 * sn; v[bj][1] = x2 * cs + x1 * sn; } }
;                 const unsigned ro = offA + (unsigned)(ai * 8 + m) * 32u * pitch;
;                 u32x4 w[2];
; #pragma unroll
;                 for (int bj = 0; bj < 2; ++bj) { w[bj].x = cvtpk_h(v[bj][0][0], v[bj][0][1]); w[bj].y = cvtpk_h(v[bj][0][2], v[bj][0][3]); w[bj].z = cvtpk_h(v[bj][1][0], v[bj][1][1]); w[bj].w = cvtpk_h(v[bj][1][2], v[bj][1][3]); }
;                 stg_line_pair(wst, ro, 2u * pitch, w[0], w[1], odd);
;                 asm volatile("" ::: "memory"); }
.LBB0_587:
	v_cvt_pk_f16_f32 v152, v152, v153
	v_cvt_pk_f16_f32 v153, v154, v155
	v_cvt_pk_f16_f32 v154, v188, v189
	v_cvt_pk_f16_f32 v149, v148, v149
	v_mov_b32_e32 v148, v1
	v_mov_b32_e32 v188, v1
	v_cvt_pk_f16_f32 v150, v150, v151
	v_mov_b32_dpp v148, v149 quad_perm:[1,0,3,2] row_mask:0xf bank_mask:0xf
	v_mov_b32_dpp v188, v152 quad_perm:[1,0,3,2] row_mask:0xf bank_mask:0xf
	v_cndmask_b32_e64 v148, v148, v152, s[2:3]
	v_cndmask_b32_e64 v152, v149, v188, s[2:3]
	v_mov_b32_e32 v149, v1
	v_mov_b32_e32 v188, v1
	v_cvt_pk_f16_f32 v151, v192, v193
	v_mov_b32_dpp v149, v150 quad_perm:[1,0,3,2] row_mask:0xf bank_mask:0xf
	v_mov_b32_dpp v188, v153 quad_perm:[1,0,3,2] row_mask:0xf bank_mask:0xf
	v_cndmask_b32_e64 v149, v149, v153, s[2:3]
	v_cndmask_b32_e64 v153, v150, v188, s[2:3]
	v_mov_b32_e32 v150, v1
	v_mov_b32_e32 v188, v1
	v_cvt_pk_f16_f32 v155, v186, v187
	v_mov_b32_dpp v150, v151 quad_perm:[1,0,3,2] row_mask:0xf bank_mask:0xf
	v_mov_b32_dpp v188, v154 quad_perm:[1,0,3,2] row_mask:0xf bank_mask:0xf
	v_cvt_pk_f16_f32 v186, v190, v191
	v_cndmask_b32_e64 v150, v150, v154, s[2:3]
	v_cndmask_b32_e64 v154, v151, v188, s[2:3]
	v_mov_b32_e32 v151, v1
	s_lshl_b32 s38, 0x120, s42
	v_mov_b32_e32 v188, v1
	v_mov_b32_dpp v151, v186 quad_perm:[1,0,3,2] row_mask:0xf bank_mask:0xf
	v_add_u32_e32 v187, s38, v206
	v_mov_b32_dpp v188, v155 quad_perm:[1,0,3,2] row_mask:0xf bank_mask:0xf
	v_cndmask_b32_e64 v151, v151, v155, s[2:3]
	v_cndmask_b32_e64 v155, v186, v188, s[2:3]
	s_mov_b32 s100, 2
	global_store_dwordx4 v187, v[148:151], s[36:37] sc1
	v_fma_f32 v188, v10, v170, v132
	v_fma_f32 v189, v11, v170, v133
	v_fma_f32 v190, v80, v170, v142
	v_fma_f32 v191, v81, v170, v143
	v_add_u32_e32 v148, s9, v187
	s_mov_b32 s100, 2
	global_store_dwordx4 v148, v[152:155], s[36:37] sc1
	v_fma_f32 v148, v16, v170, v138
	v_fma_f32 v149, v17, v170, v139
	v_fma_f32 v150, v14, v170, v136
	v_fma_f32 v151, v15, v170, v137
	v_mul_f32_e32 v153, v149, v149
	v_mul_f32_e32 v152, v151, v151
	v_fmac_f32_e32 v152, v150, v150
	v_fmac_f32_e32 v153, v148, v148
	v_fma_f32 v186, v12, v170, v134
	v_fma_f32 v187, v13, v170, v135
	v_add_f32_e32 v152, v152, v153
	v_mul_f32_e32 v153, v189, v189
	v_mul_f32_e32 v154, v187, v187
	v_fmac_f32_e32 v153, v188, v188
	v_fmac_f32_e32 v154, v186, v186
	v_add_f32_e32 v153, v153, v154
	v_fma_f32 v192, v78, v170, v140
	v_fma_f32 v193, v79, v170, v141
	v_add_f32_e32 v152, v152, v153
	v_mul_f32_e32 v153, v193, v193
	v_mul_f32_e32 v154, v191, v191
	v_fmac_f32_e32 v153, v192, v192
	v_fmac_f32_e32 v154, v190, v190
	v_add_f32_e32 v153, v153, v154
	v_fma_f32 v214, v76, v170, v146
	v_fma_f32 v215, v77, v170, v147
	v_fma_f32 v216, v74, v170, v144
	v_fma_f32 v217, v75, v170, v145
	v_add_f32_e32 v152, v153, v152
	v_mul_f32_e32 v153, v217, v217
	v_mul_f32_e32 v154, v215, v215
	v_fmac_f32_e32 v153, v216, v216
	v_fmac_f32_e32 v154, v214, v214
	v_add_f32_e32 v153, v153, v154
	v_add_f32_e32 v152, v153, v152
	v_mov_b32_e32 v153, v152
	s_nop 1
	v_permlane16_swap_b32_e32 v152, v153
	v_add_f32_e32 v152, v152, v153
	v_mov_b32_e32 v153, v152
	s_nop 1
	v_permlane32_swap_b32_e32 v152, v153
	v_add_f32_e32 v152, v152, v153
	v_fmamk_f32 v152, v152, 0x3c800000, v229
	v_rsq_f32_e32 v218, v152
	s_and_b64 vcc, exec, s[4:5]
	v_mul_f32_e32 v150, v150, v218
	v_mul_f32_e32 v151, v151, v218
	v_mul_f32_e32 v148, v148, v218
	v_mul_f32_e32 v149, v149, v218
	v_mul_f32_e32 v152, v184, v150
	v_mul_f32_e32 v153, v185, v151
	v_mul_f32_e32 v154, v182, v148
	v_mul_f32_e32 v155, v183, v149
	v_mul_f32_e32 v148, v188, v218
	v_mul_f32_e32 v149, v189, v218
	v_mul_f32_e32 v150, v186, v218
	v_mul_f32_e32 v151, v187, v218
	v_mul_f32_e32 v188, v180, v148
	v_mul_f32_e32 v189, v181, v149
	v_mul_f32_e32 v186, v178, v150
	v_mul_f32_e32 v187, v179, v151
	v_mul_f32_e32 v148, v192, v218
	v_mul_f32_e32 v149, v193, v218
	v_mul_f32_e32 v150, v190, v218
	v_mul_f32_e32 v151, v191, v218
	v_mul_f32_e32 v192, v216, v218
	v_mul_f32_e32 v193, v217, v218
	v_mul_f32_e32 v190, v214, v218
	v_mul_f32_e32 v191, v215, v218
	v_mul_f32_e32 v150, v160, v150
	v_mul_f32_e32 v151, v161, v151
	v_mul_f32_e32 v148, v162, v148
	v_mul_f32_e32 v149, v163, v149
	v_mul_f32_e32 v190, v156, v190
	v_mul_f32_e32 v191, v157, v191
	v_mul_f32_e32 v192, v158, v192
	v_mul_f32_e32 v193, v159, v193
	s_cbranch_vccnz .LBB0_589
	v_add_u32_e32 v207, 0xa0, v201
	v_and_b32_e32 v207, 0x7c0, v207
	v_add_u32_e32 v210, v205, v207
	v_add_u32_e32 v207, v204, v207
	ds_read_b128 v[214:217], v210
	ds_read_b128 v[218:221], v207
	s_waitcnt lgkmcnt(0)
	v_mul_f32_e32 v222, v186, v220
	v_mul_f32_e32 v223, v187, v221
	v_mul_f32_e32 v226, v188, v218
	v_mul_f32_e32 v227, v189, v219
	v_fma_f32 v224, v154, v216, -v222
	v_fma_f32 v225, v155, v217, -v223
	v_fma_f32 v222, v152, v214, -v226
	v_fma_f32 v223, v153, v215, -v227
	v_mul_f32_e32 v152, v152, v218
	v_mul_f32_e32 v153, v153, v219
	v_mul_f32_e32 v154, v154, v220
	v_mul_f32_e32 v155, v155, v221
	v_fma_f32 v188, v188, v214, v152
	v_fma_f32 v189, v189, v215, v153
	v_add_u32_e32 v152, v205, v195
	v_add_u32_e32 v195, v204, v195
	v_fma_f32 v186, v186, v216, v154
	v_fma_f32 v187, v187, v217, v155
	ds_read_b128 v[152:155], v152
	ds_read_b128 v[214:217], v195
	s_waitcnt lgkmcnt(0)
	v_mul_f32_e32 v218, v190, v216
	v_mul_f32_e32 v219, v191, v217
	v_mul_f32_e32 v226, v192, v214
	v_mul_f32_e32 v227, v193, v215
	v_fma_f32 v220, v150, v154, -v218
	v_fma_f32 v221, v151, v155, -v219
	v_fma_f32 v218, v148, v152, -v226
	v_fma_f32 v219, v149, v153, -v227
	v_mul_f32_e32 v150, v150, v216
	v_mul_f32_e32 v151, v151, v217
	v_mul_f32_e32 v148, v148, v214
	v_mul_f32_e32 v149, v149, v215
	v_fma_f32 v190, v190, v154, v150
	v_fma_f32 v191, v191, v155, v151
	v_fma_f32 v192, v192, v152, v148
	v_fma_f32 v193, v193, v153, v149
	v_mov_b64_e32 v[148:149], v[218:219]
	v_mov_b64_e32 v[152:153], v[222:223]
	v_mov_b64_e32 v[150:151], v[220:221]
	v_mov_b64_e32 v[154:155], v[224:225]
; #define LAS __attribute__((address_space(3)))
; __device__ __forceinline__ unsigned cvtpk_h(float lo, float hi) { f32x2 v = {lo, hi}; h16x2 b = __builtin_convertvector(v, h16x2); return __builtin_bit_cast(unsigned, b); }
;     __device__ __forceinline__ void operator()(const f32x4 (&acc)[2][2][4][2], const pg8::Unit& u, int wr, int wc, int fr, int fq) const {
;     ...
;             for (int m = 0; m < 4; ++m) { const float r = rs[ai][m]; f32x4 v[2][2]; float ss = 0.f;
; #pragma unroll
;                 for (int bj = 0; bj < 2; ++bj)
; #pragma unroll
;                     for (int n = 0; n < 2; ++n) { v[bj][n] = acc[ai][bj][m][n] * r + bv[bj][n]; ss += (v[bj][n][0] * v[bj][n][0] + v[bj][n][1] * v[bj][n][1]) + (v[bj][n][2] * v[bj][n][2] + v[bj][n][3] * v[bj][n][3]); }
;                 const float rn = __builtin_amdgcn_rsqf(red4(ss, fq * 16 + fr) * (1.f / 64.f) + EPS);
; #pragma unroll
;                 for (int bj = 0; bj < 2; ++bj)
; #pragma unroll
;                     for (int n = 0; n < 2; ++n) v[bj][n] = v[bj][n] * rn * g4[bj][n];
;                 if (lat) { const unsigned t = (rbase + ai * 128 + m * 16) & (SEQ - 1);
; #pragma unroll
;                     for (int bj = 0; bj < 2; ++bj) { const unsigned pos = bj ? (t & 63u) : (t >> 6); const f32x4 cs = *(const LAS f32x4*)(ropel + pos * 16u + 4u * fq), sn = *(const LAS f32x4*)(ropel + 1024u + pos * 16u + 4u * fq);
;                         const f32x4 x1 = v[bj][0], x2 = v[bj][1]; v[bj][0] = x1 * cs - x2 * sn; v[bj][1] = x2 * cs + x1 * sn; } }
;                 const unsigned ro = offA + (unsigned)(ai * 8 + m) * 32u * pitch;
;                 u32x4 w[2];
; #pragma unroll
;                 for (int bj = 0; bj < 2; ++bj) { w[bj].x = cvtpk_h(v[bj][0][0], v[bj][0][1]); w[bj].y = cvtpk_h(v[bj][0][2], v[bj][0][3]); w[bj].z = cvtpk_h(v[bj][1][0], v[bj][1][1]); w[bj].w = cvtpk_h(v[bj][1][2], v[bj][1][3]); }
;                 stg_line_pair(wst, ro, 2u * pitch, w[0], w[1], odd);
;                 asm volatile("" ::: "memory"); }
.LBB0_589:
	v_cvt_pk_f16_f32 v152, v152, v153
	v_cvt_pk_f16_f32 v153, v154, v155
	v_cvt_pk_f16_f32 v154, v188, v189
	v_cvt_pk_f16_f32 v149, v148, v149
	v_mov_b32_e32 v148, v1
	v_mov_b32_e32 v188, v1
	v_cvt_pk_f16_f32 v150, v150, v151
	v_mov_b32_dpp v148, v149 quad_perm:[1,0,3,2] row_mask:0xf bank_mask:0xf
	v_mov_b32_dpp v188, v152 quad_perm:[1,0,3,2] row_mask:0xf bank_mask:0xf
	v_cndmask_b32_e64 v148, v148, v152, s[2:3]
	v_cndmask_b32_e64 v152, v149, v188, s[2:3]
	v_mov_b32_e32 v149, v1
	v_mov_b32_e32 v188, v1
	v_cvt_pk_f16_f32 v151, v192, v193
	v_mov_b32_dpp v149, v150 quad_perm:[1,0,3,2] row_mask:0xf bank_mask:0xf
	v_mov_b32_dpp v188, v153 quad_perm:[1,0,3,2] row_mask:0xf bank_mask:0xf
	v_cndmask_b32_e64 v149, v149, v153, s[2:3]
	v_cndmask_b32_e64 v153, v150, v188, s[2:3]
	v_mov_b32_e32 v150, v1
	v_mov_b32_e32 v188, v1
	v_cvt_pk_f16_f32 v155, v186, v187
	v_mov_b32_dpp v150, v151 quad_perm:[1,0,3,2] row_mask:0xf bank_mask:0xf
	v_mov_b32_dpp v188, v154 quad_perm:[1,0,3,2] row_mask:0xf bank_mask:0xf
	v_cvt_pk_f16_f32 v186, v190, v191
	v_cndmask_b32_e64 v150, v150, v154, s[2:3]
	v_cndmask_b32_e64 v154, v151, v188, s[2:3]
	v_mov_b32_e32 v151, v1
	s_lshl_b32 s38, 0x140, s42
	v_mov_b32_e32 v188, v1
	v_mov_b32_dpp v151, v186 quad_perm:[1,0,3,2] row_mask:0xf bank_mask:0xf
	v_add_u32_e32 v187, s38, v206
	v_mov_b32_dpp v188, v155 quad_perm:[1,0,3,2] row_mask:0xf bank_mask:0xf
	v_cndmask_b32_e64 v151, v151, v155, s[2:3]
	v_cndmask_b32_e64 v155, v186, v188, s[2:3]
	s_mov_b32 s100, 2
	global_store_dwordx4 v187, v[148:151], s[36:37] sc1
	s_and_b64 vcc, exec, s[4:5]
	s_nop 0
	v_add_u32_e32 v148, s9, v187
	s_mov_b32 s100, 2
	global_store_dwordx4 v148, v[152:155], s[36:37] sc1
	v_mov_b32_e32 v148, v171
	v_fma_f32 v150, v8, v148, v138
	v_fma_f32 v151, v9, v148, v139
	v_fma_f32 v152, v6, v148, v136
	v_fma_f32 v153, v7, v148, v137
	v_mul_f32_e32 v154, v151, v151
	v_mul_f32_e32 v149, v153, v153
	v_fmac_f32_e32 v149, v152, v152
	v_fmac_f32_e32 v154, v150, v150
	v_add_f32_e32 v149, v149, v154
	v_fma_f32 v186, v4, v148, v134
	v_fma_f32 v187, v5, v148, v135
	v_fma_f32 v188, v2, v148, v132
	v_fma_f32 v189, v3, v148, v133
	v_mul_f32_e32 v155, v187, v187
	v_mul_f32_e32 v154, v189, v189
	v_fmac_f32_e32 v154, v188, v188
	v_fmac_f32_e32 v155, v186, v186
	v_add_f32_e32 v154, v154, v155
	v_add_f32_e32 v149, v149, v154
	v_fma_f32 v190, v64, v148, v142
	v_fma_f32 v191, v65, v148, v143
	v_fma_f32 v192, v62, v148, v140
	v_fma_f32 v193, v63, v148, v141
	v_mul_f32_e32 v155, v191, v191
	v_mul_f32_e32 v154, v193, v193
	v_fmac_f32_e32 v154, v192, v192
	v_fmac_f32_e32 v155, v190, v190
	v_add_f32_e32 v154, v154, v155
	v_add_f32_e32 v149, v154, v149
	v_fma_f32 v214, v60, v148, v146
	v_fma_f32 v215, v61, v148, v147
	v_fma_f32 v216, v58, v148, v144
	v_fma_f32 v217, v59, v148, v145
	v_mul_f32_e32 v154, v215, v215
	v_mul_f32_e32 v148, v217, v217
	v_fmac_f32_e32 v148, v216, v216
	v_fmac_f32_e32 v154, v214, v214
	v_add_f32_e32 v148, v148, v154
	v_add_f32_e32 v148, v148, v149
	v_mov_b32_e32 v149, v148
	s_nop 1
	v_permlane16_swap_b32_e32 v148, v149
	v_add_f32_e32 v148, v148, v149
	v_mov_b32_e32 v149, v148
	s_nop 1
	v_permlane32_swap_b32_e32 v148, v149
	v_add_f32_e32 v148, v148, v149
	v_fmamk_f32 v148, v148, 0x3c800000, v229
	v_rsq_f32_e32 v218, v148
	s_nop 0
	v_mul_f32_e32 v148, v152, v218
	v_mul_f32_e32 v149, v153, v218
	v_mul_f32_e32 v150, v150, v218
	v_mul_f32_e32 v151, v151, v218
	v_mul_f32_e32 v152, v184, v148
	v_mul_f32_e32 v153, v185, v149
	v_mul_f32_e32 v154, v182, v150
	v_mul_f32_e32 v155, v183, v151
	v_mul_f32_e32 v148, v188, v218
	v_mul_f32_e32 v149, v189, v218
	v_mul_f32_e32 v150, v186, v218
	v_mul_f32_e32 v151, v187, v218
	v_mul_f32_e32 v180, v180, v148
	v_mul_f32_e32 v181, v181, v149
	v_mul_f32_e32 v178, v178, v150
	v_mul_f32_e32 v179, v179, v151
	v_mul_f32_e32 v148, v192, v218
	v_mul_f32_e32 v149, v193, v218
	v_mul_f32_e32 v150, v190, v218
	v_mul_f32_e32 v151, v191, v218
	v_mul_f32_e32 v148, v162, v148
	v_mul_f32_e32 v149, v163, v149
	v_mul_f32_e32 v150, v160, v150
	v_mul_f32_e32 v151, v161, v151
	v_mul_f32_e32 v160, v216, v218
	v_mul_f32_e32 v161, v217, v218
	v_mul_f32_e32 v162, v214, v218
	v_mul_f32_e32 v163, v215, v218
	v_mul_f32_e32 v158, v158, v160
	v_mul_f32_e32 v159, v159, v161
	v_mul_f32_e32 v156, v156, v162
	v_mul_f32_e32 v157, v157, v163
	s_cbranch_vccnz .LBB0_591
	v_add_u32_e32 v160, 0xb0, v201
	v_and_b32_e32 v182, 0x7c0, v160
	v_add_u32_e32 v160, v205, v182
	v_add_u32_e32 v182, v204, v182
	ds_read_b128 v[160:163], v160
	ds_read_b128 v[182:185], v182
	s_waitcnt lgkmcnt(0)
	v_mul_f32_e32 v186, v178, v184
	v_mul_f32_e32 v187, v179, v185
	v_mul_f32_e32 v190, v180, v182
	v_mul_f32_e32 v191, v181, v183
	v_fma_f32 v188, v154, v162, -v186
	v_fma_f32 v189, v155, v163, -v187
	v_fma_f32 v186, v152, v160, -v190
	v_fma_f32 v187, v153, v161, -v191
	v_mul_f32_e32 v152, v152, v182
	v_mul_f32_e32 v153, v153, v183
	v_mul_f32_e32 v154, v154, v184
	v_mul_f32_e32 v155, v155, v185
	v_fma_f32 v180, v180, v160, v152
	v_fma_f32 v181, v181, v161, v153
	v_add_u32_e32 v152, v205, v194
	v_add_u32_e32 v160, v204, v194
	v_fma_f32 v178, v178, v162, v154
	v_fma_f32 v179, v179, v163, v155
	ds_read_b128 v[152:155], v152
	ds_read_b128 v[160:163], v160
	s_waitcnt lgkmcnt(0)
	v_mul_f32_e32 v182, v156, v162
	v_mul_f32_e32 v183, v157, v163
	v_mul_f32_e32 v190, v158, v160
	v_mul_f32_e32 v191, v159, v161
	v_fma_f32 v184, v150, v154, -v182
	v_fma_f32 v185, v151, v155, -v183
	v_fma_f32 v182, v148, v152, -v190
	v_fma_f32 v183, v149, v153, -v191
	v_mul_f32_e32 v150, v150, v162
	v_mul_f32_e32 v151, v151, v163
	v_mul_f32_e32 v148, v148, v160
	v_mul_f32_e32 v149, v149, v161
	v_fma_f32 v156, v156, v154, v150
	v_fma_f32 v157, v157, v155, v151
	v_fma_f32 v158, v158, v152, v148
	v_fma_f32 v159, v159, v153, v149
	v_mov_b64_e32 v[148:149], v[182:183]
	v_mov_b64_e32 v[152:153], v[186:187]
	v_mov_b64_e32 v[150:151], v[184:185]
	v_mov_b64_e32 v[154:155], v[188:189]

;     __device__ __forceinline__ void operator()(const f32x4 (&acc)[2][2][4][2], const pg8::Unit& u, int wr, int wc, int fr, int fq) const {
;     ...
;             if (act == 4) {
; #pragma unroll
;                 for (int ai = 0; ai < 2; ++ai)
; #pragma unroll
;                     for (int m = 0; m < 4; ++m) rs[ai][m] *= 0.125f;
; #pragma unroll
;                 for (int bj = 0; bj < 2; ++bj)
; #pragma unroll
;                     for (int n = 0; n < 2; ++n) bv[bj][n] *= 0.125f; }
.LBB0_597:
	s_mov_b32 s2, 0x3e000000
	v_mul_f32_e32 v162, s2, v176
	v_mul_f32_e32 v163, s2, v177
	v_mul_f32_e32 v160, s2, v174
	v_mul_f32_e32 v161, s2, v175
	v_mul_f32_e32 v158, s2, v172
	v_mul_f32_e32 v159, s2, v173
	v_mul_f32_e32 v156, s2, v170
	v_mul_f32_e32 v157, s2, v171
	s_waitcnt vmcnt(3)
	v_mul_f32_e32 v150, s2, v138
	v_mul_f32_e32 v151, s2, v139
	v_mul_f32_e32 v148, s2, v136
	v_mul_f32_e32 v149, s2, v137
	s_waitcnt vmcnt(2)
	v_mul_f32_e32 v154, s2, v134
	v_mul_f32_e32 v155, s2, v135
	v_mul_f32_e32 v152, s2, v132
	v_mul_f32_e32 v153, s2, v133
	s_waitcnt vmcnt(1)
	v_mul_f32_e32 v142, s2, v142
	v_mul_f32_e32 v143, s2, v143
	v_mul_f32_e32 v140, s2, v140
	v_mul_f32_e32 v141, s2, v141
	s_waitcnt vmcnt(0)
	v_mul_f32_e32 v146, s2, v146
	v_mul_f32_e32 v147, s2, v147
	v_mul_f32_e32 v144, s2, v144
	v_mul_f32_e32 v145, s2, v145
	s_branch .LBB0_632

; __device__ __forceinline__ unsigned cvtpk_h(float lo, float hi) { f32x2 v = {lo, hi}; h16x2 b = __builtin_convertvector(v, h16x2); return __builtin_bit_cast(unsigned, b); }
;     __device__ __forceinline__ void operator()(const f32x4 (&acc)[2][2][4][2], const pg8::Unit& u, int wr, int wc, int fr, int fq) const {
;     ...
;             const bool odd = (fr & 1) != 0;
;             const unsigned offA = base + ((row0 + (unsigned)(wr * 64 + (fr & ~1))) * pitch + coff) * 2u + (odd ? 64u : 0u) + 16u * fq;
; #pragma unroll
;             for (int ai = 0; ai < 2; ++ai)
; #pragma unroll
;                 for (int m = 0; m < 4; ++m) { const unsigned ro = offA + (unsigned)(ai * 8 + m) * rowstep; const float r = rs[ai][m];
;                     u32x4 w[2];
; #pragma unroll
;                     for (int bj = 0; bj < 2; ++bj) { const f32x4 v0 = acc[ai][bj][m][0] * r + bv[bj][0], v1 = acc[ai][bj][m][1] * r + bv[bj][1];
;                         w[bj].x = cvtpk_h(v0[0], v0[1]); w[bj].y = cvtpk_h(v0[2], v0[3]); w[bj].z = cvtpk_h(v1[0], v1[1]); w[bj].w = cvtpk_h(v1[2], v1[3]); }
;                     stg_line_pair(wst, ro, 2u * pitch, w[0], w[1], odd);
;                     asm volatile("" ::: "memory"); }
.LBB0_632:
	v_and_b32_e32 v178, 0x7ffffffe, v202
	s_add_i32 s2, s42, s77
	v_add_u32_e32 v178, s2, v178
	v_and_b32_e32 v186, 1, v202
	v_mul_lo_u32 v178, s9, v178
	v_add_lshl_u32 v178, v178, s38, 1
	v_lshl_add_u32 v179, v186, 6, v203
	v_fma_f32 v180, v70, v162, v148
	v_fma_f32 v181, v71, v162, v149
	s_waitcnt vmcnt(1)
	v_fma_f32 v128, v128, v162, v142
	v_fma_f32 v129, v129, v162, v143
	v_fma_f32 v126, v126, v162, v140
	v_fma_f32 v127, v127, v162, v141
	s_waitcnt vmcnt(0)
	v_fma_f32 v122, v122, v162, v144
	v_fma_f32 v123, v123, v162, v145
	v_add3_u32 v187, v179, s39, v178
	v_fma_f32 v178, v72, v162, v150
	v_fma_f32 v179, v73, v162, v151
	v_cvt_pk_f16_f32 v180, v180, v181
	v_fma_f32 v124, v124, v162, v146
	v_fma_f32 v125, v125, v162, v147
	v_cvt_pk_f16_f32 v126, v126, v127
	v_cvt_pk_f16_f32 v127, v128, v129
	v_cvt_pk_f16_f32 v128, v122, v123
	v_mov_b32_e32 v123, v1
	v_fma_f32 v184, v66, v162, v152
	v_fma_f32 v185, v67, v162, v153
	v_cvt_pk_f16_f32 v178, v178, v179
	v_cvt_pk_f16_f32 v129, v124, v125
	v_mov_b32_e32 v122, v1
	v_mov_b32_dpp v123, v180 quad_perm:[1,0,3,2] row_mask:0xf bank_mask:0xf
	v_cmp_eq_u32_e32 vcc, 0, v186
	v_mov_b32_e32 v124, v1
	v_cvt_pk_f16_f32 v179, v184, v185
	v_mov_b32_dpp v122, v126 quad_perm:[1,0,3,2] row_mask:0xf bank_mask:0xf
	v_cndmask_b32_e32 v126, v126, v123, vcc
	v_mov_b32_e32 v123, v1
	v_mov_b32_dpp v124, v178 quad_perm:[1,0,3,2] row_mask:0xf bank_mask:0xf
	v_mov_b32_e32 v125, v1
	v_mov_b32_dpp v123, v127 quad_perm:[1,0,3,2] row_mask:0xf bank_mask:0xf
	v_cndmask_b32_e32 v127, v127, v124, vcc
	v_mov_b32_e32 v124, v1
	v_mov_b32_dpp v125, v179 quad_perm:[1,0,3,2] row_mask:0xf bank_mask:0xf
	v_fma_f32 v182, v68, v162, v154
	v_fma_f32 v183, v69, v162, v155
	v_mov_b32_dpp v124, v128 quad_perm:[1,0,3,2] row_mask:0xf bank_mask:0xf
	v_cndmask_b32_e32 v128, v128, v125, vcc
	v_mov_b32_e32 v125, v1
	v_cvt_pk_f16_f32 v181, v182, v183
	v_cndmask_b32_e32 v123, v123, v178, vcc
	v_mov_b32_dpp v125, v129 quad_perm:[1,0,3,2] row_mask:0xf bank_mask:0xf
	v_mov_b32_e32 v178, v1
	s_lshl_b32 s2, s9, 1
	v_cndmask_b32_e32 v122, v122, v180, vcc
	v_cndmask_b32_e32 v124, v124, v179, vcc
	v_mov_b32_dpp v178, v181 quad_perm:[1,0,3,2] row_mask:0xf bank_mask:0xf
	v_cndmask_b32_e32 v125, v125, v181, vcc
	v_cndmask_b32_e32 v129, v129, v178, vcc
	s_mov_b32 s100, 2
	global_store_dwordx4 v187, v[122:125], s[36:37] sc1
	v_fma_f32 v120, v120, v163, v142
	v_fma_f32 v121, v121, v163, v143
	v_fma_f32 v118, v118, v163, v140
	v_fma_f32 v119, v119, v163, v141
	v_add_u32_e32 v122, s2, v187
	s_mov_b32 s100, 2
	global_store_dwordx4 v122, v[126:129], s[36:37] sc1
	v_fma_f32 v114, v114, v163, v144
	v_fma_f32 v115, v115, v163, v145
	v_fma_f32 v124, v52, v163, v150
	v_fma_f32 v125, v53, v163, v151
	v_fma_f32 v126, v50, v163, v148
	v_fma_f32 v127, v51, v163, v149
	v_fma_f32 v116, v116, v163, v146
	v_fma_f32 v117, v117, v163, v147
	v_cvt_pk_f16_f32 v126, v126, v127
	v_cvt_pk_f16_f32 v118, v118, v119
	v_cvt_pk_f16_f32 v119, v120, v121
	v_cvt_pk_f16_f32 v120, v114, v115
	v_mov_b32_e32 v115, v1
	v_fma_f32 v178, v46, v163, v152
	v_fma_f32 v179, v47, v163, v153
	v_cvt_pk_f16_f32 v124, v124, v125
	v_cvt_pk_f16_f32 v121, v116, v117
	v_mov_b32_e32 v114, v1
	v_mov_b32_dpp v115, v126 quad_perm:[1,0,3,2] row_mask:0xf bank_mask:0xf
	v_mov_b32_e32 v116, v1
	v_cvt_pk_f16_f32 v125, v178, v179
	v_mov_b32_dpp v114, v118 quad_perm:[1,0,3,2] row_mask:0xf bank_mask:0xf
	v_cndmask_b32_e32 v118, v118, v115, vcc
	v_mov_b32_e32 v115, v1
	v_mov_b32_dpp v116, v124 quad_perm:[1,0,3,2] row_mask:0xf bank_mask:0xf
	v_mov_b32_e32 v117, v1
	v_mov_b32_dpp v115, v119 quad_perm:[1,0,3,2] row_mask:0xf bank_mask:0xf
	v_cndmask_b32_e32 v119, v119, v116, vcc
	v_mov_b32_e32 v116, v1
	v_mov_b32_dpp v117, v125 quad_perm:[1,0,3,2] row_mask:0xf bank_mask:0xf
	v_fma_f32 v128, v48, v163, v154
	v_fma_f32 v129, v49, v163, v155
	v_mad_u64_u32 v[122:123], s[4:5], s9, 30, v[122:123]
	v_mov_b32_dpp v116, v120 quad_perm:[1,0,3,2] row_mask:0xf bank_mask:0xf
	v_cndmask_b32_e32 v120, v120, v117, vcc
	v_mov_b32_e32 v117, v1
	v_cvt_pk_f16_f32 v127, v128, v129
	v_mov_b32_e32 v123, v1
	v_mov_b32_dpp v117, v121 quad_perm:[1,0,3,2] row_mask:0xf bank_mask:0xf
	v_cndmask_b32_e32 v114, v114, v126, vcc
	v_cndmask_b32_e32 v115, v115, v124, vcc
	v_cndmask_b32_e32 v116, v116, v125, vcc
	v_mov_b32_dpp v123, v127 quad_perm:[1,0,3,2] row_mask:0xf bank_mask:0xf
	v_cndmask_b32_e32 v117, v117, v127, vcc
	v_cndmask_b32_e32 v121, v121, v123, vcc
	s_mov_b32 s100, 2
	global_store_dwordx4 v122, v[114:117], s[36:37] sc1
	v_fma_f32 v112, v112, v160, v142
	v_fma_f32 v113, v113, v160, v143
	v_fma_f32 v110, v110, v160, v140
	v_fma_f32 v111, v111, v160, v141
	v_add_u32_e32 v114, s2, v122
	v_fma_f32 v116, v54, v160, v148
	v_fma_f32 v117, v55, v160, v149
	v_fma_f32 v106, v106, v160, v144
	v_fma_f32 v107, v107, v160, v145
	s_mov_b32 s100, 2
	global_store_dwordx4 v114, v[118:121], s[36:37] sc1
	v_fma_f32 v114, v56, v160, v150
	v_fma_f32 v115, v57, v160, v151
	v_cvt_pk_f16_f32 v116, v116, v117
	v_fma_f32 v108, v108, v160, v146
	v_fma_f32 v109, v109, v160, v147
	v_cvt_pk_f16_f32 v110, v110, v111
	v_cvt_pk_f16_f32 v111, v112, v113
	v_cvt_pk_f16_f32 v112, v106, v107
	v_mov_b32_e32 v107, v1
	v_fma_f32 v120, v42, v160, v152
	v_fma_f32 v121, v43, v160, v153
	v_cvt_pk_f16_f32 v114, v114, v115
	v_cvt_pk_f16_f32 v113, v108, v109
	v_mov_b32_e32 v106, v1
	v_mov_b32_dpp v107, v116 quad_perm:[1,0,3,2] row_mask:0xf bank_mask:0xf
	v_mov_b32_e32 v108, v1
	v_cvt_pk_f16_f32 v115, v120, v121
	v_mov_b32_dpp v106, v110 quad_perm:[1,0,3,2] row_mask:0xf bank_mask:0xf
	v_cndmask_b32_e32 v110, v110, v107, vcc
	v_mov_b32_e32 v107, v1
	v_mov_b32_dpp v108, v114 quad_perm:[1,0,3,2] row_mask:0xf bank_mask:0xf
; __device__ __forceinline__ unsigned cvtpk_h(float lo, float hi) { f32x2 v = {lo, hi}; h16x2 b = __builtin_convertvector(v, h16x2); return __builtin_bit_cast(unsigned, b); }
;     __device__ __forceinline__ void operator()(const f32x4 (&acc)[2][2][4][2], const pg8::Unit& u, int wr, int wc, int fr, int fq) const {
;     ...
;             const bool odd = (fr & 1) != 0;
;             const unsigned offA = base + ((row0 + (unsigned)(wr * 64 + (fr & ~1))) * pitch + coff) * 2u + (odd ? 64u : 0u) + 16u * fq;
; #pragma unroll
;             for (int ai = 0; ai < 2; ++ai)
; #pragma unroll
;                 for (int m = 0; m < 4; ++m) { const unsigned ro = offA + (unsigned)(ai * 8 + m) * rowstep; const float r = rs[ai][m];
;                     u32x4 w[2];
; #pragma unroll
;                     for (int bj = 0; bj < 2; ++bj) { const f32x4 v0 = acc[ai][bj][m][0] * r + bv[bj][0], v1 = acc[ai][bj][m][1] * r + bv[bj][1];
;                         w[bj].x = cvtpk_h(v0[0], v0[1]); w[bj].y = cvtpk_h(v0[2], v0[3]); w[bj].z = cvtpk_h(v1[0], v1[1]); w[bj].w = cvtpk_h(v1[2], v1[3]); }
;                     stg_line_pair(wst, ro, 2u * pitch, w[0], w[1], odd);
;                     asm volatile("" ::: "memory"); }
	v_mov_b32_e32 v109, v1
	v_mov_b32_dpp v107, v111 quad_perm:[1,0,3,2] row_mask:0xf bank_mask:0xf
	v_cndmask_b32_e32 v111, v111, v108, vcc
	v_mov_b32_e32 v108, v1
	v_mov_b32_dpp v109, v115 quad_perm:[1,0,3,2] row_mask:0xf bank_mask:0xf
	v_fma_f32 v118, v44, v160, v154
	v_fma_f32 v119, v45, v160, v155
	v_mov_b32_dpp v108, v112 quad_perm:[1,0,3,2] row_mask:0xf bank_mask:0xf
	v_cndmask_b32_e32 v112, v112, v109, vcc
	v_mov_b32_e32 v109, v1
	v_cvt_pk_f16_f32 v117, v118, v119
	s_lshl_b32 s3, s9, 5
	v_cndmask_b32_e32 v107, v107, v114, vcc
	v_mov_b32_dpp v109, v113 quad_perm:[1,0,3,2] row_mask:0xf bank_mask:0xf
	v_mov_b32_e32 v114, v1
	v_add_u32_e32 v118, s3, v122
	v_cndmask_b32_e32 v106, v106, v116, vcc
	v_cndmask_b32_e32 v108, v108, v115, vcc
	v_mov_b32_dpp v114, v117 quad_perm:[1,0,3,2] row_mask:0xf bank_mask:0xf
	v_cndmask_b32_e32 v109, v109, v117, vcc
	v_cndmask_b32_e32 v113, v113, v114, vcc
	s_mov_b32 s100, 2
	global_store_dwordx4 v118, v[106:109], s[36:37] sc1
	v_fma_f32 v104, v104, v161, v142
	v_fma_f32 v105, v105, v161, v143
	v_fma_f32 v102, v102, v161, v140
	v_fma_f32 v103, v103, v161, v141
	v_add_u32_e32 v106, s2, v118
	v_fma_f32 v108, v38, v161, v148
	v_fma_f32 v109, v39, v161, v149
	v_fma_f32 v98, v98, v161, v144
	v_fma_f32 v99, v99, v161, v145
	s_mov_b32 s100, 2
	global_store_dwordx4 v106, v[110:113], s[36:37] sc1
	v_fma_f32 v106, v40, v161, v150
	v_fma_f32 v107, v41, v161, v151
	v_cvt_pk_f16_f32 v108, v108, v109
	v_fma_f32 v100, v100, v161, v146
	v_fma_f32 v101, v101, v161, v147
	v_cvt_pk_f16_f32 v102, v102, v103
	v_cvt_pk_f16_f32 v103, v104, v105
	v_cvt_pk_f16_f32 v104, v98, v99
	v_mov_b32_e32 v99, v1
	v_fma_f32 v112, v34, v161, v152
	v_fma_f32 v113, v35, v161, v153
	v_cvt_pk_f16_f32 v106, v106, v107
	v_cvt_pk_f16_f32 v105, v100, v101
	v_mov_b32_e32 v98, v1
	v_mov_b32_dpp v99, v108 quad_perm:[1,0,3,2] row_mask:0xf bank_mask:0xf
	v_mov_b32_e32 v100, v1
	v_cvt_pk_f16_f32 v107, v112, v113
	v_mov_b32_dpp v98, v102 quad_perm:[1,0,3,2] row_mask:0xf bank_mask:0xf
	v_cndmask_b32_e32 v102, v102, v99, vcc
	v_mov_b32_e32 v99, v1
	v_mov_b32_dpp v100, v106 quad_perm:[1,0,3,2] row_mask:0xf bank_mask:0xf
	v_mov_b32_e32 v101, v1
	v_mov_b32_dpp v99, v103 quad_perm:[1,0,3,2] row_mask:0xf bank_mask:0xf
	v_cndmask_b32_e32 v103, v103, v100, vcc
	v_mov_b32_e32 v100, v1
	v_mov_b32_dpp v101, v107 quad_perm:[1,0,3,2] row_mask:0xf bank_mask:0xf
	v_fma_f32 v110, v36, v161, v154
	v_fma_f32 v111, v37, v161, v155
	v_mov_b32_dpp v100, v104 quad_perm:[1,0,3,2] row_mask:0xf bank_mask:0xf
	v_cndmask_b32_e32 v104, v104, v101, vcc
	v_mov_b32_e32 v101, v1
	v_cvt_pk_f16_f32 v109, v110, v111
	v_cndmask_b32_e32 v99, v99, v106, vcc
	v_mov_b32_dpp v101, v105 quad_perm:[1,0,3,2] row_mask:0xf bank_mask:0xf
	v_mov_b32_e32 v106, v1
	v_add_u32_e32 v110, s3, v118
	v_cndmask_b32_e32 v98, v98, v108, vcc
	v_cndmask_b32_e32 v100, v100, v107, vcc
	v_mov_b32_dpp v106, v109 quad_perm:[1,0,3,2] row_mask:0xf bank_mask:0xf
	v_cndmask_b32_e32 v101, v101, v109, vcc
	v_cndmask_b32_e32 v105, v105, v106, vcc
	s_mov_b32 s100, 2
	global_store_dwordx4 v110, v[98:101], s[36:37] sc1
	v_fma_f32 v96, v96, v158, v142
	v_fma_f32 v97, v97, v158, v143
	v_fma_f32 v94, v94, v158, v140
	v_fma_f32 v95, v95, v158, v141
	v_add_u32_e32 v98, s2, v110
	v_fma_f32 v100, v30, v158, v148
	v_fma_f32 v101, v31, v158, v149
	v_fma_f32 v90, v90, v158, v144
	v_fma_f32 v91, v91, v158, v145
	s_mov_b32 s100, 2
	global_store_dwordx4 v98, v[102:105], s[36:37] sc1
	v_fma_f32 v98, v32, v158, v150
	v_fma_f32 v99, v33, v158, v151
	v_cvt_pk_f16_f32 v100, v100, v101
	v_fma_f32 v92, v92, v158, v146
	v_fma_f32 v93, v93, v158, v147
	v_cvt_pk_f16_f32 v94, v94, v95
	v_cvt_pk_f16_f32 v95, v96, v97
	v_cvt_pk_f16_f32 v96, v90, v91
	v_mov_b32_e32 v91, v1
	v_fma_f32 v104, v26, v158, v152
	v_fma_f32 v105, v27, v158, v153
	v_cvt_pk_f16_f32 v98, v98, v99
	v_cvt_pk_f16_f32 v97, v92, v93
	v_mov_b32_e32 v90, v1
	v_mov_b32_dpp v91, v100 quad_perm:[1,0,3,2] row_mask:0xf bank_mask:0xf
	v_mov_b32_e32 v92, v1
	v_cvt_pk_f16_f32 v99, v104, v105
	v_mov_b32_dpp v90, v94 quad_perm:[1,0,3,2] row_mask:0xf bank_mask:0xf
	v_cndmask_b32_e32 v94, v94, v91, vcc
	v_mov_b32_e32 v91, v1
	v_mov_b32_dpp v92, v98 quad_perm:[1,0,3,2] row_mask:0xf bank_mask:0xf
	v_mov_b32_e32 v93, v1
	v_mov_b32_dpp v91, v95 quad_perm:[1,0,3,2] row_mask:0xf bank_mask:0xf
	v_cndmask_b32_e32 v95, v95, v92, vcc
	v_mov_b32_e32 v92, v1
	v_mov_b32_dpp v93, v99 quad_perm:[1,0,3,2] row_mask:0xf bank_mask:0xf
	v_fma_f32 v102, v28, v158, v154
	v_fma_f32 v103, v29, v158, v155
	v_mov_b32_dpp v92, v96 quad_perm:[1,0,3,2] row_mask:0xf bank_mask:0xf
	v_cndmask_b32_e32 v96, v96, v93, vcc
	v_mov_b32_e32 v93, v1
	v_cvt_pk_f16_f32 v101, v102, v103
	s_mul_i32 s4, s9, 0xa0
	v_cndmask_b32_e32 v91, v91, v98, vcc
	v_mov_b32_dpp v93, v97 quad_perm:[1,0,3,2] row_mask:0xf bank_mask:0xf
	v_mov_b32_e32 v98, v1
	v_add_u32_e32 v102, s4, v110
	v_cndmask_b32_e32 v90, v90, v100, vcc
	v_cndmask_b32_e32 v92, v92, v99, vcc
	v_mov_b32_dpp v98, v101 quad_perm:[1,0,3,2] row_mask:0xf bank_mask:0xf
	v_cndmask_b32_e32 v93, v93, v101, vcc
	v_cndmask_b32_e32 v97, v97, v98, vcc
	s_mov_b32 s100, 2
	global_store_dwordx4 v102, v[90:93], s[36:37] sc1
	v_fma_f32 v88, v88, v159, v142
	v_fma_f32 v89, v89, v159, v143
	v_fma_f32 v86, v86, v159, v140
	v_fma_f32 v87, v87, v159, v141
	v_add_u32_e32 v90, s2, v102
	v_fma_f32 v92, v22, v159, v148
	v_fma_f32 v93, v23, v159, v149
	v_fma_f32 v82, v82, v159, v144
	v_fma_f32 v83, v83, v159, v145
	s_mov_b32 s100, 2
	global_store_dwordx4 v90, v[94:97], s[36:37] sc1
	v_fma_f32 v90, v24, v159, v150
	v_fma_f32 v91, v25, v159, v151
	v_cvt_pk_f16_f32 v92, v92, v93
	v_fma_f32 v84, v84, v159, v146
; __device__ __forceinline__ unsigned cvtpk_h(float lo, float hi) { f32x2 v = {lo, hi}; h16x2 b = __builtin_convertvector(v, h16x2); return __builtin_bit_cast(unsigned, b); }
;     __device__ __forceinline__ void operator()(const f32x4 (&acc)[2][2][4][2], const pg8::Unit& u, int wr, int wc, int fr, int fq) const {
;     ...
;             const bool odd = (fr & 1) != 0;
;             const unsigned offA = base + ((row0 + (unsigned)(wr * 64 + (fr & ~1))) * pitch + coff) * 2u + (odd ? 64u : 0u) + 16u * fq;
; #pragma unroll
;             for (int ai = 0; ai < 2; ++ai)
; #pragma unroll
;                 for (int m = 0; m < 4; ++m) { const unsigned ro = offA + (unsigned)(ai * 8 + m) * rowstep; const float r = rs[ai][m];
;                     u32x4 w[2];
; #pragma unroll
;                     for (int bj = 0; bj < 2; ++bj) { const f32x4 v0 = acc[ai][bj][m][0] * r + bv[bj][0], v1 = acc[ai][bj][m][1] * r + bv[bj][1];
;                         w[bj].x = cvtpk_h(v0[0], v0[1]); w[bj].y = cvtpk_h(v0[2], v0[3]); w[bj].z = cvtpk_h(v1[0], v1[1]); w[bj].w = cvtpk_h(v1[2], v1[3]); }
;                     stg_line_pair(wst, ro, 2u * pitch, w[0], w[1], odd);
;                     asm volatile("" ::: "memory"); }
	v_fma_f32 v85, v85, v159, v147
	v_cvt_pk_f16_f32 v86, v86, v87
	v_cvt_pk_f16_f32 v87, v88, v89
	v_cvt_pk_f16_f32 v88, v82, v83
	v_mov_b32_e32 v83, v1
	v_fma_f32 v96, v18, v159, v152
	v_fma_f32 v97, v19, v159, v153
	v_cvt_pk_f16_f32 v90, v90, v91
	v_cvt_pk_f16_f32 v89, v84, v85
	v_mov_b32_e32 v82, v1
	v_mov_b32_dpp v83, v92 quad_perm:[1,0,3,2] row_mask:0xf bank_mask:0xf
	v_mov_b32_e32 v84, v1
	v_cvt_pk_f16_f32 v91, v96, v97
	v_mov_b32_dpp v82, v86 quad_perm:[1,0,3,2] row_mask:0xf bank_mask:0xf
	v_cndmask_b32_e32 v86, v86, v83, vcc
	v_mov_b32_e32 v83, v1
	v_mov_b32_dpp v84, v90 quad_perm:[1,0,3,2] row_mask:0xf bank_mask:0xf
	v_mov_b32_e32 v85, v1
	v_mov_b32_dpp v83, v87 quad_perm:[1,0,3,2] row_mask:0xf bank_mask:0xf
	v_cndmask_b32_e32 v87, v87, v84, vcc
	v_mov_b32_e32 v84, v1
	v_mov_b32_dpp v85, v91 quad_perm:[1,0,3,2] row_mask:0xf bank_mask:0xf
	v_fma_f32 v94, v20, v159, v154
	v_fma_f32 v95, v21, v159, v155
	v_mov_b32_dpp v84, v88 quad_perm:[1,0,3,2] row_mask:0xf bank_mask:0xf
	v_cndmask_b32_e32 v88, v88, v85, vcc
	v_mov_b32_e32 v85, v1
	v_cvt_pk_f16_f32 v93, v94, v95
	v_cndmask_b32_e32 v83, v83, v90, vcc
	v_mov_b32_dpp v85, v89 quad_perm:[1,0,3,2] row_mask:0xf bank_mask:0xf
	v_mov_b32_e32 v90, v1
	v_add_u32_e32 v94, s3, v102
	v_cndmask_b32_e32 v82, v82, v92, vcc
	v_cndmask_b32_e32 v84, v84, v91, vcc
	v_mov_b32_dpp v90, v93 quad_perm:[1,0,3,2] row_mask:0xf bank_mask:0xf
	v_cndmask_b32_e32 v85, v85, v93, vcc
	v_cndmask_b32_e32 v89, v89, v90, vcc
	s_mov_b32 s100, 2
	global_store_dwordx4 v94, v[82:85], s[36:37] sc1
	v_fma_f32 v80, v80, v156, v142
	v_fma_f32 v81, v81, v156, v143
	v_fma_f32 v78, v78, v156, v140
	v_fma_f32 v79, v79, v156, v141
	v_add_u32_e32 v82, s2, v94
	v_fma_f32 v84, v14, v156, v148
	v_fma_f32 v85, v15, v156, v149
	v_fma_f32 v74, v74, v156, v144
	v_fma_f32 v75, v75, v156, v145
	s_mov_b32 s100, 2
	global_store_dwordx4 v82, v[86:89], s[36:37] sc1
	v_fma_f32 v82, v16, v156, v150
	v_fma_f32 v83, v17, v156, v151
	v_cvt_pk_f16_f32 v84, v84, v85
	v_fma_f32 v76, v76, v156, v146
	v_fma_f32 v77, v77, v156, v147
	v_cvt_pk_f16_f32 v78, v78, v79
	v_cvt_pk_f16_f32 v79, v80, v81
	v_cvt_pk_f16_f32 v80, v74, v75
	v_mov_b32_e32 v75, v1
	v_fma_f32 v88, v10, v156, v152
	v_fma_f32 v89, v11, v156, v153
	v_cvt_pk_f16_f32 v82, v82, v83
	v_cvt_pk_f16_f32 v81, v76, v77
	v_mov_b32_e32 v74, v1
	v_mov_b32_dpp v75, v84 quad_perm:[1,0,3,2] row_mask:0xf bank_mask:0xf
	v_mov_b32_e32 v76, v1
	v_cvt_pk_f16_f32 v83, v88, v89
	v_mov_b32_dpp v74, v78 quad_perm:[1,0,3,2] row_mask:0xf bank_mask:0xf
	v_cndmask_b32_e32 v78, v78, v75, vcc
	v_mov_b32_e32 v75, v1
	v_mov_b32_dpp v76, v82 quad_perm:[1,0,3,2] row_mask:0xf bank_mask:0xf
	v_mov_b32_e32 v77, v1
	v_mov_b32_dpp v75, v79 quad_perm:[1,0,3,2] row_mask:0xf bank_mask:0xf
	v_cndmask_b32_e32 v79, v79, v76, vcc
	v_mov_b32_e32 v76, v1
	v_mov_b32_dpp v77, v83 quad_perm:[1,0,3,2] row_mask:0xf bank_mask:0xf
	v_fma_f32 v86, v12, v156, v154
	v_fma_f32 v87, v13, v156, v155
	v_mov_b32_dpp v76, v80 quad_perm:[1,0,3,2] row_mask:0xf bank_mask:0xf
	v_cndmask_b32_e32 v80, v80, v77, vcc
	v_mov_b32_e32 v77, v1
	v_cvt_pk_f16_f32 v85, v86, v87
	v_cndmask_b32_e32 v75, v75, v82, vcc
	v_mov_b32_dpp v77, v81 quad_perm:[1,0,3,2] row_mask:0xf bank_mask:0xf
	v_mov_b32_e32 v82, v1
	v_add_u32_e32 v86, s3, v94
	v_cndmask_b32_e32 v74, v74, v84, vcc
	v_cndmask_b32_e32 v76, v76, v83, vcc
	v_mov_b32_dpp v82, v85 quad_perm:[1,0,3,2] row_mask:0xf bank_mask:0xf
	v_cndmask_b32_e32 v77, v77, v85, vcc
	v_cndmask_b32_e32 v81, v81, v82, vcc
	s_mov_b32 s100, 2
	global_store_dwordx4 v86, v[74:77], s[36:37] sc1
	v_fma_f32 v64, v64, v157, v142
	v_fma_f32 v65, v65, v157, v143
	v_fma_f32 v62, v62, v157, v140
	v_fma_f32 v63, v63, v157, v141
	v_add_u32_e32 v74, s2, v86
	v_fma_f32 v76, v6, v157, v148
	v_fma_f32 v77, v7, v157, v149
	v_fma_f32 v58, v58, v157, v144
	v_fma_f32 v59, v59, v157, v145
	s_mov_b32 s100, 2
	global_store_dwordx4 v74, v[78:81], s[36:37] sc1
	v_fma_f32 v74, v8, v157, v150
	v_fma_f32 v75, v9, v157, v151
	v_cvt_pk_f16_f32 v76, v76, v77
	v_fma_f32 v60, v60, v157, v146
	v_fma_f32 v61, v61, v157, v147
	v_cvt_pk_f16_f32 v62, v62, v63
	v_cvt_pk_f16_f32 v63, v64, v65
	v_cvt_pk_f16_f32 v64, v58, v59
	v_mov_b32_e32 v59, v1
	v_fma_f32 v80, v2, v157, v152
	v_fma_f32 v81, v3, v157, v153
	v_cvt_pk_f16_f32 v74, v74, v75
	v_cvt_pk_f16_f32 v65, v60, v61
	v_mov_b32_e32 v58, v1
	v_mov_b32_dpp v59, v76 quad_perm:[1,0,3,2] row_mask:0xf bank_mask:0xf
	v_mov_b32_e32 v60, v1
	v_cvt_pk_f16_f32 v75, v80, v81
	v_mov_b32_dpp v58, v62 quad_perm:[1,0,3,2] row_mask:0xf bank_mask:0xf
	v_cndmask_b32_e32 v62, v62, v59, vcc
	v_mov_b32_e32 v59, v1
	v_mov_b32_dpp v60, v74 quad_perm:[1,0,3,2] row_mask:0xf bank_mask:0xf
	v_mov_b32_e32 v61, v1
	v_mov_b32_dpp v59, v63 quad_perm:[1,0,3,2] row_mask:0xf bank_mask:0xf
	v_cndmask_b32_e32 v63, v63, v60, vcc
	v_mov_b32_e32 v60, v1
	v_mov_b32_dpp v61, v75 quad_perm:[1,0,3,2] row_mask:0xf bank_mask:0xf
	v_fma_f32 v78, v4, v157, v154
	v_fma_f32 v79, v5, v157, v155
	v_mov_b32_dpp v60, v64 quad_perm:[1,0,3,2] row_mask:0xf bank_mask:0xf
	v_cndmask_b32_e32 v64, v64, v61, vcc
	v_mov_b32_e32 v61, v1
	v_cvt_pk_f16_f32 v77, v78, v79
	v_cndmask_b32_e32 v59, v59, v74, vcc
	v_mov_b32_dpp v61, v65 quad_perm:[1,0,3,2] row_mask:0xf bank_mask:0xf
	v_mov_b32_e32 v74, v1
	v_add_u32_e32 v78, s3, v86
	v_cndmask_b32_e32 v58, v58, v76, vcc
	v_cndmask_b32_e32 v60, v60, v75, vcc
	v_mov_b32_dpp v74, v77 quad_perm:[1,0,3,2] row_mask:0xf bank_mask:0xf
	v_cndmask_b32_e32 v61, v61, v77, vcc
	v_cndmask_b32_e32 v65, v65, v74, vcc
	s_mov_b32 s100, 2
	global_store_dwordx4 v78, v[58:61], s[36:37] sc1
	s_nop 1
	v_add_u32_e32 v58, s2, v78
	s_mov_b32 s100, 2
	global_store_dwordx4 v58, v[62:65], s[36:37] sc1
	s_mov_b64 s[2:3], 0
; #define GAS __attribute__((address_space(1)))
; __device__ __forceinline__ float logsigf(float x) { return fminf(x, 0.f) - 0.6931471805599453f * __builtin_amdgcn_logf(1.f + __builtin_amdgcn_exp2f(-1.4426950408889634f * fabsf(x))); }
;     __device__ __forceinline__ void operator()(const f32x4 (&acc)[2][2][4][2], const pg8::Unit& u, int wr, int wc, int fr, int fq) const {
;     ...
;             if (s == 52) {
;                 if (fq < 2) { const f32x4 g0 = *(const GAS f32x4*)(bg + 8 * fq), g1 = *(const GAS f32x4*)(bg + 8 * fq + 4);
; #pragma unroll
;                     for (int ai = 0; ai < 2; ++ai)
; #pragma unroll
;                         for (int m = 0; m < 4; ++m) { const float r = rs[ai][m]; const f32x4 vi = acc[ai][0][m][0] * r + bv[0][0] + g0; f32x4 vf = acc[ai][0][m][1] * r + bv[0][1] + g1;
;                             vf = (f32x4){logsigf(vf[0]), logsigf(vf[1]), logsigf(vf[2]), logsigf(vf[3])};
;                             const unsigned go = (unsigned)WS_G + (rbase + ai * 128 + m * 16) * 64u + 32u * fq; stg_f4(wst, go, vi); stg_f4(wst, go + 16u, vf); } }
;                 return;
.LBB0_633:
	s_and_b64 vcc, exec, s[2:3]
	s_cbranch_vccz .LBB0_637
	v_cmp_gt_i32_e32 vcc, 2, v200
	s_and_saveexec_b64 s[2:3], vcc
	s_cbranch_execz .LBB0_636
	v_lshlrev_b32_e32 v58, 3, v200
	v_readlane_b32 s4, v253, 5
	v_ashrrev_i32_e32 v59, 31, v58
	v_readlane_b32 s5, v253, 6
	v_lshlrev_b32_e32 v75, 6, v201
	s_waitcnt vmcnt(2)
	v_fma_f32 v68, v68, v176, v134
	v_fma_f32 v69, v69, v176, v135
	v_lshl_add_u64 v[58:59], v[58:59], 2, s[4:5]
	global_load_dwordx4 v[62:65], v[58:59], off
	s_nop 0
	global_load_dwordx4 v[58:61], v[58:59], off offset:16
	v_fma_f32 v66, v66, v176, v132
	v_fma_f32 v67, v67, v176, v133
	v_mov_b32_e32 v74, v177
	v_fma_f32 v72, v72, v176, v138
	v_fma_f32 v73, v73, v176, v139
	v_fma_f32 v70, v70, v176, v136
	v_fma_f32 v71, v71, v176, v137
	v_fma_f32 v56, v56, v174, v138
	v_fma_f32 v57, v57, v174, v139
	v_fma_f32 v54, v54, v174, v136
	v_fma_f32 v55, v55, v174, v137
	v_fma_f32 v76, v44, v174, v134
	v_fma_f32 v77, v45, v174, v135
	v_fma_f32 v78, v42, v174, v132
	v_fma_f32 v79, v43, v174, v133
	v_lshl_add_u32 v82, v200, 5, v75
	v_fma_f32 v52, v52, v74, v138
	v_fma_f32 v53, v53, v74, v139
	v_fma_f32 v50, v50, v74, v136
	v_fma_f32 v51, v51, v74, v137
	v_fma_f32 v80, v48, v74, v134
	v_fma_f32 v81, v49, v74, v135
	v_fma_f32 v75, v47, v74, v133
	v_fma_f32 v74, v46, v74, v132
	s_mov_b32 s4, 0xbfb8aa3b
	v_add_u32_e32 v83, 0x2b00000, v82
	v_add_u32_e32 v84, 0x2b00400, v82
	s_mov_b32 s8, 0x3f317218
	v_fma_f32 v26, v26, v172, v132
	v_fma_f32 v27, v27, v172, v133
	v_fma_f32 v28, v28, v172, v134
	v_fma_f32 v29, v29, v172, v135
	v_fma_f32 v32, v32, v172, v138
	v_fma_f32 v33, v33, v172, v139
	v_fma_f32 v30, v30, v172, v136
	v_fma_f32 v31, v31, v172, v137
	v_fma_f32 v10, v10, v170, v132
	v_fma_f32 v11, v11, v170, v133
	v_fma_f32 v12, v12, v170, v134
	v_fma_f32 v13, v13, v170, v135
	v_fma_f32 v16, v16, v170, v138
	v_fma_f32 v17, v17, v170, v139
	v_fma_f32 v14, v14, v170, v136
	v_fma_f32 v15, v15, v170, v137
	s_waitcnt vmcnt(1)
	v_add_f32_e32 v44, v72, v64
	v_add_f32_e32 v45, v73, v65
	s_waitcnt vmcnt(0)
	v_add_f32_e32 v68, v68, v60
	v_add_f32_e32 v69, v69, v61
	v_add_f32_e32 v66, v66, v58
	v_add_f32_e32 v67, v67, v59
	v_add_f32_e32 v42, v70, v62
	v_add_f32_e32 v43, v71, v63
	v_add_f32_e32 v48, v52, v64
	v_add_f32_e32 v49, v53, v65
	v_add_f32_e32 v46, v50, v62
	v_add_f32_e32 v47, v51, v63
	v_add_f32_e32 v70, v80, v60
	v_add_f32_e32 v71, v81, v61
	v_add_f32_e32 v72, v74, v58
	v_add_f32_e32 v73, v75, v59
	v_add_f32_e32 v52, v56, v64
	v_add_f32_e32 v53, v57, v65
	v_add_f32_e32 v50, v54, v62
	v_add_f32_e32 v51, v55, v63
	v_add_f32_e32 v54, v76, v60
	v_add_f32_e32 v55, v77, v61
	v_add_f32_e32 v56, v78, v58
	v_add_f32_e32 v57, v79, v59
	v_mul_f32_e64 v76, |v66|, s4
	v_mul_f32_e64 v77, |v67|, s4
	v_mul_f32_e64 v78, |v68|, s4
	v_mul_f32_e64 v79, |v69|, s4
	v_min_f32_e32 v74, 0, v66
	v_min_f32_e32 v66, 0, v68
	s_mov_b32 s100, 2
	global_store_dwordx4 v83, v[42:45], s[36:37] sc1
	v_min_f32_e32 v68, 0, v72
	s_mov_b32 s100, 2
	global_store_dwordx4 v84, v[46:49], s[36:37] sc1
	v_mul_f32_e64 v42, |v72|, s4
	v_mul_f32_e64 v43, |v73|, s4
	v_min_f32_e32 v72, 0, v70
	v_mul_f32_e64 v44, |v70|, s4
	v_mul_f32_e64 v45, |v71|, s4
	v_min_f32_e32 v70, 0, v56
	v_mul_f32_e64 v46, |v56|, s4
	v_exp_f32_e32 v47, v76
	v_exp_f32_e32 v48, v77
	v_exp_f32_e32 v49, v78
	v_exp_f32_e32 v56, v79
	v_exp_f32_e32 v42, v42
	v_exp_f32_e32 v43, v43
	v_exp_f32_e32 v44, v44
	v_exp_f32_e32 v45, v45
	v_exp_f32_e32 v46, v46
	v_add_f32_e32 v47, 1.0, v47
	v_add_f32_e32 v48, 1.0, v48
	v_add_f32_e32 v49, 1.0, v49
	v_add_f32_e32 v56, 1.0, v56
	v_min_f32_e32 v75, 0, v67
	v_min_f32_e32 v67, 0, v69
	v_min_f32_e32 v69, 0, v73
	v_min_f32_e32 v73, 0, v71
	v_min_f32_e32 v71, 0, v57
	v_mul_f32_e64 v80, |v57|, s4
	v_add_f32_e32 v42, 1.0, v42
	v_add_f32_e32 v43, 1.0, v43
	v_add_f32_e32 v44, 1.0, v44
	v_add_f32_e32 v45, 1.0, v45
	v_log_f32_e32 v57, v47
	v_log_f32_e32 v47, v48
	v_log_f32_e32 v48, v49
	v_log_f32_e32 v49, v56
	v_log_f32_e32 v56, v42
	v_log_f32_e32 v76, v43
	v_log_f32_e32 v44, v44
	v_log_f32_e32 v45, v45
	v_add_f32_e32 v46, 1.0, v46
	v_log_f32_e32 v77, v46
	v_xor_b32_e32 v43, 0x80000000, v49
	v_xor_b32_e32 v42, 0x80000000, v48
	v_xor_b32_e32 v47, 0x80000000, v47
	v_xor_b32_e32 v46, 0x80000000, v57
	v_xor_b32_e32 v49, 0x80000000, v45
	v_xor_b32_e32 v48, 0x80000000, v44
	v_xor_b32_e32 v57, 0x80000000, v76
	v_xor_b32_e32 v56, 0x80000000, v56
	v_fma_f32 v44, v42, s8, v66
	v_fma_f32 v45, v43, s8, v67
	v_fma_f32 v42, v46, s8, v74
	v_fma_f32 v43, v47, s8, v75
	v_fma_f32 v48, v48, s8, v72
	v_fma_f32 v49, v49, s8, v73
	v_fma_f32 v46, v56, s8, v68
	v_fma_f32 v47, v57, s8, v69
	s_mov_b32 s100, 2
	global_store_dwordx4 v83, v[42:45], s[36:37] offset:16 sc1
	s_mov_b32 s100, 2
	global_store_dwordx4 v84, v[46:49], s[36:37] offset:16 sc1
	v_add_f32_e32 v26, v26, v58
	v_add_f32_e32 v27, v27, v59
	v_exp_f32_e32 v42, v80
	v_mul_f32_e64 v43, |v54|, s4
	v_mul_f32_e64 v44, |v55|, s4
	v_exp_f32_e32 v43, v43
	v_exp_f32_e32 v44, v44
	v_add_f32_e32 v42, 1.0, v42
	v_log_f32_e32 v46, v42
	v_add_f32_e32 v42, 1.0, v43
	v_add_f32_e32 v43, 1.0, v44
	v_log_f32_e32 v44, v43
	v_log_f32_e32 v47, v42
	v_min_f32_e32 v42, 0, v54
	v_min_f32_e32 v43, 0, v55
	v_xor_b32_e32 v45, 0x80000000, v44
	v_xor_b32_e32 v44, 0x80000000, v47
	v_fma_f32 v44, v44, s8, v42
	v_fma_f32 v45, v45, s8, v43
	v_xor_b32_e32 v43, 0x80000000, v46
	v_xor_b32_e32 v42, 0x80000000, v77
	v_fma_f32 v42, v42, s8, v70
	v_fma_f32 v43, v43, s8, v71
	v_add_u32_e32 v46, 0x2b00800, v82
	s_mov_b32 s100, 2
	global_store_dwordx4 v46, v[50:53], s[36:37] sc1
	s_mov_b32 s100, 2
	global_store_dwordx4 v46, v[42:45], s[36:37] offset:16 sc1
	v_add_f32_e32 v28, v28, v60
; #define GAS __attribute__((address_space(1)))
; __device__ __forceinline__ float logsigf(float x) { return fminf(x, 0.f) - 0.6931471805599453f * __builtin_amdgcn_logf(1.f + __builtin_amdgcn_exp2f(-1.4426950408889634f * fabsf(x))); }
;     __device__ __forceinline__ void operator()(const f32x4 (&acc)[2][2][4][2], const pg8::Unit& u, int wr, int wc, int fr, int fq) const {
;     ...
;             if (s == 52) {
;                 if (fq < 2) { const f32x4 g0 = *(const GAS f32x4*)(bg + 8 * fq), g1 = *(const GAS f32x4*)(bg + 8 * fq + 4);
; #pragma unroll
;                     for (int ai = 0; ai < 2; ++ai)
; #pragma unroll
;                         for (int m = 0; m < 4; ++m) { const float r = rs[ai][m]; const f32x4 vi = acc[ai][0][m][0] * r + bv[0][0] + g0; f32x4 vf = acc[ai][0][m][1] * r + bv[0][1] + g1;
;                             vf = (f32x4){logsigf(vf[0]), logsigf(vf[1]), logsigf(vf[2]), logsigf(vf[3])};
;                             const unsigned go = (unsigned)WS_G + (rbase + ai * 128 + m * 16) * 64u + 32u * fq; stg_f4(wst, go, vi); stg_f4(wst, go + 16u, vf); } }
;                 return;
	v_add_f32_e32 v29, v29, v61
	v_add_f32_e32 v32, v32, v64
	v_add_f32_e32 v33, v33, v65
	v_mov_b32_e32 v42, v175
	v_fma_f32 v34, v34, v42, v132
	v_fma_f32 v35, v35, v42, v133
	v_fma_f32 v40, v40, v42, v138
	v_fma_f32 v41, v41, v42, v139
	v_add_f32_e32 v34, v34, v58
	v_add_f32_e32 v35, v35, v59
	v_fma_f32 v38, v38, v42, v136
	v_fma_f32 v39, v39, v42, v137
	v_mul_f32_e64 v43, |v34|, s4
	v_exp_f32_e32 v43, v43
	v_add_f32_e32 v40, v40, v64
	v_add_f32_e32 v41, v41, v65
	v_add_f32_e32 v38, v38, v62
	v_add_f32_e32 v39, v39, v63
	v_add_f32_e32 v30, v30, v62
	v_add_f32_e32 v31, v31, v63
	v_fma_f32 v36, v36, v42, v134
	v_fma_f32 v37, v37, v42, v135
	v_min_f32_e32 v42, 0, v34
	v_add_f32_e32 v34, 1.0, v43
	v_add_f32_e32 v36, v36, v60
	v_add_f32_e32 v37, v37, v61
	v_log_f32_e32 v44, v34
	v_mul_f32_e64 v34, |v35|, s4
	v_min_f32_e32 v43, 0, v35
	v_exp_f32_e32 v34, v34
	v_mul_f32_e64 v35, |v36|, s4
	v_mul_f32_e64 v45, |v37|, s4
	v_exp_f32_e32 v35, v35
	v_exp_f32_e32 v45, v45
	v_add_f32_e32 v34, 1.0, v34
	v_log_f32_e32 v46, v34
	v_add_f32_e32 v34, 1.0, v35
	v_add_f32_e32 v35, 1.0, v45
	v_log_f32_e32 v45, v35
	v_log_f32_e32 v47, v34
	v_min_f32_e32 v34, 0, v36
	v_min_f32_e32 v35, 0, v37
	v_xor_b32_e32 v37, 0x80000000, v45
	v_xor_b32_e32 v36, 0x80000000, v47
	v_fma_f32 v36, v36, s8, v34
	v_fma_f32 v37, v37, s8, v35
	v_xor_b32_e32 v35, 0x80000000, v46
	v_xor_b32_e32 v34, 0x80000000, v44
	v_fma_f32 v34, v34, s8, v42
	v_fma_f32 v35, v35, s8, v43
	v_add_u32_e32 v42, 0x2b00c00, v82
	s_mov_b32 s100, 2
	global_store_dwordx4 v42, v[38:41], s[36:37] sc1
	s_mov_b32 s100, 2
	global_store_dwordx4 v42, v[34:37], s[36:37] offset:16 sc1
	v_add_f32_e32 v10, v10, v58
	v_add_f32_e32 v11, v11, v59
	v_mul_f32_e64 v38, |v29|, s4
	v_mul_f32_e64 v34, |v26|, s4
	v_exp_f32_e32 v35, v34
	v_min_f32_e32 v34, 0, v26
	v_exp_f32_e32 v38, v38
	v_add_u32_e32 v36, 0x2b02000, v82
	v_add_f32_e32 v26, 1.0, v35
	v_log_f32_e32 v37, v26
	v_mul_f32_e64 v26, |v27|, s4
	v_min_f32_e32 v35, 0, v27
	v_exp_f32_e32 v26, v26
	v_mul_f32_e64 v27, |v28|, s4
	v_exp_f32_e32 v27, v27
	v_add_f32_e32 v12, v12, v60
	v_add_f32_e32 v13, v13, v61
	v_add_f32_e32 v26, 1.0, v26
	v_log_f32_e32 v39, v26
	v_add_f32_e32 v26, 1.0, v27
	v_add_f32_e32 v27, 1.0, v38
	v_log_f32_e32 v38, v27
	v_log_f32_e32 v40, v26
	v_min_f32_e32 v26, 0, v28
	v_min_f32_e32 v27, 0, v29
	v_xor_b32_e32 v29, 0x80000000, v38
	v_xor_b32_e32 v28, 0x80000000, v40
	v_fma_f32 v28, v28, s8, v26
	v_fma_f32 v29, v29, s8, v27
	v_xor_b32_e32 v27, 0x80000000, v39
	v_xor_b32_e32 v26, 0x80000000, v37
	v_fma_f32 v26, v26, s8, v34
	v_fma_f32 v27, v27, s8, v35
	s_mov_b32 s100, 2
	global_store_dwordx4 v36, v[30:33], s[36:37] sc1
	s_mov_b32 s100, 2
	global_store_dwordx4 v36, v[26:29], s[36:37] offset:16 sc1
	v_add_f32_e32 v16, v16, v64
	v_add_f32_e32 v17, v17, v65
	v_add_f32_e32 v14, v14, v62
	v_add_f32_e32 v15, v15, v63
	v_mov_b32_e32 v26, v173
	v_fma_f32 v18, v18, v26, v132
	v_fma_f32 v19, v19, v26, v133
	v_fma_f32 v24, v24, v26, v138
	v_fma_f32 v25, v25, v26, v139
	v_add_f32_e32 v18, v18, v58
	v_add_f32_e32 v19, v19, v59
	v_fma_f32 v22, v22, v26, v136
	v_fma_f32 v23, v23, v26, v137
	v_mul_f32_e64 v27, |v18|, s4
	v_exp_f32_e32 v27, v27
	v_add_f32_e32 v24, v24, v64
	v_add_f32_e32 v25, v25, v65
	v_add_f32_e32 v22, v22, v62
	v_add_f32_e32 v23, v23, v63
	v_fma_f32 v20, v20, v26, v134
	v_fma_f32 v21, v21, v26, v135
	v_min_f32_e32 v26, 0, v18
	v_add_f32_e32 v18, 1.0, v27
	v_add_f32_e32 v20, v20, v60
	v_add_f32_e32 v21, v21, v61
	v_log_f32_e32 v28, v18
	v_mul_f32_e64 v18, |v19|, s4
	v_min_f32_e32 v27, 0, v19
	v_exp_f32_e32 v18, v18
	v_mul_f32_e64 v19, |v20|, s4
	v_mul_f32_e64 v29, |v21|, s4
	v_exp_f32_e32 v19, v19
	v_exp_f32_e32 v29, v29
	v_add_f32_e32 v18, 1.0, v18
	v_log_f32_e32 v30, v18
	v_add_f32_e32 v18, 1.0, v19
	v_add_f32_e32 v19, 1.0, v29
	v_log_f32_e32 v29, v19
	v_log_f32_e32 v31, v18
	v_min_f32_e32 v18, 0, v20
	v_min_f32_e32 v19, 0, v21
	v_xor_b32_e32 v21, 0x80000000, v29
	v_xor_b32_e32 v20, 0x80000000, v31
	v_fma_f32 v20, v20, s8, v18
	v_fma_f32 v21, v21, s8, v19
	v_xor_b32_e32 v19, 0x80000000, v30
	v_xor_b32_e32 v18, 0x80000000, v28
	v_fma_f32 v18, v18, s8, v26
	v_fma_f32 v19, v19, s8, v27
	v_add_u32_e32 v26, 0x2b02400, v82
	s_mov_b32 s100, 2
	global_store_dwordx4 v26, v[22:25], s[36:37] sc1
	s_mov_b32 s100, 2
	global_store_dwordx4 v26, v[18:21], s[36:37] offset:16 sc1
	s_nop 1
	v_mul_f32_e64 v18, |v10|, s4
	v_exp_f32_e32 v19, v18
	v_min_f32_e32 v18, 0, v10
	v_mul_f32_e64 v21, |v13|, s4
	v_exp_f32_e32 v21, v21
	v_add_f32_e32 v10, 1.0, v19
	v_log_f32_e32 v20, v10
	v_mul_f32_e64 v10, |v11|, s4
	v_min_f32_e32 v19, 0, v11
	v_exp_f32_e32 v10, v10
	v_mul_f32_e64 v11, |v12|, s4
	v_exp_f32_e32 v11, v11
	v_add_f32_e32 v10, 1.0, v10
	v_log_f32_e32 v22, v10
	v_add_f32_e32 v10, 1.0, v11
	v_add_f32_e32 v11, 1.0, v21
	v_log_f32_e32 v21, v11
	v_log_f32_e32 v23, v10
	v_min_f32_e32 v10, 0, v12
	v_min_f32_e32 v11, 0, v13
	v_xor_b32_e32 v13, 0x80000000, v21
	v_xor_b32_e32 v12, 0x80000000, v23
	v_fma_f32 v12, v12, s8, v10
	v_fma_f32 v13, v13, s8, v11
	v_xor_b32_e32 v11, 0x80000000, v22
	v_xor_b32_e32 v10, 0x80000000, v20
	v_fma_f32 v10, v10, s8, v18
	v_fma_f32 v11, v11, s8, v19
	v_add_u32_e32 v18, 0x2b02800, v82
	s_mov_b32 s100, 2
	global_store_dwordx4 v18, v[14:17], s[36:37] sc1
	s_mov_b32 s100, 2
	global_store_dwordx4 v18, v[10:13], s[36:37] offset:16 sc1
	s_nop 1
	v_mov_b32_e32 v10, v171
	v_fma_f32 v2, v2, v10, v132
	v_fma_f32 v3, v3, v10, v133
	v_fma_f32 v8, v8, v10, v138
	v_fma_f32 v9, v9, v10, v139
	v_add_f32_e32 v2, v2, v58
	v_add_f32_e32 v3, v3, v59
	v_fma_f32 v6, v6, v10, v136
	v_fma_f32 v7, v7, v10, v137
	v_mul_f32_e64 v11, |v2|, s4
	v_exp_f32_e32 v11, v11
	v_add_f32_e32 v8, v8, v64
	v_add_f32_e32 v9, v9, v65
	v_add_f32_e32 v6, v6, v62
	v_add_f32_e32 v7, v7, v63
	v_fma_f32 v4, v4, v10, v134
	v_fma_f32 v5, v5, v10, v135
	v_min_f32_e32 v10, 0, v2
	v_add_f32_e32 v2, 1.0, v11
	v_add_f32_e32 v4, v4, v60
	v_add_f32_e32 v5, v5, v61
	v_log_f32_e32 v12, v2
	v_mul_f32_e64 v2, |v3|, s4
	v_min_f32_e32 v11, 0, v3
	v_exp_f32_e32 v2, v2
	v_mul_f32_e64 v3, |v4|, s4
	v_mul_f32_e64 v13, |v5|, s4
	v_exp_f32_e32 v3, v3
	v_exp_f32_e32 v13, v13
	v_add_f32_e32 v2, 1.0, v2
	v_log_f32_e32 v14, v2
	v_add_f32_e32 v2, 1.0, v3
	v_add_f32_e32 v3, 1.0, v13
	v_log_f32_e32 v13, v3
	v_log_f32_e32 v15, v2
	v_min_f32_e32 v2, 0, v4
	v_min_f32_e32 v3, 0, v5
	v_xor_b32_e32 v5, 0x80000000, v13
	v_xor_b32_e32 v4, 0x80000000, v15
	v_fma_f32 v4, v4, s8, v2
	v_fma_f32 v5, v5, s8, v3
	v_xor_b32_e32 v3, 0x80000000, v14
	v_xor_b32_e32 v2, 0x80000000, v12
	v_fma_f32 v2, v2, s8, v10
	v_fma_f32 v3, v3, s8, v11
	v_add_u32_e32 v10, 0x2b02c00, v82
	s_mov_b32 s100, 2
	global_store_dwordx4 v10, v[6:9], s[36:37] sc1
	s_mov_b32 s100, 2
	global_store_dwordx4 v10, v[2:5], s[36:37] offset:16 sc1

; #define GAS __attribute__((address_space(1)))
; __device__ __forceinline__ float lx_xor(float v, int m, int lane) { return __int_as_float(__builtin_amdgcn_ds_bpermute((lane ^ m) << 2, __float_as_int(v))); }
; __device__ __forceinline__ unsigned cvtpk_h(float lo, float hi) { f32x2 v = {lo, hi}; h16x2 b = __builtin_convertvector(v, h16x2); return __builtin_bit_cast(unsigned, b); }
; __device__ __forceinline__ void p0c(Frame& F) {
;     ...
;       for (int r0 = gw; r0 < MROWS; r0 += 2 * NGW) {
;           f32x4 xv[2][2][2]; int rr[2]; bool ok[2];
; #pragma unroll
;           for (int q = 0; q < 2; ++q) { rr[q] = r0 + q * NGW; ok[q] = rr[q] < MROWS; const int r = ok[q] ? rr[q] : gw; const float* xr = r < MLAT ? p.x + (size_t)r * D : p.ctx + (size_t)(r - MLAT) * D;
; #pragma unroll
;               for (int j = 0; j < 2; ++j) { const int k = j * 512 + F.lane * 8; xv[q][j][0] = *(const GAS f32x4*)(xr + k); xv[q][j][1] = *(const GAS f32x4*)(xr + k + 4); } }
; #pragma unroll
;           for (int q = 0; q < 2; ++q) { const int r = ok[q] ? rr[q] : gw; const int bb = r < MLAT ? (r >> 11) : 16; const float* mod = MOD + (size_t)bb * 3072 + 1024; float ss = 0.f;
; #pragma unroll
;               for (int j = 0; j < 2; ++j) { const int k = j * 512 + F.lane * 8; u32x4 wx, wy;
; #pragma unroll
;                   for (int hh = 0; hh < 2; ++hh) { const f32x4 v = xv[q][j][hh], g = *(const GAS f32x4*)(p.gnorm + k + 4 * hh), s1 = *(const GAS f32x4*)(mod + k + 4 * hh);
;                       ss += (v[0] * v[0] + v[1] * v[1]) + (v[2] * v[2] + v[3] * v[3]); const f32x4 y = v * (g * (s1 + 1.f));
;                       if (hh == 0) { wy.x = cvtpk_h(y[0], y[1]); wy.y = cvtpk_h(y[2], y[3]); wx.x = cvtpk_h(v[0], v[1]); wx.y = cvtpk_h(v[2], v[3]); } else { wy.z = cvtpk_h(y[0], y[1]); wy.w = cvtpk_h(y[2], y[3]); wx.z = cvtpk_h(v[0], v[1]); wx.w = cvtpk_h(v[2], v[3]); } }
;                   if (ok[q]) { *(GAS u32x4*)(XS + (size_t)r * D + k) = wy; *(GAS u32x4*)(X16 + (size_t)r * D + k) = wx; } }
; #pragma unroll
;               for (int o = 1; o < 64; o <<= 1) ss += lx_xor(ss, o, F.lane);
;               if (ok[q] && F.lane == 0) *(GAS float*)(RQ + r) = ss; } }
.LBB0_704:
	s_add_i32 s2, s6, 0xffff8000
	s_cmp_lt_i32 s6, 0x8000
	v_readlane_b32 s56, v251, 15
	s_cselect_b32 s3, s7, 0
	s_cselect_b32 s2, s6, s2
	v_readlane_b32 s57, v251, 16
	v_readlane_b32 s60, v251, 19
	v_readlane_b32 s61, v251, 20
	s_cselect_b32 s5, s57, s61
	s_cselect_b32 s8, s56, s60
	s_lshl_b64 s[2:3], s[2:3], 12
	s_add_u32 s2, s8, s2
	s_addc_u32 s3, s5, s3
	v_lshlrev_b64 v[44:45], 2, v[36:37]
	s_waitcnt lgkmcnt(0)
	v_lshl_add_u64 v[2:3], s[2:3], 0, v[44:45]
	global_load_dwordx4 v[26:29], v[2:3], off offset:16
	global_load_dwordx4 v[30:33], v[2:3], off
	global_load_dwordx4 v[18:21], v[2:3], off offset:2064
	global_load_dwordx4 v[22:25], v[2:3], off offset:2048
	s_add_i32 s5, s78, s6
	s_cmp_lt_i32 s5, 0x9000
	s_cselect_b64 s[10:11], -1, 0
	s_and_b64 s[2:3], s[10:11], exec
	s_cselect_b32 s8, s5, s4
	s_ashr_i32 s9, s8, 31
	s_add_i32 s2, s8, 0xffff8000
	s_cmp_lt_i32 s8, 0x8000
	s_cselect_b32 s3, s9, 0
	s_cselect_b32 s2, s8, s2
	s_cselect_b32 s5, s57, s61
	s_cselect_b32 s12, s56, s60
	s_lshl_b64 s[2:3], s[2:3], 12
	s_add_u32 s2, s12, s2
	s_addc_u32 s3, s5, s3
	v_lshl_add_u64 v[6:7], s[2:3], 0, v[44:45]
	s_min_i32 s2, s6, 0x8000
	s_ashr_i32 s2, s2, 11
	s_mul_hi_i32 s3, s2, 0x3000
	s_mulk_i32 s2, 0x3000
	s_add_u32 s2, s36, s2
	s_addc_u32 s3, s37, s3
	v_lshl_add_u64 v[60:61], s[2:3], 0, v[44:45]
	s_mov_b64 s[2:3], 0x1000
	v_lshl_add_u64 v[44:45], v[60:61], 0, s[2:3]
	s_movk_i32 s2, 0x1000
	v_add_co_u32_e32 v60, vcc, s2, v60
	global_load_dwordx4 v[10:13], v[6:7], off offset:16
	global_load_dwordx4 v[14:17], v[6:7], off
	global_load_dwordx4 v[2:5], v[6:7], off offset:2064
	s_nop 0
	global_load_dwordx4 v[6:9], v[6:7], off offset:2048
	v_addc_co_u32_e32 v61, vcc, 0, v61, vcc
	v_readlane_b32 s2, v253, 0
	v_readlane_b32 s3, v253, 1
	v_readlane_b32 s58, v251, 17
	v_readlane_b32 s59, v251, 18
	v_readlane_b32 s62, v251, 21
	v_readlane_b32 s63, v251, 22
	v_readlane_b32 s64, v251, 23
	v_readlane_b32 s65, v251, 24
	v_readlane_b32 s66, v251, 25
	v_readlane_b32 s67, v251, 26
	v_readlane_b32 s68, v251, 27
	v_readlane_b32 s69, v251, 28
	v_readlane_b32 s70, v251, 29
	v_readlane_b32 s71, v251, 30
	s_waitcnt vmcnt(0)
	v_mul_f32_e32 v46, v31, v31
	v_mul_f32_e32 v47, v33, v33
	v_fmac_f32_e32 v46, v30, v30
	v_fmac_f32_e32 v47, v32, v32
	v_add_f32_e32 v55, v46, v47
	global_load_dwordx4 v[46:49], v[40:41], off offset:16
	global_load_dwordx4 v[56:59], v[40:41], off
	s_nop 0
	global_load_dwordx4 v[60:63], v[60:61], off
	s_nop 0
	global_load_dwordx4 v[64:67], v[44:45], off offset:16
	s_waitcnt vmcnt(0)
	v_add_f32_e32 v62, 1.0, v62
	v_add_f32_e32 v63, 1.0, v63
	v_add_f32_e32 v60, 1.0, v60
	v_add_f32_e32 v61, 1.0, v61
	v_mul_f32_e32 v58, v58, v62
	v_mul_f32_e32 v59, v59, v63
	v_mul_f32_e32 v56, v56, v60
	v_mul_f32_e32 v57, v57, v61
	v_mul_f32_e32 v58, v32, v58
	v_mul_f32_e32 v59, v33, v59
	v_mul_f32_e32 v56, v30, v56
	v_mul_f32_e32 v57, v31, v57
	v_cvt_pk_f16_f32 v30, v30, v31
	v_cvt_pk_f16_f32 v31, v32, v33
	v_mul_f32_e32 v32, v27, v27
	v_mul_f32_e32 v33, v29, v29
	v_fmac_f32_e32 v32, v26, v26
	v_fmac_f32_e32 v33, v28, v28
	v_add_f32_e32 v32, v32, v33
	v_add_f32_e32 v55, v55, v32
	v_add_f32_e32 v32, 1.0, v66
	v_add_f32_e32 v33, 1.0, v67
	v_cvt_pk_f16_f32 v56, v56, v57
	v_cvt_pk_f16_f32 v57, v58, v59
	v_add_f32_e32 v58, 1.0, v64
	v_add_f32_e32 v59, 1.0, v65
	v_mul_f32_e32 v32, v48, v32
	v_mul_f32_e32 v33, v49, v33
	v_mul_f32_e32 v46, v46, v58
	v_mul_f32_e32 v47, v47, v59
	v_mul_f32_e32 v32, v28, v32
	v_mul_f32_e32 v33, v29, v33
	v_mul_f32_e32 v46, v26, v46
	v_mul_f32_e32 v47, v27, v47
	v_cvt_pk_f16_f32 v59, v32, v33
	v_cvt_pk_f16_f32 v32, v26, v27
	v_lshl_add_u64 v[26:27], s[2:3], 0, v[42:43]
	s_mov_b32 s2, 0x3d80000
	v_cvt_pk_f16_f32 v58, v46, v47
	v_add_co_u32_e32 v46, vcc, s2, v26
	s_mov_b32 s2, 0x16f80000
	s_nop 0
	v_addc_co_u32_e32 v47, vcc, 0, v27, vcc
	v_add_co_u32_e32 v48, vcc, s2, v26
	v_mul_f32_e32 v26, v23, v23
	s_nop 0
	v_addc_co_u32_e32 v49, vcc, 0, v27, vcc
	v_mul_f32_e32 v27, v25, v25
	v_cvt_pk_f16_f32 v33, v28, v29
	v_fmac_f32_e32 v26, v22, v22
	v_fmac_f32_e32 v27, v24, v24
	global_store_dwordx4 v[46:47], v[56:59], off sc1
	global_store_dwordx4 v[48:49], v[30:33], off sc1
	v_add_f32_e32 v26, v26, v27
	v_add_f32_e32 v55, v55, v26
	global_load_dwordx4 v[26:29], v[40:41], off offset:2064
	global_load_dwordx4 v[56:59], v[40:41], off offset:2048
	global_load_dwordx4 v[30:33], v[44:45], off offset:2064
	global_load_dwordx4 v[60:63], v[44:45], off offset:2048
	s_waitcnt vmcnt(0)
	v_add_f32_e32 v30, 1.0, v30
	v_add_f32_e32 v31, 1.0, v31
	v_add_f32_e32 v44, 1.0, v62
	v_add_f32_e32 v45, 1.0, v63
	v_add_f32_e32 v60, 1.0, v60
	v_add_f32_e32 v61, 1.0, v61
	v_mul_f32_e32 v44, v58, v44
	v_mul_f32_e32 v45, v59, v45
	v_mul_f32_e32 v56, v56, v60
	v_mul_f32_e32 v57, v57, v61
	v_mul_f32_e32 v44, v24, v44
	v_mul_f32_e32 v45, v25, v45
	v_mul_f32_e32 v56, v22, v56
	v_mul_f32_e32 v57, v23, v57
	v_cvt_pk_f16_f32 v22, v22, v23
	v_cvt_pk_f16_f32 v23, v24, v25
	v_mul_f32_e32 v24, v19, v19
	v_mul_f32_e32 v25, v21, v21
	v_fmac_f32_e32 v24, v18, v18
	v_fmac_f32_e32 v25, v20, v20
	v_add_f32_e32 v24, v24, v25
	v_cvt_pk_f16_f32 v56, v56, v57
	v_cvt_pk_f16_f32 v57, v44, v45
	v_add_f32_e32 v44, v55, v24
	v_add_f32_e32 v24, 1.0, v32
	v_add_f32_e32 v25, 1.0, v33
	v_mul_f32_e32 v26, v26, v30
	v_mul_f32_e32 v27, v27, v31
	v_mul_f32_e32 v24, v28, v24
	v_mul_f32_e32 v25, v29, v25
	v_mul_f32_e32 v26, v18, v26
	v_mul_f32_e32 v27, v19, v27
	v_mul_f32_e32 v24, v20, v24
	v_mul_f32_e32 v25, v21, v25
	v_cvt_pk_f16_f32 v58, v26, v27
	v_cvt_pk_f16_f32 v59, v24, v25
	v_cvt_pk_f16_f32 v24, v18, v19
	ds_bpermute_b32 v18, v0, v44
	v_cvt_pk_f16_f32 v25, v20, v21
	global_store_dwordx4 v[46:47], v[56:59], off offset:1024 sc1
	global_store_dwordx4 v[48:49], v[22:25], off offset:1024 sc1
	s_waitcnt lgkmcnt(0)
	v_add_f32_e32 v18, v44, v18
	ds_bpermute_b32 v19, v50, v18
	s_waitcnt lgkmcnt(0)
	v_add_f32_e32 v18, v18, v19
	ds_bpermute_b32 v19, v51, v18
	s_waitcnt lgkmcnt(0)
	v_add_f32_e32 v18, v18, v19
	ds_bpermute_b32 v19, v52, v18
	s_waitcnt lgkmcnt(0)
	v_add_f32_e32 v18, v18, v19
	ds_bpermute_b32 v19, v53, v18
	s_waitcnt lgkmcnt(0)
	v_add_f32_e32 v18, v18, v19
	ds_bpermute_b32 v19, v54, v18
	s_and_saveexec_b64 s[2:3], s[0:1]
	s_cbranch_execz .LBB0_706
	v_readlane_b32 s12, v253, 0
	v_readlane_b32 s13, v253, 1
	s_add_u32 s12, s12, s20
	s_addc_u32 s13, s13, s21
	s_waitcnt lgkmcnt(0)
	v_add_f32_e32 v18, v18, v19
	s_nop 0
	global_store_dword v1, v18, s[12:13] sc1
; #define GAS __attribute__((address_space(1)))
; __device__ __forceinline__ float lx_xor(float v, int m, int lane) { return __int_as_float(__builtin_amdgcn_ds_bpermute((lane ^ m) << 2, __float_as_int(v))); }
; __device__ __forceinline__ unsigned cvtpk_h(float lo, float hi) { f32x2 v = {lo, hi}; h16x2 b = __builtin_convertvector(v, h16x2); return __builtin_bit_cast(unsigned, b); }
; __device__ __forceinline__ void p0c(Frame& F) {
;     ...
;           for (int q = 0; q < 2; ++q) { const int r = ok[q] ? rr[q] : gw; const int bb = r < MLAT ? (r >> 11) : 16; const float* mod = MOD + (size_t)bb * 3072 + 1024; float ss = 0.f;
; #pragma unroll
;               for (int j = 0; j < 2; ++j) { const int k = j * 512 + F.lane * 8; u32x4 wx, wy;
; #pragma unroll
;                   for (int hh = 0; hh < 2; ++hh) { const f32x4 v = xv[q][j][hh], g = *(const GAS f32x4*)(p.gnorm + k + 4 * hh), s1 = *(const GAS f32x4*)(mod + k + 4 * hh);
;                       ss += (v[0] * v[0] + v[1] * v[1]) + (v[2] * v[2] + v[3] * v[3]); const f32x4 y = v * (g * (s1 + 1.f));
;                       if (hh == 0) { wy.x = cvtpk_h(y[0], y[1]); wy.y = cvtpk_h(y[2], y[3]); wx.x = cvtpk_h(v[0], v[1]); wx.y = cvtpk_h(v[2], v[3]); } else { wy.z = cvtpk_h(y[0], y[1]); wy.w = cvtpk_h(y[2], y[3]); wx.z = cvtpk_h(v[0], v[1]); wx.w = cvtpk_h(v[2], v[3]); } }
;                   if (ok[q]) { *(GAS u32x4*)(XS + (size_t)r * D + k) = wy; *(GAS u32x4*)(X16 + (size_t)r * D + k) = wx; } }
; #pragma unroll
;               for (int o = 1; o < 64; o <<= 1) ss += lx_xor(ss, o, F.lane);
;               if (ok[q] && F.lane == 0) *(GAS float*)(RQ + r) = ss; } }
.LBB0_706:
	s_or_b64 exec, exec, s[2:3]
	s_min_i32 s2, s8, 0x8000
	s_ashr_i32 s2, s2, 11
	s_mul_hi_i32 s3, s2, 0x3000
	s_mulk_i32 s2, 0x3000
	s_add_u32 s2, s36, s2
	s_addc_u32 s3, s37, s3
	s_add_u32 s12, s2, 0x1000
	s_addc_u32 s13, s3, 0
	s_lshl_b64 s[2:3], s[8:9], 11
	s_add_u32 s22, s16, s2
	s_addc_u32 s23, s17, s3
	s_add_u32 s24, s14, s2
	s_addc_u32 s25, s15, s3
	v_cndmask_b32_e64 v18, 0, 1, s[10:11]
	v_lshlrev_b64 v[20:21], 1, v[36:37]
	v_cmp_ne_u32_e64 s[2:3], 1, v18
	s_andn2_b64 vcc, exec, s[10:11]
	s_waitcnt lgkmcnt(0)
	v_lshl_add_u64 v[18:19], s[22:23], 0, v[20:21]
	v_lshl_add_u64 v[20:21], s[24:25], 0, v[20:21]
	s_cbranch_vccnz .LBB0_708
	v_lshl_add_u64 v[26:27], v[36:37], 2, s[12:13]
	global_load_dwordx4 v[22:25], v[26:27], off
	s_nop 0
	global_load_dwordx4 v[26:29], v[26:27], off offset:16
	s_nop 0
	global_load_dwordx4 v[30:33], v[40:41], off
	global_load_dwordx4 v[44:47], v[40:41], off offset:16
	v_cvt_pk_f16_f32 v56, v14, v15
	v_cvt_pk_f16_f32 v57, v16, v17
	v_cvt_pk_f16_f32 v58, v10, v11
	v_cvt_pk_f16_f32 v59, v12, v13
	s_waitcnt vmcnt(3)
	v_add_f32_e32 v24, 1.0, v24
	v_add_f32_e32 v25, 1.0, v25
	v_add_f32_e32 v22, 1.0, v22
	v_add_f32_e32 v23, 1.0, v23
	s_waitcnt vmcnt(2)
	v_add_f32_e32 v28, 1.0, v28
	v_add_f32_e32 v29, 1.0, v29
	v_add_f32_e32 v26, 1.0, v26
	v_add_f32_e32 v27, 1.0, v27
	s_waitcnt vmcnt(1)
	v_mul_f32_e32 v24, v32, v24
	v_mul_f32_e32 v25, v33, v25
	v_mul_f32_e32 v22, v30, v22
	v_mul_f32_e32 v23, v31, v23
	s_waitcnt vmcnt(0)
	v_mul_f32_e32 v28, v46, v28
	v_mul_f32_e32 v29, v47, v29
	v_mul_f32_e32 v26, v44, v26
	v_mul_f32_e32 v27, v45, v27
	v_mul_f32_e32 v24, v16, v24
	v_mul_f32_e32 v25, v17, v25
	v_mul_f32_e32 v22, v14, v22
	v_mul_f32_e32 v23, v15, v23
	v_mul_f32_e32 v28, v12, v28
	v_mul_f32_e32 v29, v13, v29
	v_mul_f32_e32 v26, v10, v26
	v_mul_f32_e32 v27, v11, v27
	v_cvt_pk_f16_f32 v22, v22, v23
	v_cvt_pk_f16_f32 v23, v24, v25
	v_cvt_pk_f16_f32 v24, v26, v27
	v_cvt_pk_f16_f32 v25, v28, v29
	global_store_dwordx4 v[20:21], v[22:25], off sc1
	global_store_dwordx4 v[18:19], v[56:59], off sc1
.LBB0_708:
	v_readlane_b32 s30, v252, 54
	s_and_b64 vcc, exec, s[2:3]
	v_readlane_b32 s31, v252, 55
	s_cbranch_vccnz .LBB0_710
	v_lshl_add_u64 v[26:27], v[38:39], 2, s[12:13]
	global_load_dwordx4 v[22:25], v[26:27], off
	s_nop 0
	global_load_dwordx4 v[26:29], v[26:27], off offset:16
	s_nop 0
	global_load_dwordx4 v[30:33], v[40:41], off offset:2048
	global_load_dwordx4 v[44:47], v[40:41], off offset:2064
	v_cvt_pk_f16_f32 v56, v6, v7
	v_cvt_pk_f16_f32 v57, v8, v9
	v_cvt_pk_f16_f32 v58, v2, v3
	v_cvt_pk_f16_f32 v59, v4, v5
	s_waitcnt vmcnt(3)
	v_add_f32_e32 v24, 1.0, v24
	v_add_f32_e32 v25, 1.0, v25
	v_add_f32_e32 v22, 1.0, v22
	v_add_f32_e32 v23, 1.0, v23
	s_waitcnt vmcnt(2)
	v_add_f32_e32 v28, 1.0, v28
	v_add_f32_e32 v29, 1.0, v29
	v_add_f32_e32 v26, 1.0, v26
	v_add_f32_e32 v27, 1.0, v27
	s_waitcnt vmcnt(1)
	v_mul_f32_e32 v24, v32, v24
	v_mul_f32_e32 v25, v33, v25
	v_mul_f32_e32 v22, v30, v22
	v_mul_f32_e32 v23, v31, v23
	s_waitcnt vmcnt(0)
	v_mul_f32_e32 v28, v46, v28
	v_mul_f32_e32 v29, v47, v29
	v_mul_f32_e32 v26, v44, v26
	v_mul_f32_e32 v27, v45, v27
	v_mul_f32_e32 v24, v8, v24
	v_mul_f32_e32 v25, v9, v25
	v_mul_f32_e32 v22, v6, v22
	v_mul_f32_e32 v23, v7, v23
	v_mul_f32_e32 v28, v4, v28
	v_mul_f32_e32 v29, v5, v29
	v_mul_f32_e32 v26, v2, v26
	v_mul_f32_e32 v27, v3, v27
	v_cvt_pk_f16_f32 v22, v22, v23
	v_cvt_pk_f16_f32 v23, v24, v25
	v_cvt_pk_f16_f32 v24, v26, v27
	v_cvt_pk_f16_f32 v25, v28, v29
	global_store_dwordx4 v[20:21], v[22:25], off offset:1024 sc1
	global_store_dwordx4 v[18:19], v[56:59], off offset:1024 sc1

; #define LAS __attribute__((address_space(3)))
; #define GAS __attribute__((address_space(1)))
; __device__ __forceinline__ float siluf(float x) { return x * __builtin_amdgcn_rcpf(1.f + __builtin_amdgcn_exp2f(-1.4426950408889634f * x)); }
; __device__ __forceinline__ void p0ab(Frame& F) {
;     ...
;           if (!loaded) { f32x4 tv[9];
; #pragma unroll
;               for (int j = 0; j < 9; ++j) { const int i = F.tid + NTHREADS * j, bb = i >> 8, k4 = i & 255; const float* src = bb < 16 ? p.c + bb * D : p.cctx; tv[j] = (j < 8 || F.tid < 256) ? *(const GAS f32x4*)(src + 4 * k4) : (f32x4){0.f, 0.f, 0.f, 0.f}; }
; #pragma unroll
;               for (int j = 0; j < 9; ++j) { const int i = F.tid + NTHREADS * j; if (j < 8 || F.tid < 256) *(LAS f32x4*)(AL + 4 * i) = (f32x4){siluf(tv[j][0]), siluf(tv[j][1]), siluf(tv[j][2]), siluf(tv[j][3])}; }
;               __syncthreads(); loaded = true; }
.LBB0_779:
	s_or_b64 exec, exec, s[6:7]
	s_waitcnt vmcnt(0)
	v_mul_f32_e32 v58, 0xbfb8aa3b, v34
	v_exp_f32_e32 v58, v58
	v_mul_f32_e32 v59, 0xbfb8aa3b, v35
	v_mul_f32_e32 v60, 0xbfb8aa3b, v36
	v_exp_f32_e32 v60, v60
	v_add_f32_e32 v61, 1.0, v58
	v_mul_f32_e32 v58, 0xbfb8aa3b, v37
	v_exp_f32_e32 v62, v58
	v_exp_f32_e32 v63, v59
	v_add_f32_e32 v58, 1.0, v60
	v_rcp_f32_e32 v60, v61
	v_add_f32_e32 v59, 1.0, v62
	v_add_f32_e32 v61, 1.0, v63
	v_rcp_f32_e32 v58, v58
	v_rcp_f32_e32 v59, v59
	v_rcp_f32_e32 v61, v61
	v_mul_f32_e32 v36, v36, v58
	v_mul_f32_e32 v37, v37, v59
	v_mul_f32_e32 v34, v34, v60
	v_mul_f32_e32 v35, v35, v61
	v_add_u32_e32 v59, s74, v163
	s_waitcnt vmcnt(6)
	v_mul_f32_e32 v58, 0xbfb8aa3b, v30
	ds_write_b128 v59, v[34:37]
	v_mul_f32_e32 v35, 0xbfb8aa3b, v31
	v_mul_f32_e32 v36, 0xbfb8aa3b, v32
	v_mul_f32_e32 v37, 0xbfb8aa3b, v33
	v_exp_f32_e32 v58, v58
	v_exp_f32_e32 v35, v35
	v_exp_f32_e32 v36, v36
	v_exp_f32_e32 v37, v37
	v_add_f32_e32 v34, 1.0, v58
	v_add_f32_e32 v35, 1.0, v35
	v_add_f32_e32 v36, 1.0, v36
	v_add_f32_e32 v37, 1.0, v37
	v_rcp_f32_e32 v34, v34
	v_rcp_f32_e32 v36, v36
	v_rcp_f32_e32 v37, v37
	v_rcp_f32_e32 v35, v35
	s_waitcnt vmcnt(5)
	v_mul_f32_e32 v58, 0xbfb8aa3b, v26
	v_exp_f32_e32 v58, v58
	v_mul_f32_e32 v32, v32, v36
	v_mul_f32_e32 v33, v33, v37
	v_mul_f32_e32 v30, v30, v34
	v_mul_f32_e32 v31, v31, v35
	ds_write_b128 v59, v[30:33] offset:8192
	v_mul_f32_e32 v31, 0xbfb8aa3b, v27
	v_mul_f32_e32 v32, 0xbfb8aa3b, v28
	v_mul_f32_e32 v33, 0xbfb8aa3b, v29
	v_exp_f32_e32 v31, v31
	v_exp_f32_e32 v32, v32
	v_exp_f32_e32 v33, v33
	v_add_f32_e32 v30, 1.0, v58
	v_add_f32_e32 v31, 1.0, v31
	v_add_f32_e32 v32, 1.0, v32
	v_add_f32_e32 v33, 1.0, v33
	v_rcp_f32_e32 v30, v30
	v_rcp_f32_e32 v32, v32
	v_rcp_f32_e32 v33, v33
	v_rcp_f32_e32 v31, v31
	s_waitcnt vmcnt(4)
	v_mul_f32_e32 v34, 0xbfb8aa3b, v22
	v_exp_f32_e32 v34, v34
	v_mul_f32_e32 v28, v28, v32
	v_mul_f32_e32 v29, v29, v33
	v_mul_f32_e32 v26, v26, v30
	v_mul_f32_e32 v27, v27, v31
	ds_write_b128 v59, v[26:29] offset:16384
	v_mul_f32_e32 v27, 0xbfb8aa3b, v23
	v_mul_f32_e32 v28, 0xbfb8aa3b, v24
	v_mul_f32_e32 v29, 0xbfb8aa3b, v25
	v_exp_f32_e32 v27, v27
	v_exp_f32_e32 v28, v28
	v_exp_f32_e32 v29, v29
	v_add_f32_e32 v26, 1.0, v34
	v_add_f32_e32 v27, 1.0, v27
	v_add_f32_e32 v28, 1.0, v28
	v_add_f32_e32 v29, 1.0, v29
	v_rcp_f32_e32 v26, v26
	v_rcp_f32_e32 v28, v28
	v_rcp_f32_e32 v29, v29
	v_rcp_f32_e32 v27, v27
	s_waitcnt vmcnt(3)
	v_mul_f32_e32 v30, 0xbfb8aa3b, v18
	v_exp_f32_e32 v30, v30
	v_mul_f32_e32 v24, v24, v28
	v_mul_f32_e32 v25, v25, v29
	v_mul_f32_e32 v22, v22, v26
	v_mul_f32_e32 v23, v23, v27
	ds_write_b128 v59, v[22:25] offset:24576
	v_mul_f32_e32 v23, 0xbfb8aa3b, v19
	v_mul_f32_e32 v24, 0xbfb8aa3b, v20
	v_mul_f32_e32 v25, 0xbfb8aa3b, v21
	v_exp_f32_e32 v23, v23
	v_exp_f32_e32 v24, v24
	v_exp_f32_e32 v25, v25
	v_add_f32_e32 v22, 1.0, v30
	v_add_f32_e32 v23, 1.0, v23
	v_add_f32_e32 v24, 1.0, v24
	v_add_f32_e32 v25, 1.0, v25
	v_rcp_f32_e32 v22, v22
	v_rcp_f32_e32 v24, v24
	v_rcp_f32_e32 v25, v25
	v_rcp_f32_e32 v23, v23
	s_waitcnt vmcnt(2)
	v_mul_f32_e32 v26, 0xbfb8aa3b, v14
	v_exp_f32_e32 v26, v26
	v_mul_f32_e32 v20, v20, v24
	v_mul_f32_e32 v21, v21, v25
	v_mul_f32_e32 v18, v18, v22
	v_mul_f32_e32 v19, v19, v23
	ds_write_b128 v59, v[18:21] offset:32768
	v_mul_f32_e32 v19, 0xbfb8aa3b, v15
	v_mul_f32_e32 v20, 0xbfb8aa3b, v16
	v_mul_f32_e32 v21, 0xbfb8aa3b, v17
	v_exp_f32_e32 v19, v19
	v_exp_f32_e32 v20, v20
	v_exp_f32_e32 v21, v21
	v_add_f32_e32 v18, 1.0, v26
	v_add_f32_e32 v19, 1.0, v19
	v_add_f32_e32 v20, 1.0, v20
	v_add_f32_e32 v21, 1.0, v21
	v_rcp_f32_e32 v18, v18
	v_rcp_f32_e32 v20, v20
	v_rcp_f32_e32 v21, v21
	v_rcp_f32_e32 v19, v19
	s_waitcnt vmcnt(1)
	v_mul_f32_e32 v22, 0xbfb8aa3b, v10
	v_exp_f32_e32 v22, v22
	v_mul_f32_e32 v16, v16, v20
	v_mul_f32_e32 v17, v17, v21
	v_mul_f32_e32 v14, v14, v18
	v_mul_f32_e32 v15, v15, v19
	ds_write_b128 v59, v[14:17] offset:40960
	v_mul_f32_e32 v16, 0xbfb8aa3b, v12
	v_mul_f32_e32 v17, 0xbfb8aa3b, v13
	v_exp_f32_e32 v16, v16
	v_exp_f32_e32 v17, v17
	s_waitcnt vmcnt(0)
	v_mul_f32_e32 v18, 0xbfb8aa3b, v6
	v_exp_f32_e32 v18, v18
	v_add_f32_e32 v16, 1.0, v16
	v_add_f32_e32 v17, 1.0, v17
	v_rcp_f32_e32 v16, v16
	v_rcp_f32_e32 v17, v17
	v_mul_f32_e32 v15, 0xbfb8aa3b, v11
	v_mul_f32_e32 v19, 0xbfb8aa3b, v9
	v_exp_f32_e32 v15, v15
	v_mul_f32_e32 v12, v12, v16
	v_mul_f32_e32 v13, v13, v17
	v_add_f32_e32 v16, 1.0, v18
	v_mul_f32_e32 v17, 0xbfb8aa3b, v7
	v_mul_f32_e32 v18, 0xbfb8aa3b, v8
	v_exp_f32_e32 v17, v17
	v_exp_f32_e32 v18, v18
	v_exp_f32_e32 v19, v19
	v_add_f32_e32 v14, 1.0, v22
	v_add_f32_e32 v15, 1.0, v15
	v_add_f32_e32 v17, 1.0, v17
	v_add_f32_e32 v18, 1.0, v18
	v_add_f32_e32 v19, 1.0, v19
	v_rcp_f32_e32 v14, v14
	v_rcp_f32_e32 v15, v15
	v_rcp_f32_e32 v16, v16
	v_rcp_f32_e32 v18, v18
	v_rcp_f32_e32 v19, v19
	v_rcp_f32_e32 v17, v17
	v_mul_f32_e32 v10, v10, v14
	v_mul_f32_e32 v11, v11, v15
	ds_write_b128 v59, v[10:13] offset:49152
	v_mul_f32_e32 v8, v8, v18
	v_mul_f32_e32 v9, v9, v19
	v_mul_f32_e32 v6, v6, v16
	v_mul_f32_e32 v7, v7, v17
	ds_write_b128 v59, v[6:9] offset:57344
	s_and_saveexec_b64 s[6:7], s[4:5]
	s_cbranch_execz .LBB0_781
	v_mul_f32_e32 v6, 0xbfb8aa3b, v2
	v_mul_f32_e32 v7, 0xbfb8aa3b, v3
	v_mul_f32_e32 v8, 0xbfb8aa3b, v4
	v_mul_f32_e32 v9, 0xbfb8aa3b, v5
	v_exp_f32_e32 v6, v6
	v_exp_f32_e32 v7, v7
	v_exp_f32_e32 v8, v8
	v_exp_f32_e32 v9, v9
	v_add_f32_e32 v6, 1.0, v6
	v_add_f32_e32 v7, 1.0, v7
	v_add_f32_e32 v8, 1.0, v8
	v_add_f32_e32 v9, 1.0, v9
	v_rcp_f32_e32 v6, v6
	v_rcp_f32_e32 v8, v8
	v_rcp_f32_e32 v9, v9
	v_rcp_f32_e32 v7, v7
	v_mul_f32_e32 v4, v4, v8
	v_mul_f32_e32 v5, v5, v9
	v_mul_f32_e32 v2, v2, v6
	v_mul_f32_e32 v3, v3, v7
	v_add_u32_e32 v6, s12, v163
	ds_write_b128 v6, v[2:5]

; #define LAS __attribute__((address_space(3)))
; #define GAS __attribute__((address_space(1)))
; __device__ __forceinline__ void skinny_item(Frame& F, const LAS float* AL, LAS float* RED, const float* W, int ldw, int nvalid, int n0, const float* bias, float* out, int ldo) {
;     ...
;     for (int k = 0; k < 32; k += 8) {
;         f32x4 w[8];
; #pragma unroll
;         for (int j = 0; j < 8; ++j) w[j] = valid ? *(const GAS f32x4*)(wp + (size_t)(k + j) * ldw) : (f32x4){0.f, 0.f, 0.f, 0.f};
; #pragma unroll
;         for (int q = 0; q < 2; ++q)
; #pragma unroll
;             for (int i = 0; i < 17; ++i) { const f32x4 a = *(const LAS f32x4*)(AL + i * 1024 + kg * 32 + k + 4 * q); acc[i] += (w[4 * q] * a[0] + w[4 * q + 1] * a[1]) + (w[4 * q + 2] * a[2] + w[4 * q + 3] * a[3]); }
.LBB0_783:
	v_add_co_u32_e32 v2, vcc, s93, v58
	global_load_dwordx4 v[18:21], v[58:59], off
	s_nop 0
	v_addc_co_u32_e32 v3, vcc, 0, v59, vcc
	global_load_dwordx4 v[26:29], v[2:3], off
	v_add_co_u32_e32 v2, vcc, s90, v58
	s_mov_b32 s8, 0x9000
	s_nop 0
	v_addc_co_u32_e32 v3, vcc, 0, v59, vcc
	global_load_dwordx4 v[22:25], v[2:3], off
	v_add_co_u32_e32 v2, vcc, s8, v58
	s_mov_b32 s8, 0xc000
	s_nop 0
	v_addc_co_u32_e32 v3, vcc, 0, v59, vcc
	global_load_dwordx4 v[30:33], v[2:3], off
	v_add_co_u32_e32 v2, vcc, s8, v58
	s_mov_b32 s8, 0xf000
	s_nop 0
	v_addc_co_u32_e32 v3, vcc, 0, v59, vcc
	global_load_dwordx4 v[10:13], v[2:3], off
	v_add_co_u32_e32 v2, vcc, s8, v58
	s_mov_b32 s8, 0x12000
	s_nop 0
	v_addc_co_u32_e32 v3, vcc, 0, v59, vcc
	global_load_dwordx4 v[14:17], v[2:3], off
	v_add_co_u32_e32 v2, vcc, s8, v58
	s_mov_b32 s8, 0x15000
	s_nop 0
	v_addc_co_u32_e32 v3, vcc, 0, v59, vcc
	v_add_co_u32_e32 v6, vcc, s8, v58
	global_load_dwordx4 v[2:5], v[2:3], off
	s_nop 0
	v_addc_co_u32_e32 v7, vcc, 0, v59, vcc
	global_load_dwordx4 v[6:9], v[6:7], off
	ds_read_b128 v[132:135], v128
	ds_read_b128 v[34:37], v128 offset:16
	v_add_u32_e32 v129, 0x10000, v128
	s_add_i32 s7, s7, 8
	s_mov_b64 s[8:9], 0x18000
	v_lshl_add_u64 v[58:59], v[58:59], 0, s[8:9]
	s_cmp_lt_u32 s7, 24
	s_waitcnt vmcnt(0) lgkmcnt(0)
	v_mul_f32_e32 v136, v28, v133
	v_mul_f32_e32 v137, v29, v133
	v_mul_f32_e32 v138, v26, v133
	v_mul_f32_e32 v139, v27, v133
	v_fma_f32 v136, v20, v132, v136
	v_fma_f32 v137, v21, v132, v137
	v_fma_f32 v133, v19, v132, v139
	v_fma_f32 v132, v18, v132, v138
	v_mov_b32_e32 v138, v135
	s_waitcnt vmcnt(4)
	v_mul_f32_e32 v140, v32, v138
	v_mul_f32_e32 v141, v33, v138
	v_mul_f32_e32 v139, v31, v138
	v_mul_f32_e32 v138, v30, v138
	v_fma_f32 v140, v24, v134, v140
	v_fma_f32 v141, v25, v134, v141
	v_fma_f32 v135, v23, v134, v139
	v_fma_f32 v134, v22, v134, v138
	v_add_f32_e32 v136, v136, v140
	v_add_f32_e32 v137, v137, v141
	v_add_f32_e32 v132, v132, v134
	v_add_f32_e32 v133, v133, v135
	v_add_f32_e32 v60, v60, v136
	v_add_f32_e32 v61, v61, v137
	v_add_f32_e32 v62, v62, v132
	v_add_f32_e32 v63, v63, v133
	ds_read_b128 v[132:135], v128 offset:4096
	s_waitcnt lgkmcnt(0)
	v_mul_f32_e32 v136, v28, v133
	v_mul_f32_e32 v137, v29, v133
	v_mul_f32_e32 v138, v26, v133
	v_mul_f32_e32 v139, v27, v133
	v_fma_f32 v136, v20, v132, v136
	v_fma_f32 v137, v21, v132, v137
	v_fma_f32 v133, v19, v132, v139
	v_fma_f32 v132, v18, v132, v138
	v_mov_b32_e32 v138, v135
	v_mul_f32_e32 v140, v32, v138
	v_mul_f32_e32 v141, v33, v138
	v_mul_f32_e32 v139, v31, v138
	v_mul_f32_e32 v138, v30, v138
	v_fma_f32 v140, v24, v134, v140
	v_fma_f32 v141, v25, v134, v141
	v_fma_f32 v135, v23, v134, v139
	v_fma_f32 v134, v22, v134, v138
	v_add_f32_e32 v136, v136, v140
	v_add_f32_e32 v137, v137, v141
	v_add_f32_e32 v132, v132, v134
	v_add_f32_e32 v133, v133, v135
	v_add_f32_e32 v72, v72, v136
	v_add_f32_e32 v73, v73, v137
	v_add_f32_e32 v74, v74, v132
	v_add_f32_e32 v75, v75, v133
	ds_read_b128 v[132:135], v128 offset:8192
	s_waitcnt lgkmcnt(0)
	v_mul_f32_e32 v136, v28, v133
	v_mul_f32_e32 v137, v29, v133
	v_mul_f32_e32 v138, v26, v133
	v_mul_f32_e32 v139, v27, v133
	v_fma_f32 v136, v20, v132, v136
	v_fma_f32 v137, v21, v132, v137
	v_fma_f32 v133, v19, v132, v139
	v_fma_f32 v132, v18, v132, v138
	v_mov_b32_e32 v138, v135
	v_mul_f32_e32 v140, v32, v138
	v_mul_f32_e32 v141, v33, v138
	v_mul_f32_e32 v139, v31, v138
	v_mul_f32_e32 v138, v30, v138
	v_fma_f32 v140, v24, v134, v140
	v_fma_f32 v141, v25, v134, v141
	v_fma_f32 v135, v23, v134, v139
	v_fma_f32 v134, v22, v134, v138
	v_add_f32_e32 v136, v136, v140
	v_add_f32_e32 v137, v137, v141
	v_add_f32_e32 v132, v132, v134
	v_add_f32_e32 v133, v133, v135
	v_add_f32_e32 v76, v76, v136
	v_add_f32_e32 v77, v77, v137
	v_add_f32_e32 v78, v78, v132
	v_add_f32_e32 v79, v79, v133
	ds_read_b128 v[132:135], v128 offset:12288
	s_waitcnt lgkmcnt(0)
	v_mul_f32_e32 v136, v28, v133
	v_mul_f32_e32 v137, v29, v133
	v_mul_f32_e32 v138, v26, v133
	v_mul_f32_e32 v139, v27, v133
	v_fma_f32 v136, v20, v132, v136
	v_fma_f32 v137, v21, v132, v137
	v_fma_f32 v133, v19, v132, v139
	v_fma_f32 v132, v18, v132, v138
	v_mov_b32_e32 v138, v135
	v_mul_f32_e32 v140, v32, v138
	v_mul_f32_e32 v141, v33, v138
	v_mul_f32_e32 v139, v31, v138
	v_mul_f32_e32 v138, v30, v138
	v_fma_f32 v140, v24, v134, v140
	v_fma_f32 v141, v25, v134, v141
	v_fma_f32 v135, v23, v134, v139
	v_fma_f32 v134, v22, v134, v138
	v_add_f32_e32 v136, v136, v140
	v_add_f32_e32 v137, v137, v141
	v_add_f32_e32 v132, v132, v134
	v_add_f32_e32 v133, v133, v135
	v_add_f32_e32 v80, v80, v136
	v_add_f32_e32 v81, v81, v137
	v_add_f32_e32 v82, v82, v132
	v_add_f32_e32 v83, v83, v133
	ds_read_b128 v[132:135], v128 offset:16384
	s_waitcnt lgkmcnt(0)
	v_mul_f32_e32 v136, v28, v133
	v_mul_f32_e32 v137, v29, v133
	v_mul_f32_e32 v138, v26, v133
	v_mul_f32_e32 v139, v27, v133
	v_fma_f32 v136, v20, v132, v136
	v_fma_f32 v137, v21, v132, v137
	v_fma_f32 v133, v19, v132, v139
	v_fma_f32 v132, v18, v132, v138
	v_mov_b32_e32 v138, v135
	v_mul_f32_e32 v140, v32, v138
	v_mul_f32_e32 v141, v33, v138
	v_mul_f32_e32 v139, v31, v138
	v_mul_f32_e32 v138, v30, v138
	v_fma_f32 v140, v24, v134, v140
	v_fma_f32 v141, v25, v134, v141
	v_fma_f32 v135, v23, v134, v139
	v_fma_f32 v134, v22, v134, v138
	v_add_f32_e32 v136, v136, v140
	v_add_f32_e32 v137, v137, v141
	v_add_f32_e32 v132, v132, v134
	v_add_f32_e32 v133, v133, v135
	v_add_f32_e32 v84, v84, v136
	v_add_f32_e32 v85, v85, v137
	v_add_f32_e32 v86, v86, v132
	v_add_f32_e32 v87, v87, v133
	ds_read_b128 v[132:135], v128 offset:20480
	s_waitcnt lgkmcnt(0)
; #define LAS __attribute__((address_space(3)))
; #define GAS __attribute__((address_space(1)))
; __device__ __forceinline__ void skinny_item(Frame& F, const LAS float* AL, LAS float* RED, const float* W, int ldw, int nvalid, int n0, const float* bias, float* out, int ldo) {
;     ...
;         for (int j = 0; j < 8; ++j) w[j] = valid ? *(const GAS f32x4*)(wp + (size_t)(k + j) * ldw) : (f32x4){0.f, 0.f, 0.f, 0.f};
; #pragma unroll
;         for (int q = 0; q < 2; ++q)
; #pragma unroll
;             for (int i = 0; i < 17; ++i) { const f32x4 a = *(const LAS f32x4*)(AL + i * 1024 + kg * 32 + k + 4 * q); acc[i] += (w[4 * q] * a[0] + w[4 * q + 1] * a[1]) + (w[4 * q + 2] * a[2] + w[4 * q + 3] * a[3]); }
	v_mul_f32_e32 v136, v28, v133
	v_mul_f32_e32 v137, v29, v133
	v_mul_f32_e32 v138, v26, v133
	v_mul_f32_e32 v139, v27, v133
	v_fma_f32 v136, v20, v132, v136
	v_fma_f32 v137, v21, v132, v137
	v_fma_f32 v133, v19, v132, v139
	v_fma_f32 v132, v18, v132, v138
	v_mov_b32_e32 v138, v135
	v_mul_f32_e32 v140, v32, v138
	v_mul_f32_e32 v141, v33, v138
	v_mul_f32_e32 v139, v31, v138
	v_mul_f32_e32 v138, v30, v138
	v_fma_f32 v140, v24, v134, v140
	v_fma_f32 v141, v25, v134, v141
	v_fma_f32 v135, v23, v134, v139
	v_fma_f32 v134, v22, v134, v138
	v_add_f32_e32 v136, v136, v140
	v_add_f32_e32 v137, v137, v141
	v_add_f32_e32 v132, v132, v134
	v_add_f32_e32 v133, v133, v135
	v_add_f32_e32 v88, v88, v136
	v_add_f32_e32 v89, v89, v137
	v_add_f32_e32 v90, v90, v132
	v_add_f32_e32 v91, v91, v133
	ds_read_b128 v[132:135], v128 offset:24576
	s_waitcnt lgkmcnt(0)
	v_mul_f32_e32 v136, v28, v133
	v_mul_f32_e32 v137, v29, v133
	v_mul_f32_e32 v138, v26, v133
	v_mul_f32_e32 v139, v27, v133
	v_fma_f32 v136, v20, v132, v136
	v_fma_f32 v137, v21, v132, v137
	v_fma_f32 v133, v19, v132, v139
	v_fma_f32 v132, v18, v132, v138
	v_mov_b32_e32 v138, v135
	v_mul_f32_e32 v140, v32, v138
	v_mul_f32_e32 v141, v33, v138
	v_mul_f32_e32 v139, v31, v138
	v_mul_f32_e32 v138, v30, v138
	v_fma_f32 v140, v24, v134, v140
	v_fma_f32 v141, v25, v134, v141
	v_fma_f32 v135, v23, v134, v139
	v_fma_f32 v134, v22, v134, v138
	v_add_f32_e32 v136, v136, v140
	v_add_f32_e32 v137, v137, v141
	v_add_f32_e32 v132, v132, v134
	v_add_f32_e32 v133, v133, v135
	v_add_f32_e32 v92, v92, v136
	v_add_f32_e32 v93, v93, v137
	v_add_f32_e32 v94, v94, v132
	v_add_f32_e32 v95, v95, v133
	ds_read_b128 v[132:135], v128 offset:28672
	s_waitcnt lgkmcnt(0)
	v_mul_f32_e32 v136, v28, v133
	v_mul_f32_e32 v137, v29, v133
	v_mul_f32_e32 v138, v26, v133
	v_mul_f32_e32 v139, v27, v133
	v_fma_f32 v136, v20, v132, v136
	v_fma_f32 v137, v21, v132, v137
	v_fma_f32 v133, v19, v132, v139
	v_fma_f32 v132, v18, v132, v138
	v_mov_b32_e32 v138, v135
	v_mul_f32_e32 v140, v32, v138
	v_mul_f32_e32 v141, v33, v138
	v_mul_f32_e32 v139, v31, v138
	v_mul_f32_e32 v138, v30, v138
	v_fma_f32 v140, v24, v134, v140
	v_fma_f32 v141, v25, v134, v141
	v_fma_f32 v135, v23, v134, v139
	v_fma_f32 v134, v22, v134, v138
	v_add_f32_e32 v136, v136, v140
	v_add_f32_e32 v137, v137, v141
	v_add_f32_e32 v132, v132, v134
	v_add_f32_e32 v133, v133, v135
	v_add_f32_e32 v96, v96, v136
	v_add_f32_e32 v97, v97, v137
	v_add_f32_e32 v98, v98, v132
	v_add_f32_e32 v99, v99, v133
	ds_read_b128 v[132:135], v128 offset:32768
	s_waitcnt lgkmcnt(0)
	v_mul_f32_e32 v136, v28, v133
	v_mul_f32_e32 v137, v29, v133
	v_mul_f32_e32 v138, v26, v133
	v_mul_f32_e32 v139, v27, v133
	v_fma_f32 v136, v20, v132, v136
	v_fma_f32 v137, v21, v132, v137
	v_fma_f32 v133, v19, v132, v139
	v_fma_f32 v132, v18, v132, v138
	v_mov_b32_e32 v138, v135
	v_mul_f32_e32 v140, v32, v138
	v_mul_f32_e32 v141, v33, v138
	v_mul_f32_e32 v139, v31, v138
	v_mul_f32_e32 v138, v30, v138
	v_fma_f32 v140, v24, v134, v140
	v_fma_f32 v141, v25, v134, v141
	v_fma_f32 v135, v23, v134, v139
	v_fma_f32 v134, v22, v134, v138
	v_add_f32_e32 v136, v136, v140
	v_add_f32_e32 v137, v137, v141
	v_add_f32_e32 v132, v132, v134
	v_add_f32_e32 v133, v133, v135
	v_add_f32_e32 v100, v100, v136
	v_add_f32_e32 v101, v101, v137
	v_add_f32_e32 v102, v102, v132
	v_add_f32_e32 v103, v103, v133
	ds_read_b128 v[132:135], v128 offset:36864
	s_waitcnt lgkmcnt(0)
	v_mul_f32_e32 v136, v28, v133
	v_mul_f32_e32 v137, v29, v133
	v_mul_f32_e32 v138, v26, v133
	v_mul_f32_e32 v139, v27, v133
	v_fma_f32 v136, v20, v132, v136
	v_fma_f32 v137, v21, v132, v137
	v_fma_f32 v133, v19, v132, v139
	v_fma_f32 v132, v18, v132, v138
	v_mov_b32_e32 v138, v135
	v_mul_f32_e32 v140, v32, v138
	v_mul_f32_e32 v141, v33, v138
	v_mul_f32_e32 v139, v31, v138
	v_mul_f32_e32 v138, v30, v138
	v_fma_f32 v140, v24, v134, v140
	v_fma_f32 v141, v25, v134, v141
	v_fma_f32 v135, v23, v134, v139
	v_fma_f32 v134, v22, v134, v138
	v_add_f32_e32 v136, v136, v140
	v_add_f32_e32 v137, v137, v141
	v_add_f32_e32 v132, v132, v134
	v_add_f32_e32 v133, v133, v135
	v_add_f32_e32 v104, v104, v136
	v_add_f32_e32 v105, v105, v137
	v_add_f32_e32 v106, v106, v132
	v_add_f32_e32 v107, v107, v133
	ds_read_b128 v[132:135], v128 offset:40960
	s_waitcnt lgkmcnt(0)
	v_mul_f32_e32 v136, v28, v133
	v_mul_f32_e32 v137, v29, v133
	v_mul_f32_e32 v138, v26, v133
	v_mul_f32_e32 v139, v27, v133
	v_fma_f32 v136, v20, v132, v136
	v_fma_f32 v137, v21, v132, v137
	v_fma_f32 v133, v19, v132, v139
	v_fma_f32 v132, v18, v132, v138
	v_mov_b32_e32 v138, v135
	v_mul_f32_e32 v140, v32, v138
	v_mul_f32_e32 v141, v33, v138
	v_mul_f32_e32 v139, v31, v138
	v_mul_f32_e32 v138, v30, v138
	v_fma_f32 v140, v24, v134, v140
	v_fma_f32 v141, v25, v134, v141
	v_fma_f32 v135, v23, v134, v139
	v_fma_f32 v134, v22, v134, v138
	v_add_f32_e32 v136, v136, v140
	v_add_f32_e32 v137, v137, v141
	v_add_f32_e32 v132, v132, v134
	v_add_f32_e32 v133, v133, v135
	v_add_f32_e32 v108, v108, v136
	v_add_f32_e32 v109, v109, v137
	v_add_f32_e32 v110, v110, v132
	v_add_f32_e32 v111, v111, v133
	ds_read_b128 v[132:135], v128 offset:45056
	s_waitcnt lgkmcnt(0)
	v_mul_f32_e32 v136, v28, v133
	v_mul_f32_e32 v137, v29, v133
	v_mul_f32_e32 v138, v26, v133
	v_mul_f32_e32 v139, v27, v133
	v_fma_f32 v136, v20, v132, v136
	v_fma_f32 v137, v21, v132, v137
	v_fma_f32 v133, v19, v132, v139
	v_fma_f32 v132, v18, v132, v138
	v_mov_b32_e32 v138, v135
	v_mul_f32_e32 v140, v32, v138
	v_mul_f32_e32 v141, v33, v138
	v_mul_f32_e32 v139, v31, v138
	v_mul_f32_e32 v138, v30, v138
	v_fma_f32 v140, v24, v134, v140
	v_fma_f32 v141, v25, v134, v141
	v_fma_f32 v135, v23, v134, v139
	v_fma_f32 v134, v22, v134, v138
	v_add_f32_e32 v136, v136, v140
	v_add_f32_e32 v137, v137, v141
	v_add_f32_e32 v132, v132, v134
	v_add_f32_e32 v133, v133, v135
	v_add_f32_e32 v112, v112, v136
	v_add_f32_e32 v113, v113, v137
	v_add_f32_e32 v114, v114, v132
	v_add_f32_e32 v115, v115, v133
	ds_read_b128 v[132:135], v128 offset:49152
	s_waitcnt lgkmcnt(0)
; #define LAS __attribute__((address_space(3)))
; #define GAS __attribute__((address_space(1)))
; __device__ __forceinline__ void skinny_item(Frame& F, const LAS float* AL, LAS float* RED, const float* W, int ldw, int nvalid, int n0, const float* bias, float* out, int ldo) {
;     ...
;         for (int j = 0; j < 8; ++j) w[j] = valid ? *(const GAS f32x4*)(wp + (size_t)(k + j) * ldw) : (f32x4){0.f, 0.f, 0.f, 0.f};
; #pragma unroll
;         for (int q = 0; q < 2; ++q)
; #pragma unroll
;             for (int i = 0; i < 17; ++i) { const f32x4 a = *(const LAS f32x4*)(AL + i * 1024 + kg * 32 + k + 4 * q); acc[i] += (w[4 * q] * a[0] + w[4 * q + 1] * a[1]) + (w[4 * q + 2] * a[2] + w[4 * q + 3] * a[3]); }
	v_mul_f32_e32 v136, v28, v133
	v_mul_f32_e32 v137, v29, v133
	v_mul_f32_e32 v138, v26, v133
	v_mul_f32_e32 v139, v27, v133
	v_fma_f32 v136, v20, v132, v136
	v_fma_f32 v137, v21, v132, v137
	v_fma_f32 v133, v19, v132, v139
	v_fma_f32 v132, v18, v132, v138
	v_mov_b32_e32 v138, v135
	v_mul_f32_e32 v140, v32, v138
	v_mul_f32_e32 v141, v33, v138
	v_mul_f32_e32 v139, v31, v138
	v_mul_f32_e32 v138, v30, v138
	v_fma_f32 v140, v24, v134, v140
	v_fma_f32 v141, v25, v134, v141
	v_fma_f32 v135, v23, v134, v139
	v_fma_f32 v134, v22, v134, v138
	v_add_f32_e32 v136, v136, v140
	v_add_f32_e32 v137, v137, v141
	v_add_f32_e32 v132, v132, v134
	v_add_f32_e32 v133, v133, v135
	v_add_f32_e32 v116, v116, v136
	v_add_f32_e32 v117, v117, v137
	v_add_f32_e32 v118, v118, v132
	v_add_f32_e32 v119, v119, v133
	ds_read_b128 v[132:135], v128 offset:53248
	s_waitcnt lgkmcnt(0)
	v_mul_f32_e32 v136, v28, v133
	v_mul_f32_e32 v137, v29, v133
	v_mul_f32_e32 v138, v26, v133
	v_mul_f32_e32 v139, v27, v133
	v_fma_f32 v136, v20, v132, v136
	v_fma_f32 v137, v21, v132, v137
	v_fma_f32 v133, v19, v132, v139
	v_fma_f32 v132, v18, v132, v138
	v_mov_b32_e32 v138, v135
	v_mul_f32_e32 v140, v32, v138
	v_mul_f32_e32 v141, v33, v138
	v_mul_f32_e32 v139, v31, v138
	v_mul_f32_e32 v138, v30, v138
	v_fma_f32 v140, v24, v134, v140
	v_fma_f32 v141, v25, v134, v141
	v_fma_f32 v135, v23, v134, v139
	v_fma_f32 v134, v22, v134, v138
	v_add_f32_e32 v136, v136, v140
	v_add_f32_e32 v137, v137, v141
	v_add_f32_e32 v132, v132, v134
	v_add_f32_e32 v133, v133, v135
	v_add_f32_e32 v120, v120, v136
	v_add_f32_e32 v121, v121, v137
	v_add_f32_e32 v122, v122, v132
	v_add_f32_e32 v123, v123, v133
	ds_read_b128 v[132:135], v128 offset:57344
	s_waitcnt lgkmcnt(0)
	v_mul_f32_e32 v136, v28, v133
	v_mul_f32_e32 v137, v29, v133
	v_mul_f32_e32 v138, v26, v133
	v_mul_f32_e32 v139, v27, v133
	v_fma_f32 v136, v20, v132, v136
	v_fma_f32 v137, v21, v132, v137
	v_fma_f32 v133, v19, v132, v139
	v_fma_f32 v132, v18, v132, v138
	v_mov_b32_e32 v138, v135
	v_mul_f32_e32 v140, v32, v138
	v_mul_f32_e32 v141, v33, v138
	v_mul_f32_e32 v139, v31, v138
	v_mul_f32_e32 v138, v30, v138
	v_fma_f32 v140, v24, v134, v140
	v_fma_f32 v141, v25, v134, v141
	v_fma_f32 v135, v23, v134, v139
	v_fma_f32 v134, v22, v134, v138
	v_add_f32_e32 v136, v136, v140
	v_add_f32_e32 v137, v137, v141
	v_add_f32_e32 v132, v132, v134
	v_add_f32_e32 v133, v133, v135
	v_add_f32_e32 v68, v68, v136
	v_add_f32_e32 v69, v69, v137
	v_add_f32_e32 v70, v70, v132
	v_add_f32_e32 v71, v71, v133
	ds_read_b128 v[132:135], v128 offset:61440
	s_waitcnt lgkmcnt(0)
	v_mul_f32_e32 v136, v28, v133
	v_mul_f32_e32 v137, v29, v133
	v_mul_f32_e32 v138, v26, v133
	v_mul_f32_e32 v139, v27, v133
	v_fma_f32 v136, v20, v132, v136
	v_fma_f32 v137, v21, v132, v137
	v_fma_f32 v133, v19, v132, v139
	v_fma_f32 v132, v18, v132, v138
	v_mov_b32_e32 v138, v135
	v_mul_f32_e32 v140, v32, v138
	v_mul_f32_e32 v141, v33, v138
	v_mul_f32_e32 v139, v31, v138
	v_mul_f32_e32 v138, v30, v138
	v_fma_f32 v140, v24, v134, v140
	v_fma_f32 v141, v25, v134, v141
	v_fma_f32 v135, v23, v134, v139
	v_fma_f32 v134, v22, v134, v138
	v_add_f32_e32 v136, v136, v140
	v_add_f32_e32 v137, v137, v141
	v_add_f32_e32 v132, v132, v134
	v_add_f32_e32 v133, v133, v135
	v_add_f32_e32 v64, v64, v136
	v_add_f32_e32 v65, v65, v137
	v_add_f32_e32 v66, v66, v132
	v_add_f32_e32 v67, v67, v133
	ds_read_b128 v[132:135], v129
	s_waitcnt lgkmcnt(0)
	v_mul_f32_e32 v26, v26, v133
	v_mul_f32_e32 v27, v27, v133
	v_mul_f32_e32 v28, v28, v133
	v_mul_f32_e32 v29, v29, v133
	v_fma_f32 v18, v18, v132, v26
	v_fma_f32 v19, v19, v132, v27
	v_mov_b32_e32 v26, v135
	v_fma_f32 v20, v20, v132, v28
	v_fma_f32 v21, v21, v132, v29
	v_mul_f32_e32 v28, v32, v26
	v_mul_f32_e32 v29, v33, v26
	v_mul_f32_e32 v27, v31, v26
	v_mul_f32_e32 v26, v30, v26
	v_fma_f32 v24, v24, v134, v28
	v_fma_f32 v25, v25, v134, v29
	v_fma_f32 v22, v22, v134, v26
	v_fma_f32 v23, v23, v134, v27
	v_add_f32_e32 v20, v20, v24
	v_add_f32_e32 v21, v21, v25
	v_add_f32_e32 v18, v18, v22
	v_add_f32_e32 v19, v19, v23
	v_mov_b32_e32 v26, v37
	v_add_f32_e32 v22, v124, v20
	v_add_f32_e32 v23, v125, v21
	v_add_f32_e32 v24, v126, v18
	v_add_f32_e32 v25, v127, v19
	s_waitcnt vmcnt(2)
	v_mul_f32_e32 v18, v16, v35
	v_mul_f32_e32 v19, v17, v35
	v_mul_f32_e32 v20, v14, v35
	v_mul_f32_e32 v21, v15, v35
	s_waitcnt vmcnt(0)
	v_mul_f32_e32 v28, v8, v26
	v_mul_f32_e32 v29, v9, v26
	v_mul_f32_e32 v27, v7, v26
	v_mul_f32_e32 v26, v6, v26
	v_fma_f32 v18, v12, v34, v18
	v_fma_f32 v19, v13, v34, v19
	v_fma_f32 v20, v10, v34, v20
	v_fma_f32 v21, v11, v34, v21
	v_fma_f32 v28, v4, v36, v28
	v_fma_f32 v29, v5, v36, v29
	v_fma_f32 v26, v2, v36, v26
	v_fma_f32 v27, v3, v36, v27
	v_add_f32_e32 v18, v18, v28
	v_add_f32_e32 v19, v19, v29
	v_add_f32_e32 v20, v20, v26
	v_add_f32_e32 v21, v21, v27
	v_add_f32_e32 v60, v60, v18
	v_add_f32_e32 v61, v61, v19
	v_add_f32_e32 v62, v62, v20
	v_add_f32_e32 v63, v63, v21
	ds_read_b128 v[18:21], v128 offset:4112
	s_waitcnt lgkmcnt(0)
	v_mul_f32_e32 v26, v16, v19
	v_mul_f32_e32 v27, v17, v19
	v_mul_f32_e32 v28, v14, v19
	v_mul_f32_e32 v29, v15, v19
	v_fma_f32 v26, v12, v18, v26
	v_fma_f32 v27, v13, v18, v27
	v_fma_f32 v19, v11, v18, v29
	v_fma_f32 v18, v10, v18, v28
	v_mov_b32_e32 v28, v21
	v_mul_f32_e32 v30, v8, v28
	v_mul_f32_e32 v31, v9, v28
	v_mul_f32_e32 v29, v7, v28
	v_mul_f32_e32 v28, v6, v28
	v_fma_f32 v30, v4, v20, v30
	v_fma_f32 v31, v5, v20, v31
	v_fma_f32 v21, v3, v20, v29
	v_fma_f32 v20, v2, v20, v28
	v_add_f32_e32 v26, v26, v30
	v_add_f32_e32 v27, v27, v31
	v_add_f32_e32 v18, v18, v20
	v_add_f32_e32 v19, v19, v21
	v_add_f32_e32 v72, v72, v26
	v_add_f32_e32 v73, v73, v27
	v_add_f32_e32 v74, v74, v18
	v_add_f32_e32 v75, v75, v19
	ds_read_b128 v[18:21], v128 offset:8208
	s_waitcnt lgkmcnt(0)
; #define LAS __attribute__((address_space(3)))
; #define GAS __attribute__((address_space(1)))
; __device__ __forceinline__ void skinny_item(Frame& F, const LAS float* AL, LAS float* RED, const float* W, int ldw, int nvalid, int n0, const float* bias, float* out, int ldo) {
;     ...
;         for (int j = 0; j < 8; ++j) w[j] = valid ? *(const GAS f32x4*)(wp + (size_t)(k + j) * ldw) : (f32x4){0.f, 0.f, 0.f, 0.f};
; #pragma unroll
;         for (int q = 0; q < 2; ++q)
; #pragma unroll
;             for (int i = 0; i < 17; ++i) { const f32x4 a = *(const LAS f32x4*)(AL + i * 1024 + kg * 32 + k + 4 * q); acc[i] += (w[4 * q] * a[0] + w[4 * q + 1] * a[1]) + (w[4 * q + 2] * a[2] + w[4 * q + 3] * a[3]); }
	v_mul_f32_e32 v26, v16, v19
	v_mul_f32_e32 v27, v17, v19
	v_mul_f32_e32 v28, v14, v19
	v_mul_f32_e32 v29, v15, v19
	v_fma_f32 v26, v12, v18, v26
	v_fma_f32 v27, v13, v18, v27
	v_fma_f32 v19, v11, v18, v29
	v_fma_f32 v18, v10, v18, v28
	v_mov_b32_e32 v28, v21
	v_mul_f32_e32 v30, v8, v28
	v_mul_f32_e32 v31, v9, v28
	v_mul_f32_e32 v29, v7, v28
	v_mul_f32_e32 v28, v6, v28
	v_fma_f32 v30, v4, v20, v30
	v_fma_f32 v31, v5, v20, v31
	v_fma_f32 v21, v3, v20, v29
	v_fma_f32 v20, v2, v20, v28
	v_add_f32_e32 v26, v26, v30
	v_add_f32_e32 v27, v27, v31
	v_add_f32_e32 v18, v18, v20
	v_add_f32_e32 v19, v19, v21
	v_add_f32_e32 v76, v76, v26
	v_add_f32_e32 v77, v77, v27
	v_add_f32_e32 v78, v78, v18
	v_add_f32_e32 v79, v79, v19
	ds_read_b128 v[18:21], v128 offset:12304
	s_waitcnt lgkmcnt(0)
	v_mul_f32_e32 v26, v16, v19
	v_mul_f32_e32 v27, v17, v19
	v_mul_f32_e32 v28, v14, v19
	v_mul_f32_e32 v29, v15, v19
	v_fma_f32 v26, v12, v18, v26
	v_fma_f32 v27, v13, v18, v27
	v_fma_f32 v19, v11, v18, v29
	v_fma_f32 v18, v10, v18, v28
	v_mov_b32_e32 v28, v21
	v_mul_f32_e32 v30, v8, v28
	v_mul_f32_e32 v31, v9, v28
	v_mul_f32_e32 v29, v7, v28
	v_mul_f32_e32 v28, v6, v28
	v_fma_f32 v30, v4, v20, v30
	v_fma_f32 v31, v5, v20, v31
	v_fma_f32 v21, v3, v20, v29
	v_fma_f32 v20, v2, v20, v28
	v_add_f32_e32 v26, v26, v30
	v_add_f32_e32 v27, v27, v31
	v_add_f32_e32 v18, v18, v20
	v_add_f32_e32 v19, v19, v21
	v_add_f32_e32 v80, v80, v26
	v_add_f32_e32 v81, v81, v27
	v_add_f32_e32 v82, v82, v18
	v_add_f32_e32 v83, v83, v19
	ds_read_b128 v[18:21], v128 offset:16400
	s_waitcnt lgkmcnt(0)
	v_mul_f32_e32 v26, v16, v19
	v_mul_f32_e32 v27, v17, v19
	v_mul_f32_e32 v28, v14, v19
	v_mul_f32_e32 v29, v15, v19
	v_fma_f32 v26, v12, v18, v26
	v_fma_f32 v27, v13, v18, v27
	v_fma_f32 v19, v11, v18, v29
	v_fma_f32 v18, v10, v18, v28
	v_mov_b32_e32 v28, v21
	v_mul_f32_e32 v30, v8, v28
	v_mul_f32_e32 v31, v9, v28
	v_mul_f32_e32 v29, v7, v28
	v_mul_f32_e32 v28, v6, v28
	v_fma_f32 v30, v4, v20, v30
	v_fma_f32 v31, v5, v20, v31
	v_fma_f32 v21, v3, v20, v29
	v_fma_f32 v20, v2, v20, v28
	v_add_f32_e32 v26, v26, v30
	v_add_f32_e32 v27, v27, v31
	v_add_f32_e32 v18, v18, v20
	v_add_f32_e32 v19, v19, v21
	v_add_f32_e32 v84, v84, v26
	v_add_f32_e32 v85, v85, v27
	v_add_f32_e32 v86, v86, v18
	v_add_f32_e32 v87, v87, v19
	ds_read_b128 v[18:21], v128 offset:20496
	s_waitcnt lgkmcnt(0)
	v_mul_f32_e32 v26, v16, v19
	v_mul_f32_e32 v27, v17, v19
	v_mul_f32_e32 v28, v14, v19
	v_mul_f32_e32 v29, v15, v19
	v_fma_f32 v26, v12, v18, v26
	v_fma_f32 v27, v13, v18, v27
	v_fma_f32 v19, v11, v18, v29
	v_fma_f32 v18, v10, v18, v28
	v_mov_b32_e32 v28, v21
	v_mul_f32_e32 v30, v8, v28
	v_mul_f32_e32 v31, v9, v28
	v_mul_f32_e32 v29, v7, v28
	v_mul_f32_e32 v28, v6, v28
	v_fma_f32 v30, v4, v20, v30
	v_fma_f32 v31, v5, v20, v31
	v_fma_f32 v21, v3, v20, v29
	v_fma_f32 v20, v2, v20, v28
	v_add_f32_e32 v26, v26, v30
	v_add_f32_e32 v27, v27, v31
	v_add_f32_e32 v18, v18, v20
	v_add_f32_e32 v19, v19, v21
	v_add_f32_e32 v88, v88, v26
	v_add_f32_e32 v89, v89, v27
	v_add_f32_e32 v90, v90, v18
	v_add_f32_e32 v91, v91, v19
	ds_read_b128 v[18:21], v128 offset:24592
	s_waitcnt lgkmcnt(0)
	v_mul_f32_e32 v26, v16, v19
	v_mul_f32_e32 v27, v17, v19
	v_mul_f32_e32 v28, v14, v19
	v_mul_f32_e32 v29, v15, v19
	v_fma_f32 v26, v12, v18, v26
	v_fma_f32 v27, v13, v18, v27
	v_fma_f32 v19, v11, v18, v29
	v_fma_f32 v18, v10, v18, v28
	v_mov_b32_e32 v28, v21
	v_mul_f32_e32 v30, v8, v28
	v_mul_f32_e32 v31, v9, v28
	v_mul_f32_e32 v29, v7, v28
	v_mul_f32_e32 v28, v6, v28
	v_fma_f32 v30, v4, v20, v30
	v_fma_f32 v31, v5, v20, v31
	v_fma_f32 v21, v3, v20, v29
	v_fma_f32 v20, v2, v20, v28
	v_add_f32_e32 v26, v26, v30
	v_add_f32_e32 v27, v27, v31
	v_add_f32_e32 v18, v18, v20
	v_add_f32_e32 v19, v19, v21
	v_add_f32_e32 v92, v92, v26
	v_add_f32_e32 v93, v93, v27
	v_add_f32_e32 v94, v94, v18
	v_add_f32_e32 v95, v95, v19
	ds_read_b128 v[18:21], v128 offset:28688
	s_waitcnt lgkmcnt(0)
	v_mul_f32_e32 v26, v16, v19
	v_mul_f32_e32 v27, v17, v19
	v_mul_f32_e32 v28, v14, v19
	v_mul_f32_e32 v29, v15, v19
	v_fma_f32 v26, v12, v18, v26
	v_fma_f32 v27, v13, v18, v27
	v_fma_f32 v19, v11, v18, v29
	v_fma_f32 v18, v10, v18, v28
	v_mov_b32_e32 v28, v21
	v_mul_f32_e32 v30, v8, v28
	v_mul_f32_e32 v31, v9, v28
	v_mul_f32_e32 v29, v7, v28
	v_mul_f32_e32 v28, v6, v28
	v_fma_f32 v30, v4, v20, v30
	v_fma_f32 v31, v5, v20, v31
	v_fma_f32 v21, v3, v20, v29
	v_fma_f32 v20, v2, v20, v28
	v_add_f32_e32 v26, v26, v30
	v_add_f32_e32 v27, v27, v31
	v_add_f32_e32 v18, v18, v20
	v_add_f32_e32 v19, v19, v21
	v_add_f32_e32 v96, v96, v26
	v_add_f32_e32 v97, v97, v27
	v_add_f32_e32 v98, v98, v18
	v_add_f32_e32 v99, v99, v19
	ds_read_b128 v[18:21], v128 offset:32784
	s_waitcnt lgkmcnt(0)
	v_mul_f32_e32 v26, v16, v19
	v_mul_f32_e32 v27, v17, v19
	v_mul_f32_e32 v28, v14, v19
	v_mul_f32_e32 v29, v15, v19
	v_fma_f32 v26, v12, v18, v26
	v_fma_f32 v27, v13, v18, v27
	v_fma_f32 v19, v11, v18, v29
	v_fma_f32 v18, v10, v18, v28
	v_mov_b32_e32 v28, v21
	v_mul_f32_e32 v30, v8, v28
	v_mul_f32_e32 v31, v9, v28
	v_mul_f32_e32 v29, v7, v28
	v_mul_f32_e32 v28, v6, v28
	v_fma_f32 v30, v4, v20, v30
	v_fma_f32 v31, v5, v20, v31
	v_fma_f32 v21, v3, v20, v29
	v_fma_f32 v20, v2, v20, v28
	v_add_f32_e32 v26, v26, v30
	v_add_f32_e32 v27, v27, v31
	v_add_f32_e32 v18, v18, v20
	v_add_f32_e32 v19, v19, v21
	v_add_f32_e32 v100, v100, v26
	v_add_f32_e32 v101, v101, v27
	v_add_f32_e32 v102, v102, v18
	v_add_f32_e32 v103, v103, v19
	ds_read_b128 v[18:21], v128 offset:36880
	s_waitcnt lgkmcnt(0)
; #define LAS __attribute__((address_space(3)))
; #define GAS __attribute__((address_space(1)))
; __device__ __forceinline__ void skinny_item(Frame& F, const LAS float* AL, LAS float* RED, const float* W, int ldw, int nvalid, int n0, const float* bias, float* out, int ldo) {
;     ...
;     for (int k = 0; k < 32; k += 8) {
;         f32x4 w[8];
; #pragma unroll
;         for (int j = 0; j < 8; ++j) w[j] = valid ? *(const GAS f32x4*)(wp + (size_t)(k + j) * ldw) : (f32x4){0.f, 0.f, 0.f, 0.f};
; #pragma unroll
;         for (int q = 0; q < 2; ++q)
; #pragma unroll
;             for (int i = 0; i < 17; ++i) { const f32x4 a = *(const LAS f32x4*)(AL + i * 1024 + kg * 32 + k + 4 * q); acc[i] += (w[4 * q] * a[0] + w[4 * q + 1] * a[1]) + (w[4 * q + 2] * a[2] + w[4 * q + 3] * a[3]); }
	v_mul_f32_e32 v26, v16, v19
	v_mul_f32_e32 v27, v17, v19
	v_mul_f32_e32 v28, v14, v19
	v_mul_f32_e32 v29, v15, v19
	v_fma_f32 v26, v12, v18, v26
	v_fma_f32 v27, v13, v18, v27
	v_fma_f32 v19, v11, v18, v29
	v_fma_f32 v18, v10, v18, v28
	v_mov_b32_e32 v28, v21
	v_mul_f32_e32 v30, v8, v28
	v_mul_f32_e32 v31, v9, v28
	v_mul_f32_e32 v29, v7, v28
	v_mul_f32_e32 v28, v6, v28
	v_fma_f32 v30, v4, v20, v30
	v_fma_f32 v31, v5, v20, v31
	v_fma_f32 v21, v3, v20, v29
	v_fma_f32 v20, v2, v20, v28
	v_add_f32_e32 v26, v26, v30
	v_add_f32_e32 v27, v27, v31
	v_add_f32_e32 v18, v18, v20
	v_add_f32_e32 v19, v19, v21
	v_add_f32_e32 v104, v104, v26
	v_add_f32_e32 v105, v105, v27
	v_add_f32_e32 v106, v106, v18
	v_add_f32_e32 v107, v107, v19
	ds_read_b128 v[18:21], v128 offset:40976
	s_waitcnt lgkmcnt(0)
	v_mul_f32_e32 v26, v16, v19
	v_mul_f32_e32 v27, v17, v19
	v_mul_f32_e32 v28, v14, v19
	v_mul_f32_e32 v29, v15, v19
	v_fma_f32 v26, v12, v18, v26
	v_fma_f32 v27, v13, v18, v27
	v_fma_f32 v19, v11, v18, v29
	v_fma_f32 v18, v10, v18, v28
	v_mov_b32_e32 v28, v21
	v_mul_f32_e32 v30, v8, v28
	v_mul_f32_e32 v31, v9, v28
	v_mul_f32_e32 v29, v7, v28
	v_mul_f32_e32 v28, v6, v28
	v_fma_f32 v30, v4, v20, v30
	v_fma_f32 v31, v5, v20, v31
	v_fma_f32 v21, v3, v20, v29
	v_fma_f32 v20, v2, v20, v28
	v_add_f32_e32 v26, v26, v30
	v_add_f32_e32 v27, v27, v31
	v_add_f32_e32 v18, v18, v20
	v_add_f32_e32 v19, v19, v21
	v_add_f32_e32 v108, v108, v26
	v_add_f32_e32 v109, v109, v27
	v_add_f32_e32 v110, v110, v18
	v_add_f32_e32 v111, v111, v19
	ds_read_b128 v[18:21], v128 offset:45072
	s_waitcnt lgkmcnt(0)
	v_mul_f32_e32 v26, v16, v19
	v_mul_f32_e32 v27, v17, v19
	v_mul_f32_e32 v28, v14, v19
	v_mul_f32_e32 v29, v15, v19
	v_fma_f32 v26, v12, v18, v26
	v_fma_f32 v27, v13, v18, v27
	v_fma_f32 v19, v11, v18, v29
	v_fma_f32 v18, v10, v18, v28
	v_mov_b32_e32 v28, v21
	v_mul_f32_e32 v30, v8, v28
	v_mul_f32_e32 v31, v9, v28
	v_mul_f32_e32 v29, v7, v28
	v_mul_f32_e32 v28, v6, v28
	v_fma_f32 v30, v4, v20, v30
	v_fma_f32 v31, v5, v20, v31
	v_fma_f32 v21, v3, v20, v29
	v_fma_f32 v20, v2, v20, v28
	v_add_f32_e32 v26, v26, v30
	v_add_f32_e32 v27, v27, v31
	v_add_f32_e32 v18, v18, v20
	v_add_f32_e32 v19, v19, v21
	v_add_f32_e32 v112, v112, v26
	v_add_f32_e32 v113, v113, v27
	v_add_f32_e32 v114, v114, v18
	v_add_f32_e32 v115, v115, v19
	ds_read_b128 v[18:21], v128 offset:49168
	s_waitcnt lgkmcnt(0)
	v_mul_f32_e32 v26, v16, v19
	v_mul_f32_e32 v27, v17, v19
	v_mul_f32_e32 v28, v14, v19
	v_mul_f32_e32 v29, v15, v19
	v_fma_f32 v26, v12, v18, v26
	v_fma_f32 v27, v13, v18, v27
	v_fma_f32 v19, v11, v18, v29
	v_fma_f32 v18, v10, v18, v28
	v_mov_b32_e32 v28, v21
	v_mul_f32_e32 v30, v8, v28
	v_mul_f32_e32 v31, v9, v28
	v_mul_f32_e32 v29, v7, v28
	v_mul_f32_e32 v28, v6, v28
	v_fma_f32 v30, v4, v20, v30
	v_fma_f32 v31, v5, v20, v31
	v_fma_f32 v21, v3, v20, v29
	v_fma_f32 v20, v2, v20, v28
	v_add_f32_e32 v26, v26, v30
	v_add_f32_e32 v27, v27, v31
	v_add_f32_e32 v18, v18, v20
	v_add_f32_e32 v19, v19, v21
	v_add_f32_e32 v116, v116, v26
	v_add_f32_e32 v117, v117, v27
	v_add_f32_e32 v118, v118, v18
	v_add_f32_e32 v119, v119, v19
	ds_read_b128 v[18:21], v128 offset:53264
	s_waitcnt lgkmcnt(0)
	v_mul_f32_e32 v26, v16, v19
	v_mul_f32_e32 v27, v17, v19
	v_mul_f32_e32 v28, v14, v19
	v_mul_f32_e32 v29, v15, v19
	v_fma_f32 v26, v12, v18, v26
	v_fma_f32 v27, v13, v18, v27
	v_fma_f32 v19, v11, v18, v29
	v_fma_f32 v18, v10, v18, v28
	v_mov_b32_e32 v28, v21
	v_mul_f32_e32 v30, v8, v28
	v_mul_f32_e32 v31, v9, v28
	v_mul_f32_e32 v29, v7, v28
	v_mul_f32_e32 v28, v6, v28
	v_fma_f32 v30, v4, v20, v30
	v_fma_f32 v31, v5, v20, v31
	v_fma_f32 v21, v3, v20, v29
	v_fma_f32 v20, v2, v20, v28
	v_add_f32_e32 v26, v26, v30
	v_add_f32_e32 v27, v27, v31
	v_add_f32_e32 v18, v18, v20
	v_add_f32_e32 v19, v19, v21
	v_add_f32_e32 v120, v120, v26
	v_add_f32_e32 v121, v121, v27
	v_add_f32_e32 v122, v122, v18
	v_add_f32_e32 v123, v123, v19
	ds_read_b128 v[18:21], v128 offset:57360
	s_waitcnt lgkmcnt(0)
	v_mul_f32_e32 v26, v16, v19
	v_mul_f32_e32 v27, v17, v19
	v_mul_f32_e32 v28, v14, v19
	v_mul_f32_e32 v29, v15, v19
	v_fma_f32 v26, v12, v18, v26
	v_fma_f32 v27, v13, v18, v27
	v_fma_f32 v19, v11, v18, v29
	v_fma_f32 v18, v10, v18, v28
	v_mov_b32_e32 v28, v21
	v_mul_f32_e32 v30, v8, v28
	v_mul_f32_e32 v31, v9, v28
	v_mul_f32_e32 v29, v7, v28
	v_mul_f32_e32 v28, v6, v28
	v_fma_f32 v30, v4, v20, v30
	v_fma_f32 v31, v5, v20, v31
	v_fma_f32 v21, v3, v20, v29
	v_fma_f32 v20, v2, v20, v28
	v_add_f32_e32 v26, v26, v30
	v_add_f32_e32 v27, v27, v31
	v_add_f32_e32 v18, v18, v20
	v_add_f32_e32 v19, v19, v21
	v_add_f32_e32 v68, v68, v26
	v_add_f32_e32 v69, v69, v27
	v_add_f32_e32 v70, v70, v18
	v_add_f32_e32 v71, v71, v19
	ds_read_b128 v[18:21], v128 offset:61456
	s_waitcnt lgkmcnt(0)
	v_mul_f32_e32 v26, v16, v19
	v_mul_f32_e32 v27, v17, v19
	v_mul_f32_e32 v28, v14, v19
	v_mul_f32_e32 v29, v15, v19
	v_fma_f32 v26, v12, v18, v26
	v_fma_f32 v27, v13, v18, v27
	v_fma_f32 v19, v11, v18, v29
	v_fma_f32 v18, v10, v18, v28
	v_mov_b32_e32 v28, v21
	v_mul_f32_e32 v30, v8, v28
	v_mul_f32_e32 v31, v9, v28
	v_mul_f32_e32 v29, v7, v28
	v_mul_f32_e32 v28, v6, v28
	v_fma_f32 v30, v4, v20, v30
	v_fma_f32 v31, v5, v20, v31
	v_fma_f32 v21, v3, v20, v29
	v_fma_f32 v20, v2, v20, v28
	v_add_f32_e32 v26, v26, v30
	v_add_f32_e32 v27, v27, v31
	v_add_f32_e32 v18, v18, v20
	v_add_f32_e32 v19, v19, v21
	v_add_f32_e32 v64, v64, v26
	v_add_f32_e32 v65, v65, v27
	v_add_f32_e32 v66, v66, v18
	v_add_f32_e32 v67, v67, v19
	v_add_u32_e32 v18, 0x10010, v128
	ds_read_b128 v[18:21], v18
	v_add_u32_e32 v128, 32, v128
	s_waitcnt lgkmcnt(0)
	v_mul_f32_e32 v14, v14, v19
	v_mul_f32_e32 v15, v15, v19
	s_nop 0
	v_fma_f32 v10, v10, v18, v14
	v_fma_f32 v11, v11, v18, v15
	v_mov_b32_e32 v14, v21
	v_mul_f32_e32 v16, v16, v19
	v_mul_f32_e32 v17, v17, v19
	v_mul_f32_e32 v8, v8, v14
	v_mul_f32_e32 v9, v9, v14
	v_mul_f32_e32 v6, v6, v14
	v_mul_f32_e32 v7, v7, v14
	v_fma_f32 v12, v12, v18, v16
	v_fma_f32 v13, v13, v18, v17
	v_fma_f32 v4, v4, v20, v8
	v_fma_f32 v5, v5, v20, v9
	v_fma_f32 v2, v2, v20, v6
	v_fma_f32 v3, v3, v20, v7
	v_add_f32_e32 v4, v12, v4
	v_add_f32_e32 v5, v13, v5
	v_add_f32_e32 v2, v10, v2
	v_add_f32_e32 v3, v11, v3
	v_add_f32_e32 v124, v22, v4
	v_add_f32_e32 v125, v23, v5
	v_add_f32_e32 v126, v24, v2
	v_add_f32_e32 v127, v25, v3
	s_cbranch_scc1 .LBB0_783
; __device__ __forceinline__ float lx_xor(float v, int m, int lane) { return __int_as_float(__builtin_amdgcn_ds_bpermute((lane ^ m) << 2, __float_as_int(v))); }
; __device__ __forceinline__ void skinny_item(Frame& F, const LAS float* AL, LAS float* RED, const float* W, int ldw, int nvalid, int n0, const float* bias, float* out, int ldo) {
;     ...
;     for (int i = 0; i < 17; ++i)
; #pragma unroll
;         for (int c = 0; c < 4; ++c) { float v = acc[i][c]; v += lx_xor(v, 16, lane); v += lx_xor(v, 32, lane); acc[i][c] = v; }
	ds_bpermute_b32 v18, v161, v78
	ds_bpermute_b32 v19, v161, v79
	ds_bpermute_b32 v2, v161, v62
	ds_bpermute_b32 v3, v161, v63
	ds_bpermute_b32 v34, v161, v86
	ds_bpermute_b32 v35, v161, v87
	s_waitcnt lgkmcnt(4)
	v_add_f32_e32 v18, v78, v18
	v_add_f32_e32 v19, v79, v19
	ds_bpermute_b32 v78, v161, v94
	ds_bpermute_b32 v79, v161, v95
	s_waitcnt lgkmcnt(4)
	v_add_f32_e32 v2, v62, v2
	v_add_f32_e32 v3, v63, v3
	ds_bpermute_b32 v10, v161, v74
	ds_bpermute_b32 v11, v161, v75
	ds_bpermute_b32 v26, v161, v82
	ds_bpermute_b32 v27, v161, v83
	s_waitcnt lgkmcnt(6)
	v_add_f32_e32 v34, v86, v34
	v_add_f32_e32 v35, v87, v35
	ds_bpermute_b32 v62, v161, v90
	ds_bpermute_b32 v63, v161, v91
	s_waitcnt lgkmcnt(6)
	v_add_f32_e32 v78, v94, v78
	v_add_f32_e32 v79, v95, v79
	ds_bpermute_b32 v86, v161, v98
	ds_bpermute_b32 v87, v161, v99
	ds_bpermute_b32 v94, v161, v102
	ds_bpermute_b32 v95, v161, v103
	ds_bpermute_b32 v6, v161, v60
	ds_bpermute_b32 v7, v161, v61
	ds_bpermute_b32 v14, v161, v72
	ds_bpermute_b32 v15, v161, v73
	s_waitcnt lgkmcnt(12)
	v_add_f32_e32 v10, v74, v10
	v_add_f32_e32 v11, v75, v11
	ds_bpermute_b32 v22, v161, v76
	ds_bpermute_b32 v23, v161, v77
	ds_bpermute_b32 v30, v161, v80
	ds_bpermute_b32 v31, v161, v81
	s_waitcnt lgkmcnt(14)
	v_add_f32_e32 v26, v82, v26
	v_add_f32_e32 v27, v83, v27
	ds_bpermute_b32 v58, v161, v84
	ds_bpermute_b32 v59, v161, v85
	ds_bpermute_b32 v74, v161, v88
	ds_bpermute_b32 v75, v161, v89
	s_waitcnt lgkmcnt(14)
	v_add_f32_e32 v62, v90, v62
	v_add_f32_e32 v63, v91, v63
	ds_bpermute_b32 v82, v161, v92
	ds_bpermute_b32 v83, v161, v93
	ds_bpermute_b32 v90, v161, v96
	ds_bpermute_b32 v91, v161, v97
	v_add_f32_e32 v86, v98, v86
	v_add_f32_e32 v87, v99, v87
	ds_bpermute_b32 v98, v161, v100
	ds_bpermute_b32 v99, v161, v101
	s_waitcnt lgkmcnt(14)
	v_add_f32_e32 v94, v102, v94
	v_add_f32_e32 v95, v103, v95
	ds_bpermute_b32 v102, v161, v106
	ds_bpermute_b32 v103, v161, v107
	ds_bpermute_b32 v128, v161, v104
	ds_bpermute_b32 v129, v161, v105
	ds_bpermute_b32 v132, v161, v110
	ds_bpermute_b32 v133, v161, v111
	ds_bpermute_b32 v134, v161, v108
	ds_bpermute_b32 v135, v161, v109
	ds_bpermute_b32 v136, v161, v114
	ds_bpermute_b32 v137, v161, v115
	ds_bpermute_b32 v138, v161, v112
	ds_bpermute_b32 v139, v161, v113
	ds_bpermute_b32 v140, v161, v118
	ds_bpermute_b32 v141, v161, v119
	ds_bpermute_b32 v142, v161, v116
	ds_bpermute_b32 v143, v161, v117
	ds_bpermute_b32 v144, v161, v122
	ds_bpermute_b32 v145, v161, v123
	ds_bpermute_b32 v146, v161, v120
	ds_bpermute_b32 v147, v161, v121
	ds_bpermute_b32 v148, v161, v70
	ds_bpermute_b32 v149, v161, v71
	ds_bpermute_b32 v150, v161, v68
	ds_bpermute_b32 v151, v161, v69
	ds_bpermute_b32 v152, v161, v66
	ds_bpermute_b32 v153, v161, v67
	ds_bpermute_b32 v154, v161, v64
	ds_bpermute_b32 v155, v161, v65
	ds_bpermute_b32 v156, v161, v126
	ds_bpermute_b32 v157, v161, v127
	ds_bpermute_b32 v158, v161, v124
	ds_bpermute_b32 v159, v161, v125
	v_add_f32_e32 v6, v60, v6
	v_add_f32_e32 v7, v61, v7
	v_add_f32_e32 v14, v72, v14
	v_add_f32_e32 v15, v73, v15
	s_waitcnt lgkmcnt(14)
	v_add_f32_e32 v22, v76, v22
	v_add_f32_e32 v23, v77, v23
	v_add_f32_e32 v30, v80, v30
	v_add_f32_e32 v31, v81, v31
	v_add_f32_e32 v58, v84, v58
	v_add_f32_e32 v59, v85, v59
	v_add_f32_e32 v74, v88, v74
	v_add_f32_e32 v75, v89, v75
	v_add_f32_e32 v82, v92, v82
	v_add_f32_e32 v83, v93, v83
	v_add_f32_e32 v90, v96, v90
	v_add_f32_e32 v91, v97, v91
	v_add_f32_e32 v98, v100, v98
	v_add_f32_e32 v99, v101, v99
	v_add_f32_e32 v102, v106, v102
	v_add_f32_e32 v103, v107, v103
	v_add_f32_e32 v104, v104, v128
	v_add_f32_e32 v105, v105, v129
	v_add_f32_e32 v110, v110, v132
	v_add_f32_e32 v111, v111, v133
	v_add_f32_e32 v108, v108, v134
	v_add_f32_e32 v109, v109, v135
	v_add_f32_e32 v114, v114, v136
	v_add_f32_e32 v115, v115, v137
	v_add_f32_e32 v112, v112, v138
	v_add_f32_e32 v113, v113, v139
	v_add_f32_e32 v118, v118, v140
	v_add_f32_e32 v119, v119, v141
	v_add_f32_e32 v116, v116, v142
	v_add_f32_e32 v117, v117, v143
	v_add_f32_e32 v122, v122, v144
	v_add_f32_e32 v123, v123, v145
	s_waitcnt lgkmcnt(12)
	v_add_f32_e32 v120, v120, v146
	v_add_f32_e32 v121, v121, v147
	s_waitcnt lgkmcnt(10)
	v_add_f32_e32 v70, v70, v148
	v_add_f32_e32 v71, v71, v149
	s_waitcnt lgkmcnt(8)
	v_add_f32_e32 v68, v68, v150
	v_add_f32_e32 v69, v69, v151
	s_waitcnt lgkmcnt(6)
	v_add_f32_e32 v66, v66, v152
	v_add_f32_e32 v67, v67, v153
	s_waitcnt lgkmcnt(4)
	v_add_f32_e32 v64, v64, v154
	v_add_f32_e32 v65, v65, v155
	s_waitcnt lgkmcnt(2)
	v_add_f32_e32 v126, v126, v156
	v_add_f32_e32 v127, v127, v157
	s_waitcnt lgkmcnt(0)
	v_add_f32_e32 v124, v124, v158
	v_add_f32_e32 v125, v125, v159
	ds_bpermute_b32 v4, v162, v2
	ds_bpermute_b32 v5, v162, v3
	ds_bpermute_b32 v8, v162, v6
	ds_bpermute_b32 v9, v162, v7
	ds_bpermute_b32 v12, v162, v10
	ds_bpermute_b32 v13, v162, v11
	ds_bpermute_b32 v16, v162, v14
	ds_bpermute_b32 v17, v162, v15
	ds_bpermute_b32 v20, v162, v18
	ds_bpermute_b32 v21, v162, v19
	ds_bpermute_b32 v24, v162, v22
	ds_bpermute_b32 v25, v162, v23
	ds_bpermute_b32 v28, v162, v26
	ds_bpermute_b32 v29, v162, v27
	ds_bpermute_b32 v32, v162, v30
	ds_bpermute_b32 v33, v162, v31
	ds_bpermute_b32 v36, v162, v34
	ds_bpermute_b32 v37, v162, v35
	ds_bpermute_b32 v60, v162, v58
	ds_bpermute_b32 v61, v162, v59
	ds_bpermute_b32 v72, v162, v62
	ds_bpermute_b32 v73, v162, v63
	ds_bpermute_b32 v76, v162, v74
	ds_bpermute_b32 v77, v162, v75
	ds_bpermute_b32 v80, v162, v78
	ds_bpermute_b32 v81, v162, v79
	ds_bpermute_b32 v84, v162, v82
	ds_bpermute_b32 v85, v162, v83
	ds_bpermute_b32 v88, v162, v86
	ds_bpermute_b32 v89, v162, v87
	ds_bpermute_b32 v92, v162, v90
	ds_bpermute_b32 v93, v162, v91
	ds_bpermute_b32 v96, v162, v94
	ds_bpermute_b32 v97, v162, v95
	ds_bpermute_b32 v100, v162, v98
	ds_bpermute_b32 v101, v162, v99
	ds_bpermute_b32 v106, v162, v102
	ds_bpermute_b32 v107, v162, v103
	ds_bpermute_b32 v128, v162, v104
	ds_bpermute_b32 v129, v162, v105
	ds_bpermute_b32 v132, v162, v110
	ds_bpermute_b32 v133, v162, v111
	ds_bpermute_b32 v134, v162, v108
	ds_bpermute_b32 v135, v162, v109
	ds_bpermute_b32 v136, v162, v114
	ds_bpermute_b32 v137, v162, v115
	ds_bpermute_b32 v138, v162, v112
	ds_bpermute_b32 v139, v162, v113
	ds_bpermute_b32 v140, v162, v118
	ds_bpermute_b32 v141, v162, v119
	ds_bpermute_b32 v142, v162, v116
	ds_bpermute_b32 v143, v162, v117
	ds_bpermute_b32 v144, v162, v122
	ds_bpermute_b32 v145, v162, v123
	ds_bpermute_b32 v146, v162, v120
	ds_bpermute_b32 v147, v162, v121
	ds_bpermute_b32 v148, v162, v70
	ds_bpermute_b32 v149, v162, v71
	ds_bpermute_b32 v150, v162, v68
	ds_bpermute_b32 v151, v162, v69
	ds_bpermute_b32 v152, v162, v66
	ds_bpermute_b32 v153, v162, v67
	ds_bpermute_b32 v154, v162, v64
	ds_bpermute_b32 v155, v162, v65
	ds_bpermute_b32 v156, v162, v126
	ds_bpermute_b32 v157, v162, v127
	ds_bpermute_b32 v158, v162, v124
	ds_bpermute_b32 v159, v162, v125
	s_and_saveexec_b64 s[8:9], s[0:1]
	s_cbranch_execz .LBB0_786
; #define LAS __attribute__((address_space(3)))
; __device__ __forceinline__ float lx_xor(float v, int m, int lane) { return __int_as_float(__builtin_amdgcn_ds_bpermute((lane ^ m) << 2, __float_as_int(v))); }
; __device__ __forceinline__ void skinny_item(Frame& F, const LAS float* AL, LAS float* RED, const float* W, int ldw, int nvalid, int n0, const float* bias, float* out, int ldo) {
;     ...
;     for (int i = 0; i < 17; ++i)
; #pragma unroll
;         for (int c = 0; c < 4; ++c) { float v = acc[i][c]; v += lx_xor(v, 16, lane); v += lx_xor(v, 32, lane); acc[i][c] = v; }
;     if (lane < 16) {
; #pragma unroll
;         for (int i = 0; i < 17; ++i) *(LAS f32x4*)(RED + (wv * 17 + i) * 64 + 4 * cq) = acc[i]; }
	s_waitcnt lgkmcnt(14)
	v_add_f32_e32 v6, v6, v8
	v_add_f32_e32 v7, v7, v9
	v_add_f32_e32 v4, v2, v4
	v_add_f32_e32 v5, v3, v5
	s_waitcnt lgkmcnt(0)
	v_add_f32_e32 v158, v124, v158
	v_add_f32_e32 v159, v125, v159
	v_add_f32_e32 v156, v126, v156
	v_add_f32_e32 v157, v127, v157
	v_add_f32_e32 v126, v64, v154
	v_add_f32_e32 v127, v65, v155
	v_add_f32_e32 v124, v66, v152
	v_add_f32_e32 v125, v67, v153
	v_add_f32_e32 v66, v68, v150
	v_add_f32_e32 v67, v69, v151
	v_add_f32_e32 v64, v70, v148
	v_add_f32_e32 v65, v71, v149
	v_add_f32_e32 v70, v120, v146
	v_add_f32_e32 v71, v121, v147
	v_add_f32_e32 v68, v122, v144
	v_add_f32_e32 v69, v123, v145
	v_add_f32_e32 v120, v116, v142
	v_add_f32_e32 v121, v117, v143
	v_add_f32_e32 v118, v118, v140
	v_add_f32_e32 v119, v119, v141
	v_add_f32_e32 v116, v112, v138
	v_add_f32_e32 v117, v113, v139
	v_add_f32_e32 v114, v114, v136
	v_add_f32_e32 v115, v115, v137
	v_add_f32_e32 v112, v108, v134
	v_add_f32_e32 v113, v109, v135
	v_add_f32_e32 v110, v110, v132
	v_add_f32_e32 v111, v111, v133
	v_add_f32_e32 v104, v104, v128
	v_add_f32_e32 v105, v105, v129
	v_add_f32_e32 v102, v102, v106
	v_add_f32_e32 v103, v103, v107
	v_add_f32_e32 v98, v98, v100
	v_add_f32_e32 v99, v99, v101
	v_add_f32_e32 v96, v94, v96
	v_add_f32_e32 v97, v95, v97
	v_add_f32_e32 v90, v90, v92
	v_add_f32_e32 v91, v91, v93
	v_add_f32_e32 v88, v86, v88
	v_add_f32_e32 v89, v87, v89
	v_add_f32_e32 v82, v82, v84
	v_add_f32_e32 v83, v83, v85
	v_add_f32_e32 v80, v78, v80
	v_add_f32_e32 v81, v79, v81
	v_add_f32_e32 v74, v74, v76
	v_add_f32_e32 v75, v75, v77
	v_add_f32_e32 v72, v62, v72
	v_add_f32_e32 v73, v63, v73
	v_add_f32_e32 v60, v58, v60
	v_add_f32_e32 v61, v59, v61
	v_add_f32_e32 v58, v34, v36
	v_add_f32_e32 v59, v35, v37
	v_add_f32_e32 v30, v30, v32
	v_add_f32_e32 v31, v31, v33
	v_add_f32_e32 v28, v26, v28
	v_add_f32_e32 v29, v27, v29
	v_add_f32_e32 v22, v22, v24
	v_add_f32_e32 v23, v23, v25
	v_add_f32_e32 v20, v18, v20
	v_add_f32_e32 v21, v19, v21
	v_add_f32_e32 v14, v14, v16
	v_add_f32_e32 v15, v15, v17
	v_add_f32_e32 v12, v10, v12
	v_add_f32_e32 v13, v11, v13
	ds_write_b128 v165, v[4:7]
	ds_write_b128 v165, v[12:15] offset:256
	ds_write_b128 v165, v[20:23] offset:512
	ds_write_b128 v165, v[28:31] offset:768
	ds_write_b128 v165, v[58:61] offset:1024
	ds_write_b128 v165, v[72:75] offset:1280
	ds_write_b128 v165, v[80:83] offset:1536
	ds_write_b128 v165, v[88:91] offset:1792
	ds_write_b128 v165, v[96:99] offset:2048
	ds_write_b128 v165, v[102:105] offset:2304
	ds_write_b128 v165, v[110:113] offset:2560
	ds_write_b128 v165, v[114:117] offset:2816
	ds_write_b128 v165, v[118:121] offset:3072
	ds_write_b128 v165, v[68:71] offset:3328
	ds_write_b128 v165, v[64:67] offset:3584
	ds_write_b128 v165, v[124:127] offset:3840
	ds_write_b128 v165, v[156:159] offset:4096
